# load segments: the M0 wait-state slots before each LDS-DMA are filled with the segment's last ds_reads (10 s_nop per iteration gone); on top of the v54 stack
# baseline (speedup 1.0000x reference)
; #define PG8_STAGE(bufoff, gbase, voff) do { _Pragma("unroll") for (int _i = 0; _i < 2; ++_i) \
;         __builtin_amdgcn_global_load_lds((const unsigned*)((const char*)(gbase) + (voff)[_i]), (LAS unsigned*)(lds + (bufoff) + ldsw + _i * 8192), 16, 0, 0); } while (0)
; #define PG8_WAIT_V(n) asm volatile("s_waitcnt vmcnt(" #n ")" ::: "memory")
; template <class Epi, class Sched, bool ABLK = false, bool ALIGN_EPI = true, bool SP2 = true, bool BBLK = true>
; __device__ __forceinline__ void gemm_phase(LAS unsigned char* lds, const Gemm g, const Sched& S, const Epi& E) {
;     ...
;         const bool has_next = S.next(ui + 1, nxt);
;         const int nt = cur.nt;
;         const char* nuA = has_next ? a_unit(nxt) : uA; const int ntbA = has_next ? nxt.k0 / BK : tbA; const char* nB = has_next ? (const char*)g.Bt + (size_t)nxt.pn * tstepB + b_k0(nxt.k0) : cB;
;         for (int t = 0; t < nt; t += 2) {
;             const bool last = (t == nt - 2);
;             const char* a1 = a_tile(uA, tbA + t + 1);
;             const char* a2 = last ? a_tile(nuA, ntbA) : a_tile(uA, tbA + t + 2); const char* b2 = last ? nB : cB + (size_t)(t + 2) * kstepB;
;             const char* a3 = last ? a_tile(nuA, ntbA + 1) : a_tile(uA, tbA + t + 3); const char* b3 = b2 + kstepB;
;             if (last && has_next) S.a_ready(nxt);
;             if constexpr (SP2) {
;             PG8_LDB(B0, 0, 0); PG8_LDB(B1, 0, 1); PG8_SCHED; PG8_LDA(At, 0, 0); PG8_STAGE(PG8_SA(1, 1), a1 + hstepA, voffA);
;             PG8_WAIT_V(8); PG8_WAIT_L(0); PG8_BAR; PG8_MMA(0, 0, At, B0); PG8_MMA(0, 1, At, B1); PG8_BAR; PG8_SCHED;
;             PG8_LDA(At, 0, 1); PG8_STAGE(PG8_SB(0, 0), b2, voffB); PG8_STAGE(PG8_SB(0, 1), b2 + hstepB, voffB); PG8_STAGE(PG8_SA(0, 0), a2, voffA);
;             PG8_WAIT_V(8); PG8_WAIT_L(0); PG8_BAR; PG8_MMA(1, 0, At, B0); PG8_MMA(1, 1, At, B1); PG8_BAR; PG8_SCHED;
;             PG8_LDB(B0, 1, 0); PG8_LDB(B1, 1, 1); PG8_SCHED; PG8_LDA(At, 1, 0); PG8_STAGE(PG8_SA(0, 1), a2 + hstepA, voffA);
;             PG8_WAIT_V(8); PG8_WAIT_L(0); PG8_BAR; PG8_MMA(0, 0, At, B0); PG8_MMA(0, 1, At, B1); PG8_BAR; PG8_SCHED;
;             PG8_LDA(At, 1, 1); PG8_STAGE(PG8_SB(1, 0), b3, voffB); PG8_STAGE(PG8_SB(1, 1), b3 + hstepB, voffB); PG8_STAGE(PG8_SA(1, 0), a3, voffA);
;             PG8_WAIT_V(8); PG8_WAIT_L(0); PG8_BAR; PG8_MMA(1, 0, At, B0); PG8_MMA(1, 1, At, B1); PG8_BAR; PG8_SCHED;
.LBB0_349:
	s_ashr_i32 s9, s8, 31
	s_lshl_b64 s[4:5], s[8:9], 20
	s_add_u32 s12, s36, s4
	s_addc_u32 s13, s37, s5
	s_and_b64 s[4:5], s[14:15], exec
	s_cselect_b32 s4, s13, s25
	s_cselect_b32 s5, s12, s24
	s_ashr_i32 s11, s10, 31
	s_lshl_b64 s[18:19], s[10:11], 20
	s_add_u32 s18, s0, s18
	s_addc_u32 s19, s1, s19
	s_and_b64 s[28:29], s[14:15], exec
	s_cselect_b32 s9, s19, s27
	s_cselect_b32 s11, s18, s26
	s_add_u32 s50, s5, 0x80
	s_addc_u32 s51, s4, 0
	s_add_u32 s52, s26, 0x10000
	v_mov_b32_e32 v2, 0
	s_addc_u32 s53, s27, 0
	v_lshl_add_u64 v[142:143], s[24:25], 0, v[138:139]
	v_lshl_add_u64 v[144:145], s[24:25], 0, v[140:141]
	s_mov_b32 s54, -2
	s_mov_b64 s[26:27], 0
	ds_read_b128 v[152:155], v148
	ds_read_b128 v[156:159], v148 offset:1024
	ds_read_b128 v[160:163], v148 offset:2048
	ds_read_b128 v[164:167], v148 offset:3072
	ds_read_b128 v[168:171], v149
	ds_read_b128 v[172:175], v149 offset:1024
	ds_read_b128 v[176:179], v149 offset:2048
	ds_read_b128 v[180:183], v149 offset:3072
	s_add_u32 s28, s24, s26
	s_addc_u32 s29, s25, s27
	s_add_u32 s34, s28, 0x100
	s_addc_u32 s35, s29, 0
	s_add_u32 s28, s28, 0x180
	s_addc_u32 s29, s29, 0
	s_cmpk_eq_i32 s26, 0xf00
	s_cselect_b32 s29, s51, s29
	s_cselect_b32 s28, s50, s28
	s_cselect_b32 s31, s9, s53
	s_cselect_b32 s30, s11, s52
	s_cselect_b32 s35, s4, s35
	s_cselect_b32 s34, s5, s34
	s_mov_b32 m0, s49
	v_lshl_add_u64 v[216:217], v[142:143], 0, s[26:27]
	ds_read_b128 v[184:187], v150
	ds_read_b128 v[188:191], v150 offset:1024
	ds_read_b128 v[192:195], v150 offset:2048
	ds_read_b128 v[196:199], v150 offset:3072
	ds_read_b128 v[200:203], v150 offset:4096
	ds_read_b128 v[204:207], v150 offset:5120
	ds_read_b128 v[208:211], v150 offset:6144
	global_load_lds_dwordx4 v[216:217], off
	v_lshl_add_u64 v[216:217], v[144:145], 0, s[26:27]
	s_add_i32 m0, s21, 0xe000
	ds_read_b128 v[212:215], v150 offset:7168
	global_load_lds_dwordx4 v[216:217], off
	s_waitcnt vmcnt(8) lgkmcnt(0)
	s_barrier
	v_mfma_f32_16x16x32_bf16 v[122:125], v[152:155], v[184:187], 0
	v_mfma_f32_16x16x32_bf16 v[118:121], v[160:163], v[184:187], 0
	v_mfma_f32_16x16x32_bf16 v[106:109], v[152:155], v[192:195], 0
	v_mfma_f32_16x16x32_bf16 v[102:105], v[160:163], v[192:195], 0
	v_mfma_f32_16x16x32_bf16 v[90:93], v[152:155], v[200:203], 0
	v_mfma_f32_16x16x32_bf16 v[86:89], v[160:163], v[200:203], 0
	v_mfma_f32_16x16x32_bf16 v[74:77], v[152:155], v[208:211], 0
	v_mfma_f32_16x16x32_bf16 v[70:73], v[160:163], v[208:211], 0
	v_mfma_f32_16x16x32_bf16 v[122:125], v[156:159], v[188:191], v[122:125]
	v_mfma_f32_16x16x32_bf16 v[118:121], v[164:167], v[188:191], v[118:121]
	v_mfma_f32_16x16x32_bf16 v[106:109], v[156:159], v[196:199], v[106:109]
	v_mfma_f32_16x16x32_bf16 v[102:105], v[164:167], v[196:199], v[102:105]
	v_mfma_f32_16x16x32_bf16 v[90:93], v[156:159], v[204:207], v[90:93]
	v_mfma_f32_16x16x32_bf16 v[86:89], v[164:167], v[204:207], v[86:89]
	v_mfma_f32_16x16x32_bf16 v[74:77], v[156:159], v[212:215], v[74:77]
	v_mfma_f32_16x16x32_bf16 v[70:73], v[164:167], v[212:215], v[70:73]
	v_mfma_f32_16x16x32_bf16 v[126:129], v[168:171], v[184:187], 0
	v_mfma_f32_16x16x32_bf16 v[114:117], v[176:179], v[184:187], 0
	v_mfma_f32_16x16x32_bf16 v[110:113], v[168:171], v[192:195], 0
	v_mfma_f32_16x16x32_bf16 v[98:101], v[176:179], v[192:195], 0
	v_mfma_f32_16x16x32_bf16 v[94:97], v[168:171], v[200:203], 0
	v_mfma_f32_16x16x32_bf16 v[82:85], v[176:179], v[200:203], 0
	v_mfma_f32_16x16x32_bf16 v[78:81], v[168:171], v[208:211], 0
	v_mfma_f32_16x16x32_bf16 v[66:69], v[176:179], v[208:211], 0
	v_mfma_f32_16x16x32_bf16 v[126:129], v[172:175], v[188:191], v[126:129]
	v_mfma_f32_16x16x32_bf16 v[114:117], v[180:183], v[188:191], v[114:117]
	v_mfma_f32_16x16x32_bf16 v[110:113], v[172:175], v[196:199], v[110:113]
	v_mfma_f32_16x16x32_bf16 v[98:101], v[180:183], v[196:199], v[98:101]
	v_mfma_f32_16x16x32_bf16 v[94:97], v[172:175], v[204:207], v[94:97]
	v_mfma_f32_16x16x32_bf16 v[82:85], v[180:183], v[204:207], v[82:85]
	v_mfma_f32_16x16x32_bf16 v[78:81], v[172:175], v[212:215], v[78:81]
	v_mfma_f32_16x16x32_bf16 v[66:69], v[180:183], v[212:215], v[66:69]
	s_barrier
	s_add_i32 s55, s44, s33
	s_mov_b32 m0, s55
	ds_read_b128 v[184:187], v150 offset:16384
	ds_read_b128 v[188:191], v150 offset:17408
	ds_read_b128 v[192:195], v150 offset:18432
	ds_read_b128 v[196:199], v150 offset:19456
	global_load_lds_dwordx4 v134, s[30:31]
	s_add_i32 m0, s55, 0x2000
	s_add_u32 s56, s30, 0x4000
	s_addc_u32 s57, s31, 0
	s_add_i32 s55, s45, s33
	global_load_lds_dwordx4 v130, s[30:31]
	s_mov_b32 m0, s55
	ds_read_b128 v[200:203], v150 offset:20480
	global_load_lds_dwordx4 v134, s[56:57]
	s_add_i32 m0, s55, 0x2000
	ds_read_b128 v[204:207], v150 offset:21504
	global_load_lds_dwordx4 v130, s[56:57]
	s_mov_b32 m0, s21
	ds_read_b128 v[208:211], v150 offset:22528
	global_load_lds_dwordx4 v136, s[34:35]
	s_mov_b32 m0, s23
	ds_read_b128 v[212:215], v150 offset:23552
	global_load_lds_dwordx4 v132, s[34:35]
	s_waitcnt vmcnt(8) lgkmcnt(0)
	s_barrier
; #define PG8_STAGE(bufoff, gbase, voff) do { _Pragma("unroll") for (int _i = 0; _i < 2; ++_i) \
;         __builtin_amdgcn_global_load_lds((const unsigned*)((const char*)(gbase) + (voff)[_i]), (LAS unsigned*)(lds + (bufoff) + ldsw + _i * 8192), 16, 0, 0); } while (0)
; #define PG8_LDA(dst, b, h) do { _Pragma("unroll") for (int m = 0; m < 4; ++m) _Pragma("unroll") for (int k = 0; k < 2; ++k) dst[m][k] = *(const LAS bf16x8*)(lds + PG8_SA(b, h) + aoff + m * 2048 + k * 1024); } while (0)
; #define PG8_LDB(dst, b, h) do { _Pragma("unroll") for (int n = 0; n < 2; ++n) _Pragma("unroll") for (int k = 0; k < 2; ++k) dst[n][k] = *(const LAS bf16x8*)(lds + PG8_SB(b, h) + boff + n * 2048 + k * 1024); } while (0)
; #define PG8_MMA(ai, bj, At, Bt) do { __builtin_amdgcn_s_setprio(1); _Pragma("unroll") for (int m = 0; m < 4; ++m) _Pragma("unroll") for (int n = 0; n < 2; ++n) _Pragma("unroll") for (int k = 0; k < 2; ++k) \
;         acc[ai][bj][m][n] = __builtin_amdgcn_mfma_f32_16x16x32_bf16(Bt[n][k], At[m][k], acc[ai][bj][m][n], 0, 0, 0); __builtin_amdgcn_s_setprio(0); } while (0)
; #define PG8_WAIT_V(n) asm volatile("s_waitcnt vmcnt(" #n ")" ::: "memory")
; #define PG8_WAIT_L(n) asm volatile("s_waitcnt lgkmcnt(" #n ")" ::: "memory")
; #define PG8_BAR __builtin_amdgcn_s_barrier()
; #define PG8_SCHED __builtin_amdgcn_sched_barrier(0)
; template <class Epi, class Sched, bool ABLK = false, bool ALIGN_EPI = true, bool SP2 = true, bool BBLK = true>
; __device__ __forceinline__ void gemm_phase(LAS unsigned char* lds, const Gemm g, const Sched& S, const Epi& E) {
;     ...
;             PG8_WAIT_V(8); PG8_WAIT_L(0); PG8_BAR; PG8_MMA(1, 0, At, B0); PG8_MMA(1, 1, At, B1); PG8_BAR; PG8_SCHED;
;             PG8_LDB(B0, 1, 0); PG8_LDB(B1, 1, 1); PG8_SCHED; PG8_LDA(At, 1, 0); PG8_STAGE(PG8_SA(0, 1), a2 + hstepA, voffA);
;             PG8_WAIT_V(8); PG8_WAIT_L(0); PG8_BAR; PG8_MMA(0, 0, At, B0); PG8_MMA(0, 1, At, B1); PG8_BAR; PG8_SCHED;
	v_mfma_f32_16x16x32_bf16 v[58:61], v[152:155], v[184:187], 0
	v_mfma_f32_16x16x32_bf16 v[54:57], v[160:163], v[184:187], 0
	v_mfma_f32_16x16x32_bf16 v[42:45], v[152:155], v[192:195], 0
	v_mfma_f32_16x16x32_bf16 v[38:41], v[160:163], v[192:195], 0
	v_mfma_f32_16x16x32_bf16 v[26:29], v[152:155], v[200:203], 0
	v_mfma_f32_16x16x32_bf16 v[22:25], v[160:163], v[200:203], 0
	v_mfma_f32_16x16x32_bf16 v[10:13], v[152:155], v[208:211], 0
	v_mfma_f32_16x16x32_bf16 v[6:9], v[160:163], v[208:211], 0
	v_mfma_f32_16x16x32_bf16 v[58:61], v[156:159], v[188:191], v[58:61]
	v_mfma_f32_16x16x32_bf16 v[54:57], v[164:167], v[188:191], v[54:57]
	v_mfma_f32_16x16x32_bf16 v[42:45], v[156:159], v[196:199], v[42:45]
	v_mfma_f32_16x16x32_bf16 v[38:41], v[164:167], v[196:199], v[38:41]
	v_mfma_f32_16x16x32_bf16 v[26:29], v[156:159], v[204:207], v[26:29]
	v_mfma_f32_16x16x32_bf16 v[22:25], v[164:167], v[204:207], v[22:25]
	v_mfma_f32_16x16x32_bf16 v[10:13], v[156:159], v[212:215], v[10:13]
	v_mfma_f32_16x16x32_bf16 v[6:9], v[164:167], v[212:215], v[6:9]
	v_mfma_f32_16x16x32_bf16 v[62:65], v[168:171], v[184:187], 0
	v_mfma_f32_16x16x32_bf16 v[50:53], v[176:179], v[184:187], 0
	v_mfma_f32_16x16x32_bf16 v[46:49], v[168:171], v[192:195], 0
	v_mfma_f32_16x16x32_bf16 v[34:37], v[176:179], v[192:195], 0
	v_mfma_f32_16x16x32_bf16 v[30:33], v[168:171], v[200:203], 0
	v_mfma_f32_16x16x32_bf16 v[18:21], v[176:179], v[200:203], 0
	v_mfma_f32_16x16x32_bf16 v[14:17], v[168:171], v[208:211], 0
	v_mfma_f32_16x16x32_bf16 v[2:5], v[176:179], v[208:211], 0
	v_mfma_f32_16x16x32_bf16 v[62:65], v[172:175], v[188:191], v[62:65]
	v_mfma_f32_16x16x32_bf16 v[50:53], v[180:183], v[188:191], v[50:53]
	v_mfma_f32_16x16x32_bf16 v[46:49], v[172:175], v[196:199], v[46:49]
	v_mfma_f32_16x16x32_bf16 v[34:37], v[180:183], v[196:199], v[34:37]
	v_mfma_f32_16x16x32_bf16 v[30:33], v[172:175], v[204:207], v[30:33]
	v_mfma_f32_16x16x32_bf16 v[18:21], v[180:183], v[204:207], v[18:21]
	v_mfma_f32_16x16x32_bf16 v[14:17], v[172:175], v[212:215], v[14:17]
	v_mfma_f32_16x16x32_bf16 v[2:5], v[180:183], v[212:215], v[2:5]
	s_barrier
	s_add_i32 s55, 0, 0x18000
	v_add_u32_e32 v151, s55, v146
	s_add_i32 s56, 0, 0x1c000
	ds_read_b128 v[152:155], v151
	ds_read_b128 v[156:159], v151 offset:1024
	ds_read_b128 v[160:163], v151 offset:2048
	ds_read_b128 v[164:167], v151 offset:3072
	v_add_u32_e32 v151, s56, v146
	ds_read_b128 v[168:171], v151
	ds_read_b128 v[172:175], v151 offset:1024
	ds_read_b128 v[176:179], v151 offset:2048
	ds_read_b128 v[180:183], v151 offset:3072
	s_add_u32 s34, s34, 0x80000
	s_addc_u32 s35, s35, 0
	s_mov_b32 m0, s39
	ds_read_b128 v[184:187], v150 offset:32768
	ds_read_b128 v[188:191], v150 offset:33792
	ds_read_b128 v[192:195], v150 offset:34816
	ds_read_b128 v[196:199], v150 offset:35840
	ds_read_b128 v[200:203], v150 offset:36864
	ds_read_b128 v[204:207], v150 offset:37888
	ds_read_b128 v[208:211], v150 offset:38912
	global_load_lds_dwordx4 v136, s[34:35]
	s_mov_b32 m0, s40
	ds_read_b128 v[212:215], v150 offset:39936
	global_load_lds_dwordx4 v132, s[34:35]
	s_waitcnt vmcnt(8) lgkmcnt(0)
	s_barrier
	v_mfma_f32_16x16x32_bf16 v[122:125], v[152:155], v[184:187], v[122:125]
	v_mfma_f32_16x16x32_bf16 v[118:121], v[160:163], v[184:187], v[118:121]
	v_mfma_f32_16x16x32_bf16 v[106:109], v[152:155], v[192:195], v[106:109]
	v_mfma_f32_16x16x32_bf16 v[102:105], v[160:163], v[192:195], v[102:105]
	v_mfma_f32_16x16x32_bf16 v[90:93], v[152:155], v[200:203], v[90:93]
	v_mfma_f32_16x16x32_bf16 v[86:89], v[160:163], v[200:203], v[86:89]
	v_mfma_f32_16x16x32_bf16 v[74:77], v[152:155], v[208:211], v[74:77]
	v_mfma_f32_16x16x32_bf16 v[70:73], v[160:163], v[208:211], v[70:73]
	v_mfma_f32_16x16x32_bf16 v[122:125], v[156:159], v[188:191], v[122:125]
	v_mfma_f32_16x16x32_bf16 v[118:121], v[164:167], v[188:191], v[118:121]
	v_mfma_f32_16x16x32_bf16 v[106:109], v[156:159], v[196:199], v[106:109]
	v_mfma_f32_16x16x32_bf16 v[102:105], v[164:167], v[196:199], v[102:105]
	v_mfma_f32_16x16x32_bf16 v[90:93], v[156:159], v[204:207], v[90:93]
	v_mfma_f32_16x16x32_bf16 v[86:89], v[164:167], v[204:207], v[86:89]
	v_mfma_f32_16x16x32_bf16 v[74:77], v[156:159], v[212:215], v[74:77]
	v_mfma_f32_16x16x32_bf16 v[70:73], v[164:167], v[212:215], v[70:73]
	v_mfma_f32_16x16x32_bf16 v[126:129], v[168:171], v[184:187], v[126:129]
	v_mfma_f32_16x16x32_bf16 v[114:117], v[176:179], v[184:187], v[114:117]
	v_mfma_f32_16x16x32_bf16 v[110:113], v[168:171], v[192:195], v[110:113]
	v_mfma_f32_16x16x32_bf16 v[98:101], v[176:179], v[192:195], v[98:101]
	v_mfma_f32_16x16x32_bf16 v[94:97], v[168:171], v[200:203], v[94:97]
	v_mfma_f32_16x16x32_bf16 v[82:85], v[176:179], v[200:203], v[82:85]
	v_mfma_f32_16x16x32_bf16 v[78:81], v[168:171], v[208:211], v[78:81]
	v_mfma_f32_16x16x32_bf16 v[66:69], v[176:179], v[208:211], v[66:69]
	v_mfma_f32_16x16x32_bf16 v[126:129], v[172:175], v[188:191], v[126:129]
	v_mfma_f32_16x16x32_bf16 v[114:117], v[180:183], v[188:191], v[114:117]
	v_mfma_f32_16x16x32_bf16 v[110:113], v[172:175], v[196:199], v[110:113]
	v_mfma_f32_16x16x32_bf16 v[98:101], v[180:183], v[196:199], v[98:101]
	v_mfma_f32_16x16x32_bf16 v[94:97], v[172:175], v[204:207], v[94:97]
	v_mfma_f32_16x16x32_bf16 v[82:85], v[180:183], v[204:207], v[82:85]
	v_mfma_f32_16x16x32_bf16 v[78:81], v[172:175], v[212:215], v[78:81]
	v_mfma_f32_16x16x32_bf16 v[66:69], v[180:183], v[212:215], v[66:69]
	s_barrier
; #define PG8_STAGE(bufoff, gbase, voff) do { _Pragma("unroll") for (int _i = 0; _i < 2; ++_i) \
;         __builtin_amdgcn_global_load_lds((const unsigned*)((const char*)(gbase) + (voff)[_i]), (LAS unsigned*)(lds + (bufoff) + ldsw + _i * 8192), 16, 0, 0); } while (0)
; #define PG8_LDA(dst, b, h) do { _Pragma("unroll") for (int m = 0; m < 4; ++m) _Pragma("unroll") for (int k = 0; k < 2; ++k) dst[m][k] = *(const LAS bf16x8*)(lds + PG8_SA(b, h) + aoff + m * 2048 + k * 1024); } while (0)
; #define PG8_LDB(dst, b, h) do { _Pragma("unroll") for (int n = 0; n < 2; ++n) _Pragma("unroll") for (int k = 0; k < 2; ++k) dst[n][k] = *(const LAS bf16x8*)(lds + PG8_SB(b, h) + boff + n * 2048 + k * 1024); } while (0)
; #define PG8_MMA(ai, bj, At, Bt) do { __builtin_amdgcn_s_setprio(1); _Pragma("unroll") for (int m = 0; m < 4; ++m) _Pragma("unroll") for (int n = 0; n < 2; ++n) _Pragma("unroll") for (int k = 0; k < 2; ++k) \
;         acc[ai][bj][m][n] = __builtin_amdgcn_mfma_f32_16x16x32_bf16(Bt[n][k], At[m][k], acc[ai][bj][m][n], 0, 0, 0); __builtin_amdgcn_s_setprio(0); } while (0)
; #define PG8_WAIT_V(n) asm volatile("s_waitcnt vmcnt(" #n ")" ::: "memory")
; template <class Epi, class Sched, bool ABLK = false, bool ALIGN_EPI = true, bool SP2 = true, bool BBLK = true>
; __device__ __forceinline__ void gemm_phase(LAS unsigned char* lds, const Gemm g, const Sched& S, const Epi& E) {
;     ...
;         for (int t = 0; t < nt; t += 2) {
;             const bool last = (t == nt - 2);
;             const char* a1 = a_tile(uA, tbA + t + 1);
;             const char* a2 = last ? a_tile(nuA, ntbA) : a_tile(uA, tbA + t + 2); const char* b2 = last ? nB : cB + (size_t)(t + 2) * kstepB;
;             const char* a3 = last ? a_tile(nuA, ntbA + 1) : a_tile(uA, tbA + t + 3); const char* b3 = b2 + kstepB;
;             if (last && has_next) S.a_ready(nxt);
;             if constexpr (SP2) {
;             PG8_LDB(B0, 0, 0); PG8_LDB(B1, 0, 1); PG8_SCHED; PG8_LDA(At, 0, 0); PG8_STAGE(PG8_SA(1, 1), a1 + hstepA, voffA);
;             PG8_WAIT_V(8); PG8_WAIT_L(0); PG8_BAR; PG8_MMA(0, 0, At, B0); PG8_MMA(0, 1, At, B1); PG8_BAR; PG8_SCHED;
;     ...
;             PG8_LDA(At, 1, 1); PG8_STAGE(PG8_SB(1, 0), b3, voffB); PG8_STAGE(PG8_SB(1, 1), b3 + hstepB, voffB); PG8_STAGE(PG8_SA(1, 0), a3, voffA);
;             PG8_WAIT_V(8); PG8_WAIT_L(0); PG8_BAR; PG8_MMA(1, 0, At, B0); PG8_MMA(1, 1, At, B1); PG8_BAR; PG8_SCHED;
	s_add_u32 s34, s30, 0x8000
	s_addc_u32 s35, s31, 0
	s_add_i32 s55, s55, s33
	s_mov_b32 m0, s55
	ds_read_b128 v[184:187], v150 offset:49152
	ds_read_b128 v[188:191], v150 offset:50176
	ds_read_b128 v[192:195], v150 offset:51200
	ds_read_b128 v[196:199], v150 offset:52224
	global_load_lds_dwordx4 v134, s[34:35]
	s_add_i32 m0, s55, 0x2000
	s_add_u32 s30, s30, 0xc000
	v_lshl_add_u64 v[216:217], s[34:35], 0, v[130:131]
	s_addc_u32 s31, s31, 0
	s_add_i32 s34, s56, s33
	global_load_lds_dwordx4 v[216:217], off
	s_mov_b32 m0, s34
	ds_read_b128 v[200:203], v150 offset:53248
	global_load_lds_dwordx4 v134, s[30:31]
	s_add_i32 m0, s34, 0x2000
	ds_read_b128 v[204:207], v150 offset:54272
	global_load_lds_dwordx4 v130, s[30:31]
	s_mov_b32 m0, s42
	ds_read_b128 v[208:211], v150 offset:55296
	global_load_lds_dwordx4 v136, s[28:29]
	s_mov_b32 m0, s43
	ds_read_b128 v[212:215], v150 offset:56320
	global_load_lds_dwordx4 v132, s[28:29]
	s_waitcnt vmcnt(8) lgkmcnt(0)
	s_barrier
	v_mfma_f32_16x16x32_bf16 v[58:61], v[152:155], v[184:187], v[58:61]
	v_mfma_f32_16x16x32_bf16 v[54:57], v[160:163], v[184:187], v[54:57]
	v_mfma_f32_16x16x32_bf16 v[42:45], v[152:155], v[192:195], v[42:45]
	v_mfma_f32_16x16x32_bf16 v[38:41], v[160:163], v[192:195], v[38:41]
	v_mfma_f32_16x16x32_bf16 v[26:29], v[152:155], v[200:203], v[26:29]
	v_mfma_f32_16x16x32_bf16 v[22:25], v[160:163], v[200:203], v[22:25]
	v_mfma_f32_16x16x32_bf16 v[10:13], v[152:155], v[208:211], v[10:13]
	v_mfma_f32_16x16x32_bf16 v[6:9], v[160:163], v[208:211], v[6:9]
	v_mfma_f32_16x16x32_bf16 v[58:61], v[156:159], v[188:191], v[58:61]
	v_mfma_f32_16x16x32_bf16 v[54:57], v[164:167], v[188:191], v[54:57]
	v_mfma_f32_16x16x32_bf16 v[42:45], v[156:159], v[196:199], v[42:45]
	v_mfma_f32_16x16x32_bf16 v[38:41], v[164:167], v[196:199], v[38:41]
	v_mfma_f32_16x16x32_bf16 v[26:29], v[156:159], v[204:207], v[26:29]
	v_mfma_f32_16x16x32_bf16 v[22:25], v[164:167], v[204:207], v[22:25]
	v_mfma_f32_16x16x32_bf16 v[10:13], v[156:159], v[212:215], v[10:13]
	v_mfma_f32_16x16x32_bf16 v[6:9], v[164:167], v[212:215], v[6:9]
	v_mfma_f32_16x16x32_bf16 v[62:65], v[168:171], v[184:187], v[62:65]
	v_mfma_f32_16x16x32_bf16 v[50:53], v[176:179], v[184:187], v[50:53]
	v_mfma_f32_16x16x32_bf16 v[46:49], v[168:171], v[192:195], v[46:49]
	v_mfma_f32_16x16x32_bf16 v[34:37], v[176:179], v[192:195], v[34:37]
	v_mfma_f32_16x16x32_bf16 v[30:33], v[168:171], v[200:203], v[30:33]
	v_mfma_f32_16x16x32_bf16 v[18:21], v[176:179], v[200:203], v[18:21]
	v_mfma_f32_16x16x32_bf16 v[14:17], v[168:171], v[208:211], v[14:17]
	v_mfma_f32_16x16x32_bf16 v[2:5], v[176:179], v[208:211], v[2:5]
	v_mfma_f32_16x16x32_bf16 v[62:65], v[172:175], v[188:191], v[62:65]
	v_mfma_f32_16x16x32_bf16 v[50:53], v[180:183], v[188:191], v[50:53]
	v_mfma_f32_16x16x32_bf16 v[46:49], v[172:175], v[196:199], v[46:49]
	v_mfma_f32_16x16x32_bf16 v[34:37], v[180:183], v[196:199], v[34:37]
	v_mfma_f32_16x16x32_bf16 v[30:33], v[172:175], v[204:207], v[30:33]
	v_mfma_f32_16x16x32_bf16 v[18:21], v[180:183], v[204:207], v[18:21]
	v_mfma_f32_16x16x32_bf16 v[14:17], v[172:175], v[212:215], v[14:17]
	v_mfma_f32_16x16x32_bf16 v[2:5], v[180:183], v[212:215], v[2:5]
	s_barrier
	s_add_i32 s54, s54, 2
	s_add_u32 s26, s26, 0x100
	s_addc_u32 s27, s27, 0
	s_add_u32 s52, s52, 0x10000
	s_addc_u32 s53, s53, 0
	s_cmp_gt_u32 s54, 29
.LBB0_350:
	ds_read_b128 v[152:155], v148
	ds_read_b128 v[156:159], v148 offset:1024
	ds_read_b128 v[160:163], v148 offset:2048
	ds_read_b128 v[164:167], v148 offset:3072
	ds_read_b128 v[168:171], v149
	ds_read_b128 v[172:175], v149 offset:1024
	ds_read_b128 v[176:179], v149 offset:2048
	ds_read_b128 v[180:183], v149 offset:3072
	s_add_u32 s28, s24, s26
	s_addc_u32 s29, s25, s27
	s_add_u32 s34, s28, 0x100
	s_addc_u32 s35, s29, 0
	s_add_u32 s28, s28, 0x180
	s_addc_u32 s29, s29, 0
	s_cmpk_eq_i32 s26, 0xf00
	s_cselect_b32 s29, s51, s29
	s_cselect_b32 s28, s50, s28
	s_cselect_b32 s31, s9, s53
	s_cselect_b32 s30, s11, s52
	s_cselect_b32 s35, s4, s35
	s_cselect_b32 s34, s5, s34
	s_mov_b32 m0, s49
	v_lshl_add_u64 v[216:217], v[142:143], 0, s[26:27]
	ds_read_b128 v[184:187], v150
	ds_read_b128 v[188:191], v150 offset:1024
	ds_read_b128 v[192:195], v150 offset:2048
	ds_read_b128 v[196:199], v150 offset:3072
	ds_read_b128 v[200:203], v150 offset:4096
	ds_read_b128 v[204:207], v150 offset:5120
	ds_read_b128 v[208:211], v150 offset:6144
	global_load_lds_dwordx4 v[216:217], off
	v_lshl_add_u64 v[216:217], v[144:145], 0, s[26:27]
	s_add_i32 m0, s21, 0xe000
	ds_read_b128 v[212:215], v150 offset:7168
	global_load_lds_dwordx4 v[216:217], off
	s_waitcnt vmcnt(8) lgkmcnt(0)
	s_barrier
; #define PG8_STAGE(bufoff, gbase, voff) do { _Pragma("unroll") for (int _i = 0; _i < 2; ++_i) \
;         __builtin_amdgcn_global_load_lds((const unsigned*)((const char*)(gbase) + (voff)[_i]), (LAS unsigned*)(lds + (bufoff) + ldsw + _i * 8192), 16, 0, 0); } while (0)
; #define PG8_LDA(dst, b, h) do { _Pragma("unroll") for (int m = 0; m < 4; ++m) _Pragma("unroll") for (int k = 0; k < 2; ++k) dst[m][k] = *(const LAS bf16x8*)(lds + PG8_SA(b, h) + aoff + m * 2048 + k * 1024); } while (0)
; #define PG8_MMA(ai, bj, At, Bt) do { __builtin_amdgcn_s_setprio(1); _Pragma("unroll") for (int m = 0; m < 4; ++m) _Pragma("unroll") for (int n = 0; n < 2; ++n) _Pragma("unroll") for (int k = 0; k < 2; ++k) \
;         acc[ai][bj][m][n] = __builtin_amdgcn_mfma_f32_16x16x32_bf16(Bt[n][k], At[m][k], acc[ai][bj][m][n], 0, 0, 0); __builtin_amdgcn_s_setprio(0); } while (0)
; #define PG8_WAIT_V(n) asm volatile("s_waitcnt vmcnt(" #n ")" ::: "memory")
; #define PG8_WAIT_L(n) asm volatile("s_waitcnt lgkmcnt(" #n ")" ::: "memory")
; #define PG8_BAR __builtin_amdgcn_s_barrier()
; #define PG8_SCHED __builtin_amdgcn_sched_barrier(0)
; template <class Epi, class Sched, bool ABLK = false, bool ALIGN_EPI = true, bool SP2 = true, bool BBLK = true>
; __device__ __forceinline__ void gemm_phase(LAS unsigned char* lds, const Gemm g, const Sched& S, const Epi& E) {
;     ...
;             PG8_WAIT_V(8); PG8_WAIT_L(0); PG8_BAR; PG8_MMA(0, 0, At, B0); PG8_MMA(0, 1, At, B1); PG8_BAR; PG8_SCHED;
;             PG8_LDA(At, 0, 1); PG8_STAGE(PG8_SB(0, 0), b2, voffB); PG8_STAGE(PG8_SB(0, 1), b2 + hstepB, voffB); PG8_STAGE(PG8_SA(0, 0), a2, voffA);
;             PG8_WAIT_V(8); PG8_WAIT_L(0); PG8_BAR; PG8_MMA(1, 0, At, B0); PG8_MMA(1, 1, At, B1); PG8_BAR; PG8_SCHED;
	v_mfma_f32_16x16x32_bf16 v[122:125], v[152:155], v[184:187], v[122:125]
	v_mfma_f32_16x16x32_bf16 v[118:121], v[160:163], v[184:187], v[118:121]
	v_mfma_f32_16x16x32_bf16 v[106:109], v[152:155], v[192:195], v[106:109]
	v_mfma_f32_16x16x32_bf16 v[102:105], v[160:163], v[192:195], v[102:105]
	v_mfma_f32_16x16x32_bf16 v[90:93], v[152:155], v[200:203], v[90:93]
	v_mfma_f32_16x16x32_bf16 v[86:89], v[160:163], v[200:203], v[86:89]
	v_mfma_f32_16x16x32_bf16 v[74:77], v[152:155], v[208:211], v[74:77]
	v_mfma_f32_16x16x32_bf16 v[70:73], v[160:163], v[208:211], v[70:73]
	v_mfma_f32_16x16x32_bf16 v[122:125], v[156:159], v[188:191], v[122:125]
	v_mfma_f32_16x16x32_bf16 v[118:121], v[164:167], v[188:191], v[118:121]
	v_mfma_f32_16x16x32_bf16 v[106:109], v[156:159], v[196:199], v[106:109]
	v_mfma_f32_16x16x32_bf16 v[102:105], v[164:167], v[196:199], v[102:105]
	v_mfma_f32_16x16x32_bf16 v[90:93], v[156:159], v[204:207], v[90:93]
	v_mfma_f32_16x16x32_bf16 v[86:89], v[164:167], v[204:207], v[86:89]
	v_mfma_f32_16x16x32_bf16 v[74:77], v[156:159], v[212:215], v[74:77]
	v_mfma_f32_16x16x32_bf16 v[70:73], v[164:167], v[212:215], v[70:73]
	v_mfma_f32_16x16x32_bf16 v[126:129], v[168:171], v[184:187], v[126:129]
	v_mfma_f32_16x16x32_bf16 v[114:117], v[176:179], v[184:187], v[114:117]
	v_mfma_f32_16x16x32_bf16 v[110:113], v[168:171], v[192:195], v[110:113]
	v_mfma_f32_16x16x32_bf16 v[98:101], v[176:179], v[192:195], v[98:101]
	v_mfma_f32_16x16x32_bf16 v[94:97], v[168:171], v[200:203], v[94:97]
	v_mfma_f32_16x16x32_bf16 v[82:85], v[176:179], v[200:203], v[82:85]
	v_mfma_f32_16x16x32_bf16 v[78:81], v[168:171], v[208:211], v[78:81]
	v_mfma_f32_16x16x32_bf16 v[66:69], v[176:179], v[208:211], v[66:69]
	v_mfma_f32_16x16x32_bf16 v[126:129], v[172:175], v[188:191], v[126:129]
	v_mfma_f32_16x16x32_bf16 v[114:117], v[180:183], v[188:191], v[114:117]
	v_mfma_f32_16x16x32_bf16 v[110:113], v[172:175], v[196:199], v[110:113]
	v_mfma_f32_16x16x32_bf16 v[98:101], v[180:183], v[196:199], v[98:101]
	v_mfma_f32_16x16x32_bf16 v[94:97], v[172:175], v[204:207], v[94:97]
	v_mfma_f32_16x16x32_bf16 v[82:85], v[180:183], v[204:207], v[82:85]
	v_mfma_f32_16x16x32_bf16 v[78:81], v[172:175], v[212:215], v[78:81]
	v_mfma_f32_16x16x32_bf16 v[66:69], v[180:183], v[212:215], v[66:69]
	s_barrier
	s_add_i32 s55, s44, s33
	s_mov_b32 m0, s55
	ds_read_b128 v[184:187], v150 offset:16384
	ds_read_b128 v[188:191], v150 offset:17408
	ds_read_b128 v[192:195], v150 offset:18432
	ds_read_b128 v[196:199], v150 offset:19456
	global_load_lds_dwordx4 v134, s[30:31]
	s_add_i32 m0, s55, 0x2000
	s_add_u32 s56, s30, 0x4000
	s_addc_u32 s57, s31, 0
	s_add_i32 s55, s45, s33
	global_load_lds_dwordx4 v130, s[30:31]
	s_mov_b32 m0, s55
	ds_read_b128 v[200:203], v150 offset:20480
	global_load_lds_dwordx4 v134, s[56:57]
	s_add_i32 m0, s55, 0x2000
	ds_read_b128 v[204:207], v150 offset:21504
	global_load_lds_dwordx4 v130, s[56:57]
	s_mov_b32 m0, s21
	ds_read_b128 v[208:211], v150 offset:22528
	global_load_lds_dwordx4 v136, s[34:35]
	s_mov_b32 m0, s23
	ds_read_b128 v[212:215], v150 offset:23552
	global_load_lds_dwordx4 v132, s[34:35]
	s_waitcnt vmcnt(8) lgkmcnt(0)
	s_barrier
	v_mfma_f32_16x16x32_bf16 v[58:61], v[152:155], v[184:187], v[58:61]
	v_mfma_f32_16x16x32_bf16 v[54:57], v[160:163], v[184:187], v[54:57]
	v_mfma_f32_16x16x32_bf16 v[42:45], v[152:155], v[192:195], v[42:45]
	v_mfma_f32_16x16x32_bf16 v[38:41], v[160:163], v[192:195], v[38:41]
	v_mfma_f32_16x16x32_bf16 v[26:29], v[152:155], v[200:203], v[26:29]
	v_mfma_f32_16x16x32_bf16 v[22:25], v[160:163], v[200:203], v[22:25]
	v_mfma_f32_16x16x32_bf16 v[10:13], v[152:155], v[208:211], v[10:13]
	v_mfma_f32_16x16x32_bf16 v[6:9], v[160:163], v[208:211], v[6:9]
	v_mfma_f32_16x16x32_bf16 v[58:61], v[156:159], v[188:191], v[58:61]
	v_mfma_f32_16x16x32_bf16 v[54:57], v[164:167], v[188:191], v[54:57]
	v_mfma_f32_16x16x32_bf16 v[42:45], v[156:159], v[196:199], v[42:45]
	v_mfma_f32_16x16x32_bf16 v[38:41], v[164:167], v[196:199], v[38:41]
	v_mfma_f32_16x16x32_bf16 v[26:29], v[156:159], v[204:207], v[26:29]
	v_mfma_f32_16x16x32_bf16 v[22:25], v[164:167], v[204:207], v[22:25]
	v_mfma_f32_16x16x32_bf16 v[10:13], v[156:159], v[212:215], v[10:13]
	v_mfma_f32_16x16x32_bf16 v[6:9], v[164:167], v[212:215], v[6:9]
	v_mfma_f32_16x16x32_bf16 v[62:65], v[168:171], v[184:187], v[62:65]
	v_mfma_f32_16x16x32_bf16 v[50:53], v[176:179], v[184:187], v[50:53]
	v_mfma_f32_16x16x32_bf16 v[46:49], v[168:171], v[192:195], v[46:49]
	v_mfma_f32_16x16x32_bf16 v[34:37], v[176:179], v[192:195], v[34:37]
	v_mfma_f32_16x16x32_bf16 v[30:33], v[168:171], v[200:203], v[30:33]
	v_mfma_f32_16x16x32_bf16 v[18:21], v[176:179], v[200:203], v[18:21]
	v_mfma_f32_16x16x32_bf16 v[14:17], v[168:171], v[208:211], v[14:17]
	v_mfma_f32_16x16x32_bf16 v[2:5], v[176:179], v[208:211], v[2:5]
	v_mfma_f32_16x16x32_bf16 v[62:65], v[172:175], v[188:191], v[62:65]
	v_mfma_f32_16x16x32_bf16 v[50:53], v[180:183], v[188:191], v[50:53]
	v_mfma_f32_16x16x32_bf16 v[46:49], v[172:175], v[196:199], v[46:49]
	v_mfma_f32_16x16x32_bf16 v[34:37], v[180:183], v[196:199], v[34:37]
	v_mfma_f32_16x16x32_bf16 v[30:33], v[172:175], v[204:207], v[30:33]
	v_mfma_f32_16x16x32_bf16 v[18:21], v[180:183], v[204:207], v[18:21]
	v_mfma_f32_16x16x32_bf16 v[14:17], v[172:175], v[212:215], v[14:17]
	v_mfma_f32_16x16x32_bf16 v[2:5], v[180:183], v[212:215], v[2:5]
	s_barrier
; #define PG8_STAGE(bufoff, gbase, voff) do { _Pragma("unroll") for (int _i = 0; _i < 2; ++_i) \
;         __builtin_amdgcn_global_load_lds((const unsigned*)((const char*)(gbase) + (voff)[_i]), (LAS unsigned*)(lds + (bufoff) + ldsw + _i * 8192), 16, 0, 0); } while (0)
; #define PG8_LDA(dst, b, h) do { _Pragma("unroll") for (int m = 0; m < 4; ++m) _Pragma("unroll") for (int k = 0; k < 2; ++k) dst[m][k] = *(const LAS bf16x8*)(lds + PG8_SA(b, h) + aoff + m * 2048 + k * 1024); } while (0)
; #define PG8_LDB(dst, b, h) do { _Pragma("unroll") for (int n = 0; n < 2; ++n) _Pragma("unroll") for (int k = 0; k < 2; ++k) dst[n][k] = *(const LAS bf16x8*)(lds + PG8_SB(b, h) + boff + n * 2048 + k * 1024); } while (0)
; #define PG8_MMA(ai, bj, At, Bt) do { __builtin_amdgcn_s_setprio(1); _Pragma("unroll") for (int m = 0; m < 4; ++m) _Pragma("unroll") for (int n = 0; n < 2; ++n) _Pragma("unroll") for (int k = 0; k < 2; ++k) \
;         acc[ai][bj][m][n] = __builtin_amdgcn_mfma_f32_16x16x32_bf16(Bt[n][k], At[m][k], acc[ai][bj][m][n], 0, 0, 0); __builtin_amdgcn_s_setprio(0); } while (0)
; #define PG8_WAIT_V(n) asm volatile("s_waitcnt vmcnt(" #n ")" ::: "memory")
; #define PG8_WAIT_L(n) asm volatile("s_waitcnt lgkmcnt(" #n ")" ::: "memory")
; #define PG8_BAR __builtin_amdgcn_s_barrier()
; #define PG8_SCHED __builtin_amdgcn_sched_barrier(0)
; template <class Epi, class Sched, bool ABLK = false, bool ALIGN_EPI = true, bool SP2 = true, bool BBLK = true>
; __device__ __forceinline__ void gemm_phase(LAS unsigned char* lds, const Gemm g, const Sched& S, const Epi& E) {
;     ...
;             PG8_LDB(B0, 1, 0); PG8_LDB(B1, 1, 1); PG8_SCHED; PG8_LDA(At, 1, 0); PG8_STAGE(PG8_SA(0, 1), a2 + hstepA, voffA);
;             PG8_WAIT_V(8); PG8_WAIT_L(0); PG8_BAR; PG8_MMA(0, 0, At, B0); PG8_MMA(0, 1, At, B1); PG8_BAR; PG8_SCHED;
;             PG8_LDA(At, 1, 1); PG8_STAGE(PG8_SB(1, 0), b3, voffB); PG8_STAGE(PG8_SB(1, 1), b3 + hstepB, voffB); PG8_STAGE(PG8_SA(1, 0), a3, voffA);
;             PG8_WAIT_V(8); PG8_WAIT_L(0); PG8_BAR; PG8_MMA(1, 0, At, B0); PG8_MMA(1, 1, At, B1); PG8_BAR; PG8_SCHED;
	s_add_i32 s55, 0, 0x18000
	v_add_u32_e32 v151, s55, v146
	s_add_i32 s56, 0, 0x1c000
	ds_read_b128 v[152:155], v151
	ds_read_b128 v[156:159], v151 offset:1024
	ds_read_b128 v[160:163], v151 offset:2048
	ds_read_b128 v[164:167], v151 offset:3072
	v_add_u32_e32 v151, s56, v146
	ds_read_b128 v[168:171], v151
	ds_read_b128 v[172:175], v151 offset:1024
	ds_read_b128 v[176:179], v151 offset:2048
	ds_read_b128 v[180:183], v151 offset:3072
	s_add_u32 s34, s34, 0x80000
	s_addc_u32 s35, s35, 0
	s_mov_b32 m0, s39
	ds_read_b128 v[184:187], v150 offset:32768
	ds_read_b128 v[188:191], v150 offset:33792
	ds_read_b128 v[192:195], v150 offset:34816
	ds_read_b128 v[196:199], v150 offset:35840
	ds_read_b128 v[200:203], v150 offset:36864
	ds_read_b128 v[204:207], v150 offset:37888
	ds_read_b128 v[208:211], v150 offset:38912
	global_load_lds_dwordx4 v136, s[34:35]
	s_mov_b32 m0, s40
	ds_read_b128 v[212:215], v150 offset:39936
	global_load_lds_dwordx4 v132, s[34:35]
	s_waitcnt vmcnt(8) lgkmcnt(0)
	s_barrier
	v_mfma_f32_16x16x32_bf16 v[122:125], v[152:155], v[184:187], v[122:125]
	v_mfma_f32_16x16x32_bf16 v[118:121], v[160:163], v[184:187], v[118:121]
	v_mfma_f32_16x16x32_bf16 v[106:109], v[152:155], v[192:195], v[106:109]
	v_mfma_f32_16x16x32_bf16 v[102:105], v[160:163], v[192:195], v[102:105]
	v_mfma_f32_16x16x32_bf16 v[90:93], v[152:155], v[200:203], v[90:93]
	v_mfma_f32_16x16x32_bf16 v[86:89], v[160:163], v[200:203], v[86:89]
	v_mfma_f32_16x16x32_bf16 v[74:77], v[152:155], v[208:211], v[74:77]
	v_mfma_f32_16x16x32_bf16 v[70:73], v[160:163], v[208:211], v[70:73]
	v_mfma_f32_16x16x32_bf16 v[122:125], v[156:159], v[188:191], v[122:125]
	v_mfma_f32_16x16x32_bf16 v[118:121], v[164:167], v[188:191], v[118:121]
	v_mfma_f32_16x16x32_bf16 v[106:109], v[156:159], v[196:199], v[106:109]
	v_mfma_f32_16x16x32_bf16 v[102:105], v[164:167], v[196:199], v[102:105]
	v_mfma_f32_16x16x32_bf16 v[90:93], v[156:159], v[204:207], v[90:93]
	v_mfma_f32_16x16x32_bf16 v[86:89], v[164:167], v[204:207], v[86:89]
	v_mfma_f32_16x16x32_bf16 v[74:77], v[156:159], v[212:215], v[74:77]
	v_mfma_f32_16x16x32_bf16 v[70:73], v[164:167], v[212:215], v[70:73]
	v_mfma_f32_16x16x32_bf16 v[126:129], v[168:171], v[184:187], v[126:129]
	v_mfma_f32_16x16x32_bf16 v[114:117], v[176:179], v[184:187], v[114:117]
	v_mfma_f32_16x16x32_bf16 v[110:113], v[168:171], v[192:195], v[110:113]
	v_mfma_f32_16x16x32_bf16 v[98:101], v[176:179], v[192:195], v[98:101]
	v_mfma_f32_16x16x32_bf16 v[94:97], v[168:171], v[200:203], v[94:97]
	v_mfma_f32_16x16x32_bf16 v[82:85], v[176:179], v[200:203], v[82:85]
	v_mfma_f32_16x16x32_bf16 v[78:81], v[168:171], v[208:211], v[78:81]
	v_mfma_f32_16x16x32_bf16 v[66:69], v[176:179], v[208:211], v[66:69]
	v_mfma_f32_16x16x32_bf16 v[126:129], v[172:175], v[188:191], v[126:129]
	v_mfma_f32_16x16x32_bf16 v[114:117], v[180:183], v[188:191], v[114:117]
	v_mfma_f32_16x16x32_bf16 v[110:113], v[172:175], v[196:199], v[110:113]
	v_mfma_f32_16x16x32_bf16 v[98:101], v[180:183], v[196:199], v[98:101]
	v_mfma_f32_16x16x32_bf16 v[94:97], v[172:175], v[204:207], v[94:97]
	v_mfma_f32_16x16x32_bf16 v[82:85], v[180:183], v[204:207], v[82:85]
	v_mfma_f32_16x16x32_bf16 v[78:81], v[172:175], v[212:215], v[78:81]
	v_mfma_f32_16x16x32_bf16 v[66:69], v[180:183], v[212:215], v[66:69]
	s_barrier
	s_add_u32 s34, s30, 0x8000
	s_addc_u32 s35, s31, 0
	s_add_i32 s55, s55, s33
	s_mov_b32 m0, s55
	ds_read_b128 v[184:187], v150 offset:49152
	ds_read_b128 v[188:191], v150 offset:50176
	ds_read_b128 v[192:195], v150 offset:51200
	ds_read_b128 v[196:199], v150 offset:52224
	global_load_lds_dwordx4 v134, s[34:35]
	s_add_i32 m0, s55, 0x2000
	s_add_u32 s30, s30, 0xc000
	v_lshl_add_u64 v[216:217], s[34:35], 0, v[130:131]
	s_addc_u32 s31, s31, 0
	s_add_i32 s34, s56, s33
	global_load_lds_dwordx4 v[216:217], off
	s_mov_b32 m0, s34
	ds_read_b128 v[200:203], v150 offset:53248
	global_load_lds_dwordx4 v134, s[30:31]
	s_add_i32 m0, s34, 0x2000
	ds_read_b128 v[204:207], v150 offset:54272
	global_load_lds_dwordx4 v130, s[30:31]
	s_mov_b32 m0, s42
	ds_read_b128 v[208:211], v150 offset:55296
	global_load_lds_dwordx4 v136, s[28:29]
	s_mov_b32 m0, s43
	ds_read_b128 v[212:215], v150 offset:56320
	global_load_lds_dwordx4 v132, s[28:29]
	s_waitcnt vmcnt(8) lgkmcnt(0)
	s_barrier
	v_mfma_f32_16x16x32_bf16 v[58:61], v[152:155], v[184:187], v[58:61]
	v_mfma_f32_16x16x32_bf16 v[54:57], v[160:163], v[184:187], v[54:57]
	v_mfma_f32_16x16x32_bf16 v[42:45], v[152:155], v[192:195], v[42:45]
	v_mfma_f32_16x16x32_bf16 v[38:41], v[160:163], v[192:195], v[38:41]
	v_mfma_f32_16x16x32_bf16 v[26:29], v[152:155], v[200:203], v[26:29]
	v_mfma_f32_16x16x32_bf16 v[22:25], v[160:163], v[200:203], v[22:25]
	v_mfma_f32_16x16x32_bf16 v[10:13], v[152:155], v[208:211], v[10:13]
	v_mfma_f32_16x16x32_bf16 v[6:9], v[160:163], v[208:211], v[6:9]
	v_mfma_f32_16x16x32_bf16 v[58:61], v[156:159], v[188:191], v[58:61]
	v_mfma_f32_16x16x32_bf16 v[54:57], v[164:167], v[188:191], v[54:57]
	v_mfma_f32_16x16x32_bf16 v[42:45], v[156:159], v[196:199], v[42:45]
	v_mfma_f32_16x16x32_bf16 v[38:41], v[164:167], v[196:199], v[38:41]
	v_mfma_f32_16x16x32_bf16 v[26:29], v[156:159], v[204:207], v[26:29]
	v_mfma_f32_16x16x32_bf16 v[22:25], v[164:167], v[204:207], v[22:25]
	v_mfma_f32_16x16x32_bf16 v[10:13], v[156:159], v[212:215], v[10:13]
	v_mfma_f32_16x16x32_bf16 v[6:9], v[164:167], v[212:215], v[6:9]
	v_mfma_f32_16x16x32_bf16 v[62:65], v[168:171], v[184:187], v[62:65]
	v_mfma_f32_16x16x32_bf16 v[50:53], v[176:179], v[184:187], v[50:53]
	v_mfma_f32_16x16x32_bf16 v[46:49], v[168:171], v[192:195], v[46:49]
	v_mfma_f32_16x16x32_bf16 v[34:37], v[176:179], v[192:195], v[34:37]
	v_mfma_f32_16x16x32_bf16 v[30:33], v[168:171], v[200:203], v[30:33]
	v_mfma_f32_16x16x32_bf16 v[18:21], v[176:179], v[200:203], v[18:21]
	v_mfma_f32_16x16x32_bf16 v[14:17], v[168:171], v[208:211], v[14:17]
	v_mfma_f32_16x16x32_bf16 v[2:5], v[176:179], v[208:211], v[2:5]
	v_mfma_f32_16x16x32_bf16 v[62:65], v[172:175], v[188:191], v[62:65]
	v_mfma_f32_16x16x32_bf16 v[50:53], v[180:183], v[188:191], v[50:53]
	v_mfma_f32_16x16x32_bf16 v[46:49], v[172:175], v[196:199], v[46:49]
	v_mfma_f32_16x16x32_bf16 v[34:37], v[180:183], v[196:199], v[34:37]
	v_mfma_f32_16x16x32_bf16 v[30:33], v[172:175], v[204:207], v[30:33]
	v_mfma_f32_16x16x32_bf16 v[18:21], v[180:183], v[204:207], v[18:21]
	v_mfma_f32_16x16x32_bf16 v[14:17], v[172:175], v[212:215], v[14:17]
	v_mfma_f32_16x16x32_bf16 v[2:5], v[180:183], v[212:215], v[2:5]
	s_barrier
	s_add_i32 s54, s54, 2
	s_add_u32 s26, s26, 0x100
	s_addc_u32 s27, s27, 0
	s_add_u32 s52, s52, 0x10000
	s_addc_u32 s53, s53, 0
	s_cmp_gt_u32 s54, 29
	s_cbranch_scc0 .LBB0_350
	s_and_b64 vcc, exec, s[6:7]
	s_cbranch_vccz .LBB0_353
	s_barrier

; #define PG8_STAGE(bufoff, gbase, voff) do { _Pragma("unroll") for (int _i = 0; _i < 2; ++_i) \
;         __builtin_amdgcn_global_load_lds((const unsigned*)((const char*)(gbase) + (voff)[_i]), (LAS unsigned*)(lds + (bufoff) + ldsw + _i * 8192), 16, 0, 0); } while (0)
; #define PG8_LDA(dst, b, h) do { _Pragma("unroll") for (int m = 0; m < 4; ++m) _Pragma("unroll") for (int k = 0; k < 2; ++k) dst[m][k] = *(const LAS bf16x8*)(lds + PG8_SA(b, h) + aoff + m * 2048 + k * 1024); } while (0)
; #define PG8_LDB(dst, b, h) do { _Pragma("unroll") for (int n = 0; n < 2; ++n) _Pragma("unroll") for (int k = 0; k < 2; ++k) dst[n][k] = *(const LAS bf16x8*)(lds + PG8_SB(b, h) + boff + n * 2048 + k * 1024); } while (0)
; #define PG8_WAIT_V(n) asm volatile("s_waitcnt vmcnt(" #n ")" ::: "memory")
; #define PG8_WAIT_L(n) asm volatile("s_waitcnt lgkmcnt(" #n ")" ::: "memory")
; template <class Epi, class Sched, bool ABLK = false, bool ALIGN_EPI = true, bool SP2 = true, bool BBLK = true>
; __device__ __forceinline__ void gemm_phase(LAS unsigned char* lds, const Gemm g, const Sched& S, const Epi& E) {
;     ...
;         const bool has_next = S.next(ui + 1, nxt);
;         const int nt = cur.nt;
;         const char* nuA = has_next ? a_unit(nxt) : uA; const int ntbA = has_next ? nxt.k0 / BK : tbA; const char* nB = has_next ? (const char*)g.Bt + (size_t)nxt.pn * tstepB + b_k0(nxt.k0) : cB;
;         for (int t = 0; t < nt; t += 2) {
;             const bool last = (t == nt - 2);
;             const char* a1 = a_tile(uA, tbA + t + 1);
;             const char* a2 = last ? a_tile(nuA, ntbA) : a_tile(uA, tbA + t + 2); const char* b2 = last ? nB : cB + (size_t)(t + 2) * kstepB;
;             const char* a3 = last ? a_tile(nuA, ntbA + 1) : a_tile(uA, tbA + t + 3); const char* b3 = b2 + kstepB;
;             if (last && has_next) S.a_ready(nxt);
;             if constexpr (SP2) {
;             PG8_LDB(B0, 0, 0); PG8_LDB(B1, 0, 1); PG8_SCHED; PG8_LDA(At, 0, 0); PG8_STAGE(PG8_SA(1, 1), a1 + hstepA, voffA);
;             PG8_WAIT_V(8); PG8_WAIT_L(0); PG8_BAR; PG8_MMA(0, 0, At, B0); PG8_MMA(0, 1, At, B1); PG8_BAR; PG8_SCHED;
;             PG8_LDA(At, 0, 1); PG8_STAGE(PG8_SB(0, 0), b2, voffB); PG8_STAGE(PG8_SB(0, 1), b2 + hstepB, voffB); PG8_STAGE(PG8_SA(0, 0), a2, voffA);
;             PG8_WAIT_V(8); PG8_WAIT_L(0); PG8_BAR; PG8_MMA(1, 0, At, B0); PG8_MMA(1, 1, At, B1); PG8_BAR; PG8_SCHED;
.LBB0_474:
	s_ashr_i32 s11, s10, 31
	s_lshl_b64 s[4:5], s[10:11], 20
	s_add_u32 s14, s41, s4
	s_addc_u32 s15, s42, s5
	s_and_b64 s[4:5], s[18:19], exec
	s_cselect_b32 s4, s15, s27
	s_cselect_b32 s5, s14, s26
	s_ashr_i32 s13, s12, 31
	s_lshl_b64 s[20:21], s[12:13], 20
	s_add_u32 s20, s0, s20
	s_addc_u32 s21, s39, s21
	s_and_b64 s[30:31], s[18:19], exec
	s_cselect_b32 s11, s21, s29
	s_cselect_b32 s13, s20, s28
	s_add_u32 s23, s5, 0x80
	s_addc_u32 s57, s4, 0
	s_add_u32 s58, s28, 0x10000
	v_mov_b32_e32 v2, 0
	s_addc_u32 s59, s29, 0
	v_lshl_add_u64 v[164:165], s[26:27], 0, v[160:161]
	v_lshl_add_u64 v[166:167], s[26:27], 0, v[162:163]
	s_mov_b32 s60, -2
	s_mov_b64 s[28:29], 0
	ds_read_b128 v[172:175], v168
	ds_read_b128 v[176:179], v168 offset:1024
	ds_read_b128 v[180:183], v168 offset:2048
	ds_read_b128 v[184:187], v168 offset:3072
	ds_read_b128 v[188:191], v169
	ds_read_b128 v[192:195], v169 offset:1024
	ds_read_b128 v[196:199], v169 offset:2048
	ds_read_b128 v[200:203], v169 offset:3072
	s_add_u32 s30, s26, s28
	s_addc_u32 s31, s27, s29
	s_add_u32 s36, s30, 0x100
	s_addc_u32 s37, s31, 0
	s_add_u32 s30, s30, 0x180
	s_addc_u32 s31, s31, 0
	s_cmpk_eq_i32 s28, 0xf00
	s_cselect_b32 s31, s57, s31
	s_cselect_b32 s30, s23, s30
	s_cselect_b32 s35, s11, s59
	s_cselect_b32 s34, s13, s58
	s_cselect_b32 s37, s4, s37
	s_cselect_b32 s36, s5, s36
	s_mov_b32 m0, s53
	v_lshl_add_u64 v[236:237], v[164:165], 0, s[28:29]
	ds_read_b128 v[204:207], v170
	ds_read_b128 v[208:211], v170 offset:1024
	ds_read_b128 v[212:215], v170 offset:2048
	ds_read_b128 v[216:219], v170 offset:3072
	ds_read_b128 v[220:223], v170 offset:4096
	ds_read_b128 v[224:227], v170 offset:5120
	ds_read_b128 v[228:231], v170 offset:6144
	global_load_lds_dwordx4 v[236:237], off
	v_lshl_add_u64 v[236:237], v[166:167], 0, s[28:29]
	s_mov_b32 m0, s54
	ds_read_b128 v[232:235], v170 offset:7168
	global_load_lds_dwordx4 v[236:237], off
	s_waitcnt vmcnt(8) lgkmcnt(0)
	s_barrier
	v_mfma_f32_16x16x32_bf16 v[126:129], v[172:175], v[204:207], 0
	v_mfma_f32_16x16x32_bf16 v[122:125], v[180:183], v[204:207], 0
	v_mfma_f32_16x16x32_bf16 v[110:113], v[172:175], v[212:215], 0
	v_mfma_f32_16x16x32_bf16 v[106:109], v[180:183], v[212:215], 0
	v_mfma_f32_16x16x32_bf16 v[94:97], v[172:175], v[220:223], 0
	v_mfma_f32_16x16x32_bf16 v[90:93], v[180:183], v[220:223], 0
	v_mfma_f32_16x16x32_bf16 v[78:81], v[172:175], v[228:231], 0
	v_mfma_f32_16x16x32_bf16 v[74:77], v[180:183], v[228:231], 0
	v_mfma_f32_16x16x32_bf16 v[126:129], v[176:179], v[208:211], v[126:129]
	v_mfma_f32_16x16x32_bf16 v[122:125], v[184:187], v[208:211], v[122:125]
	v_mfma_f32_16x16x32_bf16 v[110:113], v[176:179], v[216:219], v[110:113]
	v_mfma_f32_16x16x32_bf16 v[106:109], v[184:187], v[216:219], v[106:109]
	v_mfma_f32_16x16x32_bf16 v[94:97], v[176:179], v[224:227], v[94:97]
	v_mfma_f32_16x16x32_bf16 v[90:93], v[184:187], v[224:227], v[90:93]
	v_mfma_f32_16x16x32_bf16 v[78:81], v[176:179], v[232:235], v[78:81]
	v_mfma_f32_16x16x32_bf16 v[74:77], v[184:187], v[232:235], v[74:77]
	v_mfma_f32_16x16x32_bf16 v[118:121], v[188:191], v[204:207], 0
	v_mfma_f32_16x16x32_bf16 v[114:117], v[196:199], v[204:207], 0
	v_mfma_f32_16x16x32_bf16 v[102:105], v[188:191], v[212:215], 0
	v_mfma_f32_16x16x32_bf16 v[98:101], v[196:199], v[212:215], 0
	v_mfma_f32_16x16x32_bf16 v[86:89], v[188:191], v[220:223], 0
	v_mfma_f32_16x16x32_bf16 v[82:85], v[196:199], v[220:223], 0
	v_mfma_f32_16x16x32_bf16 v[70:73], v[188:191], v[228:231], 0
	v_mfma_f32_16x16x32_bf16 v[66:69], v[196:199], v[228:231], 0
	v_mfma_f32_16x16x32_bf16 v[118:121], v[192:195], v[208:211], v[118:121]
	v_mfma_f32_16x16x32_bf16 v[114:117], v[200:203], v[208:211], v[114:117]
	v_mfma_f32_16x16x32_bf16 v[102:105], v[192:195], v[216:219], v[102:105]
	v_mfma_f32_16x16x32_bf16 v[98:101], v[200:203], v[216:219], v[98:101]
	v_mfma_f32_16x16x32_bf16 v[86:89], v[192:195], v[224:227], v[86:89]
	v_mfma_f32_16x16x32_bf16 v[82:85], v[200:203], v[224:227], v[82:85]
	v_mfma_f32_16x16x32_bf16 v[70:73], v[192:195], v[232:235], v[70:73]
	v_mfma_f32_16x16x32_bf16 v[66:69], v[200:203], v[232:235], v[66:69]
	s_barrier
	s_mov_b32 m0, s55
	s_add_u32 s62, s34, 0x4000
	ds_read_b128 v[204:207], v170 offset:16384
	ds_read_b128 v[208:211], v170 offset:17408
	ds_read_b128 v[212:215], v170 offset:18432
	ds_read_b128 v[216:219], v170 offset:19456
	global_load_lds_dwordx4 v134, s[34:35]
	s_mov_b32 m0, s56
	s_addc_u32 s63, s35, 0
	s_add_i32 s61, s52, s40
	global_load_lds_dwordx4 v130, s[34:35]
	s_mov_b32 m0, s61
	ds_read_b128 v[220:223], v170 offset:20480
	global_load_lds_dwordx4 v134, s[62:63]
	s_add_i32 m0, s61, 0x2000
	ds_read_b128 v[224:227], v170 offset:21504
	global_load_lds_dwordx4 v130, s[62:63]
	s_mov_b32 m0, s25
	ds_read_b128 v[228:231], v170 offset:22528
	global_load_lds_dwordx4 v136, s[36:37]
	s_mov_b32 m0, s43
	ds_read_b128 v[232:235], v170 offset:23552
	global_load_lds_dwordx4 v132, s[36:37]
	s_waitcnt vmcnt(8) lgkmcnt(0)
	s_barrier
; #define PG8_STAGE(bufoff, gbase, voff) do { _Pragma("unroll") for (int _i = 0; _i < 2; ++_i) \
;         __builtin_amdgcn_global_load_lds((const unsigned*)((const char*)(gbase) + (voff)[_i]), (LAS unsigned*)(lds + (bufoff) + ldsw + _i * 8192), 16, 0, 0); } while (0)
; #define PG8_LDA(dst, b, h) do { _Pragma("unroll") for (int m = 0; m < 4; ++m) _Pragma("unroll") for (int k = 0; k < 2; ++k) dst[m][k] = *(const LAS bf16x8*)(lds + PG8_SA(b, h) + aoff + m * 2048 + k * 1024); } while (0)
; #define PG8_LDB(dst, b, h) do { _Pragma("unroll") for (int n = 0; n < 2; ++n) _Pragma("unroll") for (int k = 0; k < 2; ++k) dst[n][k] = *(const LAS bf16x8*)(lds + PG8_SB(b, h) + boff + n * 2048 + k * 1024); } while (0)
; #define PG8_MMA(ai, bj, At, Bt) do { __builtin_amdgcn_s_setprio(1); _Pragma("unroll") for (int m = 0; m < 4; ++m) _Pragma("unroll") for (int n = 0; n < 2; ++n) _Pragma("unroll") for (int k = 0; k < 2; ++k) \
;         acc[ai][bj][m][n] = __builtin_amdgcn_mfma_f32_16x16x32_bf16(Bt[n][k], At[m][k], acc[ai][bj][m][n], 0, 0, 0); __builtin_amdgcn_s_setprio(0); } while (0)
; #define PG8_WAIT_V(n) asm volatile("s_waitcnt vmcnt(" #n ")" ::: "memory")
; #define PG8_WAIT_L(n) asm volatile("s_waitcnt lgkmcnt(" #n ")" ::: "memory")
; #define PG8_BAR __builtin_amdgcn_s_barrier()
; #define PG8_SCHED __builtin_amdgcn_sched_barrier(0)
; template <class Epi, class Sched, bool ABLK = false, bool ALIGN_EPI = true, bool SP2 = true, bool BBLK = true>
; __device__ __forceinline__ void gemm_phase(LAS unsigned char* lds, const Gemm g, const Sched& S, const Epi& E) {
;     ...
;             PG8_LDB(B0, 1, 0); PG8_LDB(B1, 1, 1); PG8_SCHED; PG8_LDA(At, 1, 0); PG8_STAGE(PG8_SA(0, 1), a2 + hstepA, voffA);
;             PG8_WAIT_V(8); PG8_WAIT_L(0); PG8_BAR; PG8_MMA(0, 0, At, B0); PG8_MMA(0, 1, At, B1); PG8_BAR; PG8_SCHED;
;             PG8_LDA(At, 1, 1); PG8_STAGE(PG8_SB(1, 0), b3, voffB); PG8_STAGE(PG8_SB(1, 1), b3 + hstepB, voffB); PG8_STAGE(PG8_SA(1, 0), a3, voffA);
;             PG8_WAIT_V(8); PG8_WAIT_L(0); PG8_BAR; PG8_MMA(1, 0, At, B0); PG8_MMA(1, 1, At, B1); PG8_BAR; PG8_SCHED;
	v_mfma_f32_16x16x32_bf16 v[62:65], v[172:175], v[204:207], 0
	v_mfma_f32_16x16x32_bf16 v[58:61], v[180:183], v[204:207], 0
	v_mfma_f32_16x16x32_bf16 v[46:49], v[172:175], v[212:215], 0
	v_mfma_f32_16x16x32_bf16 v[42:45], v[180:183], v[212:215], 0
	v_mfma_f32_16x16x32_bf16 v[30:33], v[172:175], v[220:223], 0
	v_mfma_f32_16x16x32_bf16 v[26:29], v[180:183], v[220:223], 0
	v_mfma_f32_16x16x32_bf16 v[14:17], v[172:175], v[228:231], 0
	v_mfma_f32_16x16x32_bf16 v[10:13], v[180:183], v[228:231], 0
	v_mfma_f32_16x16x32_bf16 v[62:65], v[176:179], v[208:211], v[62:65]
	v_mfma_f32_16x16x32_bf16 v[58:61], v[184:187], v[208:211], v[58:61]
	v_mfma_f32_16x16x32_bf16 v[46:49], v[176:179], v[216:219], v[46:49]
	v_mfma_f32_16x16x32_bf16 v[42:45], v[184:187], v[216:219], v[42:45]
	v_mfma_f32_16x16x32_bf16 v[30:33], v[176:179], v[224:227], v[30:33]
	v_mfma_f32_16x16x32_bf16 v[26:29], v[184:187], v[224:227], v[26:29]
	v_mfma_f32_16x16x32_bf16 v[14:17], v[176:179], v[232:235], v[14:17]
	v_mfma_f32_16x16x32_bf16 v[10:13], v[184:187], v[232:235], v[10:13]
	v_mfma_f32_16x16x32_bf16 v[54:57], v[188:191], v[204:207], 0
	v_mfma_f32_16x16x32_bf16 v[50:53], v[196:199], v[204:207], 0
	v_mfma_f32_16x16x32_bf16 v[38:41], v[188:191], v[212:215], 0
	v_mfma_f32_16x16x32_bf16 v[34:37], v[196:199], v[212:215], 0
	v_mfma_f32_16x16x32_bf16 v[22:25], v[188:191], v[220:223], 0
	v_mfma_f32_16x16x32_bf16 v[18:21], v[196:199], v[220:223], 0
	v_mfma_f32_16x16x32_bf16 v[6:9], v[188:191], v[228:231], 0
	v_mfma_f32_16x16x32_bf16 v[2:5], v[196:199], v[228:231], 0
	v_mfma_f32_16x16x32_bf16 v[54:57], v[192:195], v[208:211], v[54:57]
	v_mfma_f32_16x16x32_bf16 v[50:53], v[200:203], v[208:211], v[50:53]
	v_mfma_f32_16x16x32_bf16 v[38:41], v[192:195], v[216:219], v[38:41]
	v_mfma_f32_16x16x32_bf16 v[34:37], v[200:203], v[216:219], v[34:37]
	v_mfma_f32_16x16x32_bf16 v[22:25], v[192:195], v[224:227], v[22:25]
	v_mfma_f32_16x16x32_bf16 v[18:21], v[200:203], v[224:227], v[18:21]
	v_mfma_f32_16x16x32_bf16 v[6:9], v[192:195], v[232:235], v[6:9]
	v_mfma_f32_16x16x32_bf16 v[2:5], v[200:203], v[232:235], v[2:5]
	s_barrier
	s_add_i32 s61, 0, 0x18000
	v_add_u32_e32 v171, s61, v1
	s_add_i32 s62, 0, 0x1c000
	ds_read_b128 v[172:175], v171
	ds_read_b128 v[176:179], v171 offset:1024
	ds_read_b128 v[180:183], v171 offset:2048
	ds_read_b128 v[184:187], v171 offset:3072
	v_add_u32_e32 v171, s62, v1
	ds_read_b128 v[188:191], v171
	ds_read_b128 v[192:195], v171 offset:1024
	ds_read_b128 v[196:199], v171 offset:2048
	ds_read_b128 v[200:203], v171 offset:3072
	s_add_u32 s36, s36, 0x80000
	s_addc_u32 s37, s37, 0
	s_mov_b32 m0, s46
	ds_read_b128 v[204:207], v170 offset:32768
	ds_read_b128 v[208:211], v170 offset:33792
	ds_read_b128 v[212:215], v170 offset:34816
	ds_read_b128 v[216:219], v170 offset:35840
	ds_read_b128 v[220:223], v170 offset:36864
	ds_read_b128 v[224:227], v170 offset:37888
	ds_read_b128 v[228:231], v170 offset:38912
	global_load_lds_dwordx4 v136, s[36:37]
	s_mov_b32 m0, s47
	ds_read_b128 v[232:235], v170 offset:39936
	global_load_lds_dwordx4 v132, s[36:37]
	s_waitcnt vmcnt(8) lgkmcnt(0)
	s_barrier
	v_mfma_f32_16x16x32_bf16 v[126:129], v[172:175], v[204:207], v[126:129]
	v_mfma_f32_16x16x32_bf16 v[122:125], v[180:183], v[204:207], v[122:125]
	v_mfma_f32_16x16x32_bf16 v[110:113], v[172:175], v[212:215], v[110:113]
	v_mfma_f32_16x16x32_bf16 v[106:109], v[180:183], v[212:215], v[106:109]
	v_mfma_f32_16x16x32_bf16 v[94:97], v[172:175], v[220:223], v[94:97]
	v_mfma_f32_16x16x32_bf16 v[90:93], v[180:183], v[220:223], v[90:93]
	v_mfma_f32_16x16x32_bf16 v[78:81], v[172:175], v[228:231], v[78:81]
	v_mfma_f32_16x16x32_bf16 v[74:77], v[180:183], v[228:231], v[74:77]
	v_mfma_f32_16x16x32_bf16 v[126:129], v[176:179], v[208:211], v[126:129]
	v_mfma_f32_16x16x32_bf16 v[122:125], v[184:187], v[208:211], v[122:125]
	v_mfma_f32_16x16x32_bf16 v[110:113], v[176:179], v[216:219], v[110:113]
	v_mfma_f32_16x16x32_bf16 v[106:109], v[184:187], v[216:219], v[106:109]
	v_mfma_f32_16x16x32_bf16 v[94:97], v[176:179], v[224:227], v[94:97]
	v_mfma_f32_16x16x32_bf16 v[90:93], v[184:187], v[224:227], v[90:93]
	v_mfma_f32_16x16x32_bf16 v[78:81], v[176:179], v[232:235], v[78:81]
	v_mfma_f32_16x16x32_bf16 v[74:77], v[184:187], v[232:235], v[74:77]
	v_mfma_f32_16x16x32_bf16 v[118:121], v[188:191], v[204:207], v[118:121]
	v_mfma_f32_16x16x32_bf16 v[114:117], v[196:199], v[204:207], v[114:117]
	v_mfma_f32_16x16x32_bf16 v[102:105], v[188:191], v[212:215], v[102:105]
	v_mfma_f32_16x16x32_bf16 v[98:101], v[196:199], v[212:215], v[98:101]
	v_mfma_f32_16x16x32_bf16 v[86:89], v[188:191], v[220:223], v[86:89]
	v_mfma_f32_16x16x32_bf16 v[82:85], v[196:199], v[220:223], v[82:85]
	v_mfma_f32_16x16x32_bf16 v[70:73], v[188:191], v[228:231], v[70:73]
	v_mfma_f32_16x16x32_bf16 v[66:69], v[196:199], v[228:231], v[66:69]
	v_mfma_f32_16x16x32_bf16 v[118:121], v[192:195], v[208:211], v[118:121]
	v_mfma_f32_16x16x32_bf16 v[114:117], v[200:203], v[208:211], v[114:117]
	v_mfma_f32_16x16x32_bf16 v[102:105], v[192:195], v[216:219], v[102:105]
	v_mfma_f32_16x16x32_bf16 v[98:101], v[200:203], v[216:219], v[98:101]
	v_mfma_f32_16x16x32_bf16 v[86:89], v[192:195], v[224:227], v[86:89]
	v_mfma_f32_16x16x32_bf16 v[82:85], v[200:203], v[224:227], v[82:85]
	v_mfma_f32_16x16x32_bf16 v[70:73], v[192:195], v[232:235], v[70:73]
	v_mfma_f32_16x16x32_bf16 v[66:69], v[200:203], v[232:235], v[66:69]
	s_barrier
; #define PG8_STAGE(bufoff, gbase, voff) do { _Pragma("unroll") for (int _i = 0; _i < 2; ++_i) \
;         __builtin_amdgcn_global_load_lds((const unsigned*)((const char*)(gbase) + (voff)[_i]), (LAS unsigned*)(lds + (bufoff) + ldsw + _i * 8192), 16, 0, 0); } while (0)
; #define PG8_LDA(dst, b, h) do { _Pragma("unroll") for (int m = 0; m < 4; ++m) _Pragma("unroll") for (int k = 0; k < 2; ++k) dst[m][k] = *(const LAS bf16x8*)(lds + PG8_SA(b, h) + aoff + m * 2048 + k * 1024); } while (0)
; #define PG8_LDB(dst, b, h) do { _Pragma("unroll") for (int n = 0; n < 2; ++n) _Pragma("unroll") for (int k = 0; k < 2; ++k) dst[n][k] = *(const LAS bf16x8*)(lds + PG8_SB(b, h) + boff + n * 2048 + k * 1024); } while (0)
; #define PG8_MMA(ai, bj, At, Bt) do { __builtin_amdgcn_s_setprio(1); _Pragma("unroll") for (int m = 0; m < 4; ++m) _Pragma("unroll") for (int n = 0; n < 2; ++n) _Pragma("unroll") for (int k = 0; k < 2; ++k) \
;         acc[ai][bj][m][n] = __builtin_amdgcn_mfma_f32_16x16x32_bf16(Bt[n][k], At[m][k], acc[ai][bj][m][n], 0, 0, 0); __builtin_amdgcn_s_setprio(0); } while (0)
; #define PG8_WAIT_V(n) asm volatile("s_waitcnt vmcnt(" #n ")" ::: "memory")
; template <class Epi, class Sched, bool ABLK = false, bool ALIGN_EPI = true, bool SP2 = true, bool BBLK = true>
; __device__ __forceinline__ void gemm_phase(LAS unsigned char* lds, const Gemm g, const Sched& S, const Epi& E) {
;     ...
;         for (int t = 0; t < nt; t += 2) {
;             const bool last = (t == nt - 2);
;             const char* a1 = a_tile(uA, tbA + t + 1);
;             const char* a2 = last ? a_tile(nuA, ntbA) : a_tile(uA, tbA + t + 2); const char* b2 = last ? nB : cB + (size_t)(t + 2) * kstepB;
;             const char* a3 = last ? a_tile(nuA, ntbA + 1) : a_tile(uA, tbA + t + 3); const char* b3 = b2 + kstepB;
;             if (last && has_next) S.a_ready(nxt);
;             if constexpr (SP2) {
;             PG8_LDB(B0, 0, 0); PG8_LDB(B1, 0, 1); PG8_SCHED; PG8_LDA(At, 0, 0); PG8_STAGE(PG8_SA(1, 1), a1 + hstepA, voffA);
;             PG8_WAIT_V(8); PG8_WAIT_L(0); PG8_BAR; PG8_MMA(0, 0, At, B0); PG8_MMA(0, 1, At, B1); PG8_BAR; PG8_SCHED;
;     ...
;             PG8_LDA(At, 1, 1); PG8_STAGE(PG8_SB(1, 0), b3, voffB); PG8_STAGE(PG8_SB(1, 1), b3 + hstepB, voffB); PG8_STAGE(PG8_SA(1, 0), a3, voffA);
;             PG8_WAIT_V(8); PG8_WAIT_L(0); PG8_BAR; PG8_MMA(1, 0, At, B0); PG8_MMA(1, 1, At, B1); PG8_BAR; PG8_SCHED;
	s_add_u32 s36, s34, 0x8000
	s_addc_u32 s37, s35, 0
	s_add_i32 s61, s61, s40
	s_mov_b32 m0, s61
	ds_read_b128 v[204:207], v170 offset:49152
	ds_read_b128 v[208:211], v170 offset:50176
	ds_read_b128 v[212:215], v170 offset:51200
	ds_read_b128 v[216:219], v170 offset:52224
	global_load_lds_dwordx4 v134, s[36:37]
	s_add_i32 m0, s61, 0x2000
	s_add_u32 s34, s34, 0xc000
	v_lshl_add_u64 v[236:237], s[36:37], 0, v[130:131]
	s_addc_u32 s35, s35, 0
	s_add_i32 s36, s62, s40
	global_load_lds_dwordx4 v[236:237], off
	s_mov_b32 m0, s36
	ds_read_b128 v[220:223], v170 offset:53248
	global_load_lds_dwordx4 v134, s[34:35]
	s_add_i32 m0, s36, 0x2000
	ds_read_b128 v[224:227], v170 offset:54272
	global_load_lds_dwordx4 v130, s[34:35]
	s_mov_b32 m0, s50
	ds_read_b128 v[228:231], v170 offset:55296
	global_load_lds_dwordx4 v136, s[30:31]
	s_mov_b32 m0, s51
	ds_read_b128 v[232:235], v170 offset:56320
	global_load_lds_dwordx4 v132, s[30:31]
	s_waitcnt vmcnt(8) lgkmcnt(0)
	s_barrier
	v_mfma_f32_16x16x32_bf16 v[62:65], v[172:175], v[204:207], v[62:65]
	v_mfma_f32_16x16x32_bf16 v[58:61], v[180:183], v[204:207], v[58:61]
	v_mfma_f32_16x16x32_bf16 v[46:49], v[172:175], v[212:215], v[46:49]
	v_mfma_f32_16x16x32_bf16 v[42:45], v[180:183], v[212:215], v[42:45]
	v_mfma_f32_16x16x32_bf16 v[30:33], v[172:175], v[220:223], v[30:33]
	v_mfma_f32_16x16x32_bf16 v[26:29], v[180:183], v[220:223], v[26:29]
	v_mfma_f32_16x16x32_bf16 v[14:17], v[172:175], v[228:231], v[14:17]
	v_mfma_f32_16x16x32_bf16 v[10:13], v[180:183], v[228:231], v[10:13]
	v_mfma_f32_16x16x32_bf16 v[62:65], v[176:179], v[208:211], v[62:65]
	v_mfma_f32_16x16x32_bf16 v[58:61], v[184:187], v[208:211], v[58:61]
	v_mfma_f32_16x16x32_bf16 v[46:49], v[176:179], v[216:219], v[46:49]
	v_mfma_f32_16x16x32_bf16 v[42:45], v[184:187], v[216:219], v[42:45]
	v_mfma_f32_16x16x32_bf16 v[30:33], v[176:179], v[224:227], v[30:33]
	v_mfma_f32_16x16x32_bf16 v[26:29], v[184:187], v[224:227], v[26:29]
	v_mfma_f32_16x16x32_bf16 v[14:17], v[176:179], v[232:235], v[14:17]
	v_mfma_f32_16x16x32_bf16 v[10:13], v[184:187], v[232:235], v[10:13]
	v_mfma_f32_16x16x32_bf16 v[54:57], v[188:191], v[204:207], v[54:57]
	v_mfma_f32_16x16x32_bf16 v[50:53], v[196:199], v[204:207], v[50:53]
	v_mfma_f32_16x16x32_bf16 v[38:41], v[188:191], v[212:215], v[38:41]
	v_mfma_f32_16x16x32_bf16 v[34:37], v[196:199], v[212:215], v[34:37]
	v_mfma_f32_16x16x32_bf16 v[22:25], v[188:191], v[220:223], v[22:25]
	v_mfma_f32_16x16x32_bf16 v[18:21], v[196:199], v[220:223], v[18:21]
	v_mfma_f32_16x16x32_bf16 v[6:9], v[188:191], v[228:231], v[6:9]
	v_mfma_f32_16x16x32_bf16 v[2:5], v[196:199], v[228:231], v[2:5]
	v_mfma_f32_16x16x32_bf16 v[54:57], v[192:195], v[208:211], v[54:57]
	v_mfma_f32_16x16x32_bf16 v[50:53], v[200:203], v[208:211], v[50:53]
	v_mfma_f32_16x16x32_bf16 v[38:41], v[192:195], v[216:219], v[38:41]
	v_mfma_f32_16x16x32_bf16 v[34:37], v[200:203], v[216:219], v[34:37]
	v_mfma_f32_16x16x32_bf16 v[22:25], v[192:195], v[224:227], v[22:25]
	v_mfma_f32_16x16x32_bf16 v[18:21], v[200:203], v[224:227], v[18:21]
	v_mfma_f32_16x16x32_bf16 v[6:9], v[192:195], v[232:235], v[6:9]
	v_mfma_f32_16x16x32_bf16 v[2:5], v[200:203], v[232:235], v[2:5]
	s_barrier
	s_add_i32 s60, s60, 2
	s_add_u32 s28, s28, 0x100
	s_addc_u32 s29, s29, 0
	s_add_u32 s58, s58, 0x10000
	s_addc_u32 s59, s59, 0
	s_cmp_gt_u32 s60, 29
.LBB0_475:
	ds_read_b128 v[172:175], v168
	ds_read_b128 v[176:179], v168 offset:1024
	ds_read_b128 v[180:183], v168 offset:2048
	ds_read_b128 v[184:187], v168 offset:3072
	ds_read_b128 v[188:191], v169
	ds_read_b128 v[192:195], v169 offset:1024
	ds_read_b128 v[196:199], v169 offset:2048
	ds_read_b128 v[200:203], v169 offset:3072
	s_add_u32 s30, s26, s28
	s_addc_u32 s31, s27, s29
	s_add_u32 s36, s30, 0x100
	s_addc_u32 s37, s31, 0
	s_add_u32 s30, s30, 0x180
	s_addc_u32 s31, s31, 0
	s_cmpk_eq_i32 s28, 0xf00
	s_cselect_b32 s31, s57, s31
	s_cselect_b32 s30, s23, s30
	s_cselect_b32 s35, s11, s59
	s_cselect_b32 s34, s13, s58
	s_cselect_b32 s37, s4, s37
	s_cselect_b32 s36, s5, s36
	s_mov_b32 m0, s53
	v_lshl_add_u64 v[236:237], v[164:165], 0, s[28:29]
	ds_read_b128 v[204:207], v170
	ds_read_b128 v[208:211], v170 offset:1024
	ds_read_b128 v[212:215], v170 offset:2048
	ds_read_b128 v[216:219], v170 offset:3072
	ds_read_b128 v[220:223], v170 offset:4096
	ds_read_b128 v[224:227], v170 offset:5120
	ds_read_b128 v[228:231], v170 offset:6144
	global_load_lds_dwordx4 v[236:237], off
	v_lshl_add_u64 v[236:237], v[166:167], 0, s[28:29]
	s_mov_b32 m0, s54
	ds_read_b128 v[232:235], v170 offset:7168
	global_load_lds_dwordx4 v[236:237], off
	s_waitcnt vmcnt(8) lgkmcnt(0)
	s_barrier
; #define PG8_STAGE(bufoff, gbase, voff) do { _Pragma("unroll") for (int _i = 0; _i < 2; ++_i) \
;         __builtin_amdgcn_global_load_lds((const unsigned*)((const char*)(gbase) + (voff)[_i]), (LAS unsigned*)(lds + (bufoff) + ldsw + _i * 8192), 16, 0, 0); } while (0)
; #define PG8_LDA(dst, b, h) do { _Pragma("unroll") for (int m = 0; m < 4; ++m) _Pragma("unroll") for (int k = 0; k < 2; ++k) dst[m][k] = *(const LAS bf16x8*)(lds + PG8_SA(b, h) + aoff + m * 2048 + k * 1024); } while (0)
; #define PG8_MMA(ai, bj, At, Bt) do { __builtin_amdgcn_s_setprio(1); _Pragma("unroll") for (int m = 0; m < 4; ++m) _Pragma("unroll") for (int n = 0; n < 2; ++n) _Pragma("unroll") for (int k = 0; k < 2; ++k) \
;         acc[ai][bj][m][n] = __builtin_amdgcn_mfma_f32_16x16x32_bf16(Bt[n][k], At[m][k], acc[ai][bj][m][n], 0, 0, 0); __builtin_amdgcn_s_setprio(0); } while (0)
; #define PG8_WAIT_V(n) asm volatile("s_waitcnt vmcnt(" #n ")" ::: "memory")
; #define PG8_WAIT_L(n) asm volatile("s_waitcnt lgkmcnt(" #n ")" ::: "memory")
; #define PG8_BAR __builtin_amdgcn_s_barrier()
; #define PG8_SCHED __builtin_amdgcn_sched_barrier(0)
; template <class Epi, class Sched, bool ABLK = false, bool ALIGN_EPI = true, bool SP2 = true, bool BBLK = true>
; __device__ __forceinline__ void gemm_phase(LAS unsigned char* lds, const Gemm g, const Sched& S, const Epi& E) {
;     ...
;             PG8_WAIT_V(8); PG8_WAIT_L(0); PG8_BAR; PG8_MMA(0, 0, At, B0); PG8_MMA(0, 1, At, B1); PG8_BAR; PG8_SCHED;
;             PG8_LDA(At, 0, 1); PG8_STAGE(PG8_SB(0, 0), b2, voffB); PG8_STAGE(PG8_SB(0, 1), b2 + hstepB, voffB); PG8_STAGE(PG8_SA(0, 0), a2, voffA);
;             PG8_WAIT_V(8); PG8_WAIT_L(0); PG8_BAR; PG8_MMA(1, 0, At, B0); PG8_MMA(1, 1, At, B1); PG8_BAR; PG8_SCHED;
	v_mfma_f32_16x16x32_bf16 v[126:129], v[172:175], v[204:207], v[126:129]
	v_mfma_f32_16x16x32_bf16 v[122:125], v[180:183], v[204:207], v[122:125]
	v_mfma_f32_16x16x32_bf16 v[110:113], v[172:175], v[212:215], v[110:113]
	v_mfma_f32_16x16x32_bf16 v[106:109], v[180:183], v[212:215], v[106:109]
	v_mfma_f32_16x16x32_bf16 v[94:97], v[172:175], v[220:223], v[94:97]
	v_mfma_f32_16x16x32_bf16 v[90:93], v[180:183], v[220:223], v[90:93]
	v_mfma_f32_16x16x32_bf16 v[78:81], v[172:175], v[228:231], v[78:81]
	v_mfma_f32_16x16x32_bf16 v[74:77], v[180:183], v[228:231], v[74:77]
	v_mfma_f32_16x16x32_bf16 v[126:129], v[176:179], v[208:211], v[126:129]
	v_mfma_f32_16x16x32_bf16 v[122:125], v[184:187], v[208:211], v[122:125]
	v_mfma_f32_16x16x32_bf16 v[110:113], v[176:179], v[216:219], v[110:113]
	v_mfma_f32_16x16x32_bf16 v[106:109], v[184:187], v[216:219], v[106:109]
	v_mfma_f32_16x16x32_bf16 v[94:97], v[176:179], v[224:227], v[94:97]
	v_mfma_f32_16x16x32_bf16 v[90:93], v[184:187], v[224:227], v[90:93]
	v_mfma_f32_16x16x32_bf16 v[78:81], v[176:179], v[232:235], v[78:81]
	v_mfma_f32_16x16x32_bf16 v[74:77], v[184:187], v[232:235], v[74:77]
	v_mfma_f32_16x16x32_bf16 v[118:121], v[188:191], v[204:207], v[118:121]
	v_mfma_f32_16x16x32_bf16 v[114:117], v[196:199], v[204:207], v[114:117]
	v_mfma_f32_16x16x32_bf16 v[102:105], v[188:191], v[212:215], v[102:105]
	v_mfma_f32_16x16x32_bf16 v[98:101], v[196:199], v[212:215], v[98:101]
	v_mfma_f32_16x16x32_bf16 v[86:89], v[188:191], v[220:223], v[86:89]
	v_mfma_f32_16x16x32_bf16 v[82:85], v[196:199], v[220:223], v[82:85]
	v_mfma_f32_16x16x32_bf16 v[70:73], v[188:191], v[228:231], v[70:73]
	v_mfma_f32_16x16x32_bf16 v[66:69], v[196:199], v[228:231], v[66:69]
	v_mfma_f32_16x16x32_bf16 v[118:121], v[192:195], v[208:211], v[118:121]
	v_mfma_f32_16x16x32_bf16 v[114:117], v[200:203], v[208:211], v[114:117]
	v_mfma_f32_16x16x32_bf16 v[102:105], v[192:195], v[216:219], v[102:105]
	v_mfma_f32_16x16x32_bf16 v[98:101], v[200:203], v[216:219], v[98:101]
	v_mfma_f32_16x16x32_bf16 v[86:89], v[192:195], v[224:227], v[86:89]
	v_mfma_f32_16x16x32_bf16 v[82:85], v[200:203], v[224:227], v[82:85]
	v_mfma_f32_16x16x32_bf16 v[70:73], v[192:195], v[232:235], v[70:73]
	v_mfma_f32_16x16x32_bf16 v[66:69], v[200:203], v[232:235], v[66:69]
	s_barrier
	s_mov_b32 m0, s55
	s_add_u32 s62, s34, 0x4000
	ds_read_b128 v[204:207], v170 offset:16384
	ds_read_b128 v[208:211], v170 offset:17408
	ds_read_b128 v[212:215], v170 offset:18432
	ds_read_b128 v[216:219], v170 offset:19456
	global_load_lds_dwordx4 v134, s[34:35]
	s_mov_b32 m0, s56
	s_addc_u32 s63, s35, 0
	s_add_i32 s61, s52, s40
	global_load_lds_dwordx4 v130, s[34:35]
	s_mov_b32 m0, s61
	ds_read_b128 v[220:223], v170 offset:20480
	global_load_lds_dwordx4 v134, s[62:63]
	s_add_i32 m0, s61, 0x2000
	ds_read_b128 v[224:227], v170 offset:21504
	global_load_lds_dwordx4 v130, s[62:63]
	s_mov_b32 m0, s25
	ds_read_b128 v[228:231], v170 offset:22528
	global_load_lds_dwordx4 v136, s[36:37]
	s_mov_b32 m0, s43
	ds_read_b128 v[232:235], v170 offset:23552
	global_load_lds_dwordx4 v132, s[36:37]
	s_waitcnt vmcnt(8) lgkmcnt(0)
	s_barrier
	v_mfma_f32_16x16x32_bf16 v[62:65], v[172:175], v[204:207], v[62:65]
	v_mfma_f32_16x16x32_bf16 v[58:61], v[180:183], v[204:207], v[58:61]
	v_mfma_f32_16x16x32_bf16 v[46:49], v[172:175], v[212:215], v[46:49]
	v_mfma_f32_16x16x32_bf16 v[42:45], v[180:183], v[212:215], v[42:45]
	v_mfma_f32_16x16x32_bf16 v[30:33], v[172:175], v[220:223], v[30:33]
	v_mfma_f32_16x16x32_bf16 v[26:29], v[180:183], v[220:223], v[26:29]
	v_mfma_f32_16x16x32_bf16 v[14:17], v[172:175], v[228:231], v[14:17]
	v_mfma_f32_16x16x32_bf16 v[10:13], v[180:183], v[228:231], v[10:13]
	v_mfma_f32_16x16x32_bf16 v[62:65], v[176:179], v[208:211], v[62:65]
	v_mfma_f32_16x16x32_bf16 v[58:61], v[184:187], v[208:211], v[58:61]
	v_mfma_f32_16x16x32_bf16 v[46:49], v[176:179], v[216:219], v[46:49]
	v_mfma_f32_16x16x32_bf16 v[42:45], v[184:187], v[216:219], v[42:45]
	v_mfma_f32_16x16x32_bf16 v[30:33], v[176:179], v[224:227], v[30:33]
	v_mfma_f32_16x16x32_bf16 v[26:29], v[184:187], v[224:227], v[26:29]
	v_mfma_f32_16x16x32_bf16 v[14:17], v[176:179], v[232:235], v[14:17]
	v_mfma_f32_16x16x32_bf16 v[10:13], v[184:187], v[232:235], v[10:13]
	v_mfma_f32_16x16x32_bf16 v[54:57], v[188:191], v[204:207], v[54:57]
	v_mfma_f32_16x16x32_bf16 v[50:53], v[196:199], v[204:207], v[50:53]
	v_mfma_f32_16x16x32_bf16 v[38:41], v[188:191], v[212:215], v[38:41]
	v_mfma_f32_16x16x32_bf16 v[34:37], v[196:199], v[212:215], v[34:37]
	v_mfma_f32_16x16x32_bf16 v[22:25], v[188:191], v[220:223], v[22:25]
	v_mfma_f32_16x16x32_bf16 v[18:21], v[196:199], v[220:223], v[18:21]
	v_mfma_f32_16x16x32_bf16 v[6:9], v[188:191], v[228:231], v[6:9]
	v_mfma_f32_16x16x32_bf16 v[2:5], v[196:199], v[228:231], v[2:5]
	v_mfma_f32_16x16x32_bf16 v[54:57], v[192:195], v[208:211], v[54:57]
	v_mfma_f32_16x16x32_bf16 v[50:53], v[200:203], v[208:211], v[50:53]
	v_mfma_f32_16x16x32_bf16 v[38:41], v[192:195], v[216:219], v[38:41]
	v_mfma_f32_16x16x32_bf16 v[34:37], v[200:203], v[216:219], v[34:37]
	v_mfma_f32_16x16x32_bf16 v[22:25], v[192:195], v[224:227], v[22:25]
	v_mfma_f32_16x16x32_bf16 v[18:21], v[200:203], v[224:227], v[18:21]
	v_mfma_f32_16x16x32_bf16 v[6:9], v[192:195], v[232:235], v[6:9]
	v_mfma_f32_16x16x32_bf16 v[2:5], v[200:203], v[232:235], v[2:5]
	s_barrier
; #define PG8_STAGE(bufoff, gbase, voff) do { _Pragma("unroll") for (int _i = 0; _i < 2; ++_i) \
;         __builtin_amdgcn_global_load_lds((const unsigned*)((const char*)(gbase) + (voff)[_i]), (LAS unsigned*)(lds + (bufoff) + ldsw + _i * 8192), 16, 0, 0); } while (0)
; #define PG8_LDA(dst, b, h) do { _Pragma("unroll") for (int m = 0; m < 4; ++m) _Pragma("unroll") for (int k = 0; k < 2; ++k) dst[m][k] = *(const LAS bf16x8*)(lds + PG8_SA(b, h) + aoff + m * 2048 + k * 1024); } while (0)
; #define PG8_LDB(dst, b, h) do { _Pragma("unroll") for (int n = 0; n < 2; ++n) _Pragma("unroll") for (int k = 0; k < 2; ++k) dst[n][k] = *(const LAS bf16x8*)(lds + PG8_SB(b, h) + boff + n * 2048 + k * 1024); } while (0)
; #define PG8_MMA(ai, bj, At, Bt) do { __builtin_amdgcn_s_setprio(1); _Pragma("unroll") for (int m = 0; m < 4; ++m) _Pragma("unroll") for (int n = 0; n < 2; ++n) _Pragma("unroll") for (int k = 0; k < 2; ++k) \
;         acc[ai][bj][m][n] = __builtin_amdgcn_mfma_f32_16x16x32_bf16(Bt[n][k], At[m][k], acc[ai][bj][m][n], 0, 0, 0); __builtin_amdgcn_s_setprio(0); } while (0)
; #define PG8_WAIT_V(n) asm volatile("s_waitcnt vmcnt(" #n ")" ::: "memory")
; #define PG8_WAIT_L(n) asm volatile("s_waitcnt lgkmcnt(" #n ")" ::: "memory")
; #define PG8_BAR __builtin_amdgcn_s_barrier()
; #define PG8_SCHED __builtin_amdgcn_sched_barrier(0)
; template <class Epi, class Sched, bool ABLK = false, bool ALIGN_EPI = true, bool SP2 = true, bool BBLK = true>
; __device__ __forceinline__ void gemm_phase(LAS unsigned char* lds, const Gemm g, const Sched& S, const Epi& E) {
;     ...
;             PG8_LDB(B0, 1, 0); PG8_LDB(B1, 1, 1); PG8_SCHED; PG8_LDA(At, 1, 0); PG8_STAGE(PG8_SA(0, 1), a2 + hstepA, voffA);
;             PG8_WAIT_V(8); PG8_WAIT_L(0); PG8_BAR; PG8_MMA(0, 0, At, B0); PG8_MMA(0, 1, At, B1); PG8_BAR; PG8_SCHED;
;             PG8_LDA(At, 1, 1); PG8_STAGE(PG8_SB(1, 0), b3, voffB); PG8_STAGE(PG8_SB(1, 1), b3 + hstepB, voffB); PG8_STAGE(PG8_SA(1, 0), a3, voffA);
;             PG8_WAIT_V(8); PG8_WAIT_L(0); PG8_BAR; PG8_MMA(1, 0, At, B0); PG8_MMA(1, 1, At, B1); PG8_BAR; PG8_SCHED;
	s_add_i32 s61, 0, 0x18000
	v_add_u32_e32 v171, s61, v1
	s_add_i32 s62, 0, 0x1c000
	ds_read_b128 v[172:175], v171
	ds_read_b128 v[176:179], v171 offset:1024
	ds_read_b128 v[180:183], v171 offset:2048
	ds_read_b128 v[184:187], v171 offset:3072
	v_add_u32_e32 v171, s62, v1
	ds_read_b128 v[188:191], v171
	ds_read_b128 v[192:195], v171 offset:1024
	ds_read_b128 v[196:199], v171 offset:2048
	ds_read_b128 v[200:203], v171 offset:3072
	s_add_u32 s36, s36, 0x80000
	s_addc_u32 s37, s37, 0
	s_mov_b32 m0, s46
	ds_read_b128 v[204:207], v170 offset:32768
	ds_read_b128 v[208:211], v170 offset:33792
	ds_read_b128 v[212:215], v170 offset:34816
	ds_read_b128 v[216:219], v170 offset:35840
	ds_read_b128 v[220:223], v170 offset:36864
	ds_read_b128 v[224:227], v170 offset:37888
	ds_read_b128 v[228:231], v170 offset:38912
	global_load_lds_dwordx4 v136, s[36:37]
	s_mov_b32 m0, s47
	ds_read_b128 v[232:235], v170 offset:39936
	global_load_lds_dwordx4 v132, s[36:37]
	s_waitcnt vmcnt(8) lgkmcnt(0)
	s_barrier
	v_mfma_f32_16x16x32_bf16 v[126:129], v[172:175], v[204:207], v[126:129]
	v_mfma_f32_16x16x32_bf16 v[122:125], v[180:183], v[204:207], v[122:125]
	v_mfma_f32_16x16x32_bf16 v[110:113], v[172:175], v[212:215], v[110:113]
	v_mfma_f32_16x16x32_bf16 v[106:109], v[180:183], v[212:215], v[106:109]
	v_mfma_f32_16x16x32_bf16 v[94:97], v[172:175], v[220:223], v[94:97]
	v_mfma_f32_16x16x32_bf16 v[90:93], v[180:183], v[220:223], v[90:93]
	v_mfma_f32_16x16x32_bf16 v[78:81], v[172:175], v[228:231], v[78:81]
	v_mfma_f32_16x16x32_bf16 v[74:77], v[180:183], v[228:231], v[74:77]
	v_mfma_f32_16x16x32_bf16 v[126:129], v[176:179], v[208:211], v[126:129]
	v_mfma_f32_16x16x32_bf16 v[122:125], v[184:187], v[208:211], v[122:125]
	v_mfma_f32_16x16x32_bf16 v[110:113], v[176:179], v[216:219], v[110:113]
	v_mfma_f32_16x16x32_bf16 v[106:109], v[184:187], v[216:219], v[106:109]
	v_mfma_f32_16x16x32_bf16 v[94:97], v[176:179], v[224:227], v[94:97]
	v_mfma_f32_16x16x32_bf16 v[90:93], v[184:187], v[224:227], v[90:93]
	v_mfma_f32_16x16x32_bf16 v[78:81], v[176:179], v[232:235], v[78:81]
	v_mfma_f32_16x16x32_bf16 v[74:77], v[184:187], v[232:235], v[74:77]
	v_mfma_f32_16x16x32_bf16 v[118:121], v[188:191], v[204:207], v[118:121]
	v_mfma_f32_16x16x32_bf16 v[114:117], v[196:199], v[204:207], v[114:117]
	v_mfma_f32_16x16x32_bf16 v[102:105], v[188:191], v[212:215], v[102:105]
	v_mfma_f32_16x16x32_bf16 v[98:101], v[196:199], v[212:215], v[98:101]
	v_mfma_f32_16x16x32_bf16 v[86:89], v[188:191], v[220:223], v[86:89]
	v_mfma_f32_16x16x32_bf16 v[82:85], v[196:199], v[220:223], v[82:85]
	v_mfma_f32_16x16x32_bf16 v[70:73], v[188:191], v[228:231], v[70:73]
	v_mfma_f32_16x16x32_bf16 v[66:69], v[196:199], v[228:231], v[66:69]
	v_mfma_f32_16x16x32_bf16 v[118:121], v[192:195], v[208:211], v[118:121]
	v_mfma_f32_16x16x32_bf16 v[114:117], v[200:203], v[208:211], v[114:117]
	v_mfma_f32_16x16x32_bf16 v[102:105], v[192:195], v[216:219], v[102:105]
	v_mfma_f32_16x16x32_bf16 v[98:101], v[200:203], v[216:219], v[98:101]
	v_mfma_f32_16x16x32_bf16 v[86:89], v[192:195], v[224:227], v[86:89]
	v_mfma_f32_16x16x32_bf16 v[82:85], v[200:203], v[224:227], v[82:85]
	v_mfma_f32_16x16x32_bf16 v[70:73], v[192:195], v[232:235], v[70:73]
	v_mfma_f32_16x16x32_bf16 v[66:69], v[200:203], v[232:235], v[66:69]
	s_barrier
	s_add_u32 s36, s34, 0x8000
	s_addc_u32 s37, s35, 0
	s_add_i32 s61, s61, s40
	s_mov_b32 m0, s61
	ds_read_b128 v[204:207], v170 offset:49152
	ds_read_b128 v[208:211], v170 offset:50176
	ds_read_b128 v[212:215], v170 offset:51200
	ds_read_b128 v[216:219], v170 offset:52224
	global_load_lds_dwordx4 v134, s[36:37]
	s_add_i32 m0, s61, 0x2000
	s_add_u32 s34, s34, 0xc000
	v_lshl_add_u64 v[236:237], s[36:37], 0, v[130:131]
	s_addc_u32 s35, s35, 0
	s_add_i32 s36, s62, s40
	global_load_lds_dwordx4 v[236:237], off
	s_mov_b32 m0, s36
	ds_read_b128 v[220:223], v170 offset:53248
	global_load_lds_dwordx4 v134, s[34:35]
	s_add_i32 m0, s36, 0x2000
	ds_read_b128 v[224:227], v170 offset:54272
	global_load_lds_dwordx4 v130, s[34:35]
	s_mov_b32 m0, s50
	ds_read_b128 v[228:231], v170 offset:55296
	global_load_lds_dwordx4 v136, s[30:31]
	s_mov_b32 m0, s51
	ds_read_b128 v[232:235], v170 offset:56320
	global_load_lds_dwordx4 v132, s[30:31]
	s_waitcnt vmcnt(8) lgkmcnt(0)
	s_barrier
	v_mfma_f32_16x16x32_bf16 v[62:65], v[172:175], v[204:207], v[62:65]
	v_mfma_f32_16x16x32_bf16 v[58:61], v[180:183], v[204:207], v[58:61]
	v_mfma_f32_16x16x32_bf16 v[46:49], v[172:175], v[212:215], v[46:49]
	v_mfma_f32_16x16x32_bf16 v[42:45], v[180:183], v[212:215], v[42:45]
	v_mfma_f32_16x16x32_bf16 v[30:33], v[172:175], v[220:223], v[30:33]
	v_mfma_f32_16x16x32_bf16 v[26:29], v[180:183], v[220:223], v[26:29]
	v_mfma_f32_16x16x32_bf16 v[14:17], v[172:175], v[228:231], v[14:17]
	v_mfma_f32_16x16x32_bf16 v[10:13], v[180:183], v[228:231], v[10:13]
	v_mfma_f32_16x16x32_bf16 v[62:65], v[176:179], v[208:211], v[62:65]
	v_mfma_f32_16x16x32_bf16 v[58:61], v[184:187], v[208:211], v[58:61]
	v_mfma_f32_16x16x32_bf16 v[46:49], v[176:179], v[216:219], v[46:49]
	v_mfma_f32_16x16x32_bf16 v[42:45], v[184:187], v[216:219], v[42:45]
	v_mfma_f32_16x16x32_bf16 v[30:33], v[176:179], v[224:227], v[30:33]
	v_mfma_f32_16x16x32_bf16 v[26:29], v[184:187], v[224:227], v[26:29]
	v_mfma_f32_16x16x32_bf16 v[14:17], v[176:179], v[232:235], v[14:17]
	v_mfma_f32_16x16x32_bf16 v[10:13], v[184:187], v[232:235], v[10:13]
	v_mfma_f32_16x16x32_bf16 v[54:57], v[188:191], v[204:207], v[54:57]
	v_mfma_f32_16x16x32_bf16 v[50:53], v[196:199], v[204:207], v[50:53]
	v_mfma_f32_16x16x32_bf16 v[38:41], v[188:191], v[212:215], v[38:41]
	v_mfma_f32_16x16x32_bf16 v[34:37], v[196:199], v[212:215], v[34:37]
	v_mfma_f32_16x16x32_bf16 v[22:25], v[188:191], v[220:223], v[22:25]
	v_mfma_f32_16x16x32_bf16 v[18:21], v[196:199], v[220:223], v[18:21]
	v_mfma_f32_16x16x32_bf16 v[6:9], v[188:191], v[228:231], v[6:9]
	v_mfma_f32_16x16x32_bf16 v[2:5], v[196:199], v[228:231], v[2:5]
	v_mfma_f32_16x16x32_bf16 v[54:57], v[192:195], v[208:211], v[54:57]
	v_mfma_f32_16x16x32_bf16 v[50:53], v[200:203], v[208:211], v[50:53]
	v_mfma_f32_16x16x32_bf16 v[38:41], v[192:195], v[216:219], v[38:41]
	v_mfma_f32_16x16x32_bf16 v[34:37], v[200:203], v[216:219], v[34:37]
	v_mfma_f32_16x16x32_bf16 v[22:25], v[192:195], v[224:227], v[22:25]
	v_mfma_f32_16x16x32_bf16 v[18:21], v[200:203], v[224:227], v[18:21]
	v_mfma_f32_16x16x32_bf16 v[6:9], v[192:195], v[232:235], v[6:9]
	v_mfma_f32_16x16x32_bf16 v[2:5], v[200:203], v[232:235], v[2:5]
	s_barrier
	s_add_i32 s60, s60, 2
	s_add_u32 s28, s28, 0x100
	s_addc_u32 s29, s29, 0
	s_add_u32 s58, s58, 0x10000
	s_addc_u32 s59, s59, 0
	s_cmp_gt_u32 s60, 29
	s_cbranch_scc0 .LBB0_475
	s_and_b64 vcc, exec, s[8:9]
	s_cbranch_vccz .LBB0_478
	s_barrier

; #define PG8_STAGE(bufoff, gbase, voff) do { _Pragma("unroll") for (int _i = 0; _i < 2; ++_i) \
;         __builtin_amdgcn_global_load_lds((const unsigned*)((const char*)(gbase) + (voff)[_i]), (LAS unsigned*)(lds + (bufoff) + ldsw + _i * 8192), 16, 0, 0); } while (0)
; #define PG8_LDA(dst, b, h) do { _Pragma("unroll") for (int m = 0; m < 4; ++m) _Pragma("unroll") for (int k = 0; k < 2; ++k) dst[m][k] = *(const LAS bf16x8*)(lds + PG8_SA(b, h) + aoff + m * 2048 + k * 1024); } while (0)
; #define PG8_LDB(dst, b, h) do { _Pragma("unroll") for (int n = 0; n < 2; ++n) _Pragma("unroll") for (int k = 0; k < 2; ++k) dst[n][k] = *(const LAS bf16x8*)(lds + PG8_SB(b, h) + boff + n * 2048 + k * 1024); } while (0)
; #define PG8_WAIT_V(n) asm volatile("s_waitcnt vmcnt(" #n ")" ::: "memory")
; #define PG8_WAIT_L(n) asm volatile("s_waitcnt lgkmcnt(" #n ")" ::: "memory")
; template <class Epi, class Sched, bool ABLK = false, bool ALIGN_EPI = true, bool SP2 = true, bool BBLK = true>
; __device__ __forceinline__ void gemm_phase(LAS unsigned char* lds, const Gemm g, const Sched& S, const Epi& E) {
;     ...
;         const bool has_next = S.next(ui + 1, nxt);
;         const int nt = cur.nt;
;         const char* nuA = has_next ? a_unit(nxt) : uA; const int ntbA = has_next ? nxt.k0 / BK : tbA; const char* nB = has_next ? (const char*)g.Bt + (size_t)nxt.pn * tstepB + b_k0(nxt.k0) : cB;
;         for (int t = 0; t < nt; t += 2) {
;             const bool last = (t == nt - 2);
;             const char* a1 = a_tile(uA, tbA + t + 1);
;             const char* a2 = last ? a_tile(nuA, ntbA) : a_tile(uA, tbA + t + 2); const char* b2 = last ? nB : cB + (size_t)(t + 2) * kstepB;
;             const char* a3 = last ? a_tile(nuA, ntbA + 1) : a_tile(uA, tbA + t + 3); const char* b3 = b2 + kstepB;
;             if (last && has_next) S.a_ready(nxt);
;             if constexpr (SP2) {
;             PG8_LDB(B0, 0, 0); PG8_LDB(B1, 0, 1); PG8_SCHED; PG8_LDA(At, 0, 0); PG8_STAGE(PG8_SA(1, 1), a1 + hstepA, voffA);
;             PG8_WAIT_V(8); PG8_WAIT_L(0); PG8_BAR; PG8_MMA(0, 0, At, B0); PG8_MMA(0, 1, At, B1); PG8_BAR; PG8_SCHED;
;             PG8_LDA(At, 0, 1); PG8_STAGE(PG8_SB(0, 0), b2, voffB); PG8_STAGE(PG8_SB(0, 1), b2 + hstepB, voffB); PG8_STAGE(PG8_SA(0, 0), a2, voffA);
;             PG8_WAIT_V(8); PG8_WAIT_L(0); PG8_BAR; PG8_MMA(1, 0, At, B0); PG8_MMA(1, 1, At, B1); PG8_BAR; PG8_SCHED;
.LBB0_539:
	s_ashr_i32 s81, s80, 31
	s_andn2_b64 vcc, exec, s[4:5]
	s_lshl_b64 s[30:31], s[80:81], 22
	s_add_u32 s30, s1, s30
	s_addc_u32 s31, s33, s31
	s_and_b64 s[34:35], s[4:5], exec
	s_cselect_b32 s47, s31, s43
	s_cselect_b32 s60, s30, s42
	s_ashr_i32 s34, s0, 31
	s_lshr_b32 s34, s34, 26
	s_add_i32 s34, s0, s34
	s_ashr_i32 s34, s34, 6
	s_and_b64 s[36:37], s[4:5], exec
	s_cselect_b32 s48, s34, s46
	s_ashr_i32 s79, s78, 31
	s_lshl_b64 s[36:37], s[78:79], 22
	s_add_u32 s49, s39, s36
	s_addc_u32 s61, s50, s37
	s_ashr_i32 s35, s34, 31
	s_lshl_b64 s[36:37], s[34:35], 15
	s_add_u32 s36, s49, s36
	s_addc_u32 s37, s61, s37
	v_cndmask_b32_e64 v2, 0, 1, s[4:5]
	s_and_b64 s[4:5], s[4:5], exec
	s_cselect_b32 s4, s37, s41
	s_cselect_b32 s5, s36, s40
	s_ashr_i32 s49, s48, 31
	s_lshl_b64 s[48:49], s[48:49], 15
	s_add_u32 s35, s60, s48
	s_addc_u32 s63, s47, s49
	s_add_u32 s64, s35, 0x8000
	s_addc_u32 s65, s63, 0
	s_add_u32 s66, s40, 0x10000
	s_addc_u32 s67, s41, 0
	s_ashr_i32 s47, s46, 31
	v_cmp_ne_u32_e64 s[8:9], 1, v2
	s_lshl_b64 s[40:41], s[46:47], 15
	v_lshl_add_u64 v[2:3], s[42:43], 0, v[138:139]
	s_add_u32 s75, s42, s40
	v_lshl_add_u64 v[142:143], v[2:3], 0, s[40:41]
	v_lshl_add_u64 v[2:3], s[42:43], 0, v[140:141]
	s_addc_u32 s76, s43, s41
	v_lshl_add_u64 v[144:145], v[2:3], 0, s[40:41]
	s_lshl_b32 s40, s59, 15
	s_add_i32 s40, s40, 0xfff00000
	v_mov_b32_e32 v2, 0
	s_add_u32 s77, s40, 0xf0000
	s_mov_b32 s79, 0
	s_mov_b64 s[40:41], 0
	ds_read_b128 v[152:155], v148
	ds_read_b128 v[156:159], v148 offset:1024
	ds_read_b128 v[160:163], v148 offset:2048
	ds_read_b128 v[164:167], v148 offset:3072
	ds_read_b128 v[168:171], v149
	ds_read_b128 v[172:175], v149 offset:1024
	ds_read_b128 v[176:179], v149 offset:2048
	ds_read_b128 v[180:183], v149 offset:3072
	s_add_u32 s42, s75, s40
	s_addc_u32 s43, s76, s41
	s_add_u32 s48, s42, 0x10000
	s_addc_u32 s49, s43, 0
	s_add_i32 s79, s79, 2
	s_add_u32 s46, s66, s40
	s_addc_u32 s47, s67, s41
	s_add_u32 s42, s42, 0x18000
	s_addc_u32 s43, s43, 0
	s_cmp_eq_u32 s77, s40
	s_cselect_b32 s43, s65, s43
	s_cselect_b32 s42, s64, s42
	s_cselect_b32 s47, s4, s47
	s_cselect_b32 s46, s5, s46
	s_cselect_b32 s49, s63, s49
	s_cselect_b32 s48, s35, s48
	v_lshl_add_u64 v[216:217], v[142:143], 0, s[40:41]
	s_add_i32 m0, s52, 0xc000
	ds_read_b128 v[184:187], v150
	ds_read_b128 v[188:191], v150 offset:1024
	ds_read_b128 v[192:195], v150 offset:2048
	ds_read_b128 v[196:199], v150 offset:3072
	ds_read_b128 v[200:203], v150 offset:4096
	ds_read_b128 v[204:207], v150 offset:5120
	ds_read_b128 v[208:211], v150 offset:6144
	global_load_lds_dwordx4 v[216:217], off
	v_lshl_add_u64 v[216:217], v[144:145], 0, s[40:41]
	s_add_i32 m0, s52, 0xe000
	ds_read_b128 v[212:215], v150 offset:7168
	global_load_lds_dwordx4 v[216:217], off
	s_waitcnt vmcnt(8) lgkmcnt(0)
	s_barrier
	v_mfma_f32_16x16x32_bf16 v[126:129], v[152:155], v[184:187], 0
	v_mfma_f32_16x16x32_bf16 v[122:125], v[160:163], v[184:187], 0
	v_mfma_f32_16x16x32_bf16 v[110:113], v[152:155], v[192:195], 0
	v_mfma_f32_16x16x32_bf16 v[106:109], v[160:163], v[192:195], 0
	v_mfma_f32_16x16x32_bf16 v[94:97], v[152:155], v[200:203], 0
	v_mfma_f32_16x16x32_bf16 v[90:93], v[160:163], v[200:203], 0
	v_mfma_f32_16x16x32_bf16 v[78:81], v[152:155], v[208:211], 0
	v_mfma_f32_16x16x32_bf16 v[74:77], v[160:163], v[208:211], 0
	v_mfma_f32_16x16x32_bf16 v[126:129], v[156:159], v[188:191], v[126:129]
	v_mfma_f32_16x16x32_bf16 v[122:125], v[164:167], v[188:191], v[122:125]
	v_mfma_f32_16x16x32_bf16 v[110:113], v[156:159], v[196:199], v[110:113]
	v_mfma_f32_16x16x32_bf16 v[106:109], v[164:167], v[196:199], v[106:109]
	v_mfma_f32_16x16x32_bf16 v[94:97], v[156:159], v[204:207], v[94:97]
	v_mfma_f32_16x16x32_bf16 v[90:93], v[164:167], v[204:207], v[90:93]
	v_mfma_f32_16x16x32_bf16 v[78:81], v[156:159], v[212:215], v[78:81]
	v_mfma_f32_16x16x32_bf16 v[74:77], v[164:167], v[212:215], v[74:77]
	v_mfma_f32_16x16x32_bf16 v[118:121], v[168:171], v[184:187], 0
	v_mfma_f32_16x16x32_bf16 v[114:117], v[176:179], v[184:187], 0
	v_mfma_f32_16x16x32_bf16 v[102:105], v[168:171], v[192:195], 0
	v_mfma_f32_16x16x32_bf16 v[98:101], v[176:179], v[192:195], 0
	v_mfma_f32_16x16x32_bf16 v[86:89], v[168:171], v[200:203], 0
	v_mfma_f32_16x16x32_bf16 v[82:85], v[176:179], v[200:203], 0
	v_mfma_f32_16x16x32_bf16 v[70:73], v[168:171], v[208:211], 0
	v_mfma_f32_16x16x32_bf16 v[66:69], v[176:179], v[208:211], 0
	v_mfma_f32_16x16x32_bf16 v[118:121], v[172:175], v[188:191], v[118:121]
	v_mfma_f32_16x16x32_bf16 v[114:117], v[180:183], v[188:191], v[114:117]
	v_mfma_f32_16x16x32_bf16 v[102:105], v[172:175], v[196:199], v[102:105]
	v_mfma_f32_16x16x32_bf16 v[98:101], v[180:183], v[196:199], v[98:101]
	v_mfma_f32_16x16x32_bf16 v[86:89], v[172:175], v[204:207], v[86:89]
	v_mfma_f32_16x16x32_bf16 v[82:85], v[180:183], v[204:207], v[82:85]
	v_mfma_f32_16x16x32_bf16 v[70:73], v[172:175], v[212:215], v[70:73]
	v_mfma_f32_16x16x32_bf16 v[66:69], v[180:183], v[212:215], v[66:69]
	s_barrier
	s_add_i32 s60, s72, s51
	s_mov_b32 m0, s60
	ds_read_b128 v[184:187], v150 offset:16384
	ds_read_b128 v[188:191], v150 offset:17408
	ds_read_b128 v[192:195], v150 offset:18432
	ds_read_b128 v[196:199], v150 offset:19456
	global_load_lds_dwordx4 v130, s[46:47]
	s_add_i32 m0, s60, 0x2000
	s_add_u32 s60, s46, 0x4000
	s_addc_u32 s61, s47, 0
	s_add_i32 s81, s73, s51
	global_load_lds_dwordx4 v132, s[46:47]
	s_mov_b32 m0, s81
	ds_read_b128 v[200:203], v150 offset:20480
	global_load_lds_dwordx4 v130, s[60:61]
	s_add_i32 m0, s81, 0x2000
	ds_read_b128 v[204:207], v150 offset:21504
	global_load_lds_dwordx4 v132, s[60:61]
	s_mov_b32 m0, s52
	ds_read_b128 v[208:211], v150 offset:22528
	global_load_lds_dwordx4 v130, s[48:49]
	s_mov_b32 m0, s53
	ds_read_b128 v[212:215], v150 offset:23552
	global_load_lds_dwordx4 v132, s[48:49]
	s_waitcnt vmcnt(8) lgkmcnt(0)
	s_barrier
; #define PG8_STAGE(bufoff, gbase, voff) do { _Pragma("unroll") for (int _i = 0; _i < 2; ++_i) \
;         __builtin_amdgcn_global_load_lds((const unsigned*)((const char*)(gbase) + (voff)[_i]), (LAS unsigned*)(lds + (bufoff) + ldsw + _i * 8192), 16, 0, 0); } while (0)
; #define PG8_LDA(dst, b, h) do { _Pragma("unroll") for (int m = 0; m < 4; ++m) _Pragma("unroll") for (int k = 0; k < 2; ++k) dst[m][k] = *(const LAS bf16x8*)(lds + PG8_SA(b, h) + aoff + m * 2048 + k * 1024); } while (0)
; #define PG8_LDB(dst, b, h) do { _Pragma("unroll") for (int n = 0; n < 2; ++n) _Pragma("unroll") for (int k = 0; k < 2; ++k) dst[n][k] = *(const LAS bf16x8*)(lds + PG8_SB(b, h) + boff + n * 2048 + k * 1024); } while (0)
; #define PG8_MMA(ai, bj, At, Bt) do { __builtin_amdgcn_s_setprio(1); _Pragma("unroll") for (int m = 0; m < 4; ++m) _Pragma("unroll") for (int n = 0; n < 2; ++n) _Pragma("unroll") for (int k = 0; k < 2; ++k) \
;         acc[ai][bj][m][n] = __builtin_amdgcn_mfma_f32_16x16x32_bf16(Bt[n][k], At[m][k], acc[ai][bj][m][n], 0, 0, 0); __builtin_amdgcn_s_setprio(0); } while (0)
; #define PG8_WAIT_V(n) asm volatile("s_waitcnt vmcnt(" #n ")" ::: "memory")
; #define PG8_WAIT_L(n) asm volatile("s_waitcnt lgkmcnt(" #n ")" ::: "memory")
; #define PG8_BAR __builtin_amdgcn_s_barrier()
; #define PG8_SCHED __builtin_amdgcn_sched_barrier(0)
; template <class Epi, class Sched, bool ABLK = false, bool ALIGN_EPI = true, bool SP2 = true, bool BBLK = true>
; __device__ __forceinline__ void gemm_phase(LAS unsigned char* lds, const Gemm g, const Sched& S, const Epi& E) {
;     ...
;             PG8_WAIT_V(8); PG8_WAIT_L(0); PG8_BAR; PG8_MMA(0, 0, At, B0); PG8_MMA(0, 1, At, B1); PG8_BAR; PG8_SCHED;
;             PG8_LDA(At, 0, 1); PG8_STAGE(PG8_SB(0, 0), b2, voffB); PG8_STAGE(PG8_SB(0, 1), b2 + hstepB, voffB); PG8_STAGE(PG8_SA(0, 0), a2, voffA);
;             PG8_WAIT_V(8); PG8_WAIT_L(0); PG8_BAR; PG8_MMA(1, 0, At, B0); PG8_MMA(1, 1, At, B1); PG8_BAR; PG8_SCHED;
;             PG8_LDB(B0, 1, 0); PG8_LDB(B1, 1, 1); PG8_SCHED; PG8_LDA(At, 1, 0); PG8_STAGE(PG8_SA(0, 1), a2 + hstepA, voffA);
;             PG8_WAIT_V(8); PG8_WAIT_L(0); PG8_BAR; PG8_MMA(0, 0, At, B0); PG8_MMA(0, 1, At, B1); PG8_BAR; PG8_SCHED;
	v_mfma_f32_16x16x32_bf16 v[62:65], v[152:155], v[184:187], 0
	v_mfma_f32_16x16x32_bf16 v[58:61], v[160:163], v[184:187], 0
	v_mfma_f32_16x16x32_bf16 v[46:49], v[152:155], v[192:195], 0
	v_mfma_f32_16x16x32_bf16 v[42:45], v[160:163], v[192:195], 0
	v_mfma_f32_16x16x32_bf16 v[30:33], v[152:155], v[200:203], 0
	v_mfma_f32_16x16x32_bf16 v[26:29], v[160:163], v[200:203], 0
	v_mfma_f32_16x16x32_bf16 v[14:17], v[152:155], v[208:211], 0
	v_mfma_f32_16x16x32_bf16 v[10:13], v[160:163], v[208:211], 0
	v_mfma_f32_16x16x32_bf16 v[62:65], v[156:159], v[188:191], v[62:65]
	v_mfma_f32_16x16x32_bf16 v[58:61], v[164:167], v[188:191], v[58:61]
	v_mfma_f32_16x16x32_bf16 v[46:49], v[156:159], v[196:199], v[46:49]
	v_mfma_f32_16x16x32_bf16 v[42:45], v[164:167], v[196:199], v[42:45]
	v_mfma_f32_16x16x32_bf16 v[30:33], v[156:159], v[204:207], v[30:33]
	v_mfma_f32_16x16x32_bf16 v[26:29], v[164:167], v[204:207], v[26:29]
	v_mfma_f32_16x16x32_bf16 v[14:17], v[156:159], v[212:215], v[14:17]
	v_mfma_f32_16x16x32_bf16 v[10:13], v[164:167], v[212:215], v[10:13]
	v_mfma_f32_16x16x32_bf16 v[54:57], v[168:171], v[184:187], 0
	v_mfma_f32_16x16x32_bf16 v[50:53], v[176:179], v[184:187], 0
	v_mfma_f32_16x16x32_bf16 v[38:41], v[168:171], v[192:195], 0
	v_mfma_f32_16x16x32_bf16 v[34:37], v[176:179], v[192:195], 0
	v_mfma_f32_16x16x32_bf16 v[22:25], v[168:171], v[200:203], 0
	v_mfma_f32_16x16x32_bf16 v[18:21], v[176:179], v[200:203], 0
	v_mfma_f32_16x16x32_bf16 v[6:9], v[168:171], v[208:211], 0
	v_mfma_f32_16x16x32_bf16 v[2:5], v[176:179], v[208:211], 0
	v_mfma_f32_16x16x32_bf16 v[54:57], v[172:175], v[188:191], v[54:57]
	v_mfma_f32_16x16x32_bf16 v[50:53], v[180:183], v[188:191], v[50:53]
	v_mfma_f32_16x16x32_bf16 v[38:41], v[172:175], v[196:199], v[38:41]
	v_mfma_f32_16x16x32_bf16 v[34:37], v[180:183], v[196:199], v[34:37]
	v_mfma_f32_16x16x32_bf16 v[22:25], v[172:175], v[204:207], v[22:25]
	v_mfma_f32_16x16x32_bf16 v[18:21], v[180:183], v[204:207], v[18:21]
	v_mfma_f32_16x16x32_bf16 v[6:9], v[172:175], v[212:215], v[6:9]
	v_mfma_f32_16x16x32_bf16 v[2:5], v[180:183], v[212:215], v[2:5]
	s_barrier
	s_add_i32 s60, 0, 0x18000
	v_add_u32_e32 v151, s60, v146
	s_add_i32 s61, 0, 0x1c000
	ds_read_b128 v[152:155], v151
	ds_read_b128 v[156:159], v151 offset:1024
	ds_read_b128 v[160:163], v151 offset:2048
	ds_read_b128 v[164:167], v151 offset:3072
	v_add_u32_e32 v151, s61, v146
	ds_read_b128 v[168:171], v151
	ds_read_b128 v[172:175], v151 offset:1024
	ds_read_b128 v[176:179], v151 offset:2048
	ds_read_b128 v[180:183], v151 offset:3072
	s_add_u32 s48, s48, 0x4000
	s_addc_u32 s49, s49, 0
	s_mov_b32 m0, s54
	ds_read_b128 v[184:187], v150 offset:32768
	ds_read_b128 v[188:191], v150 offset:33792
	ds_read_b128 v[192:195], v150 offset:34816
	ds_read_b128 v[196:199], v150 offset:35840
	ds_read_b128 v[200:203], v150 offset:36864
	ds_read_b128 v[204:207], v150 offset:37888
	ds_read_b128 v[208:211], v150 offset:38912
	global_load_lds_dwordx4 v130, s[48:49]
	s_mov_b32 m0, s55
	ds_read_b128 v[212:215], v150 offset:39936
	global_load_lds_dwordx4 v132, s[48:49]
	s_waitcnt vmcnt(8) lgkmcnt(0)
	s_barrier
	v_mfma_f32_16x16x32_bf16 v[126:129], v[152:155], v[184:187], v[126:129]
	v_mfma_f32_16x16x32_bf16 v[122:125], v[160:163], v[184:187], v[122:125]
	v_mfma_f32_16x16x32_bf16 v[110:113], v[152:155], v[192:195], v[110:113]
	v_mfma_f32_16x16x32_bf16 v[106:109], v[160:163], v[192:195], v[106:109]
	v_mfma_f32_16x16x32_bf16 v[94:97], v[152:155], v[200:203], v[94:97]
	v_mfma_f32_16x16x32_bf16 v[90:93], v[160:163], v[200:203], v[90:93]
	v_mfma_f32_16x16x32_bf16 v[78:81], v[152:155], v[208:211], v[78:81]
	v_mfma_f32_16x16x32_bf16 v[74:77], v[160:163], v[208:211], v[74:77]
	v_mfma_f32_16x16x32_bf16 v[126:129], v[156:159], v[188:191], v[126:129]
	v_mfma_f32_16x16x32_bf16 v[122:125], v[164:167], v[188:191], v[122:125]
	v_mfma_f32_16x16x32_bf16 v[110:113], v[156:159], v[196:199], v[110:113]
	v_mfma_f32_16x16x32_bf16 v[106:109], v[164:167], v[196:199], v[106:109]
	v_mfma_f32_16x16x32_bf16 v[94:97], v[156:159], v[204:207], v[94:97]
	v_mfma_f32_16x16x32_bf16 v[90:93], v[164:167], v[204:207], v[90:93]
	v_mfma_f32_16x16x32_bf16 v[78:81], v[156:159], v[212:215], v[78:81]
	v_mfma_f32_16x16x32_bf16 v[74:77], v[164:167], v[212:215], v[74:77]
	v_mfma_f32_16x16x32_bf16 v[118:121], v[168:171], v[184:187], v[118:121]
	v_mfma_f32_16x16x32_bf16 v[114:117], v[176:179], v[184:187], v[114:117]
	v_mfma_f32_16x16x32_bf16 v[102:105], v[168:171], v[192:195], v[102:105]
	v_mfma_f32_16x16x32_bf16 v[98:101], v[176:179], v[192:195], v[98:101]
	v_mfma_f32_16x16x32_bf16 v[86:89], v[168:171], v[200:203], v[86:89]
	v_mfma_f32_16x16x32_bf16 v[82:85], v[176:179], v[200:203], v[82:85]
	v_mfma_f32_16x16x32_bf16 v[70:73], v[168:171], v[208:211], v[70:73]
	v_mfma_f32_16x16x32_bf16 v[66:69], v[176:179], v[208:211], v[66:69]
	v_mfma_f32_16x16x32_bf16 v[118:121], v[172:175], v[188:191], v[118:121]
	v_mfma_f32_16x16x32_bf16 v[114:117], v[180:183], v[188:191], v[114:117]
	v_mfma_f32_16x16x32_bf16 v[102:105], v[172:175], v[196:199], v[102:105]
	v_mfma_f32_16x16x32_bf16 v[98:101], v[180:183], v[196:199], v[98:101]
	v_mfma_f32_16x16x32_bf16 v[86:89], v[172:175], v[204:207], v[86:89]
	v_mfma_f32_16x16x32_bf16 v[82:85], v[180:183], v[204:207], v[82:85]
	v_mfma_f32_16x16x32_bf16 v[70:73], v[172:175], v[212:215], v[70:73]
	v_mfma_f32_16x16x32_bf16 v[66:69], v[180:183], v[212:215], v[66:69]
	s_barrier
; #define PG8_STAGE(bufoff, gbase, voff) do { _Pragma("unroll") for (int _i = 0; _i < 2; ++_i) \
;         __builtin_amdgcn_global_load_lds((const unsigned*)((const char*)(gbase) + (voff)[_i]), (LAS unsigned*)(lds + (bufoff) + ldsw + _i * 8192), 16, 0, 0); } while (0)
; #define PG8_LDA(dst, b, h) do { _Pragma("unroll") for (int m = 0; m < 4; ++m) _Pragma("unroll") for (int k = 0; k < 2; ++k) dst[m][k] = *(const LAS bf16x8*)(lds + PG8_SA(b, h) + aoff + m * 2048 + k * 1024); } while (0)
; #define PG8_LDB(dst, b, h) do { _Pragma("unroll") for (int n = 0; n < 2; ++n) _Pragma("unroll") for (int k = 0; k < 2; ++k) dst[n][k] = *(const LAS bf16x8*)(lds + PG8_SB(b, h) + boff + n * 2048 + k * 1024); } while (0)
; #define PG8_MMA(ai, bj, At, Bt) do { __builtin_amdgcn_s_setprio(1); _Pragma("unroll") for (int m = 0; m < 4; ++m) _Pragma("unroll") for (int n = 0; n < 2; ++n) _Pragma("unroll") for (int k = 0; k < 2; ++k) \
;         acc[ai][bj][m][n] = __builtin_amdgcn_mfma_f32_16x16x32_bf16(Bt[n][k], At[m][k], acc[ai][bj][m][n], 0, 0, 0); __builtin_amdgcn_s_setprio(0); } while (0)
; #define PG8_BAR __builtin_amdgcn_s_barrier()
; template <class Epi, class Sched, bool ABLK = false, bool ALIGN_EPI = true, bool SP2 = true, bool BBLK = true>
; __device__ __forceinline__ void gemm_phase(LAS unsigned char* lds, const Gemm g, const Sched& S, const Epi& E) {
;     ...
;             PG8_LDB(B0, 0, 0); PG8_LDB(B1, 0, 1); PG8_SCHED; PG8_LDA(At, 0, 0); PG8_STAGE(PG8_SA(1, 1), a1 + hstepA, voffA);
;             PG8_WAIT_V(8); PG8_WAIT_L(0); PG8_BAR; PG8_MMA(0, 0, At, B0); PG8_MMA(0, 1, At, B1); PG8_BAR; PG8_SCHED;
;             PG8_LDA(At, 0, 1); PG8_STAGE(PG8_SB(0, 0), b2, voffB); PG8_STAGE(PG8_SB(0, 1), b2 + hstepB, voffB); PG8_STAGE(PG8_SA(0, 0), a2, voffA);
;             PG8_WAIT_V(8); PG8_WAIT_L(0); PG8_BAR; PG8_MMA(1, 0, At, B0); PG8_MMA(1, 1, At, B1); PG8_BAR; PG8_SCHED;
;             PG8_LDB(B0, 1, 0); PG8_LDB(B1, 1, 1); PG8_SCHED; PG8_LDA(At, 1, 0); PG8_STAGE(PG8_SA(0, 1), a2 + hstepA, voffA);
;             PG8_WAIT_V(8); PG8_WAIT_L(0); PG8_BAR; PG8_MMA(0, 0, At, B0); PG8_MMA(0, 1, At, B1); PG8_BAR; PG8_SCHED;
;             PG8_LDA(At, 1, 1); PG8_STAGE(PG8_SB(1, 0), b3, voffB); PG8_STAGE(PG8_SB(1, 1), b3 + hstepB, voffB); PG8_STAGE(PG8_SA(1, 0), a3, voffA);
;             PG8_WAIT_V(8); PG8_WAIT_L(0); PG8_BAR; PG8_MMA(1, 0, At, B0); PG8_MMA(1, 1, At, B1); PG8_BAR; PG8_SCHED;
	s_add_u32 s48, s46, 0x8000
	s_addc_u32 s49, s47, 0
	s_add_i32 s81, s60, s51
	s_mov_b32 m0, s81
	ds_read_b128 v[184:187], v150 offset:49152
	ds_read_b128 v[188:191], v150 offset:50176
	ds_read_b128 v[192:195], v150 offset:51200
	ds_read_b128 v[196:199], v150 offset:52224
	global_load_lds_dwordx4 v130, s[48:49]
	s_add_i32 m0, s81, 0x2000
	s_add_u32 s46, s46, 0xc000
	v_lshl_add_u64 v[216:217], s[48:49], 0, v[132:133]
	s_addc_u32 s47, s47, 0
	s_add_i32 s48, s61, s51
	global_load_lds_dwordx4 v[216:217], off
	s_mov_b32 m0, s48
	ds_read_b128 v[200:203], v150 offset:53248
	global_load_lds_dwordx4 v130, s[46:47]
	s_add_i32 m0, s48, 0x2000
	ds_read_b128 v[204:207], v150 offset:54272
	global_load_lds_dwordx4 v132, s[46:47]
	s_mov_b32 m0, s56
	ds_read_b128 v[208:211], v150 offset:55296
	global_load_lds_dwordx4 v130, s[42:43]
	s_mov_b32 m0, s57
	ds_read_b128 v[212:215], v150 offset:56320
	global_load_lds_dwordx4 v132, s[42:43]
	s_waitcnt vmcnt(8) lgkmcnt(0)
	s_barrier
	v_mfma_f32_16x16x32_bf16 v[62:65], v[152:155], v[184:187], v[62:65]
	v_mfma_f32_16x16x32_bf16 v[58:61], v[160:163], v[184:187], v[58:61]
	v_mfma_f32_16x16x32_bf16 v[46:49], v[152:155], v[192:195], v[46:49]
	v_mfma_f32_16x16x32_bf16 v[42:45], v[160:163], v[192:195], v[42:45]
	v_mfma_f32_16x16x32_bf16 v[30:33], v[152:155], v[200:203], v[30:33]
	v_mfma_f32_16x16x32_bf16 v[26:29], v[160:163], v[200:203], v[26:29]
	v_mfma_f32_16x16x32_bf16 v[14:17], v[152:155], v[208:211], v[14:17]
	v_mfma_f32_16x16x32_bf16 v[10:13], v[160:163], v[208:211], v[10:13]
	v_mfma_f32_16x16x32_bf16 v[62:65], v[156:159], v[188:191], v[62:65]
	v_mfma_f32_16x16x32_bf16 v[58:61], v[164:167], v[188:191], v[58:61]
	v_mfma_f32_16x16x32_bf16 v[46:49], v[156:159], v[196:199], v[46:49]
	v_mfma_f32_16x16x32_bf16 v[42:45], v[164:167], v[196:199], v[42:45]
	v_mfma_f32_16x16x32_bf16 v[30:33], v[156:159], v[204:207], v[30:33]
	v_mfma_f32_16x16x32_bf16 v[26:29], v[164:167], v[204:207], v[26:29]
	v_mfma_f32_16x16x32_bf16 v[14:17], v[156:159], v[212:215], v[14:17]
	v_mfma_f32_16x16x32_bf16 v[10:13], v[164:167], v[212:215], v[10:13]
	v_mfma_f32_16x16x32_bf16 v[54:57], v[168:171], v[184:187], v[54:57]
	v_mfma_f32_16x16x32_bf16 v[50:53], v[176:179], v[184:187], v[50:53]
	v_mfma_f32_16x16x32_bf16 v[38:41], v[168:171], v[192:195], v[38:41]
	v_mfma_f32_16x16x32_bf16 v[34:37], v[176:179], v[192:195], v[34:37]
	v_mfma_f32_16x16x32_bf16 v[22:25], v[168:171], v[200:203], v[22:25]
	v_mfma_f32_16x16x32_bf16 v[18:21], v[176:179], v[200:203], v[18:21]
	v_mfma_f32_16x16x32_bf16 v[6:9], v[168:171], v[208:211], v[6:9]
	v_mfma_f32_16x16x32_bf16 v[2:5], v[176:179], v[208:211], v[2:5]
	v_mfma_f32_16x16x32_bf16 v[54:57], v[172:175], v[188:191], v[54:57]
	v_mfma_f32_16x16x32_bf16 v[50:53], v[180:183], v[188:191], v[50:53]
	v_mfma_f32_16x16x32_bf16 v[38:41], v[172:175], v[196:199], v[38:41]
	v_mfma_f32_16x16x32_bf16 v[34:37], v[180:183], v[196:199], v[34:37]
	v_mfma_f32_16x16x32_bf16 v[22:25], v[172:175], v[204:207], v[22:25]
	v_mfma_f32_16x16x32_bf16 v[18:21], v[180:183], v[204:207], v[18:21]
	v_mfma_f32_16x16x32_bf16 v[6:9], v[172:175], v[212:215], v[6:9]
	v_mfma_f32_16x16x32_bf16 v[2:5], v[180:183], v[212:215], v[2:5]
	s_barrier
	s_add_u32 s40, s40, 0x10000
	s_addc_u32 s41, s41, 0
	s_cmp_ge_u32 s79, s59
.LBB0_540:
	ds_read_b128 v[152:155], v148
	ds_read_b128 v[156:159], v148 offset:1024
	ds_read_b128 v[160:163], v148 offset:2048
	ds_read_b128 v[164:167], v148 offset:3072
	ds_read_b128 v[168:171], v149
	ds_read_b128 v[172:175], v149 offset:1024
	ds_read_b128 v[176:179], v149 offset:2048
	ds_read_b128 v[180:183], v149 offset:3072
	s_add_u32 s42, s75, s40
	s_addc_u32 s43, s76, s41
	s_add_u32 s48, s42, 0x10000
	s_addc_u32 s49, s43, 0
	s_add_i32 s79, s79, 2
	s_add_u32 s46, s66, s40
	s_addc_u32 s47, s67, s41
	s_add_u32 s42, s42, 0x18000
	s_addc_u32 s43, s43, 0
	s_cmp_eq_u32 s77, s40
	s_cselect_b32 s43, s65, s43
	s_cselect_b32 s42, s64, s42
	s_cselect_b32 s47, s4, s47
	s_cselect_b32 s46, s5, s46
	s_cselect_b32 s49, s63, s49
	s_cselect_b32 s48, s35, s48
	v_lshl_add_u64 v[216:217], v[142:143], 0, s[40:41]
	s_add_i32 m0, s52, 0xc000
	ds_read_b128 v[184:187], v150
	ds_read_b128 v[188:191], v150 offset:1024
	ds_read_b128 v[192:195], v150 offset:2048
	ds_read_b128 v[196:199], v150 offset:3072
	ds_read_b128 v[200:203], v150 offset:4096
	ds_read_b128 v[204:207], v150 offset:5120
	ds_read_b128 v[208:211], v150 offset:6144
	global_load_lds_dwordx4 v[216:217], off
	v_lshl_add_u64 v[216:217], v[144:145], 0, s[40:41]
	s_add_i32 m0, s52, 0xe000
	ds_read_b128 v[212:215], v150 offset:7168
	global_load_lds_dwordx4 v[216:217], off
	s_waitcnt vmcnt(8) lgkmcnt(0)
	s_barrier
; #define PG8_STAGE(bufoff, gbase, voff) do { _Pragma("unroll") for (int _i = 0; _i < 2; ++_i) \
;         __builtin_amdgcn_global_load_lds((const unsigned*)((const char*)(gbase) + (voff)[_i]), (LAS unsigned*)(lds + (bufoff) + ldsw + _i * 8192), 16, 0, 0); } while (0)
; #define PG8_LDA(dst, b, h) do { _Pragma("unroll") for (int m = 0; m < 4; ++m) _Pragma("unroll") for (int k = 0; k < 2; ++k) dst[m][k] = *(const LAS bf16x8*)(lds + PG8_SA(b, h) + aoff + m * 2048 + k * 1024); } while (0)
; #define PG8_LDB(dst, b, h) do { _Pragma("unroll") for (int n = 0; n < 2; ++n) _Pragma("unroll") for (int k = 0; k < 2; ++k) dst[n][k] = *(const LAS bf16x8*)(lds + PG8_SB(b, h) + boff + n * 2048 + k * 1024); } while (0)
; #define PG8_MMA(ai, bj, At, Bt) do { __builtin_amdgcn_s_setprio(1); _Pragma("unroll") for (int m = 0; m < 4; ++m) _Pragma("unroll") for (int n = 0; n < 2; ++n) _Pragma("unroll") for (int k = 0; k < 2; ++k) \
;         acc[ai][bj][m][n] = __builtin_amdgcn_mfma_f32_16x16x32_bf16(Bt[n][k], At[m][k], acc[ai][bj][m][n], 0, 0, 0); __builtin_amdgcn_s_setprio(0); } while (0)
; #define PG8_WAIT_V(n) asm volatile("s_waitcnt vmcnt(" #n ")" ::: "memory")
; #define PG8_WAIT_L(n) asm volatile("s_waitcnt lgkmcnt(" #n ")" ::: "memory")
; #define PG8_BAR __builtin_amdgcn_s_barrier()
; #define PG8_SCHED __builtin_amdgcn_sched_barrier(0)
; template <class Epi, class Sched, bool ABLK = false, bool ALIGN_EPI = true, bool SP2 = true, bool BBLK = true>
; __device__ __forceinline__ void gemm_phase(LAS unsigned char* lds, const Gemm g, const Sched& S, const Epi& E) {
;     ...
;             PG8_WAIT_V(8); PG8_WAIT_L(0); PG8_BAR; PG8_MMA(0, 0, At, B0); PG8_MMA(0, 1, At, B1); PG8_BAR; PG8_SCHED;
;             PG8_LDA(At, 0, 1); PG8_STAGE(PG8_SB(0, 0), b2, voffB); PG8_STAGE(PG8_SB(0, 1), b2 + hstepB, voffB); PG8_STAGE(PG8_SA(0, 0), a2, voffA);
;             PG8_WAIT_V(8); PG8_WAIT_L(0); PG8_BAR; PG8_MMA(1, 0, At, B0); PG8_MMA(1, 1, At, B1); PG8_BAR; PG8_SCHED;
;             PG8_LDB(B0, 1, 0); PG8_LDB(B1, 1, 1); PG8_SCHED; PG8_LDA(At, 1, 0); PG8_STAGE(PG8_SA(0, 1), a2 + hstepA, voffA);
	v_mfma_f32_16x16x32_bf16 v[126:129], v[152:155], v[184:187], v[126:129]
	v_mfma_f32_16x16x32_bf16 v[122:125], v[160:163], v[184:187], v[122:125]
	v_mfma_f32_16x16x32_bf16 v[110:113], v[152:155], v[192:195], v[110:113]
	v_mfma_f32_16x16x32_bf16 v[106:109], v[160:163], v[192:195], v[106:109]
	v_mfma_f32_16x16x32_bf16 v[94:97], v[152:155], v[200:203], v[94:97]
	v_mfma_f32_16x16x32_bf16 v[90:93], v[160:163], v[200:203], v[90:93]
	v_mfma_f32_16x16x32_bf16 v[78:81], v[152:155], v[208:211], v[78:81]
	v_mfma_f32_16x16x32_bf16 v[74:77], v[160:163], v[208:211], v[74:77]
	v_mfma_f32_16x16x32_bf16 v[126:129], v[156:159], v[188:191], v[126:129]
	v_mfma_f32_16x16x32_bf16 v[122:125], v[164:167], v[188:191], v[122:125]
	v_mfma_f32_16x16x32_bf16 v[110:113], v[156:159], v[196:199], v[110:113]
	v_mfma_f32_16x16x32_bf16 v[106:109], v[164:167], v[196:199], v[106:109]
	v_mfma_f32_16x16x32_bf16 v[94:97], v[156:159], v[204:207], v[94:97]
	v_mfma_f32_16x16x32_bf16 v[90:93], v[164:167], v[204:207], v[90:93]
	v_mfma_f32_16x16x32_bf16 v[78:81], v[156:159], v[212:215], v[78:81]
	v_mfma_f32_16x16x32_bf16 v[74:77], v[164:167], v[212:215], v[74:77]
	v_mfma_f32_16x16x32_bf16 v[118:121], v[168:171], v[184:187], v[118:121]
	v_mfma_f32_16x16x32_bf16 v[114:117], v[176:179], v[184:187], v[114:117]
	v_mfma_f32_16x16x32_bf16 v[102:105], v[168:171], v[192:195], v[102:105]
	v_mfma_f32_16x16x32_bf16 v[98:101], v[176:179], v[192:195], v[98:101]
	v_mfma_f32_16x16x32_bf16 v[86:89], v[168:171], v[200:203], v[86:89]
	v_mfma_f32_16x16x32_bf16 v[82:85], v[176:179], v[200:203], v[82:85]
	v_mfma_f32_16x16x32_bf16 v[70:73], v[168:171], v[208:211], v[70:73]
	v_mfma_f32_16x16x32_bf16 v[66:69], v[176:179], v[208:211], v[66:69]
	v_mfma_f32_16x16x32_bf16 v[118:121], v[172:175], v[188:191], v[118:121]
	v_mfma_f32_16x16x32_bf16 v[114:117], v[180:183], v[188:191], v[114:117]
	v_mfma_f32_16x16x32_bf16 v[102:105], v[172:175], v[196:199], v[102:105]
	v_mfma_f32_16x16x32_bf16 v[98:101], v[180:183], v[196:199], v[98:101]
	v_mfma_f32_16x16x32_bf16 v[86:89], v[172:175], v[204:207], v[86:89]
	v_mfma_f32_16x16x32_bf16 v[82:85], v[180:183], v[204:207], v[82:85]
	v_mfma_f32_16x16x32_bf16 v[70:73], v[172:175], v[212:215], v[70:73]
	v_mfma_f32_16x16x32_bf16 v[66:69], v[180:183], v[212:215], v[66:69]
	s_barrier
	s_add_i32 s60, s72, s51
	s_mov_b32 m0, s60
	ds_read_b128 v[184:187], v150 offset:16384
	ds_read_b128 v[188:191], v150 offset:17408
	ds_read_b128 v[192:195], v150 offset:18432
	ds_read_b128 v[196:199], v150 offset:19456
	global_load_lds_dwordx4 v130, s[46:47]
	s_add_i32 m0, s60, 0x2000
	s_add_u32 s60, s46, 0x4000
	s_addc_u32 s61, s47, 0
	s_add_i32 s81, s73, s51
	global_load_lds_dwordx4 v132, s[46:47]
	s_mov_b32 m0, s81
	ds_read_b128 v[200:203], v150 offset:20480
	global_load_lds_dwordx4 v130, s[60:61]
	s_add_i32 m0, s81, 0x2000
	ds_read_b128 v[204:207], v150 offset:21504
	global_load_lds_dwordx4 v132, s[60:61]
	s_mov_b32 m0, s52
	ds_read_b128 v[208:211], v150 offset:22528
	global_load_lds_dwordx4 v130, s[48:49]
	s_mov_b32 m0, s53
	ds_read_b128 v[212:215], v150 offset:23552
	global_load_lds_dwordx4 v132, s[48:49]
	s_waitcnt vmcnt(8) lgkmcnt(0)
	s_barrier
	v_mfma_f32_16x16x32_bf16 v[62:65], v[152:155], v[184:187], v[62:65]
	v_mfma_f32_16x16x32_bf16 v[58:61], v[160:163], v[184:187], v[58:61]
	v_mfma_f32_16x16x32_bf16 v[46:49], v[152:155], v[192:195], v[46:49]
	v_mfma_f32_16x16x32_bf16 v[42:45], v[160:163], v[192:195], v[42:45]
	v_mfma_f32_16x16x32_bf16 v[30:33], v[152:155], v[200:203], v[30:33]
	v_mfma_f32_16x16x32_bf16 v[26:29], v[160:163], v[200:203], v[26:29]
	v_mfma_f32_16x16x32_bf16 v[14:17], v[152:155], v[208:211], v[14:17]
	v_mfma_f32_16x16x32_bf16 v[10:13], v[160:163], v[208:211], v[10:13]
	v_mfma_f32_16x16x32_bf16 v[62:65], v[156:159], v[188:191], v[62:65]
	v_mfma_f32_16x16x32_bf16 v[58:61], v[164:167], v[188:191], v[58:61]
	v_mfma_f32_16x16x32_bf16 v[46:49], v[156:159], v[196:199], v[46:49]
	v_mfma_f32_16x16x32_bf16 v[42:45], v[164:167], v[196:199], v[42:45]
	v_mfma_f32_16x16x32_bf16 v[30:33], v[156:159], v[204:207], v[30:33]
	v_mfma_f32_16x16x32_bf16 v[26:29], v[164:167], v[204:207], v[26:29]
	v_mfma_f32_16x16x32_bf16 v[14:17], v[156:159], v[212:215], v[14:17]
	v_mfma_f32_16x16x32_bf16 v[10:13], v[164:167], v[212:215], v[10:13]
	v_mfma_f32_16x16x32_bf16 v[54:57], v[168:171], v[184:187], v[54:57]
	v_mfma_f32_16x16x32_bf16 v[50:53], v[176:179], v[184:187], v[50:53]
	v_mfma_f32_16x16x32_bf16 v[38:41], v[168:171], v[192:195], v[38:41]
	v_mfma_f32_16x16x32_bf16 v[34:37], v[176:179], v[192:195], v[34:37]
	v_mfma_f32_16x16x32_bf16 v[22:25], v[168:171], v[200:203], v[22:25]
	v_mfma_f32_16x16x32_bf16 v[18:21], v[176:179], v[200:203], v[18:21]
	v_mfma_f32_16x16x32_bf16 v[6:9], v[168:171], v[208:211], v[6:9]
	v_mfma_f32_16x16x32_bf16 v[2:5], v[176:179], v[208:211], v[2:5]
	v_mfma_f32_16x16x32_bf16 v[54:57], v[172:175], v[188:191], v[54:57]
	v_mfma_f32_16x16x32_bf16 v[50:53], v[180:183], v[188:191], v[50:53]
	v_mfma_f32_16x16x32_bf16 v[38:41], v[172:175], v[196:199], v[38:41]
	v_mfma_f32_16x16x32_bf16 v[34:37], v[180:183], v[196:199], v[34:37]
	v_mfma_f32_16x16x32_bf16 v[22:25], v[172:175], v[204:207], v[22:25]
	v_mfma_f32_16x16x32_bf16 v[18:21], v[180:183], v[204:207], v[18:21]
	v_mfma_f32_16x16x32_bf16 v[6:9], v[172:175], v[212:215], v[6:9]
	v_mfma_f32_16x16x32_bf16 v[2:5], v[180:183], v[212:215], v[2:5]
	s_barrier
; #define PG8_STAGE(bufoff, gbase, voff) do { _Pragma("unroll") for (int _i = 0; _i < 2; ++_i) \
;         __builtin_amdgcn_global_load_lds((const unsigned*)((const char*)(gbase) + (voff)[_i]), (LAS unsigned*)(lds + (bufoff) + ldsw + _i * 8192), 16, 0, 0); } while (0)
; #define PG8_LDA(dst, b, h) do { _Pragma("unroll") for (int m = 0; m < 4; ++m) _Pragma("unroll") for (int k = 0; k < 2; ++k) dst[m][k] = *(const LAS bf16x8*)(lds + PG8_SA(b, h) + aoff + m * 2048 + k * 1024); } while (0)
; #define PG8_LDB(dst, b, h) do { _Pragma("unroll") for (int n = 0; n < 2; ++n) _Pragma("unroll") for (int k = 0; k < 2; ++k) dst[n][k] = *(const LAS bf16x8*)(lds + PG8_SB(b, h) + boff + n * 2048 + k * 1024); } while (0)
; #define PG8_MMA(ai, bj, At, Bt) do { __builtin_amdgcn_s_setprio(1); _Pragma("unroll") for (int m = 0; m < 4; ++m) _Pragma("unroll") for (int n = 0; n < 2; ++n) _Pragma("unroll") for (int k = 0; k < 2; ++k) \
;         acc[ai][bj][m][n] = __builtin_amdgcn_mfma_f32_16x16x32_bf16(Bt[n][k], At[m][k], acc[ai][bj][m][n], 0, 0, 0); __builtin_amdgcn_s_setprio(0); } while (0)
; #define PG8_WAIT_V(n) asm volatile("s_waitcnt vmcnt(" #n ")" ::: "memory")
; #define PG8_WAIT_L(n) asm volatile("s_waitcnt lgkmcnt(" #n ")" ::: "memory")
; #define PG8_BAR __builtin_amdgcn_s_barrier()
; #define PG8_SCHED __builtin_amdgcn_sched_barrier(0)
; template <class Epi, class Sched, bool ABLK = false, bool ALIGN_EPI = true, bool SP2 = true, bool BBLK = true>
; __device__ __forceinline__ void gemm_phase(LAS unsigned char* lds, const Gemm g, const Sched& S, const Epi& E) {
;     ...
;             PG8_LDB(B0, 1, 0); PG8_LDB(B1, 1, 1); PG8_SCHED; PG8_LDA(At, 1, 0); PG8_STAGE(PG8_SA(0, 1), a2 + hstepA, voffA);
;             PG8_WAIT_V(8); PG8_WAIT_L(0); PG8_BAR; PG8_MMA(0, 0, At, B0); PG8_MMA(0, 1, At, B1); PG8_BAR; PG8_SCHED;
;             PG8_LDA(At, 1, 1); PG8_STAGE(PG8_SB(1, 0), b3, voffB); PG8_STAGE(PG8_SB(1, 1), b3 + hstepB, voffB); PG8_STAGE(PG8_SA(1, 0), a3, voffA);
;             PG8_WAIT_V(8); PG8_WAIT_L(0); PG8_BAR; PG8_MMA(1, 0, At, B0); PG8_MMA(1, 1, At, B1); PG8_BAR; PG8_SCHED;
;     ...
;         if constexpr (ALIGN_EPI) { if (wr == 0) PG8_BAR; }
	s_add_i32 s60, 0, 0x18000
	v_add_u32_e32 v151, s60, v146
	s_add_i32 s61, 0, 0x1c000
	ds_read_b128 v[152:155], v151
	ds_read_b128 v[156:159], v151 offset:1024
	ds_read_b128 v[160:163], v151 offset:2048
	ds_read_b128 v[164:167], v151 offset:3072
	v_add_u32_e32 v151, s61, v146
	ds_read_b128 v[168:171], v151
	ds_read_b128 v[172:175], v151 offset:1024
	ds_read_b128 v[176:179], v151 offset:2048
	ds_read_b128 v[180:183], v151 offset:3072
	s_add_u32 s48, s48, 0x4000
	s_addc_u32 s49, s49, 0
	s_mov_b32 m0, s54
	ds_read_b128 v[184:187], v150 offset:32768
	ds_read_b128 v[188:191], v150 offset:33792
	ds_read_b128 v[192:195], v150 offset:34816
	ds_read_b128 v[196:199], v150 offset:35840
	ds_read_b128 v[200:203], v150 offset:36864
	ds_read_b128 v[204:207], v150 offset:37888
	ds_read_b128 v[208:211], v150 offset:38912
	global_load_lds_dwordx4 v130, s[48:49]
	s_mov_b32 m0, s55
	ds_read_b128 v[212:215], v150 offset:39936
	global_load_lds_dwordx4 v132, s[48:49]
	s_waitcnt vmcnt(8) lgkmcnt(0)
	s_barrier
	v_mfma_f32_16x16x32_bf16 v[126:129], v[152:155], v[184:187], v[126:129]
	v_mfma_f32_16x16x32_bf16 v[122:125], v[160:163], v[184:187], v[122:125]
	v_mfma_f32_16x16x32_bf16 v[110:113], v[152:155], v[192:195], v[110:113]
	v_mfma_f32_16x16x32_bf16 v[106:109], v[160:163], v[192:195], v[106:109]
	v_mfma_f32_16x16x32_bf16 v[94:97], v[152:155], v[200:203], v[94:97]
	v_mfma_f32_16x16x32_bf16 v[90:93], v[160:163], v[200:203], v[90:93]
	v_mfma_f32_16x16x32_bf16 v[78:81], v[152:155], v[208:211], v[78:81]
	v_mfma_f32_16x16x32_bf16 v[74:77], v[160:163], v[208:211], v[74:77]
	v_mfma_f32_16x16x32_bf16 v[126:129], v[156:159], v[188:191], v[126:129]
	v_mfma_f32_16x16x32_bf16 v[122:125], v[164:167], v[188:191], v[122:125]
	v_mfma_f32_16x16x32_bf16 v[110:113], v[156:159], v[196:199], v[110:113]
	v_mfma_f32_16x16x32_bf16 v[106:109], v[164:167], v[196:199], v[106:109]
	v_mfma_f32_16x16x32_bf16 v[94:97], v[156:159], v[204:207], v[94:97]
	v_mfma_f32_16x16x32_bf16 v[90:93], v[164:167], v[204:207], v[90:93]
	v_mfma_f32_16x16x32_bf16 v[78:81], v[156:159], v[212:215], v[78:81]
	v_mfma_f32_16x16x32_bf16 v[74:77], v[164:167], v[212:215], v[74:77]
	v_mfma_f32_16x16x32_bf16 v[118:121], v[168:171], v[184:187], v[118:121]
	v_mfma_f32_16x16x32_bf16 v[114:117], v[176:179], v[184:187], v[114:117]
	v_mfma_f32_16x16x32_bf16 v[102:105], v[168:171], v[192:195], v[102:105]
	v_mfma_f32_16x16x32_bf16 v[98:101], v[176:179], v[192:195], v[98:101]
	v_mfma_f32_16x16x32_bf16 v[86:89], v[168:171], v[200:203], v[86:89]
	v_mfma_f32_16x16x32_bf16 v[82:85], v[176:179], v[200:203], v[82:85]
	v_mfma_f32_16x16x32_bf16 v[70:73], v[168:171], v[208:211], v[70:73]
	v_mfma_f32_16x16x32_bf16 v[66:69], v[176:179], v[208:211], v[66:69]
	v_mfma_f32_16x16x32_bf16 v[118:121], v[172:175], v[188:191], v[118:121]
	v_mfma_f32_16x16x32_bf16 v[114:117], v[180:183], v[188:191], v[114:117]
	v_mfma_f32_16x16x32_bf16 v[102:105], v[172:175], v[196:199], v[102:105]
	v_mfma_f32_16x16x32_bf16 v[98:101], v[180:183], v[196:199], v[98:101]
	v_mfma_f32_16x16x32_bf16 v[86:89], v[172:175], v[204:207], v[86:89]
	v_mfma_f32_16x16x32_bf16 v[82:85], v[180:183], v[204:207], v[82:85]
	v_mfma_f32_16x16x32_bf16 v[70:73], v[172:175], v[212:215], v[70:73]
	v_mfma_f32_16x16x32_bf16 v[66:69], v[180:183], v[212:215], v[66:69]
	s_barrier
	s_add_u32 s48, s46, 0x8000
	s_addc_u32 s49, s47, 0
	s_add_i32 s81, s60, s51
	s_mov_b32 m0, s81
	ds_read_b128 v[184:187], v150 offset:49152
	ds_read_b128 v[188:191], v150 offset:50176
	ds_read_b128 v[192:195], v150 offset:51200
	ds_read_b128 v[196:199], v150 offset:52224
	global_load_lds_dwordx4 v130, s[48:49]
	s_add_i32 m0, s81, 0x2000
	s_add_u32 s46, s46, 0xc000
	v_lshl_add_u64 v[216:217], s[48:49], 0, v[132:133]
	s_addc_u32 s47, s47, 0
	s_add_i32 s48, s61, s51
	global_load_lds_dwordx4 v[216:217], off
	s_mov_b32 m0, s48
	ds_read_b128 v[200:203], v150 offset:53248
	global_load_lds_dwordx4 v130, s[46:47]
	s_add_i32 m0, s48, 0x2000
	ds_read_b128 v[204:207], v150 offset:54272
	global_load_lds_dwordx4 v132, s[46:47]
	s_mov_b32 m0, s56
	ds_read_b128 v[208:211], v150 offset:55296
	global_load_lds_dwordx4 v130, s[42:43]
	s_mov_b32 m0, s57
	ds_read_b128 v[212:215], v150 offset:56320
	global_load_lds_dwordx4 v132, s[42:43]
	s_waitcnt vmcnt(8) lgkmcnt(0)
	s_barrier
	v_mfma_f32_16x16x32_bf16 v[62:65], v[152:155], v[184:187], v[62:65]
	v_mfma_f32_16x16x32_bf16 v[58:61], v[160:163], v[184:187], v[58:61]
	v_mfma_f32_16x16x32_bf16 v[46:49], v[152:155], v[192:195], v[46:49]
	v_mfma_f32_16x16x32_bf16 v[42:45], v[160:163], v[192:195], v[42:45]
	v_mfma_f32_16x16x32_bf16 v[30:33], v[152:155], v[200:203], v[30:33]
	v_mfma_f32_16x16x32_bf16 v[26:29], v[160:163], v[200:203], v[26:29]
	v_mfma_f32_16x16x32_bf16 v[14:17], v[152:155], v[208:211], v[14:17]
	v_mfma_f32_16x16x32_bf16 v[10:13], v[160:163], v[208:211], v[10:13]
	v_mfma_f32_16x16x32_bf16 v[62:65], v[156:159], v[188:191], v[62:65]
	v_mfma_f32_16x16x32_bf16 v[58:61], v[164:167], v[188:191], v[58:61]
	v_mfma_f32_16x16x32_bf16 v[46:49], v[156:159], v[196:199], v[46:49]
	v_mfma_f32_16x16x32_bf16 v[42:45], v[164:167], v[196:199], v[42:45]
	v_mfma_f32_16x16x32_bf16 v[30:33], v[156:159], v[204:207], v[30:33]
	v_mfma_f32_16x16x32_bf16 v[26:29], v[164:167], v[204:207], v[26:29]
	v_mfma_f32_16x16x32_bf16 v[14:17], v[156:159], v[212:215], v[14:17]
	v_mfma_f32_16x16x32_bf16 v[10:13], v[164:167], v[212:215], v[10:13]
	v_mfma_f32_16x16x32_bf16 v[54:57], v[168:171], v[184:187], v[54:57]
	v_mfma_f32_16x16x32_bf16 v[50:53], v[176:179], v[184:187], v[50:53]
	v_mfma_f32_16x16x32_bf16 v[38:41], v[168:171], v[192:195], v[38:41]
	v_mfma_f32_16x16x32_bf16 v[34:37], v[176:179], v[192:195], v[34:37]
	v_mfma_f32_16x16x32_bf16 v[22:25], v[168:171], v[200:203], v[22:25]
	v_mfma_f32_16x16x32_bf16 v[18:21], v[176:179], v[200:203], v[18:21]
	v_mfma_f32_16x16x32_bf16 v[6:9], v[168:171], v[208:211], v[6:9]
	v_mfma_f32_16x16x32_bf16 v[2:5], v[176:179], v[208:211], v[2:5]
	v_mfma_f32_16x16x32_bf16 v[54:57], v[172:175], v[188:191], v[54:57]
	v_mfma_f32_16x16x32_bf16 v[50:53], v[180:183], v[188:191], v[50:53]
	v_mfma_f32_16x16x32_bf16 v[38:41], v[172:175], v[196:199], v[38:41]
	v_mfma_f32_16x16x32_bf16 v[34:37], v[180:183], v[196:199], v[34:37]
	v_mfma_f32_16x16x32_bf16 v[22:25], v[172:175], v[204:207], v[22:25]
	v_mfma_f32_16x16x32_bf16 v[18:21], v[180:183], v[204:207], v[18:21]
	v_mfma_f32_16x16x32_bf16 v[6:9], v[172:175], v[212:215], v[6:9]
	v_mfma_f32_16x16x32_bf16 v[2:5], v[180:183], v[212:215], v[2:5]
	s_barrier
	s_add_u32 s40, s40, 0x10000
	s_addc_u32 s41, s41, 0
	s_cmp_ge_u32 s79, s59
	s_cbranch_scc0 .LBB0_540
	s_and_b64 vcc, exec, s[12:13]
	s_cbranch_vccz .LBB0_543
	s_barrier

; #define PG8_STAGE(bufoff, gbase, voff) do { _Pragma("unroll") for (int _i = 0; _i < 2; ++_i) \
;         __builtin_amdgcn_global_load_lds((const unsigned*)((const char*)(gbase) + (voff)[_i]), (LAS unsigned*)(lds + (bufoff) + ldsw + _i * 8192), 16, 0, 0); } while (0)
; #define PG8_LDA(dst, b, h) do { _Pragma("unroll") for (int m = 0; m < 4; ++m) _Pragma("unroll") for (int k = 0; k < 2; ++k) dst[m][k] = *(const LAS bf16x8*)(lds + PG8_SA(b, h) + aoff + m * 2048 + k * 1024); } while (0)
; #define PG8_LDB(dst, b, h) do { _Pragma("unroll") for (int n = 0; n < 2; ++n) _Pragma("unroll") for (int k = 0; k < 2; ++k) dst[n][k] = *(const LAS bf16x8*)(lds + PG8_SB(b, h) + boff + n * 2048 + k * 1024); } while (0)
; #define PG8_WAIT_V(n) asm volatile("s_waitcnt vmcnt(" #n ")" ::: "memory")
; #define PG8_WAIT_L(n) asm volatile("s_waitcnt lgkmcnt(" #n ")" ::: "memory")
; template <class Epi, class Sched, bool ABLK = false, bool ALIGN_EPI = true, bool SP2 = true, bool BBLK = true>
; __device__ __forceinline__ void gemm_phase(LAS unsigned char* lds, const Gemm g, const Sched& S, const Epi& E) {
;     ...
;         const bool has_next = S.next(ui + 1, nxt);
;         const int nt = cur.nt;
;         const char* nuA = has_next ? a_unit(nxt) : uA; const int ntbA = has_next ? nxt.k0 / BK : tbA; const char* nB = has_next ? (const char*)g.Bt + (size_t)nxt.pn * tstepB + b_k0(nxt.k0) : cB;
;         for (int t = 0; t < nt; t += 2) {
;             const bool last = (t == nt - 2);
;             const char* a1 = a_tile(uA, tbA + t + 1);
;             const char* a2 = last ? a_tile(nuA, ntbA) : a_tile(uA, tbA + t + 2); const char* b2 = last ? nB : cB + (size_t)(t + 2) * kstepB;
;             const char* a3 = last ? a_tile(nuA, ntbA + 1) : a_tile(uA, tbA + t + 3); const char* b3 = b2 + kstepB;
;             if (last && has_next) S.a_ready(nxt);
;             if constexpr (SP2) {
;             PG8_LDB(B0, 0, 0); PG8_LDB(B1, 0, 1); PG8_SCHED; PG8_LDA(At, 0, 0); PG8_STAGE(PG8_SA(1, 1), a1 + hstepA, voffA);
;             PG8_WAIT_V(8); PG8_WAIT_L(0); PG8_BAR; PG8_MMA(0, 0, At, B0); PG8_MMA(0, 1, At, B1); PG8_BAR; PG8_SCHED;
;             PG8_LDA(At, 0, 1); PG8_STAGE(PG8_SB(0, 0), b2, voffB); PG8_STAGE(PG8_SB(0, 1), b2 + hstepB, voffB); PG8_STAGE(PG8_SA(0, 0), a2, voffA);
;             PG8_WAIT_V(8); PG8_WAIT_L(0); PG8_BAR; PG8_MMA(1, 0, At, B0); PG8_MMA(1, 1, At, B1); PG8_BAR; PG8_SCHED;
.LBB0_667:
	s_ashr_i32 s15, s14, 31
	s_lshl_b64 s[4:5], s[14:15], 20
	s_add_u32 s18, s59, s4
	s_addc_u32 s19, s62, s5
	s_and_b64 s[4:5], s[20:21], exec
	s_cselect_b32 s2, s19, s27
	s_cselect_b32 s4, s18, s26
	s_ashr_i32 s17, s16, 31
	s_lshl_b64 s[22:23], s[16:17], 20
	s_add_u32 s22, s39, s22
	s_addc_u32 s23, s40, s23
	s_and_b64 s[30:31], s[20:21], exec
	s_cselect_b32 s5, s23, s29
	s_cselect_b32 s9, s22, s28
	s_add_u32 s15, s4, 0x80
	s_addc_u32 s17, s2, 0
	s_add_u32 s52, s28, 0x10000
	v_mov_b32_e32 v2, 0
	s_addc_u32 s53, s29, 0
	v_lshl_add_u64 v[180:181], s[26:27], 0, v[176:177]
	v_lshl_add_u64 v[182:183], s[26:27], 0, v[178:179]
	s_mov_b32 s54, -2
	s_mov_b64 s[28:29], 0
	ds_read_b128 v[184:187], v153
	ds_read_b128 v[188:191], v153 offset:1024
	ds_read_b128 v[192:195], v153 offset:2048
	ds_read_b128 v[196:199], v153 offset:3072
	ds_read_b128 v[200:203], v157
	ds_read_b128 v[204:207], v157 offset:1024
	ds_read_b128 v[208:211], v157 offset:2048
	ds_read_b128 v[212:215], v157 offset:3072
	s_add_u32 s30, s26, s28
	s_addc_u32 s31, s27, s29
	s_add_u32 s36, s30, 0x100
	s_addc_u32 s37, s31, 0
	s_add_u32 s30, s30, 0x180
	s_addc_u32 s31, s31, 0
	s_cmpk_eq_i32 s28, 0xf00
	s_cselect_b32 s31, s17, s31
	s_cselect_b32 s30, s15, s30
	s_cselect_b32 s35, s5, s53
	s_cselect_b32 s34, s9, s52
	s_cselect_b32 s37, s2, s37
	s_cselect_b32 s36, s4, s36
	v_lshl_add_u64 v[248:249], v[180:181], 0, s[28:29]
	s_add_i32 m0, s25, 0xc000
	ds_read_b128 v[216:219], v149
	ds_read_b128 v[220:223], v149 offset:1024
	ds_read_b128 v[224:227], v149 offset:2048
	ds_read_b128 v[228:231], v149 offset:3072
	ds_read_b128 v[232:235], v149 offset:4096
	ds_read_b128 v[236:239], v149 offset:5120
	ds_read_b128 v[240:243], v149 offset:6144
	global_load_lds_dwordx4 v[248:249], off
	v_lshl_add_u64 v[248:249], v[182:183], 0, s[28:29]
	s_add_i32 m0, s25, 0xe000
	ds_read_b128 v[244:247], v149 offset:7168
	global_load_lds_dwordx4 v[248:249], off
	s_waitcnt vmcnt(8) lgkmcnt(0)
	s_barrier
	v_mfma_f32_16x16x32_bf16 v[126:129], v[184:187], v[216:219], 0
	v_mfma_f32_16x16x32_bf16 v[122:125], v[192:195], v[216:219], 0
	v_mfma_f32_16x16x32_bf16 v[110:113], v[184:187], v[224:227], 0
	v_mfma_f32_16x16x32_bf16 v[106:109], v[192:195], v[224:227], 0
	v_mfma_f32_16x16x32_bf16 v[94:97], v[184:187], v[232:235], 0
	v_mfma_f32_16x16x32_bf16 v[90:93], v[192:195], v[232:235], 0
	v_mfma_f32_16x16x32_bf16 v[78:81], v[184:187], v[240:243], 0
	v_mfma_f32_16x16x32_bf16 v[74:77], v[192:195], v[240:243], 0
	v_mfma_f32_16x16x32_bf16 v[126:129], v[188:191], v[220:223], v[126:129]
	v_mfma_f32_16x16x32_bf16 v[122:125], v[196:199], v[220:223], v[122:125]
	v_mfma_f32_16x16x32_bf16 v[110:113], v[188:191], v[228:231], v[110:113]
	v_mfma_f32_16x16x32_bf16 v[106:109], v[196:199], v[228:231], v[106:109]
	v_mfma_f32_16x16x32_bf16 v[94:97], v[188:191], v[236:239], v[94:97]
	v_mfma_f32_16x16x32_bf16 v[90:93], v[196:199], v[236:239], v[90:93]
	v_mfma_f32_16x16x32_bf16 v[78:81], v[188:191], v[244:247], v[78:81]
	v_mfma_f32_16x16x32_bf16 v[74:77], v[196:199], v[244:247], v[74:77]
	v_mfma_f32_16x16x32_bf16 v[118:121], v[200:203], v[216:219], 0
	v_mfma_f32_16x16x32_bf16 v[114:117], v[208:211], v[216:219], 0
	v_mfma_f32_16x16x32_bf16 v[102:105], v[200:203], v[224:227], 0
	v_mfma_f32_16x16x32_bf16 v[98:101], v[208:211], v[224:227], 0
	v_mfma_f32_16x16x32_bf16 v[86:89], v[200:203], v[232:235], 0
	v_mfma_f32_16x16x32_bf16 v[82:85], v[208:211], v[232:235], 0
	v_mfma_f32_16x16x32_bf16 v[70:73], v[200:203], v[240:243], 0
	v_mfma_f32_16x16x32_bf16 v[66:69], v[208:211], v[240:243], 0
	v_mfma_f32_16x16x32_bf16 v[118:121], v[204:207], v[220:223], v[118:121]
	v_mfma_f32_16x16x32_bf16 v[114:117], v[212:215], v[220:223], v[114:117]
	v_mfma_f32_16x16x32_bf16 v[102:105], v[204:207], v[228:231], v[102:105]
	v_mfma_f32_16x16x32_bf16 v[98:101], v[212:215], v[228:231], v[98:101]
	v_mfma_f32_16x16x32_bf16 v[86:89], v[204:207], v[236:239], v[86:89]
	v_mfma_f32_16x16x32_bf16 v[82:85], v[212:215], v[236:239], v[82:85]
	v_mfma_f32_16x16x32_bf16 v[70:73], v[204:207], v[244:247], v[70:73]
	v_mfma_f32_16x16x32_bf16 v[66:69], v[212:215], v[244:247], v[66:69]
	s_barrier
	s_add_i32 s55, s72, s41
	s_mov_b32 m0, s55
	ds_read_b128 v[216:219], v149 offset:16384
	ds_read_b128 v[220:223], v149 offset:17408
	ds_read_b128 v[224:227], v149 offset:18432
	ds_read_b128 v[228:231], v149 offset:19456
	global_load_lds_dwordx4 v132, s[34:35]
	s_add_i32 m0, s55, 0x2000
	s_add_u32 s56, s34, 0x4000
	s_addc_u32 s57, s35, 0
	s_add_i32 s55, s73, s41
	global_load_lds_dwordx4 v136, s[34:35]
	s_mov_b32 m0, s55
	ds_read_b128 v[232:235], v149 offset:20480
	global_load_lds_dwordx4 v132, s[56:57]
	s_add_i32 m0, s55, 0x2000
	ds_read_b128 v[236:239], v149 offset:21504
	global_load_lds_dwordx4 v136, s[56:57]
	s_mov_b32 m0, s25
	ds_read_b128 v[240:243], v149 offset:22528
	global_load_lds_dwordx4 v130, s[36:37]
	s_mov_b32 m0, s42
	ds_read_b128 v[244:247], v149 offset:23552
	global_load_lds_dwordx4 v134, s[36:37]
	s_waitcnt vmcnt(8) lgkmcnt(0)
	s_barrier
; #define PG8_STAGE(bufoff, gbase, voff) do { _Pragma("unroll") for (int _i = 0; _i < 2; ++_i) \
;         __builtin_amdgcn_global_load_lds((const unsigned*)((const char*)(gbase) + (voff)[_i]), (LAS unsigned*)(lds + (bufoff) + ldsw + _i * 8192), 16, 0, 0); } while (0)
; #define PG8_LDA(dst, b, h) do { _Pragma("unroll") for (int m = 0; m < 4; ++m) _Pragma("unroll") for (int k = 0; k < 2; ++k) dst[m][k] = *(const LAS bf16x8*)(lds + PG8_SA(b, h) + aoff + m * 2048 + k * 1024); } while (0)
; #define PG8_LDB(dst, b, h) do { _Pragma("unroll") for (int n = 0; n < 2; ++n) _Pragma("unroll") for (int k = 0; k < 2; ++k) dst[n][k] = *(const LAS bf16x8*)(lds + PG8_SB(b, h) + boff + n * 2048 + k * 1024); } while (0)
; #define PG8_MMA(ai, bj, At, Bt) do { __builtin_amdgcn_s_setprio(1); _Pragma("unroll") for (int m = 0; m < 4; ++m) _Pragma("unroll") for (int n = 0; n < 2; ++n) _Pragma("unroll") for (int k = 0; k < 2; ++k) \
;         acc[ai][bj][m][n] = __builtin_amdgcn_mfma_f32_16x16x32_bf16(Bt[n][k], At[m][k], acc[ai][bj][m][n], 0, 0, 0); __builtin_amdgcn_s_setprio(0); } while (0)
; #define PG8_WAIT_V(n) asm volatile("s_waitcnt vmcnt(" #n ")" ::: "memory")
; #define PG8_WAIT_L(n) asm volatile("s_waitcnt lgkmcnt(" #n ")" ::: "memory")
; #define PG8_BAR __builtin_amdgcn_s_barrier()
; #define PG8_SCHED __builtin_amdgcn_sched_barrier(0)
; template <class Epi, class Sched, bool ABLK = false, bool ALIGN_EPI = true, bool SP2 = true, bool BBLK = true>
; __device__ __forceinline__ void gemm_phase(LAS unsigned char* lds, const Gemm g, const Sched& S, const Epi& E) {
;     ...
;             PG8_WAIT_V(8); PG8_WAIT_L(0); PG8_BAR; PG8_MMA(0, 0, At, B0); PG8_MMA(0, 1, At, B1); PG8_BAR; PG8_SCHED;
;             PG8_LDA(At, 0, 1); PG8_STAGE(PG8_SB(0, 0), b2, voffB); PG8_STAGE(PG8_SB(0, 1), b2 + hstepB, voffB); PG8_STAGE(PG8_SA(0, 0), a2, voffA);
;             PG8_WAIT_V(8); PG8_WAIT_L(0); PG8_BAR; PG8_MMA(1, 0, At, B0); PG8_MMA(1, 1, At, B1); PG8_BAR; PG8_SCHED;
;             PG8_LDB(B0, 1, 0); PG8_LDB(B1, 1, 1); PG8_SCHED; PG8_LDA(At, 1, 0); PG8_STAGE(PG8_SA(0, 1), a2 + hstepA, voffA);
;             PG8_WAIT_V(8); PG8_WAIT_L(0); PG8_BAR; PG8_MMA(0, 0, At, B0); PG8_MMA(0, 1, At, B1); PG8_BAR; PG8_SCHED;
	v_mfma_f32_16x16x32_bf16 v[62:65], v[184:187], v[216:219], 0
	v_mfma_f32_16x16x32_bf16 v[58:61], v[192:195], v[216:219], 0
	v_mfma_f32_16x16x32_bf16 v[46:49], v[184:187], v[224:227], 0
	v_mfma_f32_16x16x32_bf16 v[42:45], v[192:195], v[224:227], 0
	v_mfma_f32_16x16x32_bf16 v[30:33], v[184:187], v[232:235], 0
	v_mfma_f32_16x16x32_bf16 v[26:29], v[192:195], v[232:235], 0
	v_mfma_f32_16x16x32_bf16 v[14:17], v[184:187], v[240:243], 0
	v_mfma_f32_16x16x32_bf16 v[10:13], v[192:195], v[240:243], 0
	v_mfma_f32_16x16x32_bf16 v[62:65], v[188:191], v[220:223], v[62:65]
	v_mfma_f32_16x16x32_bf16 v[58:61], v[196:199], v[220:223], v[58:61]
	v_mfma_f32_16x16x32_bf16 v[46:49], v[188:191], v[228:231], v[46:49]
	v_mfma_f32_16x16x32_bf16 v[42:45], v[196:199], v[228:231], v[42:45]
	v_mfma_f32_16x16x32_bf16 v[30:33], v[188:191], v[236:239], v[30:33]
	v_mfma_f32_16x16x32_bf16 v[26:29], v[196:199], v[236:239], v[26:29]
	v_mfma_f32_16x16x32_bf16 v[14:17], v[188:191], v[244:247], v[14:17]
	v_mfma_f32_16x16x32_bf16 v[10:13], v[196:199], v[244:247], v[10:13]
	v_mfma_f32_16x16x32_bf16 v[54:57], v[200:203], v[216:219], 0
	v_mfma_f32_16x16x32_bf16 v[50:53], v[208:211], v[216:219], 0
	v_mfma_f32_16x16x32_bf16 v[38:41], v[200:203], v[224:227], 0
	v_mfma_f32_16x16x32_bf16 v[34:37], v[208:211], v[224:227], 0
	v_mfma_f32_16x16x32_bf16 v[22:25], v[200:203], v[232:235], 0
	v_mfma_f32_16x16x32_bf16 v[18:21], v[208:211], v[232:235], 0
	v_mfma_f32_16x16x32_bf16 v[6:9], v[200:203], v[240:243], 0
	v_mfma_f32_16x16x32_bf16 v[2:5], v[208:211], v[240:243], 0
	v_mfma_f32_16x16x32_bf16 v[54:57], v[204:207], v[220:223], v[54:57]
	v_mfma_f32_16x16x32_bf16 v[50:53], v[212:215], v[220:223], v[50:53]
	v_mfma_f32_16x16x32_bf16 v[38:41], v[204:207], v[228:231], v[38:41]
	v_mfma_f32_16x16x32_bf16 v[34:37], v[212:215], v[228:231], v[34:37]
	v_mfma_f32_16x16x32_bf16 v[22:25], v[204:207], v[236:239], v[22:25]
	v_mfma_f32_16x16x32_bf16 v[18:21], v[212:215], v[236:239], v[18:21]
	v_mfma_f32_16x16x32_bf16 v[6:9], v[204:207], v[244:247], v[6:9]
	v_mfma_f32_16x16x32_bf16 v[2:5], v[212:215], v[244:247], v[2:5]
	s_barrier
	v_add_u32_e32 v138, s60, v1
	ds_read_b128 v[184:187], v138
	ds_read_b128 v[188:191], v138 offset:1024
	ds_read_b128 v[192:195], v138 offset:2048
	ds_read_b128 v[196:199], v138 offset:3072
	v_add_u32_e32 v138, s61, v1
	ds_read_b128 v[200:203], v138
	ds_read_b128 v[204:207], v138 offset:1024
	ds_read_b128 v[208:211], v138 offset:2048
	ds_read_b128 v[212:215], v138 offset:3072
	s_add_u32 s36, s36, 0x80000
	s_addc_u32 s37, s37, 0
	s_mov_b32 m0, s43
	ds_read_b128 v[216:219], v149 offset:32768
	ds_read_b128 v[220:223], v149 offset:33792
	ds_read_b128 v[224:227], v149 offset:34816
	ds_read_b128 v[228:231], v149 offset:35840
	ds_read_b128 v[232:235], v149 offset:36864
	ds_read_b128 v[236:239], v149 offset:37888
	ds_read_b128 v[240:243], v149 offset:38912
	global_load_lds_dwordx4 v130, s[36:37]
	s_mov_b32 m0, s46
	ds_read_b128 v[244:247], v149 offset:39936
	global_load_lds_dwordx4 v134, s[36:37]
	s_waitcnt vmcnt(8) lgkmcnt(0)
	s_barrier
	v_mfma_f32_16x16x32_bf16 v[126:129], v[184:187], v[216:219], v[126:129]
	v_mfma_f32_16x16x32_bf16 v[122:125], v[192:195], v[216:219], v[122:125]
	v_mfma_f32_16x16x32_bf16 v[110:113], v[184:187], v[224:227], v[110:113]
	v_mfma_f32_16x16x32_bf16 v[106:109], v[192:195], v[224:227], v[106:109]
	v_mfma_f32_16x16x32_bf16 v[94:97], v[184:187], v[232:235], v[94:97]
	v_mfma_f32_16x16x32_bf16 v[90:93], v[192:195], v[232:235], v[90:93]
	v_mfma_f32_16x16x32_bf16 v[78:81], v[184:187], v[240:243], v[78:81]
	v_mfma_f32_16x16x32_bf16 v[74:77], v[192:195], v[240:243], v[74:77]
	v_mfma_f32_16x16x32_bf16 v[126:129], v[188:191], v[220:223], v[126:129]
	v_mfma_f32_16x16x32_bf16 v[122:125], v[196:199], v[220:223], v[122:125]
	v_mfma_f32_16x16x32_bf16 v[110:113], v[188:191], v[228:231], v[110:113]
	v_mfma_f32_16x16x32_bf16 v[106:109], v[196:199], v[228:231], v[106:109]
	v_mfma_f32_16x16x32_bf16 v[94:97], v[188:191], v[236:239], v[94:97]
	v_mfma_f32_16x16x32_bf16 v[90:93], v[196:199], v[236:239], v[90:93]
	v_mfma_f32_16x16x32_bf16 v[78:81], v[188:191], v[244:247], v[78:81]
	v_mfma_f32_16x16x32_bf16 v[74:77], v[196:199], v[244:247], v[74:77]
	v_mfma_f32_16x16x32_bf16 v[118:121], v[200:203], v[216:219], v[118:121]
	v_mfma_f32_16x16x32_bf16 v[114:117], v[208:211], v[216:219], v[114:117]
	v_mfma_f32_16x16x32_bf16 v[102:105], v[200:203], v[224:227], v[102:105]
	v_mfma_f32_16x16x32_bf16 v[98:101], v[208:211], v[224:227], v[98:101]
	v_mfma_f32_16x16x32_bf16 v[86:89], v[200:203], v[232:235], v[86:89]
	v_mfma_f32_16x16x32_bf16 v[82:85], v[208:211], v[232:235], v[82:85]
	v_mfma_f32_16x16x32_bf16 v[70:73], v[200:203], v[240:243], v[70:73]
	v_mfma_f32_16x16x32_bf16 v[66:69], v[208:211], v[240:243], v[66:69]
	v_mfma_f32_16x16x32_bf16 v[118:121], v[204:207], v[220:223], v[118:121]
	v_mfma_f32_16x16x32_bf16 v[114:117], v[212:215], v[220:223], v[114:117]
	v_mfma_f32_16x16x32_bf16 v[102:105], v[204:207], v[228:231], v[102:105]
	v_mfma_f32_16x16x32_bf16 v[98:101], v[212:215], v[228:231], v[98:101]
	v_mfma_f32_16x16x32_bf16 v[86:89], v[204:207], v[236:239], v[86:89]
	v_mfma_f32_16x16x32_bf16 v[82:85], v[212:215], v[236:239], v[82:85]
	v_mfma_f32_16x16x32_bf16 v[70:73], v[204:207], v[244:247], v[70:73]
	v_mfma_f32_16x16x32_bf16 v[66:69], v[212:215], v[244:247], v[66:69]
	s_barrier
; #define PG8_STAGE(bufoff, gbase, voff) do { _Pragma("unroll") for (int _i = 0; _i < 2; ++_i) \
;         __builtin_amdgcn_global_load_lds((const unsigned*)((const char*)(gbase) + (voff)[_i]), (LAS unsigned*)(lds + (bufoff) + ldsw + _i * 8192), 16, 0, 0); } while (0)
; #define PG8_LDA(dst, b, h) do { _Pragma("unroll") for (int m = 0; m < 4; ++m) _Pragma("unroll") for (int k = 0; k < 2; ++k) dst[m][k] = *(const LAS bf16x8*)(lds + PG8_SA(b, h) + aoff + m * 2048 + k * 1024); } while (0)
; #define PG8_LDB(dst, b, h) do { _Pragma("unroll") for (int n = 0; n < 2; ++n) _Pragma("unroll") for (int k = 0; k < 2; ++k) dst[n][k] = *(const LAS bf16x8*)(lds + PG8_SB(b, h) + boff + n * 2048 + k * 1024); } while (0)
; #define PG8_MMA(ai, bj, At, Bt) do { __builtin_amdgcn_s_setprio(1); _Pragma("unroll") for (int m = 0; m < 4; ++m) _Pragma("unroll") for (int n = 0; n < 2; ++n) _Pragma("unroll") for (int k = 0; k < 2; ++k) \
;         acc[ai][bj][m][n] = __builtin_amdgcn_mfma_f32_16x16x32_bf16(Bt[n][k], At[m][k], acc[ai][bj][m][n], 0, 0, 0); __builtin_amdgcn_s_setprio(0); } while (0)
; #define PG8_BAR __builtin_amdgcn_s_barrier()
; template <class Epi, class Sched, bool ABLK = false, bool ALIGN_EPI = true, bool SP2 = true, bool BBLK = true>
; __device__ __forceinline__ void gemm_phase(LAS unsigned char* lds, const Gemm g, const Sched& S, const Epi& E) {
;     ...
;             PG8_LDB(B0, 0, 0); PG8_LDB(B1, 0, 1); PG8_SCHED; PG8_LDA(At, 0, 0); PG8_STAGE(PG8_SA(1, 1), a1 + hstepA, voffA);
;             PG8_WAIT_V(8); PG8_WAIT_L(0); PG8_BAR; PG8_MMA(0, 0, At, B0); PG8_MMA(0, 1, At, B1); PG8_BAR; PG8_SCHED;
;             PG8_LDA(At, 0, 1); PG8_STAGE(PG8_SB(0, 0), b2, voffB); PG8_STAGE(PG8_SB(0, 1), b2 + hstepB, voffB); PG8_STAGE(PG8_SA(0, 0), a2, voffA);
;             PG8_WAIT_V(8); PG8_WAIT_L(0); PG8_BAR; PG8_MMA(1, 0, At, B0); PG8_MMA(1, 1, At, B1); PG8_BAR; PG8_SCHED;
;             PG8_LDB(B0, 1, 0); PG8_LDB(B1, 1, 1); PG8_SCHED; PG8_LDA(At, 1, 0); PG8_STAGE(PG8_SA(0, 1), a2 + hstepA, voffA);
;             PG8_WAIT_V(8); PG8_WAIT_L(0); PG8_BAR; PG8_MMA(0, 0, At, B0); PG8_MMA(0, 1, At, B1); PG8_BAR; PG8_SCHED;
;             PG8_LDA(At, 1, 1); PG8_STAGE(PG8_SB(1, 0), b3, voffB); PG8_STAGE(PG8_SB(1, 1), b3 + hstepB, voffB); PG8_STAGE(PG8_SA(1, 0), a3, voffA);
;             PG8_WAIT_V(8); PG8_WAIT_L(0); PG8_BAR; PG8_MMA(1, 0, At, B0); PG8_MMA(1, 1, At, B1); PG8_BAR; PG8_SCHED;
	s_add_u32 s36, s34, 0x8000
	s_addc_u32 s37, s35, 0
	s_add_i32 s55, s60, s41
	s_mov_b32 m0, s55
	ds_read_b128 v[216:219], v149 offset:49152
	ds_read_b128 v[220:223], v149 offset:50176
	ds_read_b128 v[224:227], v149 offset:51200
	ds_read_b128 v[228:231], v149 offset:52224
	global_load_lds_dwordx4 v132, s[36:37]
	s_add_i32 m0, s55, 0x2000
	s_add_u32 s34, s34, 0xc000
	v_lshl_add_u64 v[248:249], s[36:37], 0, v[136:137]
	s_addc_u32 s35, s35, 0
	s_add_i32 s36, s61, s41
	global_load_lds_dwordx4 v[248:249], off
	s_mov_b32 m0, s36
	ds_read_b128 v[232:235], v149 offset:53248
	global_load_lds_dwordx4 v132, s[34:35]
	s_add_i32 m0, s36, 0x2000
	ds_read_b128 v[236:239], v149 offset:54272
	global_load_lds_dwordx4 v136, s[34:35]
	s_mov_b32 m0, s47
	ds_read_b128 v[240:243], v149 offset:55296
	global_load_lds_dwordx4 v130, s[30:31]
	s_mov_b32 m0, s48
	ds_read_b128 v[244:247], v149 offset:56320
	global_load_lds_dwordx4 v134, s[30:31]
	s_waitcnt vmcnt(8) lgkmcnt(0)
	s_barrier
	v_mfma_f32_16x16x32_bf16 v[62:65], v[184:187], v[216:219], v[62:65]
	v_mfma_f32_16x16x32_bf16 v[58:61], v[192:195], v[216:219], v[58:61]
	v_mfma_f32_16x16x32_bf16 v[46:49], v[184:187], v[224:227], v[46:49]
	v_mfma_f32_16x16x32_bf16 v[42:45], v[192:195], v[224:227], v[42:45]
	v_mfma_f32_16x16x32_bf16 v[30:33], v[184:187], v[232:235], v[30:33]
	v_mfma_f32_16x16x32_bf16 v[26:29], v[192:195], v[232:235], v[26:29]
	v_mfma_f32_16x16x32_bf16 v[14:17], v[184:187], v[240:243], v[14:17]
	v_mfma_f32_16x16x32_bf16 v[10:13], v[192:195], v[240:243], v[10:13]
	v_mfma_f32_16x16x32_bf16 v[62:65], v[188:191], v[220:223], v[62:65]
	v_mfma_f32_16x16x32_bf16 v[58:61], v[196:199], v[220:223], v[58:61]
	v_mfma_f32_16x16x32_bf16 v[46:49], v[188:191], v[228:231], v[46:49]
	v_mfma_f32_16x16x32_bf16 v[42:45], v[196:199], v[228:231], v[42:45]
	v_mfma_f32_16x16x32_bf16 v[30:33], v[188:191], v[236:239], v[30:33]
	v_mfma_f32_16x16x32_bf16 v[26:29], v[196:199], v[236:239], v[26:29]
	v_mfma_f32_16x16x32_bf16 v[14:17], v[188:191], v[244:247], v[14:17]
	v_mfma_f32_16x16x32_bf16 v[10:13], v[196:199], v[244:247], v[10:13]
	v_mfma_f32_16x16x32_bf16 v[54:57], v[200:203], v[216:219], v[54:57]
	v_mfma_f32_16x16x32_bf16 v[50:53], v[208:211], v[216:219], v[50:53]
	v_mfma_f32_16x16x32_bf16 v[38:41], v[200:203], v[224:227], v[38:41]
	v_mfma_f32_16x16x32_bf16 v[34:37], v[208:211], v[224:227], v[34:37]
	v_mfma_f32_16x16x32_bf16 v[22:25], v[200:203], v[232:235], v[22:25]
	v_mfma_f32_16x16x32_bf16 v[18:21], v[208:211], v[232:235], v[18:21]
	v_mfma_f32_16x16x32_bf16 v[6:9], v[200:203], v[240:243], v[6:9]
	v_mfma_f32_16x16x32_bf16 v[2:5], v[208:211], v[240:243], v[2:5]
	v_mfma_f32_16x16x32_bf16 v[54:57], v[204:207], v[220:223], v[54:57]
	v_mfma_f32_16x16x32_bf16 v[50:53], v[212:215], v[220:223], v[50:53]
	v_mfma_f32_16x16x32_bf16 v[38:41], v[204:207], v[228:231], v[38:41]
	v_mfma_f32_16x16x32_bf16 v[34:37], v[212:215], v[228:231], v[34:37]
	v_mfma_f32_16x16x32_bf16 v[22:25], v[204:207], v[236:239], v[22:25]
	v_mfma_f32_16x16x32_bf16 v[18:21], v[212:215], v[236:239], v[18:21]
	v_mfma_f32_16x16x32_bf16 v[6:9], v[204:207], v[244:247], v[6:9]
	v_mfma_f32_16x16x32_bf16 v[2:5], v[212:215], v[244:247], v[2:5]
	s_barrier
	s_add_i32 s54, s54, 2
	s_add_u32 s28, s28, 0x100
	s_addc_u32 s29, s29, 0
	s_add_u32 s52, s52, 0x10000
	s_addc_u32 s53, s53, 0
	s_cmp_gt_u32 s54, 29
.LBB0_668:
	ds_read_b128 v[184:187], v153
	ds_read_b128 v[188:191], v153 offset:1024
	ds_read_b128 v[192:195], v153 offset:2048
	ds_read_b128 v[196:199], v153 offset:3072
	ds_read_b128 v[200:203], v157
	ds_read_b128 v[204:207], v157 offset:1024
	ds_read_b128 v[208:211], v157 offset:2048
	ds_read_b128 v[212:215], v157 offset:3072
	s_add_u32 s30, s26, s28
	s_addc_u32 s31, s27, s29
	s_add_u32 s36, s30, 0x100
	s_addc_u32 s37, s31, 0
	s_add_u32 s30, s30, 0x180
	s_addc_u32 s31, s31, 0
	s_cmpk_eq_i32 s28, 0xf00
	s_cselect_b32 s31, s17, s31
	s_cselect_b32 s30, s15, s30
	s_cselect_b32 s35, s5, s53
	s_cselect_b32 s34, s9, s52
	s_cselect_b32 s37, s2, s37
	s_cselect_b32 s36, s4, s36
	v_lshl_add_u64 v[248:249], v[180:181], 0, s[28:29]
	s_add_i32 m0, s25, 0xc000
	ds_read_b128 v[216:219], v149
	ds_read_b128 v[220:223], v149 offset:1024
	ds_read_b128 v[224:227], v149 offset:2048
	ds_read_b128 v[228:231], v149 offset:3072
	ds_read_b128 v[232:235], v149 offset:4096
	ds_read_b128 v[236:239], v149 offset:5120
	ds_read_b128 v[240:243], v149 offset:6144
	global_load_lds_dwordx4 v[248:249], off
	v_lshl_add_u64 v[248:249], v[182:183], 0, s[28:29]
	s_add_i32 m0, s25, 0xe000
	ds_read_b128 v[244:247], v149 offset:7168
	global_load_lds_dwordx4 v[248:249], off
	s_waitcnt vmcnt(8) lgkmcnt(0)
	s_barrier
; #define PG8_STAGE(bufoff, gbase, voff) do { _Pragma("unroll") for (int _i = 0; _i < 2; ++_i) \
;         __builtin_amdgcn_global_load_lds((const unsigned*)((const char*)(gbase) + (voff)[_i]), (LAS unsigned*)(lds + (bufoff) + ldsw + _i * 8192), 16, 0, 0); } while (0)
; #define PG8_LDA(dst, b, h) do { _Pragma("unroll") for (int m = 0; m < 4; ++m) _Pragma("unroll") for (int k = 0; k < 2; ++k) dst[m][k] = *(const LAS bf16x8*)(lds + PG8_SA(b, h) + aoff + m * 2048 + k * 1024); } while (0)
; #define PG8_LDB(dst, b, h) do { _Pragma("unroll") for (int n = 0; n < 2; ++n) _Pragma("unroll") for (int k = 0; k < 2; ++k) dst[n][k] = *(const LAS bf16x8*)(lds + PG8_SB(b, h) + boff + n * 2048 + k * 1024); } while (0)
; #define PG8_MMA(ai, bj, At, Bt) do { __builtin_amdgcn_s_setprio(1); _Pragma("unroll") for (int m = 0; m < 4; ++m) _Pragma("unroll") for (int n = 0; n < 2; ++n) _Pragma("unroll") for (int k = 0; k < 2; ++k) \
;         acc[ai][bj][m][n] = __builtin_amdgcn_mfma_f32_16x16x32_bf16(Bt[n][k], At[m][k], acc[ai][bj][m][n], 0, 0, 0); __builtin_amdgcn_s_setprio(0); } while (0)
; #define PG8_WAIT_V(n) asm volatile("s_waitcnt vmcnt(" #n ")" ::: "memory")
; #define PG8_WAIT_L(n) asm volatile("s_waitcnt lgkmcnt(" #n ")" ::: "memory")
; #define PG8_BAR __builtin_amdgcn_s_barrier()
; #define PG8_SCHED __builtin_amdgcn_sched_barrier(0)
; template <class Epi, class Sched, bool ABLK = false, bool ALIGN_EPI = true, bool SP2 = true, bool BBLK = true>
; __device__ __forceinline__ void gemm_phase(LAS unsigned char* lds, const Gemm g, const Sched& S, const Epi& E) {
;     ...
;             PG8_WAIT_V(8); PG8_WAIT_L(0); PG8_BAR; PG8_MMA(0, 0, At, B0); PG8_MMA(0, 1, At, B1); PG8_BAR; PG8_SCHED;
;             PG8_LDA(At, 0, 1); PG8_STAGE(PG8_SB(0, 0), b2, voffB); PG8_STAGE(PG8_SB(0, 1), b2 + hstepB, voffB); PG8_STAGE(PG8_SA(0, 0), a2, voffA);
;             PG8_WAIT_V(8); PG8_WAIT_L(0); PG8_BAR; PG8_MMA(1, 0, At, B0); PG8_MMA(1, 1, At, B1); PG8_BAR; PG8_SCHED;
;             PG8_LDB(B0, 1, 0); PG8_LDB(B1, 1, 1); PG8_SCHED; PG8_LDA(At, 1, 0); PG8_STAGE(PG8_SA(0, 1), a2 + hstepA, voffA);
	v_mfma_f32_16x16x32_bf16 v[126:129], v[184:187], v[216:219], v[126:129]
	v_mfma_f32_16x16x32_bf16 v[122:125], v[192:195], v[216:219], v[122:125]
	v_mfma_f32_16x16x32_bf16 v[110:113], v[184:187], v[224:227], v[110:113]
	v_mfma_f32_16x16x32_bf16 v[106:109], v[192:195], v[224:227], v[106:109]
	v_mfma_f32_16x16x32_bf16 v[94:97], v[184:187], v[232:235], v[94:97]
	v_mfma_f32_16x16x32_bf16 v[90:93], v[192:195], v[232:235], v[90:93]
	v_mfma_f32_16x16x32_bf16 v[78:81], v[184:187], v[240:243], v[78:81]
	v_mfma_f32_16x16x32_bf16 v[74:77], v[192:195], v[240:243], v[74:77]
	v_mfma_f32_16x16x32_bf16 v[126:129], v[188:191], v[220:223], v[126:129]
	v_mfma_f32_16x16x32_bf16 v[122:125], v[196:199], v[220:223], v[122:125]
	v_mfma_f32_16x16x32_bf16 v[110:113], v[188:191], v[228:231], v[110:113]
	v_mfma_f32_16x16x32_bf16 v[106:109], v[196:199], v[228:231], v[106:109]
	v_mfma_f32_16x16x32_bf16 v[94:97], v[188:191], v[236:239], v[94:97]
	v_mfma_f32_16x16x32_bf16 v[90:93], v[196:199], v[236:239], v[90:93]
	v_mfma_f32_16x16x32_bf16 v[78:81], v[188:191], v[244:247], v[78:81]
	v_mfma_f32_16x16x32_bf16 v[74:77], v[196:199], v[244:247], v[74:77]
	v_mfma_f32_16x16x32_bf16 v[118:121], v[200:203], v[216:219], v[118:121]
	v_mfma_f32_16x16x32_bf16 v[114:117], v[208:211], v[216:219], v[114:117]
	v_mfma_f32_16x16x32_bf16 v[102:105], v[200:203], v[224:227], v[102:105]
	v_mfma_f32_16x16x32_bf16 v[98:101], v[208:211], v[224:227], v[98:101]
	v_mfma_f32_16x16x32_bf16 v[86:89], v[200:203], v[232:235], v[86:89]
	v_mfma_f32_16x16x32_bf16 v[82:85], v[208:211], v[232:235], v[82:85]
	v_mfma_f32_16x16x32_bf16 v[70:73], v[200:203], v[240:243], v[70:73]
	v_mfma_f32_16x16x32_bf16 v[66:69], v[208:211], v[240:243], v[66:69]
	v_mfma_f32_16x16x32_bf16 v[118:121], v[204:207], v[220:223], v[118:121]
	v_mfma_f32_16x16x32_bf16 v[114:117], v[212:215], v[220:223], v[114:117]
	v_mfma_f32_16x16x32_bf16 v[102:105], v[204:207], v[228:231], v[102:105]
	v_mfma_f32_16x16x32_bf16 v[98:101], v[212:215], v[228:231], v[98:101]
	v_mfma_f32_16x16x32_bf16 v[86:89], v[204:207], v[236:239], v[86:89]
	v_mfma_f32_16x16x32_bf16 v[82:85], v[212:215], v[236:239], v[82:85]
	v_mfma_f32_16x16x32_bf16 v[70:73], v[204:207], v[244:247], v[70:73]
	v_mfma_f32_16x16x32_bf16 v[66:69], v[212:215], v[244:247], v[66:69]
	s_barrier
	s_add_i32 s55, s72, s41
	s_mov_b32 m0, s55
	ds_read_b128 v[216:219], v149 offset:16384
	ds_read_b128 v[220:223], v149 offset:17408
	ds_read_b128 v[224:227], v149 offset:18432
	ds_read_b128 v[228:231], v149 offset:19456
	global_load_lds_dwordx4 v132, s[34:35]
	s_add_i32 m0, s55, 0x2000
	s_add_u32 s56, s34, 0x4000
	s_addc_u32 s57, s35, 0
	s_add_i32 s55, s73, s41
	global_load_lds_dwordx4 v136, s[34:35]
	s_mov_b32 m0, s55
	ds_read_b128 v[232:235], v149 offset:20480
	global_load_lds_dwordx4 v132, s[56:57]
	s_add_i32 m0, s55, 0x2000
	ds_read_b128 v[236:239], v149 offset:21504
	global_load_lds_dwordx4 v136, s[56:57]
	s_mov_b32 m0, s25
	ds_read_b128 v[240:243], v149 offset:22528
	global_load_lds_dwordx4 v130, s[36:37]
	s_mov_b32 m0, s42
	ds_read_b128 v[244:247], v149 offset:23552
	global_load_lds_dwordx4 v134, s[36:37]
	s_waitcnt vmcnt(8) lgkmcnt(0)
	s_barrier
	v_mfma_f32_16x16x32_bf16 v[62:65], v[184:187], v[216:219], v[62:65]
	v_mfma_f32_16x16x32_bf16 v[58:61], v[192:195], v[216:219], v[58:61]
	v_mfma_f32_16x16x32_bf16 v[46:49], v[184:187], v[224:227], v[46:49]
	v_mfma_f32_16x16x32_bf16 v[42:45], v[192:195], v[224:227], v[42:45]
	v_mfma_f32_16x16x32_bf16 v[30:33], v[184:187], v[232:235], v[30:33]
	v_mfma_f32_16x16x32_bf16 v[26:29], v[192:195], v[232:235], v[26:29]
	v_mfma_f32_16x16x32_bf16 v[14:17], v[184:187], v[240:243], v[14:17]
	v_mfma_f32_16x16x32_bf16 v[10:13], v[192:195], v[240:243], v[10:13]
	v_mfma_f32_16x16x32_bf16 v[62:65], v[188:191], v[220:223], v[62:65]
	v_mfma_f32_16x16x32_bf16 v[58:61], v[196:199], v[220:223], v[58:61]
	v_mfma_f32_16x16x32_bf16 v[46:49], v[188:191], v[228:231], v[46:49]
	v_mfma_f32_16x16x32_bf16 v[42:45], v[196:199], v[228:231], v[42:45]
	v_mfma_f32_16x16x32_bf16 v[30:33], v[188:191], v[236:239], v[30:33]
	v_mfma_f32_16x16x32_bf16 v[26:29], v[196:199], v[236:239], v[26:29]
	v_mfma_f32_16x16x32_bf16 v[14:17], v[188:191], v[244:247], v[14:17]
	v_mfma_f32_16x16x32_bf16 v[10:13], v[196:199], v[244:247], v[10:13]
	v_mfma_f32_16x16x32_bf16 v[54:57], v[200:203], v[216:219], v[54:57]
	v_mfma_f32_16x16x32_bf16 v[50:53], v[208:211], v[216:219], v[50:53]
	v_mfma_f32_16x16x32_bf16 v[38:41], v[200:203], v[224:227], v[38:41]
	v_mfma_f32_16x16x32_bf16 v[34:37], v[208:211], v[224:227], v[34:37]
	v_mfma_f32_16x16x32_bf16 v[22:25], v[200:203], v[232:235], v[22:25]
	v_mfma_f32_16x16x32_bf16 v[18:21], v[208:211], v[232:235], v[18:21]
	v_mfma_f32_16x16x32_bf16 v[6:9], v[200:203], v[240:243], v[6:9]
	v_mfma_f32_16x16x32_bf16 v[2:5], v[208:211], v[240:243], v[2:5]
	v_mfma_f32_16x16x32_bf16 v[54:57], v[204:207], v[220:223], v[54:57]
	v_mfma_f32_16x16x32_bf16 v[50:53], v[212:215], v[220:223], v[50:53]
	v_mfma_f32_16x16x32_bf16 v[38:41], v[204:207], v[228:231], v[38:41]
	v_mfma_f32_16x16x32_bf16 v[34:37], v[212:215], v[228:231], v[34:37]
	v_mfma_f32_16x16x32_bf16 v[22:25], v[204:207], v[236:239], v[22:25]
	v_mfma_f32_16x16x32_bf16 v[18:21], v[212:215], v[236:239], v[18:21]
	v_mfma_f32_16x16x32_bf16 v[6:9], v[204:207], v[244:247], v[6:9]
	v_mfma_f32_16x16x32_bf16 v[2:5], v[212:215], v[244:247], v[2:5]
	s_barrier
; #define PG8_STAGE(bufoff, gbase, voff) do { _Pragma("unroll") for (int _i = 0; _i < 2; ++_i) \
;         __builtin_amdgcn_global_load_lds((const unsigned*)((const char*)(gbase) + (voff)[_i]), (LAS unsigned*)(lds + (bufoff) + ldsw + _i * 8192), 16, 0, 0); } while (0)
; #define PG8_LDA(dst, b, h) do { _Pragma("unroll") for (int m = 0; m < 4; ++m) _Pragma("unroll") for (int k = 0; k < 2; ++k) dst[m][k] = *(const LAS bf16x8*)(lds + PG8_SA(b, h) + aoff + m * 2048 + k * 1024); } while (0)
; #define PG8_LDB(dst, b, h) do { _Pragma("unroll") for (int n = 0; n < 2; ++n) _Pragma("unroll") for (int k = 0; k < 2; ++k) dst[n][k] = *(const LAS bf16x8*)(lds + PG8_SB(b, h) + boff + n * 2048 + k * 1024); } while (0)
; #define PG8_MMA(ai, bj, At, Bt) do { __builtin_amdgcn_s_setprio(1); _Pragma("unroll") for (int m = 0; m < 4; ++m) _Pragma("unroll") for (int n = 0; n < 2; ++n) _Pragma("unroll") for (int k = 0; k < 2; ++k) \
;         acc[ai][bj][m][n] = __builtin_amdgcn_mfma_f32_16x16x32_bf16(Bt[n][k], At[m][k], acc[ai][bj][m][n], 0, 0, 0); __builtin_amdgcn_s_setprio(0); } while (0)
; #define PG8_WAIT_V(n) asm volatile("s_waitcnt vmcnt(" #n ")" ::: "memory")
; #define PG8_WAIT_L(n) asm volatile("s_waitcnt lgkmcnt(" #n ")" ::: "memory")
; #define PG8_BAR __builtin_amdgcn_s_barrier()
; #define PG8_SCHED __builtin_amdgcn_sched_barrier(0)
; template <class Epi, class Sched, bool ABLK = false, bool ALIGN_EPI = true, bool SP2 = true, bool BBLK = true>
; __device__ __forceinline__ void gemm_phase(LAS unsigned char* lds, const Gemm g, const Sched& S, const Epi& E) {
;     ...
;             PG8_LDB(B0, 1, 0); PG8_LDB(B1, 1, 1); PG8_SCHED; PG8_LDA(At, 1, 0); PG8_STAGE(PG8_SA(0, 1), a2 + hstepA, voffA);
;             PG8_WAIT_V(8); PG8_WAIT_L(0); PG8_BAR; PG8_MMA(0, 0, At, B0); PG8_MMA(0, 1, At, B1); PG8_BAR; PG8_SCHED;
;             PG8_LDA(At, 1, 1); PG8_STAGE(PG8_SB(1, 0), b3, voffB); PG8_STAGE(PG8_SB(1, 1), b3 + hstepB, voffB); PG8_STAGE(PG8_SA(1, 0), a3, voffA);
;             PG8_WAIT_V(8); PG8_WAIT_L(0); PG8_BAR; PG8_MMA(1, 0, At, B0); PG8_MMA(1, 1, At, B1); PG8_BAR; PG8_SCHED;
;     ...
;         if constexpr (ALIGN_EPI) { if (wr == 0) PG8_BAR; }
	v_add_u32_e32 v138, s60, v1
	ds_read_b128 v[184:187], v138
	ds_read_b128 v[188:191], v138 offset:1024
	ds_read_b128 v[192:195], v138 offset:2048
	ds_read_b128 v[196:199], v138 offset:3072
	v_add_u32_e32 v138, s61, v1
	ds_read_b128 v[200:203], v138
	ds_read_b128 v[204:207], v138 offset:1024
	ds_read_b128 v[208:211], v138 offset:2048
	ds_read_b128 v[212:215], v138 offset:3072
	s_add_u32 s36, s36, 0x80000
	s_addc_u32 s37, s37, 0
	s_mov_b32 m0, s43
	ds_read_b128 v[216:219], v149 offset:32768
	ds_read_b128 v[220:223], v149 offset:33792
	ds_read_b128 v[224:227], v149 offset:34816
	ds_read_b128 v[228:231], v149 offset:35840
	ds_read_b128 v[232:235], v149 offset:36864
	ds_read_b128 v[236:239], v149 offset:37888
	ds_read_b128 v[240:243], v149 offset:38912
	global_load_lds_dwordx4 v130, s[36:37]
	s_mov_b32 m0, s46
	ds_read_b128 v[244:247], v149 offset:39936
	global_load_lds_dwordx4 v134, s[36:37]
	s_waitcnt vmcnt(8) lgkmcnt(0)
	s_barrier
	v_mfma_f32_16x16x32_bf16 v[126:129], v[184:187], v[216:219], v[126:129]
	v_mfma_f32_16x16x32_bf16 v[122:125], v[192:195], v[216:219], v[122:125]
	v_mfma_f32_16x16x32_bf16 v[110:113], v[184:187], v[224:227], v[110:113]
	v_mfma_f32_16x16x32_bf16 v[106:109], v[192:195], v[224:227], v[106:109]
	v_mfma_f32_16x16x32_bf16 v[94:97], v[184:187], v[232:235], v[94:97]
	v_mfma_f32_16x16x32_bf16 v[90:93], v[192:195], v[232:235], v[90:93]
	v_mfma_f32_16x16x32_bf16 v[78:81], v[184:187], v[240:243], v[78:81]
	v_mfma_f32_16x16x32_bf16 v[74:77], v[192:195], v[240:243], v[74:77]
	v_mfma_f32_16x16x32_bf16 v[126:129], v[188:191], v[220:223], v[126:129]
	v_mfma_f32_16x16x32_bf16 v[122:125], v[196:199], v[220:223], v[122:125]
	v_mfma_f32_16x16x32_bf16 v[110:113], v[188:191], v[228:231], v[110:113]
	v_mfma_f32_16x16x32_bf16 v[106:109], v[196:199], v[228:231], v[106:109]
	v_mfma_f32_16x16x32_bf16 v[94:97], v[188:191], v[236:239], v[94:97]
	v_mfma_f32_16x16x32_bf16 v[90:93], v[196:199], v[236:239], v[90:93]
	v_mfma_f32_16x16x32_bf16 v[78:81], v[188:191], v[244:247], v[78:81]
	v_mfma_f32_16x16x32_bf16 v[74:77], v[196:199], v[244:247], v[74:77]
	v_mfma_f32_16x16x32_bf16 v[118:121], v[200:203], v[216:219], v[118:121]
	v_mfma_f32_16x16x32_bf16 v[114:117], v[208:211], v[216:219], v[114:117]
	v_mfma_f32_16x16x32_bf16 v[102:105], v[200:203], v[224:227], v[102:105]
	v_mfma_f32_16x16x32_bf16 v[98:101], v[208:211], v[224:227], v[98:101]
	v_mfma_f32_16x16x32_bf16 v[86:89], v[200:203], v[232:235], v[86:89]
	v_mfma_f32_16x16x32_bf16 v[82:85], v[208:211], v[232:235], v[82:85]
	v_mfma_f32_16x16x32_bf16 v[70:73], v[200:203], v[240:243], v[70:73]
	v_mfma_f32_16x16x32_bf16 v[66:69], v[208:211], v[240:243], v[66:69]
	v_mfma_f32_16x16x32_bf16 v[118:121], v[204:207], v[220:223], v[118:121]
	v_mfma_f32_16x16x32_bf16 v[114:117], v[212:215], v[220:223], v[114:117]
	v_mfma_f32_16x16x32_bf16 v[102:105], v[204:207], v[228:231], v[102:105]
	v_mfma_f32_16x16x32_bf16 v[98:101], v[212:215], v[228:231], v[98:101]
	v_mfma_f32_16x16x32_bf16 v[86:89], v[204:207], v[236:239], v[86:89]
	v_mfma_f32_16x16x32_bf16 v[82:85], v[212:215], v[236:239], v[82:85]
	v_mfma_f32_16x16x32_bf16 v[70:73], v[204:207], v[244:247], v[70:73]
	v_mfma_f32_16x16x32_bf16 v[66:69], v[212:215], v[244:247], v[66:69]
	s_barrier
	s_add_u32 s36, s34, 0x8000
	s_addc_u32 s37, s35, 0
	s_add_i32 s55, s60, s41
	s_mov_b32 m0, s55
	ds_read_b128 v[216:219], v149 offset:49152
	ds_read_b128 v[220:223], v149 offset:50176
	ds_read_b128 v[224:227], v149 offset:51200
	ds_read_b128 v[228:231], v149 offset:52224
	global_load_lds_dwordx4 v132, s[36:37]
	s_add_i32 m0, s55, 0x2000
	s_add_u32 s34, s34, 0xc000
	v_lshl_add_u64 v[248:249], s[36:37], 0, v[136:137]
	s_addc_u32 s35, s35, 0
	s_add_i32 s36, s61, s41
	global_load_lds_dwordx4 v[248:249], off
	s_mov_b32 m0, s36
	ds_read_b128 v[232:235], v149 offset:53248
	global_load_lds_dwordx4 v132, s[34:35]
	s_add_i32 m0, s36, 0x2000
	ds_read_b128 v[236:239], v149 offset:54272
	global_load_lds_dwordx4 v136, s[34:35]
	s_mov_b32 m0, s47
	ds_read_b128 v[240:243], v149 offset:55296
	global_load_lds_dwordx4 v130, s[30:31]
	s_mov_b32 m0, s48
	ds_read_b128 v[244:247], v149 offset:56320
	global_load_lds_dwordx4 v134, s[30:31]
	s_waitcnt vmcnt(8) lgkmcnt(0)
	s_barrier
	v_mfma_f32_16x16x32_bf16 v[62:65], v[184:187], v[216:219], v[62:65]
	v_mfma_f32_16x16x32_bf16 v[58:61], v[192:195], v[216:219], v[58:61]
	v_mfma_f32_16x16x32_bf16 v[46:49], v[184:187], v[224:227], v[46:49]
	v_mfma_f32_16x16x32_bf16 v[42:45], v[192:195], v[224:227], v[42:45]
	v_mfma_f32_16x16x32_bf16 v[30:33], v[184:187], v[232:235], v[30:33]
	v_mfma_f32_16x16x32_bf16 v[26:29], v[192:195], v[232:235], v[26:29]
	v_mfma_f32_16x16x32_bf16 v[14:17], v[184:187], v[240:243], v[14:17]
	v_mfma_f32_16x16x32_bf16 v[10:13], v[192:195], v[240:243], v[10:13]
	v_mfma_f32_16x16x32_bf16 v[62:65], v[188:191], v[220:223], v[62:65]
	v_mfma_f32_16x16x32_bf16 v[58:61], v[196:199], v[220:223], v[58:61]
	v_mfma_f32_16x16x32_bf16 v[46:49], v[188:191], v[228:231], v[46:49]
	v_mfma_f32_16x16x32_bf16 v[42:45], v[196:199], v[228:231], v[42:45]
	v_mfma_f32_16x16x32_bf16 v[30:33], v[188:191], v[236:239], v[30:33]
	v_mfma_f32_16x16x32_bf16 v[26:29], v[196:199], v[236:239], v[26:29]
	v_mfma_f32_16x16x32_bf16 v[14:17], v[188:191], v[244:247], v[14:17]
	v_mfma_f32_16x16x32_bf16 v[10:13], v[196:199], v[244:247], v[10:13]
	v_mfma_f32_16x16x32_bf16 v[54:57], v[200:203], v[216:219], v[54:57]
	v_mfma_f32_16x16x32_bf16 v[50:53], v[208:211], v[216:219], v[50:53]
	v_mfma_f32_16x16x32_bf16 v[38:41], v[200:203], v[224:227], v[38:41]
	v_mfma_f32_16x16x32_bf16 v[34:37], v[208:211], v[224:227], v[34:37]
	v_mfma_f32_16x16x32_bf16 v[22:25], v[200:203], v[232:235], v[22:25]
	v_mfma_f32_16x16x32_bf16 v[18:21], v[208:211], v[232:235], v[18:21]
	v_mfma_f32_16x16x32_bf16 v[6:9], v[200:203], v[240:243], v[6:9]
	v_mfma_f32_16x16x32_bf16 v[2:5], v[208:211], v[240:243], v[2:5]
	v_mfma_f32_16x16x32_bf16 v[54:57], v[204:207], v[220:223], v[54:57]
	v_mfma_f32_16x16x32_bf16 v[50:53], v[212:215], v[220:223], v[50:53]
	v_mfma_f32_16x16x32_bf16 v[38:41], v[204:207], v[228:231], v[38:41]
	v_mfma_f32_16x16x32_bf16 v[34:37], v[212:215], v[228:231], v[34:37]
	v_mfma_f32_16x16x32_bf16 v[22:25], v[204:207], v[236:239], v[22:25]
	v_mfma_f32_16x16x32_bf16 v[18:21], v[212:215], v[236:239], v[18:21]
	v_mfma_f32_16x16x32_bf16 v[6:9], v[204:207], v[244:247], v[6:9]
	v_mfma_f32_16x16x32_bf16 v[2:5], v[212:215], v[244:247], v[2:5]
	s_barrier
	s_add_i32 s54, s54, 2
	s_add_u32 s28, s28, 0x100
	s_addc_u32 s29, s29, 0
	s_add_u32 s52, s52, 0x10000
	s_addc_u32 s53, s53, 0
	s_cmp_gt_u32 s54, 29
	s_cbranch_scc0 .LBB0_668
	s_and_b64 vcc, exec, s[12:13]
	s_cbranch_vccz .LBB0_671
	s_barrier

; #define PG8_STAGE(bufoff, gbase, voff) do { _Pragma("unroll") for (int _i = 0; _i < 2; ++_i) \
;         __builtin_amdgcn_global_load_lds((const unsigned*)((const char*)(gbase) + (voff)[_i]), (LAS unsigned*)(lds + (bufoff) + ldsw + _i * 8192), 16, 0, 0); } while (0)
; #define PG8_LDA(dst, b, h) do { _Pragma("unroll") for (int m = 0; m < 4; ++m) _Pragma("unroll") for (int k = 0; k < 2; ++k) dst[m][k] = *(const LAS bf16x8*)(lds + PG8_SA(b, h) + aoff + m * 2048 + k * 1024); } while (0)
; #define PG8_LDB(dst, b, h) do { _Pragma("unroll") for (int n = 0; n < 2; ++n) _Pragma("unroll") for (int k = 0; k < 2; ++k) dst[n][k] = *(const LAS bf16x8*)(lds + PG8_SB(b, h) + boff + n * 2048 + k * 1024); } while (0)
; #define PG8_WAIT_V(n) asm volatile("s_waitcnt vmcnt(" #n ")" ::: "memory")
; #define PG8_WAIT_L(n) asm volatile("s_waitcnt lgkmcnt(" #n ")" ::: "memory")
; template <class Epi, class Sched, bool ABLK = false, bool ALIGN_EPI = true, bool SP2 = true, bool BBLK = true>
; __device__ __forceinline__ void gemm_phase(LAS unsigned char* lds, const Gemm g, const Sched& S, const Epi& E) {
;     ...
;         const bool has_next = S.next(ui + 1, nxt);
;         const int nt = cur.nt;
;         const char* nuA = has_next ? a_unit(nxt) : uA; const int ntbA = has_next ? nxt.k0 / BK : tbA; const char* nB = has_next ? (const char*)g.Bt + (size_t)nxt.pn * tstepB + b_k0(nxt.k0) : cB;
;         for (int t = 0; t < nt; t += 2) {
;             const bool last = (t == nt - 2);
;             const char* a1 = a_tile(uA, tbA + t + 1);
;             const char* a2 = last ? a_tile(nuA, ntbA) : a_tile(uA, tbA + t + 2); const char* b2 = last ? nB : cB + (size_t)(t + 2) * kstepB;
;             const char* a3 = last ? a_tile(nuA, ntbA + 1) : a_tile(uA, tbA + t + 3); const char* b3 = b2 + kstepB;
;             if (last && has_next) S.a_ready(nxt);
;             if constexpr (SP2) {
;             PG8_LDB(B0, 0, 0); PG8_LDB(B1, 0, 1); PG8_SCHED; PG8_LDA(At, 0, 0); PG8_STAGE(PG8_SA(1, 1), a1 + hstepA, voffA);
;             PG8_WAIT_V(8); PG8_WAIT_L(0); PG8_BAR; PG8_MMA(0, 0, At, B0); PG8_MMA(0, 1, At, B1); PG8_BAR; PG8_SCHED;
;             PG8_LDA(At, 0, 1); PG8_STAGE(PG8_SB(0, 0), b2, voffB); PG8_STAGE(PG8_SB(0, 1), b2 + hstepB, voffB); PG8_STAGE(PG8_SA(0, 0), a2, voffA);
;             PG8_WAIT_V(8); PG8_WAIT_L(0); PG8_BAR; PG8_MMA(1, 0, At, B0); PG8_MMA(1, 1, At, B1); PG8_BAR; PG8_SCHED;
.LBB0_1037:
	s_ashr_i32 s81, s80, 31
	s_andn2_b64 vcc, exec, s[4:5]
	s_lshl_b64 s[14:15], s[80:81], 20
	s_add_u32 s14, s28, s14
	s_addc_u32 s15, s29, s15
	s_and_b64 s[16:17], s[4:5], exec
	s_cselect_b32 s25, s15, s23
	s_cselect_b32 s48, s14, s22
	s_ashr_i32 s16, s63, 31
	s_lshr_b32 s16, s16, 26
	s_add_i32 s16, s63, s16
	s_ashr_i32 s16, s16, 6
	s_and_b64 s[18:19], s[4:5], exec
	s_cselect_b32 s26, s16, s24
	s_ashr_i32 s79, s78, 31
	s_lshl_b64 s[18:19], s[78:79], 20
	s_add_u32 s27, s30, s18
	s_addc_u32 s49, s31, s19
	s_ashr_i32 s17, s16, 31
	s_lshl_b64 s[18:19], s[16:17], 15
	s_add_u32 s18, s27, s18
	s_addc_u32 s19, s49, s19
	v_cndmask_b32_e64 v2, 0, 1, s[4:5]
	s_and_b64 s[4:5], s[4:5], exec
	s_cselect_b32 s4, s19, s21
	s_cselect_b32 s5, s18, s20
	s_ashr_i32 s27, s26, 31
	s_lshl_b64 s[26:27], s[26:27], 7
	s_add_u32 s17, s48, s26
	s_addc_u32 s48, s25, s27
	s_add_u32 s49, s17, 0x80
	s_addc_u32 s50, s48, 0
	s_add_u32 s51, s20, 0x10000
	s_addc_u32 s55, s21, 0
	s_ashr_i32 s25, s24, 31
	v_cmp_ne_u32_e64 s[8:9], 1, v2
	s_lshl_b64 s[20:21], s[24:25], 7
	v_lshl_add_u64 v[2:3], s[22:23], 0, v[142:143]
	s_add_u32 s56, s22, s20
	v_lshl_add_u64 v[146:147], v[2:3], 0, s[20:21]
	v_lshl_add_u64 v[2:3], s[22:23], 0, v[144:145]
	s_addc_u32 s57, s23, s21
	v_lshl_add_u64 v[148:149], v[2:3], 0, s[20:21]
	s_lshl_b32 s20, s46, 7
	s_addk_i32 s20, 0xfc00
	v_mov_b32_e32 v2, 0
	s_add_u32 s64, s20, 0x300
	s_mov_b32 s65, 0
	s_mov_b64 s[20:21], 0
	ds_read_b128 v[156:159], v153
	ds_read_b128 v[160:163], v153 offset:1024
	ds_read_b128 v[164:167], v153 offset:2048
	ds_read_b128 v[168:171], v153 offset:3072
	ds_read_b128 v[172:175], v154
	ds_read_b128 v[176:179], v154 offset:1024
	ds_read_b128 v[180:183], v154 offset:2048
	ds_read_b128 v[184:187], v154 offset:3072
	s_add_u32 s22, s56, s20
	s_addc_u32 s23, s57, s21
	s_add_u32 s26, s22, 0x100
	s_addc_u32 s27, s23, 0
	s_add_i32 s65, s65, 2
	s_add_u32 s22, s22, 0x180
	s_addc_u32 s23, s23, 0
	s_cmp_eq_u32 s64, s20
	s_cselect_b32 s23, s50, s23
	s_cselect_b32 s22, s49, s22
	s_cselect_b32 s25, s4, s55
	s_cselect_b32 s24, s5, s51
	s_cselect_b32 s27, s48, s27
	s_cselect_b32 s26, s17, s26
	v_lshl_add_u64 v[220:221], v[146:147], 0, s[20:21]
	s_add_i32 m0, s35, 0xc000
	ds_read_b128 v[188:191], v155
	ds_read_b128 v[192:195], v155 offset:1024
	ds_read_b128 v[196:199], v155 offset:2048
	ds_read_b128 v[200:203], v155 offset:3072
	ds_read_b128 v[204:207], v155 offset:4096
	ds_read_b128 v[208:211], v155 offset:5120
	ds_read_b128 v[212:215], v155 offset:6144
	global_load_lds_dwordx4 v[220:221], off
	v_lshl_add_u64 v[220:221], v[148:149], 0, s[20:21]
	s_add_i32 m0, s35, 0xe000
	ds_read_b128 v[216:219], v155 offset:7168
	global_load_lds_dwordx4 v[220:221], off
	s_waitcnt vmcnt(8) lgkmcnt(0)
	s_barrier
	v_mfma_f32_16x16x32_bf16 v[126:129], v[156:159], v[188:191], 0
	v_mfma_f32_16x16x32_bf16 v[122:125], v[164:167], v[188:191], 0
	v_mfma_f32_16x16x32_bf16 v[110:113], v[156:159], v[196:199], 0
	v_mfma_f32_16x16x32_bf16 v[106:109], v[164:167], v[196:199], 0
	v_mfma_f32_16x16x32_bf16 v[94:97], v[156:159], v[204:207], 0
	v_mfma_f32_16x16x32_bf16 v[90:93], v[164:167], v[204:207], 0
	v_mfma_f32_16x16x32_bf16 v[78:81], v[156:159], v[212:215], 0
	v_mfma_f32_16x16x32_bf16 v[74:77], v[164:167], v[212:215], 0
	v_mfma_f32_16x16x32_bf16 v[126:129], v[160:163], v[192:195], v[126:129]
	v_mfma_f32_16x16x32_bf16 v[122:125], v[168:171], v[192:195], v[122:125]
	v_mfma_f32_16x16x32_bf16 v[110:113], v[160:163], v[200:203], v[110:113]
	v_mfma_f32_16x16x32_bf16 v[106:109], v[168:171], v[200:203], v[106:109]
	v_mfma_f32_16x16x32_bf16 v[94:97], v[160:163], v[208:211], v[94:97]
	v_mfma_f32_16x16x32_bf16 v[90:93], v[168:171], v[208:211], v[90:93]
	v_mfma_f32_16x16x32_bf16 v[78:81], v[160:163], v[216:219], v[78:81]
	v_mfma_f32_16x16x32_bf16 v[74:77], v[168:171], v[216:219], v[74:77]
	v_mfma_f32_16x16x32_bf16 v[118:121], v[172:175], v[188:191], 0
	v_mfma_f32_16x16x32_bf16 v[114:117], v[180:183], v[188:191], 0
	v_mfma_f32_16x16x32_bf16 v[102:105], v[172:175], v[196:199], 0
	v_mfma_f32_16x16x32_bf16 v[98:101], v[180:183], v[196:199], 0
	v_mfma_f32_16x16x32_bf16 v[86:89], v[172:175], v[204:207], 0
	v_mfma_f32_16x16x32_bf16 v[82:85], v[180:183], v[204:207], 0
	v_mfma_f32_16x16x32_bf16 v[70:73], v[172:175], v[212:215], 0
	v_mfma_f32_16x16x32_bf16 v[66:69], v[180:183], v[212:215], 0
	v_mfma_f32_16x16x32_bf16 v[118:121], v[176:179], v[192:195], v[118:121]
	v_mfma_f32_16x16x32_bf16 v[114:117], v[184:187], v[192:195], v[114:117]
	v_mfma_f32_16x16x32_bf16 v[102:105], v[176:179], v[200:203], v[102:105]
	v_mfma_f32_16x16x32_bf16 v[98:101], v[184:187], v[200:203], v[98:101]
	v_mfma_f32_16x16x32_bf16 v[86:89], v[176:179], v[208:211], v[86:89]
	v_mfma_f32_16x16x32_bf16 v[82:85], v[184:187], v[208:211], v[82:85]
	v_mfma_f32_16x16x32_bf16 v[70:73], v[176:179], v[216:219], v[70:73]
	v_mfma_f32_16x16x32_bf16 v[66:69], v[184:187], v[216:219], v[66:69]
	s_barrier
	s_add_i32 s66, s72, s34
	s_mov_b32 m0, s66
	ds_read_b128 v[188:191], v155 offset:16384
	ds_read_b128 v[192:195], v155 offset:17408
	ds_read_b128 v[196:199], v155 offset:18432
	ds_read_b128 v[200:203], v155 offset:19456
	global_load_lds_dwordx4 v132, s[24:25]
	s_add_i32 m0, s66, 0x2000
	s_add_u32 s66, s24, 0x4000
	s_addc_u32 s67, s25, 0
	s_add_i32 s75, s73, s34
	global_load_lds_dwordx4 v136, s[24:25]
	s_mov_b32 m0, s75
	ds_read_b128 v[204:207], v155 offset:20480
	global_load_lds_dwordx4 v132, s[66:67]
	s_add_i32 m0, s75, 0x2000
	ds_read_b128 v[208:211], v155 offset:21504
	global_load_lds_dwordx4 v136, s[66:67]
	s_mov_b32 m0, s35
	ds_read_b128 v[212:215], v155 offset:22528
	global_load_lds_dwordx4 v130, s[26:27]
	s_mov_b32 m0, s36
	ds_read_b128 v[216:219], v155 offset:23552
	global_load_lds_dwordx4 v134, s[26:27]
	s_waitcnt vmcnt(8) lgkmcnt(0)
	s_barrier
; #define PG8_STAGE(bufoff, gbase, voff) do { _Pragma("unroll") for (int _i = 0; _i < 2; ++_i) \
;         __builtin_amdgcn_global_load_lds((const unsigned*)((const char*)(gbase) + (voff)[_i]), (LAS unsigned*)(lds + (bufoff) + ldsw + _i * 8192), 16, 0, 0); } while (0)
; #define PG8_LDA(dst, b, h) do { _Pragma("unroll") for (int m = 0; m < 4; ++m) _Pragma("unroll") for (int k = 0; k < 2; ++k) dst[m][k] = *(const LAS bf16x8*)(lds + PG8_SA(b, h) + aoff + m * 2048 + k * 1024); } while (0)
; #define PG8_LDB(dst, b, h) do { _Pragma("unroll") for (int n = 0; n < 2; ++n) _Pragma("unroll") for (int k = 0; k < 2; ++k) dst[n][k] = *(const LAS bf16x8*)(lds + PG8_SB(b, h) + boff + n * 2048 + k * 1024); } while (0)
; #define PG8_MMA(ai, bj, At, Bt) do { __builtin_amdgcn_s_setprio(1); _Pragma("unroll") for (int m = 0; m < 4; ++m) _Pragma("unroll") for (int n = 0; n < 2; ++n) _Pragma("unroll") for (int k = 0; k < 2; ++k) \
;         acc[ai][bj][m][n] = __builtin_amdgcn_mfma_f32_16x16x32_bf16(Bt[n][k], At[m][k], acc[ai][bj][m][n], 0, 0, 0); __builtin_amdgcn_s_setprio(0); } while (0)
; #define PG8_WAIT_V(n) asm volatile("s_waitcnt vmcnt(" #n ")" ::: "memory")
; #define PG8_WAIT_L(n) asm volatile("s_waitcnt lgkmcnt(" #n ")" ::: "memory")
; #define PG8_BAR __builtin_amdgcn_s_barrier()
; #define PG8_SCHED __builtin_amdgcn_sched_barrier(0)
; template <class Epi, class Sched, bool ABLK = false, bool ALIGN_EPI = true, bool SP2 = true, bool BBLK = true>
; __device__ __forceinline__ void gemm_phase(LAS unsigned char* lds, const Gemm g, const Sched& S, const Epi& E) {
;     ...
;             PG8_WAIT_V(8); PG8_WAIT_L(0); PG8_BAR; PG8_MMA(0, 0, At, B0); PG8_MMA(0, 1, At, B1); PG8_BAR; PG8_SCHED;
;             PG8_LDA(At, 0, 1); PG8_STAGE(PG8_SB(0, 0), b2, voffB); PG8_STAGE(PG8_SB(0, 1), b2 + hstepB, voffB); PG8_STAGE(PG8_SA(0, 0), a2, voffA);
;             PG8_WAIT_V(8); PG8_WAIT_L(0); PG8_BAR; PG8_MMA(1, 0, At, B0); PG8_MMA(1, 1, At, B1); PG8_BAR; PG8_SCHED;
;             PG8_LDB(B0, 1, 0); PG8_LDB(B1, 1, 1); PG8_SCHED; PG8_LDA(At, 1, 0); PG8_STAGE(PG8_SA(0, 1), a2 + hstepA, voffA);
;             PG8_WAIT_V(8); PG8_WAIT_L(0); PG8_BAR; PG8_MMA(0, 0, At, B0); PG8_MMA(0, 1, At, B1); PG8_BAR; PG8_SCHED;
	v_mfma_f32_16x16x32_bf16 v[62:65], v[156:159], v[188:191], 0
	v_mfma_f32_16x16x32_bf16 v[58:61], v[164:167], v[188:191], 0
	v_mfma_f32_16x16x32_bf16 v[46:49], v[156:159], v[196:199], 0
	v_mfma_f32_16x16x32_bf16 v[42:45], v[164:167], v[196:199], 0
	v_mfma_f32_16x16x32_bf16 v[30:33], v[156:159], v[204:207], 0
	v_mfma_f32_16x16x32_bf16 v[26:29], v[164:167], v[204:207], 0
	v_mfma_f32_16x16x32_bf16 v[14:17], v[156:159], v[212:215], 0
	v_mfma_f32_16x16x32_bf16 v[10:13], v[164:167], v[212:215], 0
	v_mfma_f32_16x16x32_bf16 v[62:65], v[160:163], v[192:195], v[62:65]
	v_mfma_f32_16x16x32_bf16 v[58:61], v[168:171], v[192:195], v[58:61]
	v_mfma_f32_16x16x32_bf16 v[46:49], v[160:163], v[200:203], v[46:49]
	v_mfma_f32_16x16x32_bf16 v[42:45], v[168:171], v[200:203], v[42:45]
	v_mfma_f32_16x16x32_bf16 v[30:33], v[160:163], v[208:211], v[30:33]
	v_mfma_f32_16x16x32_bf16 v[26:29], v[168:171], v[208:211], v[26:29]
	v_mfma_f32_16x16x32_bf16 v[14:17], v[160:163], v[216:219], v[14:17]
	v_mfma_f32_16x16x32_bf16 v[10:13], v[168:171], v[216:219], v[10:13]
	v_mfma_f32_16x16x32_bf16 v[54:57], v[172:175], v[188:191], 0
	v_mfma_f32_16x16x32_bf16 v[50:53], v[180:183], v[188:191], 0
	v_mfma_f32_16x16x32_bf16 v[38:41], v[172:175], v[196:199], 0
	v_mfma_f32_16x16x32_bf16 v[34:37], v[180:183], v[196:199], 0
	v_mfma_f32_16x16x32_bf16 v[22:25], v[172:175], v[204:207], 0
	v_mfma_f32_16x16x32_bf16 v[18:21], v[180:183], v[204:207], 0
	v_mfma_f32_16x16x32_bf16 v[6:9], v[172:175], v[212:215], 0
	v_mfma_f32_16x16x32_bf16 v[2:5], v[180:183], v[212:215], 0
	v_mfma_f32_16x16x32_bf16 v[54:57], v[176:179], v[192:195], v[54:57]
	v_mfma_f32_16x16x32_bf16 v[50:53], v[184:187], v[192:195], v[50:53]
	v_mfma_f32_16x16x32_bf16 v[38:41], v[176:179], v[200:203], v[38:41]
	v_mfma_f32_16x16x32_bf16 v[34:37], v[184:187], v[200:203], v[34:37]
	v_mfma_f32_16x16x32_bf16 v[22:25], v[176:179], v[208:211], v[22:25]
	v_mfma_f32_16x16x32_bf16 v[18:21], v[184:187], v[208:211], v[18:21]
	v_mfma_f32_16x16x32_bf16 v[6:9], v[176:179], v[216:219], v[6:9]
	v_mfma_f32_16x16x32_bf16 v[2:5], v[184:187], v[216:219], v[2:5]
	s_barrier
	v_add_u32_e32 v168, s60, v151
	v_add_u32_e32 v184, s61, v151
	ds_read_b128 v[156:159], v168
	ds_read_b128 v[160:163], v168 offset:1024
	ds_read_b128 v[164:167], v168 offset:2048
	ds_read_b128 v[168:171], v168 offset:3072
	ds_read_b128 v[172:175], v184
	ds_read_b128 v[176:179], v184 offset:1024
	ds_read_b128 v[180:183], v184 offset:2048
	ds_read_b128 v[184:187], v184 offset:3072
	s_add_u32 s26, s26, 0x80000
	s_addc_u32 s27, s27, 0
	s_mov_b32 m0, s37
	ds_read_b128 v[188:191], v155 offset:32768
	ds_read_b128 v[192:195], v155 offset:33792
	ds_read_b128 v[196:199], v155 offset:34816
	ds_read_b128 v[200:203], v155 offset:35840
	ds_read_b128 v[204:207], v155 offset:36864
	ds_read_b128 v[208:211], v155 offset:37888
	ds_read_b128 v[212:215], v155 offset:38912
	global_load_lds_dwordx4 v130, s[26:27]
	s_mov_b32 m0, s40
	ds_read_b128 v[216:219], v155 offset:39936
	global_load_lds_dwordx4 v134, s[26:27]
	s_waitcnt vmcnt(8) lgkmcnt(0)
	s_barrier
	v_mfma_f32_16x16x32_bf16 v[126:129], v[156:159], v[188:191], v[126:129]
	v_mfma_f32_16x16x32_bf16 v[122:125], v[164:167], v[188:191], v[122:125]
	v_mfma_f32_16x16x32_bf16 v[110:113], v[156:159], v[196:199], v[110:113]
	v_mfma_f32_16x16x32_bf16 v[106:109], v[164:167], v[196:199], v[106:109]
	v_mfma_f32_16x16x32_bf16 v[94:97], v[156:159], v[204:207], v[94:97]
	v_mfma_f32_16x16x32_bf16 v[90:93], v[164:167], v[204:207], v[90:93]
	v_mfma_f32_16x16x32_bf16 v[78:81], v[156:159], v[212:215], v[78:81]
	v_mfma_f32_16x16x32_bf16 v[74:77], v[164:167], v[212:215], v[74:77]
	v_mfma_f32_16x16x32_bf16 v[126:129], v[160:163], v[192:195], v[126:129]
	v_mfma_f32_16x16x32_bf16 v[122:125], v[168:171], v[192:195], v[122:125]
	v_mfma_f32_16x16x32_bf16 v[110:113], v[160:163], v[200:203], v[110:113]
	v_mfma_f32_16x16x32_bf16 v[106:109], v[168:171], v[200:203], v[106:109]
	v_mfma_f32_16x16x32_bf16 v[94:97], v[160:163], v[208:211], v[94:97]
	v_mfma_f32_16x16x32_bf16 v[90:93], v[168:171], v[208:211], v[90:93]
	v_mfma_f32_16x16x32_bf16 v[78:81], v[160:163], v[216:219], v[78:81]
	v_mfma_f32_16x16x32_bf16 v[74:77], v[168:171], v[216:219], v[74:77]
	v_mfma_f32_16x16x32_bf16 v[118:121], v[172:175], v[188:191], v[118:121]
	v_mfma_f32_16x16x32_bf16 v[114:117], v[180:183], v[188:191], v[114:117]
	v_mfma_f32_16x16x32_bf16 v[102:105], v[172:175], v[196:199], v[102:105]
	v_mfma_f32_16x16x32_bf16 v[98:101], v[180:183], v[196:199], v[98:101]
	v_mfma_f32_16x16x32_bf16 v[86:89], v[172:175], v[204:207], v[86:89]
	v_mfma_f32_16x16x32_bf16 v[82:85], v[180:183], v[204:207], v[82:85]
	v_mfma_f32_16x16x32_bf16 v[70:73], v[172:175], v[212:215], v[70:73]
	v_mfma_f32_16x16x32_bf16 v[66:69], v[180:183], v[212:215], v[66:69]
	v_mfma_f32_16x16x32_bf16 v[118:121], v[176:179], v[192:195], v[118:121]
	v_mfma_f32_16x16x32_bf16 v[114:117], v[184:187], v[192:195], v[114:117]
	v_mfma_f32_16x16x32_bf16 v[102:105], v[176:179], v[200:203], v[102:105]
	v_mfma_f32_16x16x32_bf16 v[98:101], v[184:187], v[200:203], v[98:101]
	v_mfma_f32_16x16x32_bf16 v[86:89], v[176:179], v[208:211], v[86:89]
	v_mfma_f32_16x16x32_bf16 v[82:85], v[184:187], v[208:211], v[82:85]
	v_mfma_f32_16x16x32_bf16 v[70:73], v[176:179], v[216:219], v[70:73]
	v_mfma_f32_16x16x32_bf16 v[66:69], v[184:187], v[216:219], v[66:69]
	s_barrier
; #define PG8_STAGE(bufoff, gbase, voff) do { _Pragma("unroll") for (int _i = 0; _i < 2; ++_i) \
;         __builtin_amdgcn_global_load_lds((const unsigned*)((const char*)(gbase) + (voff)[_i]), (LAS unsigned*)(lds + (bufoff) + ldsw + _i * 8192), 16, 0, 0); } while (0)
; #define PG8_LDA(dst, b, h) do { _Pragma("unroll") for (int m = 0; m < 4; ++m) _Pragma("unroll") for (int k = 0; k < 2; ++k) dst[m][k] = *(const LAS bf16x8*)(lds + PG8_SA(b, h) + aoff + m * 2048 + k * 1024); } while (0)
; #define PG8_LDB(dst, b, h) do { _Pragma("unroll") for (int n = 0; n < 2; ++n) _Pragma("unroll") for (int k = 0; k < 2; ++k) dst[n][k] = *(const LAS bf16x8*)(lds + PG8_SB(b, h) + boff + n * 2048 + k * 1024); } while (0)
; #define PG8_MMA(ai, bj, At, Bt) do { __builtin_amdgcn_s_setprio(1); _Pragma("unroll") for (int m = 0; m < 4; ++m) _Pragma("unroll") for (int n = 0; n < 2; ++n) _Pragma("unroll") for (int k = 0; k < 2; ++k) \
;         acc[ai][bj][m][n] = __builtin_amdgcn_mfma_f32_16x16x32_bf16(Bt[n][k], At[m][k], acc[ai][bj][m][n], 0, 0, 0); __builtin_amdgcn_s_setprio(0); } while (0)
; #define PG8_BAR __builtin_amdgcn_s_barrier()
; template <class Epi, class Sched, bool ABLK = false, bool ALIGN_EPI = true, bool SP2 = true, bool BBLK = true>
; __device__ __forceinline__ void gemm_phase(LAS unsigned char* lds, const Gemm g, const Sched& S, const Epi& E) {
;     ...
;             PG8_LDB(B0, 0, 0); PG8_LDB(B1, 0, 1); PG8_SCHED; PG8_LDA(At, 0, 0); PG8_STAGE(PG8_SA(1, 1), a1 + hstepA, voffA);
;             PG8_WAIT_V(8); PG8_WAIT_L(0); PG8_BAR; PG8_MMA(0, 0, At, B0); PG8_MMA(0, 1, At, B1); PG8_BAR; PG8_SCHED;
;             PG8_LDA(At, 0, 1); PG8_STAGE(PG8_SB(0, 0), b2, voffB); PG8_STAGE(PG8_SB(0, 1), b2 + hstepB, voffB); PG8_STAGE(PG8_SA(0, 0), a2, voffA);
;             PG8_WAIT_V(8); PG8_WAIT_L(0); PG8_BAR; PG8_MMA(1, 0, At, B0); PG8_MMA(1, 1, At, B1); PG8_BAR; PG8_SCHED;
;             PG8_LDB(B0, 1, 0); PG8_LDB(B1, 1, 1); PG8_SCHED; PG8_LDA(At, 1, 0); PG8_STAGE(PG8_SA(0, 1), a2 + hstepA, voffA);
;             PG8_WAIT_V(8); PG8_WAIT_L(0); PG8_BAR; PG8_MMA(0, 0, At, B0); PG8_MMA(0, 1, At, B1); PG8_BAR; PG8_SCHED;
;             PG8_LDA(At, 1, 1); PG8_STAGE(PG8_SB(1, 0), b3, voffB); PG8_STAGE(PG8_SB(1, 1), b3 + hstepB, voffB); PG8_STAGE(PG8_SA(1, 0), a3, voffA);
;             PG8_WAIT_V(8); PG8_WAIT_L(0); PG8_BAR; PG8_MMA(1, 0, At, B0); PG8_MMA(1, 1, At, B1); PG8_BAR; PG8_SCHED;
	s_add_u32 s26, s24, 0x8000
	s_addc_u32 s27, s25, 0
	s_add_i32 s66, s60, s34
	s_mov_b32 m0, s66
	ds_read_b128 v[188:191], v155 offset:49152
	ds_read_b128 v[192:195], v155 offset:50176
	ds_read_b128 v[196:199], v155 offset:51200
	ds_read_b128 v[200:203], v155 offset:52224
	global_load_lds_dwordx4 v132, s[26:27]
	s_add_i32 m0, s66, 0x2000
	s_add_u32 s24, s24, 0xc000
	v_lshl_add_u64 v[220:221], s[26:27], 0, v[136:137]
	s_addc_u32 s25, s25, 0
	s_add_i32 s26, s61, s34
	global_load_lds_dwordx4 v[220:221], off
	s_mov_b32 m0, s26
	ds_read_b128 v[204:207], v155 offset:53248
	global_load_lds_dwordx4 v132, s[24:25]
	s_add_i32 m0, s26, 0x2000
	ds_read_b128 v[208:211], v155 offset:54272
	global_load_lds_dwordx4 v136, s[24:25]
	s_mov_b32 m0, s41
	ds_read_b128 v[212:215], v155 offset:55296
	global_load_lds_dwordx4 v130, s[22:23]
	s_mov_b32 m0, s42
	ds_read_b128 v[216:219], v155 offset:56320
	global_load_lds_dwordx4 v134, s[22:23]
	s_waitcnt vmcnt(8) lgkmcnt(0)
	s_barrier
	v_mfma_f32_16x16x32_bf16 v[62:65], v[156:159], v[188:191], v[62:65]
	v_mfma_f32_16x16x32_bf16 v[58:61], v[164:167], v[188:191], v[58:61]
	v_mfma_f32_16x16x32_bf16 v[46:49], v[156:159], v[196:199], v[46:49]
	v_mfma_f32_16x16x32_bf16 v[42:45], v[164:167], v[196:199], v[42:45]
	v_mfma_f32_16x16x32_bf16 v[30:33], v[156:159], v[204:207], v[30:33]
	v_mfma_f32_16x16x32_bf16 v[26:29], v[164:167], v[204:207], v[26:29]
	v_mfma_f32_16x16x32_bf16 v[14:17], v[156:159], v[212:215], v[14:17]
	v_mfma_f32_16x16x32_bf16 v[10:13], v[164:167], v[212:215], v[10:13]
	v_mfma_f32_16x16x32_bf16 v[62:65], v[160:163], v[192:195], v[62:65]
	v_mfma_f32_16x16x32_bf16 v[58:61], v[168:171], v[192:195], v[58:61]
	v_mfma_f32_16x16x32_bf16 v[46:49], v[160:163], v[200:203], v[46:49]
	v_mfma_f32_16x16x32_bf16 v[42:45], v[168:171], v[200:203], v[42:45]
	v_mfma_f32_16x16x32_bf16 v[30:33], v[160:163], v[208:211], v[30:33]
	v_mfma_f32_16x16x32_bf16 v[26:29], v[168:171], v[208:211], v[26:29]
	v_mfma_f32_16x16x32_bf16 v[14:17], v[160:163], v[216:219], v[14:17]
	v_mfma_f32_16x16x32_bf16 v[10:13], v[168:171], v[216:219], v[10:13]
	v_mfma_f32_16x16x32_bf16 v[54:57], v[172:175], v[188:191], v[54:57]
	v_mfma_f32_16x16x32_bf16 v[50:53], v[180:183], v[188:191], v[50:53]
	v_mfma_f32_16x16x32_bf16 v[38:41], v[172:175], v[196:199], v[38:41]
	v_mfma_f32_16x16x32_bf16 v[34:37], v[180:183], v[196:199], v[34:37]
	v_mfma_f32_16x16x32_bf16 v[22:25], v[172:175], v[204:207], v[22:25]
	v_mfma_f32_16x16x32_bf16 v[18:21], v[180:183], v[204:207], v[18:21]
	v_mfma_f32_16x16x32_bf16 v[6:9], v[172:175], v[212:215], v[6:9]
	v_mfma_f32_16x16x32_bf16 v[2:5], v[180:183], v[212:215], v[2:5]
	v_mfma_f32_16x16x32_bf16 v[54:57], v[176:179], v[192:195], v[54:57]
	v_mfma_f32_16x16x32_bf16 v[50:53], v[184:187], v[192:195], v[50:53]
	v_mfma_f32_16x16x32_bf16 v[38:41], v[176:179], v[200:203], v[38:41]
	v_mfma_f32_16x16x32_bf16 v[34:37], v[184:187], v[200:203], v[34:37]
	v_mfma_f32_16x16x32_bf16 v[22:25], v[176:179], v[208:211], v[22:25]
	v_mfma_f32_16x16x32_bf16 v[18:21], v[184:187], v[208:211], v[18:21]
	v_mfma_f32_16x16x32_bf16 v[6:9], v[176:179], v[216:219], v[6:9]
	v_mfma_f32_16x16x32_bf16 v[2:5], v[184:187], v[216:219], v[2:5]
	s_barrier
	s_add_u32 s51, s51, 0x10000
	s_addc_u32 s55, s55, 0
	s_add_u32 s20, s20, 0x100
	s_addc_u32 s21, s21, 0
	s_cmp_ge_u32 s65, s46
.LBB0_1038:
	ds_read_b128 v[156:159], v153
	ds_read_b128 v[160:163], v153 offset:1024
	ds_read_b128 v[164:167], v153 offset:2048
	ds_read_b128 v[168:171], v153 offset:3072
	ds_read_b128 v[172:175], v154
	ds_read_b128 v[176:179], v154 offset:1024
	ds_read_b128 v[180:183], v154 offset:2048
	ds_read_b128 v[184:187], v154 offset:3072
	s_add_u32 s22, s56, s20
	s_addc_u32 s23, s57, s21
	s_add_u32 s26, s22, 0x100
	s_addc_u32 s27, s23, 0
	s_add_i32 s65, s65, 2
	s_add_u32 s22, s22, 0x180
	s_addc_u32 s23, s23, 0
	s_cmp_eq_u32 s64, s20
	s_cselect_b32 s23, s50, s23
	s_cselect_b32 s22, s49, s22
	s_cselect_b32 s25, s4, s55
	s_cselect_b32 s24, s5, s51
	s_cselect_b32 s27, s48, s27
	s_cselect_b32 s26, s17, s26
	v_lshl_add_u64 v[220:221], v[146:147], 0, s[20:21]
	s_add_i32 m0, s35, 0xc000
	ds_read_b128 v[188:191], v155
	ds_read_b128 v[192:195], v155 offset:1024
	ds_read_b128 v[196:199], v155 offset:2048
	ds_read_b128 v[200:203], v155 offset:3072
	ds_read_b128 v[204:207], v155 offset:4096
	ds_read_b128 v[208:211], v155 offset:5120
	ds_read_b128 v[212:215], v155 offset:6144
	global_load_lds_dwordx4 v[220:221], off
	v_lshl_add_u64 v[220:221], v[148:149], 0, s[20:21]
	s_add_i32 m0, s35, 0xe000
	ds_read_b128 v[216:219], v155 offset:7168
	global_load_lds_dwordx4 v[220:221], off
	s_waitcnt vmcnt(8) lgkmcnt(0)
	s_barrier
; #define PG8_STAGE(bufoff, gbase, voff) do { _Pragma("unroll") for (int _i = 0; _i < 2; ++_i) \
;         __builtin_amdgcn_global_load_lds((const unsigned*)((const char*)(gbase) + (voff)[_i]), (LAS unsigned*)(lds + (bufoff) + ldsw + _i * 8192), 16, 0, 0); } while (0)
; #define PG8_LDA(dst, b, h) do { _Pragma("unroll") for (int m = 0; m < 4; ++m) _Pragma("unroll") for (int k = 0; k < 2; ++k) dst[m][k] = *(const LAS bf16x8*)(lds + PG8_SA(b, h) + aoff + m * 2048 + k * 1024); } while (0)
; #define PG8_LDB(dst, b, h) do { _Pragma("unroll") for (int n = 0; n < 2; ++n) _Pragma("unroll") for (int k = 0; k < 2; ++k) dst[n][k] = *(const LAS bf16x8*)(lds + PG8_SB(b, h) + boff + n * 2048 + k * 1024); } while (0)
; #define PG8_MMA(ai, bj, At, Bt) do { __builtin_amdgcn_s_setprio(1); _Pragma("unroll") for (int m = 0; m < 4; ++m) _Pragma("unroll") for (int n = 0; n < 2; ++n) _Pragma("unroll") for (int k = 0; k < 2; ++k) \
;         acc[ai][bj][m][n] = __builtin_amdgcn_mfma_f32_16x16x32_bf16(Bt[n][k], At[m][k], acc[ai][bj][m][n], 0, 0, 0); __builtin_amdgcn_s_setprio(0); } while (0)
; #define PG8_WAIT_V(n) asm volatile("s_waitcnt vmcnt(" #n ")" ::: "memory")
; #define PG8_WAIT_L(n) asm volatile("s_waitcnt lgkmcnt(" #n ")" ::: "memory")
; #define PG8_BAR __builtin_amdgcn_s_barrier()
; #define PG8_SCHED __builtin_amdgcn_sched_barrier(0)
; template <class Epi, class Sched, bool ABLK = false, bool ALIGN_EPI = true, bool SP2 = true, bool BBLK = true>
; __device__ __forceinline__ void gemm_phase(LAS unsigned char* lds, const Gemm g, const Sched& S, const Epi& E) {
;     ...
;             PG8_WAIT_V(8); PG8_WAIT_L(0); PG8_BAR; PG8_MMA(0, 0, At, B0); PG8_MMA(0, 1, At, B1); PG8_BAR; PG8_SCHED;
;             PG8_LDA(At, 0, 1); PG8_STAGE(PG8_SB(0, 0), b2, voffB); PG8_STAGE(PG8_SB(0, 1), b2 + hstepB, voffB); PG8_STAGE(PG8_SA(0, 0), a2, voffA);
;             PG8_WAIT_V(8); PG8_WAIT_L(0); PG8_BAR; PG8_MMA(1, 0, At, B0); PG8_MMA(1, 1, At, B1); PG8_BAR; PG8_SCHED;
;             PG8_LDB(B0, 1, 0); PG8_LDB(B1, 1, 1); PG8_SCHED; PG8_LDA(At, 1, 0); PG8_STAGE(PG8_SA(0, 1), a2 + hstepA, voffA);
	v_mfma_f32_16x16x32_bf16 v[126:129], v[156:159], v[188:191], v[126:129]
	v_mfma_f32_16x16x32_bf16 v[122:125], v[164:167], v[188:191], v[122:125]
	v_mfma_f32_16x16x32_bf16 v[110:113], v[156:159], v[196:199], v[110:113]
	v_mfma_f32_16x16x32_bf16 v[106:109], v[164:167], v[196:199], v[106:109]
	v_mfma_f32_16x16x32_bf16 v[94:97], v[156:159], v[204:207], v[94:97]
	v_mfma_f32_16x16x32_bf16 v[90:93], v[164:167], v[204:207], v[90:93]
	v_mfma_f32_16x16x32_bf16 v[78:81], v[156:159], v[212:215], v[78:81]
	v_mfma_f32_16x16x32_bf16 v[74:77], v[164:167], v[212:215], v[74:77]
	v_mfma_f32_16x16x32_bf16 v[126:129], v[160:163], v[192:195], v[126:129]
	v_mfma_f32_16x16x32_bf16 v[122:125], v[168:171], v[192:195], v[122:125]
	v_mfma_f32_16x16x32_bf16 v[110:113], v[160:163], v[200:203], v[110:113]
	v_mfma_f32_16x16x32_bf16 v[106:109], v[168:171], v[200:203], v[106:109]
	v_mfma_f32_16x16x32_bf16 v[94:97], v[160:163], v[208:211], v[94:97]
	v_mfma_f32_16x16x32_bf16 v[90:93], v[168:171], v[208:211], v[90:93]
	v_mfma_f32_16x16x32_bf16 v[78:81], v[160:163], v[216:219], v[78:81]
	v_mfma_f32_16x16x32_bf16 v[74:77], v[168:171], v[216:219], v[74:77]
	v_mfma_f32_16x16x32_bf16 v[118:121], v[172:175], v[188:191], v[118:121]
	v_mfma_f32_16x16x32_bf16 v[114:117], v[180:183], v[188:191], v[114:117]
	v_mfma_f32_16x16x32_bf16 v[102:105], v[172:175], v[196:199], v[102:105]
	v_mfma_f32_16x16x32_bf16 v[98:101], v[180:183], v[196:199], v[98:101]
	v_mfma_f32_16x16x32_bf16 v[86:89], v[172:175], v[204:207], v[86:89]
	v_mfma_f32_16x16x32_bf16 v[82:85], v[180:183], v[204:207], v[82:85]
	v_mfma_f32_16x16x32_bf16 v[70:73], v[172:175], v[212:215], v[70:73]
	v_mfma_f32_16x16x32_bf16 v[66:69], v[180:183], v[212:215], v[66:69]
	v_mfma_f32_16x16x32_bf16 v[118:121], v[176:179], v[192:195], v[118:121]
	v_mfma_f32_16x16x32_bf16 v[114:117], v[184:187], v[192:195], v[114:117]
	v_mfma_f32_16x16x32_bf16 v[102:105], v[176:179], v[200:203], v[102:105]
	v_mfma_f32_16x16x32_bf16 v[98:101], v[184:187], v[200:203], v[98:101]
	v_mfma_f32_16x16x32_bf16 v[86:89], v[176:179], v[208:211], v[86:89]
	v_mfma_f32_16x16x32_bf16 v[82:85], v[184:187], v[208:211], v[82:85]
	v_mfma_f32_16x16x32_bf16 v[70:73], v[176:179], v[216:219], v[70:73]
	v_mfma_f32_16x16x32_bf16 v[66:69], v[184:187], v[216:219], v[66:69]
	s_barrier
	s_add_i32 s66, s72, s34
	s_mov_b32 m0, s66
	ds_read_b128 v[188:191], v155 offset:16384
	ds_read_b128 v[192:195], v155 offset:17408
	ds_read_b128 v[196:199], v155 offset:18432
	ds_read_b128 v[200:203], v155 offset:19456
	global_load_lds_dwordx4 v132, s[24:25]
	s_add_i32 m0, s66, 0x2000
	s_add_u32 s66, s24, 0x4000
	s_addc_u32 s67, s25, 0
	s_add_i32 s75, s73, s34
	global_load_lds_dwordx4 v136, s[24:25]
	s_mov_b32 m0, s75
	ds_read_b128 v[204:207], v155 offset:20480
	global_load_lds_dwordx4 v132, s[66:67]
	s_add_i32 m0, s75, 0x2000
	ds_read_b128 v[208:211], v155 offset:21504
	global_load_lds_dwordx4 v136, s[66:67]
	s_mov_b32 m0, s35
	ds_read_b128 v[212:215], v155 offset:22528
	global_load_lds_dwordx4 v130, s[26:27]
	s_mov_b32 m0, s36
	ds_read_b128 v[216:219], v155 offset:23552
	global_load_lds_dwordx4 v134, s[26:27]
	s_waitcnt vmcnt(8) lgkmcnt(0)
	s_barrier
	v_mfma_f32_16x16x32_bf16 v[62:65], v[156:159], v[188:191], v[62:65]
	v_mfma_f32_16x16x32_bf16 v[58:61], v[164:167], v[188:191], v[58:61]
	v_mfma_f32_16x16x32_bf16 v[46:49], v[156:159], v[196:199], v[46:49]
	v_mfma_f32_16x16x32_bf16 v[42:45], v[164:167], v[196:199], v[42:45]
	v_mfma_f32_16x16x32_bf16 v[30:33], v[156:159], v[204:207], v[30:33]
	v_mfma_f32_16x16x32_bf16 v[26:29], v[164:167], v[204:207], v[26:29]
	v_mfma_f32_16x16x32_bf16 v[14:17], v[156:159], v[212:215], v[14:17]
	v_mfma_f32_16x16x32_bf16 v[10:13], v[164:167], v[212:215], v[10:13]
	v_mfma_f32_16x16x32_bf16 v[62:65], v[160:163], v[192:195], v[62:65]
	v_mfma_f32_16x16x32_bf16 v[58:61], v[168:171], v[192:195], v[58:61]
	v_mfma_f32_16x16x32_bf16 v[46:49], v[160:163], v[200:203], v[46:49]
	v_mfma_f32_16x16x32_bf16 v[42:45], v[168:171], v[200:203], v[42:45]
	v_mfma_f32_16x16x32_bf16 v[30:33], v[160:163], v[208:211], v[30:33]
	v_mfma_f32_16x16x32_bf16 v[26:29], v[168:171], v[208:211], v[26:29]
	v_mfma_f32_16x16x32_bf16 v[14:17], v[160:163], v[216:219], v[14:17]
	v_mfma_f32_16x16x32_bf16 v[10:13], v[168:171], v[216:219], v[10:13]
	v_mfma_f32_16x16x32_bf16 v[54:57], v[172:175], v[188:191], v[54:57]
	v_mfma_f32_16x16x32_bf16 v[50:53], v[180:183], v[188:191], v[50:53]
	v_mfma_f32_16x16x32_bf16 v[38:41], v[172:175], v[196:199], v[38:41]
	v_mfma_f32_16x16x32_bf16 v[34:37], v[180:183], v[196:199], v[34:37]
	v_mfma_f32_16x16x32_bf16 v[22:25], v[172:175], v[204:207], v[22:25]
	v_mfma_f32_16x16x32_bf16 v[18:21], v[180:183], v[204:207], v[18:21]
	v_mfma_f32_16x16x32_bf16 v[6:9], v[172:175], v[212:215], v[6:9]
	v_mfma_f32_16x16x32_bf16 v[2:5], v[180:183], v[212:215], v[2:5]
	v_mfma_f32_16x16x32_bf16 v[54:57], v[176:179], v[192:195], v[54:57]
	v_mfma_f32_16x16x32_bf16 v[50:53], v[184:187], v[192:195], v[50:53]
	v_mfma_f32_16x16x32_bf16 v[38:41], v[176:179], v[200:203], v[38:41]
	v_mfma_f32_16x16x32_bf16 v[34:37], v[184:187], v[200:203], v[34:37]
	v_mfma_f32_16x16x32_bf16 v[22:25], v[176:179], v[208:211], v[22:25]
	v_mfma_f32_16x16x32_bf16 v[18:21], v[184:187], v[208:211], v[18:21]
	v_mfma_f32_16x16x32_bf16 v[6:9], v[176:179], v[216:219], v[6:9]
	v_mfma_f32_16x16x32_bf16 v[2:5], v[184:187], v[216:219], v[2:5]
	s_barrier
; #define PG8_STAGE(bufoff, gbase, voff) do { _Pragma("unroll") for (int _i = 0; _i < 2; ++_i) \
;         __builtin_amdgcn_global_load_lds((const unsigned*)((const char*)(gbase) + (voff)[_i]), (LAS unsigned*)(lds + (bufoff) + ldsw + _i * 8192), 16, 0, 0); } while (0)
; #define PG8_LDA(dst, b, h) do { _Pragma("unroll") for (int m = 0; m < 4; ++m) _Pragma("unroll") for (int k = 0; k < 2; ++k) dst[m][k] = *(const LAS bf16x8*)(lds + PG8_SA(b, h) + aoff + m * 2048 + k * 1024); } while (0)
; #define PG8_LDB(dst, b, h) do { _Pragma("unroll") for (int n = 0; n < 2; ++n) _Pragma("unroll") for (int k = 0; k < 2; ++k) dst[n][k] = *(const LAS bf16x8*)(lds + PG8_SB(b, h) + boff + n * 2048 + k * 1024); } while (0)
; #define PG8_MMA(ai, bj, At, Bt) do { __builtin_amdgcn_s_setprio(1); _Pragma("unroll") for (int m = 0; m < 4; ++m) _Pragma("unroll") for (int n = 0; n < 2; ++n) _Pragma("unroll") for (int k = 0; k < 2; ++k) \
;         acc[ai][bj][m][n] = __builtin_amdgcn_mfma_f32_16x16x32_bf16(Bt[n][k], At[m][k], acc[ai][bj][m][n], 0, 0, 0); __builtin_amdgcn_s_setprio(0); } while (0)
; #define PG8_WAIT_V(n) asm volatile("s_waitcnt vmcnt(" #n ")" ::: "memory")
; #define PG8_WAIT_L(n) asm volatile("s_waitcnt lgkmcnt(" #n ")" ::: "memory")
; #define PG8_BAR __builtin_amdgcn_s_barrier()
; #define PG8_SCHED __builtin_amdgcn_sched_barrier(0)
; template <class Epi, class Sched, bool ABLK = false, bool ALIGN_EPI = true, bool SP2 = true, bool BBLK = true>
; __device__ __forceinline__ void gemm_phase(LAS unsigned char* lds, const Gemm g, const Sched& S, const Epi& E) {
;     ...
;             PG8_LDB(B0, 1, 0); PG8_LDB(B1, 1, 1); PG8_SCHED; PG8_LDA(At, 1, 0); PG8_STAGE(PG8_SA(0, 1), a2 + hstepA, voffA);
;             PG8_WAIT_V(8); PG8_WAIT_L(0); PG8_BAR; PG8_MMA(0, 0, At, B0); PG8_MMA(0, 1, At, B1); PG8_BAR; PG8_SCHED;
;             PG8_LDA(At, 1, 1); PG8_STAGE(PG8_SB(1, 0), b3, voffB); PG8_STAGE(PG8_SB(1, 1), b3 + hstepB, voffB); PG8_STAGE(PG8_SA(1, 0), a3, voffA);
;             PG8_WAIT_V(8); PG8_WAIT_L(0); PG8_BAR; PG8_MMA(1, 0, At, B0); PG8_MMA(1, 1, At, B1); PG8_BAR; PG8_SCHED;
;     ...
;         if constexpr (ALIGN_EPI) { if (wr == 0) PG8_BAR; }
	v_add_u32_e32 v168, s60, v151
	v_add_u32_e32 v184, s61, v151
	ds_read_b128 v[156:159], v168
	ds_read_b128 v[160:163], v168 offset:1024
	ds_read_b128 v[164:167], v168 offset:2048
	ds_read_b128 v[168:171], v168 offset:3072
	ds_read_b128 v[172:175], v184
	ds_read_b128 v[176:179], v184 offset:1024
	ds_read_b128 v[180:183], v184 offset:2048
	ds_read_b128 v[184:187], v184 offset:3072
	s_add_u32 s26, s26, 0x80000
	s_addc_u32 s27, s27, 0
	s_mov_b32 m0, s37
	ds_read_b128 v[188:191], v155 offset:32768
	ds_read_b128 v[192:195], v155 offset:33792
	ds_read_b128 v[196:199], v155 offset:34816
	ds_read_b128 v[200:203], v155 offset:35840
	ds_read_b128 v[204:207], v155 offset:36864
	ds_read_b128 v[208:211], v155 offset:37888
	ds_read_b128 v[212:215], v155 offset:38912
	global_load_lds_dwordx4 v130, s[26:27]
	s_mov_b32 m0, s40
	ds_read_b128 v[216:219], v155 offset:39936
	global_load_lds_dwordx4 v134, s[26:27]
	s_waitcnt vmcnt(8) lgkmcnt(0)
	s_barrier
	v_mfma_f32_16x16x32_bf16 v[126:129], v[156:159], v[188:191], v[126:129]
	v_mfma_f32_16x16x32_bf16 v[122:125], v[164:167], v[188:191], v[122:125]
	v_mfma_f32_16x16x32_bf16 v[110:113], v[156:159], v[196:199], v[110:113]
	v_mfma_f32_16x16x32_bf16 v[106:109], v[164:167], v[196:199], v[106:109]
	v_mfma_f32_16x16x32_bf16 v[94:97], v[156:159], v[204:207], v[94:97]
	v_mfma_f32_16x16x32_bf16 v[90:93], v[164:167], v[204:207], v[90:93]
	v_mfma_f32_16x16x32_bf16 v[78:81], v[156:159], v[212:215], v[78:81]
	v_mfma_f32_16x16x32_bf16 v[74:77], v[164:167], v[212:215], v[74:77]
	v_mfma_f32_16x16x32_bf16 v[126:129], v[160:163], v[192:195], v[126:129]
	v_mfma_f32_16x16x32_bf16 v[122:125], v[168:171], v[192:195], v[122:125]
	v_mfma_f32_16x16x32_bf16 v[110:113], v[160:163], v[200:203], v[110:113]
	v_mfma_f32_16x16x32_bf16 v[106:109], v[168:171], v[200:203], v[106:109]
	v_mfma_f32_16x16x32_bf16 v[94:97], v[160:163], v[208:211], v[94:97]
	v_mfma_f32_16x16x32_bf16 v[90:93], v[168:171], v[208:211], v[90:93]
	v_mfma_f32_16x16x32_bf16 v[78:81], v[160:163], v[216:219], v[78:81]
	v_mfma_f32_16x16x32_bf16 v[74:77], v[168:171], v[216:219], v[74:77]
	v_mfma_f32_16x16x32_bf16 v[118:121], v[172:175], v[188:191], v[118:121]
	v_mfma_f32_16x16x32_bf16 v[114:117], v[180:183], v[188:191], v[114:117]
	v_mfma_f32_16x16x32_bf16 v[102:105], v[172:175], v[196:199], v[102:105]
	v_mfma_f32_16x16x32_bf16 v[98:101], v[180:183], v[196:199], v[98:101]
	v_mfma_f32_16x16x32_bf16 v[86:89], v[172:175], v[204:207], v[86:89]
	v_mfma_f32_16x16x32_bf16 v[82:85], v[180:183], v[204:207], v[82:85]
	v_mfma_f32_16x16x32_bf16 v[70:73], v[172:175], v[212:215], v[70:73]
	v_mfma_f32_16x16x32_bf16 v[66:69], v[180:183], v[212:215], v[66:69]
	v_mfma_f32_16x16x32_bf16 v[118:121], v[176:179], v[192:195], v[118:121]
	v_mfma_f32_16x16x32_bf16 v[114:117], v[184:187], v[192:195], v[114:117]
	v_mfma_f32_16x16x32_bf16 v[102:105], v[176:179], v[200:203], v[102:105]
	v_mfma_f32_16x16x32_bf16 v[98:101], v[184:187], v[200:203], v[98:101]
	v_mfma_f32_16x16x32_bf16 v[86:89], v[176:179], v[208:211], v[86:89]
	v_mfma_f32_16x16x32_bf16 v[82:85], v[184:187], v[208:211], v[82:85]
	v_mfma_f32_16x16x32_bf16 v[70:73], v[176:179], v[216:219], v[70:73]
	v_mfma_f32_16x16x32_bf16 v[66:69], v[184:187], v[216:219], v[66:69]
	s_barrier
	s_add_u32 s26, s24, 0x8000
	s_addc_u32 s27, s25, 0
	s_add_i32 s66, s60, s34
	s_mov_b32 m0, s66
	ds_read_b128 v[188:191], v155 offset:49152
	ds_read_b128 v[192:195], v155 offset:50176
	ds_read_b128 v[196:199], v155 offset:51200
	ds_read_b128 v[200:203], v155 offset:52224
	global_load_lds_dwordx4 v132, s[26:27]
	s_add_i32 m0, s66, 0x2000
	s_add_u32 s24, s24, 0xc000
	v_lshl_add_u64 v[220:221], s[26:27], 0, v[136:137]
	s_addc_u32 s25, s25, 0
	s_add_i32 s26, s61, s34
	global_load_lds_dwordx4 v[220:221], off
	s_mov_b32 m0, s26
	ds_read_b128 v[204:207], v155 offset:53248
	global_load_lds_dwordx4 v132, s[24:25]
	s_add_i32 m0, s26, 0x2000
	ds_read_b128 v[208:211], v155 offset:54272
	global_load_lds_dwordx4 v136, s[24:25]
	s_mov_b32 m0, s41
	ds_read_b128 v[212:215], v155 offset:55296
	global_load_lds_dwordx4 v130, s[22:23]
	s_mov_b32 m0, s42
	ds_read_b128 v[216:219], v155 offset:56320
	global_load_lds_dwordx4 v134, s[22:23]
	s_waitcnt vmcnt(8) lgkmcnt(0)
	s_barrier
	v_mfma_f32_16x16x32_bf16 v[62:65], v[156:159], v[188:191], v[62:65]
	v_mfma_f32_16x16x32_bf16 v[58:61], v[164:167], v[188:191], v[58:61]
	v_mfma_f32_16x16x32_bf16 v[46:49], v[156:159], v[196:199], v[46:49]
	v_mfma_f32_16x16x32_bf16 v[42:45], v[164:167], v[196:199], v[42:45]
	v_mfma_f32_16x16x32_bf16 v[30:33], v[156:159], v[204:207], v[30:33]
	v_mfma_f32_16x16x32_bf16 v[26:29], v[164:167], v[204:207], v[26:29]
	v_mfma_f32_16x16x32_bf16 v[14:17], v[156:159], v[212:215], v[14:17]
	v_mfma_f32_16x16x32_bf16 v[10:13], v[164:167], v[212:215], v[10:13]
	v_mfma_f32_16x16x32_bf16 v[62:65], v[160:163], v[192:195], v[62:65]
	v_mfma_f32_16x16x32_bf16 v[58:61], v[168:171], v[192:195], v[58:61]
	v_mfma_f32_16x16x32_bf16 v[46:49], v[160:163], v[200:203], v[46:49]
	v_mfma_f32_16x16x32_bf16 v[42:45], v[168:171], v[200:203], v[42:45]
	v_mfma_f32_16x16x32_bf16 v[30:33], v[160:163], v[208:211], v[30:33]
	v_mfma_f32_16x16x32_bf16 v[26:29], v[168:171], v[208:211], v[26:29]
	v_mfma_f32_16x16x32_bf16 v[14:17], v[160:163], v[216:219], v[14:17]
	v_mfma_f32_16x16x32_bf16 v[10:13], v[168:171], v[216:219], v[10:13]
	v_mfma_f32_16x16x32_bf16 v[54:57], v[172:175], v[188:191], v[54:57]
	v_mfma_f32_16x16x32_bf16 v[50:53], v[180:183], v[188:191], v[50:53]
	v_mfma_f32_16x16x32_bf16 v[38:41], v[172:175], v[196:199], v[38:41]
	v_mfma_f32_16x16x32_bf16 v[34:37], v[180:183], v[196:199], v[34:37]
	v_mfma_f32_16x16x32_bf16 v[22:25], v[172:175], v[204:207], v[22:25]
	v_mfma_f32_16x16x32_bf16 v[18:21], v[180:183], v[204:207], v[18:21]
	v_mfma_f32_16x16x32_bf16 v[6:9], v[172:175], v[212:215], v[6:9]
	v_mfma_f32_16x16x32_bf16 v[2:5], v[180:183], v[212:215], v[2:5]
	v_mfma_f32_16x16x32_bf16 v[54:57], v[176:179], v[192:195], v[54:57]
	v_mfma_f32_16x16x32_bf16 v[50:53], v[184:187], v[192:195], v[50:53]
	v_mfma_f32_16x16x32_bf16 v[38:41], v[176:179], v[200:203], v[38:41]
	v_mfma_f32_16x16x32_bf16 v[34:37], v[184:187], v[200:203], v[34:37]
	v_mfma_f32_16x16x32_bf16 v[22:25], v[176:179], v[208:211], v[22:25]
	v_mfma_f32_16x16x32_bf16 v[18:21], v[184:187], v[208:211], v[18:21]
	v_mfma_f32_16x16x32_bf16 v[6:9], v[176:179], v[216:219], v[6:9]
	v_mfma_f32_16x16x32_bf16 v[2:5], v[184:187], v[216:219], v[2:5]
	s_barrier
	s_add_u32 s51, s51, 0x10000
	s_addc_u32 s55, s55, 0
	s_add_u32 s20, s20, 0x100
	s_addc_u32 s21, s21, 0
	s_cmp_ge_u32 s65, s46
	s_cbranch_scc0 .LBB0_1038
	s_and_b64 vcc, exec, s[10:11]
	s_cbranch_vccz .LBB0_1041
	s_barrier

; #define PG8_STAGE(bufoff, gbase, voff) do { _Pragma("unroll") for (int _i = 0; _i < 2; ++_i) \
;         __builtin_amdgcn_global_load_lds((const unsigned*)((const char*)(gbase) + (voff)[_i]), (LAS unsigned*)(lds + (bufoff) + ldsw + _i * 8192), 16, 0, 0); } while (0)
; #define PG8_LDA(dst, b, h) do { _Pragma("unroll") for (int m = 0; m < 4; ++m) _Pragma("unroll") for (int k = 0; k < 2; ++k) dst[m][k] = *(const LAS bf16x8*)(lds + PG8_SA(b, h) + aoff + m * 2048 + k * 1024); } while (0)
; #define PG8_LDB(dst, b, h) do { _Pragma("unroll") for (int n = 0; n < 2; ++n) _Pragma("unroll") for (int k = 0; k < 2; ++k) dst[n][k] = *(const LAS bf16x8*)(lds + PG8_SB(b, h) + boff + n * 2048 + k * 1024); } while (0)
; #define PG8_WAIT_V(n) asm volatile("s_waitcnt vmcnt(" #n ")" ::: "memory")
; #define PG8_WAIT_L(n) asm volatile("s_waitcnt lgkmcnt(" #n ")" ::: "memory")
; template <class Epi, class Sched, bool ABLK = false, bool ALIGN_EPI = true, bool SP2 = true, bool BBLK = true>
; __device__ __forceinline__ void gemm_phase(LAS unsigned char* lds, const Gemm g, const Sched& S, const Epi& E) {
;     ...
;         const bool has_next = S.next(ui + 1, nxt);
;         const int nt = cur.nt;
;         const char* nuA = has_next ? a_unit(nxt) : uA; const int ntbA = has_next ? nxt.k0 / BK : tbA; const char* nB = has_next ? (const char*)g.Bt + (size_t)nxt.pn * tstepB + b_k0(nxt.k0) : cB;
;         for (int t = 0; t < nt; t += 2) {
;             const bool last = (t == nt - 2);
;             const char* a1 = a_tile(uA, tbA + t + 1);
;             const char* a2 = last ? a_tile(nuA, ntbA) : a_tile(uA, tbA + t + 2); const char* b2 = last ? nB : cB + (size_t)(t + 2) * kstepB;
;             const char* a3 = last ? a_tile(nuA, ntbA + 1) : a_tile(uA, tbA + t + 3); const char* b3 = b2 + kstepB;
;             if (last && has_next) S.a_ready(nxt);
;             if constexpr (SP2) {
;             PG8_LDB(B0, 0, 0); PG8_LDB(B1, 0, 1); PG8_SCHED; PG8_LDA(At, 0, 0); PG8_STAGE(PG8_SA(1, 1), a1 + hstepA, voffA);
;             PG8_WAIT_V(8); PG8_WAIT_L(0); PG8_BAR; PG8_MMA(0, 0, At, B0); PG8_MMA(0, 1, At, B1); PG8_BAR; PG8_SCHED;
;             PG8_LDA(At, 0, 1); PG8_STAGE(PG8_SB(0, 0), b2, voffB); PG8_STAGE(PG8_SB(0, 1), b2 + hstepB, voffB); PG8_STAGE(PG8_SA(0, 0), a2, voffA);
;             PG8_WAIT_V(8); PG8_WAIT_L(0); PG8_BAR; PG8_MMA(1, 0, At, B0); PG8_MMA(1, 1, At, B1); PG8_BAR; PG8_SCHED;
.LBB0_1163:
	s_ashr_i32 s11, s10, 31
	s_lshl_b64 s[4:5], s[10:11], 20
	s_add_u32 s16, s59, s4
	s_addc_u32 s17, s62, s5
	s_and_b64 s[4:5], s[18:19], exec
	s_cselect_b32 s4, s17, s27
	s_cselect_b32 s5, s16, s26
	s_ashr_i32 s15, s14, 31
	s_lshl_b64 s[20:21], s[14:15], 20
	s_add_u32 s20, s40, s20
	s_addc_u32 s21, s41, s21
	s_and_b64 s[30:31], s[18:19], exec
	s_cselect_b32 s11, s21, s29
	s_cselect_b32 s15, s20, s28
	s_add_u32 s23, s5, 0x80
	s_addc_u32 s57, s4, 0
	s_add_u32 s64, s28, 0x10000
	v_mov_b32_e32 v2, 0
	s_addc_u32 s65, s29, 0
	v_lshl_add_u64 v[164:165], s[26:27], 0, v[160:161]
	v_lshl_add_u64 v[166:167], s[26:27], 0, v[162:163]
	s_mov_b32 s66, -2
	s_mov_b64 s[28:29], 0
	ds_read_b128 v[172:175], v169
	ds_read_b128 v[176:179], v169 offset:1024
	ds_read_b128 v[180:183], v169 offset:2048
	ds_read_b128 v[184:187], v169 offset:3072
	ds_read_b128 v[188:191], v170
	ds_read_b128 v[192:195], v170 offset:1024
	ds_read_b128 v[196:199], v170 offset:2048
	ds_read_b128 v[200:203], v170 offset:3072
	s_add_u32 s30, s26, s28
	s_addc_u32 s31, s27, s29
	s_add_u32 s36, s30, 0x100
	s_addc_u32 s37, s31, 0
	s_add_u32 s30, s30, 0x180
	s_addc_u32 s31, s31, 0
	s_cmpk_eq_i32 s28, 0xf00
	s_cselect_b32 s31, s57, s31
	s_cselect_b32 s30, s23, s30
	s_cselect_b32 s35, s11, s65
	s_cselect_b32 s34, s15, s64
	s_cselect_b32 s37, s4, s37
	s_cselect_b32 s36, s5, s36
	s_mov_b32 m0, s50
	v_lshl_add_u64 v[236:237], v[164:165], 0, s[28:29]
	ds_read_b128 v[204:207], v171
	ds_read_b128 v[208:211], v171 offset:1024
	ds_read_b128 v[212:215], v171 offset:2048
	ds_read_b128 v[216:219], v171 offset:3072
	ds_read_b128 v[220:223], v171 offset:4096
	ds_read_b128 v[224:227], v171 offset:5120
	ds_read_b128 v[228:231], v171 offset:6144
	global_load_lds_dwordx4 v[236:237], off
	v_lshl_add_u64 v[236:237], v[166:167], 0, s[28:29]
	s_mov_b32 m0, s51
	ds_read_b128 v[232:235], v171 offset:7168
	global_load_lds_dwordx4 v[236:237], off
	s_waitcnt vmcnt(8) lgkmcnt(0)
	s_barrier
	v_mfma_f32_16x16x32_bf16 v[126:129], v[172:175], v[204:207], 0
	v_mfma_f32_16x16x32_bf16 v[122:125], v[180:183], v[204:207], 0
	v_mfma_f32_16x16x32_bf16 v[110:113], v[172:175], v[212:215], 0
	v_mfma_f32_16x16x32_bf16 v[106:109], v[180:183], v[212:215], 0
	v_mfma_f32_16x16x32_bf16 v[94:97], v[172:175], v[220:223], 0
	v_mfma_f32_16x16x32_bf16 v[90:93], v[180:183], v[220:223], 0
	v_mfma_f32_16x16x32_bf16 v[78:81], v[172:175], v[228:231], 0
	v_mfma_f32_16x16x32_bf16 v[74:77], v[180:183], v[228:231], 0
	v_mfma_f32_16x16x32_bf16 v[126:129], v[176:179], v[208:211], v[126:129]
	v_mfma_f32_16x16x32_bf16 v[122:125], v[184:187], v[208:211], v[122:125]
	v_mfma_f32_16x16x32_bf16 v[110:113], v[176:179], v[216:219], v[110:113]
	v_mfma_f32_16x16x32_bf16 v[106:109], v[184:187], v[216:219], v[106:109]
	v_mfma_f32_16x16x32_bf16 v[94:97], v[176:179], v[224:227], v[94:97]
	v_mfma_f32_16x16x32_bf16 v[90:93], v[184:187], v[224:227], v[90:93]
	v_mfma_f32_16x16x32_bf16 v[78:81], v[176:179], v[232:235], v[78:81]
	v_mfma_f32_16x16x32_bf16 v[74:77], v[184:187], v[232:235], v[74:77]
	v_mfma_f32_16x16x32_bf16 v[118:121], v[188:191], v[204:207], 0
	v_mfma_f32_16x16x32_bf16 v[114:117], v[196:199], v[204:207], 0
	v_mfma_f32_16x16x32_bf16 v[102:105], v[188:191], v[212:215], 0
	v_mfma_f32_16x16x32_bf16 v[98:101], v[196:199], v[212:215], 0
	v_mfma_f32_16x16x32_bf16 v[86:89], v[188:191], v[220:223], 0
	v_mfma_f32_16x16x32_bf16 v[82:85], v[196:199], v[220:223], 0
	v_mfma_f32_16x16x32_bf16 v[70:73], v[188:191], v[228:231], 0
	v_mfma_f32_16x16x32_bf16 v[66:69], v[196:199], v[228:231], 0
	v_mfma_f32_16x16x32_bf16 v[118:121], v[192:195], v[208:211], v[118:121]
	v_mfma_f32_16x16x32_bf16 v[114:117], v[200:203], v[208:211], v[114:117]
	v_mfma_f32_16x16x32_bf16 v[102:105], v[192:195], v[216:219], v[102:105]
	v_mfma_f32_16x16x32_bf16 v[98:101], v[200:203], v[216:219], v[98:101]
	v_mfma_f32_16x16x32_bf16 v[86:89], v[192:195], v[224:227], v[86:89]
	v_mfma_f32_16x16x32_bf16 v[82:85], v[200:203], v[224:227], v[82:85]
	v_mfma_f32_16x16x32_bf16 v[70:73], v[192:195], v[232:235], v[70:73]
	v_mfma_f32_16x16x32_bf16 v[66:69], v[200:203], v[232:235], v[66:69]
	s_barrier
	s_mov_b32 m0, s55
	s_add_u32 s76, s34, 0x4000
	ds_read_b128 v[204:207], v171 offset:16384
	ds_read_b128 v[208:211], v171 offset:17408
	ds_read_b128 v[212:215], v171 offset:18432
	ds_read_b128 v[216:219], v171 offset:19456
	global_load_lds_dwordx4 v134, s[34:35]
	s_mov_b32 m0, s56
	s_addc_u32 s77, s35, 0
	s_add_i32 s67, s73, s42
	global_load_lds_dwordx4 v130, s[34:35]
	s_mov_b32 m0, s67
	ds_read_b128 v[220:223], v171 offset:20480
	global_load_lds_dwordx4 v134, s[76:77]
	s_add_i32 m0, s67, 0x2000
	ds_read_b128 v[224:227], v171 offset:21504
	global_load_lds_dwordx4 v130, s[76:77]
	s_mov_b32 m0, s25
	ds_read_b128 v[228:231], v171 offset:22528
	global_load_lds_dwordx4 v136, s[36:37]
	s_mov_b32 m0, s43
	ds_read_b128 v[232:235], v171 offset:23552
	global_load_lds_dwordx4 v132, s[36:37]
	s_waitcnt vmcnt(8) lgkmcnt(0)
	s_barrier
; #define PG8_STAGE(bufoff, gbase, voff) do { _Pragma("unroll") for (int _i = 0; _i < 2; ++_i) \
;         __builtin_amdgcn_global_load_lds((const unsigned*)((const char*)(gbase) + (voff)[_i]), (LAS unsigned*)(lds + (bufoff) + ldsw + _i * 8192), 16, 0, 0); } while (0)
; #define PG8_LDA(dst, b, h) do { _Pragma("unroll") for (int m = 0; m < 4; ++m) _Pragma("unroll") for (int k = 0; k < 2; ++k) dst[m][k] = *(const LAS bf16x8*)(lds + PG8_SA(b, h) + aoff + m * 2048 + k * 1024); } while (0)
; #define PG8_LDB(dst, b, h) do { _Pragma("unroll") for (int n = 0; n < 2; ++n) _Pragma("unroll") for (int k = 0; k < 2; ++k) dst[n][k] = *(const LAS bf16x8*)(lds + PG8_SB(b, h) + boff + n * 2048 + k * 1024); } while (0)
; #define PG8_MMA(ai, bj, At, Bt) do { __builtin_amdgcn_s_setprio(1); _Pragma("unroll") for (int m = 0; m < 4; ++m) _Pragma("unroll") for (int n = 0; n < 2; ++n) _Pragma("unroll") for (int k = 0; k < 2; ++k) \
;         acc[ai][bj][m][n] = __builtin_amdgcn_mfma_f32_16x16x32_bf16(Bt[n][k], At[m][k], acc[ai][bj][m][n], 0, 0, 0); __builtin_amdgcn_s_setprio(0); } while (0)
; #define PG8_WAIT_V(n) asm volatile("s_waitcnt vmcnt(" #n ")" ::: "memory")
; #define PG8_WAIT_L(n) asm volatile("s_waitcnt lgkmcnt(" #n ")" ::: "memory")
; #define PG8_BAR __builtin_amdgcn_s_barrier()
; #define PG8_SCHED __builtin_amdgcn_sched_barrier(0)
; template <class Epi, class Sched, bool ABLK = false, bool ALIGN_EPI = true, bool SP2 = true, bool BBLK = true>
; __device__ __forceinline__ void gemm_phase(LAS unsigned char* lds, const Gemm g, const Sched& S, const Epi& E) {
;     ...
;             PG8_WAIT_V(8); PG8_WAIT_L(0); PG8_BAR; PG8_MMA(0, 0, At, B0); PG8_MMA(0, 1, At, B1); PG8_BAR; PG8_SCHED;
;             PG8_LDA(At, 0, 1); PG8_STAGE(PG8_SB(0, 0), b2, voffB); PG8_STAGE(PG8_SB(0, 1), b2 + hstepB, voffB); PG8_STAGE(PG8_SA(0, 0), a2, voffA);
;             PG8_WAIT_V(8); PG8_WAIT_L(0); PG8_BAR; PG8_MMA(1, 0, At, B0); PG8_MMA(1, 1, At, B1); PG8_BAR; PG8_SCHED;
;             PG8_LDB(B0, 1, 0); PG8_LDB(B1, 1, 1); PG8_SCHED; PG8_LDA(At, 1, 0); PG8_STAGE(PG8_SA(0, 1), a2 + hstepA, voffA);
;             PG8_WAIT_V(8); PG8_WAIT_L(0); PG8_BAR; PG8_MMA(0, 0, At, B0); PG8_MMA(0, 1, At, B1); PG8_BAR; PG8_SCHED;
	v_mfma_f32_16x16x32_bf16 v[62:65], v[172:175], v[204:207], 0
	v_mfma_f32_16x16x32_bf16 v[58:61], v[180:183], v[204:207], 0
	v_mfma_f32_16x16x32_bf16 v[46:49], v[172:175], v[212:215], 0
	v_mfma_f32_16x16x32_bf16 v[42:45], v[180:183], v[212:215], 0
	v_mfma_f32_16x16x32_bf16 v[30:33], v[172:175], v[220:223], 0
	v_mfma_f32_16x16x32_bf16 v[26:29], v[180:183], v[220:223], 0
	v_mfma_f32_16x16x32_bf16 v[14:17], v[172:175], v[228:231], 0
	v_mfma_f32_16x16x32_bf16 v[10:13], v[180:183], v[228:231], 0
	v_mfma_f32_16x16x32_bf16 v[62:65], v[176:179], v[208:211], v[62:65]
	v_mfma_f32_16x16x32_bf16 v[58:61], v[184:187], v[208:211], v[58:61]
	v_mfma_f32_16x16x32_bf16 v[46:49], v[176:179], v[216:219], v[46:49]
	v_mfma_f32_16x16x32_bf16 v[42:45], v[184:187], v[216:219], v[42:45]
	v_mfma_f32_16x16x32_bf16 v[30:33], v[176:179], v[224:227], v[30:33]
	v_mfma_f32_16x16x32_bf16 v[26:29], v[184:187], v[224:227], v[26:29]
	v_mfma_f32_16x16x32_bf16 v[14:17], v[176:179], v[232:235], v[14:17]
	v_mfma_f32_16x16x32_bf16 v[10:13], v[184:187], v[232:235], v[10:13]
	v_mfma_f32_16x16x32_bf16 v[54:57], v[188:191], v[204:207], 0
	v_mfma_f32_16x16x32_bf16 v[50:53], v[196:199], v[204:207], 0
	v_mfma_f32_16x16x32_bf16 v[38:41], v[188:191], v[212:215], 0
	v_mfma_f32_16x16x32_bf16 v[34:37], v[196:199], v[212:215], 0
	v_mfma_f32_16x16x32_bf16 v[22:25], v[188:191], v[220:223], 0
	v_mfma_f32_16x16x32_bf16 v[18:21], v[196:199], v[220:223], 0
	v_mfma_f32_16x16x32_bf16 v[6:9], v[188:191], v[228:231], 0
	v_mfma_f32_16x16x32_bf16 v[2:5], v[196:199], v[228:231], 0
	v_mfma_f32_16x16x32_bf16 v[54:57], v[192:195], v[208:211], v[54:57]
	v_mfma_f32_16x16x32_bf16 v[50:53], v[200:203], v[208:211], v[50:53]
	v_mfma_f32_16x16x32_bf16 v[38:41], v[192:195], v[216:219], v[38:41]
	v_mfma_f32_16x16x32_bf16 v[34:37], v[200:203], v[216:219], v[34:37]
	v_mfma_f32_16x16x32_bf16 v[22:25], v[192:195], v[224:227], v[22:25]
	v_mfma_f32_16x16x32_bf16 v[18:21], v[200:203], v[224:227], v[18:21]
	v_mfma_f32_16x16x32_bf16 v[6:9], v[192:195], v[232:235], v[6:9]
	v_mfma_f32_16x16x32_bf16 v[2:5], v[200:203], v[232:235], v[2:5]
	s_barrier
	v_add_u32_e32 v184, s60, v168
	v_add_u32_e32 v200, s61, v168
	ds_read_b128 v[172:175], v184
	ds_read_b128 v[176:179], v184 offset:1024
	ds_read_b128 v[180:183], v184 offset:2048
	ds_read_b128 v[184:187], v184 offset:3072
	ds_read_b128 v[188:191], v200
	ds_read_b128 v[192:195], v200 offset:1024
	ds_read_b128 v[196:199], v200 offset:2048
	ds_read_b128 v[200:203], v200 offset:3072
	s_add_u32 s36, s36, 0x80000
	s_addc_u32 s37, s37, 0
	s_mov_b32 m0, s44
	ds_read_b128 v[204:207], v171 offset:32768
	ds_read_b128 v[208:211], v171 offset:33792
	ds_read_b128 v[212:215], v171 offset:34816
	ds_read_b128 v[216:219], v171 offset:35840
	ds_read_b128 v[220:223], v171 offset:36864
	ds_read_b128 v[224:227], v171 offset:37888
	ds_read_b128 v[228:231], v171 offset:38912
	global_load_lds_dwordx4 v136, s[36:37]
	s_mov_b32 m0, s45
	ds_read_b128 v[232:235], v171 offset:39936
	global_load_lds_dwordx4 v132, s[36:37]
	s_waitcnt vmcnt(8) lgkmcnt(0)
	s_barrier
	v_mfma_f32_16x16x32_bf16 v[126:129], v[172:175], v[204:207], v[126:129]
	v_mfma_f32_16x16x32_bf16 v[122:125], v[180:183], v[204:207], v[122:125]
	v_mfma_f32_16x16x32_bf16 v[110:113], v[172:175], v[212:215], v[110:113]
	v_mfma_f32_16x16x32_bf16 v[106:109], v[180:183], v[212:215], v[106:109]
	v_mfma_f32_16x16x32_bf16 v[94:97], v[172:175], v[220:223], v[94:97]
	v_mfma_f32_16x16x32_bf16 v[90:93], v[180:183], v[220:223], v[90:93]
	v_mfma_f32_16x16x32_bf16 v[78:81], v[172:175], v[228:231], v[78:81]
	v_mfma_f32_16x16x32_bf16 v[74:77], v[180:183], v[228:231], v[74:77]
	v_mfma_f32_16x16x32_bf16 v[126:129], v[176:179], v[208:211], v[126:129]
	v_mfma_f32_16x16x32_bf16 v[122:125], v[184:187], v[208:211], v[122:125]
	v_mfma_f32_16x16x32_bf16 v[110:113], v[176:179], v[216:219], v[110:113]
	v_mfma_f32_16x16x32_bf16 v[106:109], v[184:187], v[216:219], v[106:109]
	v_mfma_f32_16x16x32_bf16 v[94:97], v[176:179], v[224:227], v[94:97]
	v_mfma_f32_16x16x32_bf16 v[90:93], v[184:187], v[224:227], v[90:93]
	v_mfma_f32_16x16x32_bf16 v[78:81], v[176:179], v[232:235], v[78:81]
	v_mfma_f32_16x16x32_bf16 v[74:77], v[184:187], v[232:235], v[74:77]
	v_mfma_f32_16x16x32_bf16 v[118:121], v[188:191], v[204:207], v[118:121]
	v_mfma_f32_16x16x32_bf16 v[114:117], v[196:199], v[204:207], v[114:117]
	v_mfma_f32_16x16x32_bf16 v[102:105], v[188:191], v[212:215], v[102:105]
	v_mfma_f32_16x16x32_bf16 v[98:101], v[196:199], v[212:215], v[98:101]
	v_mfma_f32_16x16x32_bf16 v[86:89], v[188:191], v[220:223], v[86:89]
	v_mfma_f32_16x16x32_bf16 v[82:85], v[196:199], v[220:223], v[82:85]
	v_mfma_f32_16x16x32_bf16 v[70:73], v[188:191], v[228:231], v[70:73]
	v_mfma_f32_16x16x32_bf16 v[66:69], v[196:199], v[228:231], v[66:69]
	v_mfma_f32_16x16x32_bf16 v[118:121], v[192:195], v[208:211], v[118:121]
	v_mfma_f32_16x16x32_bf16 v[114:117], v[200:203], v[208:211], v[114:117]
	v_mfma_f32_16x16x32_bf16 v[102:105], v[192:195], v[216:219], v[102:105]
	v_mfma_f32_16x16x32_bf16 v[98:101], v[200:203], v[216:219], v[98:101]
	v_mfma_f32_16x16x32_bf16 v[86:89], v[192:195], v[224:227], v[86:89]
	v_mfma_f32_16x16x32_bf16 v[82:85], v[200:203], v[224:227], v[82:85]
	v_mfma_f32_16x16x32_bf16 v[70:73], v[192:195], v[232:235], v[70:73]
	v_mfma_f32_16x16x32_bf16 v[66:69], v[200:203], v[232:235], v[66:69]
	s_barrier
; #define PG8_STAGE(bufoff, gbase, voff) do { _Pragma("unroll") for (int _i = 0; _i < 2; ++_i) \
;         __builtin_amdgcn_global_load_lds((const unsigned*)((const char*)(gbase) + (voff)[_i]), (LAS unsigned*)(lds + (bufoff) + ldsw + _i * 8192), 16, 0, 0); } while (0)
; #define PG8_LDA(dst, b, h) do { _Pragma("unroll") for (int m = 0; m < 4; ++m) _Pragma("unroll") for (int k = 0; k < 2; ++k) dst[m][k] = *(const LAS bf16x8*)(lds + PG8_SA(b, h) + aoff + m * 2048 + k * 1024); } while (0)
; #define PG8_LDB(dst, b, h) do { _Pragma("unroll") for (int n = 0; n < 2; ++n) _Pragma("unroll") for (int k = 0; k < 2; ++k) dst[n][k] = *(const LAS bf16x8*)(lds + PG8_SB(b, h) + boff + n * 2048 + k * 1024); } while (0)
; #define PG8_MMA(ai, bj, At, Bt) do { __builtin_amdgcn_s_setprio(1); _Pragma("unroll") for (int m = 0; m < 4; ++m) _Pragma("unroll") for (int n = 0; n < 2; ++n) _Pragma("unroll") for (int k = 0; k < 2; ++k) \
;         acc[ai][bj][m][n] = __builtin_amdgcn_mfma_f32_16x16x32_bf16(Bt[n][k], At[m][k], acc[ai][bj][m][n], 0, 0, 0); __builtin_amdgcn_s_setprio(0); } while (0)
; #define PG8_BAR __builtin_amdgcn_s_barrier()
; template <class Epi, class Sched, bool ABLK = false, bool ALIGN_EPI = true, bool SP2 = true, bool BBLK = true>
; __device__ __forceinline__ void gemm_phase(LAS unsigned char* lds, const Gemm g, const Sched& S, const Epi& E) {
;     ...
;             PG8_LDB(B0, 0, 0); PG8_LDB(B1, 0, 1); PG8_SCHED; PG8_LDA(At, 0, 0); PG8_STAGE(PG8_SA(1, 1), a1 + hstepA, voffA);
;             PG8_WAIT_V(8); PG8_WAIT_L(0); PG8_BAR; PG8_MMA(0, 0, At, B0); PG8_MMA(0, 1, At, B1); PG8_BAR; PG8_SCHED;
;             PG8_LDA(At, 0, 1); PG8_STAGE(PG8_SB(0, 0), b2, voffB); PG8_STAGE(PG8_SB(0, 1), b2 + hstepB, voffB); PG8_STAGE(PG8_SA(0, 0), a2, voffA);
;             PG8_WAIT_V(8); PG8_WAIT_L(0); PG8_BAR; PG8_MMA(1, 0, At, B0); PG8_MMA(1, 1, At, B1); PG8_BAR; PG8_SCHED;
;             PG8_LDB(B0, 1, 0); PG8_LDB(B1, 1, 1); PG8_SCHED; PG8_LDA(At, 1, 0); PG8_STAGE(PG8_SA(0, 1), a2 + hstepA, voffA);
;             PG8_WAIT_V(8); PG8_WAIT_L(0); PG8_BAR; PG8_MMA(0, 0, At, B0); PG8_MMA(0, 1, At, B1); PG8_BAR; PG8_SCHED;
;             PG8_LDA(At, 1, 1); PG8_STAGE(PG8_SB(1, 0), b3, voffB); PG8_STAGE(PG8_SB(1, 1), b3 + hstepB, voffB); PG8_STAGE(PG8_SA(1, 0), a3, voffA);
;             PG8_WAIT_V(8); PG8_WAIT_L(0); PG8_BAR; PG8_MMA(1, 0, At, B0); PG8_MMA(1, 1, At, B1); PG8_BAR; PG8_SCHED;
	s_add_u32 s36, s34, 0x8000
	s_addc_u32 s37, s35, 0
	s_add_i32 s67, s60, s42
	s_mov_b32 m0, s67
	ds_read_b128 v[204:207], v171 offset:49152
	ds_read_b128 v[208:211], v171 offset:50176
	ds_read_b128 v[212:215], v171 offset:51200
	ds_read_b128 v[216:219], v171 offset:52224
	global_load_lds_dwordx4 v134, s[36:37]
	s_add_i32 m0, s67, 0x2000
	s_add_u32 s34, s34, 0xc000
	v_lshl_add_u64 v[236:237], s[36:37], 0, v[130:131]
	s_addc_u32 s35, s35, 0
	s_add_i32 s36, s61, s42
	global_load_lds_dwordx4 v[236:237], off
	s_mov_b32 m0, s36
	ds_read_b128 v[220:223], v171 offset:53248
	global_load_lds_dwordx4 v134, s[34:35]
	s_add_i32 m0, s36, 0x2000
	ds_read_b128 v[224:227], v171 offset:54272
	global_load_lds_dwordx4 v130, s[34:35]
	s_mov_b32 m0, s48
	ds_read_b128 v[228:231], v171 offset:55296
	global_load_lds_dwordx4 v136, s[30:31]
	s_mov_b32 m0, s49
	ds_read_b128 v[232:235], v171 offset:56320
	global_load_lds_dwordx4 v132, s[30:31]
	s_waitcnt vmcnt(8) lgkmcnt(0)
	s_barrier
	v_mfma_f32_16x16x32_bf16 v[62:65], v[172:175], v[204:207], v[62:65]
	v_mfma_f32_16x16x32_bf16 v[58:61], v[180:183], v[204:207], v[58:61]
	v_mfma_f32_16x16x32_bf16 v[46:49], v[172:175], v[212:215], v[46:49]
	v_mfma_f32_16x16x32_bf16 v[42:45], v[180:183], v[212:215], v[42:45]
	v_mfma_f32_16x16x32_bf16 v[30:33], v[172:175], v[220:223], v[30:33]
	v_mfma_f32_16x16x32_bf16 v[26:29], v[180:183], v[220:223], v[26:29]
	v_mfma_f32_16x16x32_bf16 v[14:17], v[172:175], v[228:231], v[14:17]
	v_mfma_f32_16x16x32_bf16 v[10:13], v[180:183], v[228:231], v[10:13]
	v_mfma_f32_16x16x32_bf16 v[62:65], v[176:179], v[208:211], v[62:65]
	v_mfma_f32_16x16x32_bf16 v[58:61], v[184:187], v[208:211], v[58:61]
	v_mfma_f32_16x16x32_bf16 v[46:49], v[176:179], v[216:219], v[46:49]
	v_mfma_f32_16x16x32_bf16 v[42:45], v[184:187], v[216:219], v[42:45]
	v_mfma_f32_16x16x32_bf16 v[30:33], v[176:179], v[224:227], v[30:33]
	v_mfma_f32_16x16x32_bf16 v[26:29], v[184:187], v[224:227], v[26:29]
	v_mfma_f32_16x16x32_bf16 v[14:17], v[176:179], v[232:235], v[14:17]
	v_mfma_f32_16x16x32_bf16 v[10:13], v[184:187], v[232:235], v[10:13]
	v_mfma_f32_16x16x32_bf16 v[54:57], v[188:191], v[204:207], v[54:57]
	v_mfma_f32_16x16x32_bf16 v[50:53], v[196:199], v[204:207], v[50:53]
	v_mfma_f32_16x16x32_bf16 v[38:41], v[188:191], v[212:215], v[38:41]
	v_mfma_f32_16x16x32_bf16 v[34:37], v[196:199], v[212:215], v[34:37]
	v_mfma_f32_16x16x32_bf16 v[22:25], v[188:191], v[220:223], v[22:25]
	v_mfma_f32_16x16x32_bf16 v[18:21], v[196:199], v[220:223], v[18:21]
	v_mfma_f32_16x16x32_bf16 v[6:9], v[188:191], v[228:231], v[6:9]
	v_mfma_f32_16x16x32_bf16 v[2:5], v[196:199], v[228:231], v[2:5]
	v_mfma_f32_16x16x32_bf16 v[54:57], v[192:195], v[208:211], v[54:57]
	v_mfma_f32_16x16x32_bf16 v[50:53], v[200:203], v[208:211], v[50:53]
	v_mfma_f32_16x16x32_bf16 v[38:41], v[192:195], v[216:219], v[38:41]
	v_mfma_f32_16x16x32_bf16 v[34:37], v[200:203], v[216:219], v[34:37]
	v_mfma_f32_16x16x32_bf16 v[22:25], v[192:195], v[224:227], v[22:25]
	v_mfma_f32_16x16x32_bf16 v[18:21], v[200:203], v[224:227], v[18:21]
	v_mfma_f32_16x16x32_bf16 v[6:9], v[192:195], v[232:235], v[6:9]
	v_mfma_f32_16x16x32_bf16 v[2:5], v[200:203], v[232:235], v[2:5]
	s_barrier
	s_add_i32 s66, s66, 2
	s_add_u32 s28, s28, 0x100
	s_addc_u32 s29, s29, 0
	s_add_u32 s64, s64, 0x10000
	s_addc_u32 s65, s65, 0
	s_cmp_gt_u32 s66, 29
.LBB0_1164:
	ds_read_b128 v[172:175], v169
	ds_read_b128 v[176:179], v169 offset:1024
	ds_read_b128 v[180:183], v169 offset:2048
	ds_read_b128 v[184:187], v169 offset:3072
	ds_read_b128 v[188:191], v170
	ds_read_b128 v[192:195], v170 offset:1024
	ds_read_b128 v[196:199], v170 offset:2048
	ds_read_b128 v[200:203], v170 offset:3072
	s_add_u32 s30, s26, s28
	s_addc_u32 s31, s27, s29
	s_add_u32 s36, s30, 0x100
	s_addc_u32 s37, s31, 0
	s_add_u32 s30, s30, 0x180
	s_addc_u32 s31, s31, 0
	s_cmpk_eq_i32 s28, 0xf00
	s_cselect_b32 s31, s57, s31
	s_cselect_b32 s30, s23, s30
	s_cselect_b32 s35, s11, s65
	s_cselect_b32 s34, s15, s64
	s_cselect_b32 s37, s4, s37
	s_cselect_b32 s36, s5, s36
	s_mov_b32 m0, s50
	v_lshl_add_u64 v[236:237], v[164:165], 0, s[28:29]
	ds_read_b128 v[204:207], v171
	ds_read_b128 v[208:211], v171 offset:1024
	ds_read_b128 v[212:215], v171 offset:2048
	ds_read_b128 v[216:219], v171 offset:3072
	ds_read_b128 v[220:223], v171 offset:4096
	ds_read_b128 v[224:227], v171 offset:5120
	ds_read_b128 v[228:231], v171 offset:6144
	global_load_lds_dwordx4 v[236:237], off
	v_lshl_add_u64 v[236:237], v[166:167], 0, s[28:29]
	s_mov_b32 m0, s51
	ds_read_b128 v[232:235], v171 offset:7168
	global_load_lds_dwordx4 v[236:237], off
	s_waitcnt vmcnt(8) lgkmcnt(0)
	s_barrier
; #define PG8_STAGE(bufoff, gbase, voff) do { _Pragma("unroll") for (int _i = 0; _i < 2; ++_i) \
;         __builtin_amdgcn_global_load_lds((const unsigned*)((const char*)(gbase) + (voff)[_i]), (LAS unsigned*)(lds + (bufoff) + ldsw + _i * 8192), 16, 0, 0); } while (0)
; #define PG8_LDA(dst, b, h) do { _Pragma("unroll") for (int m = 0; m < 4; ++m) _Pragma("unroll") for (int k = 0; k < 2; ++k) dst[m][k] = *(const LAS bf16x8*)(lds + PG8_SA(b, h) + aoff + m * 2048 + k * 1024); } while (0)
; #define PG8_LDB(dst, b, h) do { _Pragma("unroll") for (int n = 0; n < 2; ++n) _Pragma("unroll") for (int k = 0; k < 2; ++k) dst[n][k] = *(const LAS bf16x8*)(lds + PG8_SB(b, h) + boff + n * 2048 + k * 1024); } while (0)
; #define PG8_MMA(ai, bj, At, Bt) do { __builtin_amdgcn_s_setprio(1); _Pragma("unroll") for (int m = 0; m < 4; ++m) _Pragma("unroll") for (int n = 0; n < 2; ++n) _Pragma("unroll") for (int k = 0; k < 2; ++k) \
;         acc[ai][bj][m][n] = __builtin_amdgcn_mfma_f32_16x16x32_bf16(Bt[n][k], At[m][k], acc[ai][bj][m][n], 0, 0, 0); __builtin_amdgcn_s_setprio(0); } while (0)
; #define PG8_WAIT_V(n) asm volatile("s_waitcnt vmcnt(" #n ")" ::: "memory")
; #define PG8_WAIT_L(n) asm volatile("s_waitcnt lgkmcnt(" #n ")" ::: "memory")
; #define PG8_BAR __builtin_amdgcn_s_barrier()
; #define PG8_SCHED __builtin_amdgcn_sched_barrier(0)
; template <class Epi, class Sched, bool ABLK = false, bool ALIGN_EPI = true, bool SP2 = true, bool BBLK = true>
; __device__ __forceinline__ void gemm_phase(LAS unsigned char* lds, const Gemm g, const Sched& S, const Epi& E) {
;     ...
;             PG8_WAIT_V(8); PG8_WAIT_L(0); PG8_BAR; PG8_MMA(0, 0, At, B0); PG8_MMA(0, 1, At, B1); PG8_BAR; PG8_SCHED;
;             PG8_LDA(At, 0, 1); PG8_STAGE(PG8_SB(0, 0), b2, voffB); PG8_STAGE(PG8_SB(0, 1), b2 + hstepB, voffB); PG8_STAGE(PG8_SA(0, 0), a2, voffA);
;             PG8_WAIT_V(8); PG8_WAIT_L(0); PG8_BAR; PG8_MMA(1, 0, At, B0); PG8_MMA(1, 1, At, B1); PG8_BAR; PG8_SCHED;
;             PG8_LDB(B0, 1, 0); PG8_LDB(B1, 1, 1); PG8_SCHED; PG8_LDA(At, 1, 0); PG8_STAGE(PG8_SA(0, 1), a2 + hstepA, voffA);
	v_mfma_f32_16x16x32_bf16 v[126:129], v[172:175], v[204:207], v[126:129]
	v_mfma_f32_16x16x32_bf16 v[122:125], v[180:183], v[204:207], v[122:125]
	v_mfma_f32_16x16x32_bf16 v[110:113], v[172:175], v[212:215], v[110:113]
	v_mfma_f32_16x16x32_bf16 v[106:109], v[180:183], v[212:215], v[106:109]
	v_mfma_f32_16x16x32_bf16 v[94:97], v[172:175], v[220:223], v[94:97]
	v_mfma_f32_16x16x32_bf16 v[90:93], v[180:183], v[220:223], v[90:93]
	v_mfma_f32_16x16x32_bf16 v[78:81], v[172:175], v[228:231], v[78:81]
	v_mfma_f32_16x16x32_bf16 v[74:77], v[180:183], v[228:231], v[74:77]
	v_mfma_f32_16x16x32_bf16 v[126:129], v[176:179], v[208:211], v[126:129]
	v_mfma_f32_16x16x32_bf16 v[122:125], v[184:187], v[208:211], v[122:125]
	v_mfma_f32_16x16x32_bf16 v[110:113], v[176:179], v[216:219], v[110:113]
	v_mfma_f32_16x16x32_bf16 v[106:109], v[184:187], v[216:219], v[106:109]
	v_mfma_f32_16x16x32_bf16 v[94:97], v[176:179], v[224:227], v[94:97]
	v_mfma_f32_16x16x32_bf16 v[90:93], v[184:187], v[224:227], v[90:93]
	v_mfma_f32_16x16x32_bf16 v[78:81], v[176:179], v[232:235], v[78:81]
	v_mfma_f32_16x16x32_bf16 v[74:77], v[184:187], v[232:235], v[74:77]
	v_mfma_f32_16x16x32_bf16 v[118:121], v[188:191], v[204:207], v[118:121]
	v_mfma_f32_16x16x32_bf16 v[114:117], v[196:199], v[204:207], v[114:117]
	v_mfma_f32_16x16x32_bf16 v[102:105], v[188:191], v[212:215], v[102:105]
	v_mfma_f32_16x16x32_bf16 v[98:101], v[196:199], v[212:215], v[98:101]
	v_mfma_f32_16x16x32_bf16 v[86:89], v[188:191], v[220:223], v[86:89]
	v_mfma_f32_16x16x32_bf16 v[82:85], v[196:199], v[220:223], v[82:85]
	v_mfma_f32_16x16x32_bf16 v[70:73], v[188:191], v[228:231], v[70:73]
	v_mfma_f32_16x16x32_bf16 v[66:69], v[196:199], v[228:231], v[66:69]
	v_mfma_f32_16x16x32_bf16 v[118:121], v[192:195], v[208:211], v[118:121]
	v_mfma_f32_16x16x32_bf16 v[114:117], v[200:203], v[208:211], v[114:117]
	v_mfma_f32_16x16x32_bf16 v[102:105], v[192:195], v[216:219], v[102:105]
	v_mfma_f32_16x16x32_bf16 v[98:101], v[200:203], v[216:219], v[98:101]
	v_mfma_f32_16x16x32_bf16 v[86:89], v[192:195], v[224:227], v[86:89]
	v_mfma_f32_16x16x32_bf16 v[82:85], v[200:203], v[224:227], v[82:85]
	v_mfma_f32_16x16x32_bf16 v[70:73], v[192:195], v[232:235], v[70:73]
	v_mfma_f32_16x16x32_bf16 v[66:69], v[200:203], v[232:235], v[66:69]
	s_barrier
	s_mov_b32 m0, s55
	s_add_u32 s76, s34, 0x4000
	ds_read_b128 v[204:207], v171 offset:16384
	ds_read_b128 v[208:211], v171 offset:17408
	ds_read_b128 v[212:215], v171 offset:18432
	ds_read_b128 v[216:219], v171 offset:19456
	global_load_lds_dwordx4 v134, s[34:35]
	s_mov_b32 m0, s56
	s_addc_u32 s77, s35, 0
	s_add_i32 s67, s73, s42
	global_load_lds_dwordx4 v130, s[34:35]
	s_mov_b32 m0, s67
	ds_read_b128 v[220:223], v171 offset:20480
	global_load_lds_dwordx4 v134, s[76:77]
	s_add_i32 m0, s67, 0x2000
	ds_read_b128 v[224:227], v171 offset:21504
	global_load_lds_dwordx4 v130, s[76:77]
	s_mov_b32 m0, s25
	ds_read_b128 v[228:231], v171 offset:22528
	global_load_lds_dwordx4 v136, s[36:37]
	s_mov_b32 m0, s43
	ds_read_b128 v[232:235], v171 offset:23552
	global_load_lds_dwordx4 v132, s[36:37]
	s_waitcnt vmcnt(8) lgkmcnt(0)
	s_barrier
	v_mfma_f32_16x16x32_bf16 v[62:65], v[172:175], v[204:207], v[62:65]
	v_mfma_f32_16x16x32_bf16 v[58:61], v[180:183], v[204:207], v[58:61]
	v_mfma_f32_16x16x32_bf16 v[46:49], v[172:175], v[212:215], v[46:49]
	v_mfma_f32_16x16x32_bf16 v[42:45], v[180:183], v[212:215], v[42:45]
	v_mfma_f32_16x16x32_bf16 v[30:33], v[172:175], v[220:223], v[30:33]
	v_mfma_f32_16x16x32_bf16 v[26:29], v[180:183], v[220:223], v[26:29]
	v_mfma_f32_16x16x32_bf16 v[14:17], v[172:175], v[228:231], v[14:17]
	v_mfma_f32_16x16x32_bf16 v[10:13], v[180:183], v[228:231], v[10:13]
	v_mfma_f32_16x16x32_bf16 v[62:65], v[176:179], v[208:211], v[62:65]
	v_mfma_f32_16x16x32_bf16 v[58:61], v[184:187], v[208:211], v[58:61]
	v_mfma_f32_16x16x32_bf16 v[46:49], v[176:179], v[216:219], v[46:49]
	v_mfma_f32_16x16x32_bf16 v[42:45], v[184:187], v[216:219], v[42:45]
	v_mfma_f32_16x16x32_bf16 v[30:33], v[176:179], v[224:227], v[30:33]
	v_mfma_f32_16x16x32_bf16 v[26:29], v[184:187], v[224:227], v[26:29]
	v_mfma_f32_16x16x32_bf16 v[14:17], v[176:179], v[232:235], v[14:17]
	v_mfma_f32_16x16x32_bf16 v[10:13], v[184:187], v[232:235], v[10:13]
	v_mfma_f32_16x16x32_bf16 v[54:57], v[188:191], v[204:207], v[54:57]
	v_mfma_f32_16x16x32_bf16 v[50:53], v[196:199], v[204:207], v[50:53]
	v_mfma_f32_16x16x32_bf16 v[38:41], v[188:191], v[212:215], v[38:41]
	v_mfma_f32_16x16x32_bf16 v[34:37], v[196:199], v[212:215], v[34:37]
	v_mfma_f32_16x16x32_bf16 v[22:25], v[188:191], v[220:223], v[22:25]
	v_mfma_f32_16x16x32_bf16 v[18:21], v[196:199], v[220:223], v[18:21]
	v_mfma_f32_16x16x32_bf16 v[6:9], v[188:191], v[228:231], v[6:9]
	v_mfma_f32_16x16x32_bf16 v[2:5], v[196:199], v[228:231], v[2:5]
	v_mfma_f32_16x16x32_bf16 v[54:57], v[192:195], v[208:211], v[54:57]
	v_mfma_f32_16x16x32_bf16 v[50:53], v[200:203], v[208:211], v[50:53]
	v_mfma_f32_16x16x32_bf16 v[38:41], v[192:195], v[216:219], v[38:41]
	v_mfma_f32_16x16x32_bf16 v[34:37], v[200:203], v[216:219], v[34:37]
	v_mfma_f32_16x16x32_bf16 v[22:25], v[192:195], v[224:227], v[22:25]
	v_mfma_f32_16x16x32_bf16 v[18:21], v[200:203], v[224:227], v[18:21]
	v_mfma_f32_16x16x32_bf16 v[6:9], v[192:195], v[232:235], v[6:9]
	v_mfma_f32_16x16x32_bf16 v[2:5], v[200:203], v[232:235], v[2:5]
	s_barrier
; #define PG8_STAGE(bufoff, gbase, voff) do { _Pragma("unroll") for (int _i = 0; _i < 2; ++_i) \
;         __builtin_amdgcn_global_load_lds((const unsigned*)((const char*)(gbase) + (voff)[_i]), (LAS unsigned*)(lds + (bufoff) + ldsw + _i * 8192), 16, 0, 0); } while (0)
; #define PG8_LDA(dst, b, h) do { _Pragma("unroll") for (int m = 0; m < 4; ++m) _Pragma("unroll") for (int k = 0; k < 2; ++k) dst[m][k] = *(const LAS bf16x8*)(lds + PG8_SA(b, h) + aoff + m * 2048 + k * 1024); } while (0)
; #define PG8_LDB(dst, b, h) do { _Pragma("unroll") for (int n = 0; n < 2; ++n) _Pragma("unroll") for (int k = 0; k < 2; ++k) dst[n][k] = *(const LAS bf16x8*)(lds + PG8_SB(b, h) + boff + n * 2048 + k * 1024); } while (0)
; #define PG8_MMA(ai, bj, At, Bt) do { __builtin_amdgcn_s_setprio(1); _Pragma("unroll") for (int m = 0; m < 4; ++m) _Pragma("unroll") for (int n = 0; n < 2; ++n) _Pragma("unroll") for (int k = 0; k < 2; ++k) \
;         acc[ai][bj][m][n] = __builtin_amdgcn_mfma_f32_16x16x32_bf16(Bt[n][k], At[m][k], acc[ai][bj][m][n], 0, 0, 0); __builtin_amdgcn_s_setprio(0); } while (0)
; #define PG8_WAIT_V(n) asm volatile("s_waitcnt vmcnt(" #n ")" ::: "memory")
; #define PG8_WAIT_L(n) asm volatile("s_waitcnt lgkmcnt(" #n ")" ::: "memory")
; #define PG8_BAR __builtin_amdgcn_s_barrier()
; #define PG8_SCHED __builtin_amdgcn_sched_barrier(0)
; template <class Epi, class Sched, bool ABLK = false, bool ALIGN_EPI = true, bool SP2 = true, bool BBLK = true>
; __device__ __forceinline__ void gemm_phase(LAS unsigned char* lds, const Gemm g, const Sched& S, const Epi& E) {
;     ...
;             PG8_LDB(B0, 1, 0); PG8_LDB(B1, 1, 1); PG8_SCHED; PG8_LDA(At, 1, 0); PG8_STAGE(PG8_SA(0, 1), a2 + hstepA, voffA);
;             PG8_WAIT_V(8); PG8_WAIT_L(0); PG8_BAR; PG8_MMA(0, 0, At, B0); PG8_MMA(0, 1, At, B1); PG8_BAR; PG8_SCHED;
;             PG8_LDA(At, 1, 1); PG8_STAGE(PG8_SB(1, 0), b3, voffB); PG8_STAGE(PG8_SB(1, 1), b3 + hstepB, voffB); PG8_STAGE(PG8_SA(1, 0), a3, voffA);
;             PG8_WAIT_V(8); PG8_WAIT_L(0); PG8_BAR; PG8_MMA(1, 0, At, B0); PG8_MMA(1, 1, At, B1); PG8_BAR; PG8_SCHED;
;     ...
;         if constexpr (ALIGN_EPI) { if (wr == 0) PG8_BAR; }
	v_add_u32_e32 v184, s60, v168
	v_add_u32_e32 v200, s61, v168
	ds_read_b128 v[172:175], v184
	ds_read_b128 v[176:179], v184 offset:1024
	ds_read_b128 v[180:183], v184 offset:2048
	ds_read_b128 v[184:187], v184 offset:3072
	ds_read_b128 v[188:191], v200
	ds_read_b128 v[192:195], v200 offset:1024
	ds_read_b128 v[196:199], v200 offset:2048
	ds_read_b128 v[200:203], v200 offset:3072
	s_add_u32 s36, s36, 0x80000
	s_addc_u32 s37, s37, 0
	s_mov_b32 m0, s44
	ds_read_b128 v[204:207], v171 offset:32768
	ds_read_b128 v[208:211], v171 offset:33792
	ds_read_b128 v[212:215], v171 offset:34816
	ds_read_b128 v[216:219], v171 offset:35840
	ds_read_b128 v[220:223], v171 offset:36864
	ds_read_b128 v[224:227], v171 offset:37888
	ds_read_b128 v[228:231], v171 offset:38912
	global_load_lds_dwordx4 v136, s[36:37]
	s_mov_b32 m0, s45
	ds_read_b128 v[232:235], v171 offset:39936
	global_load_lds_dwordx4 v132, s[36:37]
	s_waitcnt vmcnt(8) lgkmcnt(0)
	s_barrier
	v_mfma_f32_16x16x32_bf16 v[126:129], v[172:175], v[204:207], v[126:129]
	v_mfma_f32_16x16x32_bf16 v[122:125], v[180:183], v[204:207], v[122:125]
	v_mfma_f32_16x16x32_bf16 v[110:113], v[172:175], v[212:215], v[110:113]
	v_mfma_f32_16x16x32_bf16 v[106:109], v[180:183], v[212:215], v[106:109]
	v_mfma_f32_16x16x32_bf16 v[94:97], v[172:175], v[220:223], v[94:97]
	v_mfma_f32_16x16x32_bf16 v[90:93], v[180:183], v[220:223], v[90:93]
	v_mfma_f32_16x16x32_bf16 v[78:81], v[172:175], v[228:231], v[78:81]
	v_mfma_f32_16x16x32_bf16 v[74:77], v[180:183], v[228:231], v[74:77]
	v_mfma_f32_16x16x32_bf16 v[126:129], v[176:179], v[208:211], v[126:129]
	v_mfma_f32_16x16x32_bf16 v[122:125], v[184:187], v[208:211], v[122:125]
	v_mfma_f32_16x16x32_bf16 v[110:113], v[176:179], v[216:219], v[110:113]
	v_mfma_f32_16x16x32_bf16 v[106:109], v[184:187], v[216:219], v[106:109]
	v_mfma_f32_16x16x32_bf16 v[94:97], v[176:179], v[224:227], v[94:97]
	v_mfma_f32_16x16x32_bf16 v[90:93], v[184:187], v[224:227], v[90:93]
	v_mfma_f32_16x16x32_bf16 v[78:81], v[176:179], v[232:235], v[78:81]
	v_mfma_f32_16x16x32_bf16 v[74:77], v[184:187], v[232:235], v[74:77]
	v_mfma_f32_16x16x32_bf16 v[118:121], v[188:191], v[204:207], v[118:121]
	v_mfma_f32_16x16x32_bf16 v[114:117], v[196:199], v[204:207], v[114:117]
	v_mfma_f32_16x16x32_bf16 v[102:105], v[188:191], v[212:215], v[102:105]
	v_mfma_f32_16x16x32_bf16 v[98:101], v[196:199], v[212:215], v[98:101]
	v_mfma_f32_16x16x32_bf16 v[86:89], v[188:191], v[220:223], v[86:89]
	v_mfma_f32_16x16x32_bf16 v[82:85], v[196:199], v[220:223], v[82:85]
	v_mfma_f32_16x16x32_bf16 v[70:73], v[188:191], v[228:231], v[70:73]
	v_mfma_f32_16x16x32_bf16 v[66:69], v[196:199], v[228:231], v[66:69]
	v_mfma_f32_16x16x32_bf16 v[118:121], v[192:195], v[208:211], v[118:121]
	v_mfma_f32_16x16x32_bf16 v[114:117], v[200:203], v[208:211], v[114:117]
	v_mfma_f32_16x16x32_bf16 v[102:105], v[192:195], v[216:219], v[102:105]
	v_mfma_f32_16x16x32_bf16 v[98:101], v[200:203], v[216:219], v[98:101]
	v_mfma_f32_16x16x32_bf16 v[86:89], v[192:195], v[224:227], v[86:89]
	v_mfma_f32_16x16x32_bf16 v[82:85], v[200:203], v[224:227], v[82:85]
	v_mfma_f32_16x16x32_bf16 v[70:73], v[192:195], v[232:235], v[70:73]
	v_mfma_f32_16x16x32_bf16 v[66:69], v[200:203], v[232:235], v[66:69]
	s_barrier
	s_add_u32 s36, s34, 0x8000
	s_addc_u32 s37, s35, 0
	s_add_i32 s67, s60, s42
	s_mov_b32 m0, s67
	ds_read_b128 v[204:207], v171 offset:49152
	ds_read_b128 v[208:211], v171 offset:50176
	ds_read_b128 v[212:215], v171 offset:51200
	ds_read_b128 v[216:219], v171 offset:52224
	global_load_lds_dwordx4 v134, s[36:37]
	s_add_i32 m0, s67, 0x2000
	s_add_u32 s34, s34, 0xc000
	v_lshl_add_u64 v[236:237], s[36:37], 0, v[130:131]
	s_addc_u32 s35, s35, 0
	s_add_i32 s36, s61, s42
	global_load_lds_dwordx4 v[236:237], off
	s_mov_b32 m0, s36
	ds_read_b128 v[220:223], v171 offset:53248
	global_load_lds_dwordx4 v134, s[34:35]
	s_add_i32 m0, s36, 0x2000
	ds_read_b128 v[224:227], v171 offset:54272
	global_load_lds_dwordx4 v130, s[34:35]
	s_mov_b32 m0, s48
	ds_read_b128 v[228:231], v171 offset:55296
	global_load_lds_dwordx4 v136, s[30:31]
	s_mov_b32 m0, s49
	ds_read_b128 v[232:235], v171 offset:56320
	global_load_lds_dwordx4 v132, s[30:31]
	s_waitcnt vmcnt(8) lgkmcnt(0)
	s_barrier
	v_mfma_f32_16x16x32_bf16 v[62:65], v[172:175], v[204:207], v[62:65]
	v_mfma_f32_16x16x32_bf16 v[58:61], v[180:183], v[204:207], v[58:61]
	v_mfma_f32_16x16x32_bf16 v[46:49], v[172:175], v[212:215], v[46:49]
	v_mfma_f32_16x16x32_bf16 v[42:45], v[180:183], v[212:215], v[42:45]
	v_mfma_f32_16x16x32_bf16 v[30:33], v[172:175], v[220:223], v[30:33]
	v_mfma_f32_16x16x32_bf16 v[26:29], v[180:183], v[220:223], v[26:29]
	v_mfma_f32_16x16x32_bf16 v[14:17], v[172:175], v[228:231], v[14:17]
	v_mfma_f32_16x16x32_bf16 v[10:13], v[180:183], v[228:231], v[10:13]
	v_mfma_f32_16x16x32_bf16 v[62:65], v[176:179], v[208:211], v[62:65]
	v_mfma_f32_16x16x32_bf16 v[58:61], v[184:187], v[208:211], v[58:61]
	v_mfma_f32_16x16x32_bf16 v[46:49], v[176:179], v[216:219], v[46:49]
	v_mfma_f32_16x16x32_bf16 v[42:45], v[184:187], v[216:219], v[42:45]
	v_mfma_f32_16x16x32_bf16 v[30:33], v[176:179], v[224:227], v[30:33]
	v_mfma_f32_16x16x32_bf16 v[26:29], v[184:187], v[224:227], v[26:29]
	v_mfma_f32_16x16x32_bf16 v[14:17], v[176:179], v[232:235], v[14:17]
	v_mfma_f32_16x16x32_bf16 v[10:13], v[184:187], v[232:235], v[10:13]
	v_mfma_f32_16x16x32_bf16 v[54:57], v[188:191], v[204:207], v[54:57]
	v_mfma_f32_16x16x32_bf16 v[50:53], v[196:199], v[204:207], v[50:53]
	v_mfma_f32_16x16x32_bf16 v[38:41], v[188:191], v[212:215], v[38:41]
	v_mfma_f32_16x16x32_bf16 v[34:37], v[196:199], v[212:215], v[34:37]
	v_mfma_f32_16x16x32_bf16 v[22:25], v[188:191], v[220:223], v[22:25]
	v_mfma_f32_16x16x32_bf16 v[18:21], v[196:199], v[220:223], v[18:21]
	v_mfma_f32_16x16x32_bf16 v[6:9], v[188:191], v[228:231], v[6:9]
	v_mfma_f32_16x16x32_bf16 v[2:5], v[196:199], v[228:231], v[2:5]
	v_mfma_f32_16x16x32_bf16 v[54:57], v[192:195], v[208:211], v[54:57]
	v_mfma_f32_16x16x32_bf16 v[50:53], v[200:203], v[208:211], v[50:53]
	v_mfma_f32_16x16x32_bf16 v[38:41], v[192:195], v[216:219], v[38:41]
	v_mfma_f32_16x16x32_bf16 v[34:37], v[200:203], v[216:219], v[34:37]
	v_mfma_f32_16x16x32_bf16 v[22:25], v[192:195], v[224:227], v[22:25]
	v_mfma_f32_16x16x32_bf16 v[18:21], v[200:203], v[224:227], v[18:21]
	v_mfma_f32_16x16x32_bf16 v[6:9], v[192:195], v[232:235], v[6:9]
	v_mfma_f32_16x16x32_bf16 v[2:5], v[200:203], v[232:235], v[2:5]
	s_barrier
	s_add_i32 s66, s66, 2
	s_add_u32 s28, s28, 0x100
	s_addc_u32 s29, s29, 0
	s_add_u32 s64, s64, 0x10000
	s_addc_u32 s65, s65, 0
	s_cmp_gt_u32 s66, 29
	s_cbranch_scc0 .LBB0_1164
	s_and_b64 vcc, exec, s[6:7]
	s_cbranch_vccz .LBB0_1167
	s_barrier

; #define PG8_STAGE(bufoff, gbase, voff) do { _Pragma("unroll") for (int _i = 0; _i < 2; ++_i) \
;         __builtin_amdgcn_global_load_lds((const unsigned*)((const char*)(gbase) + (voff)[_i]), (LAS unsigned*)(lds + (bufoff) + ldsw + _i * 8192), 16, 0, 0); } while (0)
; #define PG8_LDA(dst, b, h) do { _Pragma("unroll") for (int m = 0; m < 4; ++m) _Pragma("unroll") for (int k = 0; k < 2; ++k) dst[m][k] = *(const LAS bf16x8*)(lds + PG8_SA(b, h) + aoff + m * 2048 + k * 1024); } while (0)
; #define PG8_LDB(dst, b, h) do { _Pragma("unroll") for (int n = 0; n < 2; ++n) _Pragma("unroll") for (int k = 0; k < 2; ++k) dst[n][k] = *(const LAS bf16x8*)(lds + PG8_SB(b, h) + boff + n * 2048 + k * 1024); } while (0)
; #define PG8_WAIT_V(n) asm volatile("s_waitcnt vmcnt(" #n ")" ::: "memory")
; #define PG8_WAIT_L(n) asm volatile("s_waitcnt lgkmcnt(" #n ")" ::: "memory")
; template <class Epi, class Sched, bool ABLK = false, bool ALIGN_EPI = true, bool SP2 = true, bool BBLK = true>
; __device__ __forceinline__ void gemm_phase(LAS unsigned char* lds, const Gemm g, const Sched& S, const Epi& E) {
;     ...
;         const bool has_next = S.next(ui + 1, nxt);
;         const int nt = cur.nt;
;         const char* nuA = has_next ? a_unit(nxt) : uA; const int ntbA = has_next ? nxt.k0 / BK : tbA; const char* nB = has_next ? (const char*)g.Bt + (size_t)nxt.pn * tstepB + b_k0(nxt.k0) : cB;
;         for (int t = 0; t < nt; t += 2) {
;             const bool last = (t == nt - 2);
;             const char* a1 = a_tile(uA, tbA + t + 1);
;             const char* a2 = last ? a_tile(nuA, ntbA) : a_tile(uA, tbA + t + 2); const char* b2 = last ? nB : cB + (size_t)(t + 2) * kstepB;
;             const char* a3 = last ? a_tile(nuA, ntbA + 1) : a_tile(uA, tbA + t + 3); const char* b3 = b2 + kstepB;
;             if (last && has_next) S.a_ready(nxt);
;             if constexpr (SP2) {
;             PG8_LDB(B0, 0, 0); PG8_LDB(B1, 0, 1); PG8_SCHED; PG8_LDA(At, 0, 0); PG8_STAGE(PG8_SA(1, 1), a1 + hstepA, voffA);
;             PG8_WAIT_V(8); PG8_WAIT_L(0); PG8_BAR; PG8_MMA(0, 0, At, B0); PG8_MMA(0, 1, At, B1); PG8_BAR; PG8_SCHED;
;             PG8_LDA(At, 0, 1); PG8_STAGE(PG8_SB(0, 0), b2, voffB); PG8_STAGE(PG8_SB(0, 1), b2 + hstepB, voffB); PG8_STAGE(PG8_SA(0, 0), a2, voffA);
;             PG8_WAIT_V(8); PG8_WAIT_L(0); PG8_BAR; PG8_MMA(1, 0, At, B0); PG8_MMA(1, 1, At, B1); PG8_BAR; PG8_SCHED;
.LBB0_1228:
	s_ashr_i32 s81, s80, 31
	s_andn2_b64 vcc, exec, s[4:5]
	s_lshl_b64 s[16:17], s[80:81], 22
	s_add_u32 s16, s1, s16
	s_addc_u32 s17, s33, s17
	s_and_b64 s[18:19], s[4:5], exec
	s_cselect_b32 s27, s17, s25
	s_cselect_b32 s46, s16, s24
	s_ashr_i32 s18, s0, 31
	s_lshr_b32 s18, s18, 26
	s_add_i32 s18, s0, s18
	s_ashr_i32 s18, s18, 6
	s_and_b64 s[20:21], s[4:5], exec
	s_cselect_b32 s28, s18, s26
	s_ashr_i32 s79, s78, 31
	s_lshl_b64 s[20:21], s[78:79], 22
	s_add_u32 s29, s30, s20
	s_addc_u32 s47, s31, s21
	s_ashr_i32 s19, s18, 31
	s_lshl_b64 s[20:21], s[18:19], 15
	s_add_u32 s20, s29, s20
	s_addc_u32 s21, s47, s21
	v_cndmask_b32_e64 v2, 0, 1, s[4:5]
	s_and_b64 s[4:5], s[4:5], exec
	s_cselect_b32 s4, s21, s23
	s_cselect_b32 s5, s20, s22
	s_ashr_i32 s29, s28, 31
	s_lshl_b64 s[28:29], s[28:29], 15
	s_add_u32 s19, s46, s28
	s_addc_u32 s46, s27, s29
	s_add_u32 s47, s19, 0x8000
	s_addc_u32 s48, s46, 0
	s_add_u32 s49, s22, 0x10000
	s_addc_u32 s50, s23, 0
	s_ashr_i32 s27, s26, 31
	v_cmp_ne_u32_e64 s[10:11], 1, v2
	s_lshl_b64 s[22:23], s[26:27], 15
	v_lshl_add_u64 v[2:3], s[24:25], 0, v[138:139]
	s_add_u32 s51, s24, s22
	v_lshl_add_u64 v[142:143], v[2:3], 0, s[22:23]
	v_lshl_add_u64 v[2:3], s[24:25], 0, v[140:141]
	s_addc_u32 s55, s25, s23
	v_lshl_add_u64 v[144:145], v[2:3], 0, s[22:23]
	s_lshl_b32 s22, s44, 15
	s_add_i32 s22, s22, 0xfff00000
	v_mov_b32_e32 v2, 0
	s_add_u32 s56, s22, 0xf0000
	s_mov_b32 s57, 0
	s_mov_b64 s[22:23], 0
	ds_read_b128 v[152:155], v149
	ds_read_b128 v[156:159], v149 offset:1024
	ds_read_b128 v[160:163], v149 offset:2048
	ds_read_b128 v[164:167], v149 offset:3072
	ds_read_b128 v[168:171], v150
	ds_read_b128 v[172:175], v150 offset:1024
	ds_read_b128 v[176:179], v150 offset:2048
	ds_read_b128 v[180:183], v150 offset:3072
	s_add_u32 s24, s51, s22
	s_addc_u32 s25, s55, s23
	s_add_u32 s28, s24, 0x10000
	s_addc_u32 s29, s25, 0
	s_add_i32 s57, s57, 2
	s_add_u32 s26, s49, s22
	s_addc_u32 s27, s50, s23
	s_add_u32 s24, s24, 0x18000
	s_addc_u32 s25, s25, 0
	s_cmp_eq_u32 s56, s22
	s_cselect_b32 s25, s48, s25
	s_cselect_b32 s24, s47, s24
	s_cselect_b32 s27, s4, s27
	s_cselect_b32 s26, s5, s26
	s_cselect_b32 s29, s46, s29
	s_cselect_b32 s28, s19, s28
	v_lshl_add_u64 v[216:217], v[142:143], 0, s[22:23]
	s_add_i32 m0, s35, 0xc000
	ds_read_b128 v[184:187], v151
	ds_read_b128 v[188:191], v151 offset:1024
	ds_read_b128 v[192:195], v151 offset:2048
	ds_read_b128 v[196:199], v151 offset:3072
	ds_read_b128 v[200:203], v151 offset:4096
	ds_read_b128 v[204:207], v151 offset:5120
	ds_read_b128 v[208:211], v151 offset:6144
	global_load_lds_dwordx4 v[216:217], off
	v_lshl_add_u64 v[216:217], v[144:145], 0, s[22:23]
	s_add_i32 m0, s35, 0xe000
	ds_read_b128 v[212:215], v151 offset:7168
	global_load_lds_dwordx4 v[216:217], off
	s_waitcnt vmcnt(8) lgkmcnt(0)
	s_barrier
	v_mfma_f32_16x16x32_bf16 v[126:129], v[152:155], v[184:187], 0
	v_mfma_f32_16x16x32_bf16 v[122:125], v[160:163], v[184:187], 0
	v_mfma_f32_16x16x32_bf16 v[110:113], v[152:155], v[192:195], 0
	v_mfma_f32_16x16x32_bf16 v[106:109], v[160:163], v[192:195], 0
	v_mfma_f32_16x16x32_bf16 v[94:97], v[152:155], v[200:203], 0
	v_mfma_f32_16x16x32_bf16 v[90:93], v[160:163], v[200:203], 0
	v_mfma_f32_16x16x32_bf16 v[78:81], v[152:155], v[208:211], 0
	v_mfma_f32_16x16x32_bf16 v[74:77], v[160:163], v[208:211], 0
	v_mfma_f32_16x16x32_bf16 v[126:129], v[156:159], v[188:191], v[126:129]
	v_mfma_f32_16x16x32_bf16 v[122:125], v[164:167], v[188:191], v[122:125]
	v_mfma_f32_16x16x32_bf16 v[110:113], v[156:159], v[196:199], v[110:113]
	v_mfma_f32_16x16x32_bf16 v[106:109], v[164:167], v[196:199], v[106:109]
	v_mfma_f32_16x16x32_bf16 v[94:97], v[156:159], v[204:207], v[94:97]
	v_mfma_f32_16x16x32_bf16 v[90:93], v[164:167], v[204:207], v[90:93]
	v_mfma_f32_16x16x32_bf16 v[78:81], v[156:159], v[212:215], v[78:81]
	v_mfma_f32_16x16x32_bf16 v[74:77], v[164:167], v[212:215], v[74:77]
	v_mfma_f32_16x16x32_bf16 v[118:121], v[168:171], v[184:187], 0
	v_mfma_f32_16x16x32_bf16 v[114:117], v[176:179], v[184:187], 0
	v_mfma_f32_16x16x32_bf16 v[102:105], v[168:171], v[192:195], 0
	v_mfma_f32_16x16x32_bf16 v[98:101], v[176:179], v[192:195], 0
	v_mfma_f32_16x16x32_bf16 v[86:89], v[168:171], v[200:203], 0
	v_mfma_f32_16x16x32_bf16 v[82:85], v[176:179], v[200:203], 0
	v_mfma_f32_16x16x32_bf16 v[70:73], v[168:171], v[208:211], 0
	v_mfma_f32_16x16x32_bf16 v[66:69], v[176:179], v[208:211], 0
	v_mfma_f32_16x16x32_bf16 v[118:121], v[172:175], v[188:191], v[118:121]
	v_mfma_f32_16x16x32_bf16 v[114:117], v[180:183], v[188:191], v[114:117]
	v_mfma_f32_16x16x32_bf16 v[102:105], v[172:175], v[196:199], v[102:105]
	v_mfma_f32_16x16x32_bf16 v[98:101], v[180:183], v[196:199], v[98:101]
	v_mfma_f32_16x16x32_bf16 v[86:89], v[172:175], v[204:207], v[86:89]
	v_mfma_f32_16x16x32_bf16 v[82:85], v[180:183], v[204:207], v[82:85]
	v_mfma_f32_16x16x32_bf16 v[70:73], v[172:175], v[212:215], v[70:73]
	v_mfma_f32_16x16x32_bf16 v[66:69], v[180:183], v[212:215], v[66:69]
	s_barrier
	s_add_i32 s59, s72, s34
	s_mov_b32 m0, s59
	ds_read_b128 v[184:187], v151 offset:16384
	ds_read_b128 v[188:191], v151 offset:17408
	ds_read_b128 v[192:195], v151 offset:18432
	ds_read_b128 v[196:199], v151 offset:19456
	global_load_lds_dwordx4 v130, s[26:27]
	s_add_i32 m0, s59, 0x2000
	s_add_u32 s64, s26, 0x4000
	s_addc_u32 s65, s27, 0
	s_add_i32 s59, s73, s34
	global_load_lds_dwordx4 v132, s[26:27]
	s_mov_b32 m0, s59
	ds_read_b128 v[200:203], v151 offset:20480
	global_load_lds_dwordx4 v130, s[64:65]
	s_add_i32 m0, s59, 0x2000
	ds_read_b128 v[204:207], v151 offset:21504
	global_load_lds_dwordx4 v132, s[64:65]
	s_mov_b32 m0, s35
	ds_read_b128 v[208:211], v151 offset:22528
	global_load_lds_dwordx4 v130, s[28:29]
	s_mov_b32 m0, s36
	ds_read_b128 v[212:215], v151 offset:23552
	global_load_lds_dwordx4 v132, s[28:29]
	s_waitcnt vmcnt(8) lgkmcnt(0)
	s_barrier
; #define PG8_STAGE(bufoff, gbase, voff) do { _Pragma("unroll") for (int _i = 0; _i < 2; ++_i) \
;         __builtin_amdgcn_global_load_lds((const unsigned*)((const char*)(gbase) + (voff)[_i]), (LAS unsigned*)(lds + (bufoff) + ldsw + _i * 8192), 16, 0, 0); } while (0)
; #define PG8_LDA(dst, b, h) do { _Pragma("unroll") for (int m = 0; m < 4; ++m) _Pragma("unroll") for (int k = 0; k < 2; ++k) dst[m][k] = *(const LAS bf16x8*)(lds + PG8_SA(b, h) + aoff + m * 2048 + k * 1024); } while (0)
; #define PG8_LDB(dst, b, h) do { _Pragma("unroll") for (int n = 0; n < 2; ++n) _Pragma("unroll") for (int k = 0; k < 2; ++k) dst[n][k] = *(const LAS bf16x8*)(lds + PG8_SB(b, h) + boff + n * 2048 + k * 1024); } while (0)
; #define PG8_MMA(ai, bj, At, Bt) do { __builtin_amdgcn_s_setprio(1); _Pragma("unroll") for (int m = 0; m < 4; ++m) _Pragma("unroll") for (int n = 0; n < 2; ++n) _Pragma("unroll") for (int k = 0; k < 2; ++k) \
;         acc[ai][bj][m][n] = __builtin_amdgcn_mfma_f32_16x16x32_bf16(Bt[n][k], At[m][k], acc[ai][bj][m][n], 0, 0, 0); __builtin_amdgcn_s_setprio(0); } while (0)
; #define PG8_WAIT_V(n) asm volatile("s_waitcnt vmcnt(" #n ")" ::: "memory")
; #define PG8_WAIT_L(n) asm volatile("s_waitcnt lgkmcnt(" #n ")" ::: "memory")
; #define PG8_BAR __builtin_amdgcn_s_barrier()
; #define PG8_SCHED __builtin_amdgcn_sched_barrier(0)
; template <class Epi, class Sched, bool ABLK = false, bool ALIGN_EPI = true, bool SP2 = true, bool BBLK = true>
; __device__ __forceinline__ void gemm_phase(LAS unsigned char* lds, const Gemm g, const Sched& S, const Epi& E) {
;     ...
;             PG8_WAIT_V(8); PG8_WAIT_L(0); PG8_BAR; PG8_MMA(1, 0, At, B0); PG8_MMA(1, 1, At, B1); PG8_BAR; PG8_SCHED;
;             PG8_LDB(B0, 1, 0); PG8_LDB(B1, 1, 1); PG8_SCHED; PG8_LDA(At, 1, 0); PG8_STAGE(PG8_SA(0, 1), a2 + hstepA, voffA);
;             PG8_WAIT_V(8); PG8_WAIT_L(0); PG8_BAR; PG8_MMA(0, 0, At, B0); PG8_MMA(0, 1, At, B1); PG8_BAR; PG8_SCHED;
	v_mfma_f32_16x16x32_bf16 v[62:65], v[152:155], v[184:187], 0
	v_mfma_f32_16x16x32_bf16 v[58:61], v[160:163], v[184:187], 0
	v_mfma_f32_16x16x32_bf16 v[46:49], v[152:155], v[192:195], 0
	v_mfma_f32_16x16x32_bf16 v[42:45], v[160:163], v[192:195], 0
	v_mfma_f32_16x16x32_bf16 v[30:33], v[152:155], v[200:203], 0
	v_mfma_f32_16x16x32_bf16 v[26:29], v[160:163], v[200:203], 0
	v_mfma_f32_16x16x32_bf16 v[14:17], v[152:155], v[208:211], 0
	v_mfma_f32_16x16x32_bf16 v[10:13], v[160:163], v[208:211], 0
	v_mfma_f32_16x16x32_bf16 v[62:65], v[156:159], v[188:191], v[62:65]
	v_mfma_f32_16x16x32_bf16 v[58:61], v[164:167], v[188:191], v[58:61]
	v_mfma_f32_16x16x32_bf16 v[46:49], v[156:159], v[196:199], v[46:49]
	v_mfma_f32_16x16x32_bf16 v[42:45], v[164:167], v[196:199], v[42:45]
	v_mfma_f32_16x16x32_bf16 v[30:33], v[156:159], v[204:207], v[30:33]
	v_mfma_f32_16x16x32_bf16 v[26:29], v[164:167], v[204:207], v[26:29]
	v_mfma_f32_16x16x32_bf16 v[14:17], v[156:159], v[212:215], v[14:17]
	v_mfma_f32_16x16x32_bf16 v[10:13], v[164:167], v[212:215], v[10:13]
	v_mfma_f32_16x16x32_bf16 v[54:57], v[168:171], v[184:187], 0
	v_mfma_f32_16x16x32_bf16 v[50:53], v[176:179], v[184:187], 0
	v_mfma_f32_16x16x32_bf16 v[38:41], v[168:171], v[192:195], 0
	v_mfma_f32_16x16x32_bf16 v[34:37], v[176:179], v[192:195], 0
	v_mfma_f32_16x16x32_bf16 v[22:25], v[168:171], v[200:203], 0
	v_mfma_f32_16x16x32_bf16 v[18:21], v[176:179], v[200:203], 0
	v_mfma_f32_16x16x32_bf16 v[6:9], v[168:171], v[208:211], 0
	v_mfma_f32_16x16x32_bf16 v[2:5], v[176:179], v[208:211], 0
	v_mfma_f32_16x16x32_bf16 v[54:57], v[172:175], v[188:191], v[54:57]
	v_mfma_f32_16x16x32_bf16 v[50:53], v[180:183], v[188:191], v[50:53]
	v_mfma_f32_16x16x32_bf16 v[38:41], v[172:175], v[196:199], v[38:41]
	v_mfma_f32_16x16x32_bf16 v[34:37], v[180:183], v[196:199], v[34:37]
	v_mfma_f32_16x16x32_bf16 v[22:25], v[172:175], v[204:207], v[22:25]
	v_mfma_f32_16x16x32_bf16 v[18:21], v[180:183], v[204:207], v[18:21]
	v_mfma_f32_16x16x32_bf16 v[6:9], v[172:175], v[212:215], v[6:9]
	v_mfma_f32_16x16x32_bf16 v[2:5], v[180:183], v[212:215], v[2:5]
	s_barrier
	v_add_u32_e32 v164, s60, v147
	v_add_u32_e32 v180, s61, v147
	ds_read_b128 v[152:155], v164
	ds_read_b128 v[156:159], v164 offset:1024
	ds_read_b128 v[160:163], v164 offset:2048
	ds_read_b128 v[164:167], v164 offset:3072
	ds_read_b128 v[168:171], v180
	ds_read_b128 v[172:175], v180 offset:1024
	ds_read_b128 v[176:179], v180 offset:2048
	ds_read_b128 v[180:183], v180 offset:3072
	s_add_u32 s28, s28, 0x4000
	s_addc_u32 s29, s29, 0
	s_mov_b32 m0, s37
	ds_read_b128 v[184:187], v151 offset:32768
	ds_read_b128 v[188:191], v151 offset:33792
	ds_read_b128 v[192:195], v151 offset:34816
	ds_read_b128 v[196:199], v151 offset:35840
	ds_read_b128 v[200:203], v151 offset:36864
	ds_read_b128 v[204:207], v151 offset:37888
	ds_read_b128 v[208:211], v151 offset:38912
	global_load_lds_dwordx4 v130, s[28:29]
	s_mov_b32 m0, s40
	ds_read_b128 v[212:215], v151 offset:39936
	global_load_lds_dwordx4 v132, s[28:29]
	s_waitcnt vmcnt(8) lgkmcnt(0)
	s_barrier
	v_mfma_f32_16x16x32_bf16 v[126:129], v[152:155], v[184:187], v[126:129]
	v_mfma_f32_16x16x32_bf16 v[122:125], v[160:163], v[184:187], v[122:125]
	v_mfma_f32_16x16x32_bf16 v[110:113], v[152:155], v[192:195], v[110:113]
	v_mfma_f32_16x16x32_bf16 v[106:109], v[160:163], v[192:195], v[106:109]
	v_mfma_f32_16x16x32_bf16 v[94:97], v[152:155], v[200:203], v[94:97]
	v_mfma_f32_16x16x32_bf16 v[90:93], v[160:163], v[200:203], v[90:93]
	v_mfma_f32_16x16x32_bf16 v[78:81], v[152:155], v[208:211], v[78:81]
	v_mfma_f32_16x16x32_bf16 v[74:77], v[160:163], v[208:211], v[74:77]
	v_mfma_f32_16x16x32_bf16 v[126:129], v[156:159], v[188:191], v[126:129]
	v_mfma_f32_16x16x32_bf16 v[122:125], v[164:167], v[188:191], v[122:125]
	v_mfma_f32_16x16x32_bf16 v[110:113], v[156:159], v[196:199], v[110:113]
	v_mfma_f32_16x16x32_bf16 v[106:109], v[164:167], v[196:199], v[106:109]
	v_mfma_f32_16x16x32_bf16 v[94:97], v[156:159], v[204:207], v[94:97]
	v_mfma_f32_16x16x32_bf16 v[90:93], v[164:167], v[204:207], v[90:93]
	v_mfma_f32_16x16x32_bf16 v[78:81], v[156:159], v[212:215], v[78:81]
	v_mfma_f32_16x16x32_bf16 v[74:77], v[164:167], v[212:215], v[74:77]
	v_mfma_f32_16x16x32_bf16 v[118:121], v[168:171], v[184:187], v[118:121]
	v_mfma_f32_16x16x32_bf16 v[114:117], v[176:179], v[184:187], v[114:117]
	v_mfma_f32_16x16x32_bf16 v[102:105], v[168:171], v[192:195], v[102:105]
	v_mfma_f32_16x16x32_bf16 v[98:101], v[176:179], v[192:195], v[98:101]
	v_mfma_f32_16x16x32_bf16 v[86:89], v[168:171], v[200:203], v[86:89]
	v_mfma_f32_16x16x32_bf16 v[82:85], v[176:179], v[200:203], v[82:85]
	v_mfma_f32_16x16x32_bf16 v[70:73], v[168:171], v[208:211], v[70:73]
	v_mfma_f32_16x16x32_bf16 v[66:69], v[176:179], v[208:211], v[66:69]
	v_mfma_f32_16x16x32_bf16 v[118:121], v[172:175], v[188:191], v[118:121]
	v_mfma_f32_16x16x32_bf16 v[114:117], v[180:183], v[188:191], v[114:117]
	v_mfma_f32_16x16x32_bf16 v[102:105], v[172:175], v[196:199], v[102:105]
	v_mfma_f32_16x16x32_bf16 v[98:101], v[180:183], v[196:199], v[98:101]
	v_mfma_f32_16x16x32_bf16 v[86:89], v[172:175], v[204:207], v[86:89]
	v_mfma_f32_16x16x32_bf16 v[82:85], v[180:183], v[204:207], v[82:85]
	v_mfma_f32_16x16x32_bf16 v[70:73], v[172:175], v[212:215], v[70:73]
	v_mfma_f32_16x16x32_bf16 v[66:69], v[180:183], v[212:215], v[66:69]
	s_barrier
; #define PG8_STAGE(bufoff, gbase, voff) do { _Pragma("unroll") for (int _i = 0; _i < 2; ++_i) \
;         __builtin_amdgcn_global_load_lds((const unsigned*)((const char*)(gbase) + (voff)[_i]), (LAS unsigned*)(lds + (bufoff) + ldsw + _i * 8192), 16, 0, 0); } while (0)
; #define PG8_LDA(dst, b, h) do { _Pragma("unroll") for (int m = 0; m < 4; ++m) _Pragma("unroll") for (int k = 0; k < 2; ++k) dst[m][k] = *(const LAS bf16x8*)(lds + PG8_SA(b, h) + aoff + m * 2048 + k * 1024); } while (0)
; #define PG8_LDB(dst, b, h) do { _Pragma("unroll") for (int n = 0; n < 2; ++n) _Pragma("unroll") for (int k = 0; k < 2; ++k) dst[n][k] = *(const LAS bf16x8*)(lds + PG8_SB(b, h) + boff + n * 2048 + k * 1024); } while (0)
; #define PG8_MMA(ai, bj, At, Bt) do { __builtin_amdgcn_s_setprio(1); _Pragma("unroll") for (int m = 0; m < 4; ++m) _Pragma("unroll") for (int n = 0; n < 2; ++n) _Pragma("unroll") for (int k = 0; k < 2; ++k) \
;         acc[ai][bj][m][n] = __builtin_amdgcn_mfma_f32_16x16x32_bf16(Bt[n][k], At[m][k], acc[ai][bj][m][n], 0, 0, 0); __builtin_amdgcn_s_setprio(0); } while (0)
; #define PG8_WAIT_V(n) asm volatile("s_waitcnt vmcnt(" #n ")" ::: "memory")
; template <class Epi, class Sched, bool ABLK = false, bool ALIGN_EPI = true, bool SP2 = true, bool BBLK = true>
; __device__ __forceinline__ void gemm_phase(LAS unsigned char* lds, const Gemm g, const Sched& S, const Epi& E) {
;     ...
;         for (int t = 0; t < nt; t += 2) {
;             const bool last = (t == nt - 2);
;             const char* a1 = a_tile(uA, tbA + t + 1);
;             const char* a2 = last ? a_tile(nuA, ntbA) : a_tile(uA, tbA + t + 2); const char* b2 = last ? nB : cB + (size_t)(t + 2) * kstepB;
;             const char* a3 = last ? a_tile(nuA, ntbA + 1) : a_tile(uA, tbA + t + 3); const char* b3 = b2 + kstepB;
;             if (last && has_next) S.a_ready(nxt);
;             if constexpr (SP2) {
;             PG8_LDB(B0, 0, 0); PG8_LDB(B1, 0, 1); PG8_SCHED; PG8_LDA(At, 0, 0); PG8_STAGE(PG8_SA(1, 1), a1 + hstepA, voffA);
;             PG8_WAIT_V(8); PG8_WAIT_L(0); PG8_BAR; PG8_MMA(0, 0, At, B0); PG8_MMA(0, 1, At, B1); PG8_BAR; PG8_SCHED;
;     ...
;             PG8_LDA(At, 1, 1); PG8_STAGE(PG8_SB(1, 0), b3, voffB); PG8_STAGE(PG8_SB(1, 1), b3 + hstepB, voffB); PG8_STAGE(PG8_SA(1, 0), a3, voffA);
;             PG8_WAIT_V(8); PG8_WAIT_L(0); PG8_BAR; PG8_MMA(1, 0, At, B0); PG8_MMA(1, 1, At, B1); PG8_BAR; PG8_SCHED;
	s_add_u32 s28, s26, 0x8000
	s_addc_u32 s29, s27, 0
	s_add_i32 s59, s60, s34
	s_mov_b32 m0, s59
	ds_read_b128 v[184:187], v151 offset:49152
	ds_read_b128 v[188:191], v151 offset:50176
	ds_read_b128 v[192:195], v151 offset:51200
	ds_read_b128 v[196:199], v151 offset:52224
	global_load_lds_dwordx4 v130, s[28:29]
	s_add_i32 m0, s59, 0x2000
	s_add_u32 s26, s26, 0xc000
	v_lshl_add_u64 v[216:217], s[28:29], 0, v[132:133]
	s_addc_u32 s27, s27, 0
	s_add_i32 s28, s61, s34
	global_load_lds_dwordx4 v[216:217], off
	s_mov_b32 m0, s28
	ds_read_b128 v[200:203], v151 offset:53248
	global_load_lds_dwordx4 v130, s[26:27]
	s_add_i32 m0, s28, 0x2000
	ds_read_b128 v[204:207], v151 offset:54272
	global_load_lds_dwordx4 v132, s[26:27]
	s_mov_b32 m0, s41
	ds_read_b128 v[208:211], v151 offset:55296
	global_load_lds_dwordx4 v130, s[24:25]
	s_mov_b32 m0, s42
	ds_read_b128 v[212:215], v151 offset:56320
	global_load_lds_dwordx4 v132, s[24:25]
	s_waitcnt vmcnt(8) lgkmcnt(0)
	s_barrier
	v_mfma_f32_16x16x32_bf16 v[62:65], v[152:155], v[184:187], v[62:65]
	v_mfma_f32_16x16x32_bf16 v[58:61], v[160:163], v[184:187], v[58:61]
	v_mfma_f32_16x16x32_bf16 v[46:49], v[152:155], v[192:195], v[46:49]
	v_mfma_f32_16x16x32_bf16 v[42:45], v[160:163], v[192:195], v[42:45]
	v_mfma_f32_16x16x32_bf16 v[30:33], v[152:155], v[200:203], v[30:33]
	v_mfma_f32_16x16x32_bf16 v[26:29], v[160:163], v[200:203], v[26:29]
	v_mfma_f32_16x16x32_bf16 v[14:17], v[152:155], v[208:211], v[14:17]
	v_mfma_f32_16x16x32_bf16 v[10:13], v[160:163], v[208:211], v[10:13]
	v_mfma_f32_16x16x32_bf16 v[62:65], v[156:159], v[188:191], v[62:65]
	v_mfma_f32_16x16x32_bf16 v[58:61], v[164:167], v[188:191], v[58:61]
	v_mfma_f32_16x16x32_bf16 v[46:49], v[156:159], v[196:199], v[46:49]
	v_mfma_f32_16x16x32_bf16 v[42:45], v[164:167], v[196:199], v[42:45]
	v_mfma_f32_16x16x32_bf16 v[30:33], v[156:159], v[204:207], v[30:33]
	v_mfma_f32_16x16x32_bf16 v[26:29], v[164:167], v[204:207], v[26:29]
	v_mfma_f32_16x16x32_bf16 v[14:17], v[156:159], v[212:215], v[14:17]
	v_mfma_f32_16x16x32_bf16 v[10:13], v[164:167], v[212:215], v[10:13]
	v_mfma_f32_16x16x32_bf16 v[54:57], v[168:171], v[184:187], v[54:57]
	v_mfma_f32_16x16x32_bf16 v[50:53], v[176:179], v[184:187], v[50:53]
	v_mfma_f32_16x16x32_bf16 v[38:41], v[168:171], v[192:195], v[38:41]
	v_mfma_f32_16x16x32_bf16 v[34:37], v[176:179], v[192:195], v[34:37]
	v_mfma_f32_16x16x32_bf16 v[22:25], v[168:171], v[200:203], v[22:25]
	v_mfma_f32_16x16x32_bf16 v[18:21], v[176:179], v[200:203], v[18:21]
	v_mfma_f32_16x16x32_bf16 v[6:9], v[168:171], v[208:211], v[6:9]
	v_mfma_f32_16x16x32_bf16 v[2:5], v[176:179], v[208:211], v[2:5]
	v_mfma_f32_16x16x32_bf16 v[54:57], v[172:175], v[188:191], v[54:57]
	v_mfma_f32_16x16x32_bf16 v[50:53], v[180:183], v[188:191], v[50:53]
	v_mfma_f32_16x16x32_bf16 v[38:41], v[172:175], v[196:199], v[38:41]
	v_mfma_f32_16x16x32_bf16 v[34:37], v[180:183], v[196:199], v[34:37]
	v_mfma_f32_16x16x32_bf16 v[22:25], v[172:175], v[204:207], v[22:25]
	v_mfma_f32_16x16x32_bf16 v[18:21], v[180:183], v[204:207], v[18:21]
	v_mfma_f32_16x16x32_bf16 v[6:9], v[172:175], v[212:215], v[6:9]
	v_mfma_f32_16x16x32_bf16 v[2:5], v[180:183], v[212:215], v[2:5]
	s_barrier
	s_add_u32 s22, s22, 0x10000
	s_addc_u32 s23, s23, 0
	s_cmp_ge_u32 s57, s44
.LBB0_1229:
	ds_read_b128 v[152:155], v149
	ds_read_b128 v[156:159], v149 offset:1024
	ds_read_b128 v[160:163], v149 offset:2048
	ds_read_b128 v[164:167], v149 offset:3072
	ds_read_b128 v[168:171], v150
	ds_read_b128 v[172:175], v150 offset:1024
	ds_read_b128 v[176:179], v150 offset:2048
	ds_read_b128 v[180:183], v150 offset:3072
	s_add_u32 s24, s51, s22
	s_addc_u32 s25, s55, s23
	s_add_u32 s28, s24, 0x10000
	s_addc_u32 s29, s25, 0
	s_add_i32 s57, s57, 2
	s_add_u32 s26, s49, s22
	s_addc_u32 s27, s50, s23
	s_add_u32 s24, s24, 0x18000
	s_addc_u32 s25, s25, 0
	s_cmp_eq_u32 s56, s22
	s_cselect_b32 s25, s48, s25
	s_cselect_b32 s24, s47, s24
	s_cselect_b32 s27, s4, s27
	s_cselect_b32 s26, s5, s26
	s_cselect_b32 s29, s46, s29
	s_cselect_b32 s28, s19, s28
	v_lshl_add_u64 v[216:217], v[142:143], 0, s[22:23]
	s_add_i32 m0, s35, 0xc000
	ds_read_b128 v[184:187], v151
	ds_read_b128 v[188:191], v151 offset:1024
	ds_read_b128 v[192:195], v151 offset:2048
	ds_read_b128 v[196:199], v151 offset:3072
	ds_read_b128 v[200:203], v151 offset:4096
	ds_read_b128 v[204:207], v151 offset:5120
	ds_read_b128 v[208:211], v151 offset:6144
	global_load_lds_dwordx4 v[216:217], off
	v_lshl_add_u64 v[216:217], v[144:145], 0, s[22:23]
	s_add_i32 m0, s35, 0xe000
	ds_read_b128 v[212:215], v151 offset:7168
	global_load_lds_dwordx4 v[216:217], off
	s_waitcnt vmcnt(8) lgkmcnt(0)
	s_barrier
; #define PG8_STAGE(bufoff, gbase, voff) do { _Pragma("unroll") for (int _i = 0; _i < 2; ++_i) \
;         __builtin_amdgcn_global_load_lds((const unsigned*)((const char*)(gbase) + (voff)[_i]), (LAS unsigned*)(lds + (bufoff) + ldsw + _i * 8192), 16, 0, 0); } while (0)
; #define PG8_LDA(dst, b, h) do { _Pragma("unroll") for (int m = 0; m < 4; ++m) _Pragma("unroll") for (int k = 0; k < 2; ++k) dst[m][k] = *(const LAS bf16x8*)(lds + PG8_SA(b, h) + aoff + m * 2048 + k * 1024); } while (0)
; #define PG8_LDB(dst, b, h) do { _Pragma("unroll") for (int n = 0; n < 2; ++n) _Pragma("unroll") for (int k = 0; k < 2; ++k) dst[n][k] = *(const LAS bf16x8*)(lds + PG8_SB(b, h) + boff + n * 2048 + k * 1024); } while (0)
; #define PG8_MMA(ai, bj, At, Bt) do { __builtin_amdgcn_s_setprio(1); _Pragma("unroll") for (int m = 0; m < 4; ++m) _Pragma("unroll") for (int n = 0; n < 2; ++n) _Pragma("unroll") for (int k = 0; k < 2; ++k) \
;         acc[ai][bj][m][n] = __builtin_amdgcn_mfma_f32_16x16x32_bf16(Bt[n][k], At[m][k], acc[ai][bj][m][n], 0, 0, 0); __builtin_amdgcn_s_setprio(0); } while (0)
; #define PG8_WAIT_V(n) asm volatile("s_waitcnt vmcnt(" #n ")" ::: "memory")
; #define PG8_WAIT_L(n) asm volatile("s_waitcnt lgkmcnt(" #n ")" ::: "memory")
; #define PG8_BAR __builtin_amdgcn_s_barrier()
; #define PG8_SCHED __builtin_amdgcn_sched_barrier(0)
; template <class Epi, class Sched, bool ABLK = false, bool ALIGN_EPI = true, bool SP2 = true, bool BBLK = true>
; __device__ __forceinline__ void gemm_phase(LAS unsigned char* lds, const Gemm g, const Sched& S, const Epi& E) {
;     ...
;             PG8_LDB(B0, 0, 0); PG8_LDB(B1, 0, 1); PG8_SCHED; PG8_LDA(At, 0, 0); PG8_STAGE(PG8_SA(1, 1), a1 + hstepA, voffA);
;             PG8_WAIT_V(8); PG8_WAIT_L(0); PG8_BAR; PG8_MMA(0, 0, At, B0); PG8_MMA(0, 1, At, B1); PG8_BAR; PG8_SCHED;
;             PG8_LDA(At, 0, 1); PG8_STAGE(PG8_SB(0, 0), b2, voffB); PG8_STAGE(PG8_SB(0, 1), b2 + hstepB, voffB); PG8_STAGE(PG8_SA(0, 0), a2, voffA);
;             PG8_WAIT_V(8); PG8_WAIT_L(0); PG8_BAR; PG8_MMA(1, 0, At, B0); PG8_MMA(1, 1, At, B1); PG8_BAR; PG8_SCHED;
	v_mfma_f32_16x16x32_bf16 v[126:129], v[152:155], v[184:187], v[126:129]
	v_mfma_f32_16x16x32_bf16 v[122:125], v[160:163], v[184:187], v[122:125]
	v_mfma_f32_16x16x32_bf16 v[110:113], v[152:155], v[192:195], v[110:113]
	v_mfma_f32_16x16x32_bf16 v[106:109], v[160:163], v[192:195], v[106:109]
	v_mfma_f32_16x16x32_bf16 v[94:97], v[152:155], v[200:203], v[94:97]
	v_mfma_f32_16x16x32_bf16 v[90:93], v[160:163], v[200:203], v[90:93]
	v_mfma_f32_16x16x32_bf16 v[78:81], v[152:155], v[208:211], v[78:81]
	v_mfma_f32_16x16x32_bf16 v[74:77], v[160:163], v[208:211], v[74:77]
	v_mfma_f32_16x16x32_bf16 v[126:129], v[156:159], v[188:191], v[126:129]
	v_mfma_f32_16x16x32_bf16 v[122:125], v[164:167], v[188:191], v[122:125]
	v_mfma_f32_16x16x32_bf16 v[110:113], v[156:159], v[196:199], v[110:113]
	v_mfma_f32_16x16x32_bf16 v[106:109], v[164:167], v[196:199], v[106:109]
	v_mfma_f32_16x16x32_bf16 v[94:97], v[156:159], v[204:207], v[94:97]
	v_mfma_f32_16x16x32_bf16 v[90:93], v[164:167], v[204:207], v[90:93]
	v_mfma_f32_16x16x32_bf16 v[78:81], v[156:159], v[212:215], v[78:81]
	v_mfma_f32_16x16x32_bf16 v[74:77], v[164:167], v[212:215], v[74:77]
	v_mfma_f32_16x16x32_bf16 v[118:121], v[168:171], v[184:187], v[118:121]
	v_mfma_f32_16x16x32_bf16 v[114:117], v[176:179], v[184:187], v[114:117]
	v_mfma_f32_16x16x32_bf16 v[102:105], v[168:171], v[192:195], v[102:105]
	v_mfma_f32_16x16x32_bf16 v[98:101], v[176:179], v[192:195], v[98:101]
	v_mfma_f32_16x16x32_bf16 v[86:89], v[168:171], v[200:203], v[86:89]
	v_mfma_f32_16x16x32_bf16 v[82:85], v[176:179], v[200:203], v[82:85]
	v_mfma_f32_16x16x32_bf16 v[70:73], v[168:171], v[208:211], v[70:73]
	v_mfma_f32_16x16x32_bf16 v[66:69], v[176:179], v[208:211], v[66:69]
	v_mfma_f32_16x16x32_bf16 v[118:121], v[172:175], v[188:191], v[118:121]
	v_mfma_f32_16x16x32_bf16 v[114:117], v[180:183], v[188:191], v[114:117]
	v_mfma_f32_16x16x32_bf16 v[102:105], v[172:175], v[196:199], v[102:105]
	v_mfma_f32_16x16x32_bf16 v[98:101], v[180:183], v[196:199], v[98:101]
	v_mfma_f32_16x16x32_bf16 v[86:89], v[172:175], v[204:207], v[86:89]
	v_mfma_f32_16x16x32_bf16 v[82:85], v[180:183], v[204:207], v[82:85]
	v_mfma_f32_16x16x32_bf16 v[70:73], v[172:175], v[212:215], v[70:73]
	v_mfma_f32_16x16x32_bf16 v[66:69], v[180:183], v[212:215], v[66:69]
	s_barrier
	s_add_i32 s59, s72, s34
	s_mov_b32 m0, s59
	ds_read_b128 v[184:187], v151 offset:16384
	ds_read_b128 v[188:191], v151 offset:17408
	ds_read_b128 v[192:195], v151 offset:18432
	ds_read_b128 v[196:199], v151 offset:19456
	global_load_lds_dwordx4 v130, s[26:27]
	s_add_i32 m0, s59, 0x2000
	s_add_u32 s64, s26, 0x4000
	s_addc_u32 s65, s27, 0
	s_add_i32 s59, s73, s34
	global_load_lds_dwordx4 v132, s[26:27]
	s_mov_b32 m0, s59
	ds_read_b128 v[200:203], v151 offset:20480
	global_load_lds_dwordx4 v130, s[64:65]
	s_add_i32 m0, s59, 0x2000
	ds_read_b128 v[204:207], v151 offset:21504
	global_load_lds_dwordx4 v132, s[64:65]
	s_mov_b32 m0, s35
	ds_read_b128 v[208:211], v151 offset:22528
	global_load_lds_dwordx4 v130, s[28:29]
	s_mov_b32 m0, s36
	ds_read_b128 v[212:215], v151 offset:23552
	global_load_lds_dwordx4 v132, s[28:29]
	s_waitcnt vmcnt(8) lgkmcnt(0)
	s_barrier
	v_mfma_f32_16x16x32_bf16 v[62:65], v[152:155], v[184:187], v[62:65]
	v_mfma_f32_16x16x32_bf16 v[58:61], v[160:163], v[184:187], v[58:61]
	v_mfma_f32_16x16x32_bf16 v[46:49], v[152:155], v[192:195], v[46:49]
	v_mfma_f32_16x16x32_bf16 v[42:45], v[160:163], v[192:195], v[42:45]
	v_mfma_f32_16x16x32_bf16 v[30:33], v[152:155], v[200:203], v[30:33]
	v_mfma_f32_16x16x32_bf16 v[26:29], v[160:163], v[200:203], v[26:29]
	v_mfma_f32_16x16x32_bf16 v[14:17], v[152:155], v[208:211], v[14:17]
	v_mfma_f32_16x16x32_bf16 v[10:13], v[160:163], v[208:211], v[10:13]
	v_mfma_f32_16x16x32_bf16 v[62:65], v[156:159], v[188:191], v[62:65]
	v_mfma_f32_16x16x32_bf16 v[58:61], v[164:167], v[188:191], v[58:61]
	v_mfma_f32_16x16x32_bf16 v[46:49], v[156:159], v[196:199], v[46:49]
	v_mfma_f32_16x16x32_bf16 v[42:45], v[164:167], v[196:199], v[42:45]
	v_mfma_f32_16x16x32_bf16 v[30:33], v[156:159], v[204:207], v[30:33]
	v_mfma_f32_16x16x32_bf16 v[26:29], v[164:167], v[204:207], v[26:29]
	v_mfma_f32_16x16x32_bf16 v[14:17], v[156:159], v[212:215], v[14:17]
	v_mfma_f32_16x16x32_bf16 v[10:13], v[164:167], v[212:215], v[10:13]
	v_mfma_f32_16x16x32_bf16 v[54:57], v[168:171], v[184:187], v[54:57]
	v_mfma_f32_16x16x32_bf16 v[50:53], v[176:179], v[184:187], v[50:53]
	v_mfma_f32_16x16x32_bf16 v[38:41], v[168:171], v[192:195], v[38:41]
	v_mfma_f32_16x16x32_bf16 v[34:37], v[176:179], v[192:195], v[34:37]
	v_mfma_f32_16x16x32_bf16 v[22:25], v[168:171], v[200:203], v[22:25]
	v_mfma_f32_16x16x32_bf16 v[18:21], v[176:179], v[200:203], v[18:21]
	v_mfma_f32_16x16x32_bf16 v[6:9], v[168:171], v[208:211], v[6:9]
	v_mfma_f32_16x16x32_bf16 v[2:5], v[176:179], v[208:211], v[2:5]
	v_mfma_f32_16x16x32_bf16 v[54:57], v[172:175], v[188:191], v[54:57]
	v_mfma_f32_16x16x32_bf16 v[50:53], v[180:183], v[188:191], v[50:53]
	v_mfma_f32_16x16x32_bf16 v[38:41], v[172:175], v[196:199], v[38:41]
	v_mfma_f32_16x16x32_bf16 v[34:37], v[180:183], v[196:199], v[34:37]
	v_mfma_f32_16x16x32_bf16 v[22:25], v[172:175], v[204:207], v[22:25]
	v_mfma_f32_16x16x32_bf16 v[18:21], v[180:183], v[204:207], v[18:21]
	v_mfma_f32_16x16x32_bf16 v[6:9], v[172:175], v[212:215], v[6:9]
	v_mfma_f32_16x16x32_bf16 v[2:5], v[180:183], v[212:215], v[2:5]
	s_barrier
; #define PG8_STAGE(bufoff, gbase, voff) do { _Pragma("unroll") for (int _i = 0; _i < 2; ++_i) \
;         __builtin_amdgcn_global_load_lds((const unsigned*)((const char*)(gbase) + (voff)[_i]), (LAS unsigned*)(lds + (bufoff) + ldsw + _i * 8192), 16, 0, 0); } while (0)
; #define PG8_LDA(dst, b, h) do { _Pragma("unroll") for (int m = 0; m < 4; ++m) _Pragma("unroll") for (int k = 0; k < 2; ++k) dst[m][k] = *(const LAS bf16x8*)(lds + PG8_SA(b, h) + aoff + m * 2048 + k * 1024); } while (0)
; #define PG8_LDB(dst, b, h) do { _Pragma("unroll") for (int n = 0; n < 2; ++n) _Pragma("unroll") for (int k = 0; k < 2; ++k) dst[n][k] = *(const LAS bf16x8*)(lds + PG8_SB(b, h) + boff + n * 2048 + k * 1024); } while (0)
; #define PG8_MMA(ai, bj, At, Bt) do { __builtin_amdgcn_s_setprio(1); _Pragma("unroll") for (int m = 0; m < 4; ++m) _Pragma("unroll") for (int n = 0; n < 2; ++n) _Pragma("unroll") for (int k = 0; k < 2; ++k) \
;         acc[ai][bj][m][n] = __builtin_amdgcn_mfma_f32_16x16x32_bf16(Bt[n][k], At[m][k], acc[ai][bj][m][n], 0, 0, 0); __builtin_amdgcn_s_setprio(0); } while (0)
; #define PG8_WAIT_V(n) asm volatile("s_waitcnt vmcnt(" #n ")" ::: "memory")
; #define PG8_WAIT_L(n) asm volatile("s_waitcnt lgkmcnt(" #n ")" ::: "memory")
; #define PG8_BAR __builtin_amdgcn_s_barrier()
; #define PG8_SCHED __builtin_amdgcn_sched_barrier(0)
; template <class Epi, class Sched, bool ABLK = false, bool ALIGN_EPI = true, bool SP2 = true, bool BBLK = true>
; __device__ __forceinline__ void gemm_phase(LAS unsigned char* lds, const Gemm g, const Sched& S, const Epi& E) {
;     ...
;             PG8_LDB(B0, 1, 0); PG8_LDB(B1, 1, 1); PG8_SCHED; PG8_LDA(At, 1, 0); PG8_STAGE(PG8_SA(0, 1), a2 + hstepA, voffA);
;             PG8_WAIT_V(8); PG8_WAIT_L(0); PG8_BAR; PG8_MMA(0, 0, At, B0); PG8_MMA(0, 1, At, B1); PG8_BAR; PG8_SCHED;
;             PG8_LDA(At, 1, 1); PG8_STAGE(PG8_SB(1, 0), b3, voffB); PG8_STAGE(PG8_SB(1, 1), b3 + hstepB, voffB); PG8_STAGE(PG8_SA(1, 0), a3, voffA);
;             PG8_WAIT_V(8); PG8_WAIT_L(0); PG8_BAR; PG8_MMA(1, 0, At, B0); PG8_MMA(1, 1, At, B1); PG8_BAR; PG8_SCHED;
;     ...
;         if constexpr (ALIGN_EPI) { if (wr == 0) PG8_BAR; }
	v_add_u32_e32 v164, s60, v147
	v_add_u32_e32 v180, s61, v147
	ds_read_b128 v[152:155], v164
	ds_read_b128 v[156:159], v164 offset:1024
	ds_read_b128 v[160:163], v164 offset:2048
	ds_read_b128 v[164:167], v164 offset:3072
	ds_read_b128 v[168:171], v180
	ds_read_b128 v[172:175], v180 offset:1024
	ds_read_b128 v[176:179], v180 offset:2048
	ds_read_b128 v[180:183], v180 offset:3072
	s_add_u32 s28, s28, 0x4000
	s_addc_u32 s29, s29, 0
	s_mov_b32 m0, s37
	ds_read_b128 v[184:187], v151 offset:32768
	ds_read_b128 v[188:191], v151 offset:33792
	ds_read_b128 v[192:195], v151 offset:34816
	ds_read_b128 v[196:199], v151 offset:35840
	ds_read_b128 v[200:203], v151 offset:36864
	ds_read_b128 v[204:207], v151 offset:37888
	ds_read_b128 v[208:211], v151 offset:38912
	global_load_lds_dwordx4 v130, s[28:29]
	s_mov_b32 m0, s40
	ds_read_b128 v[212:215], v151 offset:39936
	global_load_lds_dwordx4 v132, s[28:29]
	s_waitcnt vmcnt(8) lgkmcnt(0)
	s_barrier
	v_mfma_f32_16x16x32_bf16 v[126:129], v[152:155], v[184:187], v[126:129]
	v_mfma_f32_16x16x32_bf16 v[122:125], v[160:163], v[184:187], v[122:125]
	v_mfma_f32_16x16x32_bf16 v[110:113], v[152:155], v[192:195], v[110:113]
	v_mfma_f32_16x16x32_bf16 v[106:109], v[160:163], v[192:195], v[106:109]
	v_mfma_f32_16x16x32_bf16 v[94:97], v[152:155], v[200:203], v[94:97]
	v_mfma_f32_16x16x32_bf16 v[90:93], v[160:163], v[200:203], v[90:93]
	v_mfma_f32_16x16x32_bf16 v[78:81], v[152:155], v[208:211], v[78:81]
	v_mfma_f32_16x16x32_bf16 v[74:77], v[160:163], v[208:211], v[74:77]
	v_mfma_f32_16x16x32_bf16 v[126:129], v[156:159], v[188:191], v[126:129]
	v_mfma_f32_16x16x32_bf16 v[122:125], v[164:167], v[188:191], v[122:125]
	v_mfma_f32_16x16x32_bf16 v[110:113], v[156:159], v[196:199], v[110:113]
	v_mfma_f32_16x16x32_bf16 v[106:109], v[164:167], v[196:199], v[106:109]
	v_mfma_f32_16x16x32_bf16 v[94:97], v[156:159], v[204:207], v[94:97]
	v_mfma_f32_16x16x32_bf16 v[90:93], v[164:167], v[204:207], v[90:93]
	v_mfma_f32_16x16x32_bf16 v[78:81], v[156:159], v[212:215], v[78:81]
	v_mfma_f32_16x16x32_bf16 v[74:77], v[164:167], v[212:215], v[74:77]
	v_mfma_f32_16x16x32_bf16 v[118:121], v[168:171], v[184:187], v[118:121]
	v_mfma_f32_16x16x32_bf16 v[114:117], v[176:179], v[184:187], v[114:117]
	v_mfma_f32_16x16x32_bf16 v[102:105], v[168:171], v[192:195], v[102:105]
	v_mfma_f32_16x16x32_bf16 v[98:101], v[176:179], v[192:195], v[98:101]
	v_mfma_f32_16x16x32_bf16 v[86:89], v[168:171], v[200:203], v[86:89]
	v_mfma_f32_16x16x32_bf16 v[82:85], v[176:179], v[200:203], v[82:85]
	v_mfma_f32_16x16x32_bf16 v[70:73], v[168:171], v[208:211], v[70:73]
	v_mfma_f32_16x16x32_bf16 v[66:69], v[176:179], v[208:211], v[66:69]
	v_mfma_f32_16x16x32_bf16 v[118:121], v[172:175], v[188:191], v[118:121]
	v_mfma_f32_16x16x32_bf16 v[114:117], v[180:183], v[188:191], v[114:117]
	v_mfma_f32_16x16x32_bf16 v[102:105], v[172:175], v[196:199], v[102:105]
	v_mfma_f32_16x16x32_bf16 v[98:101], v[180:183], v[196:199], v[98:101]
	v_mfma_f32_16x16x32_bf16 v[86:89], v[172:175], v[204:207], v[86:89]
	v_mfma_f32_16x16x32_bf16 v[82:85], v[180:183], v[204:207], v[82:85]
	v_mfma_f32_16x16x32_bf16 v[70:73], v[172:175], v[212:215], v[70:73]
	v_mfma_f32_16x16x32_bf16 v[66:69], v[180:183], v[212:215], v[66:69]
	s_barrier
	s_add_u32 s28, s26, 0x8000
	s_addc_u32 s29, s27, 0
	s_add_i32 s59, s60, s34
	s_mov_b32 m0, s59
	ds_read_b128 v[184:187], v151 offset:49152
	ds_read_b128 v[188:191], v151 offset:50176
	ds_read_b128 v[192:195], v151 offset:51200
	ds_read_b128 v[196:199], v151 offset:52224
	global_load_lds_dwordx4 v130, s[28:29]
	s_add_i32 m0, s59, 0x2000
	s_add_u32 s26, s26, 0xc000
	v_lshl_add_u64 v[216:217], s[28:29], 0, v[132:133]
	s_addc_u32 s27, s27, 0
	s_add_i32 s28, s61, s34
	global_load_lds_dwordx4 v[216:217], off
	s_mov_b32 m0, s28
	ds_read_b128 v[200:203], v151 offset:53248
	global_load_lds_dwordx4 v130, s[26:27]
	s_add_i32 m0, s28, 0x2000
	ds_read_b128 v[204:207], v151 offset:54272
	global_load_lds_dwordx4 v132, s[26:27]
	s_mov_b32 m0, s41
	ds_read_b128 v[208:211], v151 offset:55296
	global_load_lds_dwordx4 v130, s[24:25]
	s_mov_b32 m0, s42
	ds_read_b128 v[212:215], v151 offset:56320
	global_load_lds_dwordx4 v132, s[24:25]
	s_waitcnt vmcnt(8) lgkmcnt(0)
	s_barrier
	v_mfma_f32_16x16x32_bf16 v[62:65], v[152:155], v[184:187], v[62:65]
	v_mfma_f32_16x16x32_bf16 v[58:61], v[160:163], v[184:187], v[58:61]
	v_mfma_f32_16x16x32_bf16 v[46:49], v[152:155], v[192:195], v[46:49]
	v_mfma_f32_16x16x32_bf16 v[42:45], v[160:163], v[192:195], v[42:45]
	v_mfma_f32_16x16x32_bf16 v[30:33], v[152:155], v[200:203], v[30:33]
	v_mfma_f32_16x16x32_bf16 v[26:29], v[160:163], v[200:203], v[26:29]
	v_mfma_f32_16x16x32_bf16 v[14:17], v[152:155], v[208:211], v[14:17]
	v_mfma_f32_16x16x32_bf16 v[10:13], v[160:163], v[208:211], v[10:13]
	v_mfma_f32_16x16x32_bf16 v[62:65], v[156:159], v[188:191], v[62:65]
	v_mfma_f32_16x16x32_bf16 v[58:61], v[164:167], v[188:191], v[58:61]
	v_mfma_f32_16x16x32_bf16 v[46:49], v[156:159], v[196:199], v[46:49]
	v_mfma_f32_16x16x32_bf16 v[42:45], v[164:167], v[196:199], v[42:45]
	v_mfma_f32_16x16x32_bf16 v[30:33], v[156:159], v[204:207], v[30:33]
	v_mfma_f32_16x16x32_bf16 v[26:29], v[164:167], v[204:207], v[26:29]
	v_mfma_f32_16x16x32_bf16 v[14:17], v[156:159], v[212:215], v[14:17]
	v_mfma_f32_16x16x32_bf16 v[10:13], v[164:167], v[212:215], v[10:13]
	v_mfma_f32_16x16x32_bf16 v[54:57], v[168:171], v[184:187], v[54:57]
	v_mfma_f32_16x16x32_bf16 v[50:53], v[176:179], v[184:187], v[50:53]
	v_mfma_f32_16x16x32_bf16 v[38:41], v[168:171], v[192:195], v[38:41]
	v_mfma_f32_16x16x32_bf16 v[34:37], v[176:179], v[192:195], v[34:37]
	v_mfma_f32_16x16x32_bf16 v[22:25], v[168:171], v[200:203], v[22:25]
	v_mfma_f32_16x16x32_bf16 v[18:21], v[176:179], v[200:203], v[18:21]
	v_mfma_f32_16x16x32_bf16 v[6:9], v[168:171], v[208:211], v[6:9]
	v_mfma_f32_16x16x32_bf16 v[2:5], v[176:179], v[208:211], v[2:5]
	v_mfma_f32_16x16x32_bf16 v[54:57], v[172:175], v[188:191], v[54:57]
	v_mfma_f32_16x16x32_bf16 v[50:53], v[180:183], v[188:191], v[50:53]
	v_mfma_f32_16x16x32_bf16 v[38:41], v[172:175], v[196:199], v[38:41]
	v_mfma_f32_16x16x32_bf16 v[34:37], v[180:183], v[196:199], v[34:37]
	v_mfma_f32_16x16x32_bf16 v[22:25], v[172:175], v[204:207], v[22:25]
	v_mfma_f32_16x16x32_bf16 v[18:21], v[180:183], v[204:207], v[18:21]
	v_mfma_f32_16x16x32_bf16 v[6:9], v[172:175], v[212:215], v[6:9]
	v_mfma_f32_16x16x32_bf16 v[2:5], v[180:183], v[212:215], v[2:5]
	s_barrier
	s_add_u32 s22, s22, 0x10000
	s_addc_u32 s23, s23, 0
	s_cmp_ge_u32 s57, s44
	s_cbranch_scc0 .LBB0_1229
	s_and_b64 vcc, exec, s[6:7]
	s_cbranch_vccz .LBB0_1232
	s_barrier

; #define PG8_STAGE(bufoff, gbase, voff) do { _Pragma("unroll") for (int _i = 0; _i < 2; ++_i) \
;         __builtin_amdgcn_global_load_lds((const unsigned*)((const char*)(gbase) + (voff)[_i]), (LAS unsigned*)(lds + (bufoff) + ldsw + _i * 8192), 16, 0, 0); } while (0)
; #define PG8_LDA(dst, b, h) do { _Pragma("unroll") for (int m = 0; m < 4; ++m) _Pragma("unroll") for (int k = 0; k < 2; ++k) dst[m][k] = *(const LAS bf16x8*)(lds + PG8_SA(b, h) + aoff + m * 2048 + k * 1024); } while (0)
; #define PG8_LDB(dst, b, h) do { _Pragma("unroll") for (int n = 0; n < 2; ++n) _Pragma("unroll") for (int k = 0; k < 2; ++k) dst[n][k] = *(const LAS bf16x8*)(lds + PG8_SB(b, h) + boff + n * 2048 + k * 1024); } while (0)
; #define PG8_WAIT_V(n) asm volatile("s_waitcnt vmcnt(" #n ")" ::: "memory")
; #define PG8_WAIT_L(n) asm volatile("s_waitcnt lgkmcnt(" #n ")" ::: "memory")
; #define PG8_BAR __builtin_amdgcn_s_barrier()
; #define PG8_SCHED __builtin_amdgcn_sched_barrier(0)
; template <class Epi, class Sched, bool ABLK = false, bool ALIGN_EPI = true, bool SP2 = true, bool BBLK = true>
; __device__ __forceinline__ void gemm_phase(LAS unsigned char* lds, const Gemm g, const Sched& S, const Epi& E) {
;     ...
;         const bool has_next = S.next(ui + 1, nxt);
;         const int nt = cur.nt;
;         const char* nuA = has_next ? a_unit(nxt) : uA; const int ntbA = has_next ? nxt.k0 / BK : tbA; const char* nB = has_next ? (const char*)g.Bt + (size_t)nxt.pn * tstepB + b_k0(nxt.k0) : cB;
;         for (int t = 0; t < nt; t += 2) {
;             const bool last = (t == nt - 2);
;             const char* a1 = a_tile(uA, tbA + t + 1);
;             const char* a2 = last ? a_tile(nuA, ntbA) : a_tile(uA, tbA + t + 2); const char* b2 = last ? nB : cB + (size_t)(t + 2) * kstepB;
;             const char* a3 = last ? a_tile(nuA, ntbA + 1) : a_tile(uA, tbA + t + 3); const char* b3 = b2 + kstepB;
;             if (last && has_next) S.a_ready(nxt);
;             if constexpr (SP2) {
;             PG8_LDB(B0, 0, 0); PG8_LDB(B1, 0, 1); PG8_SCHED; PG8_LDA(At, 0, 0); PG8_STAGE(PG8_SA(1, 1), a1 + hstepA, voffA);
;             PG8_WAIT_V(8); PG8_WAIT_L(0); PG8_BAR; PG8_MMA(0, 0, At, B0); PG8_MMA(0, 1, At, B1); PG8_BAR; PG8_SCHED;
;             PG8_LDA(At, 0, 1); PG8_STAGE(PG8_SB(0, 0), b2, voffB); PG8_STAGE(PG8_SB(0, 1), b2 + hstepB, voffB); PG8_STAGE(PG8_SA(0, 0), a2, voffA);
.LBB0_1354:
	s_ashr_i32 s21, s20, 31
	s_lshl_b64 s[4:5], s[20:21], 20
	s_add_u32 s24, s76, s4
	s_addc_u32 s25, s33, s5
	s_and_b64 s[4:5], s[26:27], exec
	s_cselect_b32 s4, s25, s37
	s_cselect_b32 s5, s24, s36
	s_ashr_i32 s23, s22, 31
	s_lshl_b64 s[28:29], s[22:23], 20
	s_add_u32 s28, s1, s28
	s_addc_u32 s29, s48, s29
	s_and_b64 s[42:43], s[26:27], exec
	s_cselect_b32 s21, s29, s41
	s_cselect_b32 s23, s28, s40
	s_add_u32 s56, s5, 0x80
	s_addc_u32 s57, s4, 0
	s_add_u32 s59, s40, 0x10000
	v_mov_b32_e32 v2, 0
	s_addc_u32 s64, s41, 0
	v_lshl_add_u64 v[148:149], s[36:37], 0, v[144:145]
	v_lshl_add_u64 v[150:151], s[36:37], 0, v[146:147]
	s_mov_b32 s65, -2
	s_mov_b64 s[40:41], 0
	ds_read_b128 v[152:155], v163
	ds_read_b128 v[156:159], v163 offset:1024
	ds_read_b128 v[166:169], v163 offset:2048
	ds_read_b128 v[170:173], v163 offset:3072
	ds_read_b128 v[174:177], v164
	ds_read_b128 v[178:181], v164 offset:1024
	ds_read_b128 v[182:185], v164 offset:2048
	ds_read_b128 v[186:189], v164 offset:3072
	s_add_u32 s42, s36, s40
	s_addc_u32 s43, s37, s41
	s_add_u32 s46, s42, 0x100
	s_addc_u32 s47, s43, 0
	s_add_u32 s42, s42, 0x180
	s_addc_u32 s43, s43, 0
	s_cmpk_eq_i32 s40, 0xf00
	s_cselect_b32 s43, s57, s43
	s_cselect_b32 s42, s56, s42
	s_cselect_b32 s45, s21, s64
	s_cselect_b32 s44, s23, s59
	s_cselect_b32 s47, s4, s47
	s_cselect_b32 s46, s5, s46
	v_lshl_add_u64 v[222:223], v[148:149], 0, s[40:41]
	s_add_i32 m0, s31, 0xc000
	ds_read_b128 v[190:193], v165
	ds_read_b128 v[194:197], v165 offset:1024
	ds_read_b128 v[198:201], v165 offset:2048
	ds_read_b128 v[202:205], v165 offset:3072
	ds_read_b128 v[206:209], v165 offset:4096
	ds_read_b128 v[210:213], v165 offset:5120
	ds_read_b128 v[214:217], v165 offset:6144
	global_load_lds_dwordx4 v[222:223], off
	v_lshl_add_u64 v[222:223], v[150:151], 0, s[40:41]
	s_add_i32 m0, s31, 0xe000
	ds_read_b128 v[218:221], v165 offset:7168
	global_load_lds_dwordx4 v[222:223], off
	s_waitcnt vmcnt(8) lgkmcnt(0)
	s_barrier
	v_mfma_f32_16x16x32_bf16 v[126:129], v[152:155], v[190:193], 0
	v_mfma_f32_16x16x32_bf16 v[122:125], v[166:169], v[190:193], 0
	v_mfma_f32_16x16x32_bf16 v[110:113], v[152:155], v[198:201], 0
	v_mfma_f32_16x16x32_bf16 v[106:109], v[166:169], v[198:201], 0
	v_mfma_f32_16x16x32_bf16 v[94:97], v[152:155], v[206:209], 0
	v_mfma_f32_16x16x32_bf16 v[90:93], v[166:169], v[206:209], 0
	v_mfma_f32_16x16x32_bf16 v[78:81], v[152:155], v[214:217], 0
	v_mfma_f32_16x16x32_bf16 v[74:77], v[166:169], v[214:217], 0
	v_mfma_f32_16x16x32_bf16 v[126:129], v[156:159], v[194:197], v[126:129]
	v_mfma_f32_16x16x32_bf16 v[122:125], v[170:173], v[194:197], v[122:125]
	v_mfma_f32_16x16x32_bf16 v[110:113], v[156:159], v[202:205], v[110:113]
	v_mfma_f32_16x16x32_bf16 v[106:109], v[170:173], v[202:205], v[106:109]
	v_mfma_f32_16x16x32_bf16 v[94:97], v[156:159], v[210:213], v[94:97]
	v_mfma_f32_16x16x32_bf16 v[90:93], v[170:173], v[210:213], v[90:93]
	v_mfma_f32_16x16x32_bf16 v[78:81], v[156:159], v[218:221], v[78:81]
	v_mfma_f32_16x16x32_bf16 v[74:77], v[170:173], v[218:221], v[74:77]
	v_mfma_f32_16x16x32_bf16 v[118:121], v[174:177], v[190:193], 0
	v_mfma_f32_16x16x32_bf16 v[114:117], v[182:185], v[190:193], 0
	v_mfma_f32_16x16x32_bf16 v[102:105], v[174:177], v[198:201], 0
	v_mfma_f32_16x16x32_bf16 v[98:101], v[182:185], v[198:201], 0
	v_mfma_f32_16x16x32_bf16 v[86:89], v[174:177], v[206:209], 0
	v_mfma_f32_16x16x32_bf16 v[82:85], v[182:185], v[206:209], 0
	v_mfma_f32_16x16x32_bf16 v[70:73], v[174:177], v[214:217], 0
	v_mfma_f32_16x16x32_bf16 v[66:69], v[182:185], v[214:217], 0
	v_mfma_f32_16x16x32_bf16 v[118:121], v[178:181], v[194:197], v[118:121]
	v_mfma_f32_16x16x32_bf16 v[114:117], v[186:189], v[194:197], v[114:117]
	v_mfma_f32_16x16x32_bf16 v[102:105], v[178:181], v[202:205], v[102:105]
	v_mfma_f32_16x16x32_bf16 v[98:101], v[186:189], v[202:205], v[98:101]
	v_mfma_f32_16x16x32_bf16 v[86:89], v[178:181], v[210:213], v[86:89]
	v_mfma_f32_16x16x32_bf16 v[82:85], v[186:189], v[210:213], v[82:85]
	v_mfma_f32_16x16x32_bf16 v[70:73], v[178:181], v[218:221], v[70:73]
	v_mfma_f32_16x16x32_bf16 v[66:69], v[186:189], v[218:221], v[66:69]
	s_barrier
	s_add_i32 s66, s72, s49
	s_mov_b32 m0, s66
	ds_read_b128 v[190:193], v165 offset:16384
	ds_read_b128 v[194:197], v165 offset:17408
	ds_read_b128 v[198:201], v165 offset:18432
	ds_read_b128 v[202:205], v165 offset:19456
	global_load_lds_dwordx4 v134, s[44:45]
	s_add_i32 m0, s66, 0x2000
	s_add_u32 s66, s44, 0x4000
	s_addc_u32 s67, s45, 0
	s_add_i32 s75, s73, s49
	global_load_lds_dwordx4 v130, s[44:45]
	s_mov_b32 m0, s75
	ds_read_b128 v[206:209], v165 offset:20480
	global_load_lds_dwordx4 v134, s[66:67]
	s_add_i32 m0, s75, 0x2000
	ds_read_b128 v[210:213], v165 offset:21504
	global_load_lds_dwordx4 v130, s[66:67]
	s_mov_b32 m0, s31
	ds_read_b128 v[214:217], v165 offset:22528
	global_load_lds_dwordx4 v136, s[46:47]
	s_mov_b32 m0, s35
	ds_read_b128 v[218:221], v165 offset:23552
	global_load_lds_dwordx4 v132, s[46:47]
	s_waitcnt vmcnt(8) lgkmcnt(0)
	s_barrier
; #define PG8_STAGE(bufoff, gbase, voff) do { _Pragma("unroll") for (int _i = 0; _i < 2; ++_i) \
;         __builtin_amdgcn_global_load_lds((const unsigned*)((const char*)(gbase) + (voff)[_i]), (LAS unsigned*)(lds + (bufoff) + ldsw + _i * 8192), 16, 0, 0); } while (0)
; #define PG8_LDA(dst, b, h) do { _Pragma("unroll") for (int m = 0; m < 4; ++m) _Pragma("unroll") for (int k = 0; k < 2; ++k) dst[m][k] = *(const LAS bf16x8*)(lds + PG8_SA(b, h) + aoff + m * 2048 + k * 1024); } while (0)
; #define PG8_LDB(dst, b, h) do { _Pragma("unroll") for (int n = 0; n < 2; ++n) _Pragma("unroll") for (int k = 0; k < 2; ++k) dst[n][k] = *(const LAS bf16x8*)(lds + PG8_SB(b, h) + boff + n * 2048 + k * 1024); } while (0)
; #define PG8_MMA(ai, bj, At, Bt) do { __builtin_amdgcn_s_setprio(1); _Pragma("unroll") for (int m = 0; m < 4; ++m) _Pragma("unroll") for (int n = 0; n < 2; ++n) _Pragma("unroll") for (int k = 0; k < 2; ++k) \
;         acc[ai][bj][m][n] = __builtin_amdgcn_mfma_f32_16x16x32_bf16(Bt[n][k], At[m][k], acc[ai][bj][m][n], 0, 0, 0); __builtin_amdgcn_s_setprio(0); } while (0)
; #define PG8_WAIT_V(n) asm volatile("s_waitcnt vmcnt(" #n ")" ::: "memory")
; #define PG8_WAIT_L(n) asm volatile("s_waitcnt lgkmcnt(" #n ")" ::: "memory")
; #define PG8_BAR __builtin_amdgcn_s_barrier()
; #define PG8_SCHED __builtin_amdgcn_sched_barrier(0)
; template <class Epi, class Sched, bool ABLK = false, bool ALIGN_EPI = true, bool SP2 = true, bool BBLK = true>
; __device__ __forceinline__ void gemm_phase(LAS unsigned char* lds, const Gemm g, const Sched& S, const Epi& E) {
;     ...
;             PG8_WAIT_V(8); PG8_WAIT_L(0); PG8_BAR; PG8_MMA(1, 0, At, B0); PG8_MMA(1, 1, At, B1); PG8_BAR; PG8_SCHED;
;             PG8_LDB(B0, 1, 0); PG8_LDB(B1, 1, 1); PG8_SCHED; PG8_LDA(At, 1, 0); PG8_STAGE(PG8_SA(0, 1), a2 + hstepA, voffA);
;             PG8_WAIT_V(8); PG8_WAIT_L(0); PG8_BAR; PG8_MMA(0, 0, At, B0); PG8_MMA(0, 1, At, B1); PG8_BAR; PG8_SCHED;
	v_mfma_f32_16x16x32_bf16 v[62:65], v[152:155], v[190:193], 0
	v_mfma_f32_16x16x32_bf16 v[58:61], v[166:169], v[190:193], 0
	v_mfma_f32_16x16x32_bf16 v[46:49], v[152:155], v[198:201], 0
	v_mfma_f32_16x16x32_bf16 v[42:45], v[166:169], v[198:201], 0
	v_mfma_f32_16x16x32_bf16 v[30:33], v[152:155], v[206:209], 0
	v_mfma_f32_16x16x32_bf16 v[26:29], v[166:169], v[206:209], 0
	v_mfma_f32_16x16x32_bf16 v[14:17], v[152:155], v[214:217], 0
	v_mfma_f32_16x16x32_bf16 v[10:13], v[166:169], v[214:217], 0
	v_mfma_f32_16x16x32_bf16 v[62:65], v[156:159], v[194:197], v[62:65]
	v_mfma_f32_16x16x32_bf16 v[58:61], v[170:173], v[194:197], v[58:61]
	v_mfma_f32_16x16x32_bf16 v[46:49], v[156:159], v[202:205], v[46:49]
	v_mfma_f32_16x16x32_bf16 v[42:45], v[170:173], v[202:205], v[42:45]
	v_mfma_f32_16x16x32_bf16 v[30:33], v[156:159], v[210:213], v[30:33]
	v_mfma_f32_16x16x32_bf16 v[26:29], v[170:173], v[210:213], v[26:29]
	v_mfma_f32_16x16x32_bf16 v[14:17], v[156:159], v[218:221], v[14:17]
	v_mfma_f32_16x16x32_bf16 v[10:13], v[170:173], v[218:221], v[10:13]
	v_mfma_f32_16x16x32_bf16 v[54:57], v[174:177], v[190:193], 0
	v_mfma_f32_16x16x32_bf16 v[50:53], v[182:185], v[190:193], 0
	v_mfma_f32_16x16x32_bf16 v[38:41], v[174:177], v[198:201], 0
	v_mfma_f32_16x16x32_bf16 v[34:37], v[182:185], v[198:201], 0
	v_mfma_f32_16x16x32_bf16 v[22:25], v[174:177], v[206:209], 0
	v_mfma_f32_16x16x32_bf16 v[18:21], v[182:185], v[206:209], 0
	v_mfma_f32_16x16x32_bf16 v[6:9], v[174:177], v[214:217], 0
	v_mfma_f32_16x16x32_bf16 v[2:5], v[182:185], v[214:217], 0
	v_mfma_f32_16x16x32_bf16 v[54:57], v[178:181], v[194:197], v[54:57]
	v_mfma_f32_16x16x32_bf16 v[50:53], v[186:189], v[194:197], v[50:53]
	v_mfma_f32_16x16x32_bf16 v[38:41], v[178:181], v[202:205], v[38:41]
	v_mfma_f32_16x16x32_bf16 v[34:37], v[186:189], v[202:205], v[34:37]
	v_mfma_f32_16x16x32_bf16 v[22:25], v[178:181], v[210:213], v[22:25]
	v_mfma_f32_16x16x32_bf16 v[18:21], v[186:189], v[210:213], v[18:21]
	v_mfma_f32_16x16x32_bf16 v[6:9], v[178:181], v[218:221], v[6:9]
	v_mfma_f32_16x16x32_bf16 v[2:5], v[186:189], v[218:221], v[2:5]
	s_barrier
	v_add_u32_e32 v138, s60, v161
	ds_read_b128 v[152:155], v138
	ds_read_b128 v[156:159], v138 offset:1024
	ds_read_b128 v[166:169], v138 offset:2048
	ds_read_b128 v[170:173], v138 offset:3072
	v_add_u32_e32 v138, s61, v161
	ds_read_b128 v[174:177], v138
	ds_read_b128 v[178:181], v138 offset:1024
	ds_read_b128 v[182:185], v138 offset:2048
	ds_read_b128 v[186:189], v138 offset:3072
	s_add_u32 s46, s46, 0x80000
	s_addc_u32 s47, s47, 0
	s_mov_b32 m0, s50
	ds_read_b128 v[190:193], v165 offset:32768
	ds_read_b128 v[194:197], v165 offset:33792
	ds_read_b128 v[198:201], v165 offset:34816
	ds_read_b128 v[202:205], v165 offset:35840
	ds_read_b128 v[206:209], v165 offset:36864
	ds_read_b128 v[210:213], v165 offset:37888
	ds_read_b128 v[214:217], v165 offset:38912
	global_load_lds_dwordx4 v136, s[46:47]
	s_mov_b32 m0, s51
	ds_read_b128 v[218:221], v165 offset:39936
	global_load_lds_dwordx4 v132, s[46:47]
	s_waitcnt vmcnt(8) lgkmcnt(0)
	s_barrier
	v_mfma_f32_16x16x32_bf16 v[126:129], v[152:155], v[190:193], v[126:129]
	v_mfma_f32_16x16x32_bf16 v[122:125], v[166:169], v[190:193], v[122:125]
	v_mfma_f32_16x16x32_bf16 v[110:113], v[152:155], v[198:201], v[110:113]
	v_mfma_f32_16x16x32_bf16 v[106:109], v[166:169], v[198:201], v[106:109]
	v_mfma_f32_16x16x32_bf16 v[94:97], v[152:155], v[206:209], v[94:97]
	v_mfma_f32_16x16x32_bf16 v[90:93], v[166:169], v[206:209], v[90:93]
	v_mfma_f32_16x16x32_bf16 v[78:81], v[152:155], v[214:217], v[78:81]
	v_mfma_f32_16x16x32_bf16 v[74:77], v[166:169], v[214:217], v[74:77]
	v_mfma_f32_16x16x32_bf16 v[126:129], v[156:159], v[194:197], v[126:129]
	v_mfma_f32_16x16x32_bf16 v[122:125], v[170:173], v[194:197], v[122:125]
	v_mfma_f32_16x16x32_bf16 v[110:113], v[156:159], v[202:205], v[110:113]
	v_mfma_f32_16x16x32_bf16 v[106:109], v[170:173], v[202:205], v[106:109]
	v_mfma_f32_16x16x32_bf16 v[94:97], v[156:159], v[210:213], v[94:97]
	v_mfma_f32_16x16x32_bf16 v[90:93], v[170:173], v[210:213], v[90:93]
	v_mfma_f32_16x16x32_bf16 v[78:81], v[156:159], v[218:221], v[78:81]
	v_mfma_f32_16x16x32_bf16 v[74:77], v[170:173], v[218:221], v[74:77]
	v_mfma_f32_16x16x32_bf16 v[118:121], v[174:177], v[190:193], v[118:121]
	v_mfma_f32_16x16x32_bf16 v[114:117], v[182:185], v[190:193], v[114:117]
	v_mfma_f32_16x16x32_bf16 v[102:105], v[174:177], v[198:201], v[102:105]
	v_mfma_f32_16x16x32_bf16 v[98:101], v[182:185], v[198:201], v[98:101]
	v_mfma_f32_16x16x32_bf16 v[86:89], v[174:177], v[206:209], v[86:89]
	v_mfma_f32_16x16x32_bf16 v[82:85], v[182:185], v[206:209], v[82:85]
	v_mfma_f32_16x16x32_bf16 v[70:73], v[174:177], v[214:217], v[70:73]
	v_mfma_f32_16x16x32_bf16 v[66:69], v[182:185], v[214:217], v[66:69]
	v_mfma_f32_16x16x32_bf16 v[118:121], v[178:181], v[194:197], v[118:121]
	v_mfma_f32_16x16x32_bf16 v[114:117], v[186:189], v[194:197], v[114:117]
	v_mfma_f32_16x16x32_bf16 v[102:105], v[178:181], v[202:205], v[102:105]
	v_mfma_f32_16x16x32_bf16 v[98:101], v[186:189], v[202:205], v[98:101]
	v_mfma_f32_16x16x32_bf16 v[86:89], v[178:181], v[210:213], v[86:89]
	v_mfma_f32_16x16x32_bf16 v[82:85], v[186:189], v[210:213], v[82:85]
	v_mfma_f32_16x16x32_bf16 v[70:73], v[178:181], v[218:221], v[70:73]
	v_mfma_f32_16x16x32_bf16 v[66:69], v[186:189], v[218:221], v[66:69]
	s_barrier
; #define PG8_STAGE(bufoff, gbase, voff) do { _Pragma("unroll") for (int _i = 0; _i < 2; ++_i) \
;         __builtin_amdgcn_global_load_lds((const unsigned*)((const char*)(gbase) + (voff)[_i]), (LAS unsigned*)(lds + (bufoff) + ldsw + _i * 8192), 16, 0, 0); } while (0)
; #define PG8_LDA(dst, b, h) do { _Pragma("unroll") for (int m = 0; m < 4; ++m) _Pragma("unroll") for (int k = 0; k < 2; ++k) dst[m][k] = *(const LAS bf16x8*)(lds + PG8_SA(b, h) + aoff + m * 2048 + k * 1024); } while (0)
; #define PG8_LDB(dst, b, h) do { _Pragma("unroll") for (int n = 0; n < 2; ++n) _Pragma("unroll") for (int k = 0; k < 2; ++k) dst[n][k] = *(const LAS bf16x8*)(lds + PG8_SB(b, h) + boff + n * 2048 + k * 1024); } while (0)
; #define PG8_MMA(ai, bj, At, Bt) do { __builtin_amdgcn_s_setprio(1); _Pragma("unroll") for (int m = 0; m < 4; ++m) _Pragma("unroll") for (int n = 0; n < 2; ++n) _Pragma("unroll") for (int k = 0; k < 2; ++k) \
;         acc[ai][bj][m][n] = __builtin_amdgcn_mfma_f32_16x16x32_bf16(Bt[n][k], At[m][k], acc[ai][bj][m][n], 0, 0, 0); __builtin_amdgcn_s_setprio(0); } while (0)
; #define PG8_WAIT_V(n) asm volatile("s_waitcnt vmcnt(" #n ")" ::: "memory")
; template <class Epi, class Sched, bool ABLK = false, bool ALIGN_EPI = true, bool SP2 = true, bool BBLK = true>
; __device__ __forceinline__ void gemm_phase(LAS unsigned char* lds, const Gemm g, const Sched& S, const Epi& E) {
;     ...
;         for (int t = 0; t < nt; t += 2) {
;             const bool last = (t == nt - 2);
;             const char* a1 = a_tile(uA, tbA + t + 1);
;             const char* a2 = last ? a_tile(nuA, ntbA) : a_tile(uA, tbA + t + 2); const char* b2 = last ? nB : cB + (size_t)(t + 2) * kstepB;
;             const char* a3 = last ? a_tile(nuA, ntbA + 1) : a_tile(uA, tbA + t + 3); const char* b3 = b2 + kstepB;
;             if (last && has_next) S.a_ready(nxt);
;             if constexpr (SP2) {
;             PG8_LDB(B0, 0, 0); PG8_LDB(B1, 0, 1); PG8_SCHED; PG8_LDA(At, 0, 0); PG8_STAGE(PG8_SA(1, 1), a1 + hstepA, voffA);
;             PG8_WAIT_V(8); PG8_WAIT_L(0); PG8_BAR; PG8_MMA(0, 0, At, B0); PG8_MMA(0, 1, At, B1); PG8_BAR; PG8_SCHED;
;     ...
;             PG8_LDA(At, 1, 1); PG8_STAGE(PG8_SB(1, 0), b3, voffB); PG8_STAGE(PG8_SB(1, 1), b3 + hstepB, voffB); PG8_STAGE(PG8_SA(1, 0), a3, voffA);
;             PG8_WAIT_V(8); PG8_WAIT_L(0); PG8_BAR; PG8_MMA(1, 0, At, B0); PG8_MMA(1, 1, At, B1); PG8_BAR; PG8_SCHED;
	s_add_u32 s46, s44, 0x8000
	s_addc_u32 s47, s45, 0
	s_add_i32 s66, s60, s49
	s_mov_b32 m0, s66
	ds_read_b128 v[190:193], v165 offset:49152
	ds_read_b128 v[194:197], v165 offset:50176
	ds_read_b128 v[198:201], v165 offset:51200
	ds_read_b128 v[202:205], v165 offset:52224
	global_load_lds_dwordx4 v134, s[46:47]
	s_add_i32 m0, s66, 0x2000
	s_add_u32 s44, s44, 0xc000
	v_lshl_add_u64 v[222:223], s[46:47], 0, v[130:131]
	s_addc_u32 s45, s45, 0
	s_add_i32 s46, s61, s49
	global_load_lds_dwordx4 v[222:223], off
	s_mov_b32 m0, s46
	ds_read_b128 v[206:209], v165 offset:53248
	global_load_lds_dwordx4 v134, s[44:45]
	s_add_i32 m0, s46, 0x2000
	ds_read_b128 v[210:213], v165 offset:54272
	global_load_lds_dwordx4 v130, s[44:45]
	s_mov_b32 m0, s54
	ds_read_b128 v[214:217], v165 offset:55296
	global_load_lds_dwordx4 v136, s[42:43]
	s_mov_b32 m0, s55
	ds_read_b128 v[218:221], v165 offset:56320
	global_load_lds_dwordx4 v132, s[42:43]
	s_waitcnt vmcnt(8) lgkmcnt(0)
	s_barrier
	v_mfma_f32_16x16x32_bf16 v[62:65], v[152:155], v[190:193], v[62:65]
	v_mfma_f32_16x16x32_bf16 v[58:61], v[166:169], v[190:193], v[58:61]
	v_mfma_f32_16x16x32_bf16 v[46:49], v[152:155], v[198:201], v[46:49]
	v_mfma_f32_16x16x32_bf16 v[42:45], v[166:169], v[198:201], v[42:45]
	v_mfma_f32_16x16x32_bf16 v[30:33], v[152:155], v[206:209], v[30:33]
	v_mfma_f32_16x16x32_bf16 v[26:29], v[166:169], v[206:209], v[26:29]
	v_mfma_f32_16x16x32_bf16 v[14:17], v[152:155], v[214:217], v[14:17]
	v_mfma_f32_16x16x32_bf16 v[10:13], v[166:169], v[214:217], v[10:13]
	v_mfma_f32_16x16x32_bf16 v[62:65], v[156:159], v[194:197], v[62:65]
	v_mfma_f32_16x16x32_bf16 v[58:61], v[170:173], v[194:197], v[58:61]
	v_mfma_f32_16x16x32_bf16 v[46:49], v[156:159], v[202:205], v[46:49]
	v_mfma_f32_16x16x32_bf16 v[42:45], v[170:173], v[202:205], v[42:45]
	v_mfma_f32_16x16x32_bf16 v[30:33], v[156:159], v[210:213], v[30:33]
	v_mfma_f32_16x16x32_bf16 v[26:29], v[170:173], v[210:213], v[26:29]
	v_mfma_f32_16x16x32_bf16 v[14:17], v[156:159], v[218:221], v[14:17]
	v_mfma_f32_16x16x32_bf16 v[10:13], v[170:173], v[218:221], v[10:13]
	v_mfma_f32_16x16x32_bf16 v[54:57], v[174:177], v[190:193], v[54:57]
	v_mfma_f32_16x16x32_bf16 v[50:53], v[182:185], v[190:193], v[50:53]
	v_mfma_f32_16x16x32_bf16 v[38:41], v[174:177], v[198:201], v[38:41]
	v_mfma_f32_16x16x32_bf16 v[34:37], v[182:185], v[198:201], v[34:37]
	v_mfma_f32_16x16x32_bf16 v[22:25], v[174:177], v[206:209], v[22:25]
	v_mfma_f32_16x16x32_bf16 v[18:21], v[182:185], v[206:209], v[18:21]
	v_mfma_f32_16x16x32_bf16 v[6:9], v[174:177], v[214:217], v[6:9]
	v_mfma_f32_16x16x32_bf16 v[2:5], v[182:185], v[214:217], v[2:5]
	v_mfma_f32_16x16x32_bf16 v[54:57], v[178:181], v[194:197], v[54:57]
	v_mfma_f32_16x16x32_bf16 v[50:53], v[186:189], v[194:197], v[50:53]
	v_mfma_f32_16x16x32_bf16 v[38:41], v[178:181], v[202:205], v[38:41]
	v_mfma_f32_16x16x32_bf16 v[34:37], v[186:189], v[202:205], v[34:37]
	v_mfma_f32_16x16x32_bf16 v[22:25], v[178:181], v[210:213], v[22:25]
	v_mfma_f32_16x16x32_bf16 v[18:21], v[186:189], v[210:213], v[18:21]
	v_mfma_f32_16x16x32_bf16 v[6:9], v[178:181], v[218:221], v[6:9]
	v_mfma_f32_16x16x32_bf16 v[2:5], v[186:189], v[218:221], v[2:5]
	s_barrier
	s_add_i32 s65, s65, 2
	s_add_u32 s40, s40, 0x100
	s_addc_u32 s41, s41, 0
	s_add_u32 s59, s59, 0x10000
	s_addc_u32 s64, s64, 0
	s_cmp_gt_u32 s65, 29
.LBB0_1355:
	ds_read_b128 v[152:155], v163
	ds_read_b128 v[156:159], v163 offset:1024
	ds_read_b128 v[166:169], v163 offset:2048
	ds_read_b128 v[170:173], v163 offset:3072
	ds_read_b128 v[174:177], v164
	ds_read_b128 v[178:181], v164 offset:1024
	ds_read_b128 v[182:185], v164 offset:2048
	ds_read_b128 v[186:189], v164 offset:3072
	s_add_u32 s42, s36, s40
	s_addc_u32 s43, s37, s41
	s_add_u32 s46, s42, 0x100
	s_addc_u32 s47, s43, 0
	s_add_u32 s42, s42, 0x180
	s_addc_u32 s43, s43, 0
	s_cmpk_eq_i32 s40, 0xf00
	s_cselect_b32 s43, s57, s43
	s_cselect_b32 s42, s56, s42
	s_cselect_b32 s45, s21, s64
	s_cselect_b32 s44, s23, s59
	s_cselect_b32 s47, s4, s47
	s_cselect_b32 s46, s5, s46
	v_lshl_add_u64 v[222:223], v[148:149], 0, s[40:41]
	s_add_i32 m0, s31, 0xc000
	ds_read_b128 v[190:193], v165
	ds_read_b128 v[194:197], v165 offset:1024
	ds_read_b128 v[198:201], v165 offset:2048
	ds_read_b128 v[202:205], v165 offset:3072
	ds_read_b128 v[206:209], v165 offset:4096
	ds_read_b128 v[210:213], v165 offset:5120
	ds_read_b128 v[214:217], v165 offset:6144
	global_load_lds_dwordx4 v[222:223], off
	v_lshl_add_u64 v[222:223], v[150:151], 0, s[40:41]
	s_add_i32 m0, s31, 0xe000
	ds_read_b128 v[218:221], v165 offset:7168
	global_load_lds_dwordx4 v[222:223], off
	s_waitcnt vmcnt(8) lgkmcnt(0)
	s_barrier
; #define PG8_STAGE(bufoff, gbase, voff) do { _Pragma("unroll") for (int _i = 0; _i < 2; ++_i) \
;         __builtin_amdgcn_global_load_lds((const unsigned*)((const char*)(gbase) + (voff)[_i]), (LAS unsigned*)(lds + (bufoff) + ldsw + _i * 8192), 16, 0, 0); } while (0)
; #define PG8_LDA(dst, b, h) do { _Pragma("unroll") for (int m = 0; m < 4; ++m) _Pragma("unroll") for (int k = 0; k < 2; ++k) dst[m][k] = *(const LAS bf16x8*)(lds + PG8_SA(b, h) + aoff + m * 2048 + k * 1024); } while (0)
; #define PG8_LDB(dst, b, h) do { _Pragma("unroll") for (int n = 0; n < 2; ++n) _Pragma("unroll") for (int k = 0; k < 2; ++k) dst[n][k] = *(const LAS bf16x8*)(lds + PG8_SB(b, h) + boff + n * 2048 + k * 1024); } while (0)
; #define PG8_MMA(ai, bj, At, Bt) do { __builtin_amdgcn_s_setprio(1); _Pragma("unroll") for (int m = 0; m < 4; ++m) _Pragma("unroll") for (int n = 0; n < 2; ++n) _Pragma("unroll") for (int k = 0; k < 2; ++k) \
;         acc[ai][bj][m][n] = __builtin_amdgcn_mfma_f32_16x16x32_bf16(Bt[n][k], At[m][k], acc[ai][bj][m][n], 0, 0, 0); __builtin_amdgcn_s_setprio(0); } while (0)
; #define PG8_WAIT_V(n) asm volatile("s_waitcnt vmcnt(" #n ")" ::: "memory")
; #define PG8_WAIT_L(n) asm volatile("s_waitcnt lgkmcnt(" #n ")" ::: "memory")
; #define PG8_BAR __builtin_amdgcn_s_barrier()
; #define PG8_SCHED __builtin_amdgcn_sched_barrier(0)
; template <class Epi, class Sched, bool ABLK = false, bool ALIGN_EPI = true, bool SP2 = true, bool BBLK = true>
; __device__ __forceinline__ void gemm_phase(LAS unsigned char* lds, const Gemm g, const Sched& S, const Epi& E) {
;     ...
;             PG8_LDB(B0, 0, 0); PG8_LDB(B1, 0, 1); PG8_SCHED; PG8_LDA(At, 0, 0); PG8_STAGE(PG8_SA(1, 1), a1 + hstepA, voffA);
;             PG8_WAIT_V(8); PG8_WAIT_L(0); PG8_BAR; PG8_MMA(0, 0, At, B0); PG8_MMA(0, 1, At, B1); PG8_BAR; PG8_SCHED;
;             PG8_LDA(At, 0, 1); PG8_STAGE(PG8_SB(0, 0), b2, voffB); PG8_STAGE(PG8_SB(0, 1), b2 + hstepB, voffB); PG8_STAGE(PG8_SA(0, 0), a2, voffA);
;             PG8_WAIT_V(8); PG8_WAIT_L(0); PG8_BAR; PG8_MMA(1, 0, At, B0); PG8_MMA(1, 1, At, B1); PG8_BAR; PG8_SCHED;
	v_mfma_f32_16x16x32_bf16 v[126:129], v[152:155], v[190:193], v[126:129]
	v_mfma_f32_16x16x32_bf16 v[122:125], v[166:169], v[190:193], v[122:125]
	v_mfma_f32_16x16x32_bf16 v[110:113], v[152:155], v[198:201], v[110:113]
	v_mfma_f32_16x16x32_bf16 v[106:109], v[166:169], v[198:201], v[106:109]
	v_mfma_f32_16x16x32_bf16 v[94:97], v[152:155], v[206:209], v[94:97]
	v_mfma_f32_16x16x32_bf16 v[90:93], v[166:169], v[206:209], v[90:93]
	v_mfma_f32_16x16x32_bf16 v[78:81], v[152:155], v[214:217], v[78:81]
	v_mfma_f32_16x16x32_bf16 v[74:77], v[166:169], v[214:217], v[74:77]
	v_mfma_f32_16x16x32_bf16 v[126:129], v[156:159], v[194:197], v[126:129]
	v_mfma_f32_16x16x32_bf16 v[122:125], v[170:173], v[194:197], v[122:125]
	v_mfma_f32_16x16x32_bf16 v[110:113], v[156:159], v[202:205], v[110:113]
	v_mfma_f32_16x16x32_bf16 v[106:109], v[170:173], v[202:205], v[106:109]
	v_mfma_f32_16x16x32_bf16 v[94:97], v[156:159], v[210:213], v[94:97]
	v_mfma_f32_16x16x32_bf16 v[90:93], v[170:173], v[210:213], v[90:93]
	v_mfma_f32_16x16x32_bf16 v[78:81], v[156:159], v[218:221], v[78:81]
	v_mfma_f32_16x16x32_bf16 v[74:77], v[170:173], v[218:221], v[74:77]
	v_mfma_f32_16x16x32_bf16 v[118:121], v[174:177], v[190:193], v[118:121]
	v_mfma_f32_16x16x32_bf16 v[114:117], v[182:185], v[190:193], v[114:117]
	v_mfma_f32_16x16x32_bf16 v[102:105], v[174:177], v[198:201], v[102:105]
	v_mfma_f32_16x16x32_bf16 v[98:101], v[182:185], v[198:201], v[98:101]
	v_mfma_f32_16x16x32_bf16 v[86:89], v[174:177], v[206:209], v[86:89]
	v_mfma_f32_16x16x32_bf16 v[82:85], v[182:185], v[206:209], v[82:85]
	v_mfma_f32_16x16x32_bf16 v[70:73], v[174:177], v[214:217], v[70:73]
	v_mfma_f32_16x16x32_bf16 v[66:69], v[182:185], v[214:217], v[66:69]
	v_mfma_f32_16x16x32_bf16 v[118:121], v[178:181], v[194:197], v[118:121]
	v_mfma_f32_16x16x32_bf16 v[114:117], v[186:189], v[194:197], v[114:117]
	v_mfma_f32_16x16x32_bf16 v[102:105], v[178:181], v[202:205], v[102:105]
	v_mfma_f32_16x16x32_bf16 v[98:101], v[186:189], v[202:205], v[98:101]
	v_mfma_f32_16x16x32_bf16 v[86:89], v[178:181], v[210:213], v[86:89]
	v_mfma_f32_16x16x32_bf16 v[82:85], v[186:189], v[210:213], v[82:85]
	v_mfma_f32_16x16x32_bf16 v[70:73], v[178:181], v[218:221], v[70:73]
	v_mfma_f32_16x16x32_bf16 v[66:69], v[186:189], v[218:221], v[66:69]
	s_barrier
	s_add_i32 s66, s72, s49
	s_mov_b32 m0, s66
	ds_read_b128 v[190:193], v165 offset:16384
	ds_read_b128 v[194:197], v165 offset:17408
	ds_read_b128 v[198:201], v165 offset:18432
	ds_read_b128 v[202:205], v165 offset:19456
	global_load_lds_dwordx4 v134, s[44:45]
	s_add_i32 m0, s66, 0x2000
	s_add_u32 s66, s44, 0x4000
	s_addc_u32 s67, s45, 0
	s_add_i32 s75, s73, s49
	global_load_lds_dwordx4 v130, s[44:45]
	s_mov_b32 m0, s75
	ds_read_b128 v[206:209], v165 offset:20480
	global_load_lds_dwordx4 v134, s[66:67]
	s_add_i32 m0, s75, 0x2000
	ds_read_b128 v[210:213], v165 offset:21504
	global_load_lds_dwordx4 v130, s[66:67]
	s_mov_b32 m0, s31
	ds_read_b128 v[214:217], v165 offset:22528
	global_load_lds_dwordx4 v136, s[46:47]
	s_mov_b32 m0, s35
	ds_read_b128 v[218:221], v165 offset:23552
	global_load_lds_dwordx4 v132, s[46:47]
	s_waitcnt vmcnt(8) lgkmcnt(0)
	s_barrier
	v_mfma_f32_16x16x32_bf16 v[62:65], v[152:155], v[190:193], v[62:65]
	v_mfma_f32_16x16x32_bf16 v[58:61], v[166:169], v[190:193], v[58:61]
	v_mfma_f32_16x16x32_bf16 v[46:49], v[152:155], v[198:201], v[46:49]
	v_mfma_f32_16x16x32_bf16 v[42:45], v[166:169], v[198:201], v[42:45]
	v_mfma_f32_16x16x32_bf16 v[30:33], v[152:155], v[206:209], v[30:33]
	v_mfma_f32_16x16x32_bf16 v[26:29], v[166:169], v[206:209], v[26:29]
	v_mfma_f32_16x16x32_bf16 v[14:17], v[152:155], v[214:217], v[14:17]
	v_mfma_f32_16x16x32_bf16 v[10:13], v[166:169], v[214:217], v[10:13]
	v_mfma_f32_16x16x32_bf16 v[62:65], v[156:159], v[194:197], v[62:65]
	v_mfma_f32_16x16x32_bf16 v[58:61], v[170:173], v[194:197], v[58:61]
	v_mfma_f32_16x16x32_bf16 v[46:49], v[156:159], v[202:205], v[46:49]
	v_mfma_f32_16x16x32_bf16 v[42:45], v[170:173], v[202:205], v[42:45]
	v_mfma_f32_16x16x32_bf16 v[30:33], v[156:159], v[210:213], v[30:33]
	v_mfma_f32_16x16x32_bf16 v[26:29], v[170:173], v[210:213], v[26:29]
	v_mfma_f32_16x16x32_bf16 v[14:17], v[156:159], v[218:221], v[14:17]
	v_mfma_f32_16x16x32_bf16 v[10:13], v[170:173], v[218:221], v[10:13]
	v_mfma_f32_16x16x32_bf16 v[54:57], v[174:177], v[190:193], v[54:57]
	v_mfma_f32_16x16x32_bf16 v[50:53], v[182:185], v[190:193], v[50:53]
	v_mfma_f32_16x16x32_bf16 v[38:41], v[174:177], v[198:201], v[38:41]
	v_mfma_f32_16x16x32_bf16 v[34:37], v[182:185], v[198:201], v[34:37]
	v_mfma_f32_16x16x32_bf16 v[22:25], v[174:177], v[206:209], v[22:25]
	v_mfma_f32_16x16x32_bf16 v[18:21], v[182:185], v[206:209], v[18:21]
	v_mfma_f32_16x16x32_bf16 v[6:9], v[174:177], v[214:217], v[6:9]
	v_mfma_f32_16x16x32_bf16 v[2:5], v[182:185], v[214:217], v[2:5]
	v_mfma_f32_16x16x32_bf16 v[54:57], v[178:181], v[194:197], v[54:57]
	v_mfma_f32_16x16x32_bf16 v[50:53], v[186:189], v[194:197], v[50:53]
	v_mfma_f32_16x16x32_bf16 v[38:41], v[178:181], v[202:205], v[38:41]
	v_mfma_f32_16x16x32_bf16 v[34:37], v[186:189], v[202:205], v[34:37]
	v_mfma_f32_16x16x32_bf16 v[22:25], v[178:181], v[210:213], v[22:25]
	v_mfma_f32_16x16x32_bf16 v[18:21], v[186:189], v[210:213], v[18:21]
	v_mfma_f32_16x16x32_bf16 v[6:9], v[178:181], v[218:221], v[6:9]
	v_mfma_f32_16x16x32_bf16 v[2:5], v[186:189], v[218:221], v[2:5]
	s_barrier
; #define PG8_STAGE(bufoff, gbase, voff) do { _Pragma("unroll") for (int _i = 0; _i < 2; ++_i) \
;         __builtin_amdgcn_global_load_lds((const unsigned*)((const char*)(gbase) + (voff)[_i]), (LAS unsigned*)(lds + (bufoff) + ldsw + _i * 8192), 16, 0, 0); } while (0)
; #define PG8_LDA(dst, b, h) do { _Pragma("unroll") for (int m = 0; m < 4; ++m) _Pragma("unroll") for (int k = 0; k < 2; ++k) dst[m][k] = *(const LAS bf16x8*)(lds + PG8_SA(b, h) + aoff + m * 2048 + k * 1024); } while (0)
; #define PG8_LDB(dst, b, h) do { _Pragma("unroll") for (int n = 0; n < 2; ++n) _Pragma("unroll") for (int k = 0; k < 2; ++k) dst[n][k] = *(const LAS bf16x8*)(lds + PG8_SB(b, h) + boff + n * 2048 + k * 1024); } while (0)
; #define PG8_MMA(ai, bj, At, Bt) do { __builtin_amdgcn_s_setprio(1); _Pragma("unroll") for (int m = 0; m < 4; ++m) _Pragma("unroll") for (int n = 0; n < 2; ++n) _Pragma("unroll") for (int k = 0; k < 2; ++k) \
;         acc[ai][bj][m][n] = __builtin_amdgcn_mfma_f32_16x16x32_bf16(Bt[n][k], At[m][k], acc[ai][bj][m][n], 0, 0, 0); __builtin_amdgcn_s_setprio(0); } while (0)
; #define PG8_WAIT_V(n) asm volatile("s_waitcnt vmcnt(" #n ")" ::: "memory")
; #define PG8_WAIT_L(n) asm volatile("s_waitcnt lgkmcnt(" #n ")" ::: "memory")
; #define PG8_BAR __builtin_amdgcn_s_barrier()
; #define PG8_SCHED __builtin_amdgcn_sched_barrier(0)
; template <class Epi, class Sched, bool ABLK = false, bool ALIGN_EPI = true, bool SP2 = true, bool BBLK = true>
; __device__ __forceinline__ void gemm_phase(LAS unsigned char* lds, const Gemm g, const Sched& S, const Epi& E) {
;     ...
;             PG8_LDB(B0, 1, 0); PG8_LDB(B1, 1, 1); PG8_SCHED; PG8_LDA(At, 1, 0); PG8_STAGE(PG8_SA(0, 1), a2 + hstepA, voffA);
;             PG8_WAIT_V(8); PG8_WAIT_L(0); PG8_BAR; PG8_MMA(0, 0, At, B0); PG8_MMA(0, 1, At, B1); PG8_BAR; PG8_SCHED;
;             PG8_LDA(At, 1, 1); PG8_STAGE(PG8_SB(1, 0), b3, voffB); PG8_STAGE(PG8_SB(1, 1), b3 + hstepB, voffB); PG8_STAGE(PG8_SA(1, 0), a3, voffA);
;             PG8_WAIT_V(8); PG8_WAIT_L(0); PG8_BAR; PG8_MMA(1, 0, At, B0); PG8_MMA(1, 1, At, B1); PG8_BAR; PG8_SCHED;
;     ...
;         if constexpr (ALIGN_EPI) { if (wr == 0) PG8_BAR; }
	v_add_u32_e32 v138, s60, v161
	ds_read_b128 v[152:155], v138
	ds_read_b128 v[156:159], v138 offset:1024
	ds_read_b128 v[166:169], v138 offset:2048
	ds_read_b128 v[170:173], v138 offset:3072
	v_add_u32_e32 v138, s61, v161
	ds_read_b128 v[174:177], v138
	ds_read_b128 v[178:181], v138 offset:1024
	ds_read_b128 v[182:185], v138 offset:2048
	ds_read_b128 v[186:189], v138 offset:3072
	s_add_u32 s46, s46, 0x80000
	s_addc_u32 s47, s47, 0
	s_mov_b32 m0, s50
	ds_read_b128 v[190:193], v165 offset:32768
	ds_read_b128 v[194:197], v165 offset:33792
	ds_read_b128 v[198:201], v165 offset:34816
	ds_read_b128 v[202:205], v165 offset:35840
	ds_read_b128 v[206:209], v165 offset:36864
	ds_read_b128 v[210:213], v165 offset:37888
	ds_read_b128 v[214:217], v165 offset:38912
	global_load_lds_dwordx4 v136, s[46:47]
	s_mov_b32 m0, s51
	ds_read_b128 v[218:221], v165 offset:39936
	global_load_lds_dwordx4 v132, s[46:47]
	s_waitcnt vmcnt(8) lgkmcnt(0)
	s_barrier
	v_mfma_f32_16x16x32_bf16 v[126:129], v[152:155], v[190:193], v[126:129]
	v_mfma_f32_16x16x32_bf16 v[122:125], v[166:169], v[190:193], v[122:125]
	v_mfma_f32_16x16x32_bf16 v[110:113], v[152:155], v[198:201], v[110:113]
	v_mfma_f32_16x16x32_bf16 v[106:109], v[166:169], v[198:201], v[106:109]
	v_mfma_f32_16x16x32_bf16 v[94:97], v[152:155], v[206:209], v[94:97]
	v_mfma_f32_16x16x32_bf16 v[90:93], v[166:169], v[206:209], v[90:93]
	v_mfma_f32_16x16x32_bf16 v[78:81], v[152:155], v[214:217], v[78:81]
	v_mfma_f32_16x16x32_bf16 v[74:77], v[166:169], v[214:217], v[74:77]
	v_mfma_f32_16x16x32_bf16 v[126:129], v[156:159], v[194:197], v[126:129]
	v_mfma_f32_16x16x32_bf16 v[122:125], v[170:173], v[194:197], v[122:125]
	v_mfma_f32_16x16x32_bf16 v[110:113], v[156:159], v[202:205], v[110:113]
	v_mfma_f32_16x16x32_bf16 v[106:109], v[170:173], v[202:205], v[106:109]
	v_mfma_f32_16x16x32_bf16 v[94:97], v[156:159], v[210:213], v[94:97]
	v_mfma_f32_16x16x32_bf16 v[90:93], v[170:173], v[210:213], v[90:93]
	v_mfma_f32_16x16x32_bf16 v[78:81], v[156:159], v[218:221], v[78:81]
	v_mfma_f32_16x16x32_bf16 v[74:77], v[170:173], v[218:221], v[74:77]
	v_mfma_f32_16x16x32_bf16 v[118:121], v[174:177], v[190:193], v[118:121]
	v_mfma_f32_16x16x32_bf16 v[114:117], v[182:185], v[190:193], v[114:117]
	v_mfma_f32_16x16x32_bf16 v[102:105], v[174:177], v[198:201], v[102:105]
	v_mfma_f32_16x16x32_bf16 v[98:101], v[182:185], v[198:201], v[98:101]
	v_mfma_f32_16x16x32_bf16 v[86:89], v[174:177], v[206:209], v[86:89]
	v_mfma_f32_16x16x32_bf16 v[82:85], v[182:185], v[206:209], v[82:85]
	v_mfma_f32_16x16x32_bf16 v[70:73], v[174:177], v[214:217], v[70:73]
	v_mfma_f32_16x16x32_bf16 v[66:69], v[182:185], v[214:217], v[66:69]
	v_mfma_f32_16x16x32_bf16 v[118:121], v[178:181], v[194:197], v[118:121]
	v_mfma_f32_16x16x32_bf16 v[114:117], v[186:189], v[194:197], v[114:117]
	v_mfma_f32_16x16x32_bf16 v[102:105], v[178:181], v[202:205], v[102:105]
	v_mfma_f32_16x16x32_bf16 v[98:101], v[186:189], v[202:205], v[98:101]
	v_mfma_f32_16x16x32_bf16 v[86:89], v[178:181], v[210:213], v[86:89]
	v_mfma_f32_16x16x32_bf16 v[82:85], v[186:189], v[210:213], v[82:85]
	v_mfma_f32_16x16x32_bf16 v[70:73], v[178:181], v[218:221], v[70:73]
	v_mfma_f32_16x16x32_bf16 v[66:69], v[186:189], v[218:221], v[66:69]
	s_barrier
	s_add_u32 s46, s44, 0x8000
	s_addc_u32 s47, s45, 0
	s_add_i32 s66, s60, s49
	s_mov_b32 m0, s66
	ds_read_b128 v[190:193], v165 offset:49152
	ds_read_b128 v[194:197], v165 offset:50176
	ds_read_b128 v[198:201], v165 offset:51200
	ds_read_b128 v[202:205], v165 offset:52224
	global_load_lds_dwordx4 v134, s[46:47]
	s_add_i32 m0, s66, 0x2000
	s_add_u32 s44, s44, 0xc000
	v_lshl_add_u64 v[222:223], s[46:47], 0, v[130:131]
	s_addc_u32 s45, s45, 0
	s_add_i32 s46, s61, s49
	global_load_lds_dwordx4 v[222:223], off
	s_mov_b32 m0, s46
	ds_read_b128 v[206:209], v165 offset:53248
	global_load_lds_dwordx4 v134, s[44:45]
	s_add_i32 m0, s46, 0x2000
	ds_read_b128 v[210:213], v165 offset:54272
	global_load_lds_dwordx4 v130, s[44:45]
	s_mov_b32 m0, s54
	ds_read_b128 v[214:217], v165 offset:55296
	global_load_lds_dwordx4 v136, s[42:43]
	s_mov_b32 m0, s55
	ds_read_b128 v[218:221], v165 offset:56320
	global_load_lds_dwordx4 v132, s[42:43]
	s_waitcnt vmcnt(8) lgkmcnt(0)
	s_barrier
	v_mfma_f32_16x16x32_bf16 v[62:65], v[152:155], v[190:193], v[62:65]
	v_mfma_f32_16x16x32_bf16 v[58:61], v[166:169], v[190:193], v[58:61]
	v_mfma_f32_16x16x32_bf16 v[46:49], v[152:155], v[198:201], v[46:49]
	v_mfma_f32_16x16x32_bf16 v[42:45], v[166:169], v[198:201], v[42:45]
	v_mfma_f32_16x16x32_bf16 v[30:33], v[152:155], v[206:209], v[30:33]
	v_mfma_f32_16x16x32_bf16 v[26:29], v[166:169], v[206:209], v[26:29]
	v_mfma_f32_16x16x32_bf16 v[14:17], v[152:155], v[214:217], v[14:17]
	v_mfma_f32_16x16x32_bf16 v[10:13], v[166:169], v[214:217], v[10:13]
	v_mfma_f32_16x16x32_bf16 v[62:65], v[156:159], v[194:197], v[62:65]
	v_mfma_f32_16x16x32_bf16 v[58:61], v[170:173], v[194:197], v[58:61]
	v_mfma_f32_16x16x32_bf16 v[46:49], v[156:159], v[202:205], v[46:49]
	v_mfma_f32_16x16x32_bf16 v[42:45], v[170:173], v[202:205], v[42:45]
	v_mfma_f32_16x16x32_bf16 v[30:33], v[156:159], v[210:213], v[30:33]
	v_mfma_f32_16x16x32_bf16 v[26:29], v[170:173], v[210:213], v[26:29]
	v_mfma_f32_16x16x32_bf16 v[14:17], v[156:159], v[218:221], v[14:17]
	v_mfma_f32_16x16x32_bf16 v[10:13], v[170:173], v[218:221], v[10:13]
	v_mfma_f32_16x16x32_bf16 v[54:57], v[174:177], v[190:193], v[54:57]
	v_mfma_f32_16x16x32_bf16 v[50:53], v[182:185], v[190:193], v[50:53]
	v_mfma_f32_16x16x32_bf16 v[38:41], v[174:177], v[198:201], v[38:41]
	v_mfma_f32_16x16x32_bf16 v[34:37], v[182:185], v[198:201], v[34:37]
	v_mfma_f32_16x16x32_bf16 v[22:25], v[174:177], v[206:209], v[22:25]
	v_mfma_f32_16x16x32_bf16 v[18:21], v[182:185], v[206:209], v[18:21]
	v_mfma_f32_16x16x32_bf16 v[6:9], v[174:177], v[214:217], v[6:9]
	v_mfma_f32_16x16x32_bf16 v[2:5], v[182:185], v[214:217], v[2:5]
	v_mfma_f32_16x16x32_bf16 v[54:57], v[178:181], v[194:197], v[54:57]
	v_mfma_f32_16x16x32_bf16 v[50:53], v[186:189], v[194:197], v[50:53]
	v_mfma_f32_16x16x32_bf16 v[38:41], v[178:181], v[202:205], v[38:41]
	v_mfma_f32_16x16x32_bf16 v[34:37], v[186:189], v[202:205], v[34:37]
	v_mfma_f32_16x16x32_bf16 v[22:25], v[178:181], v[210:213], v[22:25]
	v_mfma_f32_16x16x32_bf16 v[18:21], v[186:189], v[210:213], v[18:21]
	v_mfma_f32_16x16x32_bf16 v[6:9], v[178:181], v[218:221], v[6:9]
	v_mfma_f32_16x16x32_bf16 v[2:5], v[186:189], v[218:221], v[2:5]
	s_barrier
	s_add_i32 s65, s65, 2
	s_add_u32 s40, s40, 0x100
	s_addc_u32 s41, s41, 0
	s_add_u32 s59, s59, 0x10000
	s_addc_u32 s64, s64, 0
	s_cmp_gt_u32 s65, 29
	s_cbranch_scc0 .LBB0_1355
	s_and_b64 vcc, exec, s[12:13]
	s_cbranch_vccz .LBB0_1358
	s_barrier

; #define PG8_STAGE(bufoff, gbase, voff) do { _Pragma("unroll") for (int _i = 0; _i < 2; ++_i) \
;         __builtin_amdgcn_global_load_lds((const unsigned*)((const char*)(gbase) + (voff)[_i]), (LAS unsigned*)(lds + (bufoff) + ldsw + _i * 8192), 16, 0, 0); } while (0)
; #define PG8_LDA(dst, b, h) do { _Pragma("unroll") for (int m = 0; m < 4; ++m) _Pragma("unroll") for (int k = 0; k < 2; ++k) dst[m][k] = *(const LAS bf16x8*)(lds + PG8_SA(b, h) + aoff + m * 2048 + k * 1024); } while (0)
; #define PG8_LDB(dst, b, h) do { _Pragma("unroll") for (int n = 0; n < 2; ++n) _Pragma("unroll") for (int k = 0; k < 2; ++k) dst[n][k] = *(const LAS bf16x8*)(lds + PG8_SB(b, h) + boff + n * 2048 + k * 1024); } while (0)
; #define PG8_WAIT_V(n) asm volatile("s_waitcnt vmcnt(" #n ")" ::: "memory")
; #define PG8_WAIT_L(n) asm volatile("s_waitcnt lgkmcnt(" #n ")" ::: "memory")
; #define PG8_BAR __builtin_amdgcn_s_barrier()
; #define PG8_SCHED __builtin_amdgcn_sched_barrier(0)
; template <class Epi, class Sched, bool ABLK = false, bool ALIGN_EPI = true, bool SP2 = true, bool BBLK = true>
; __device__ __forceinline__ void gemm_phase(LAS unsigned char* lds, const Gemm g, const Sched& S, const Epi& E) {
;     ...
;         const bool has_next = S.next(ui + 1, nxt);
;         const int nt = cur.nt;
;         const char* nuA = has_next ? a_unit(nxt) : uA; const int ntbA = has_next ? nxt.k0 / BK : tbA; const char* nB = has_next ? (const char*)g.Bt + (size_t)nxt.pn * tstepB + b_k0(nxt.k0) : cB;
;         for (int t = 0; t < nt; t += 2) {
;             const bool last = (t == nt - 2);
;             const char* a1 = a_tile(uA, tbA + t + 1);
;             const char* a2 = last ? a_tile(nuA, ntbA) : a_tile(uA, tbA + t + 2); const char* b2 = last ? nB : cB + (size_t)(t + 2) * kstepB;
;             const char* a3 = last ? a_tile(nuA, ntbA + 1) : a_tile(uA, tbA + t + 3); const char* b3 = b2 + kstepB;
;             if (last && has_next) S.a_ready(nxt);
;             if constexpr (SP2) {
;             PG8_LDB(B0, 0, 0); PG8_LDB(B1, 0, 1); PG8_SCHED; PG8_LDA(At, 0, 0); PG8_STAGE(PG8_SA(1, 1), a1 + hstepA, voffA);
;             PG8_WAIT_V(8); PG8_WAIT_L(0); PG8_BAR; PG8_MMA(0, 0, At, B0); PG8_MMA(0, 1, At, B1); PG8_BAR; PG8_SCHED;
;             PG8_LDA(At, 0, 1); PG8_STAGE(PG8_SB(0, 0), b2, voffB); PG8_STAGE(PG8_SB(0, 1), b2 + hstepB, voffB); PG8_STAGE(PG8_SA(0, 0), a2, voffA);
.LBB0_1715:
	s_ashr_i32 s81, s80, 31
	s_andn2_b64 vcc, exec, s[4:5]
	s_lshl_b64 s[20:21], s[80:81], 20
	s_add_u32 s20, s1, s20
	s_addc_u32 s21, s36, s21
	s_and_b64 s[22:23], s[4:5], exec
	s_cselect_b32 s31, s21, s29
	s_cselect_b32 s49, s20, s28
	s_ashr_i32 s22, s63, 31
	s_lshr_b32 s22, s22, 26
	s_add_i32 s22, s63, s22
	s_ashr_i32 s22, s22, 6
	s_and_b64 s[24:25], s[4:5], exec
	s_cselect_b32 s34, s22, s30
	s_ashr_i32 s79, s78, 31
	s_lshl_b64 s[24:25], s[78:79], 20
	s_add_u32 s35, s37, s24
	s_addc_u32 s50, s38, s25
	s_ashr_i32 s23, s22, 31
	s_lshl_b64 s[24:25], s[22:23], 15
	s_add_u32 s24, s35, s24
	s_addc_u32 s25, s50, s25
	v_cndmask_b32_e64 v2, 0, 1, s[4:5]
	s_and_b64 s[4:5], s[4:5], exec
	s_cselect_b32 s4, s25, s27
	s_cselect_b32 s5, s24, s26
	s_ashr_i32 s35, s34, 31
	s_lshl_b64 s[34:35], s[34:35], 7
	s_add_u32 s23, s49, s34
	s_addc_u32 s49, s31, s35
	s_add_u32 s50, s23, 0x80
	s_addc_u32 s51, s49, 0
	s_add_u32 s52, s26, 0x10000
	s_addc_u32 s53, s27, 0
	s_ashr_i32 s31, s30, 31
	v_cmp_ne_u32_e64 s[10:11], 1, v2
	s_lshl_b64 s[26:27], s[30:31], 7
	v_lshl_add_u64 v[2:3], s[28:29], 0, v[142:143]
	s_add_u32 s54, s28, s26
	v_lshl_add_u64 v[146:147], v[2:3], 0, s[26:27]
	v_lshl_add_u64 v[2:3], s[28:29], 0, v[144:145]
	s_addc_u32 s55, s29, s27
	v_lshl_add_u64 v[148:149], v[2:3], 0, s[26:27]
	s_lshl_b32 s26, s47, 7
	s_addk_i32 s26, 0xfc00
	v_mov_b32_e32 v2, 0
	s_add_u32 s56, s26, 0x300
	s_mov_b32 s57, 0
	s_mov_b64 s[26:27], 0
	ds_read_b128 v[156:159], v152
	ds_read_b128 v[160:163], v152 offset:1024
	ds_read_b128 v[164:167], v152 offset:2048
	ds_read_b128 v[168:171], v152 offset:3072
	ds_read_b128 v[172:175], v153
	ds_read_b128 v[176:179], v153 offset:1024
	ds_read_b128 v[180:183], v153 offset:2048
	ds_read_b128 v[184:187], v153 offset:3072
	s_add_u32 s28, s54, s26
	s_addc_u32 s29, s55, s27
	s_add_u32 s34, s28, 0x100
	s_addc_u32 s35, s29, 0
	s_add_i32 s57, s57, 2
	s_add_u32 s28, s28, 0x180
	s_addc_u32 s29, s29, 0
	s_cmp_eq_u32 s56, s26
	s_cselect_b32 s29, s51, s29
	s_cselect_b32 s28, s50, s28
	s_cselect_b32 s31, s4, s53
	s_cselect_b32 s30, s5, s52
	s_cselect_b32 s35, s49, s35
	s_cselect_b32 s34, s23, s34
	v_lshl_add_u64 v[220:221], v[146:147], 0, s[26:27]
	s_add_i32 m0, s40, 0xc000
	ds_read_b128 v[188:191], v154
	ds_read_b128 v[192:195], v154 offset:1024
	ds_read_b128 v[196:199], v154 offset:2048
	ds_read_b128 v[200:203], v154 offset:3072
	ds_read_b128 v[204:207], v154 offset:4096
	ds_read_b128 v[208:211], v154 offset:5120
	ds_read_b128 v[212:215], v154 offset:6144
	global_load_lds_dwordx4 v[220:221], off
	v_lshl_add_u64 v[220:221], v[148:149], 0, s[26:27]
	s_add_i32 m0, s40, 0xe000
	ds_read_b128 v[216:219], v154 offset:7168
	global_load_lds_dwordx4 v[220:221], off
	s_waitcnt vmcnt(8) lgkmcnt(0)
	s_barrier
	v_mfma_f32_16x16x32_bf16 v[126:129], v[156:159], v[188:191], 0
	v_mfma_f32_16x16x32_bf16 v[122:125], v[164:167], v[188:191], 0
	v_mfma_f32_16x16x32_bf16 v[110:113], v[156:159], v[196:199], 0
	v_mfma_f32_16x16x32_bf16 v[106:109], v[164:167], v[196:199], 0
	v_mfma_f32_16x16x32_bf16 v[94:97], v[156:159], v[204:207], 0
	v_mfma_f32_16x16x32_bf16 v[90:93], v[164:167], v[204:207], 0
	v_mfma_f32_16x16x32_bf16 v[78:81], v[156:159], v[212:215], 0
	v_mfma_f32_16x16x32_bf16 v[74:77], v[164:167], v[212:215], 0
	v_mfma_f32_16x16x32_bf16 v[126:129], v[160:163], v[192:195], v[126:129]
	v_mfma_f32_16x16x32_bf16 v[122:125], v[168:171], v[192:195], v[122:125]
	v_mfma_f32_16x16x32_bf16 v[110:113], v[160:163], v[200:203], v[110:113]
	v_mfma_f32_16x16x32_bf16 v[106:109], v[168:171], v[200:203], v[106:109]
	v_mfma_f32_16x16x32_bf16 v[94:97], v[160:163], v[208:211], v[94:97]
	v_mfma_f32_16x16x32_bf16 v[90:93], v[168:171], v[208:211], v[90:93]
	v_mfma_f32_16x16x32_bf16 v[78:81], v[160:163], v[216:219], v[78:81]
	v_mfma_f32_16x16x32_bf16 v[74:77], v[168:171], v[216:219], v[74:77]
	v_mfma_f32_16x16x32_bf16 v[118:121], v[172:175], v[188:191], 0
	v_mfma_f32_16x16x32_bf16 v[114:117], v[180:183], v[188:191], 0
	v_mfma_f32_16x16x32_bf16 v[102:105], v[172:175], v[196:199], 0
	v_mfma_f32_16x16x32_bf16 v[98:101], v[180:183], v[196:199], 0
	v_mfma_f32_16x16x32_bf16 v[86:89], v[172:175], v[204:207], 0
	v_mfma_f32_16x16x32_bf16 v[82:85], v[180:183], v[204:207], 0
	v_mfma_f32_16x16x32_bf16 v[70:73], v[172:175], v[212:215], 0
	v_mfma_f32_16x16x32_bf16 v[66:69], v[180:183], v[212:215], 0
	v_mfma_f32_16x16x32_bf16 v[118:121], v[176:179], v[192:195], v[118:121]
	v_mfma_f32_16x16x32_bf16 v[114:117], v[184:187], v[192:195], v[114:117]
	v_mfma_f32_16x16x32_bf16 v[102:105], v[176:179], v[200:203], v[102:105]
	v_mfma_f32_16x16x32_bf16 v[98:101], v[184:187], v[200:203], v[98:101]
	v_mfma_f32_16x16x32_bf16 v[86:89], v[176:179], v[208:211], v[86:89]
	v_mfma_f32_16x16x32_bf16 v[82:85], v[184:187], v[208:211], v[82:85]
	v_mfma_f32_16x16x32_bf16 v[70:73], v[176:179], v[216:219], v[70:73]
	v_mfma_f32_16x16x32_bf16 v[66:69], v[184:187], v[216:219], v[66:69]
	s_barrier
	s_add_i32 s58, s72, s39
	s_mov_b32 m0, s58
	ds_read_b128 v[188:191], v154 offset:16384
	ds_read_b128 v[192:195], v154 offset:17408
	ds_read_b128 v[196:199], v154 offset:18432
	ds_read_b128 v[200:203], v154 offset:19456
	global_load_lds_dwordx4 v132, s[30:31]
	s_add_i32 m0, s58, 0x2000
	s_add_u32 s58, s30, 0x4000
	s_addc_u32 s59, s31, 0
	s_add_i32 s64, s73, s39
	global_load_lds_dwordx4 v136, s[30:31]
	s_mov_b32 m0, s64
	ds_read_b128 v[204:207], v154 offset:20480
	global_load_lds_dwordx4 v132, s[58:59]
	s_add_i32 m0, s64, 0x2000
	ds_read_b128 v[208:211], v154 offset:21504
	global_load_lds_dwordx4 v136, s[58:59]
	s_mov_b32 m0, s40
	ds_read_b128 v[212:215], v154 offset:22528
	global_load_lds_dwordx4 v130, s[34:35]
	s_mov_b32 m0, s41
	ds_read_b128 v[216:219], v154 offset:23552
	global_load_lds_dwordx4 v134, s[34:35]
	s_waitcnt vmcnt(8) lgkmcnt(0)
	s_barrier
; #define PG8_STAGE(bufoff, gbase, voff) do { _Pragma("unroll") for (int _i = 0; _i < 2; ++_i) \
;         __builtin_amdgcn_global_load_lds((const unsigned*)((const char*)(gbase) + (voff)[_i]), (LAS unsigned*)(lds + (bufoff) + ldsw + _i * 8192), 16, 0, 0); } while (0)
; #define PG8_LDA(dst, b, h) do { _Pragma("unroll") for (int m = 0; m < 4; ++m) _Pragma("unroll") for (int k = 0; k < 2; ++k) dst[m][k] = *(const LAS bf16x8*)(lds + PG8_SA(b, h) + aoff + m * 2048 + k * 1024); } while (0)
; #define PG8_LDB(dst, b, h) do { _Pragma("unroll") for (int n = 0; n < 2; ++n) _Pragma("unroll") for (int k = 0; k < 2; ++k) dst[n][k] = *(const LAS bf16x8*)(lds + PG8_SB(b, h) + boff + n * 2048 + k * 1024); } while (0)
; #define PG8_MMA(ai, bj, At, Bt) do { __builtin_amdgcn_s_setprio(1); _Pragma("unroll") for (int m = 0; m < 4; ++m) _Pragma("unroll") for (int n = 0; n < 2; ++n) _Pragma("unroll") for (int k = 0; k < 2; ++k) \
;         acc[ai][bj][m][n] = __builtin_amdgcn_mfma_f32_16x16x32_bf16(Bt[n][k], At[m][k], acc[ai][bj][m][n], 0, 0, 0); __builtin_amdgcn_s_setprio(0); } while (0)
; #define PG8_WAIT_V(n) asm volatile("s_waitcnt vmcnt(" #n ")" ::: "memory")
; #define PG8_WAIT_L(n) asm volatile("s_waitcnt lgkmcnt(" #n ")" ::: "memory")
; #define PG8_BAR __builtin_amdgcn_s_barrier()
; #define PG8_SCHED __builtin_amdgcn_sched_barrier(0)
; template <class Epi, class Sched, bool ABLK = false, bool ALIGN_EPI = true, bool SP2 = true, bool BBLK = true>
; __device__ __forceinline__ void gemm_phase(LAS unsigned char* lds, const Gemm g, const Sched& S, const Epi& E) {
;     ...
;             PG8_WAIT_V(8); PG8_WAIT_L(0); PG8_BAR; PG8_MMA(1, 0, At, B0); PG8_MMA(1, 1, At, B1); PG8_BAR; PG8_SCHED;
;             PG8_LDB(B0, 1, 0); PG8_LDB(B1, 1, 1); PG8_SCHED; PG8_LDA(At, 1, 0); PG8_STAGE(PG8_SA(0, 1), a2 + hstepA, voffA);
;             PG8_WAIT_V(8); PG8_WAIT_L(0); PG8_BAR; PG8_MMA(0, 0, At, B0); PG8_MMA(0, 1, At, B1); PG8_BAR; PG8_SCHED;
	v_mfma_f32_16x16x32_bf16 v[62:65], v[156:159], v[188:191], 0
	v_mfma_f32_16x16x32_bf16 v[58:61], v[164:167], v[188:191], 0
	v_mfma_f32_16x16x32_bf16 v[46:49], v[156:159], v[196:199], 0
	v_mfma_f32_16x16x32_bf16 v[42:45], v[164:167], v[196:199], 0
	v_mfma_f32_16x16x32_bf16 v[30:33], v[156:159], v[204:207], 0
	v_mfma_f32_16x16x32_bf16 v[26:29], v[164:167], v[204:207], 0
	v_mfma_f32_16x16x32_bf16 v[14:17], v[156:159], v[212:215], 0
	v_mfma_f32_16x16x32_bf16 v[10:13], v[164:167], v[212:215], 0
	v_mfma_f32_16x16x32_bf16 v[62:65], v[160:163], v[192:195], v[62:65]
	v_mfma_f32_16x16x32_bf16 v[58:61], v[168:171], v[192:195], v[58:61]
	v_mfma_f32_16x16x32_bf16 v[46:49], v[160:163], v[200:203], v[46:49]
	v_mfma_f32_16x16x32_bf16 v[42:45], v[168:171], v[200:203], v[42:45]
	v_mfma_f32_16x16x32_bf16 v[30:33], v[160:163], v[208:211], v[30:33]
	v_mfma_f32_16x16x32_bf16 v[26:29], v[168:171], v[208:211], v[26:29]
	v_mfma_f32_16x16x32_bf16 v[14:17], v[160:163], v[216:219], v[14:17]
	v_mfma_f32_16x16x32_bf16 v[10:13], v[168:171], v[216:219], v[10:13]
	v_mfma_f32_16x16x32_bf16 v[54:57], v[172:175], v[188:191], 0
	v_mfma_f32_16x16x32_bf16 v[50:53], v[180:183], v[188:191], 0
	v_mfma_f32_16x16x32_bf16 v[38:41], v[172:175], v[196:199], 0
	v_mfma_f32_16x16x32_bf16 v[34:37], v[180:183], v[196:199], 0
	v_mfma_f32_16x16x32_bf16 v[22:25], v[172:175], v[204:207], 0
	v_mfma_f32_16x16x32_bf16 v[18:21], v[180:183], v[204:207], 0
	v_mfma_f32_16x16x32_bf16 v[6:9], v[172:175], v[212:215], 0
	v_mfma_f32_16x16x32_bf16 v[2:5], v[180:183], v[212:215], 0
	v_mfma_f32_16x16x32_bf16 v[54:57], v[176:179], v[192:195], v[54:57]
	v_mfma_f32_16x16x32_bf16 v[50:53], v[184:187], v[192:195], v[50:53]
	v_mfma_f32_16x16x32_bf16 v[38:41], v[176:179], v[200:203], v[38:41]
	v_mfma_f32_16x16x32_bf16 v[34:37], v[184:187], v[200:203], v[34:37]
	v_mfma_f32_16x16x32_bf16 v[22:25], v[176:179], v[208:211], v[22:25]
	v_mfma_f32_16x16x32_bf16 v[18:21], v[184:187], v[208:211], v[18:21]
	v_mfma_f32_16x16x32_bf16 v[6:9], v[176:179], v[216:219], v[6:9]
	v_mfma_f32_16x16x32_bf16 v[2:5], v[184:187], v[216:219], v[2:5]
	s_barrier
	v_add_u32_e32 v155, s60, v150
	ds_read_b128 v[156:159], v155
	ds_read_b128 v[160:163], v155 offset:1024
	ds_read_b128 v[164:167], v155 offset:2048
	ds_read_b128 v[168:171], v155 offset:3072
	v_add_u32_e32 v155, s61, v150
	ds_read_b128 v[172:175], v155
	ds_read_b128 v[176:179], v155 offset:1024
	ds_read_b128 v[180:183], v155 offset:2048
	ds_read_b128 v[184:187], v155 offset:3072
	s_add_u32 s34, s34, 0x80000
	s_addc_u32 s35, s35, 0
	s_mov_b32 m0, s42
	ds_read_b128 v[188:191], v154 offset:32768
	ds_read_b128 v[192:195], v154 offset:33792
	ds_read_b128 v[196:199], v154 offset:34816
	ds_read_b128 v[200:203], v154 offset:35840
	ds_read_b128 v[204:207], v154 offset:36864
	ds_read_b128 v[208:211], v154 offset:37888
	ds_read_b128 v[212:215], v154 offset:38912
	global_load_lds_dwordx4 v130, s[34:35]
	s_mov_b32 m0, s43
	ds_read_b128 v[216:219], v154 offset:39936
	global_load_lds_dwordx4 v134, s[34:35]
	s_waitcnt vmcnt(8) lgkmcnt(0)
	s_barrier
	v_mfma_f32_16x16x32_bf16 v[126:129], v[156:159], v[188:191], v[126:129]
	v_mfma_f32_16x16x32_bf16 v[122:125], v[164:167], v[188:191], v[122:125]
	v_mfma_f32_16x16x32_bf16 v[110:113], v[156:159], v[196:199], v[110:113]
	v_mfma_f32_16x16x32_bf16 v[106:109], v[164:167], v[196:199], v[106:109]
	v_mfma_f32_16x16x32_bf16 v[94:97], v[156:159], v[204:207], v[94:97]
	v_mfma_f32_16x16x32_bf16 v[90:93], v[164:167], v[204:207], v[90:93]
	v_mfma_f32_16x16x32_bf16 v[78:81], v[156:159], v[212:215], v[78:81]
	v_mfma_f32_16x16x32_bf16 v[74:77], v[164:167], v[212:215], v[74:77]
	v_mfma_f32_16x16x32_bf16 v[126:129], v[160:163], v[192:195], v[126:129]
	v_mfma_f32_16x16x32_bf16 v[122:125], v[168:171], v[192:195], v[122:125]
	v_mfma_f32_16x16x32_bf16 v[110:113], v[160:163], v[200:203], v[110:113]
	v_mfma_f32_16x16x32_bf16 v[106:109], v[168:171], v[200:203], v[106:109]
	v_mfma_f32_16x16x32_bf16 v[94:97], v[160:163], v[208:211], v[94:97]
	v_mfma_f32_16x16x32_bf16 v[90:93], v[168:171], v[208:211], v[90:93]
	v_mfma_f32_16x16x32_bf16 v[78:81], v[160:163], v[216:219], v[78:81]
	v_mfma_f32_16x16x32_bf16 v[74:77], v[168:171], v[216:219], v[74:77]
	v_mfma_f32_16x16x32_bf16 v[118:121], v[172:175], v[188:191], v[118:121]
	v_mfma_f32_16x16x32_bf16 v[114:117], v[180:183], v[188:191], v[114:117]
	v_mfma_f32_16x16x32_bf16 v[102:105], v[172:175], v[196:199], v[102:105]
	v_mfma_f32_16x16x32_bf16 v[98:101], v[180:183], v[196:199], v[98:101]
	v_mfma_f32_16x16x32_bf16 v[86:89], v[172:175], v[204:207], v[86:89]
	v_mfma_f32_16x16x32_bf16 v[82:85], v[180:183], v[204:207], v[82:85]
	v_mfma_f32_16x16x32_bf16 v[70:73], v[172:175], v[212:215], v[70:73]
	v_mfma_f32_16x16x32_bf16 v[66:69], v[180:183], v[212:215], v[66:69]
	v_mfma_f32_16x16x32_bf16 v[118:121], v[176:179], v[192:195], v[118:121]
	v_mfma_f32_16x16x32_bf16 v[114:117], v[184:187], v[192:195], v[114:117]
	v_mfma_f32_16x16x32_bf16 v[102:105], v[176:179], v[200:203], v[102:105]
	v_mfma_f32_16x16x32_bf16 v[98:101], v[184:187], v[200:203], v[98:101]
	v_mfma_f32_16x16x32_bf16 v[86:89], v[176:179], v[208:211], v[86:89]
	v_mfma_f32_16x16x32_bf16 v[82:85], v[184:187], v[208:211], v[82:85]
	v_mfma_f32_16x16x32_bf16 v[70:73], v[176:179], v[216:219], v[70:73]
	v_mfma_f32_16x16x32_bf16 v[66:69], v[184:187], v[216:219], v[66:69]
	s_barrier
; #define PG8_STAGE(bufoff, gbase, voff) do { _Pragma("unroll") for (int _i = 0; _i < 2; ++_i) \
;         __builtin_amdgcn_global_load_lds((const unsigned*)((const char*)(gbase) + (voff)[_i]), (LAS unsigned*)(lds + (bufoff) + ldsw + _i * 8192), 16, 0, 0); } while (0)
; #define PG8_LDA(dst, b, h) do { _Pragma("unroll") for (int m = 0; m < 4; ++m) _Pragma("unroll") for (int k = 0; k < 2; ++k) dst[m][k] = *(const LAS bf16x8*)(lds + PG8_SA(b, h) + aoff + m * 2048 + k * 1024); } while (0)
; #define PG8_LDB(dst, b, h) do { _Pragma("unroll") for (int n = 0; n < 2; ++n) _Pragma("unroll") for (int k = 0; k < 2; ++k) dst[n][k] = *(const LAS bf16x8*)(lds + PG8_SB(b, h) + boff + n * 2048 + k * 1024); } while (0)
; #define PG8_MMA(ai, bj, At, Bt) do { __builtin_amdgcn_s_setprio(1); _Pragma("unroll") for (int m = 0; m < 4; ++m) _Pragma("unroll") for (int n = 0; n < 2; ++n) _Pragma("unroll") for (int k = 0; k < 2; ++k) \
;         acc[ai][bj][m][n] = __builtin_amdgcn_mfma_f32_16x16x32_bf16(Bt[n][k], At[m][k], acc[ai][bj][m][n], 0, 0, 0); __builtin_amdgcn_s_setprio(0); } while (0)
; #define PG8_WAIT_V(n) asm volatile("s_waitcnt vmcnt(" #n ")" ::: "memory")
; template <class Epi, class Sched, bool ABLK = false, bool ALIGN_EPI = true, bool SP2 = true, bool BBLK = true>
; __device__ __forceinline__ void gemm_phase(LAS unsigned char* lds, const Gemm g, const Sched& S, const Epi& E) {
;     ...
;         for (int t = 0; t < nt; t += 2) {
;             const bool last = (t == nt - 2);
;             const char* a1 = a_tile(uA, tbA + t + 1);
;             const char* a2 = last ? a_tile(nuA, ntbA) : a_tile(uA, tbA + t + 2); const char* b2 = last ? nB : cB + (size_t)(t + 2) * kstepB;
;             const char* a3 = last ? a_tile(nuA, ntbA + 1) : a_tile(uA, tbA + t + 3); const char* b3 = b2 + kstepB;
;             if (last && has_next) S.a_ready(nxt);
;             if constexpr (SP2) {
;             PG8_LDB(B0, 0, 0); PG8_LDB(B1, 0, 1); PG8_SCHED; PG8_LDA(At, 0, 0); PG8_STAGE(PG8_SA(1, 1), a1 + hstepA, voffA);
;             PG8_WAIT_V(8); PG8_WAIT_L(0); PG8_BAR; PG8_MMA(0, 0, At, B0); PG8_MMA(0, 1, At, B1); PG8_BAR; PG8_SCHED;
;     ...
;             PG8_LDA(At, 1, 1); PG8_STAGE(PG8_SB(1, 0), b3, voffB); PG8_STAGE(PG8_SB(1, 1), b3 + hstepB, voffB); PG8_STAGE(PG8_SA(1, 0), a3, voffA);
;             PG8_WAIT_V(8); PG8_WAIT_L(0); PG8_BAR; PG8_MMA(1, 0, At, B0); PG8_MMA(1, 1, At, B1); PG8_BAR; PG8_SCHED;
	s_add_u32 s34, s30, 0x8000
	s_addc_u32 s35, s31, 0
	s_add_i32 s58, s60, s39
	s_mov_b32 m0, s58
	ds_read_b128 v[188:191], v154 offset:49152
	ds_read_b128 v[192:195], v154 offset:50176
	ds_read_b128 v[196:199], v154 offset:51200
	ds_read_b128 v[200:203], v154 offset:52224
	global_load_lds_dwordx4 v132, s[34:35]
	s_add_i32 m0, s58, 0x2000
	s_add_u32 s30, s30, 0xc000
	v_lshl_add_u64 v[220:221], s[34:35], 0, v[136:137]
	s_addc_u32 s31, s31, 0
	s_add_i32 s34, s61, s39
	global_load_lds_dwordx4 v[220:221], off
	s_mov_b32 m0, s34
	ds_read_b128 v[204:207], v154 offset:53248
	global_load_lds_dwordx4 v132, s[30:31]
	s_add_i32 m0, s34, 0x2000
	ds_read_b128 v[208:211], v154 offset:54272
	global_load_lds_dwordx4 v136, s[30:31]
	s_mov_b32 m0, s44
	ds_read_b128 v[212:215], v154 offset:55296
	global_load_lds_dwordx4 v130, s[28:29]
	s_mov_b32 m0, s45
	ds_read_b128 v[216:219], v154 offset:56320
	global_load_lds_dwordx4 v134, s[28:29]
	s_waitcnt vmcnt(8) lgkmcnt(0)
	s_barrier
	v_mfma_f32_16x16x32_bf16 v[62:65], v[156:159], v[188:191], v[62:65]
	v_mfma_f32_16x16x32_bf16 v[58:61], v[164:167], v[188:191], v[58:61]
	v_mfma_f32_16x16x32_bf16 v[46:49], v[156:159], v[196:199], v[46:49]
	v_mfma_f32_16x16x32_bf16 v[42:45], v[164:167], v[196:199], v[42:45]
	v_mfma_f32_16x16x32_bf16 v[30:33], v[156:159], v[204:207], v[30:33]
	v_mfma_f32_16x16x32_bf16 v[26:29], v[164:167], v[204:207], v[26:29]
	v_mfma_f32_16x16x32_bf16 v[14:17], v[156:159], v[212:215], v[14:17]
	v_mfma_f32_16x16x32_bf16 v[10:13], v[164:167], v[212:215], v[10:13]
	v_mfma_f32_16x16x32_bf16 v[62:65], v[160:163], v[192:195], v[62:65]
	v_mfma_f32_16x16x32_bf16 v[58:61], v[168:171], v[192:195], v[58:61]
	v_mfma_f32_16x16x32_bf16 v[46:49], v[160:163], v[200:203], v[46:49]
	v_mfma_f32_16x16x32_bf16 v[42:45], v[168:171], v[200:203], v[42:45]
	v_mfma_f32_16x16x32_bf16 v[30:33], v[160:163], v[208:211], v[30:33]
	v_mfma_f32_16x16x32_bf16 v[26:29], v[168:171], v[208:211], v[26:29]
	v_mfma_f32_16x16x32_bf16 v[14:17], v[160:163], v[216:219], v[14:17]
	v_mfma_f32_16x16x32_bf16 v[10:13], v[168:171], v[216:219], v[10:13]
	v_mfma_f32_16x16x32_bf16 v[54:57], v[172:175], v[188:191], v[54:57]
	v_mfma_f32_16x16x32_bf16 v[50:53], v[180:183], v[188:191], v[50:53]
	v_mfma_f32_16x16x32_bf16 v[38:41], v[172:175], v[196:199], v[38:41]
	v_mfma_f32_16x16x32_bf16 v[34:37], v[180:183], v[196:199], v[34:37]
	v_mfma_f32_16x16x32_bf16 v[22:25], v[172:175], v[204:207], v[22:25]
	v_mfma_f32_16x16x32_bf16 v[18:21], v[180:183], v[204:207], v[18:21]
	v_mfma_f32_16x16x32_bf16 v[6:9], v[172:175], v[212:215], v[6:9]
	v_mfma_f32_16x16x32_bf16 v[2:5], v[180:183], v[212:215], v[2:5]
	v_mfma_f32_16x16x32_bf16 v[54:57], v[176:179], v[192:195], v[54:57]
	v_mfma_f32_16x16x32_bf16 v[50:53], v[184:187], v[192:195], v[50:53]
	v_mfma_f32_16x16x32_bf16 v[38:41], v[176:179], v[200:203], v[38:41]
	v_mfma_f32_16x16x32_bf16 v[34:37], v[184:187], v[200:203], v[34:37]
	v_mfma_f32_16x16x32_bf16 v[22:25], v[176:179], v[208:211], v[22:25]
	v_mfma_f32_16x16x32_bf16 v[18:21], v[184:187], v[208:211], v[18:21]
	v_mfma_f32_16x16x32_bf16 v[6:9], v[176:179], v[216:219], v[6:9]
	v_mfma_f32_16x16x32_bf16 v[2:5], v[184:187], v[216:219], v[2:5]
	s_barrier
	s_add_u32 s52, s52, 0x10000
	s_addc_u32 s53, s53, 0
	s_add_u32 s26, s26, 0x100
	s_addc_u32 s27, s27, 0
	s_cmp_ge_u32 s57, s47
.LBB0_1716:
	ds_read_b128 v[156:159], v152
	ds_read_b128 v[160:163], v152 offset:1024
	ds_read_b128 v[164:167], v152 offset:2048
	ds_read_b128 v[168:171], v152 offset:3072
	ds_read_b128 v[172:175], v153
	ds_read_b128 v[176:179], v153 offset:1024
	ds_read_b128 v[180:183], v153 offset:2048
	ds_read_b128 v[184:187], v153 offset:3072
	s_add_u32 s28, s54, s26
	s_addc_u32 s29, s55, s27
	s_add_u32 s34, s28, 0x100
	s_addc_u32 s35, s29, 0
	s_add_i32 s57, s57, 2
	s_add_u32 s28, s28, 0x180
	s_addc_u32 s29, s29, 0
	s_cmp_eq_u32 s56, s26
	s_cselect_b32 s29, s51, s29
	s_cselect_b32 s28, s50, s28
	s_cselect_b32 s31, s4, s53
	s_cselect_b32 s30, s5, s52
	s_cselect_b32 s35, s49, s35
	s_cselect_b32 s34, s23, s34
	v_lshl_add_u64 v[220:221], v[146:147], 0, s[26:27]
	s_add_i32 m0, s40, 0xc000
	ds_read_b128 v[188:191], v154
	ds_read_b128 v[192:195], v154 offset:1024
	ds_read_b128 v[196:199], v154 offset:2048
	ds_read_b128 v[200:203], v154 offset:3072
	ds_read_b128 v[204:207], v154 offset:4096
	ds_read_b128 v[208:211], v154 offset:5120
	ds_read_b128 v[212:215], v154 offset:6144
	global_load_lds_dwordx4 v[220:221], off
	v_lshl_add_u64 v[220:221], v[148:149], 0, s[26:27]
	s_add_i32 m0, s40, 0xe000
	ds_read_b128 v[216:219], v154 offset:7168
	global_load_lds_dwordx4 v[220:221], off
	s_waitcnt vmcnt(8) lgkmcnt(0)
	s_barrier
; #define PG8_STAGE(bufoff, gbase, voff) do { _Pragma("unroll") for (int _i = 0; _i < 2; ++_i) \
;         __builtin_amdgcn_global_load_lds((const unsigned*)((const char*)(gbase) + (voff)[_i]), (LAS unsigned*)(lds + (bufoff) + ldsw + _i * 8192), 16, 0, 0); } while (0)
; #define PG8_LDA(dst, b, h) do { _Pragma("unroll") for (int m = 0; m < 4; ++m) _Pragma("unroll") for (int k = 0; k < 2; ++k) dst[m][k] = *(const LAS bf16x8*)(lds + PG8_SA(b, h) + aoff + m * 2048 + k * 1024); } while (0)
; #define PG8_LDB(dst, b, h) do { _Pragma("unroll") for (int n = 0; n < 2; ++n) _Pragma("unroll") for (int k = 0; k < 2; ++k) dst[n][k] = *(const LAS bf16x8*)(lds + PG8_SB(b, h) + boff + n * 2048 + k * 1024); } while (0)
; #define PG8_MMA(ai, bj, At, Bt) do { __builtin_amdgcn_s_setprio(1); _Pragma("unroll") for (int m = 0; m < 4; ++m) _Pragma("unroll") for (int n = 0; n < 2; ++n) _Pragma("unroll") for (int k = 0; k < 2; ++k) \
;         acc[ai][bj][m][n] = __builtin_amdgcn_mfma_f32_16x16x32_bf16(Bt[n][k], At[m][k], acc[ai][bj][m][n], 0, 0, 0); __builtin_amdgcn_s_setprio(0); } while (0)
; #define PG8_WAIT_V(n) asm volatile("s_waitcnt vmcnt(" #n ")" ::: "memory")
; #define PG8_WAIT_L(n) asm volatile("s_waitcnt lgkmcnt(" #n ")" ::: "memory")
; #define PG8_BAR __builtin_amdgcn_s_barrier()
; #define PG8_SCHED __builtin_amdgcn_sched_barrier(0)
; template <class Epi, class Sched, bool ABLK = false, bool ALIGN_EPI = true, bool SP2 = true, bool BBLK = true>
; __device__ __forceinline__ void gemm_phase(LAS unsigned char* lds, const Gemm g, const Sched& S, const Epi& E) {
;     ...
;             PG8_LDB(B0, 0, 0); PG8_LDB(B1, 0, 1); PG8_SCHED; PG8_LDA(At, 0, 0); PG8_STAGE(PG8_SA(1, 1), a1 + hstepA, voffA);
;             PG8_WAIT_V(8); PG8_WAIT_L(0); PG8_BAR; PG8_MMA(0, 0, At, B0); PG8_MMA(0, 1, At, B1); PG8_BAR; PG8_SCHED;
;             PG8_LDA(At, 0, 1); PG8_STAGE(PG8_SB(0, 0), b2, voffB); PG8_STAGE(PG8_SB(0, 1), b2 + hstepB, voffB); PG8_STAGE(PG8_SA(0, 0), a2, voffA);
;             PG8_WAIT_V(8); PG8_WAIT_L(0); PG8_BAR; PG8_MMA(1, 0, At, B0); PG8_MMA(1, 1, At, B1); PG8_BAR; PG8_SCHED;
	v_mfma_f32_16x16x32_bf16 v[126:129], v[156:159], v[188:191], v[126:129]
	v_mfma_f32_16x16x32_bf16 v[122:125], v[164:167], v[188:191], v[122:125]
	v_mfma_f32_16x16x32_bf16 v[110:113], v[156:159], v[196:199], v[110:113]
	v_mfma_f32_16x16x32_bf16 v[106:109], v[164:167], v[196:199], v[106:109]
	v_mfma_f32_16x16x32_bf16 v[94:97], v[156:159], v[204:207], v[94:97]
	v_mfma_f32_16x16x32_bf16 v[90:93], v[164:167], v[204:207], v[90:93]
	v_mfma_f32_16x16x32_bf16 v[78:81], v[156:159], v[212:215], v[78:81]
	v_mfma_f32_16x16x32_bf16 v[74:77], v[164:167], v[212:215], v[74:77]
	v_mfma_f32_16x16x32_bf16 v[126:129], v[160:163], v[192:195], v[126:129]
	v_mfma_f32_16x16x32_bf16 v[122:125], v[168:171], v[192:195], v[122:125]
	v_mfma_f32_16x16x32_bf16 v[110:113], v[160:163], v[200:203], v[110:113]
	v_mfma_f32_16x16x32_bf16 v[106:109], v[168:171], v[200:203], v[106:109]
	v_mfma_f32_16x16x32_bf16 v[94:97], v[160:163], v[208:211], v[94:97]
	v_mfma_f32_16x16x32_bf16 v[90:93], v[168:171], v[208:211], v[90:93]
	v_mfma_f32_16x16x32_bf16 v[78:81], v[160:163], v[216:219], v[78:81]
	v_mfma_f32_16x16x32_bf16 v[74:77], v[168:171], v[216:219], v[74:77]
	v_mfma_f32_16x16x32_bf16 v[118:121], v[172:175], v[188:191], v[118:121]
	v_mfma_f32_16x16x32_bf16 v[114:117], v[180:183], v[188:191], v[114:117]
	v_mfma_f32_16x16x32_bf16 v[102:105], v[172:175], v[196:199], v[102:105]
	v_mfma_f32_16x16x32_bf16 v[98:101], v[180:183], v[196:199], v[98:101]
	v_mfma_f32_16x16x32_bf16 v[86:89], v[172:175], v[204:207], v[86:89]
	v_mfma_f32_16x16x32_bf16 v[82:85], v[180:183], v[204:207], v[82:85]
	v_mfma_f32_16x16x32_bf16 v[70:73], v[172:175], v[212:215], v[70:73]
	v_mfma_f32_16x16x32_bf16 v[66:69], v[180:183], v[212:215], v[66:69]
	v_mfma_f32_16x16x32_bf16 v[118:121], v[176:179], v[192:195], v[118:121]
	v_mfma_f32_16x16x32_bf16 v[114:117], v[184:187], v[192:195], v[114:117]
	v_mfma_f32_16x16x32_bf16 v[102:105], v[176:179], v[200:203], v[102:105]
	v_mfma_f32_16x16x32_bf16 v[98:101], v[184:187], v[200:203], v[98:101]
	v_mfma_f32_16x16x32_bf16 v[86:89], v[176:179], v[208:211], v[86:89]
	v_mfma_f32_16x16x32_bf16 v[82:85], v[184:187], v[208:211], v[82:85]
	v_mfma_f32_16x16x32_bf16 v[70:73], v[176:179], v[216:219], v[70:73]
	v_mfma_f32_16x16x32_bf16 v[66:69], v[184:187], v[216:219], v[66:69]
	s_barrier
	s_add_i32 s58, s72, s39
	s_mov_b32 m0, s58
	ds_read_b128 v[188:191], v154 offset:16384
	ds_read_b128 v[192:195], v154 offset:17408
	ds_read_b128 v[196:199], v154 offset:18432
	ds_read_b128 v[200:203], v154 offset:19456
	global_load_lds_dwordx4 v132, s[30:31]
	s_add_i32 m0, s58, 0x2000
	s_add_u32 s58, s30, 0x4000
	s_addc_u32 s59, s31, 0
	s_add_i32 s64, s73, s39
	global_load_lds_dwordx4 v136, s[30:31]
	s_mov_b32 m0, s64
	ds_read_b128 v[204:207], v154 offset:20480
	global_load_lds_dwordx4 v132, s[58:59]
	s_add_i32 m0, s64, 0x2000
	ds_read_b128 v[208:211], v154 offset:21504
	global_load_lds_dwordx4 v136, s[58:59]
	s_mov_b32 m0, s40
	ds_read_b128 v[212:215], v154 offset:22528
	global_load_lds_dwordx4 v130, s[34:35]
	s_mov_b32 m0, s41
	ds_read_b128 v[216:219], v154 offset:23552
	global_load_lds_dwordx4 v134, s[34:35]
	s_waitcnt vmcnt(8) lgkmcnt(0)
	s_barrier
	v_mfma_f32_16x16x32_bf16 v[62:65], v[156:159], v[188:191], v[62:65]
	v_mfma_f32_16x16x32_bf16 v[58:61], v[164:167], v[188:191], v[58:61]
	v_mfma_f32_16x16x32_bf16 v[46:49], v[156:159], v[196:199], v[46:49]
	v_mfma_f32_16x16x32_bf16 v[42:45], v[164:167], v[196:199], v[42:45]
	v_mfma_f32_16x16x32_bf16 v[30:33], v[156:159], v[204:207], v[30:33]
	v_mfma_f32_16x16x32_bf16 v[26:29], v[164:167], v[204:207], v[26:29]
	v_mfma_f32_16x16x32_bf16 v[14:17], v[156:159], v[212:215], v[14:17]
	v_mfma_f32_16x16x32_bf16 v[10:13], v[164:167], v[212:215], v[10:13]
	v_mfma_f32_16x16x32_bf16 v[62:65], v[160:163], v[192:195], v[62:65]
	v_mfma_f32_16x16x32_bf16 v[58:61], v[168:171], v[192:195], v[58:61]
	v_mfma_f32_16x16x32_bf16 v[46:49], v[160:163], v[200:203], v[46:49]
	v_mfma_f32_16x16x32_bf16 v[42:45], v[168:171], v[200:203], v[42:45]
	v_mfma_f32_16x16x32_bf16 v[30:33], v[160:163], v[208:211], v[30:33]
	v_mfma_f32_16x16x32_bf16 v[26:29], v[168:171], v[208:211], v[26:29]
	v_mfma_f32_16x16x32_bf16 v[14:17], v[160:163], v[216:219], v[14:17]
	v_mfma_f32_16x16x32_bf16 v[10:13], v[168:171], v[216:219], v[10:13]
	v_mfma_f32_16x16x32_bf16 v[54:57], v[172:175], v[188:191], v[54:57]
	v_mfma_f32_16x16x32_bf16 v[50:53], v[180:183], v[188:191], v[50:53]
	v_mfma_f32_16x16x32_bf16 v[38:41], v[172:175], v[196:199], v[38:41]
	v_mfma_f32_16x16x32_bf16 v[34:37], v[180:183], v[196:199], v[34:37]
	v_mfma_f32_16x16x32_bf16 v[22:25], v[172:175], v[204:207], v[22:25]
	v_mfma_f32_16x16x32_bf16 v[18:21], v[180:183], v[204:207], v[18:21]
	v_mfma_f32_16x16x32_bf16 v[6:9], v[172:175], v[212:215], v[6:9]
	v_mfma_f32_16x16x32_bf16 v[2:5], v[180:183], v[212:215], v[2:5]
	v_mfma_f32_16x16x32_bf16 v[54:57], v[176:179], v[192:195], v[54:57]
	v_mfma_f32_16x16x32_bf16 v[50:53], v[184:187], v[192:195], v[50:53]
	v_mfma_f32_16x16x32_bf16 v[38:41], v[176:179], v[200:203], v[38:41]
	v_mfma_f32_16x16x32_bf16 v[34:37], v[184:187], v[200:203], v[34:37]
	v_mfma_f32_16x16x32_bf16 v[22:25], v[176:179], v[208:211], v[22:25]
	v_mfma_f32_16x16x32_bf16 v[18:21], v[184:187], v[208:211], v[18:21]
	v_mfma_f32_16x16x32_bf16 v[6:9], v[176:179], v[216:219], v[6:9]
	v_mfma_f32_16x16x32_bf16 v[2:5], v[184:187], v[216:219], v[2:5]
	s_barrier
; #define PG8_STAGE(bufoff, gbase, voff) do { _Pragma("unroll") for (int _i = 0; _i < 2; ++_i) \
;         __builtin_amdgcn_global_load_lds((const unsigned*)((const char*)(gbase) + (voff)[_i]), (LAS unsigned*)(lds + (bufoff) + ldsw + _i * 8192), 16, 0, 0); } while (0)
; #define PG8_LDA(dst, b, h) do { _Pragma("unroll") for (int m = 0; m < 4; ++m) _Pragma("unroll") for (int k = 0; k < 2; ++k) dst[m][k] = *(const LAS bf16x8*)(lds + PG8_SA(b, h) + aoff + m * 2048 + k * 1024); } while (0)
; #define PG8_LDB(dst, b, h) do { _Pragma("unroll") for (int n = 0; n < 2; ++n) _Pragma("unroll") for (int k = 0; k < 2; ++k) dst[n][k] = *(const LAS bf16x8*)(lds + PG8_SB(b, h) + boff + n * 2048 + k * 1024); } while (0)
; #define PG8_MMA(ai, bj, At, Bt) do { __builtin_amdgcn_s_setprio(1); _Pragma("unroll") for (int m = 0; m < 4; ++m) _Pragma("unroll") for (int n = 0; n < 2; ++n) _Pragma("unroll") for (int k = 0; k < 2; ++k) \
;         acc[ai][bj][m][n] = __builtin_amdgcn_mfma_f32_16x16x32_bf16(Bt[n][k], At[m][k], acc[ai][bj][m][n], 0, 0, 0); __builtin_amdgcn_s_setprio(0); } while (0)
; #define PG8_WAIT_V(n) asm volatile("s_waitcnt vmcnt(" #n ")" ::: "memory")
; #define PG8_WAIT_L(n) asm volatile("s_waitcnt lgkmcnt(" #n ")" ::: "memory")
; #define PG8_BAR __builtin_amdgcn_s_barrier()
; #define PG8_SCHED __builtin_amdgcn_sched_barrier(0)
; template <class Epi, class Sched, bool ABLK = false, bool ALIGN_EPI = true, bool SP2 = true, bool BBLK = true>
; __device__ __forceinline__ void gemm_phase(LAS unsigned char* lds, const Gemm g, const Sched& S, const Epi& E) {
;     ...
;             PG8_LDB(B0, 1, 0); PG8_LDB(B1, 1, 1); PG8_SCHED; PG8_LDA(At, 1, 0); PG8_STAGE(PG8_SA(0, 1), a2 + hstepA, voffA);
;             PG8_WAIT_V(8); PG8_WAIT_L(0); PG8_BAR; PG8_MMA(0, 0, At, B0); PG8_MMA(0, 1, At, B1); PG8_BAR; PG8_SCHED;
;             PG8_LDA(At, 1, 1); PG8_STAGE(PG8_SB(1, 0), b3, voffB); PG8_STAGE(PG8_SB(1, 1), b3 + hstepB, voffB); PG8_STAGE(PG8_SA(1, 0), a3, voffA);
;             PG8_WAIT_V(8); PG8_WAIT_L(0); PG8_BAR; PG8_MMA(1, 0, At, B0); PG8_MMA(1, 1, At, B1); PG8_BAR; PG8_SCHED;
;     ...
;         if constexpr (ALIGN_EPI) { if (wr == 0) PG8_BAR; }
	v_add_u32_e32 v155, s60, v150
	ds_read_b128 v[156:159], v155
	ds_read_b128 v[160:163], v155 offset:1024
	ds_read_b128 v[164:167], v155 offset:2048
	ds_read_b128 v[168:171], v155 offset:3072
	v_add_u32_e32 v155, s61, v150
	ds_read_b128 v[172:175], v155
	ds_read_b128 v[176:179], v155 offset:1024
	ds_read_b128 v[180:183], v155 offset:2048
	ds_read_b128 v[184:187], v155 offset:3072
	s_add_u32 s34, s34, 0x80000
	s_addc_u32 s35, s35, 0
	s_mov_b32 m0, s42
	ds_read_b128 v[188:191], v154 offset:32768
	ds_read_b128 v[192:195], v154 offset:33792
	ds_read_b128 v[196:199], v154 offset:34816
	ds_read_b128 v[200:203], v154 offset:35840
	ds_read_b128 v[204:207], v154 offset:36864
	ds_read_b128 v[208:211], v154 offset:37888
	ds_read_b128 v[212:215], v154 offset:38912
	global_load_lds_dwordx4 v130, s[34:35]
	s_mov_b32 m0, s43
	ds_read_b128 v[216:219], v154 offset:39936
	global_load_lds_dwordx4 v134, s[34:35]
	s_waitcnt vmcnt(8) lgkmcnt(0)
	s_barrier
	v_mfma_f32_16x16x32_bf16 v[126:129], v[156:159], v[188:191], v[126:129]
	v_mfma_f32_16x16x32_bf16 v[122:125], v[164:167], v[188:191], v[122:125]
	v_mfma_f32_16x16x32_bf16 v[110:113], v[156:159], v[196:199], v[110:113]
	v_mfma_f32_16x16x32_bf16 v[106:109], v[164:167], v[196:199], v[106:109]
	v_mfma_f32_16x16x32_bf16 v[94:97], v[156:159], v[204:207], v[94:97]
	v_mfma_f32_16x16x32_bf16 v[90:93], v[164:167], v[204:207], v[90:93]
	v_mfma_f32_16x16x32_bf16 v[78:81], v[156:159], v[212:215], v[78:81]
	v_mfma_f32_16x16x32_bf16 v[74:77], v[164:167], v[212:215], v[74:77]
	v_mfma_f32_16x16x32_bf16 v[126:129], v[160:163], v[192:195], v[126:129]
	v_mfma_f32_16x16x32_bf16 v[122:125], v[168:171], v[192:195], v[122:125]
	v_mfma_f32_16x16x32_bf16 v[110:113], v[160:163], v[200:203], v[110:113]
	v_mfma_f32_16x16x32_bf16 v[106:109], v[168:171], v[200:203], v[106:109]
	v_mfma_f32_16x16x32_bf16 v[94:97], v[160:163], v[208:211], v[94:97]
	v_mfma_f32_16x16x32_bf16 v[90:93], v[168:171], v[208:211], v[90:93]
	v_mfma_f32_16x16x32_bf16 v[78:81], v[160:163], v[216:219], v[78:81]
	v_mfma_f32_16x16x32_bf16 v[74:77], v[168:171], v[216:219], v[74:77]
	v_mfma_f32_16x16x32_bf16 v[118:121], v[172:175], v[188:191], v[118:121]
	v_mfma_f32_16x16x32_bf16 v[114:117], v[180:183], v[188:191], v[114:117]
	v_mfma_f32_16x16x32_bf16 v[102:105], v[172:175], v[196:199], v[102:105]
	v_mfma_f32_16x16x32_bf16 v[98:101], v[180:183], v[196:199], v[98:101]
	v_mfma_f32_16x16x32_bf16 v[86:89], v[172:175], v[204:207], v[86:89]
	v_mfma_f32_16x16x32_bf16 v[82:85], v[180:183], v[204:207], v[82:85]
	v_mfma_f32_16x16x32_bf16 v[70:73], v[172:175], v[212:215], v[70:73]
	v_mfma_f32_16x16x32_bf16 v[66:69], v[180:183], v[212:215], v[66:69]
	v_mfma_f32_16x16x32_bf16 v[118:121], v[176:179], v[192:195], v[118:121]
	v_mfma_f32_16x16x32_bf16 v[114:117], v[184:187], v[192:195], v[114:117]
	v_mfma_f32_16x16x32_bf16 v[102:105], v[176:179], v[200:203], v[102:105]
	v_mfma_f32_16x16x32_bf16 v[98:101], v[184:187], v[200:203], v[98:101]
	v_mfma_f32_16x16x32_bf16 v[86:89], v[176:179], v[208:211], v[86:89]
	v_mfma_f32_16x16x32_bf16 v[82:85], v[184:187], v[208:211], v[82:85]
	v_mfma_f32_16x16x32_bf16 v[70:73], v[176:179], v[216:219], v[70:73]
	v_mfma_f32_16x16x32_bf16 v[66:69], v[184:187], v[216:219], v[66:69]
	s_barrier
	s_add_u32 s34, s30, 0x8000
	s_addc_u32 s35, s31, 0
	s_add_i32 s58, s60, s39
	s_mov_b32 m0, s58
	ds_read_b128 v[188:191], v154 offset:49152
	ds_read_b128 v[192:195], v154 offset:50176
	ds_read_b128 v[196:199], v154 offset:51200
	ds_read_b128 v[200:203], v154 offset:52224
	global_load_lds_dwordx4 v132, s[34:35]
	s_add_i32 m0, s58, 0x2000
	s_add_u32 s30, s30, 0xc000
	v_lshl_add_u64 v[220:221], s[34:35], 0, v[136:137]
	s_addc_u32 s31, s31, 0
	s_add_i32 s34, s61, s39
	global_load_lds_dwordx4 v[220:221], off
	s_mov_b32 m0, s34
	ds_read_b128 v[204:207], v154 offset:53248
	global_load_lds_dwordx4 v132, s[30:31]
	s_add_i32 m0, s34, 0x2000
	ds_read_b128 v[208:211], v154 offset:54272
	global_load_lds_dwordx4 v136, s[30:31]
	s_mov_b32 m0, s44
	ds_read_b128 v[212:215], v154 offset:55296
	global_load_lds_dwordx4 v130, s[28:29]
	s_mov_b32 m0, s45
	ds_read_b128 v[216:219], v154 offset:56320
	global_load_lds_dwordx4 v134, s[28:29]
	s_waitcnt vmcnt(8) lgkmcnt(0)
	s_barrier
	v_mfma_f32_16x16x32_bf16 v[62:65], v[156:159], v[188:191], v[62:65]
	v_mfma_f32_16x16x32_bf16 v[58:61], v[164:167], v[188:191], v[58:61]
	v_mfma_f32_16x16x32_bf16 v[46:49], v[156:159], v[196:199], v[46:49]
	v_mfma_f32_16x16x32_bf16 v[42:45], v[164:167], v[196:199], v[42:45]
	v_mfma_f32_16x16x32_bf16 v[30:33], v[156:159], v[204:207], v[30:33]
	v_mfma_f32_16x16x32_bf16 v[26:29], v[164:167], v[204:207], v[26:29]
	v_mfma_f32_16x16x32_bf16 v[14:17], v[156:159], v[212:215], v[14:17]
	v_mfma_f32_16x16x32_bf16 v[10:13], v[164:167], v[212:215], v[10:13]
	v_mfma_f32_16x16x32_bf16 v[62:65], v[160:163], v[192:195], v[62:65]
	v_mfma_f32_16x16x32_bf16 v[58:61], v[168:171], v[192:195], v[58:61]
	v_mfma_f32_16x16x32_bf16 v[46:49], v[160:163], v[200:203], v[46:49]
	v_mfma_f32_16x16x32_bf16 v[42:45], v[168:171], v[200:203], v[42:45]
	v_mfma_f32_16x16x32_bf16 v[30:33], v[160:163], v[208:211], v[30:33]
	v_mfma_f32_16x16x32_bf16 v[26:29], v[168:171], v[208:211], v[26:29]
	v_mfma_f32_16x16x32_bf16 v[14:17], v[160:163], v[216:219], v[14:17]
	v_mfma_f32_16x16x32_bf16 v[10:13], v[168:171], v[216:219], v[10:13]
	v_mfma_f32_16x16x32_bf16 v[54:57], v[172:175], v[188:191], v[54:57]
	v_mfma_f32_16x16x32_bf16 v[50:53], v[180:183], v[188:191], v[50:53]
	v_mfma_f32_16x16x32_bf16 v[38:41], v[172:175], v[196:199], v[38:41]
	v_mfma_f32_16x16x32_bf16 v[34:37], v[180:183], v[196:199], v[34:37]
	v_mfma_f32_16x16x32_bf16 v[22:25], v[172:175], v[204:207], v[22:25]
	v_mfma_f32_16x16x32_bf16 v[18:21], v[180:183], v[204:207], v[18:21]
	v_mfma_f32_16x16x32_bf16 v[6:9], v[172:175], v[212:215], v[6:9]
	v_mfma_f32_16x16x32_bf16 v[2:5], v[180:183], v[212:215], v[2:5]
	v_mfma_f32_16x16x32_bf16 v[54:57], v[176:179], v[192:195], v[54:57]
	v_mfma_f32_16x16x32_bf16 v[50:53], v[184:187], v[192:195], v[50:53]
	v_mfma_f32_16x16x32_bf16 v[38:41], v[176:179], v[200:203], v[38:41]
	v_mfma_f32_16x16x32_bf16 v[34:37], v[184:187], v[200:203], v[34:37]
	v_mfma_f32_16x16x32_bf16 v[22:25], v[176:179], v[208:211], v[22:25]
	v_mfma_f32_16x16x32_bf16 v[18:21], v[184:187], v[208:211], v[18:21]
	v_mfma_f32_16x16x32_bf16 v[6:9], v[176:179], v[216:219], v[6:9]
	v_mfma_f32_16x16x32_bf16 v[2:5], v[184:187], v[216:219], v[2:5]
	s_barrier
	s_add_u32 s52, s52, 0x10000
	s_addc_u32 s53, s53, 0
	s_add_u32 s26, s26, 0x100
	s_addc_u32 s27, s27, 0
	s_cmp_ge_u32 s57, s47
	s_cbranch_scc0 .LBB0_1716
	s_and_b64 vcc, exec, s[6:7]
	s_cbranch_vccz .LBB0_1719
	s_barrier

; #define PG8_STAGE(bufoff, gbase, voff) do { _Pragma("unroll") for (int _i = 0; _i < 2; ++_i) \
;         __builtin_amdgcn_global_load_lds((const unsigned*)((const char*)(gbase) + (voff)[_i]), (LAS unsigned*)(lds + (bufoff) + ldsw + _i * 8192), 16, 0, 0); } while (0)
; #define PG8_LDA(dst, b, h) do { _Pragma("unroll") for (int m = 0; m < 4; ++m) _Pragma("unroll") for (int k = 0; k < 2; ++k) dst[m][k] = *(const LAS bf16x8*)(lds + PG8_SA(b, h) + aoff + m * 2048 + k * 1024); } while (0)
; #define PG8_LDB(dst, b, h) do { _Pragma("unroll") for (int n = 0; n < 2; ++n) _Pragma("unroll") for (int k = 0; k < 2; ++k) dst[n][k] = *(const LAS bf16x8*)(lds + PG8_SB(b, h) + boff + n * 2048 + k * 1024); } while (0)
; #define PG8_WAIT_V(n) asm volatile("s_waitcnt vmcnt(" #n ")" ::: "memory")
; #define PG8_WAIT_L(n) asm volatile("s_waitcnt lgkmcnt(" #n ")" ::: "memory")
; #define PG8_BAR __builtin_amdgcn_s_barrier()
; #define PG8_SCHED __builtin_amdgcn_sched_barrier(0)
; template <class Epi, class Sched, bool ABLK = false, bool ALIGN_EPI = true, bool SP2 = true, bool BBLK = true>
; __device__ __forceinline__ void gemm_phase(LAS unsigned char* lds, const Gemm g, const Sched& S, const Epi& E) {
;     ...
;         const bool has_next = S.next(ui + 1, nxt);
;         const int nt = cur.nt;
;         const char* nuA = has_next ? a_unit(nxt) : uA; const int ntbA = has_next ? nxt.k0 / BK : tbA; const char* nB = has_next ? (const char*)g.Bt + (size_t)nxt.pn * tstepB + b_k0(nxt.k0) : cB;
;         for (int t = 0; t < nt; t += 2) {
;             const bool last = (t == nt - 2);
;             const char* a1 = a_tile(uA, tbA + t + 1);
;             const char* a2 = last ? a_tile(nuA, ntbA) : a_tile(uA, tbA + t + 2); const char* b2 = last ? nB : cB + (size_t)(t + 2) * kstepB;
;             const char* a3 = last ? a_tile(nuA, ntbA + 1) : a_tile(uA, tbA + t + 3); const char* b3 = b2 + kstepB;
;             if (last && has_next) S.a_ready(nxt);
;             if constexpr (SP2) {
;             PG8_LDB(B0, 0, 0); PG8_LDB(B1, 0, 1); PG8_SCHED; PG8_LDA(At, 0, 0); PG8_STAGE(PG8_SA(1, 1), a1 + hstepA, voffA);
;             PG8_WAIT_V(8); PG8_WAIT_L(0); PG8_BAR; PG8_MMA(0, 0, At, B0); PG8_MMA(0, 1, At, B1); PG8_BAR; PG8_SCHED;
;             PG8_LDA(At, 0, 1); PG8_STAGE(PG8_SB(0, 0), b2, voffB); PG8_STAGE(PG8_SB(0, 1), b2 + hstepB, voffB); PG8_STAGE(PG8_SA(0, 0), a2, voffA);
.LBB0_1841:
	s_ashr_i32 s11, s10, 31
	s_lshl_b64 s[4:5], s[10:11], 20
	s_add_u32 s16, s76, s4
	s_addc_u32 s17, s33, s5
	s_and_b64 s[4:5], s[18:19], exec
	s_cselect_b32 s4, s17, s27
	s_cselect_b32 s5, s16, s26
	s_ashr_i32 s15, s14, 31
	s_lshl_b64 s[20:21], s[14:15], 20
	s_add_u32 s20, s1, s20
	s_addc_u32 s21, s38, s21
	s_and_b64 s[30:31], s[18:19], exec
	s_cselect_b32 s11, s21, s29
	s_cselect_b32 s15, s20, s28
	s_add_u32 s23, s5, 0x80
	s_addc_u32 s51, s4, 0
	s_add_u32 s52, s28, 0x10000
	v_mov_b32_e32 v2, 0
	s_addc_u32 s53, s29, 0
	v_lshl_add_u64 v[164:165], s[26:27], 0, v[160:161]
	v_lshl_add_u64 v[166:167], s[26:27], 0, v[162:163]
	s_mov_b32 s54, -2
	s_mov_b64 s[28:29], 0
	ds_read_b128 v[172:175], v168
	ds_read_b128 v[176:179], v168 offset:1024
	ds_read_b128 v[180:183], v168 offset:2048
	ds_read_b128 v[184:187], v168 offset:3072
	ds_read_b128 v[188:191], v169
	ds_read_b128 v[192:195], v169 offset:1024
	ds_read_b128 v[196:199], v169 offset:2048
	ds_read_b128 v[200:203], v169 offset:3072
	s_add_u32 s30, s26, s28
	s_addc_u32 s31, s27, s29
	s_add_u32 s36, s30, 0x100
	s_addc_u32 s37, s31, 0
	s_add_u32 s30, s30, 0x180
	s_addc_u32 s31, s31, 0
	s_cmpk_eq_i32 s28, 0xf00
	s_cselect_b32 s31, s51, s31
	s_cselect_b32 s30, s23, s30
	s_cselect_b32 s35, s11, s53
	s_cselect_b32 s34, s15, s52
	s_cselect_b32 s37, s4, s37
	s_cselect_b32 s36, s5, s36
	s_mov_b32 m0, s47
	v_lshl_add_u64 v[236:237], v[164:165], 0, s[28:29]
	ds_read_b128 v[204:207], v170
	ds_read_b128 v[208:211], v170 offset:1024
	ds_read_b128 v[212:215], v170 offset:2048
	ds_read_b128 v[216:219], v170 offset:3072
	ds_read_b128 v[220:223], v170 offset:4096
	ds_read_b128 v[224:227], v170 offset:5120
	ds_read_b128 v[228:231], v170 offset:6144
	global_load_lds_dwordx4 v[236:237], off
	v_lshl_add_u64 v[236:237], v[166:167], 0, s[28:29]
	s_mov_b32 m0, s48
	ds_read_b128 v[232:235], v170 offset:7168
	global_load_lds_dwordx4 v[236:237], off
	s_waitcnt vmcnt(8) lgkmcnt(0)
	s_barrier
	v_mfma_f32_16x16x32_bf16 v[126:129], v[172:175], v[204:207], 0
	v_mfma_f32_16x16x32_bf16 v[122:125], v[180:183], v[204:207], 0
	v_mfma_f32_16x16x32_bf16 v[110:113], v[172:175], v[212:215], 0
	v_mfma_f32_16x16x32_bf16 v[106:109], v[180:183], v[212:215], 0
	v_mfma_f32_16x16x32_bf16 v[94:97], v[172:175], v[220:223], 0
	v_mfma_f32_16x16x32_bf16 v[90:93], v[180:183], v[220:223], 0
	v_mfma_f32_16x16x32_bf16 v[78:81], v[172:175], v[228:231], 0
	v_mfma_f32_16x16x32_bf16 v[74:77], v[180:183], v[228:231], 0
	v_mfma_f32_16x16x32_bf16 v[126:129], v[176:179], v[208:211], v[126:129]
	v_mfma_f32_16x16x32_bf16 v[122:125], v[184:187], v[208:211], v[122:125]
	v_mfma_f32_16x16x32_bf16 v[110:113], v[176:179], v[216:219], v[110:113]
	v_mfma_f32_16x16x32_bf16 v[106:109], v[184:187], v[216:219], v[106:109]
	v_mfma_f32_16x16x32_bf16 v[94:97], v[176:179], v[224:227], v[94:97]
	v_mfma_f32_16x16x32_bf16 v[90:93], v[184:187], v[224:227], v[90:93]
	v_mfma_f32_16x16x32_bf16 v[78:81], v[176:179], v[232:235], v[78:81]
	v_mfma_f32_16x16x32_bf16 v[74:77], v[184:187], v[232:235], v[74:77]
	v_mfma_f32_16x16x32_bf16 v[118:121], v[188:191], v[204:207], 0
	v_mfma_f32_16x16x32_bf16 v[114:117], v[196:199], v[204:207], 0
	v_mfma_f32_16x16x32_bf16 v[102:105], v[188:191], v[212:215], 0
	v_mfma_f32_16x16x32_bf16 v[98:101], v[196:199], v[212:215], 0
	v_mfma_f32_16x16x32_bf16 v[86:89], v[188:191], v[220:223], 0
	v_mfma_f32_16x16x32_bf16 v[82:85], v[196:199], v[220:223], 0
	v_mfma_f32_16x16x32_bf16 v[70:73], v[188:191], v[228:231], 0
	v_mfma_f32_16x16x32_bf16 v[66:69], v[196:199], v[228:231], 0
	v_mfma_f32_16x16x32_bf16 v[118:121], v[192:195], v[208:211], v[118:121]
	v_mfma_f32_16x16x32_bf16 v[114:117], v[200:203], v[208:211], v[114:117]
	v_mfma_f32_16x16x32_bf16 v[102:105], v[192:195], v[216:219], v[102:105]
	v_mfma_f32_16x16x32_bf16 v[98:101], v[200:203], v[216:219], v[98:101]
	v_mfma_f32_16x16x32_bf16 v[86:89], v[192:195], v[224:227], v[86:89]
	v_mfma_f32_16x16x32_bf16 v[82:85], v[200:203], v[224:227], v[82:85]
	v_mfma_f32_16x16x32_bf16 v[70:73], v[192:195], v[232:235], v[70:73]
	v_mfma_f32_16x16x32_bf16 v[66:69], v[200:203], v[232:235], v[66:69]
	s_barrier
	s_mov_b32 m0, s49
	s_add_u32 s56, s34, 0x4000
	ds_read_b128 v[204:207], v170 offset:16384
	ds_read_b128 v[208:211], v170 offset:17408
	ds_read_b128 v[212:215], v170 offset:18432
	ds_read_b128 v[216:219], v170 offset:19456
	global_load_lds_dwordx4 v134, s[34:35]
	s_mov_b32 m0, s50
	s_addc_u32 s57, s35, 0
	s_add_i32 s55, s73, s39
	global_load_lds_dwordx4 v130, s[34:35]
	s_mov_b32 m0, s55
	ds_read_b128 v[220:223], v170 offset:20480
	global_load_lds_dwordx4 v134, s[56:57]
	s_add_i32 m0, s55, 0x2000
	ds_read_b128 v[224:227], v170 offset:21504
	global_load_lds_dwordx4 v130, s[56:57]
	s_mov_b32 m0, s25
	ds_read_b128 v[228:231], v170 offset:22528
	global_load_lds_dwordx4 v136, s[36:37]
	s_mov_b32 m0, s40
	ds_read_b128 v[232:235], v170 offset:23552
	global_load_lds_dwordx4 v132, s[36:37]
	s_waitcnt vmcnt(8) lgkmcnt(0)
	s_barrier
; #define PG8_STAGE(bufoff, gbase, voff) do { _Pragma("unroll") for (int _i = 0; _i < 2; ++_i) \
;         __builtin_amdgcn_global_load_lds((const unsigned*)((const char*)(gbase) + (voff)[_i]), (LAS unsigned*)(lds + (bufoff) + ldsw + _i * 8192), 16, 0, 0); } while (0)
; #define PG8_LDA(dst, b, h) do { _Pragma("unroll") for (int m = 0; m < 4; ++m) _Pragma("unroll") for (int k = 0; k < 2; ++k) dst[m][k] = *(const LAS bf16x8*)(lds + PG8_SA(b, h) + aoff + m * 2048 + k * 1024); } while (0)
; #define PG8_LDB(dst, b, h) do { _Pragma("unroll") for (int n = 0; n < 2; ++n) _Pragma("unroll") for (int k = 0; k < 2; ++k) dst[n][k] = *(const LAS bf16x8*)(lds + PG8_SB(b, h) + boff + n * 2048 + k * 1024); } while (0)
; #define PG8_MMA(ai, bj, At, Bt) do { __builtin_amdgcn_s_setprio(1); _Pragma("unroll") for (int m = 0; m < 4; ++m) _Pragma("unroll") for (int n = 0; n < 2; ++n) _Pragma("unroll") for (int k = 0; k < 2; ++k) \
;         acc[ai][bj][m][n] = __builtin_amdgcn_mfma_f32_16x16x32_bf16(Bt[n][k], At[m][k], acc[ai][bj][m][n], 0, 0, 0); __builtin_amdgcn_s_setprio(0); } while (0)
; #define PG8_WAIT_V(n) asm volatile("s_waitcnt vmcnt(" #n ")" ::: "memory")
; #define PG8_WAIT_L(n) asm volatile("s_waitcnt lgkmcnt(" #n ")" ::: "memory")
; #define PG8_BAR __builtin_amdgcn_s_barrier()
; #define PG8_SCHED __builtin_amdgcn_sched_barrier(0)
; template <class Epi, class Sched, bool ABLK = false, bool ALIGN_EPI = true, bool SP2 = true, bool BBLK = true>
; __device__ __forceinline__ void gemm_phase(LAS unsigned char* lds, const Gemm g, const Sched& S, const Epi& E) {
;     ...
;             PG8_WAIT_V(8); PG8_WAIT_L(0); PG8_BAR; PG8_MMA(1, 0, At, B0); PG8_MMA(1, 1, At, B1); PG8_BAR; PG8_SCHED;
;             PG8_LDB(B0, 1, 0); PG8_LDB(B1, 1, 1); PG8_SCHED; PG8_LDA(At, 1, 0); PG8_STAGE(PG8_SA(0, 1), a2 + hstepA, voffA);
;             PG8_WAIT_V(8); PG8_WAIT_L(0); PG8_BAR; PG8_MMA(0, 0, At, B0); PG8_MMA(0, 1, At, B1); PG8_BAR; PG8_SCHED;
	v_mfma_f32_16x16x32_bf16 v[62:65], v[172:175], v[204:207], 0
	v_mfma_f32_16x16x32_bf16 v[58:61], v[180:183], v[204:207], 0
	v_mfma_f32_16x16x32_bf16 v[46:49], v[172:175], v[212:215], 0
	v_mfma_f32_16x16x32_bf16 v[42:45], v[180:183], v[212:215], 0
	v_mfma_f32_16x16x32_bf16 v[30:33], v[172:175], v[220:223], 0
	v_mfma_f32_16x16x32_bf16 v[26:29], v[180:183], v[220:223], 0
	v_mfma_f32_16x16x32_bf16 v[14:17], v[172:175], v[228:231], 0
	v_mfma_f32_16x16x32_bf16 v[10:13], v[180:183], v[228:231], 0
	v_mfma_f32_16x16x32_bf16 v[62:65], v[176:179], v[208:211], v[62:65]
	v_mfma_f32_16x16x32_bf16 v[58:61], v[184:187], v[208:211], v[58:61]
	v_mfma_f32_16x16x32_bf16 v[46:49], v[176:179], v[216:219], v[46:49]
	v_mfma_f32_16x16x32_bf16 v[42:45], v[184:187], v[216:219], v[42:45]
	v_mfma_f32_16x16x32_bf16 v[30:33], v[176:179], v[224:227], v[30:33]
	v_mfma_f32_16x16x32_bf16 v[26:29], v[184:187], v[224:227], v[26:29]
	v_mfma_f32_16x16x32_bf16 v[14:17], v[176:179], v[232:235], v[14:17]
	v_mfma_f32_16x16x32_bf16 v[10:13], v[184:187], v[232:235], v[10:13]
	v_mfma_f32_16x16x32_bf16 v[54:57], v[188:191], v[204:207], 0
	v_mfma_f32_16x16x32_bf16 v[50:53], v[196:199], v[204:207], 0
	v_mfma_f32_16x16x32_bf16 v[38:41], v[188:191], v[212:215], 0
	v_mfma_f32_16x16x32_bf16 v[34:37], v[196:199], v[212:215], 0
	v_mfma_f32_16x16x32_bf16 v[22:25], v[188:191], v[220:223], 0
	v_mfma_f32_16x16x32_bf16 v[18:21], v[196:199], v[220:223], 0
	v_mfma_f32_16x16x32_bf16 v[6:9], v[188:191], v[228:231], 0
	v_mfma_f32_16x16x32_bf16 v[2:5], v[196:199], v[228:231], 0
	v_mfma_f32_16x16x32_bf16 v[54:57], v[192:195], v[208:211], v[54:57]
	v_mfma_f32_16x16x32_bf16 v[50:53], v[200:203], v[208:211], v[50:53]
	v_mfma_f32_16x16x32_bf16 v[38:41], v[192:195], v[216:219], v[38:41]
	v_mfma_f32_16x16x32_bf16 v[34:37], v[200:203], v[216:219], v[34:37]
	v_mfma_f32_16x16x32_bf16 v[22:25], v[192:195], v[224:227], v[22:25]
	v_mfma_f32_16x16x32_bf16 v[18:21], v[200:203], v[224:227], v[18:21]
	v_mfma_f32_16x16x32_bf16 v[6:9], v[192:195], v[232:235], v[6:9]
	v_mfma_f32_16x16x32_bf16 v[2:5], v[200:203], v[232:235], v[2:5]
	s_barrier
	v_add_u32_e32 v171, s60, v1
	ds_read_b128 v[172:175], v171
	ds_read_b128 v[176:179], v171 offset:1024
	ds_read_b128 v[180:183], v171 offset:2048
	ds_read_b128 v[184:187], v171 offset:3072
	v_add_u32_e32 v171, s61, v1
	ds_read_b128 v[188:191], v171
	ds_read_b128 v[192:195], v171 offset:1024
	ds_read_b128 v[196:199], v171 offset:2048
	ds_read_b128 v[200:203], v171 offset:3072
	s_add_u32 s36, s36, 0x80000
	s_addc_u32 s37, s37, 0
	s_mov_b32 m0, s41
	ds_read_b128 v[204:207], v170 offset:32768
	ds_read_b128 v[208:211], v170 offset:33792
	ds_read_b128 v[212:215], v170 offset:34816
	ds_read_b128 v[216:219], v170 offset:35840
	ds_read_b128 v[220:223], v170 offset:36864
	ds_read_b128 v[224:227], v170 offset:37888
	ds_read_b128 v[228:231], v170 offset:38912
	global_load_lds_dwordx4 v136, s[36:37]
	s_mov_b32 m0, s42
	ds_read_b128 v[232:235], v170 offset:39936
	global_load_lds_dwordx4 v132, s[36:37]
	s_waitcnt vmcnt(8) lgkmcnt(0)
	s_barrier
	v_mfma_f32_16x16x32_bf16 v[126:129], v[172:175], v[204:207], v[126:129]
	v_mfma_f32_16x16x32_bf16 v[122:125], v[180:183], v[204:207], v[122:125]
	v_mfma_f32_16x16x32_bf16 v[110:113], v[172:175], v[212:215], v[110:113]
	v_mfma_f32_16x16x32_bf16 v[106:109], v[180:183], v[212:215], v[106:109]
	v_mfma_f32_16x16x32_bf16 v[94:97], v[172:175], v[220:223], v[94:97]
	v_mfma_f32_16x16x32_bf16 v[90:93], v[180:183], v[220:223], v[90:93]
	v_mfma_f32_16x16x32_bf16 v[78:81], v[172:175], v[228:231], v[78:81]
	v_mfma_f32_16x16x32_bf16 v[74:77], v[180:183], v[228:231], v[74:77]
	v_mfma_f32_16x16x32_bf16 v[126:129], v[176:179], v[208:211], v[126:129]
	v_mfma_f32_16x16x32_bf16 v[122:125], v[184:187], v[208:211], v[122:125]
	v_mfma_f32_16x16x32_bf16 v[110:113], v[176:179], v[216:219], v[110:113]
	v_mfma_f32_16x16x32_bf16 v[106:109], v[184:187], v[216:219], v[106:109]
	v_mfma_f32_16x16x32_bf16 v[94:97], v[176:179], v[224:227], v[94:97]
	v_mfma_f32_16x16x32_bf16 v[90:93], v[184:187], v[224:227], v[90:93]
	v_mfma_f32_16x16x32_bf16 v[78:81], v[176:179], v[232:235], v[78:81]
	v_mfma_f32_16x16x32_bf16 v[74:77], v[184:187], v[232:235], v[74:77]
	v_mfma_f32_16x16x32_bf16 v[118:121], v[188:191], v[204:207], v[118:121]
	v_mfma_f32_16x16x32_bf16 v[114:117], v[196:199], v[204:207], v[114:117]
	v_mfma_f32_16x16x32_bf16 v[102:105], v[188:191], v[212:215], v[102:105]
	v_mfma_f32_16x16x32_bf16 v[98:101], v[196:199], v[212:215], v[98:101]
	v_mfma_f32_16x16x32_bf16 v[86:89], v[188:191], v[220:223], v[86:89]
	v_mfma_f32_16x16x32_bf16 v[82:85], v[196:199], v[220:223], v[82:85]
	v_mfma_f32_16x16x32_bf16 v[70:73], v[188:191], v[228:231], v[70:73]
	v_mfma_f32_16x16x32_bf16 v[66:69], v[196:199], v[228:231], v[66:69]
	v_mfma_f32_16x16x32_bf16 v[118:121], v[192:195], v[208:211], v[118:121]
	v_mfma_f32_16x16x32_bf16 v[114:117], v[200:203], v[208:211], v[114:117]
	v_mfma_f32_16x16x32_bf16 v[102:105], v[192:195], v[216:219], v[102:105]
	v_mfma_f32_16x16x32_bf16 v[98:101], v[200:203], v[216:219], v[98:101]
	v_mfma_f32_16x16x32_bf16 v[86:89], v[192:195], v[224:227], v[86:89]
	v_mfma_f32_16x16x32_bf16 v[82:85], v[200:203], v[224:227], v[82:85]
	v_mfma_f32_16x16x32_bf16 v[70:73], v[192:195], v[232:235], v[70:73]
	v_mfma_f32_16x16x32_bf16 v[66:69], v[200:203], v[232:235], v[66:69]
	s_barrier
; #define PG8_STAGE(bufoff, gbase, voff) do { _Pragma("unroll") for (int _i = 0; _i < 2; ++_i) \
;         __builtin_amdgcn_global_load_lds((const unsigned*)((const char*)(gbase) + (voff)[_i]), (LAS unsigned*)(lds + (bufoff) + ldsw + _i * 8192), 16, 0, 0); } while (0)
; #define PG8_LDA(dst, b, h) do { _Pragma("unroll") for (int m = 0; m < 4; ++m) _Pragma("unroll") for (int k = 0; k < 2; ++k) dst[m][k] = *(const LAS bf16x8*)(lds + PG8_SA(b, h) + aoff + m * 2048 + k * 1024); } while (0)
; #define PG8_LDB(dst, b, h) do { _Pragma("unroll") for (int n = 0; n < 2; ++n) _Pragma("unroll") for (int k = 0; k < 2; ++k) dst[n][k] = *(const LAS bf16x8*)(lds + PG8_SB(b, h) + boff + n * 2048 + k * 1024); } while (0)
; #define PG8_MMA(ai, bj, At, Bt) do { __builtin_amdgcn_s_setprio(1); _Pragma("unroll") for (int m = 0; m < 4; ++m) _Pragma("unroll") for (int n = 0; n < 2; ++n) _Pragma("unroll") for (int k = 0; k < 2; ++k) \
;         acc[ai][bj][m][n] = __builtin_amdgcn_mfma_f32_16x16x32_bf16(Bt[n][k], At[m][k], acc[ai][bj][m][n], 0, 0, 0); __builtin_amdgcn_s_setprio(0); } while (0)
; #define PG8_WAIT_V(n) asm volatile("s_waitcnt vmcnt(" #n ")" ::: "memory")
; template <class Epi, class Sched, bool ABLK = false, bool ALIGN_EPI = true, bool SP2 = true, bool BBLK = true>
; __device__ __forceinline__ void gemm_phase(LAS unsigned char* lds, const Gemm g, const Sched& S, const Epi& E) {
;     ...
;         for (int t = 0; t < nt; t += 2) {
;             const bool last = (t == nt - 2);
;             const char* a1 = a_tile(uA, tbA + t + 1);
;             const char* a2 = last ? a_tile(nuA, ntbA) : a_tile(uA, tbA + t + 2); const char* b2 = last ? nB : cB + (size_t)(t + 2) * kstepB;
;             const char* a3 = last ? a_tile(nuA, ntbA + 1) : a_tile(uA, tbA + t + 3); const char* b3 = b2 + kstepB;
;             if (last && has_next) S.a_ready(nxt);
;             if constexpr (SP2) {
;             PG8_LDB(B0, 0, 0); PG8_LDB(B1, 0, 1); PG8_SCHED; PG8_LDA(At, 0, 0); PG8_STAGE(PG8_SA(1, 1), a1 + hstepA, voffA);
;             PG8_WAIT_V(8); PG8_WAIT_L(0); PG8_BAR; PG8_MMA(0, 0, At, B0); PG8_MMA(0, 1, At, B1); PG8_BAR; PG8_SCHED;
;     ...
;             PG8_LDA(At, 1, 1); PG8_STAGE(PG8_SB(1, 0), b3, voffB); PG8_STAGE(PG8_SB(1, 1), b3 + hstepB, voffB); PG8_STAGE(PG8_SA(1, 0), a3, voffA);
;             PG8_WAIT_V(8); PG8_WAIT_L(0); PG8_BAR; PG8_MMA(1, 0, At, B0); PG8_MMA(1, 1, At, B1); PG8_BAR; PG8_SCHED;
	s_add_u32 s36, s34, 0x8000
	s_addc_u32 s37, s35, 0
	s_add_i32 s55, s60, s39
	s_mov_b32 m0, s55
	ds_read_b128 v[204:207], v170 offset:49152
	ds_read_b128 v[208:211], v170 offset:50176
	ds_read_b128 v[212:215], v170 offset:51200
	ds_read_b128 v[216:219], v170 offset:52224
	global_load_lds_dwordx4 v134, s[36:37]
	s_add_i32 m0, s55, 0x2000
	s_add_u32 s34, s34, 0xc000
	v_lshl_add_u64 v[236:237], s[36:37], 0, v[130:131]
	s_addc_u32 s35, s35, 0
	s_add_i32 s36, s61, s39
	global_load_lds_dwordx4 v[236:237], off
	s_mov_b32 m0, s36
	ds_read_b128 v[220:223], v170 offset:53248
	global_load_lds_dwordx4 v134, s[34:35]
	s_add_i32 m0, s36, 0x2000
	ds_read_b128 v[224:227], v170 offset:54272
	global_load_lds_dwordx4 v130, s[34:35]
	s_mov_b32 m0, s45
	ds_read_b128 v[228:231], v170 offset:55296
	global_load_lds_dwordx4 v136, s[30:31]
	s_mov_b32 m0, s46
	ds_read_b128 v[232:235], v170 offset:56320
	global_load_lds_dwordx4 v132, s[30:31]
	s_waitcnt vmcnt(8) lgkmcnt(0)
	s_barrier
	v_mfma_f32_16x16x32_bf16 v[62:65], v[172:175], v[204:207], v[62:65]
	v_mfma_f32_16x16x32_bf16 v[58:61], v[180:183], v[204:207], v[58:61]
	v_mfma_f32_16x16x32_bf16 v[46:49], v[172:175], v[212:215], v[46:49]
	v_mfma_f32_16x16x32_bf16 v[42:45], v[180:183], v[212:215], v[42:45]
	v_mfma_f32_16x16x32_bf16 v[30:33], v[172:175], v[220:223], v[30:33]
	v_mfma_f32_16x16x32_bf16 v[26:29], v[180:183], v[220:223], v[26:29]
	v_mfma_f32_16x16x32_bf16 v[14:17], v[172:175], v[228:231], v[14:17]
	v_mfma_f32_16x16x32_bf16 v[10:13], v[180:183], v[228:231], v[10:13]
	v_mfma_f32_16x16x32_bf16 v[62:65], v[176:179], v[208:211], v[62:65]
	v_mfma_f32_16x16x32_bf16 v[58:61], v[184:187], v[208:211], v[58:61]
	v_mfma_f32_16x16x32_bf16 v[46:49], v[176:179], v[216:219], v[46:49]
	v_mfma_f32_16x16x32_bf16 v[42:45], v[184:187], v[216:219], v[42:45]
	v_mfma_f32_16x16x32_bf16 v[30:33], v[176:179], v[224:227], v[30:33]
	v_mfma_f32_16x16x32_bf16 v[26:29], v[184:187], v[224:227], v[26:29]
	v_mfma_f32_16x16x32_bf16 v[14:17], v[176:179], v[232:235], v[14:17]
	v_mfma_f32_16x16x32_bf16 v[10:13], v[184:187], v[232:235], v[10:13]
	v_mfma_f32_16x16x32_bf16 v[54:57], v[188:191], v[204:207], v[54:57]
	v_mfma_f32_16x16x32_bf16 v[50:53], v[196:199], v[204:207], v[50:53]
	v_mfma_f32_16x16x32_bf16 v[38:41], v[188:191], v[212:215], v[38:41]
	v_mfma_f32_16x16x32_bf16 v[34:37], v[196:199], v[212:215], v[34:37]
	v_mfma_f32_16x16x32_bf16 v[22:25], v[188:191], v[220:223], v[22:25]
	v_mfma_f32_16x16x32_bf16 v[18:21], v[196:199], v[220:223], v[18:21]
	v_mfma_f32_16x16x32_bf16 v[6:9], v[188:191], v[228:231], v[6:9]
	v_mfma_f32_16x16x32_bf16 v[2:5], v[196:199], v[228:231], v[2:5]
	v_mfma_f32_16x16x32_bf16 v[54:57], v[192:195], v[208:211], v[54:57]
	v_mfma_f32_16x16x32_bf16 v[50:53], v[200:203], v[208:211], v[50:53]
	v_mfma_f32_16x16x32_bf16 v[38:41], v[192:195], v[216:219], v[38:41]
	v_mfma_f32_16x16x32_bf16 v[34:37], v[200:203], v[216:219], v[34:37]
	v_mfma_f32_16x16x32_bf16 v[22:25], v[192:195], v[224:227], v[22:25]
	v_mfma_f32_16x16x32_bf16 v[18:21], v[200:203], v[224:227], v[18:21]
	v_mfma_f32_16x16x32_bf16 v[6:9], v[192:195], v[232:235], v[6:9]
	v_mfma_f32_16x16x32_bf16 v[2:5], v[200:203], v[232:235], v[2:5]
	s_barrier
	s_add_i32 s54, s54, 2
	s_add_u32 s28, s28, 0x100
	s_addc_u32 s29, s29, 0
	s_add_u32 s52, s52, 0x10000
	s_addc_u32 s53, s53, 0
	s_cmp_gt_u32 s54, 29
.LBB0_1842:
	ds_read_b128 v[172:175], v168
	ds_read_b128 v[176:179], v168 offset:1024
	ds_read_b128 v[180:183], v168 offset:2048
	ds_read_b128 v[184:187], v168 offset:3072
	ds_read_b128 v[188:191], v169
	ds_read_b128 v[192:195], v169 offset:1024
	ds_read_b128 v[196:199], v169 offset:2048
	ds_read_b128 v[200:203], v169 offset:3072
	s_add_u32 s30, s26, s28
	s_addc_u32 s31, s27, s29
	s_add_u32 s36, s30, 0x100
	s_addc_u32 s37, s31, 0
	s_add_u32 s30, s30, 0x180
	s_addc_u32 s31, s31, 0
	s_cmpk_eq_i32 s28, 0xf00
	s_cselect_b32 s31, s51, s31
	s_cselect_b32 s30, s23, s30
	s_cselect_b32 s35, s11, s53
	s_cselect_b32 s34, s15, s52
	s_cselect_b32 s37, s4, s37
	s_cselect_b32 s36, s5, s36
	s_mov_b32 m0, s47
	v_lshl_add_u64 v[236:237], v[164:165], 0, s[28:29]
	ds_read_b128 v[204:207], v170
	ds_read_b128 v[208:211], v170 offset:1024
	ds_read_b128 v[212:215], v170 offset:2048
	ds_read_b128 v[216:219], v170 offset:3072
	ds_read_b128 v[220:223], v170 offset:4096
	ds_read_b128 v[224:227], v170 offset:5120
	ds_read_b128 v[228:231], v170 offset:6144
	global_load_lds_dwordx4 v[236:237], off
	v_lshl_add_u64 v[236:237], v[166:167], 0, s[28:29]
	s_mov_b32 m0, s48
	ds_read_b128 v[232:235], v170 offset:7168
	global_load_lds_dwordx4 v[236:237], off
	s_waitcnt vmcnt(8) lgkmcnt(0)
	s_barrier
; #define PG8_STAGE(bufoff, gbase, voff) do { _Pragma("unroll") for (int _i = 0; _i < 2; ++_i) \
;         __builtin_amdgcn_global_load_lds((const unsigned*)((const char*)(gbase) + (voff)[_i]), (LAS unsigned*)(lds + (bufoff) + ldsw + _i * 8192), 16, 0, 0); } while (0)
; #define PG8_LDA(dst, b, h) do { _Pragma("unroll") for (int m = 0; m < 4; ++m) _Pragma("unroll") for (int k = 0; k < 2; ++k) dst[m][k] = *(const LAS bf16x8*)(lds + PG8_SA(b, h) + aoff + m * 2048 + k * 1024); } while (0)
; #define PG8_LDB(dst, b, h) do { _Pragma("unroll") for (int n = 0; n < 2; ++n) _Pragma("unroll") for (int k = 0; k < 2; ++k) dst[n][k] = *(const LAS bf16x8*)(lds + PG8_SB(b, h) + boff + n * 2048 + k * 1024); } while (0)
; #define PG8_MMA(ai, bj, At, Bt) do { __builtin_amdgcn_s_setprio(1); _Pragma("unroll") for (int m = 0; m < 4; ++m) _Pragma("unroll") for (int n = 0; n < 2; ++n) _Pragma("unroll") for (int k = 0; k < 2; ++k) \
;         acc[ai][bj][m][n] = __builtin_amdgcn_mfma_f32_16x16x32_bf16(Bt[n][k], At[m][k], acc[ai][bj][m][n], 0, 0, 0); __builtin_amdgcn_s_setprio(0); } while (0)
; #define PG8_WAIT_V(n) asm volatile("s_waitcnt vmcnt(" #n ")" ::: "memory")
; #define PG8_WAIT_L(n) asm volatile("s_waitcnt lgkmcnt(" #n ")" ::: "memory")
; #define PG8_BAR __builtin_amdgcn_s_barrier()
; #define PG8_SCHED __builtin_amdgcn_sched_barrier(0)
; template <class Epi, class Sched, bool ABLK = false, bool ALIGN_EPI = true, bool SP2 = true, bool BBLK = true>
; __device__ __forceinline__ void gemm_phase(LAS unsigned char* lds, const Gemm g, const Sched& S, const Epi& E) {
;     ...
;             PG8_LDB(B0, 0, 0); PG8_LDB(B1, 0, 1); PG8_SCHED; PG8_LDA(At, 0, 0); PG8_STAGE(PG8_SA(1, 1), a1 + hstepA, voffA);
;             PG8_WAIT_V(8); PG8_WAIT_L(0); PG8_BAR; PG8_MMA(0, 0, At, B0); PG8_MMA(0, 1, At, B1); PG8_BAR; PG8_SCHED;
;             PG8_LDA(At, 0, 1); PG8_STAGE(PG8_SB(0, 0), b2, voffB); PG8_STAGE(PG8_SB(0, 1), b2 + hstepB, voffB); PG8_STAGE(PG8_SA(0, 0), a2, voffA);
;             PG8_WAIT_V(8); PG8_WAIT_L(0); PG8_BAR; PG8_MMA(1, 0, At, B0); PG8_MMA(1, 1, At, B1); PG8_BAR; PG8_SCHED;
	v_mfma_f32_16x16x32_bf16 v[126:129], v[172:175], v[204:207], v[126:129]
	v_mfma_f32_16x16x32_bf16 v[122:125], v[180:183], v[204:207], v[122:125]
	v_mfma_f32_16x16x32_bf16 v[110:113], v[172:175], v[212:215], v[110:113]
	v_mfma_f32_16x16x32_bf16 v[106:109], v[180:183], v[212:215], v[106:109]
	v_mfma_f32_16x16x32_bf16 v[94:97], v[172:175], v[220:223], v[94:97]
	v_mfma_f32_16x16x32_bf16 v[90:93], v[180:183], v[220:223], v[90:93]
	v_mfma_f32_16x16x32_bf16 v[78:81], v[172:175], v[228:231], v[78:81]
	v_mfma_f32_16x16x32_bf16 v[74:77], v[180:183], v[228:231], v[74:77]
	v_mfma_f32_16x16x32_bf16 v[126:129], v[176:179], v[208:211], v[126:129]
	v_mfma_f32_16x16x32_bf16 v[122:125], v[184:187], v[208:211], v[122:125]
	v_mfma_f32_16x16x32_bf16 v[110:113], v[176:179], v[216:219], v[110:113]
	v_mfma_f32_16x16x32_bf16 v[106:109], v[184:187], v[216:219], v[106:109]
	v_mfma_f32_16x16x32_bf16 v[94:97], v[176:179], v[224:227], v[94:97]
	v_mfma_f32_16x16x32_bf16 v[90:93], v[184:187], v[224:227], v[90:93]
	v_mfma_f32_16x16x32_bf16 v[78:81], v[176:179], v[232:235], v[78:81]
	v_mfma_f32_16x16x32_bf16 v[74:77], v[184:187], v[232:235], v[74:77]
	v_mfma_f32_16x16x32_bf16 v[118:121], v[188:191], v[204:207], v[118:121]
	v_mfma_f32_16x16x32_bf16 v[114:117], v[196:199], v[204:207], v[114:117]
	v_mfma_f32_16x16x32_bf16 v[102:105], v[188:191], v[212:215], v[102:105]
	v_mfma_f32_16x16x32_bf16 v[98:101], v[196:199], v[212:215], v[98:101]
	v_mfma_f32_16x16x32_bf16 v[86:89], v[188:191], v[220:223], v[86:89]
	v_mfma_f32_16x16x32_bf16 v[82:85], v[196:199], v[220:223], v[82:85]
	v_mfma_f32_16x16x32_bf16 v[70:73], v[188:191], v[228:231], v[70:73]
	v_mfma_f32_16x16x32_bf16 v[66:69], v[196:199], v[228:231], v[66:69]
	v_mfma_f32_16x16x32_bf16 v[118:121], v[192:195], v[208:211], v[118:121]
	v_mfma_f32_16x16x32_bf16 v[114:117], v[200:203], v[208:211], v[114:117]
	v_mfma_f32_16x16x32_bf16 v[102:105], v[192:195], v[216:219], v[102:105]
	v_mfma_f32_16x16x32_bf16 v[98:101], v[200:203], v[216:219], v[98:101]
	v_mfma_f32_16x16x32_bf16 v[86:89], v[192:195], v[224:227], v[86:89]
	v_mfma_f32_16x16x32_bf16 v[82:85], v[200:203], v[224:227], v[82:85]
	v_mfma_f32_16x16x32_bf16 v[70:73], v[192:195], v[232:235], v[70:73]
	v_mfma_f32_16x16x32_bf16 v[66:69], v[200:203], v[232:235], v[66:69]
	s_barrier
	s_mov_b32 m0, s49
	s_add_u32 s56, s34, 0x4000
	ds_read_b128 v[204:207], v170 offset:16384
	ds_read_b128 v[208:211], v170 offset:17408
	ds_read_b128 v[212:215], v170 offset:18432
	ds_read_b128 v[216:219], v170 offset:19456
	global_load_lds_dwordx4 v134, s[34:35]
	s_mov_b32 m0, s50
	s_addc_u32 s57, s35, 0
	s_add_i32 s55, s73, s39
	global_load_lds_dwordx4 v130, s[34:35]
	s_mov_b32 m0, s55
	ds_read_b128 v[220:223], v170 offset:20480
	global_load_lds_dwordx4 v134, s[56:57]
	s_add_i32 m0, s55, 0x2000
	ds_read_b128 v[224:227], v170 offset:21504
	global_load_lds_dwordx4 v130, s[56:57]
	s_mov_b32 m0, s25
	ds_read_b128 v[228:231], v170 offset:22528
	global_load_lds_dwordx4 v136, s[36:37]
	s_mov_b32 m0, s40
	ds_read_b128 v[232:235], v170 offset:23552
	global_load_lds_dwordx4 v132, s[36:37]
	s_waitcnt vmcnt(8) lgkmcnt(0)
	s_barrier
	v_mfma_f32_16x16x32_bf16 v[62:65], v[172:175], v[204:207], v[62:65]
	v_mfma_f32_16x16x32_bf16 v[58:61], v[180:183], v[204:207], v[58:61]
	v_mfma_f32_16x16x32_bf16 v[46:49], v[172:175], v[212:215], v[46:49]
	v_mfma_f32_16x16x32_bf16 v[42:45], v[180:183], v[212:215], v[42:45]
	v_mfma_f32_16x16x32_bf16 v[30:33], v[172:175], v[220:223], v[30:33]
	v_mfma_f32_16x16x32_bf16 v[26:29], v[180:183], v[220:223], v[26:29]
	v_mfma_f32_16x16x32_bf16 v[14:17], v[172:175], v[228:231], v[14:17]
	v_mfma_f32_16x16x32_bf16 v[10:13], v[180:183], v[228:231], v[10:13]
	v_mfma_f32_16x16x32_bf16 v[62:65], v[176:179], v[208:211], v[62:65]
	v_mfma_f32_16x16x32_bf16 v[58:61], v[184:187], v[208:211], v[58:61]
	v_mfma_f32_16x16x32_bf16 v[46:49], v[176:179], v[216:219], v[46:49]
	v_mfma_f32_16x16x32_bf16 v[42:45], v[184:187], v[216:219], v[42:45]
	v_mfma_f32_16x16x32_bf16 v[30:33], v[176:179], v[224:227], v[30:33]
	v_mfma_f32_16x16x32_bf16 v[26:29], v[184:187], v[224:227], v[26:29]
	v_mfma_f32_16x16x32_bf16 v[14:17], v[176:179], v[232:235], v[14:17]
	v_mfma_f32_16x16x32_bf16 v[10:13], v[184:187], v[232:235], v[10:13]
	v_mfma_f32_16x16x32_bf16 v[54:57], v[188:191], v[204:207], v[54:57]
	v_mfma_f32_16x16x32_bf16 v[50:53], v[196:199], v[204:207], v[50:53]
	v_mfma_f32_16x16x32_bf16 v[38:41], v[188:191], v[212:215], v[38:41]
	v_mfma_f32_16x16x32_bf16 v[34:37], v[196:199], v[212:215], v[34:37]
	v_mfma_f32_16x16x32_bf16 v[22:25], v[188:191], v[220:223], v[22:25]
	v_mfma_f32_16x16x32_bf16 v[18:21], v[196:199], v[220:223], v[18:21]
	v_mfma_f32_16x16x32_bf16 v[6:9], v[188:191], v[228:231], v[6:9]
	v_mfma_f32_16x16x32_bf16 v[2:5], v[196:199], v[228:231], v[2:5]
	v_mfma_f32_16x16x32_bf16 v[54:57], v[192:195], v[208:211], v[54:57]
	v_mfma_f32_16x16x32_bf16 v[50:53], v[200:203], v[208:211], v[50:53]
	v_mfma_f32_16x16x32_bf16 v[38:41], v[192:195], v[216:219], v[38:41]
	v_mfma_f32_16x16x32_bf16 v[34:37], v[200:203], v[216:219], v[34:37]
	v_mfma_f32_16x16x32_bf16 v[22:25], v[192:195], v[224:227], v[22:25]
	v_mfma_f32_16x16x32_bf16 v[18:21], v[200:203], v[224:227], v[18:21]
	v_mfma_f32_16x16x32_bf16 v[6:9], v[192:195], v[232:235], v[6:9]
	v_mfma_f32_16x16x32_bf16 v[2:5], v[200:203], v[232:235], v[2:5]
	s_barrier
; #define PG8_STAGE(bufoff, gbase, voff) do { _Pragma("unroll") for (int _i = 0; _i < 2; ++_i) \
;         __builtin_amdgcn_global_load_lds((const unsigned*)((const char*)(gbase) + (voff)[_i]), (LAS unsigned*)(lds + (bufoff) + ldsw + _i * 8192), 16, 0, 0); } while (0)
; #define PG8_LDA(dst, b, h) do { _Pragma("unroll") for (int m = 0; m < 4; ++m) _Pragma("unroll") for (int k = 0; k < 2; ++k) dst[m][k] = *(const LAS bf16x8*)(lds + PG8_SA(b, h) + aoff + m * 2048 + k * 1024); } while (0)
; #define PG8_LDB(dst, b, h) do { _Pragma("unroll") for (int n = 0; n < 2; ++n) _Pragma("unroll") for (int k = 0; k < 2; ++k) dst[n][k] = *(const LAS bf16x8*)(lds + PG8_SB(b, h) + boff + n * 2048 + k * 1024); } while (0)
; #define PG8_MMA(ai, bj, At, Bt) do { __builtin_amdgcn_s_setprio(1); _Pragma("unroll") for (int m = 0; m < 4; ++m) _Pragma("unroll") for (int n = 0; n < 2; ++n) _Pragma("unroll") for (int k = 0; k < 2; ++k) \
;         acc[ai][bj][m][n] = __builtin_amdgcn_mfma_f32_16x16x32_bf16(Bt[n][k], At[m][k], acc[ai][bj][m][n], 0, 0, 0); __builtin_amdgcn_s_setprio(0); } while (0)
; #define PG8_WAIT_V(n) asm volatile("s_waitcnt vmcnt(" #n ")" ::: "memory")
; #define PG8_WAIT_L(n) asm volatile("s_waitcnt lgkmcnt(" #n ")" ::: "memory")
; #define PG8_BAR __builtin_amdgcn_s_barrier()
; #define PG8_SCHED __builtin_amdgcn_sched_barrier(0)
; template <class Epi, class Sched, bool ABLK = false, bool ALIGN_EPI = true, bool SP2 = true, bool BBLK = true>
; __device__ __forceinline__ void gemm_phase(LAS unsigned char* lds, const Gemm g, const Sched& S, const Epi& E) {
;     ...
;             PG8_LDB(B0, 1, 0); PG8_LDB(B1, 1, 1); PG8_SCHED; PG8_LDA(At, 1, 0); PG8_STAGE(PG8_SA(0, 1), a2 + hstepA, voffA);
;             PG8_WAIT_V(8); PG8_WAIT_L(0); PG8_BAR; PG8_MMA(0, 0, At, B0); PG8_MMA(0, 1, At, B1); PG8_BAR; PG8_SCHED;
;             PG8_LDA(At, 1, 1); PG8_STAGE(PG8_SB(1, 0), b3, voffB); PG8_STAGE(PG8_SB(1, 1), b3 + hstepB, voffB); PG8_STAGE(PG8_SA(1, 0), a3, voffA);
;             PG8_WAIT_V(8); PG8_WAIT_L(0); PG8_BAR; PG8_MMA(1, 0, At, B0); PG8_MMA(1, 1, At, B1); PG8_BAR; PG8_SCHED;
;     ...
;         if constexpr (ALIGN_EPI) { if (wr == 0) PG8_BAR; }
	v_add_u32_e32 v171, s60, v1
	ds_read_b128 v[172:175], v171
	ds_read_b128 v[176:179], v171 offset:1024
	ds_read_b128 v[180:183], v171 offset:2048
	ds_read_b128 v[184:187], v171 offset:3072
	v_add_u32_e32 v171, s61, v1
	ds_read_b128 v[188:191], v171
	ds_read_b128 v[192:195], v171 offset:1024
	ds_read_b128 v[196:199], v171 offset:2048
	ds_read_b128 v[200:203], v171 offset:3072
	s_add_u32 s36, s36, 0x80000
	s_addc_u32 s37, s37, 0
	s_mov_b32 m0, s41
	ds_read_b128 v[204:207], v170 offset:32768
	ds_read_b128 v[208:211], v170 offset:33792
	ds_read_b128 v[212:215], v170 offset:34816
	ds_read_b128 v[216:219], v170 offset:35840
	ds_read_b128 v[220:223], v170 offset:36864
	ds_read_b128 v[224:227], v170 offset:37888
	ds_read_b128 v[228:231], v170 offset:38912
	global_load_lds_dwordx4 v136, s[36:37]
	s_mov_b32 m0, s42
	ds_read_b128 v[232:235], v170 offset:39936
	global_load_lds_dwordx4 v132, s[36:37]
	s_waitcnt vmcnt(8) lgkmcnt(0)
	s_barrier
	v_mfma_f32_16x16x32_bf16 v[126:129], v[172:175], v[204:207], v[126:129]
	v_mfma_f32_16x16x32_bf16 v[122:125], v[180:183], v[204:207], v[122:125]
	v_mfma_f32_16x16x32_bf16 v[110:113], v[172:175], v[212:215], v[110:113]
	v_mfma_f32_16x16x32_bf16 v[106:109], v[180:183], v[212:215], v[106:109]
	v_mfma_f32_16x16x32_bf16 v[94:97], v[172:175], v[220:223], v[94:97]
	v_mfma_f32_16x16x32_bf16 v[90:93], v[180:183], v[220:223], v[90:93]
	v_mfma_f32_16x16x32_bf16 v[78:81], v[172:175], v[228:231], v[78:81]
	v_mfma_f32_16x16x32_bf16 v[74:77], v[180:183], v[228:231], v[74:77]
	v_mfma_f32_16x16x32_bf16 v[126:129], v[176:179], v[208:211], v[126:129]
	v_mfma_f32_16x16x32_bf16 v[122:125], v[184:187], v[208:211], v[122:125]
	v_mfma_f32_16x16x32_bf16 v[110:113], v[176:179], v[216:219], v[110:113]
	v_mfma_f32_16x16x32_bf16 v[106:109], v[184:187], v[216:219], v[106:109]
	v_mfma_f32_16x16x32_bf16 v[94:97], v[176:179], v[224:227], v[94:97]
	v_mfma_f32_16x16x32_bf16 v[90:93], v[184:187], v[224:227], v[90:93]
	v_mfma_f32_16x16x32_bf16 v[78:81], v[176:179], v[232:235], v[78:81]
	v_mfma_f32_16x16x32_bf16 v[74:77], v[184:187], v[232:235], v[74:77]
	v_mfma_f32_16x16x32_bf16 v[118:121], v[188:191], v[204:207], v[118:121]
	v_mfma_f32_16x16x32_bf16 v[114:117], v[196:199], v[204:207], v[114:117]
	v_mfma_f32_16x16x32_bf16 v[102:105], v[188:191], v[212:215], v[102:105]
	v_mfma_f32_16x16x32_bf16 v[98:101], v[196:199], v[212:215], v[98:101]
	v_mfma_f32_16x16x32_bf16 v[86:89], v[188:191], v[220:223], v[86:89]
	v_mfma_f32_16x16x32_bf16 v[82:85], v[196:199], v[220:223], v[82:85]
	v_mfma_f32_16x16x32_bf16 v[70:73], v[188:191], v[228:231], v[70:73]
	v_mfma_f32_16x16x32_bf16 v[66:69], v[196:199], v[228:231], v[66:69]
	v_mfma_f32_16x16x32_bf16 v[118:121], v[192:195], v[208:211], v[118:121]
	v_mfma_f32_16x16x32_bf16 v[114:117], v[200:203], v[208:211], v[114:117]
	v_mfma_f32_16x16x32_bf16 v[102:105], v[192:195], v[216:219], v[102:105]
	v_mfma_f32_16x16x32_bf16 v[98:101], v[200:203], v[216:219], v[98:101]
	v_mfma_f32_16x16x32_bf16 v[86:89], v[192:195], v[224:227], v[86:89]
	v_mfma_f32_16x16x32_bf16 v[82:85], v[200:203], v[224:227], v[82:85]
	v_mfma_f32_16x16x32_bf16 v[70:73], v[192:195], v[232:235], v[70:73]
	v_mfma_f32_16x16x32_bf16 v[66:69], v[200:203], v[232:235], v[66:69]
	s_barrier
	s_add_u32 s36, s34, 0x8000
	s_addc_u32 s37, s35, 0
	s_add_i32 s55, s60, s39
	s_mov_b32 m0, s55
	ds_read_b128 v[204:207], v170 offset:49152
	ds_read_b128 v[208:211], v170 offset:50176
	ds_read_b128 v[212:215], v170 offset:51200
	ds_read_b128 v[216:219], v170 offset:52224
	global_load_lds_dwordx4 v134, s[36:37]
	s_add_i32 m0, s55, 0x2000
	s_add_u32 s34, s34, 0xc000
	v_lshl_add_u64 v[236:237], s[36:37], 0, v[130:131]
	s_addc_u32 s35, s35, 0
	s_add_i32 s36, s61, s39
	global_load_lds_dwordx4 v[236:237], off
	s_mov_b32 m0, s36
	ds_read_b128 v[220:223], v170 offset:53248
	global_load_lds_dwordx4 v134, s[34:35]
	s_add_i32 m0, s36, 0x2000
	ds_read_b128 v[224:227], v170 offset:54272
	global_load_lds_dwordx4 v130, s[34:35]
	s_mov_b32 m0, s45
	ds_read_b128 v[228:231], v170 offset:55296
	global_load_lds_dwordx4 v136, s[30:31]
	s_mov_b32 m0, s46
	ds_read_b128 v[232:235], v170 offset:56320
	global_load_lds_dwordx4 v132, s[30:31]
	s_waitcnt vmcnt(8) lgkmcnt(0)
	s_barrier
	v_mfma_f32_16x16x32_bf16 v[62:65], v[172:175], v[204:207], v[62:65]
	v_mfma_f32_16x16x32_bf16 v[58:61], v[180:183], v[204:207], v[58:61]
	v_mfma_f32_16x16x32_bf16 v[46:49], v[172:175], v[212:215], v[46:49]
	v_mfma_f32_16x16x32_bf16 v[42:45], v[180:183], v[212:215], v[42:45]
	v_mfma_f32_16x16x32_bf16 v[30:33], v[172:175], v[220:223], v[30:33]
	v_mfma_f32_16x16x32_bf16 v[26:29], v[180:183], v[220:223], v[26:29]
	v_mfma_f32_16x16x32_bf16 v[14:17], v[172:175], v[228:231], v[14:17]
	v_mfma_f32_16x16x32_bf16 v[10:13], v[180:183], v[228:231], v[10:13]
	v_mfma_f32_16x16x32_bf16 v[62:65], v[176:179], v[208:211], v[62:65]
	v_mfma_f32_16x16x32_bf16 v[58:61], v[184:187], v[208:211], v[58:61]
	v_mfma_f32_16x16x32_bf16 v[46:49], v[176:179], v[216:219], v[46:49]
	v_mfma_f32_16x16x32_bf16 v[42:45], v[184:187], v[216:219], v[42:45]
	v_mfma_f32_16x16x32_bf16 v[30:33], v[176:179], v[224:227], v[30:33]
	v_mfma_f32_16x16x32_bf16 v[26:29], v[184:187], v[224:227], v[26:29]
	v_mfma_f32_16x16x32_bf16 v[14:17], v[176:179], v[232:235], v[14:17]
	v_mfma_f32_16x16x32_bf16 v[10:13], v[184:187], v[232:235], v[10:13]
	v_mfma_f32_16x16x32_bf16 v[54:57], v[188:191], v[204:207], v[54:57]
	v_mfma_f32_16x16x32_bf16 v[50:53], v[196:199], v[204:207], v[50:53]
	v_mfma_f32_16x16x32_bf16 v[38:41], v[188:191], v[212:215], v[38:41]
	v_mfma_f32_16x16x32_bf16 v[34:37], v[196:199], v[212:215], v[34:37]
	v_mfma_f32_16x16x32_bf16 v[22:25], v[188:191], v[220:223], v[22:25]
	v_mfma_f32_16x16x32_bf16 v[18:21], v[196:199], v[220:223], v[18:21]
	v_mfma_f32_16x16x32_bf16 v[6:9], v[188:191], v[228:231], v[6:9]
	v_mfma_f32_16x16x32_bf16 v[2:5], v[196:199], v[228:231], v[2:5]
	v_mfma_f32_16x16x32_bf16 v[54:57], v[192:195], v[208:211], v[54:57]
	v_mfma_f32_16x16x32_bf16 v[50:53], v[200:203], v[208:211], v[50:53]
	v_mfma_f32_16x16x32_bf16 v[38:41], v[192:195], v[216:219], v[38:41]
	v_mfma_f32_16x16x32_bf16 v[34:37], v[200:203], v[216:219], v[34:37]
	v_mfma_f32_16x16x32_bf16 v[22:25], v[192:195], v[224:227], v[22:25]
	v_mfma_f32_16x16x32_bf16 v[18:21], v[200:203], v[224:227], v[18:21]
	v_mfma_f32_16x16x32_bf16 v[6:9], v[192:195], v[232:235], v[6:9]
	v_mfma_f32_16x16x32_bf16 v[2:5], v[200:203], v[232:235], v[2:5]
	s_barrier
	s_add_i32 s54, s54, 2
	s_add_u32 s28, s28, 0x100
	s_addc_u32 s29, s29, 0
	s_add_u32 s52, s52, 0x10000
	s_addc_u32 s53, s53, 0
	s_cmp_gt_u32 s54, 29
	s_cbranch_scc0 .LBB0_1842
	s_and_b64 vcc, exec, s[6:7]
	s_cbranch_vccz .LBB0_1845
	s_barrier

; #define PG8_STAGE(bufoff, gbase, voff) do { _Pragma("unroll") for (int _i = 0; _i < 2; ++_i) \
;         __builtin_amdgcn_global_load_lds((const unsigned*)((const char*)(gbase) + (voff)[_i]), (LAS unsigned*)(lds + (bufoff) + ldsw + _i * 8192), 16, 0, 0); } while (0)
; #define PG8_LDA(dst, b, h) do { _Pragma("unroll") for (int m = 0; m < 4; ++m) _Pragma("unroll") for (int k = 0; k < 2; ++k) dst[m][k] = *(const LAS bf16x8*)(lds + PG8_SA(b, h) + aoff + m * 2048 + k * 1024); } while (0)
; #define PG8_LDB(dst, b, h) do { _Pragma("unroll") for (int n = 0; n < 2; ++n) _Pragma("unroll") for (int k = 0; k < 2; ++k) dst[n][k] = *(const LAS bf16x8*)(lds + PG8_SB(b, h) + boff + n * 2048 + k * 1024); } while (0)
; #define PG8_WAIT_V(n) asm volatile("s_waitcnt vmcnt(" #n ")" ::: "memory")
; #define PG8_WAIT_L(n) asm volatile("s_waitcnt lgkmcnt(" #n ")" ::: "memory")
; #define PG8_BAR __builtin_amdgcn_s_barrier()
; #define PG8_SCHED __builtin_amdgcn_sched_barrier(0)
; template <class Epi, class Sched, bool ABLK = false, bool ALIGN_EPI = true, bool SP2 = true, bool BBLK = true>
; __device__ __forceinline__ void gemm_phase(LAS unsigned char* lds, const Gemm g, const Sched& S, const Epi& E) {
;     ...
;         const bool has_next = S.next(ui + 1, nxt);
;         const int nt = cur.nt;
;         const char* nuA = has_next ? a_unit(nxt) : uA; const int ntbA = has_next ? nxt.k0 / BK : tbA; const char* nB = has_next ? (const char*)g.Bt + (size_t)nxt.pn * tstepB + b_k0(nxt.k0) : cB;
;         for (int t = 0; t < nt; t += 2) {
;             const bool last = (t == nt - 2);
;             const char* a1 = a_tile(uA, tbA + t + 1);
;             const char* a2 = last ? a_tile(nuA, ntbA) : a_tile(uA, tbA + t + 2); const char* b2 = last ? nB : cB + (size_t)(t + 2) * kstepB;
;             const char* a3 = last ? a_tile(nuA, ntbA + 1) : a_tile(uA, tbA + t + 3); const char* b3 = b2 + kstepB;
;             if (last && has_next) S.a_ready(nxt);
;             if constexpr (SP2) {
;             PG8_LDB(B0, 0, 0); PG8_LDB(B1, 0, 1); PG8_SCHED; PG8_LDA(At, 0, 0); PG8_STAGE(PG8_SA(1, 1), a1 + hstepA, voffA);
;             PG8_WAIT_V(8); PG8_WAIT_L(0); PG8_BAR; PG8_MMA(0, 0, At, B0); PG8_MMA(0, 1, At, B1); PG8_BAR; PG8_SCHED;
;             PG8_LDA(At, 0, 1); PG8_STAGE(PG8_SB(0, 0), b2, voffB); PG8_STAGE(PG8_SB(0, 1), b2 + hstepB, voffB); PG8_STAGE(PG8_SA(0, 0), a2, voffA);
.LBB0_1906:
	s_ashr_i32 s81, s80, 31
	s_andn2_b64 vcc, exec, s[4:5]
	s_lshl_b64 s[24:25], s[80:81], 22
	s_add_u32 s24, s62, s24
	s_addc_u32 s25, s83, s25
	s_and_b64 s[26:27], s[4:5], exec
	s_cselect_b32 s37, s25, s35
	s_cselect_b32 s50, s24, s34
	s_ashr_i32 s26, s0, 31
	s_lshr_b32 s26, s26, 26
	s_add_i32 s26, s0, s26
	s_ashr_i32 s26, s26, 6
	s_and_b64 s[28:29], s[4:5], exec
	s_cselect_b32 s38, s26, s36
	s_ashr_i32 s79, s78, 31
	s_lshl_b64 s[28:29], s[78:79], 22
	s_add_u32 s39, s1, s28
	s_addc_u32 s51, s33, s29
	s_ashr_i32 s27, s26, 31
	s_lshl_b64 s[28:29], s[26:27], 15
	s_add_u32 s28, s39, s28
	s_addc_u32 s29, s51, s29
	v_cndmask_b32_e64 v2, 0, 1, s[4:5]
	s_and_b64 s[4:5], s[4:5], exec
	s_cselect_b32 s4, s29, s31
	s_cselect_b32 s5, s28, s30
	s_ashr_i32 s39, s38, 31
	s_lshl_b64 s[38:39], s[38:39], 15
	s_add_u32 s27, s50, s38
	s_addc_u32 s50, s37, s39
	s_add_u32 s51, s27, 0x8000
	s_addc_u32 s52, s50, 0
	s_add_u32 s53, s30, 0x10000
	s_addc_u32 s54, s31, 0
	s_ashr_i32 s37, s36, 31
	v_cmp_ne_u32_e64 s[10:11], 1, v2
	s_lshl_b64 s[30:31], s[36:37], 15
	v_lshl_add_u64 v[2:3], s[34:35], 0, v[138:139]
	s_add_u32 s55, s34, s30
	v_lshl_add_u64 v[142:143], v[2:3], 0, s[30:31]
	v_lshl_add_u64 v[2:3], s[34:35], 0, v[140:141]
	s_addc_u32 s56, s35, s31
	v_lshl_add_u64 v[144:145], v[2:3], 0, s[30:31]
	s_lshl_b32 s30, s48, 15
	s_add_i32 s30, s30, 0xfff00000
	v_mov_b32_e32 v2, 0
	s_add_u32 s57, s30, 0xf0000
	s_mov_b32 s58, 0
	s_mov_b64 s[30:31], 0
	ds_read_b128 v[152:155], v148
	ds_read_b128 v[156:159], v148 offset:1024
	ds_read_b128 v[160:163], v148 offset:2048
	ds_read_b128 v[164:167], v148 offset:3072
	ds_read_b128 v[168:171], v149
	ds_read_b128 v[172:175], v149 offset:1024
	ds_read_b128 v[176:179], v149 offset:2048
	ds_read_b128 v[180:183], v149 offset:3072
	s_add_u32 s34, s55, s30
	s_addc_u32 s35, s56, s31
	s_add_u32 s38, s34, 0x10000
	s_addc_u32 s39, s35, 0
	s_add_i32 s58, s58, 2
	s_add_u32 s36, s53, s30
	s_addc_u32 s37, s54, s31
	s_add_u32 s34, s34, 0x18000
	s_addc_u32 s35, s35, 0
	s_cmp_eq_u32 s57, s30
	s_cselect_b32 s35, s52, s35
	s_cselect_b32 s34, s51, s34
	s_cselect_b32 s37, s4, s37
	s_cselect_b32 s36, s5, s36
	s_cselect_b32 s39, s50, s39
	s_cselect_b32 s38, s27, s38
	v_lshl_add_u64 v[216:217], v[142:143], 0, s[30:31]
	s_add_i32 m0, s41, 0xc000
	ds_read_b128 v[184:187], v150
	ds_read_b128 v[188:191], v150 offset:1024
	ds_read_b128 v[192:195], v150 offset:2048
	ds_read_b128 v[196:199], v150 offset:3072
	ds_read_b128 v[200:203], v150 offset:4096
	ds_read_b128 v[204:207], v150 offset:5120
	ds_read_b128 v[208:211], v150 offset:6144
	global_load_lds_dwordx4 v[216:217], off
	v_lshl_add_u64 v[216:217], v[144:145], 0, s[30:31]
	s_add_i32 m0, s41, 0xe000
	ds_read_b128 v[212:215], v150 offset:7168
	global_load_lds_dwordx4 v[216:217], off
	s_waitcnt vmcnt(8) lgkmcnt(0)
	s_barrier
	v_mfma_f32_16x16x32_bf16 v[126:129], v[152:155], v[184:187], 0
	v_mfma_f32_16x16x32_bf16 v[122:125], v[160:163], v[184:187], 0
	v_mfma_f32_16x16x32_bf16 v[110:113], v[152:155], v[192:195], 0
	v_mfma_f32_16x16x32_bf16 v[106:109], v[160:163], v[192:195], 0
	v_mfma_f32_16x16x32_bf16 v[94:97], v[152:155], v[200:203], 0
	v_mfma_f32_16x16x32_bf16 v[90:93], v[160:163], v[200:203], 0
	v_mfma_f32_16x16x32_bf16 v[78:81], v[152:155], v[208:211], 0
	v_mfma_f32_16x16x32_bf16 v[74:77], v[160:163], v[208:211], 0
	v_mfma_f32_16x16x32_bf16 v[126:129], v[156:159], v[188:191], v[126:129]
	v_mfma_f32_16x16x32_bf16 v[122:125], v[164:167], v[188:191], v[122:125]
	v_mfma_f32_16x16x32_bf16 v[110:113], v[156:159], v[196:199], v[110:113]
	v_mfma_f32_16x16x32_bf16 v[106:109], v[164:167], v[196:199], v[106:109]
	v_mfma_f32_16x16x32_bf16 v[94:97], v[156:159], v[204:207], v[94:97]
	v_mfma_f32_16x16x32_bf16 v[90:93], v[164:167], v[204:207], v[90:93]
	v_mfma_f32_16x16x32_bf16 v[78:81], v[156:159], v[212:215], v[78:81]
	v_mfma_f32_16x16x32_bf16 v[74:77], v[164:167], v[212:215], v[74:77]
	v_mfma_f32_16x16x32_bf16 v[118:121], v[168:171], v[184:187], 0
	v_mfma_f32_16x16x32_bf16 v[114:117], v[176:179], v[184:187], 0
	v_mfma_f32_16x16x32_bf16 v[102:105], v[168:171], v[192:195], 0
	v_mfma_f32_16x16x32_bf16 v[98:101], v[176:179], v[192:195], 0
	v_mfma_f32_16x16x32_bf16 v[86:89], v[168:171], v[200:203], 0
	v_mfma_f32_16x16x32_bf16 v[82:85], v[176:179], v[200:203], 0
	v_mfma_f32_16x16x32_bf16 v[70:73], v[168:171], v[208:211], 0
	v_mfma_f32_16x16x32_bf16 v[66:69], v[176:179], v[208:211], 0
	v_mfma_f32_16x16x32_bf16 v[118:121], v[172:175], v[188:191], v[118:121]
	v_mfma_f32_16x16x32_bf16 v[114:117], v[180:183], v[188:191], v[114:117]
	v_mfma_f32_16x16x32_bf16 v[102:105], v[172:175], v[196:199], v[102:105]
	v_mfma_f32_16x16x32_bf16 v[98:101], v[180:183], v[196:199], v[98:101]
	v_mfma_f32_16x16x32_bf16 v[86:89], v[172:175], v[204:207], v[86:89]
	v_mfma_f32_16x16x32_bf16 v[82:85], v[180:183], v[204:207], v[82:85]
	v_mfma_f32_16x16x32_bf16 v[70:73], v[172:175], v[212:215], v[70:73]
	v_mfma_f32_16x16x32_bf16 v[66:69], v[180:183], v[212:215], v[66:69]
	s_barrier
	s_add_i32 s59, s72, s40
	s_mov_b32 m0, s59
	ds_read_b128 v[184:187], v150 offset:16384
	ds_read_b128 v[188:191], v150 offset:17408
	ds_read_b128 v[192:195], v150 offset:18432
	ds_read_b128 v[196:199], v150 offset:19456
	global_load_lds_dwordx4 v130, s[36:37]
	s_add_i32 m0, s59, 0x2000
	s_add_u32 s64, s36, 0x4000
	s_addc_u32 s65, s37, 0
	s_add_i32 s59, s73, s40
	global_load_lds_dwordx4 v132, s[36:37]
	s_mov_b32 m0, s59
	ds_read_b128 v[200:203], v150 offset:20480
	global_load_lds_dwordx4 v130, s[64:65]
	s_add_i32 m0, s59, 0x2000
	ds_read_b128 v[204:207], v150 offset:21504
	global_load_lds_dwordx4 v132, s[64:65]
	s_mov_b32 m0, s41
	ds_read_b128 v[208:211], v150 offset:22528
	global_load_lds_dwordx4 v130, s[38:39]
	s_mov_b32 m0, s42
	ds_read_b128 v[212:215], v150 offset:23552
	global_load_lds_dwordx4 v132, s[38:39]
	s_waitcnt vmcnt(8) lgkmcnt(0)
	s_barrier
; #define PG8_STAGE(bufoff, gbase, voff) do { _Pragma("unroll") for (int _i = 0; _i < 2; ++_i) \
;         __builtin_amdgcn_global_load_lds((const unsigned*)((const char*)(gbase) + (voff)[_i]), (LAS unsigned*)(lds + (bufoff) + ldsw + _i * 8192), 16, 0, 0); } while (0)
; #define PG8_LDA(dst, b, h) do { _Pragma("unroll") for (int m = 0; m < 4; ++m) _Pragma("unroll") for (int k = 0; k < 2; ++k) dst[m][k] = *(const LAS bf16x8*)(lds + PG8_SA(b, h) + aoff + m * 2048 + k * 1024); } while (0)
; #define PG8_LDB(dst, b, h) do { _Pragma("unroll") for (int n = 0; n < 2; ++n) _Pragma("unroll") for (int k = 0; k < 2; ++k) dst[n][k] = *(const LAS bf16x8*)(lds + PG8_SB(b, h) + boff + n * 2048 + k * 1024); } while (0)
; #define PG8_MMA(ai, bj, At, Bt) do { __builtin_amdgcn_s_setprio(1); _Pragma("unroll") for (int m = 0; m < 4; ++m) _Pragma("unroll") for (int n = 0; n < 2; ++n) _Pragma("unroll") for (int k = 0; k < 2; ++k) \
;         acc[ai][bj][m][n] = __builtin_amdgcn_mfma_f32_16x16x32_bf16(Bt[n][k], At[m][k], acc[ai][bj][m][n], 0, 0, 0); __builtin_amdgcn_s_setprio(0); } while (0)
; #define PG8_WAIT_V(n) asm volatile("s_waitcnt vmcnt(" #n ")" ::: "memory")
; #define PG8_WAIT_L(n) asm volatile("s_waitcnt lgkmcnt(" #n ")" ::: "memory")
; #define PG8_BAR __builtin_amdgcn_s_barrier()
; #define PG8_SCHED __builtin_amdgcn_sched_barrier(0)
; template <class Epi, class Sched, bool ABLK = false, bool ALIGN_EPI = true, bool SP2 = true, bool BBLK = true>
; __device__ __forceinline__ void gemm_phase(LAS unsigned char* lds, const Gemm g, const Sched& S, const Epi& E) {
;     ...
;             PG8_WAIT_V(8); PG8_WAIT_L(0); PG8_BAR; PG8_MMA(1, 0, At, B0); PG8_MMA(1, 1, At, B1); PG8_BAR; PG8_SCHED;
;             PG8_LDB(B0, 1, 0); PG8_LDB(B1, 1, 1); PG8_SCHED; PG8_LDA(At, 1, 0); PG8_STAGE(PG8_SA(0, 1), a2 + hstepA, voffA);
;             PG8_WAIT_V(8); PG8_WAIT_L(0); PG8_BAR; PG8_MMA(0, 0, At, B0); PG8_MMA(0, 1, At, B1); PG8_BAR; PG8_SCHED;
	v_mfma_f32_16x16x32_bf16 v[62:65], v[152:155], v[184:187], 0
	v_mfma_f32_16x16x32_bf16 v[58:61], v[160:163], v[184:187], 0
	v_mfma_f32_16x16x32_bf16 v[46:49], v[152:155], v[192:195], 0
	v_mfma_f32_16x16x32_bf16 v[42:45], v[160:163], v[192:195], 0
	v_mfma_f32_16x16x32_bf16 v[30:33], v[152:155], v[200:203], 0
	v_mfma_f32_16x16x32_bf16 v[26:29], v[160:163], v[200:203], 0
	v_mfma_f32_16x16x32_bf16 v[14:17], v[152:155], v[208:211], 0
	v_mfma_f32_16x16x32_bf16 v[10:13], v[160:163], v[208:211], 0
	v_mfma_f32_16x16x32_bf16 v[62:65], v[156:159], v[188:191], v[62:65]
	v_mfma_f32_16x16x32_bf16 v[58:61], v[164:167], v[188:191], v[58:61]
	v_mfma_f32_16x16x32_bf16 v[46:49], v[156:159], v[196:199], v[46:49]
	v_mfma_f32_16x16x32_bf16 v[42:45], v[164:167], v[196:199], v[42:45]
	v_mfma_f32_16x16x32_bf16 v[30:33], v[156:159], v[204:207], v[30:33]
	v_mfma_f32_16x16x32_bf16 v[26:29], v[164:167], v[204:207], v[26:29]
	v_mfma_f32_16x16x32_bf16 v[14:17], v[156:159], v[212:215], v[14:17]
	v_mfma_f32_16x16x32_bf16 v[10:13], v[164:167], v[212:215], v[10:13]
	v_mfma_f32_16x16x32_bf16 v[54:57], v[168:171], v[184:187], 0
	v_mfma_f32_16x16x32_bf16 v[50:53], v[176:179], v[184:187], 0
	v_mfma_f32_16x16x32_bf16 v[38:41], v[168:171], v[192:195], 0
	v_mfma_f32_16x16x32_bf16 v[34:37], v[176:179], v[192:195], 0
	v_mfma_f32_16x16x32_bf16 v[22:25], v[168:171], v[200:203], 0
	v_mfma_f32_16x16x32_bf16 v[18:21], v[176:179], v[200:203], 0
	v_mfma_f32_16x16x32_bf16 v[6:9], v[168:171], v[208:211], 0
	v_mfma_f32_16x16x32_bf16 v[2:5], v[176:179], v[208:211], 0
	v_mfma_f32_16x16x32_bf16 v[54:57], v[172:175], v[188:191], v[54:57]
	v_mfma_f32_16x16x32_bf16 v[50:53], v[180:183], v[188:191], v[50:53]
	v_mfma_f32_16x16x32_bf16 v[38:41], v[172:175], v[196:199], v[38:41]
	v_mfma_f32_16x16x32_bf16 v[34:37], v[180:183], v[196:199], v[34:37]
	v_mfma_f32_16x16x32_bf16 v[22:25], v[172:175], v[204:207], v[22:25]
	v_mfma_f32_16x16x32_bf16 v[18:21], v[180:183], v[204:207], v[18:21]
	v_mfma_f32_16x16x32_bf16 v[6:9], v[172:175], v[212:215], v[6:9]
	v_mfma_f32_16x16x32_bf16 v[2:5], v[180:183], v[212:215], v[2:5]
	s_barrier
	v_add_u32_e32 v151, s60, v146
	ds_read_b128 v[152:155], v151
	ds_read_b128 v[156:159], v151 offset:1024
	ds_read_b128 v[160:163], v151 offset:2048
	ds_read_b128 v[164:167], v151 offset:3072
	v_add_u32_e32 v151, s61, v146
	ds_read_b128 v[168:171], v151
	ds_read_b128 v[172:175], v151 offset:1024
	ds_read_b128 v[176:179], v151 offset:2048
	ds_read_b128 v[180:183], v151 offset:3072
	s_add_u32 s38, s38, 0x4000
	s_addc_u32 s39, s39, 0
	s_mov_b32 m0, s43
	ds_read_b128 v[184:187], v150 offset:32768
	ds_read_b128 v[188:191], v150 offset:33792
	ds_read_b128 v[192:195], v150 offset:34816
	ds_read_b128 v[196:199], v150 offset:35840
	ds_read_b128 v[200:203], v150 offset:36864
	ds_read_b128 v[204:207], v150 offset:37888
	ds_read_b128 v[208:211], v150 offset:38912
	global_load_lds_dwordx4 v130, s[38:39]
	s_mov_b32 m0, s44
	ds_read_b128 v[212:215], v150 offset:39936
	global_load_lds_dwordx4 v132, s[38:39]
	s_waitcnt vmcnt(8) lgkmcnt(0)
	s_barrier
	v_mfma_f32_16x16x32_bf16 v[126:129], v[152:155], v[184:187], v[126:129]
	v_mfma_f32_16x16x32_bf16 v[122:125], v[160:163], v[184:187], v[122:125]
	v_mfma_f32_16x16x32_bf16 v[110:113], v[152:155], v[192:195], v[110:113]
	v_mfma_f32_16x16x32_bf16 v[106:109], v[160:163], v[192:195], v[106:109]
	v_mfma_f32_16x16x32_bf16 v[94:97], v[152:155], v[200:203], v[94:97]
	v_mfma_f32_16x16x32_bf16 v[90:93], v[160:163], v[200:203], v[90:93]
	v_mfma_f32_16x16x32_bf16 v[78:81], v[152:155], v[208:211], v[78:81]
	v_mfma_f32_16x16x32_bf16 v[74:77], v[160:163], v[208:211], v[74:77]
	v_mfma_f32_16x16x32_bf16 v[126:129], v[156:159], v[188:191], v[126:129]
	v_mfma_f32_16x16x32_bf16 v[122:125], v[164:167], v[188:191], v[122:125]
	v_mfma_f32_16x16x32_bf16 v[110:113], v[156:159], v[196:199], v[110:113]
	v_mfma_f32_16x16x32_bf16 v[106:109], v[164:167], v[196:199], v[106:109]
	v_mfma_f32_16x16x32_bf16 v[94:97], v[156:159], v[204:207], v[94:97]
	v_mfma_f32_16x16x32_bf16 v[90:93], v[164:167], v[204:207], v[90:93]
	v_mfma_f32_16x16x32_bf16 v[78:81], v[156:159], v[212:215], v[78:81]
	v_mfma_f32_16x16x32_bf16 v[74:77], v[164:167], v[212:215], v[74:77]
	v_mfma_f32_16x16x32_bf16 v[118:121], v[168:171], v[184:187], v[118:121]
	v_mfma_f32_16x16x32_bf16 v[114:117], v[176:179], v[184:187], v[114:117]
	v_mfma_f32_16x16x32_bf16 v[102:105], v[168:171], v[192:195], v[102:105]
	v_mfma_f32_16x16x32_bf16 v[98:101], v[176:179], v[192:195], v[98:101]
	v_mfma_f32_16x16x32_bf16 v[86:89], v[168:171], v[200:203], v[86:89]
	v_mfma_f32_16x16x32_bf16 v[82:85], v[176:179], v[200:203], v[82:85]
	v_mfma_f32_16x16x32_bf16 v[70:73], v[168:171], v[208:211], v[70:73]
	v_mfma_f32_16x16x32_bf16 v[66:69], v[176:179], v[208:211], v[66:69]
	v_mfma_f32_16x16x32_bf16 v[118:121], v[172:175], v[188:191], v[118:121]
	v_mfma_f32_16x16x32_bf16 v[114:117], v[180:183], v[188:191], v[114:117]
	v_mfma_f32_16x16x32_bf16 v[102:105], v[172:175], v[196:199], v[102:105]
	v_mfma_f32_16x16x32_bf16 v[98:101], v[180:183], v[196:199], v[98:101]
	v_mfma_f32_16x16x32_bf16 v[86:89], v[172:175], v[204:207], v[86:89]
	v_mfma_f32_16x16x32_bf16 v[82:85], v[180:183], v[204:207], v[82:85]
	v_mfma_f32_16x16x32_bf16 v[70:73], v[172:175], v[212:215], v[70:73]
	v_mfma_f32_16x16x32_bf16 v[66:69], v[180:183], v[212:215], v[66:69]
	s_barrier
; #define PG8_STAGE(bufoff, gbase, voff) do { _Pragma("unroll") for (int _i = 0; _i < 2; ++_i) \
;         __builtin_amdgcn_global_load_lds((const unsigned*)((const char*)(gbase) + (voff)[_i]), (LAS unsigned*)(lds + (bufoff) + ldsw + _i * 8192), 16, 0, 0); } while (0)
; #define PG8_LDA(dst, b, h) do { _Pragma("unroll") for (int m = 0; m < 4; ++m) _Pragma("unroll") for (int k = 0; k < 2; ++k) dst[m][k] = *(const LAS bf16x8*)(lds + PG8_SA(b, h) + aoff + m * 2048 + k * 1024); } while (0)
; #define PG8_LDB(dst, b, h) do { _Pragma("unroll") for (int n = 0; n < 2; ++n) _Pragma("unroll") for (int k = 0; k < 2; ++k) dst[n][k] = *(const LAS bf16x8*)(lds + PG8_SB(b, h) + boff + n * 2048 + k * 1024); } while (0)
; #define PG8_MMA(ai, bj, At, Bt) do { __builtin_amdgcn_s_setprio(1); _Pragma("unroll") for (int m = 0; m < 4; ++m) _Pragma("unroll") for (int n = 0; n < 2; ++n) _Pragma("unroll") for (int k = 0; k < 2; ++k) \
;         acc[ai][bj][m][n] = __builtin_amdgcn_mfma_f32_16x16x32_bf16(Bt[n][k], At[m][k], acc[ai][bj][m][n], 0, 0, 0); __builtin_amdgcn_s_setprio(0); } while (0)
; #define PG8_WAIT_V(n) asm volatile("s_waitcnt vmcnt(" #n ")" ::: "memory")
; template <class Epi, class Sched, bool ABLK = false, bool ALIGN_EPI = true, bool SP2 = true, bool BBLK = true>
; __device__ __forceinline__ void gemm_phase(LAS unsigned char* lds, const Gemm g, const Sched& S, const Epi& E) {
;     ...
;         for (int t = 0; t < nt; t += 2) {
;             const bool last = (t == nt - 2);
;             const char* a1 = a_tile(uA, tbA + t + 1);
;             const char* a2 = last ? a_tile(nuA, ntbA) : a_tile(uA, tbA + t + 2); const char* b2 = last ? nB : cB + (size_t)(t + 2) * kstepB;
;             const char* a3 = last ? a_tile(nuA, ntbA + 1) : a_tile(uA, tbA + t + 3); const char* b3 = b2 + kstepB;
;             if (last && has_next) S.a_ready(nxt);
;             if constexpr (SP2) {
;             PG8_LDB(B0, 0, 0); PG8_LDB(B1, 0, 1); PG8_SCHED; PG8_LDA(At, 0, 0); PG8_STAGE(PG8_SA(1, 1), a1 + hstepA, voffA);
;             PG8_WAIT_V(8); PG8_WAIT_L(0); PG8_BAR; PG8_MMA(0, 0, At, B0); PG8_MMA(0, 1, At, B1); PG8_BAR; PG8_SCHED;
;     ...
;             PG8_LDA(At, 1, 1); PG8_STAGE(PG8_SB(1, 0), b3, voffB); PG8_STAGE(PG8_SB(1, 1), b3 + hstepB, voffB); PG8_STAGE(PG8_SA(1, 0), a3, voffA);
;             PG8_WAIT_V(8); PG8_WAIT_L(0); PG8_BAR; PG8_MMA(1, 0, At, B0); PG8_MMA(1, 1, At, B1); PG8_BAR; PG8_SCHED;
	s_add_u32 s38, s36, 0x8000
	s_addc_u32 s39, s37, 0
	s_add_i32 s59, s60, s40
	s_mov_b32 m0, s59
	ds_read_b128 v[184:187], v150 offset:49152
	ds_read_b128 v[188:191], v150 offset:50176
	ds_read_b128 v[192:195], v150 offset:51200
	ds_read_b128 v[196:199], v150 offset:52224
	global_load_lds_dwordx4 v130, s[38:39]
	s_add_i32 m0, s59, 0x2000
	s_add_u32 s36, s36, 0xc000
	v_lshl_add_u64 v[216:217], s[38:39], 0, v[132:133]
	s_addc_u32 s37, s37, 0
	s_add_i32 s38, s61, s40
	global_load_lds_dwordx4 v[216:217], off
	s_mov_b32 m0, s38
	ds_read_b128 v[200:203], v150 offset:53248
	global_load_lds_dwordx4 v130, s[36:37]
	s_add_i32 m0, s38, 0x2000
	ds_read_b128 v[204:207], v150 offset:54272
	global_load_lds_dwordx4 v132, s[36:37]
	s_mov_b32 m0, s45
	ds_read_b128 v[208:211], v150 offset:55296
	global_load_lds_dwordx4 v130, s[34:35]
	s_mov_b32 m0, s46
	ds_read_b128 v[212:215], v150 offset:56320
	global_load_lds_dwordx4 v132, s[34:35]
	s_waitcnt vmcnt(8) lgkmcnt(0)
	s_barrier
	v_mfma_f32_16x16x32_bf16 v[62:65], v[152:155], v[184:187], v[62:65]
	v_mfma_f32_16x16x32_bf16 v[58:61], v[160:163], v[184:187], v[58:61]
	v_mfma_f32_16x16x32_bf16 v[46:49], v[152:155], v[192:195], v[46:49]
	v_mfma_f32_16x16x32_bf16 v[42:45], v[160:163], v[192:195], v[42:45]
	v_mfma_f32_16x16x32_bf16 v[30:33], v[152:155], v[200:203], v[30:33]
	v_mfma_f32_16x16x32_bf16 v[26:29], v[160:163], v[200:203], v[26:29]
	v_mfma_f32_16x16x32_bf16 v[14:17], v[152:155], v[208:211], v[14:17]
	v_mfma_f32_16x16x32_bf16 v[10:13], v[160:163], v[208:211], v[10:13]
	v_mfma_f32_16x16x32_bf16 v[62:65], v[156:159], v[188:191], v[62:65]
	v_mfma_f32_16x16x32_bf16 v[58:61], v[164:167], v[188:191], v[58:61]
	v_mfma_f32_16x16x32_bf16 v[46:49], v[156:159], v[196:199], v[46:49]
	v_mfma_f32_16x16x32_bf16 v[42:45], v[164:167], v[196:199], v[42:45]
	v_mfma_f32_16x16x32_bf16 v[30:33], v[156:159], v[204:207], v[30:33]
	v_mfma_f32_16x16x32_bf16 v[26:29], v[164:167], v[204:207], v[26:29]
	v_mfma_f32_16x16x32_bf16 v[14:17], v[156:159], v[212:215], v[14:17]
	v_mfma_f32_16x16x32_bf16 v[10:13], v[164:167], v[212:215], v[10:13]
	v_mfma_f32_16x16x32_bf16 v[54:57], v[168:171], v[184:187], v[54:57]
	v_mfma_f32_16x16x32_bf16 v[50:53], v[176:179], v[184:187], v[50:53]
	v_mfma_f32_16x16x32_bf16 v[38:41], v[168:171], v[192:195], v[38:41]
	v_mfma_f32_16x16x32_bf16 v[34:37], v[176:179], v[192:195], v[34:37]
	v_mfma_f32_16x16x32_bf16 v[22:25], v[168:171], v[200:203], v[22:25]
	v_mfma_f32_16x16x32_bf16 v[18:21], v[176:179], v[200:203], v[18:21]
	v_mfma_f32_16x16x32_bf16 v[6:9], v[168:171], v[208:211], v[6:9]
	v_mfma_f32_16x16x32_bf16 v[2:5], v[176:179], v[208:211], v[2:5]
	v_mfma_f32_16x16x32_bf16 v[54:57], v[172:175], v[188:191], v[54:57]
	v_mfma_f32_16x16x32_bf16 v[50:53], v[180:183], v[188:191], v[50:53]
	v_mfma_f32_16x16x32_bf16 v[38:41], v[172:175], v[196:199], v[38:41]
	v_mfma_f32_16x16x32_bf16 v[34:37], v[180:183], v[196:199], v[34:37]
	v_mfma_f32_16x16x32_bf16 v[22:25], v[172:175], v[204:207], v[22:25]
	v_mfma_f32_16x16x32_bf16 v[18:21], v[180:183], v[204:207], v[18:21]
	v_mfma_f32_16x16x32_bf16 v[6:9], v[172:175], v[212:215], v[6:9]
	v_mfma_f32_16x16x32_bf16 v[2:5], v[180:183], v[212:215], v[2:5]
	s_barrier
	s_add_u32 s30, s30, 0x10000
	s_addc_u32 s31, s31, 0
	s_cmp_ge_u32 s58, s48
.LBB0_1907:
	ds_read_b128 v[152:155], v148
	ds_read_b128 v[156:159], v148 offset:1024
	ds_read_b128 v[160:163], v148 offset:2048
	ds_read_b128 v[164:167], v148 offset:3072
	ds_read_b128 v[168:171], v149
	ds_read_b128 v[172:175], v149 offset:1024
	ds_read_b128 v[176:179], v149 offset:2048
	ds_read_b128 v[180:183], v149 offset:3072
	s_add_u32 s34, s55, s30
	s_addc_u32 s35, s56, s31
	s_add_u32 s38, s34, 0x10000
	s_addc_u32 s39, s35, 0
	s_add_i32 s58, s58, 2
	s_add_u32 s36, s53, s30
	s_addc_u32 s37, s54, s31
	s_add_u32 s34, s34, 0x18000
	s_addc_u32 s35, s35, 0
	s_cmp_eq_u32 s57, s30
	s_cselect_b32 s35, s52, s35
	s_cselect_b32 s34, s51, s34
	s_cselect_b32 s37, s4, s37
	s_cselect_b32 s36, s5, s36
	s_cselect_b32 s39, s50, s39
	s_cselect_b32 s38, s27, s38
	v_lshl_add_u64 v[216:217], v[142:143], 0, s[30:31]
	s_add_i32 m0, s41, 0xc000
	ds_read_b128 v[184:187], v150
	ds_read_b128 v[188:191], v150 offset:1024
	ds_read_b128 v[192:195], v150 offset:2048
	ds_read_b128 v[196:199], v150 offset:3072
	ds_read_b128 v[200:203], v150 offset:4096
	ds_read_b128 v[204:207], v150 offset:5120
	ds_read_b128 v[208:211], v150 offset:6144
	global_load_lds_dwordx4 v[216:217], off
	v_lshl_add_u64 v[216:217], v[144:145], 0, s[30:31]
	s_add_i32 m0, s41, 0xe000
	ds_read_b128 v[212:215], v150 offset:7168
	global_load_lds_dwordx4 v[216:217], off
	s_waitcnt vmcnt(8) lgkmcnt(0)
	s_barrier
; #define PG8_STAGE(bufoff, gbase, voff) do { _Pragma("unroll") for (int _i = 0; _i < 2; ++_i) \
;         __builtin_amdgcn_global_load_lds((const unsigned*)((const char*)(gbase) + (voff)[_i]), (LAS unsigned*)(lds + (bufoff) + ldsw + _i * 8192), 16, 0, 0); } while (0)
; #define PG8_LDA(dst, b, h) do { _Pragma("unroll") for (int m = 0; m < 4; ++m) _Pragma("unroll") for (int k = 0; k < 2; ++k) dst[m][k] = *(const LAS bf16x8*)(lds + PG8_SA(b, h) + aoff + m * 2048 + k * 1024); } while (0)
; #define PG8_MMA(ai, bj, At, Bt) do { __builtin_amdgcn_s_setprio(1); _Pragma("unroll") for (int m = 0; m < 4; ++m) _Pragma("unroll") for (int n = 0; n < 2; ++n) _Pragma("unroll") for (int k = 0; k < 2; ++k) \
;         acc[ai][bj][m][n] = __builtin_amdgcn_mfma_f32_16x16x32_bf16(Bt[n][k], At[m][k], acc[ai][bj][m][n], 0, 0, 0); __builtin_amdgcn_s_setprio(0); } while (0)
; #define PG8_WAIT_V(n) asm volatile("s_waitcnt vmcnt(" #n ")" ::: "memory")
; #define PG8_WAIT_L(n) asm volatile("s_waitcnt lgkmcnt(" #n ")" ::: "memory")
; #define PG8_BAR __builtin_amdgcn_s_barrier()
; #define PG8_SCHED __builtin_amdgcn_sched_barrier(0)
; template <class Epi, class Sched, bool ABLK = false, bool ALIGN_EPI = true, bool SP2 = true, bool BBLK = true>
; __device__ __forceinline__ void gemm_phase(LAS unsigned char* lds, const Gemm g, const Sched& S, const Epi& E) {
;     ...
;             PG8_WAIT_V(8); PG8_WAIT_L(0); PG8_BAR; PG8_MMA(0, 0, At, B0); PG8_MMA(0, 1, At, B1); PG8_BAR; PG8_SCHED;
;             PG8_LDA(At, 0, 1); PG8_STAGE(PG8_SB(0, 0), b2, voffB); PG8_STAGE(PG8_SB(0, 1), b2 + hstepB, voffB); PG8_STAGE(PG8_SA(0, 0), a2, voffA);
;             PG8_WAIT_V(8); PG8_WAIT_L(0); PG8_BAR; PG8_MMA(1, 0, At, B0); PG8_MMA(1, 1, At, B1); PG8_BAR; PG8_SCHED;
	v_mfma_f32_16x16x32_bf16 v[126:129], v[152:155], v[184:187], v[126:129]
	v_mfma_f32_16x16x32_bf16 v[122:125], v[160:163], v[184:187], v[122:125]
	v_mfma_f32_16x16x32_bf16 v[110:113], v[152:155], v[192:195], v[110:113]
	v_mfma_f32_16x16x32_bf16 v[106:109], v[160:163], v[192:195], v[106:109]
	v_mfma_f32_16x16x32_bf16 v[94:97], v[152:155], v[200:203], v[94:97]
	v_mfma_f32_16x16x32_bf16 v[90:93], v[160:163], v[200:203], v[90:93]
	v_mfma_f32_16x16x32_bf16 v[78:81], v[152:155], v[208:211], v[78:81]
	v_mfma_f32_16x16x32_bf16 v[74:77], v[160:163], v[208:211], v[74:77]
	v_mfma_f32_16x16x32_bf16 v[126:129], v[156:159], v[188:191], v[126:129]
	v_mfma_f32_16x16x32_bf16 v[122:125], v[164:167], v[188:191], v[122:125]
	v_mfma_f32_16x16x32_bf16 v[110:113], v[156:159], v[196:199], v[110:113]
	v_mfma_f32_16x16x32_bf16 v[106:109], v[164:167], v[196:199], v[106:109]
	v_mfma_f32_16x16x32_bf16 v[94:97], v[156:159], v[204:207], v[94:97]
	v_mfma_f32_16x16x32_bf16 v[90:93], v[164:167], v[204:207], v[90:93]
	v_mfma_f32_16x16x32_bf16 v[78:81], v[156:159], v[212:215], v[78:81]
	v_mfma_f32_16x16x32_bf16 v[74:77], v[164:167], v[212:215], v[74:77]
	v_mfma_f32_16x16x32_bf16 v[118:121], v[168:171], v[184:187], v[118:121]
	v_mfma_f32_16x16x32_bf16 v[114:117], v[176:179], v[184:187], v[114:117]
	v_mfma_f32_16x16x32_bf16 v[102:105], v[168:171], v[192:195], v[102:105]
	v_mfma_f32_16x16x32_bf16 v[98:101], v[176:179], v[192:195], v[98:101]
	v_mfma_f32_16x16x32_bf16 v[86:89], v[168:171], v[200:203], v[86:89]
	v_mfma_f32_16x16x32_bf16 v[82:85], v[176:179], v[200:203], v[82:85]
	v_mfma_f32_16x16x32_bf16 v[70:73], v[168:171], v[208:211], v[70:73]
	v_mfma_f32_16x16x32_bf16 v[66:69], v[176:179], v[208:211], v[66:69]
	v_mfma_f32_16x16x32_bf16 v[118:121], v[172:175], v[188:191], v[118:121]
	v_mfma_f32_16x16x32_bf16 v[114:117], v[180:183], v[188:191], v[114:117]
	v_mfma_f32_16x16x32_bf16 v[102:105], v[172:175], v[196:199], v[102:105]
	v_mfma_f32_16x16x32_bf16 v[98:101], v[180:183], v[196:199], v[98:101]
	v_mfma_f32_16x16x32_bf16 v[86:89], v[172:175], v[204:207], v[86:89]
	v_mfma_f32_16x16x32_bf16 v[82:85], v[180:183], v[204:207], v[82:85]
	v_mfma_f32_16x16x32_bf16 v[70:73], v[172:175], v[212:215], v[70:73]
	v_mfma_f32_16x16x32_bf16 v[66:69], v[180:183], v[212:215], v[66:69]
	s_barrier
	s_add_i32 s59, s72, s40
	s_mov_b32 m0, s59
	ds_read_b128 v[184:187], v150 offset:16384
	ds_read_b128 v[188:191], v150 offset:17408
	ds_read_b128 v[192:195], v150 offset:18432
	ds_read_b128 v[196:199], v150 offset:19456
	global_load_lds_dwordx4 v130, s[36:37]
	s_add_i32 m0, s59, 0x2000
	s_add_u32 s64, s36, 0x4000
	s_addc_u32 s65, s37, 0
	s_add_i32 s59, s73, s40
	global_load_lds_dwordx4 v132, s[36:37]
	s_mov_b32 m0, s59
	ds_read_b128 v[200:203], v150 offset:20480
	global_load_lds_dwordx4 v130, s[64:65]
	s_add_i32 m0, s59, 0x2000
	ds_read_b128 v[204:207], v150 offset:21504
	global_load_lds_dwordx4 v132, s[64:65]
	s_mov_b32 m0, s41
	ds_read_b128 v[208:211], v150 offset:22528
	global_load_lds_dwordx4 v130, s[38:39]
	s_mov_b32 m0, s42
	ds_read_b128 v[212:215], v150 offset:23552
	global_load_lds_dwordx4 v132, s[38:39]
	s_waitcnt vmcnt(8) lgkmcnt(0)
	s_barrier
	v_mfma_f32_16x16x32_bf16 v[62:65], v[152:155], v[184:187], v[62:65]
	v_mfma_f32_16x16x32_bf16 v[58:61], v[160:163], v[184:187], v[58:61]
	v_mfma_f32_16x16x32_bf16 v[46:49], v[152:155], v[192:195], v[46:49]
	v_mfma_f32_16x16x32_bf16 v[42:45], v[160:163], v[192:195], v[42:45]
	v_mfma_f32_16x16x32_bf16 v[30:33], v[152:155], v[200:203], v[30:33]
	v_mfma_f32_16x16x32_bf16 v[26:29], v[160:163], v[200:203], v[26:29]
	v_mfma_f32_16x16x32_bf16 v[14:17], v[152:155], v[208:211], v[14:17]
	v_mfma_f32_16x16x32_bf16 v[10:13], v[160:163], v[208:211], v[10:13]
	v_mfma_f32_16x16x32_bf16 v[62:65], v[156:159], v[188:191], v[62:65]
	v_mfma_f32_16x16x32_bf16 v[58:61], v[164:167], v[188:191], v[58:61]
	v_mfma_f32_16x16x32_bf16 v[46:49], v[156:159], v[196:199], v[46:49]
	v_mfma_f32_16x16x32_bf16 v[42:45], v[164:167], v[196:199], v[42:45]
	v_mfma_f32_16x16x32_bf16 v[30:33], v[156:159], v[204:207], v[30:33]
	v_mfma_f32_16x16x32_bf16 v[26:29], v[164:167], v[204:207], v[26:29]
	v_mfma_f32_16x16x32_bf16 v[14:17], v[156:159], v[212:215], v[14:17]
	v_mfma_f32_16x16x32_bf16 v[10:13], v[164:167], v[212:215], v[10:13]
	v_mfma_f32_16x16x32_bf16 v[54:57], v[168:171], v[184:187], v[54:57]
	v_mfma_f32_16x16x32_bf16 v[50:53], v[176:179], v[184:187], v[50:53]
	v_mfma_f32_16x16x32_bf16 v[38:41], v[168:171], v[192:195], v[38:41]
	v_mfma_f32_16x16x32_bf16 v[34:37], v[176:179], v[192:195], v[34:37]
	v_mfma_f32_16x16x32_bf16 v[22:25], v[168:171], v[200:203], v[22:25]
	v_mfma_f32_16x16x32_bf16 v[18:21], v[176:179], v[200:203], v[18:21]
	v_mfma_f32_16x16x32_bf16 v[6:9], v[168:171], v[208:211], v[6:9]
	v_mfma_f32_16x16x32_bf16 v[2:5], v[176:179], v[208:211], v[2:5]
	v_mfma_f32_16x16x32_bf16 v[54:57], v[172:175], v[188:191], v[54:57]
	v_mfma_f32_16x16x32_bf16 v[50:53], v[180:183], v[188:191], v[50:53]
	v_mfma_f32_16x16x32_bf16 v[38:41], v[172:175], v[196:199], v[38:41]
	v_mfma_f32_16x16x32_bf16 v[34:37], v[180:183], v[196:199], v[34:37]
	v_mfma_f32_16x16x32_bf16 v[22:25], v[172:175], v[204:207], v[22:25]
	v_mfma_f32_16x16x32_bf16 v[18:21], v[180:183], v[204:207], v[18:21]
	v_mfma_f32_16x16x32_bf16 v[6:9], v[172:175], v[212:215], v[6:9]
	v_mfma_f32_16x16x32_bf16 v[2:5], v[180:183], v[212:215], v[2:5]
	s_barrier
; #define PG8_STAGE(bufoff, gbase, voff) do { _Pragma("unroll") for (int _i = 0; _i < 2; ++_i) \
;         __builtin_amdgcn_global_load_lds((const unsigned*)((const char*)(gbase) + (voff)[_i]), (LAS unsigned*)(lds + (bufoff) + ldsw + _i * 8192), 16, 0, 0); } while (0)
; #define PG8_LDA(dst, b, h) do { _Pragma("unroll") for (int m = 0; m < 4; ++m) _Pragma("unroll") for (int k = 0; k < 2; ++k) dst[m][k] = *(const LAS bf16x8*)(lds + PG8_SA(b, h) + aoff + m * 2048 + k * 1024); } while (0)
; #define PG8_LDB(dst, b, h) do { _Pragma("unroll") for (int n = 0; n < 2; ++n) _Pragma("unroll") for (int k = 0; k < 2; ++k) dst[n][k] = *(const LAS bf16x8*)(lds + PG8_SB(b, h) + boff + n * 2048 + k * 1024); } while (0)
; #define PG8_MMA(ai, bj, At, Bt) do { __builtin_amdgcn_s_setprio(1); _Pragma("unroll") for (int m = 0; m < 4; ++m) _Pragma("unroll") for (int n = 0; n < 2; ++n) _Pragma("unroll") for (int k = 0; k < 2; ++k) \
;         acc[ai][bj][m][n] = __builtin_amdgcn_mfma_f32_16x16x32_bf16(Bt[n][k], At[m][k], acc[ai][bj][m][n], 0, 0, 0); __builtin_amdgcn_s_setprio(0); } while (0)
; #define PG8_WAIT_V(n) asm volatile("s_waitcnt vmcnt(" #n ")" ::: "memory")
; #define PG8_WAIT_L(n) asm volatile("s_waitcnt lgkmcnt(" #n ")" ::: "memory")
; #define PG8_BAR __builtin_amdgcn_s_barrier()
; #define PG8_SCHED __builtin_amdgcn_sched_barrier(0)
; template <class Epi, class Sched, bool ABLK = false, bool ALIGN_EPI = true, bool SP2 = true, bool BBLK = true>
; __device__ __forceinline__ void gemm_phase(LAS unsigned char* lds, const Gemm g, const Sched& S, const Epi& E) {
;     ...
;             PG8_LDB(B0, 1, 0); PG8_LDB(B1, 1, 1); PG8_SCHED; PG8_LDA(At, 1, 0); PG8_STAGE(PG8_SA(0, 1), a2 + hstepA, voffA);
;             PG8_WAIT_V(8); PG8_WAIT_L(0); PG8_BAR; PG8_MMA(0, 0, At, B0); PG8_MMA(0, 1, At, B1); PG8_BAR; PG8_SCHED;
;             PG8_LDA(At, 1, 1); PG8_STAGE(PG8_SB(1, 0), b3, voffB); PG8_STAGE(PG8_SB(1, 1), b3 + hstepB, voffB); PG8_STAGE(PG8_SA(1, 0), a3, voffA);
;             PG8_WAIT_V(8); PG8_WAIT_L(0); PG8_BAR; PG8_MMA(1, 0, At, B0); PG8_MMA(1, 1, At, B1); PG8_BAR; PG8_SCHED;
;     ...
;         }
;         if constexpr (ALIGN_EPI) { if (wr == 0) PG8_BAR; }
	v_add_u32_e32 v151, s60, v146
	ds_read_b128 v[152:155], v151
	ds_read_b128 v[156:159], v151 offset:1024
	ds_read_b128 v[160:163], v151 offset:2048
	ds_read_b128 v[164:167], v151 offset:3072
	v_add_u32_e32 v151, s61, v146
	ds_read_b128 v[168:171], v151
	ds_read_b128 v[172:175], v151 offset:1024
	ds_read_b128 v[176:179], v151 offset:2048
	ds_read_b128 v[180:183], v151 offset:3072
	s_add_u32 s38, s38, 0x4000
	s_addc_u32 s39, s39, 0
	s_mov_b32 m0, s43
	ds_read_b128 v[184:187], v150 offset:32768
	ds_read_b128 v[188:191], v150 offset:33792
	ds_read_b128 v[192:195], v150 offset:34816
	ds_read_b128 v[196:199], v150 offset:35840
	ds_read_b128 v[200:203], v150 offset:36864
	ds_read_b128 v[204:207], v150 offset:37888
	ds_read_b128 v[208:211], v150 offset:38912
	global_load_lds_dwordx4 v130, s[38:39]
	s_mov_b32 m0, s44
	ds_read_b128 v[212:215], v150 offset:39936
	global_load_lds_dwordx4 v132, s[38:39]
	s_waitcnt vmcnt(8) lgkmcnt(0)
	s_barrier
	v_mfma_f32_16x16x32_bf16 v[126:129], v[152:155], v[184:187], v[126:129]
	v_mfma_f32_16x16x32_bf16 v[122:125], v[160:163], v[184:187], v[122:125]
	v_mfma_f32_16x16x32_bf16 v[110:113], v[152:155], v[192:195], v[110:113]
	v_mfma_f32_16x16x32_bf16 v[106:109], v[160:163], v[192:195], v[106:109]
	v_mfma_f32_16x16x32_bf16 v[94:97], v[152:155], v[200:203], v[94:97]
	v_mfma_f32_16x16x32_bf16 v[90:93], v[160:163], v[200:203], v[90:93]
	v_mfma_f32_16x16x32_bf16 v[78:81], v[152:155], v[208:211], v[78:81]
	v_mfma_f32_16x16x32_bf16 v[74:77], v[160:163], v[208:211], v[74:77]
	v_mfma_f32_16x16x32_bf16 v[126:129], v[156:159], v[188:191], v[126:129]
	v_mfma_f32_16x16x32_bf16 v[122:125], v[164:167], v[188:191], v[122:125]
	v_mfma_f32_16x16x32_bf16 v[110:113], v[156:159], v[196:199], v[110:113]
	v_mfma_f32_16x16x32_bf16 v[106:109], v[164:167], v[196:199], v[106:109]
	v_mfma_f32_16x16x32_bf16 v[94:97], v[156:159], v[204:207], v[94:97]
	v_mfma_f32_16x16x32_bf16 v[90:93], v[164:167], v[204:207], v[90:93]
	v_mfma_f32_16x16x32_bf16 v[78:81], v[156:159], v[212:215], v[78:81]
	v_mfma_f32_16x16x32_bf16 v[74:77], v[164:167], v[212:215], v[74:77]
	v_mfma_f32_16x16x32_bf16 v[118:121], v[168:171], v[184:187], v[118:121]
	v_mfma_f32_16x16x32_bf16 v[114:117], v[176:179], v[184:187], v[114:117]
	v_mfma_f32_16x16x32_bf16 v[102:105], v[168:171], v[192:195], v[102:105]
	v_mfma_f32_16x16x32_bf16 v[98:101], v[176:179], v[192:195], v[98:101]
	v_mfma_f32_16x16x32_bf16 v[86:89], v[168:171], v[200:203], v[86:89]
	v_mfma_f32_16x16x32_bf16 v[82:85], v[176:179], v[200:203], v[82:85]
	v_mfma_f32_16x16x32_bf16 v[70:73], v[168:171], v[208:211], v[70:73]
	v_mfma_f32_16x16x32_bf16 v[66:69], v[176:179], v[208:211], v[66:69]
	v_mfma_f32_16x16x32_bf16 v[118:121], v[172:175], v[188:191], v[118:121]
	v_mfma_f32_16x16x32_bf16 v[114:117], v[180:183], v[188:191], v[114:117]
	v_mfma_f32_16x16x32_bf16 v[102:105], v[172:175], v[196:199], v[102:105]
	v_mfma_f32_16x16x32_bf16 v[98:101], v[180:183], v[196:199], v[98:101]
	v_mfma_f32_16x16x32_bf16 v[86:89], v[172:175], v[204:207], v[86:89]
	v_mfma_f32_16x16x32_bf16 v[82:85], v[180:183], v[204:207], v[82:85]
	v_mfma_f32_16x16x32_bf16 v[70:73], v[172:175], v[212:215], v[70:73]
	v_mfma_f32_16x16x32_bf16 v[66:69], v[180:183], v[212:215], v[66:69]
	s_barrier
	s_add_u32 s38, s36, 0x8000
	s_addc_u32 s39, s37, 0
	s_add_i32 s59, s60, s40
	s_mov_b32 m0, s59
	ds_read_b128 v[184:187], v150 offset:49152
	ds_read_b128 v[188:191], v150 offset:50176
	ds_read_b128 v[192:195], v150 offset:51200
	ds_read_b128 v[196:199], v150 offset:52224
	global_load_lds_dwordx4 v130, s[38:39]
	s_add_i32 m0, s59, 0x2000
	s_add_u32 s36, s36, 0xc000
	v_lshl_add_u64 v[216:217], s[38:39], 0, v[132:133]
	s_addc_u32 s37, s37, 0
	s_add_i32 s38, s61, s40
	global_load_lds_dwordx4 v[216:217], off
	s_mov_b32 m0, s38
	ds_read_b128 v[200:203], v150 offset:53248
	global_load_lds_dwordx4 v130, s[36:37]
	s_add_i32 m0, s38, 0x2000
	ds_read_b128 v[204:207], v150 offset:54272
	global_load_lds_dwordx4 v132, s[36:37]
	s_mov_b32 m0, s45
	ds_read_b128 v[208:211], v150 offset:55296
	global_load_lds_dwordx4 v130, s[34:35]
	s_mov_b32 m0, s46
	ds_read_b128 v[212:215], v150 offset:56320
	global_load_lds_dwordx4 v132, s[34:35]
	s_waitcnt vmcnt(8) lgkmcnt(0)
	s_barrier
	v_mfma_f32_16x16x32_bf16 v[62:65], v[152:155], v[184:187], v[62:65]
	v_mfma_f32_16x16x32_bf16 v[58:61], v[160:163], v[184:187], v[58:61]
	v_mfma_f32_16x16x32_bf16 v[46:49], v[152:155], v[192:195], v[46:49]
	v_mfma_f32_16x16x32_bf16 v[42:45], v[160:163], v[192:195], v[42:45]
	v_mfma_f32_16x16x32_bf16 v[30:33], v[152:155], v[200:203], v[30:33]
	v_mfma_f32_16x16x32_bf16 v[26:29], v[160:163], v[200:203], v[26:29]
	v_mfma_f32_16x16x32_bf16 v[14:17], v[152:155], v[208:211], v[14:17]
	v_mfma_f32_16x16x32_bf16 v[10:13], v[160:163], v[208:211], v[10:13]
	v_mfma_f32_16x16x32_bf16 v[62:65], v[156:159], v[188:191], v[62:65]
	v_mfma_f32_16x16x32_bf16 v[58:61], v[164:167], v[188:191], v[58:61]
	v_mfma_f32_16x16x32_bf16 v[46:49], v[156:159], v[196:199], v[46:49]
	v_mfma_f32_16x16x32_bf16 v[42:45], v[164:167], v[196:199], v[42:45]
	v_mfma_f32_16x16x32_bf16 v[30:33], v[156:159], v[204:207], v[30:33]
	v_mfma_f32_16x16x32_bf16 v[26:29], v[164:167], v[204:207], v[26:29]
	v_mfma_f32_16x16x32_bf16 v[14:17], v[156:159], v[212:215], v[14:17]
	v_mfma_f32_16x16x32_bf16 v[10:13], v[164:167], v[212:215], v[10:13]
	v_mfma_f32_16x16x32_bf16 v[54:57], v[168:171], v[184:187], v[54:57]
	v_mfma_f32_16x16x32_bf16 v[50:53], v[176:179], v[184:187], v[50:53]
	v_mfma_f32_16x16x32_bf16 v[38:41], v[168:171], v[192:195], v[38:41]
	v_mfma_f32_16x16x32_bf16 v[34:37], v[176:179], v[192:195], v[34:37]
	v_mfma_f32_16x16x32_bf16 v[22:25], v[168:171], v[200:203], v[22:25]
	v_mfma_f32_16x16x32_bf16 v[18:21], v[176:179], v[200:203], v[18:21]
	v_mfma_f32_16x16x32_bf16 v[6:9], v[168:171], v[208:211], v[6:9]
	v_mfma_f32_16x16x32_bf16 v[2:5], v[176:179], v[208:211], v[2:5]
	v_mfma_f32_16x16x32_bf16 v[54:57], v[172:175], v[188:191], v[54:57]
	v_mfma_f32_16x16x32_bf16 v[50:53], v[180:183], v[188:191], v[50:53]
	v_mfma_f32_16x16x32_bf16 v[38:41], v[172:175], v[196:199], v[38:41]
	v_mfma_f32_16x16x32_bf16 v[34:37], v[180:183], v[196:199], v[34:37]
	v_mfma_f32_16x16x32_bf16 v[22:25], v[172:175], v[204:207], v[22:25]
	v_mfma_f32_16x16x32_bf16 v[18:21], v[180:183], v[204:207], v[18:21]
	v_mfma_f32_16x16x32_bf16 v[6:9], v[172:175], v[212:215], v[6:9]
	v_mfma_f32_16x16x32_bf16 v[2:5], v[180:183], v[212:215], v[2:5]
	s_barrier
	s_add_u32 s30, s30, 0x10000
	s_addc_u32 s31, s31, 0
	s_cmp_ge_u32 s58, s48
	s_cbranch_scc0 .LBB0_1907
	s_and_b64 vcc, exec, s[6:7]
	s_cbranch_vccz .LBB0_1910
	s_barrier

; #define PG8_STAGE(bufoff, gbase, voff) do { _Pragma("unroll") for (int _i = 0; _i < 2; ++_i) \
;         __builtin_amdgcn_global_load_lds((const unsigned*)((const char*)(gbase) + (voff)[_i]), (LAS unsigned*)(lds + (bufoff) + ldsw + _i * 8192), 16, 0, 0); } while (0)
; #define PG8_LDA(dst, b, h) do { _Pragma("unroll") for (int m = 0; m < 4; ++m) _Pragma("unroll") for (int k = 0; k < 2; ++k) dst[m][k] = *(const LAS bf16x8*)(lds + PG8_SA(b, h) + aoff + m * 2048 + k * 1024); } while (0)
; #define PG8_LDB(dst, b, h) do { _Pragma("unroll") for (int n = 0; n < 2; ++n) _Pragma("unroll") for (int k = 0; k < 2; ++k) dst[n][k] = *(const LAS bf16x8*)(lds + PG8_SB(b, h) + boff + n * 2048 + k * 1024); } while (0)
; #define PG8_WAIT_V(n) asm volatile("s_waitcnt vmcnt(" #n ")" ::: "memory")
; #define PG8_WAIT_L(n) asm volatile("s_waitcnt lgkmcnt(" #n ")" ::: "memory")
; #define PG8_BAR __builtin_amdgcn_s_barrier()
; #define PG8_SCHED __builtin_amdgcn_sched_barrier(0)
; template <class Epi, class Sched, bool ABLK = false, bool ALIGN_EPI = true, bool SP2 = true, bool BBLK = true>
; __device__ __forceinline__ void gemm_phase(LAS unsigned char* lds, const Gemm g, const Sched& S, const Epi& E) {
;     ...
;         const bool has_next = S.next(ui + 1, nxt);
;         const int nt = cur.nt;
;         const char* nuA = has_next ? a_unit(nxt) : uA; const int ntbA = has_next ? nxt.k0 / BK : tbA; const char* nB = has_next ? (const char*)g.Bt + (size_t)nxt.pn * tstepB + b_k0(nxt.k0) : cB;
;         for (int t = 0; t < nt; t += 2) {
;             const bool last = (t == nt - 2);
;             const char* a1 = a_tile(uA, tbA + t + 1);
;             const char* a2 = last ? a_tile(nuA, ntbA) : a_tile(uA, tbA + t + 2); const char* b2 = last ? nB : cB + (size_t)(t + 2) * kstepB;
;             const char* a3 = last ? a_tile(nuA, ntbA + 1) : a_tile(uA, tbA + t + 3); const char* b3 = b2 + kstepB;
;             if (last && has_next) S.a_ready(nxt);
;             if constexpr (SP2) {
;             PG8_LDB(B0, 0, 0); PG8_LDB(B1, 0, 1); PG8_SCHED; PG8_LDA(At, 0, 0); PG8_STAGE(PG8_SA(1, 1), a1 + hstepA, voffA);
;             PG8_WAIT_V(8); PG8_WAIT_L(0); PG8_BAR; PG8_MMA(0, 0, At, B0); PG8_MMA(0, 1, At, B1); PG8_BAR; PG8_SCHED;
;             PG8_LDA(At, 0, 1); PG8_STAGE(PG8_SB(0, 0), b2, voffB); PG8_STAGE(PG8_SB(0, 1), b2 + hstepB, voffB); PG8_STAGE(PG8_SA(0, 0), a2, voffA);
.LBB0_2137:
	s_ashr_i32 s11, s10, 31
	s_lshl_b64 s[4:5], s[10:11], 20
	s_add_u32 s14, s37, s4
	s_addc_u32 s15, s38, s5
	s_and_b64 s[4:5], s[16:17], exec
	s_cselect_b32 s4, s15, s25
	s_cselect_b32 s5, s14, s24
	s_ashr_i32 s13, s12, 31
	s_lshl_b64 s[18:19], s[12:13], 20
	s_add_u32 s18, s1, s18
	s_addc_u32 s19, s33, s19
	s_and_b64 s[28:29], s[16:17], exec
	s_cselect_b32 s11, s19, s27
	s_cselect_b32 s13, s18, s26
	s_add_u32 s48, s5, 0x80
	s_addc_u32 s49, s4, 0
	s_add_u32 s50, s26, 0x10000
	v_mov_b32_e32 v2, 0
	s_addc_u32 s51, s27, 0
	v_lshl_add_u64 v[142:143], s[24:25], 0, v[138:139]
	v_lshl_add_u64 v[144:145], s[24:25], 0, v[140:141]
	s_mov_b32 s52, -2
	s_mov_b64 s[26:27], 0
	ds_read_b128 v[152:155], v148
	ds_read_b128 v[156:159], v148 offset:1024
	ds_read_b128 v[160:163], v148 offset:2048
	ds_read_b128 v[164:167], v148 offset:3072
	ds_read_b128 v[168:171], v149
	ds_read_b128 v[172:175], v149 offset:1024
	ds_read_b128 v[176:179], v149 offset:2048
	ds_read_b128 v[180:183], v149 offset:3072
	s_add_u32 s28, s24, s26
	s_addc_u32 s29, s25, s27
	s_add_u32 s34, s28, 0x100
	s_addc_u32 s35, s29, 0
	s_add_u32 s28, s28, 0x180
	s_addc_u32 s29, s29, 0
	s_cmpk_eq_i32 s26, 0xf00
	s_cselect_b32 s29, s49, s29
	s_cselect_b32 s28, s48, s28
	s_cselect_b32 s31, s11, s51
	s_cselect_b32 s30, s13, s50
	s_cselect_b32 s35, s4, s35
	s_cselect_b32 s34, s5, s34
	s_mov_b32 m0, s47
	v_lshl_add_u64 v[216:217], v[142:143], 0, s[26:27]
	ds_read_b128 v[184:187], v150
	ds_read_b128 v[188:191], v150 offset:1024
	ds_read_b128 v[192:195], v150 offset:2048
	ds_read_b128 v[196:199], v150 offset:3072
	ds_read_b128 v[200:203], v150 offset:4096
	ds_read_b128 v[204:207], v150 offset:5120
	ds_read_b128 v[208:211], v150 offset:6144
	global_load_lds_dwordx4 v[216:217], off
	v_lshl_add_u64 v[216:217], v[144:145], 0, s[26:27]
	s_add_i32 m0, s21, 0xe000
	ds_read_b128 v[212:215], v150 offset:7168
	global_load_lds_dwordx4 v[216:217], off
	s_waitcnt vmcnt(8) lgkmcnt(0)
	s_barrier
	v_mfma_f32_16x16x32_bf16 v[122:125], v[152:155], v[184:187], 0
	v_mfma_f32_16x16x32_bf16 v[118:121], v[160:163], v[184:187], 0
	v_mfma_f32_16x16x32_bf16 v[106:109], v[152:155], v[192:195], 0
	v_mfma_f32_16x16x32_bf16 v[102:105], v[160:163], v[192:195], 0
	v_mfma_f32_16x16x32_bf16 v[90:93], v[152:155], v[200:203], 0
	v_mfma_f32_16x16x32_bf16 v[86:89], v[160:163], v[200:203], 0
	v_mfma_f32_16x16x32_bf16 v[74:77], v[152:155], v[208:211], 0
	v_mfma_f32_16x16x32_bf16 v[70:73], v[160:163], v[208:211], 0
	v_mfma_f32_16x16x32_bf16 v[122:125], v[156:159], v[188:191], v[122:125]
	v_mfma_f32_16x16x32_bf16 v[118:121], v[164:167], v[188:191], v[118:121]
	v_mfma_f32_16x16x32_bf16 v[106:109], v[156:159], v[196:199], v[106:109]
	v_mfma_f32_16x16x32_bf16 v[102:105], v[164:167], v[196:199], v[102:105]
	v_mfma_f32_16x16x32_bf16 v[90:93], v[156:159], v[204:207], v[90:93]
	v_mfma_f32_16x16x32_bf16 v[86:89], v[164:167], v[204:207], v[86:89]
	v_mfma_f32_16x16x32_bf16 v[74:77], v[156:159], v[212:215], v[74:77]
	v_mfma_f32_16x16x32_bf16 v[70:73], v[164:167], v[212:215], v[70:73]
	v_mfma_f32_16x16x32_bf16 v[126:129], v[168:171], v[184:187], 0
	v_mfma_f32_16x16x32_bf16 v[114:117], v[176:179], v[184:187], 0
	v_mfma_f32_16x16x32_bf16 v[110:113], v[168:171], v[192:195], 0
	v_mfma_f32_16x16x32_bf16 v[98:101], v[176:179], v[192:195], 0
	v_mfma_f32_16x16x32_bf16 v[94:97], v[168:171], v[200:203], 0
	v_mfma_f32_16x16x32_bf16 v[82:85], v[176:179], v[200:203], 0
	v_mfma_f32_16x16x32_bf16 v[78:81], v[168:171], v[208:211], 0
	v_mfma_f32_16x16x32_bf16 v[66:69], v[176:179], v[208:211], 0
	v_mfma_f32_16x16x32_bf16 v[126:129], v[172:175], v[188:191], v[126:129]
	v_mfma_f32_16x16x32_bf16 v[114:117], v[180:183], v[188:191], v[114:117]
	v_mfma_f32_16x16x32_bf16 v[110:113], v[172:175], v[196:199], v[110:113]
	v_mfma_f32_16x16x32_bf16 v[98:101], v[180:183], v[196:199], v[98:101]
	v_mfma_f32_16x16x32_bf16 v[94:97], v[172:175], v[204:207], v[94:97]
	v_mfma_f32_16x16x32_bf16 v[82:85], v[180:183], v[204:207], v[82:85]
	v_mfma_f32_16x16x32_bf16 v[78:81], v[172:175], v[212:215], v[78:81]
	v_mfma_f32_16x16x32_bf16 v[66:69], v[180:183], v[212:215], v[66:69]
	s_barrier
	s_add_i32 s53, s72, s36
	s_mov_b32 m0, s53
	ds_read_b128 v[184:187], v150 offset:16384
	ds_read_b128 v[188:191], v150 offset:17408
	ds_read_b128 v[192:195], v150 offset:18432
	ds_read_b128 v[196:199], v150 offset:19456
	global_load_lds_dwordx4 v134, s[30:31]
	s_add_i32 m0, s53, 0x2000
	s_add_u32 s54, s30, 0x4000
	s_addc_u32 s55, s31, 0
	s_add_i32 s53, s73, s36
	global_load_lds_dwordx4 v130, s[30:31]
	s_mov_b32 m0, s53
	ds_read_b128 v[200:203], v150 offset:20480
	global_load_lds_dwordx4 v134, s[54:55]
	s_add_i32 m0, s53, 0x2000
	ds_read_b128 v[204:207], v150 offset:21504
	global_load_lds_dwordx4 v130, s[54:55]
	s_mov_b32 m0, s21
	ds_read_b128 v[208:211], v150 offset:22528
	global_load_lds_dwordx4 v136, s[34:35]
	s_mov_b32 m0, s23
	ds_read_b128 v[212:215], v150 offset:23552
	global_load_lds_dwordx4 v132, s[34:35]
	s_waitcnt vmcnt(8) lgkmcnt(0)
	s_barrier
; #define PG8_STAGE(bufoff, gbase, voff) do { _Pragma("unroll") for (int _i = 0; _i < 2; ++_i) \
;         __builtin_amdgcn_global_load_lds((const unsigned*)((const char*)(gbase) + (voff)[_i]), (LAS unsigned*)(lds + (bufoff) + ldsw + _i * 8192), 16, 0, 0); } while (0)
; #define PG8_LDA(dst, b, h) do { _Pragma("unroll") for (int m = 0; m < 4; ++m) _Pragma("unroll") for (int k = 0; k < 2; ++k) dst[m][k] = *(const LAS bf16x8*)(lds + PG8_SA(b, h) + aoff + m * 2048 + k * 1024); } while (0)
; #define PG8_LDB(dst, b, h) do { _Pragma("unroll") for (int n = 0; n < 2; ++n) _Pragma("unroll") for (int k = 0; k < 2; ++k) dst[n][k] = *(const LAS bf16x8*)(lds + PG8_SB(b, h) + boff + n * 2048 + k * 1024); } while (0)
; #define PG8_MMA(ai, bj, At, Bt) do { __builtin_amdgcn_s_setprio(1); _Pragma("unroll") for (int m = 0; m < 4; ++m) _Pragma("unroll") for (int n = 0; n < 2; ++n) _Pragma("unroll") for (int k = 0; k < 2; ++k) \
;         acc[ai][bj][m][n] = __builtin_amdgcn_mfma_f32_16x16x32_bf16(Bt[n][k], At[m][k], acc[ai][bj][m][n], 0, 0, 0); __builtin_amdgcn_s_setprio(0); } while (0)
; #define PG8_WAIT_V(n) asm volatile("s_waitcnt vmcnt(" #n ")" ::: "memory")
; #define PG8_WAIT_L(n) asm volatile("s_waitcnt lgkmcnt(" #n ")" ::: "memory")
; #define PG8_BAR __builtin_amdgcn_s_barrier()
; #define PG8_SCHED __builtin_amdgcn_sched_barrier(0)
; template <class Epi, class Sched, bool ABLK = false, bool ALIGN_EPI = true, bool SP2 = true, bool BBLK = true>
; __device__ __forceinline__ void gemm_phase(LAS unsigned char* lds, const Gemm g, const Sched& S, const Epi& E) {
;     ...
;             PG8_WAIT_V(8); PG8_WAIT_L(0); PG8_BAR; PG8_MMA(1, 0, At, B0); PG8_MMA(1, 1, At, B1); PG8_BAR; PG8_SCHED;
;             PG8_LDB(B0, 1, 0); PG8_LDB(B1, 1, 1); PG8_SCHED; PG8_LDA(At, 1, 0); PG8_STAGE(PG8_SA(0, 1), a2 + hstepA, voffA);
;             PG8_WAIT_V(8); PG8_WAIT_L(0); PG8_BAR; PG8_MMA(0, 0, At, B0); PG8_MMA(0, 1, At, B1); PG8_BAR; PG8_SCHED;
	v_mfma_f32_16x16x32_bf16 v[58:61], v[152:155], v[184:187], 0
	v_mfma_f32_16x16x32_bf16 v[54:57], v[160:163], v[184:187], 0
	v_mfma_f32_16x16x32_bf16 v[42:45], v[152:155], v[192:195], 0
	v_mfma_f32_16x16x32_bf16 v[38:41], v[160:163], v[192:195], 0
	v_mfma_f32_16x16x32_bf16 v[26:29], v[152:155], v[200:203], 0
	v_mfma_f32_16x16x32_bf16 v[22:25], v[160:163], v[200:203], 0
	v_mfma_f32_16x16x32_bf16 v[10:13], v[152:155], v[208:211], 0
	v_mfma_f32_16x16x32_bf16 v[6:9], v[160:163], v[208:211], 0
	v_mfma_f32_16x16x32_bf16 v[58:61], v[156:159], v[188:191], v[58:61]
	v_mfma_f32_16x16x32_bf16 v[54:57], v[164:167], v[188:191], v[54:57]
	v_mfma_f32_16x16x32_bf16 v[42:45], v[156:159], v[196:199], v[42:45]
	v_mfma_f32_16x16x32_bf16 v[38:41], v[164:167], v[196:199], v[38:41]
	v_mfma_f32_16x16x32_bf16 v[26:29], v[156:159], v[204:207], v[26:29]
	v_mfma_f32_16x16x32_bf16 v[22:25], v[164:167], v[204:207], v[22:25]
	v_mfma_f32_16x16x32_bf16 v[10:13], v[156:159], v[212:215], v[10:13]
	v_mfma_f32_16x16x32_bf16 v[6:9], v[164:167], v[212:215], v[6:9]
	v_mfma_f32_16x16x32_bf16 v[62:65], v[168:171], v[184:187], 0
	v_mfma_f32_16x16x32_bf16 v[50:53], v[176:179], v[184:187], 0
	v_mfma_f32_16x16x32_bf16 v[46:49], v[168:171], v[192:195], 0
	v_mfma_f32_16x16x32_bf16 v[34:37], v[176:179], v[192:195], 0
	v_mfma_f32_16x16x32_bf16 v[30:33], v[168:171], v[200:203], 0
	v_mfma_f32_16x16x32_bf16 v[18:21], v[176:179], v[200:203], 0
	v_mfma_f32_16x16x32_bf16 v[14:17], v[168:171], v[208:211], 0
	v_mfma_f32_16x16x32_bf16 v[2:5], v[176:179], v[208:211], 0
	v_mfma_f32_16x16x32_bf16 v[62:65], v[172:175], v[188:191], v[62:65]
	v_mfma_f32_16x16x32_bf16 v[50:53], v[180:183], v[188:191], v[50:53]
	v_mfma_f32_16x16x32_bf16 v[46:49], v[172:175], v[196:199], v[46:49]
	v_mfma_f32_16x16x32_bf16 v[34:37], v[180:183], v[196:199], v[34:37]
	v_mfma_f32_16x16x32_bf16 v[30:33], v[172:175], v[204:207], v[30:33]
	v_mfma_f32_16x16x32_bf16 v[18:21], v[180:183], v[204:207], v[18:21]
	v_mfma_f32_16x16x32_bf16 v[14:17], v[172:175], v[212:215], v[14:17]
	v_mfma_f32_16x16x32_bf16 v[2:5], v[180:183], v[212:215], v[2:5]
	s_barrier
	v_add_u32_e32 v151, s60, v146
	ds_read_b128 v[152:155], v151
	ds_read_b128 v[156:159], v151 offset:1024
	ds_read_b128 v[160:163], v151 offset:2048
	ds_read_b128 v[164:167], v151 offset:3072
	v_add_u32_e32 v151, s61, v146
	ds_read_b128 v[168:171], v151
	ds_read_b128 v[172:175], v151 offset:1024
	ds_read_b128 v[176:179], v151 offset:2048
	ds_read_b128 v[180:183], v151 offset:3072
	s_add_u32 s34, s34, 0x80000
	s_addc_u32 s35, s35, 0
	s_mov_b32 m0, s39
	ds_read_b128 v[184:187], v150 offset:32768
	ds_read_b128 v[188:191], v150 offset:33792
	ds_read_b128 v[192:195], v150 offset:34816
	ds_read_b128 v[196:199], v150 offset:35840
	ds_read_b128 v[200:203], v150 offset:36864
	ds_read_b128 v[204:207], v150 offset:37888
	ds_read_b128 v[208:211], v150 offset:38912
	global_load_lds_dwordx4 v136, s[34:35]
	s_mov_b32 m0, s40
	ds_read_b128 v[212:215], v150 offset:39936
	global_load_lds_dwordx4 v132, s[34:35]
	s_waitcnt vmcnt(8) lgkmcnt(0)
	s_barrier
	v_mfma_f32_16x16x32_bf16 v[122:125], v[152:155], v[184:187], v[122:125]
	v_mfma_f32_16x16x32_bf16 v[118:121], v[160:163], v[184:187], v[118:121]
	v_mfma_f32_16x16x32_bf16 v[106:109], v[152:155], v[192:195], v[106:109]
	v_mfma_f32_16x16x32_bf16 v[102:105], v[160:163], v[192:195], v[102:105]
	v_mfma_f32_16x16x32_bf16 v[90:93], v[152:155], v[200:203], v[90:93]
	v_mfma_f32_16x16x32_bf16 v[86:89], v[160:163], v[200:203], v[86:89]
	v_mfma_f32_16x16x32_bf16 v[74:77], v[152:155], v[208:211], v[74:77]
	v_mfma_f32_16x16x32_bf16 v[70:73], v[160:163], v[208:211], v[70:73]
	v_mfma_f32_16x16x32_bf16 v[122:125], v[156:159], v[188:191], v[122:125]
	v_mfma_f32_16x16x32_bf16 v[118:121], v[164:167], v[188:191], v[118:121]
	v_mfma_f32_16x16x32_bf16 v[106:109], v[156:159], v[196:199], v[106:109]
	v_mfma_f32_16x16x32_bf16 v[102:105], v[164:167], v[196:199], v[102:105]
	v_mfma_f32_16x16x32_bf16 v[90:93], v[156:159], v[204:207], v[90:93]
	v_mfma_f32_16x16x32_bf16 v[86:89], v[164:167], v[204:207], v[86:89]
	v_mfma_f32_16x16x32_bf16 v[74:77], v[156:159], v[212:215], v[74:77]
	v_mfma_f32_16x16x32_bf16 v[70:73], v[164:167], v[212:215], v[70:73]
	v_mfma_f32_16x16x32_bf16 v[126:129], v[168:171], v[184:187], v[126:129]
	v_mfma_f32_16x16x32_bf16 v[114:117], v[176:179], v[184:187], v[114:117]
	v_mfma_f32_16x16x32_bf16 v[110:113], v[168:171], v[192:195], v[110:113]
	v_mfma_f32_16x16x32_bf16 v[98:101], v[176:179], v[192:195], v[98:101]
	v_mfma_f32_16x16x32_bf16 v[94:97], v[168:171], v[200:203], v[94:97]
	v_mfma_f32_16x16x32_bf16 v[82:85], v[176:179], v[200:203], v[82:85]
	v_mfma_f32_16x16x32_bf16 v[78:81], v[168:171], v[208:211], v[78:81]
	v_mfma_f32_16x16x32_bf16 v[66:69], v[176:179], v[208:211], v[66:69]
	v_mfma_f32_16x16x32_bf16 v[126:129], v[172:175], v[188:191], v[126:129]
	v_mfma_f32_16x16x32_bf16 v[114:117], v[180:183], v[188:191], v[114:117]
	v_mfma_f32_16x16x32_bf16 v[110:113], v[172:175], v[196:199], v[110:113]
	v_mfma_f32_16x16x32_bf16 v[98:101], v[180:183], v[196:199], v[98:101]
	v_mfma_f32_16x16x32_bf16 v[94:97], v[172:175], v[204:207], v[94:97]
	v_mfma_f32_16x16x32_bf16 v[82:85], v[180:183], v[204:207], v[82:85]
	v_mfma_f32_16x16x32_bf16 v[78:81], v[172:175], v[212:215], v[78:81]
	v_mfma_f32_16x16x32_bf16 v[66:69], v[180:183], v[212:215], v[66:69]
	s_barrier
; #define PG8_STAGE(bufoff, gbase, voff) do { _Pragma("unroll") for (int _i = 0; _i < 2; ++_i) \
;         __builtin_amdgcn_global_load_lds((const unsigned*)((const char*)(gbase) + (voff)[_i]), (LAS unsigned*)(lds + (bufoff) + ldsw + _i * 8192), 16, 0, 0); } while (0)
; #define PG8_LDA(dst, b, h) do { _Pragma("unroll") for (int m = 0; m < 4; ++m) _Pragma("unroll") for (int k = 0; k < 2; ++k) dst[m][k] = *(const LAS bf16x8*)(lds + PG8_SA(b, h) + aoff + m * 2048 + k * 1024); } while (0)
; #define PG8_WAIT_V(n) asm volatile("s_waitcnt vmcnt(" #n ")" ::: "memory")
; #define PG8_WAIT_L(n) asm volatile("s_waitcnt lgkmcnt(" #n ")" ::: "memory")
; template <class Epi, class Sched, bool ABLK = false, bool ALIGN_EPI = true, bool SP2 = true, bool BBLK = true>
; __device__ __forceinline__ void gemm_phase(LAS unsigned char* lds, const Gemm g, const Sched& S, const Epi& E) {
;     ...
;         for (int t = 0; t < nt; t += 2) {
;             const bool last = (t == nt - 2);
;             const char* a1 = a_tile(uA, tbA + t + 1);
;             const char* a2 = last ? a_tile(nuA, ntbA) : a_tile(uA, tbA + t + 2); const char* b2 = last ? nB : cB + (size_t)(t + 2) * kstepB;
;             const char* a3 = last ? a_tile(nuA, ntbA + 1) : a_tile(uA, tbA + t + 3); const char* b3 = b2 + kstepB;
;             if (last && has_next) S.a_ready(nxt);
;             if constexpr (SP2) {
;             PG8_LDB(B0, 0, 0); PG8_LDB(B1, 0, 1); PG8_SCHED; PG8_LDA(At, 0, 0); PG8_STAGE(PG8_SA(1, 1), a1 + hstepA, voffA);
;             PG8_WAIT_V(8); PG8_WAIT_L(0); PG8_BAR; PG8_MMA(0, 0, At, B0); PG8_MMA(0, 1, At, B1); PG8_BAR; PG8_SCHED;
;             PG8_LDA(At, 0, 1); PG8_STAGE(PG8_SB(0, 0), b2, voffB); PG8_STAGE(PG8_SB(0, 1), b2 + hstepB, voffB); PG8_STAGE(PG8_SA(0, 0), a2, voffA);
;             PG8_WAIT_V(8); PG8_WAIT_L(0); PG8_BAR; PG8_MMA(1, 0, At, B0); PG8_MMA(1, 1, At, B1); PG8_BAR; PG8_SCHED;
;             PG8_LDB(B0, 1, 0); PG8_LDB(B1, 1, 1); PG8_SCHED; PG8_LDA(At, 1, 0); PG8_STAGE(PG8_SA(0, 1), a2 + hstepA, voffA);
;             PG8_WAIT_V(8); PG8_WAIT_L(0); PG8_BAR; PG8_MMA(0, 0, At, B0); PG8_MMA(0, 1, At, B1); PG8_BAR; PG8_SCHED;
;             PG8_LDA(At, 1, 1); PG8_STAGE(PG8_SB(1, 0), b3, voffB); PG8_STAGE(PG8_SB(1, 1), b3 + hstepB, voffB); PG8_STAGE(PG8_SA(1, 0), a3, voffA);
;             PG8_WAIT_V(8); PG8_WAIT_L(0); PG8_BAR; PG8_MMA(1, 0, At, B0); PG8_MMA(1, 1, At, B1); PG8_BAR; PG8_SCHED;
	s_add_u32 s34, s30, 0x8000
	s_addc_u32 s35, s31, 0
	s_add_i32 s53, s60, s36
	s_mov_b32 m0, s53
	ds_read_b128 v[184:187], v150 offset:49152
	ds_read_b128 v[188:191], v150 offset:50176
	ds_read_b128 v[192:195], v150 offset:51200
	ds_read_b128 v[196:199], v150 offset:52224
	global_load_lds_dwordx4 v134, s[34:35]
	s_add_i32 m0, s53, 0x2000
	s_add_u32 s30, s30, 0xc000
	v_lshl_add_u64 v[216:217], s[34:35], 0, v[130:131]
	s_addc_u32 s31, s31, 0
	s_add_i32 s34, s61, s36
	global_load_lds_dwordx4 v[216:217], off
	s_mov_b32 m0, s34
	ds_read_b128 v[200:203], v150 offset:53248
	global_load_lds_dwordx4 v134, s[30:31]
	s_add_i32 m0, s34, 0x2000
	ds_read_b128 v[204:207], v150 offset:54272
	global_load_lds_dwordx4 v130, s[30:31]
	s_mov_b32 m0, s42
	ds_read_b128 v[208:211], v150 offset:55296
	global_load_lds_dwordx4 v136, s[28:29]
	s_mov_b32 m0, s43
	ds_read_b128 v[212:215], v150 offset:56320
	global_load_lds_dwordx4 v132, s[28:29]
	s_waitcnt vmcnt(8) lgkmcnt(0)
	s_barrier
	v_mfma_f32_16x16x32_bf16 v[58:61], v[152:155], v[184:187], v[58:61]
	v_mfma_f32_16x16x32_bf16 v[54:57], v[160:163], v[184:187], v[54:57]
	v_mfma_f32_16x16x32_bf16 v[42:45], v[152:155], v[192:195], v[42:45]
	v_mfma_f32_16x16x32_bf16 v[38:41], v[160:163], v[192:195], v[38:41]
	v_mfma_f32_16x16x32_bf16 v[26:29], v[152:155], v[200:203], v[26:29]
	v_mfma_f32_16x16x32_bf16 v[22:25], v[160:163], v[200:203], v[22:25]
	v_mfma_f32_16x16x32_bf16 v[10:13], v[152:155], v[208:211], v[10:13]
	v_mfma_f32_16x16x32_bf16 v[6:9], v[160:163], v[208:211], v[6:9]
	v_mfma_f32_16x16x32_bf16 v[58:61], v[156:159], v[188:191], v[58:61]
	v_mfma_f32_16x16x32_bf16 v[54:57], v[164:167], v[188:191], v[54:57]
	v_mfma_f32_16x16x32_bf16 v[42:45], v[156:159], v[196:199], v[42:45]
	v_mfma_f32_16x16x32_bf16 v[38:41], v[164:167], v[196:199], v[38:41]
	v_mfma_f32_16x16x32_bf16 v[26:29], v[156:159], v[204:207], v[26:29]
	v_mfma_f32_16x16x32_bf16 v[22:25], v[164:167], v[204:207], v[22:25]
	v_mfma_f32_16x16x32_bf16 v[10:13], v[156:159], v[212:215], v[10:13]
	v_mfma_f32_16x16x32_bf16 v[6:9], v[164:167], v[212:215], v[6:9]
	v_mfma_f32_16x16x32_bf16 v[62:65], v[168:171], v[184:187], v[62:65]
	v_mfma_f32_16x16x32_bf16 v[50:53], v[176:179], v[184:187], v[50:53]
	v_mfma_f32_16x16x32_bf16 v[46:49], v[168:171], v[192:195], v[46:49]
	v_mfma_f32_16x16x32_bf16 v[34:37], v[176:179], v[192:195], v[34:37]
	v_mfma_f32_16x16x32_bf16 v[30:33], v[168:171], v[200:203], v[30:33]
	v_mfma_f32_16x16x32_bf16 v[18:21], v[176:179], v[200:203], v[18:21]
	v_mfma_f32_16x16x32_bf16 v[14:17], v[168:171], v[208:211], v[14:17]
	v_mfma_f32_16x16x32_bf16 v[2:5], v[176:179], v[208:211], v[2:5]
	v_mfma_f32_16x16x32_bf16 v[62:65], v[172:175], v[188:191], v[62:65]
	v_mfma_f32_16x16x32_bf16 v[50:53], v[180:183], v[188:191], v[50:53]
	v_mfma_f32_16x16x32_bf16 v[46:49], v[172:175], v[196:199], v[46:49]
	v_mfma_f32_16x16x32_bf16 v[34:37], v[180:183], v[196:199], v[34:37]
	v_mfma_f32_16x16x32_bf16 v[30:33], v[172:175], v[204:207], v[30:33]
	v_mfma_f32_16x16x32_bf16 v[18:21], v[180:183], v[204:207], v[18:21]
	v_mfma_f32_16x16x32_bf16 v[14:17], v[172:175], v[212:215], v[14:17]
	v_mfma_f32_16x16x32_bf16 v[2:5], v[180:183], v[212:215], v[2:5]
	s_barrier
	s_add_i32 s52, s52, 2
	s_add_u32 s26, s26, 0x100
	s_addc_u32 s27, s27, 0
	s_add_u32 s50, s50, 0x10000
	s_addc_u32 s51, s51, 0
	s_cmp_gt_u32 s52, 29
.LBB0_2138:
	ds_read_b128 v[152:155], v148
	ds_read_b128 v[156:159], v148 offset:1024
	ds_read_b128 v[160:163], v148 offset:2048
	ds_read_b128 v[164:167], v148 offset:3072
	ds_read_b128 v[168:171], v149
	ds_read_b128 v[172:175], v149 offset:1024
	ds_read_b128 v[176:179], v149 offset:2048
	ds_read_b128 v[180:183], v149 offset:3072
	s_add_u32 s28, s24, s26
	s_addc_u32 s29, s25, s27
	s_add_u32 s34, s28, 0x100
	s_addc_u32 s35, s29, 0
	s_add_u32 s28, s28, 0x180
	s_addc_u32 s29, s29, 0
	s_cmpk_eq_i32 s26, 0xf00
	s_cselect_b32 s29, s49, s29
	s_cselect_b32 s28, s48, s28
	s_cselect_b32 s31, s11, s51
	s_cselect_b32 s30, s13, s50
	s_cselect_b32 s35, s4, s35
	s_cselect_b32 s34, s5, s34
	s_mov_b32 m0, s47
	v_lshl_add_u64 v[216:217], v[142:143], 0, s[26:27]
	ds_read_b128 v[184:187], v150
	ds_read_b128 v[188:191], v150 offset:1024
	ds_read_b128 v[192:195], v150 offset:2048
	ds_read_b128 v[196:199], v150 offset:3072
	ds_read_b128 v[200:203], v150 offset:4096
	ds_read_b128 v[204:207], v150 offset:5120
	ds_read_b128 v[208:211], v150 offset:6144
	global_load_lds_dwordx4 v[216:217], off
	v_lshl_add_u64 v[216:217], v[144:145], 0, s[26:27]
	s_add_i32 m0, s21, 0xe000
	ds_read_b128 v[212:215], v150 offset:7168
	global_load_lds_dwordx4 v[216:217], off
	s_waitcnt vmcnt(8) lgkmcnt(0)
	s_barrier
; #define PG8_STAGE(bufoff, gbase, voff) do { _Pragma("unroll") for (int _i = 0; _i < 2; ++_i) \
;         __builtin_amdgcn_global_load_lds((const unsigned*)((const char*)(gbase) + (voff)[_i]), (LAS unsigned*)(lds + (bufoff) + ldsw + _i * 8192), 16, 0, 0); } while (0)
; #define PG8_LDA(dst, b, h) do { _Pragma("unroll") for (int m = 0; m < 4; ++m) _Pragma("unroll") for (int k = 0; k < 2; ++k) dst[m][k] = *(const LAS bf16x8*)(lds + PG8_SA(b, h) + aoff + m * 2048 + k * 1024); } while (0)
; #define PG8_MMA(ai, bj, At, Bt) do { __builtin_amdgcn_s_setprio(1); _Pragma("unroll") for (int m = 0; m < 4; ++m) _Pragma("unroll") for (int n = 0; n < 2; ++n) _Pragma("unroll") for (int k = 0; k < 2; ++k) \
;         acc[ai][bj][m][n] = __builtin_amdgcn_mfma_f32_16x16x32_bf16(Bt[n][k], At[m][k], acc[ai][bj][m][n], 0, 0, 0); __builtin_amdgcn_s_setprio(0); } while (0)
; #define PG8_WAIT_V(n) asm volatile("s_waitcnt vmcnt(" #n ")" ::: "memory")
; #define PG8_WAIT_L(n) asm volatile("s_waitcnt lgkmcnt(" #n ")" ::: "memory")
; #define PG8_BAR __builtin_amdgcn_s_barrier()
; #define PG8_SCHED __builtin_amdgcn_sched_barrier(0)
; template <class Epi, class Sched, bool ABLK = false, bool ALIGN_EPI = true, bool SP2 = true, bool BBLK = true>
; __device__ __forceinline__ void gemm_phase(LAS unsigned char* lds, const Gemm g, const Sched& S, const Epi& E) {
;     ...
;             PG8_WAIT_V(8); PG8_WAIT_L(0); PG8_BAR; PG8_MMA(0, 0, At, B0); PG8_MMA(0, 1, At, B1); PG8_BAR; PG8_SCHED;
;             PG8_LDA(At, 0, 1); PG8_STAGE(PG8_SB(0, 0), b2, voffB); PG8_STAGE(PG8_SB(0, 1), b2 + hstepB, voffB); PG8_STAGE(PG8_SA(0, 0), a2, voffA);
;             PG8_WAIT_V(8); PG8_WAIT_L(0); PG8_BAR; PG8_MMA(1, 0, At, B0); PG8_MMA(1, 1, At, B1); PG8_BAR; PG8_SCHED;
	v_mfma_f32_16x16x32_bf16 v[122:125], v[152:155], v[184:187], v[122:125]
	v_mfma_f32_16x16x32_bf16 v[118:121], v[160:163], v[184:187], v[118:121]
	v_mfma_f32_16x16x32_bf16 v[106:109], v[152:155], v[192:195], v[106:109]
	v_mfma_f32_16x16x32_bf16 v[102:105], v[160:163], v[192:195], v[102:105]
	v_mfma_f32_16x16x32_bf16 v[90:93], v[152:155], v[200:203], v[90:93]
	v_mfma_f32_16x16x32_bf16 v[86:89], v[160:163], v[200:203], v[86:89]
	v_mfma_f32_16x16x32_bf16 v[74:77], v[152:155], v[208:211], v[74:77]
	v_mfma_f32_16x16x32_bf16 v[70:73], v[160:163], v[208:211], v[70:73]
	v_mfma_f32_16x16x32_bf16 v[122:125], v[156:159], v[188:191], v[122:125]
	v_mfma_f32_16x16x32_bf16 v[118:121], v[164:167], v[188:191], v[118:121]
	v_mfma_f32_16x16x32_bf16 v[106:109], v[156:159], v[196:199], v[106:109]
	v_mfma_f32_16x16x32_bf16 v[102:105], v[164:167], v[196:199], v[102:105]
	v_mfma_f32_16x16x32_bf16 v[90:93], v[156:159], v[204:207], v[90:93]
	v_mfma_f32_16x16x32_bf16 v[86:89], v[164:167], v[204:207], v[86:89]
	v_mfma_f32_16x16x32_bf16 v[74:77], v[156:159], v[212:215], v[74:77]
	v_mfma_f32_16x16x32_bf16 v[70:73], v[164:167], v[212:215], v[70:73]
	v_mfma_f32_16x16x32_bf16 v[126:129], v[168:171], v[184:187], v[126:129]
	v_mfma_f32_16x16x32_bf16 v[114:117], v[176:179], v[184:187], v[114:117]
	v_mfma_f32_16x16x32_bf16 v[110:113], v[168:171], v[192:195], v[110:113]
	v_mfma_f32_16x16x32_bf16 v[98:101], v[176:179], v[192:195], v[98:101]
	v_mfma_f32_16x16x32_bf16 v[94:97], v[168:171], v[200:203], v[94:97]
	v_mfma_f32_16x16x32_bf16 v[82:85], v[176:179], v[200:203], v[82:85]
	v_mfma_f32_16x16x32_bf16 v[78:81], v[168:171], v[208:211], v[78:81]
	v_mfma_f32_16x16x32_bf16 v[66:69], v[176:179], v[208:211], v[66:69]
	v_mfma_f32_16x16x32_bf16 v[126:129], v[172:175], v[188:191], v[126:129]
	v_mfma_f32_16x16x32_bf16 v[114:117], v[180:183], v[188:191], v[114:117]
	v_mfma_f32_16x16x32_bf16 v[110:113], v[172:175], v[196:199], v[110:113]
	v_mfma_f32_16x16x32_bf16 v[98:101], v[180:183], v[196:199], v[98:101]
	v_mfma_f32_16x16x32_bf16 v[94:97], v[172:175], v[204:207], v[94:97]
	v_mfma_f32_16x16x32_bf16 v[82:85], v[180:183], v[204:207], v[82:85]
	v_mfma_f32_16x16x32_bf16 v[78:81], v[172:175], v[212:215], v[78:81]
	v_mfma_f32_16x16x32_bf16 v[66:69], v[180:183], v[212:215], v[66:69]
	s_barrier
	s_add_i32 s53, s72, s36
	s_mov_b32 m0, s53
	ds_read_b128 v[184:187], v150 offset:16384
	ds_read_b128 v[188:191], v150 offset:17408
	ds_read_b128 v[192:195], v150 offset:18432
	ds_read_b128 v[196:199], v150 offset:19456
	global_load_lds_dwordx4 v134, s[30:31]
	s_add_i32 m0, s53, 0x2000
	s_add_u32 s54, s30, 0x4000
	s_addc_u32 s55, s31, 0
	s_add_i32 s53, s73, s36
	global_load_lds_dwordx4 v130, s[30:31]
	s_mov_b32 m0, s53
	ds_read_b128 v[200:203], v150 offset:20480
	global_load_lds_dwordx4 v134, s[54:55]
	s_add_i32 m0, s53, 0x2000
	ds_read_b128 v[204:207], v150 offset:21504
	global_load_lds_dwordx4 v130, s[54:55]
	s_mov_b32 m0, s21
	ds_read_b128 v[208:211], v150 offset:22528
	global_load_lds_dwordx4 v136, s[34:35]
	s_mov_b32 m0, s23
	ds_read_b128 v[212:215], v150 offset:23552
	global_load_lds_dwordx4 v132, s[34:35]
	s_waitcnt vmcnt(8) lgkmcnt(0)
	s_barrier
	v_mfma_f32_16x16x32_bf16 v[58:61], v[152:155], v[184:187], v[58:61]
	v_mfma_f32_16x16x32_bf16 v[54:57], v[160:163], v[184:187], v[54:57]
	v_mfma_f32_16x16x32_bf16 v[42:45], v[152:155], v[192:195], v[42:45]
	v_mfma_f32_16x16x32_bf16 v[38:41], v[160:163], v[192:195], v[38:41]
	v_mfma_f32_16x16x32_bf16 v[26:29], v[152:155], v[200:203], v[26:29]
	v_mfma_f32_16x16x32_bf16 v[22:25], v[160:163], v[200:203], v[22:25]
	v_mfma_f32_16x16x32_bf16 v[10:13], v[152:155], v[208:211], v[10:13]
	v_mfma_f32_16x16x32_bf16 v[6:9], v[160:163], v[208:211], v[6:9]
	v_mfma_f32_16x16x32_bf16 v[58:61], v[156:159], v[188:191], v[58:61]
	v_mfma_f32_16x16x32_bf16 v[54:57], v[164:167], v[188:191], v[54:57]
	v_mfma_f32_16x16x32_bf16 v[42:45], v[156:159], v[196:199], v[42:45]
	v_mfma_f32_16x16x32_bf16 v[38:41], v[164:167], v[196:199], v[38:41]
	v_mfma_f32_16x16x32_bf16 v[26:29], v[156:159], v[204:207], v[26:29]
	v_mfma_f32_16x16x32_bf16 v[22:25], v[164:167], v[204:207], v[22:25]
	v_mfma_f32_16x16x32_bf16 v[10:13], v[156:159], v[212:215], v[10:13]
	v_mfma_f32_16x16x32_bf16 v[6:9], v[164:167], v[212:215], v[6:9]
	v_mfma_f32_16x16x32_bf16 v[62:65], v[168:171], v[184:187], v[62:65]
	v_mfma_f32_16x16x32_bf16 v[50:53], v[176:179], v[184:187], v[50:53]
	v_mfma_f32_16x16x32_bf16 v[46:49], v[168:171], v[192:195], v[46:49]
	v_mfma_f32_16x16x32_bf16 v[34:37], v[176:179], v[192:195], v[34:37]
	v_mfma_f32_16x16x32_bf16 v[30:33], v[168:171], v[200:203], v[30:33]
	v_mfma_f32_16x16x32_bf16 v[18:21], v[176:179], v[200:203], v[18:21]
	v_mfma_f32_16x16x32_bf16 v[14:17], v[168:171], v[208:211], v[14:17]
	v_mfma_f32_16x16x32_bf16 v[2:5], v[176:179], v[208:211], v[2:5]
	v_mfma_f32_16x16x32_bf16 v[62:65], v[172:175], v[188:191], v[62:65]
	v_mfma_f32_16x16x32_bf16 v[50:53], v[180:183], v[188:191], v[50:53]
	v_mfma_f32_16x16x32_bf16 v[46:49], v[172:175], v[196:199], v[46:49]
	v_mfma_f32_16x16x32_bf16 v[34:37], v[180:183], v[196:199], v[34:37]
	v_mfma_f32_16x16x32_bf16 v[30:33], v[172:175], v[204:207], v[30:33]
	v_mfma_f32_16x16x32_bf16 v[18:21], v[180:183], v[204:207], v[18:21]
	v_mfma_f32_16x16x32_bf16 v[14:17], v[172:175], v[212:215], v[14:17]
	v_mfma_f32_16x16x32_bf16 v[2:5], v[180:183], v[212:215], v[2:5]
	s_barrier
; #define PG8_STAGE(bufoff, gbase, voff) do { _Pragma("unroll") for (int _i = 0; _i < 2; ++_i) \
;         __builtin_amdgcn_global_load_lds((const unsigned*)((const char*)(gbase) + (voff)[_i]), (LAS unsigned*)(lds + (bufoff) + ldsw + _i * 8192), 16, 0, 0); } while (0)
; #define PG8_LDA(dst, b, h) do { _Pragma("unroll") for (int m = 0; m < 4; ++m) _Pragma("unroll") for (int k = 0; k < 2; ++k) dst[m][k] = *(const LAS bf16x8*)(lds + PG8_SA(b, h) + aoff + m * 2048 + k * 1024); } while (0)
; #define PG8_LDB(dst, b, h) do { _Pragma("unroll") for (int n = 0; n < 2; ++n) _Pragma("unroll") for (int k = 0; k < 2; ++k) dst[n][k] = *(const LAS bf16x8*)(lds + PG8_SB(b, h) + boff + n * 2048 + k * 1024); } while (0)
; #define PG8_MMA(ai, bj, At, Bt) do { __builtin_amdgcn_s_setprio(1); _Pragma("unroll") for (int m = 0; m < 4; ++m) _Pragma("unroll") for (int n = 0; n < 2; ++n) _Pragma("unroll") for (int k = 0; k < 2; ++k) \
;         acc[ai][bj][m][n] = __builtin_amdgcn_mfma_f32_16x16x32_bf16(Bt[n][k], At[m][k], acc[ai][bj][m][n], 0, 0, 0); __builtin_amdgcn_s_setprio(0); } while (0)
; #define PG8_WAIT_V(n) asm volatile("s_waitcnt vmcnt(" #n ")" ::: "memory")
; #define PG8_WAIT_L(n) asm volatile("s_waitcnt lgkmcnt(" #n ")" ::: "memory")
; #define PG8_BAR __builtin_amdgcn_s_barrier()
; #define PG8_SCHED __builtin_amdgcn_sched_barrier(0)
; template <class Epi, class Sched, bool ABLK = false, bool ALIGN_EPI = true, bool SP2 = true, bool BBLK = true>
; __device__ __forceinline__ void gemm_phase(LAS unsigned char* lds, const Gemm g, const Sched& S, const Epi& E) {
;     ...
;             PG8_LDB(B0, 1, 0); PG8_LDB(B1, 1, 1); PG8_SCHED; PG8_LDA(At, 1, 0); PG8_STAGE(PG8_SA(0, 1), a2 + hstepA, voffA);
;             PG8_WAIT_V(8); PG8_WAIT_L(0); PG8_BAR; PG8_MMA(0, 0, At, B0); PG8_MMA(0, 1, At, B1); PG8_BAR; PG8_SCHED;
;             PG8_LDA(At, 1, 1); PG8_STAGE(PG8_SB(1, 0), b3, voffB); PG8_STAGE(PG8_SB(1, 1), b3 + hstepB, voffB); PG8_STAGE(PG8_SA(1, 0), a3, voffA);
;             PG8_WAIT_V(8); PG8_WAIT_L(0); PG8_BAR; PG8_MMA(1, 0, At, B0); PG8_MMA(1, 1, At, B1); PG8_BAR; PG8_SCHED;
;     ...
;         }
;         if constexpr (ALIGN_EPI) { if (wr == 0) PG8_BAR; }
	v_add_u32_e32 v151, s60, v146
	ds_read_b128 v[152:155], v151
	ds_read_b128 v[156:159], v151 offset:1024
	ds_read_b128 v[160:163], v151 offset:2048
	ds_read_b128 v[164:167], v151 offset:3072
	v_add_u32_e32 v151, s61, v146
	ds_read_b128 v[168:171], v151
	ds_read_b128 v[172:175], v151 offset:1024
	ds_read_b128 v[176:179], v151 offset:2048
	ds_read_b128 v[180:183], v151 offset:3072
	s_add_u32 s34, s34, 0x80000
	s_addc_u32 s35, s35, 0
	s_mov_b32 m0, s39
	ds_read_b128 v[184:187], v150 offset:32768
	ds_read_b128 v[188:191], v150 offset:33792
	ds_read_b128 v[192:195], v150 offset:34816
	ds_read_b128 v[196:199], v150 offset:35840
	ds_read_b128 v[200:203], v150 offset:36864
	ds_read_b128 v[204:207], v150 offset:37888
	ds_read_b128 v[208:211], v150 offset:38912
	global_load_lds_dwordx4 v136, s[34:35]
	s_mov_b32 m0, s40
	ds_read_b128 v[212:215], v150 offset:39936
	global_load_lds_dwordx4 v132, s[34:35]
	s_waitcnt vmcnt(8) lgkmcnt(0)
	s_barrier
	v_mfma_f32_16x16x32_bf16 v[122:125], v[152:155], v[184:187], v[122:125]
	v_mfma_f32_16x16x32_bf16 v[118:121], v[160:163], v[184:187], v[118:121]
	v_mfma_f32_16x16x32_bf16 v[106:109], v[152:155], v[192:195], v[106:109]
	v_mfma_f32_16x16x32_bf16 v[102:105], v[160:163], v[192:195], v[102:105]
	v_mfma_f32_16x16x32_bf16 v[90:93], v[152:155], v[200:203], v[90:93]
	v_mfma_f32_16x16x32_bf16 v[86:89], v[160:163], v[200:203], v[86:89]
	v_mfma_f32_16x16x32_bf16 v[74:77], v[152:155], v[208:211], v[74:77]
	v_mfma_f32_16x16x32_bf16 v[70:73], v[160:163], v[208:211], v[70:73]
	v_mfma_f32_16x16x32_bf16 v[122:125], v[156:159], v[188:191], v[122:125]
	v_mfma_f32_16x16x32_bf16 v[118:121], v[164:167], v[188:191], v[118:121]
	v_mfma_f32_16x16x32_bf16 v[106:109], v[156:159], v[196:199], v[106:109]
	v_mfma_f32_16x16x32_bf16 v[102:105], v[164:167], v[196:199], v[102:105]
	v_mfma_f32_16x16x32_bf16 v[90:93], v[156:159], v[204:207], v[90:93]
	v_mfma_f32_16x16x32_bf16 v[86:89], v[164:167], v[204:207], v[86:89]
	v_mfma_f32_16x16x32_bf16 v[74:77], v[156:159], v[212:215], v[74:77]
	v_mfma_f32_16x16x32_bf16 v[70:73], v[164:167], v[212:215], v[70:73]
	v_mfma_f32_16x16x32_bf16 v[126:129], v[168:171], v[184:187], v[126:129]
	v_mfma_f32_16x16x32_bf16 v[114:117], v[176:179], v[184:187], v[114:117]
	v_mfma_f32_16x16x32_bf16 v[110:113], v[168:171], v[192:195], v[110:113]
	v_mfma_f32_16x16x32_bf16 v[98:101], v[176:179], v[192:195], v[98:101]
	v_mfma_f32_16x16x32_bf16 v[94:97], v[168:171], v[200:203], v[94:97]
	v_mfma_f32_16x16x32_bf16 v[82:85], v[176:179], v[200:203], v[82:85]
	v_mfma_f32_16x16x32_bf16 v[78:81], v[168:171], v[208:211], v[78:81]
	v_mfma_f32_16x16x32_bf16 v[66:69], v[176:179], v[208:211], v[66:69]
	v_mfma_f32_16x16x32_bf16 v[126:129], v[172:175], v[188:191], v[126:129]
	v_mfma_f32_16x16x32_bf16 v[114:117], v[180:183], v[188:191], v[114:117]
	v_mfma_f32_16x16x32_bf16 v[110:113], v[172:175], v[196:199], v[110:113]
	v_mfma_f32_16x16x32_bf16 v[98:101], v[180:183], v[196:199], v[98:101]
	v_mfma_f32_16x16x32_bf16 v[94:97], v[172:175], v[204:207], v[94:97]
	v_mfma_f32_16x16x32_bf16 v[82:85], v[180:183], v[204:207], v[82:85]
	v_mfma_f32_16x16x32_bf16 v[78:81], v[172:175], v[212:215], v[78:81]
	v_mfma_f32_16x16x32_bf16 v[66:69], v[180:183], v[212:215], v[66:69]
	s_barrier
	s_add_u32 s34, s30, 0x8000
	s_addc_u32 s35, s31, 0
	s_add_i32 s53, s60, s36
	s_mov_b32 m0, s53
	ds_read_b128 v[184:187], v150 offset:49152
	ds_read_b128 v[188:191], v150 offset:50176
	ds_read_b128 v[192:195], v150 offset:51200
	ds_read_b128 v[196:199], v150 offset:52224
	global_load_lds_dwordx4 v134, s[34:35]
	s_add_i32 m0, s53, 0x2000
	s_add_u32 s30, s30, 0xc000
	v_lshl_add_u64 v[216:217], s[34:35], 0, v[130:131]
	s_addc_u32 s31, s31, 0
	s_add_i32 s34, s61, s36
	global_load_lds_dwordx4 v[216:217], off
	s_mov_b32 m0, s34
	ds_read_b128 v[200:203], v150 offset:53248
	global_load_lds_dwordx4 v134, s[30:31]
	s_add_i32 m0, s34, 0x2000
	ds_read_b128 v[204:207], v150 offset:54272
	global_load_lds_dwordx4 v130, s[30:31]
	s_mov_b32 m0, s42
	ds_read_b128 v[208:211], v150 offset:55296
	global_load_lds_dwordx4 v136, s[28:29]
	s_mov_b32 m0, s43
	ds_read_b128 v[212:215], v150 offset:56320
	global_load_lds_dwordx4 v132, s[28:29]
	s_waitcnt vmcnt(8) lgkmcnt(0)
	s_barrier
	v_mfma_f32_16x16x32_bf16 v[58:61], v[152:155], v[184:187], v[58:61]
	v_mfma_f32_16x16x32_bf16 v[54:57], v[160:163], v[184:187], v[54:57]
	v_mfma_f32_16x16x32_bf16 v[42:45], v[152:155], v[192:195], v[42:45]
	v_mfma_f32_16x16x32_bf16 v[38:41], v[160:163], v[192:195], v[38:41]
	v_mfma_f32_16x16x32_bf16 v[26:29], v[152:155], v[200:203], v[26:29]
	v_mfma_f32_16x16x32_bf16 v[22:25], v[160:163], v[200:203], v[22:25]
	v_mfma_f32_16x16x32_bf16 v[10:13], v[152:155], v[208:211], v[10:13]
	v_mfma_f32_16x16x32_bf16 v[6:9], v[160:163], v[208:211], v[6:9]
	v_mfma_f32_16x16x32_bf16 v[58:61], v[156:159], v[188:191], v[58:61]
	v_mfma_f32_16x16x32_bf16 v[54:57], v[164:167], v[188:191], v[54:57]
	v_mfma_f32_16x16x32_bf16 v[42:45], v[156:159], v[196:199], v[42:45]
	v_mfma_f32_16x16x32_bf16 v[38:41], v[164:167], v[196:199], v[38:41]
	v_mfma_f32_16x16x32_bf16 v[26:29], v[156:159], v[204:207], v[26:29]
	v_mfma_f32_16x16x32_bf16 v[22:25], v[164:167], v[204:207], v[22:25]
	v_mfma_f32_16x16x32_bf16 v[10:13], v[156:159], v[212:215], v[10:13]
	v_mfma_f32_16x16x32_bf16 v[6:9], v[164:167], v[212:215], v[6:9]
	v_mfma_f32_16x16x32_bf16 v[62:65], v[168:171], v[184:187], v[62:65]
	v_mfma_f32_16x16x32_bf16 v[50:53], v[176:179], v[184:187], v[50:53]
	v_mfma_f32_16x16x32_bf16 v[46:49], v[168:171], v[192:195], v[46:49]
	v_mfma_f32_16x16x32_bf16 v[34:37], v[176:179], v[192:195], v[34:37]
	v_mfma_f32_16x16x32_bf16 v[30:33], v[168:171], v[200:203], v[30:33]
	v_mfma_f32_16x16x32_bf16 v[18:21], v[176:179], v[200:203], v[18:21]
	v_mfma_f32_16x16x32_bf16 v[14:17], v[168:171], v[208:211], v[14:17]
	v_mfma_f32_16x16x32_bf16 v[2:5], v[176:179], v[208:211], v[2:5]
	v_mfma_f32_16x16x32_bf16 v[62:65], v[172:175], v[188:191], v[62:65]
	v_mfma_f32_16x16x32_bf16 v[50:53], v[180:183], v[188:191], v[50:53]
	v_mfma_f32_16x16x32_bf16 v[46:49], v[172:175], v[196:199], v[46:49]
	v_mfma_f32_16x16x32_bf16 v[34:37], v[180:183], v[196:199], v[34:37]
	v_mfma_f32_16x16x32_bf16 v[30:33], v[172:175], v[204:207], v[30:33]
	v_mfma_f32_16x16x32_bf16 v[18:21], v[180:183], v[204:207], v[18:21]
	v_mfma_f32_16x16x32_bf16 v[14:17], v[172:175], v[212:215], v[14:17]
	v_mfma_f32_16x16x32_bf16 v[2:5], v[180:183], v[212:215], v[2:5]
	s_barrier
	s_add_i32 s52, s52, 2
	s_add_u32 s26, s26, 0x100
	s_addc_u32 s27, s27, 0
	s_add_u32 s50, s50, 0x10000
	s_addc_u32 s51, s51, 0
	s_cmp_gt_u32 s52, 29
	s_cbranch_scc0 .LBB0_2138
	s_and_b64 vcc, exec, s[6:7]
	s_cbranch_vccz .LBB0_2141
	s_barrier

; #define PG8_STAGE(bufoff, gbase, voff) do { _Pragma("unroll") for (int _i = 0; _i < 2; ++_i) \
;         __builtin_amdgcn_global_load_lds((const unsigned*)((const char*)(gbase) + (voff)[_i]), (LAS unsigned*)(lds + (bufoff) + ldsw + _i * 8192), 16, 0, 0); } while (0)
; #define PG8_LDA(dst, b, h) do { _Pragma("unroll") for (int m = 0; m < 4; ++m) _Pragma("unroll") for (int k = 0; k < 2; ++k) dst[m][k] = *(const LAS bf16x8*)(lds + PG8_SA(b, h) + aoff + m * 2048 + k * 1024); } while (0)
; #define PG8_LDB(dst, b, h) do { _Pragma("unroll") for (int n = 0; n < 2; ++n) _Pragma("unroll") for (int k = 0; k < 2; ++k) dst[n][k] = *(const LAS bf16x8*)(lds + PG8_SB(b, h) + boff + n * 2048 + k * 1024); } while (0)
; #define PG8_WAIT_V(n) asm volatile("s_waitcnt vmcnt(" #n ")" ::: "memory")
; #define PG8_WAIT_L(n) asm volatile("s_waitcnt lgkmcnt(" #n ")" ::: "memory")
; #define PG8_BAR __builtin_amdgcn_s_barrier()
; #define PG8_SCHED __builtin_amdgcn_sched_barrier(0)
; template <class Epi, class Sched, bool ABLK = false, bool ALIGN_EPI = true, bool SP2 = true, bool BBLK = true>
; __device__ __forceinline__ void gemm_phase(LAS unsigned char* lds, const Gemm g, const Sched& S, const Epi& E) {
;     ...
;         const bool has_next = S.next(ui + 1, nxt);
;         const int nt = cur.nt;
;         const char* nuA = has_next ? a_unit(nxt) : uA; const int ntbA = has_next ? nxt.k0 / BK : tbA; const char* nB = has_next ? (const char*)g.Bt + (size_t)nxt.pn * tstepB + b_k0(nxt.k0) : cB;
;         for (int t = 0; t < nt; t += 2) {
;             const bool last = (t == nt - 2);
;             const char* a1 = a_tile(uA, tbA + t + 1);
;             const char* a2 = last ? a_tile(nuA, ntbA) : a_tile(uA, tbA + t + 2); const char* b2 = last ? nB : cB + (size_t)(t + 2) * kstepB;
;             const char* a3 = last ? a_tile(nuA, ntbA + 1) : a_tile(uA, tbA + t + 3); const char* b3 = b2 + kstepB;
;             if (last && has_next) S.a_ready(nxt);
;             if constexpr (SP2) {
;             PG8_LDB(B0, 0, 0); PG8_LDB(B1, 0, 1); PG8_SCHED; PG8_LDA(At, 0, 0); PG8_STAGE(PG8_SA(1, 1), a1 + hstepA, voffA);
;             PG8_WAIT_V(8); PG8_WAIT_L(0); PG8_BAR; PG8_MMA(0, 0, At, B0); PG8_MMA(0, 1, At, B1); PG8_BAR; PG8_SCHED;
;             PG8_LDA(At, 0, 1); PG8_STAGE(PG8_SB(0, 0), b2, voffB); PG8_STAGE(PG8_SB(0, 1), b2 + hstepB, voffB); PG8_STAGE(PG8_SA(0, 0), a2, voffA);
.LBB0_2262:
	s_ashr_i32 s13, s12, 31
	s_lshl_b64 s[4:5], s[12:13], 20
	s_add_u32 s16, s41, s4
	s_addc_u32 s17, s42, s5
	s_and_b64 s[4:5], s[18:19], exec
	s_cselect_b32 s4, s17, s27
	s_cselect_b32 s5, s16, s26
	s_ashr_i32 s15, s14, 31
	s_lshl_b64 s[20:21], s[14:15], 20
	s_add_u32 s20, s38, s20
	s_addc_u32 s21, s39, s21
	s_and_b64 s[30:31], s[18:19], exec
	s_cselect_b32 s13, s21, s29
	s_cselect_b32 s15, s20, s28
	s_add_u32 s23, s5, 0x80
	s_addc_u32 s54, s4, 0
	s_add_u32 s55, s28, 0x10000
	v_mov_b32_e32 v2, 0
	s_addc_u32 s56, s29, 0
	v_lshl_add_u64 v[164:165], s[26:27], 0, v[160:161]
	v_lshl_add_u64 v[166:167], s[26:27], 0, v[162:163]
	s_mov_b32 s57, -2
	s_mov_b64 s[28:29], 0
	ds_read_b128 v[172:175], v168
	ds_read_b128 v[176:179], v168 offset:1024
	ds_read_b128 v[180:183], v168 offset:2048
	ds_read_b128 v[184:187], v168 offset:3072
	ds_read_b128 v[188:191], v169
	ds_read_b128 v[192:195], v169 offset:1024
	ds_read_b128 v[196:199], v169 offset:2048
	ds_read_b128 v[200:203], v169 offset:3072
	s_add_u32 s30, s26, s28
	s_addc_u32 s31, s27, s29
	s_add_u32 s36, s30, 0x100
	s_addc_u32 s37, s31, 0
	s_add_u32 s30, s30, 0x180
	s_addc_u32 s31, s31, 0
	s_cmpk_eq_i32 s28, 0xf00
	s_cselect_b32 s31, s54, s31
	s_cselect_b32 s30, s23, s30
	s_cselect_b32 s35, s13, s56
	s_cselect_b32 s34, s15, s55
	s_cselect_b32 s37, s4, s37
	s_cselect_b32 s36, s5, s36
	s_mov_b32 m0, s50
	v_lshl_add_u64 v[236:237], v[164:165], 0, s[28:29]
	ds_read_b128 v[204:207], v170
	ds_read_b128 v[208:211], v170 offset:1024
	ds_read_b128 v[212:215], v170 offset:2048
	ds_read_b128 v[216:219], v170 offset:3072
	ds_read_b128 v[220:223], v170 offset:4096
	ds_read_b128 v[224:227], v170 offset:5120
	ds_read_b128 v[228:231], v170 offset:6144
	global_load_lds_dwordx4 v[236:237], off
	v_lshl_add_u64 v[236:237], v[166:167], 0, s[28:29]
	s_mov_b32 m0, s51
	ds_read_b128 v[232:235], v170 offset:7168
	global_load_lds_dwordx4 v[236:237], off
	s_waitcnt vmcnt(8) lgkmcnt(0)
	s_barrier
	v_mfma_f32_16x16x32_bf16 v[126:129], v[172:175], v[204:207], 0
	v_mfma_f32_16x16x32_bf16 v[122:125], v[180:183], v[204:207], 0
	v_mfma_f32_16x16x32_bf16 v[110:113], v[172:175], v[212:215], 0
	v_mfma_f32_16x16x32_bf16 v[106:109], v[180:183], v[212:215], 0
	v_mfma_f32_16x16x32_bf16 v[94:97], v[172:175], v[220:223], 0
	v_mfma_f32_16x16x32_bf16 v[90:93], v[180:183], v[220:223], 0
	v_mfma_f32_16x16x32_bf16 v[78:81], v[172:175], v[228:231], 0
	v_mfma_f32_16x16x32_bf16 v[74:77], v[180:183], v[228:231], 0
	v_mfma_f32_16x16x32_bf16 v[126:129], v[176:179], v[208:211], v[126:129]
	v_mfma_f32_16x16x32_bf16 v[122:125], v[184:187], v[208:211], v[122:125]
	v_mfma_f32_16x16x32_bf16 v[110:113], v[176:179], v[216:219], v[110:113]
	v_mfma_f32_16x16x32_bf16 v[106:109], v[184:187], v[216:219], v[106:109]
	v_mfma_f32_16x16x32_bf16 v[94:97], v[176:179], v[224:227], v[94:97]
	v_mfma_f32_16x16x32_bf16 v[90:93], v[184:187], v[224:227], v[90:93]
	v_mfma_f32_16x16x32_bf16 v[78:81], v[176:179], v[232:235], v[78:81]
	v_mfma_f32_16x16x32_bf16 v[74:77], v[184:187], v[232:235], v[74:77]
	v_mfma_f32_16x16x32_bf16 v[118:121], v[188:191], v[204:207], 0
	v_mfma_f32_16x16x32_bf16 v[114:117], v[196:199], v[204:207], 0
	v_mfma_f32_16x16x32_bf16 v[102:105], v[188:191], v[212:215], 0
	v_mfma_f32_16x16x32_bf16 v[98:101], v[196:199], v[212:215], 0
	v_mfma_f32_16x16x32_bf16 v[86:89], v[188:191], v[220:223], 0
	v_mfma_f32_16x16x32_bf16 v[82:85], v[196:199], v[220:223], 0
	v_mfma_f32_16x16x32_bf16 v[70:73], v[188:191], v[228:231], 0
	v_mfma_f32_16x16x32_bf16 v[66:69], v[196:199], v[228:231], 0
	v_mfma_f32_16x16x32_bf16 v[118:121], v[192:195], v[208:211], v[118:121]
	v_mfma_f32_16x16x32_bf16 v[114:117], v[200:203], v[208:211], v[114:117]
	v_mfma_f32_16x16x32_bf16 v[102:105], v[192:195], v[216:219], v[102:105]
	v_mfma_f32_16x16x32_bf16 v[98:101], v[200:203], v[216:219], v[98:101]
	v_mfma_f32_16x16x32_bf16 v[86:89], v[192:195], v[224:227], v[86:89]
	v_mfma_f32_16x16x32_bf16 v[82:85], v[200:203], v[224:227], v[82:85]
	v_mfma_f32_16x16x32_bf16 v[70:73], v[192:195], v[232:235], v[70:73]
	v_mfma_f32_16x16x32_bf16 v[66:69], v[200:203], v[232:235], v[66:69]
	s_barrier
	s_mov_b32 m0, s52
	s_add_u32 s58, s34, 0x4000
	ds_read_b128 v[204:207], v170 offset:16384
	ds_read_b128 v[208:211], v170 offset:17408
	ds_read_b128 v[212:215], v170 offset:18432
	ds_read_b128 v[216:219], v170 offset:19456
	global_load_lds_dwordx4 v134, s[34:35]
	s_mov_b32 m0, s53
	s_addc_u32 s59, s35, 0
	s_add_i32 s62, s73, s40
	global_load_lds_dwordx4 v130, s[34:35]
	s_mov_b32 m0, s62
	ds_read_b128 v[220:223], v170 offset:20480
	global_load_lds_dwordx4 v134, s[58:59]
	s_add_i32 m0, s62, 0x2000
	ds_read_b128 v[224:227], v170 offset:21504
	global_load_lds_dwordx4 v130, s[58:59]
	s_mov_b32 m0, s25
	ds_read_b128 v[228:231], v170 offset:22528
	global_load_lds_dwordx4 v136, s[36:37]
	s_mov_b32 m0, s43
	ds_read_b128 v[232:235], v170 offset:23552
	global_load_lds_dwordx4 v132, s[36:37]
	s_waitcnt vmcnt(8) lgkmcnt(0)
	s_barrier
; #define PG8_STAGE(bufoff, gbase, voff) do { _Pragma("unroll") for (int _i = 0; _i < 2; ++_i) \
;         __builtin_amdgcn_global_load_lds((const unsigned*)((const char*)(gbase) + (voff)[_i]), (LAS unsigned*)(lds + (bufoff) + ldsw + _i * 8192), 16, 0, 0); } while (0)
; #define PG8_LDA(dst, b, h) do { _Pragma("unroll") for (int m = 0; m < 4; ++m) _Pragma("unroll") for (int k = 0; k < 2; ++k) dst[m][k] = *(const LAS bf16x8*)(lds + PG8_SA(b, h) + aoff + m * 2048 + k * 1024); } while (0)
; #define PG8_LDB(dst, b, h) do { _Pragma("unroll") for (int n = 0; n < 2; ++n) _Pragma("unroll") for (int k = 0; k < 2; ++k) dst[n][k] = *(const LAS bf16x8*)(lds + PG8_SB(b, h) + boff + n * 2048 + k * 1024); } while (0)
; #define PG8_MMA(ai, bj, At, Bt) do { __builtin_amdgcn_s_setprio(1); _Pragma("unroll") for (int m = 0; m < 4; ++m) _Pragma("unroll") for (int n = 0; n < 2; ++n) _Pragma("unroll") for (int k = 0; k < 2; ++k) \
;         acc[ai][bj][m][n] = __builtin_amdgcn_mfma_f32_16x16x32_bf16(Bt[n][k], At[m][k], acc[ai][bj][m][n], 0, 0, 0); __builtin_amdgcn_s_setprio(0); } while (0)
; #define PG8_WAIT_V(n) asm volatile("s_waitcnt vmcnt(" #n ")" ::: "memory")
; #define PG8_WAIT_L(n) asm volatile("s_waitcnt lgkmcnt(" #n ")" ::: "memory")
; #define PG8_BAR __builtin_amdgcn_s_barrier()
; #define PG8_SCHED __builtin_amdgcn_sched_barrier(0)
; template <class Epi, class Sched, bool ABLK = false, bool ALIGN_EPI = true, bool SP2 = true, bool BBLK = true>
; __device__ __forceinline__ void gemm_phase(LAS unsigned char* lds, const Gemm g, const Sched& S, const Epi& E) {
;     ...
;             PG8_WAIT_V(8); PG8_WAIT_L(0); PG8_BAR; PG8_MMA(1, 0, At, B0); PG8_MMA(1, 1, At, B1); PG8_BAR; PG8_SCHED;
;             PG8_LDB(B0, 1, 0); PG8_LDB(B1, 1, 1); PG8_SCHED; PG8_LDA(At, 1, 0); PG8_STAGE(PG8_SA(0, 1), a2 + hstepA, voffA);
;             PG8_WAIT_V(8); PG8_WAIT_L(0); PG8_BAR; PG8_MMA(0, 0, At, B0); PG8_MMA(0, 1, At, B1); PG8_BAR; PG8_SCHED;
	v_mfma_f32_16x16x32_bf16 v[62:65], v[172:175], v[204:207], 0
	v_mfma_f32_16x16x32_bf16 v[58:61], v[180:183], v[204:207], 0
	v_mfma_f32_16x16x32_bf16 v[46:49], v[172:175], v[212:215], 0
	v_mfma_f32_16x16x32_bf16 v[42:45], v[180:183], v[212:215], 0
	v_mfma_f32_16x16x32_bf16 v[30:33], v[172:175], v[220:223], 0
	v_mfma_f32_16x16x32_bf16 v[26:29], v[180:183], v[220:223], 0
	v_mfma_f32_16x16x32_bf16 v[14:17], v[172:175], v[228:231], 0
	v_mfma_f32_16x16x32_bf16 v[10:13], v[180:183], v[228:231], 0
	v_mfma_f32_16x16x32_bf16 v[62:65], v[176:179], v[208:211], v[62:65]
	v_mfma_f32_16x16x32_bf16 v[58:61], v[184:187], v[208:211], v[58:61]
	v_mfma_f32_16x16x32_bf16 v[46:49], v[176:179], v[216:219], v[46:49]
	v_mfma_f32_16x16x32_bf16 v[42:45], v[184:187], v[216:219], v[42:45]
	v_mfma_f32_16x16x32_bf16 v[30:33], v[176:179], v[224:227], v[30:33]
	v_mfma_f32_16x16x32_bf16 v[26:29], v[184:187], v[224:227], v[26:29]
	v_mfma_f32_16x16x32_bf16 v[14:17], v[176:179], v[232:235], v[14:17]
	v_mfma_f32_16x16x32_bf16 v[10:13], v[184:187], v[232:235], v[10:13]
	v_mfma_f32_16x16x32_bf16 v[54:57], v[188:191], v[204:207], 0
	v_mfma_f32_16x16x32_bf16 v[50:53], v[196:199], v[204:207], 0
	v_mfma_f32_16x16x32_bf16 v[38:41], v[188:191], v[212:215], 0
	v_mfma_f32_16x16x32_bf16 v[34:37], v[196:199], v[212:215], 0
	v_mfma_f32_16x16x32_bf16 v[22:25], v[188:191], v[220:223], 0
	v_mfma_f32_16x16x32_bf16 v[18:21], v[196:199], v[220:223], 0
	v_mfma_f32_16x16x32_bf16 v[6:9], v[188:191], v[228:231], 0
	v_mfma_f32_16x16x32_bf16 v[2:5], v[196:199], v[228:231], 0
	v_mfma_f32_16x16x32_bf16 v[54:57], v[192:195], v[208:211], v[54:57]
	v_mfma_f32_16x16x32_bf16 v[50:53], v[200:203], v[208:211], v[50:53]
	v_mfma_f32_16x16x32_bf16 v[38:41], v[192:195], v[216:219], v[38:41]
	v_mfma_f32_16x16x32_bf16 v[34:37], v[200:203], v[216:219], v[34:37]
	v_mfma_f32_16x16x32_bf16 v[22:25], v[192:195], v[224:227], v[22:25]
	v_mfma_f32_16x16x32_bf16 v[18:21], v[200:203], v[224:227], v[18:21]
	v_mfma_f32_16x16x32_bf16 v[6:9], v[192:195], v[232:235], v[6:9]
	v_mfma_f32_16x16x32_bf16 v[2:5], v[200:203], v[232:235], v[2:5]
	s_barrier
	v_add_u32_e32 v171, s60, v1
	ds_read_b128 v[172:175], v171
	ds_read_b128 v[176:179], v171 offset:1024
	ds_read_b128 v[180:183], v171 offset:2048
	ds_read_b128 v[184:187], v171 offset:3072
	v_add_u32_e32 v171, s61, v1
	ds_read_b128 v[188:191], v171
	ds_read_b128 v[192:195], v171 offset:1024
	ds_read_b128 v[196:199], v171 offset:2048
	ds_read_b128 v[200:203], v171 offset:3072
	s_add_u32 s36, s36, 0x80000
	s_addc_u32 s37, s37, 0
	s_mov_b32 m0, s44
	ds_read_b128 v[204:207], v170 offset:32768
	ds_read_b128 v[208:211], v170 offset:33792
	ds_read_b128 v[212:215], v170 offset:34816
	ds_read_b128 v[216:219], v170 offset:35840
	ds_read_b128 v[220:223], v170 offset:36864
	ds_read_b128 v[224:227], v170 offset:37888
	ds_read_b128 v[228:231], v170 offset:38912
	global_load_lds_dwordx4 v136, s[36:37]
	s_mov_b32 m0, s45
	ds_read_b128 v[232:235], v170 offset:39936
	global_load_lds_dwordx4 v132, s[36:37]
	s_waitcnt vmcnt(8) lgkmcnt(0)
	s_barrier
	v_mfma_f32_16x16x32_bf16 v[126:129], v[172:175], v[204:207], v[126:129]
	v_mfma_f32_16x16x32_bf16 v[122:125], v[180:183], v[204:207], v[122:125]
	v_mfma_f32_16x16x32_bf16 v[110:113], v[172:175], v[212:215], v[110:113]
	v_mfma_f32_16x16x32_bf16 v[106:109], v[180:183], v[212:215], v[106:109]
	v_mfma_f32_16x16x32_bf16 v[94:97], v[172:175], v[220:223], v[94:97]
	v_mfma_f32_16x16x32_bf16 v[90:93], v[180:183], v[220:223], v[90:93]
	v_mfma_f32_16x16x32_bf16 v[78:81], v[172:175], v[228:231], v[78:81]
	v_mfma_f32_16x16x32_bf16 v[74:77], v[180:183], v[228:231], v[74:77]
	v_mfma_f32_16x16x32_bf16 v[126:129], v[176:179], v[208:211], v[126:129]
	v_mfma_f32_16x16x32_bf16 v[122:125], v[184:187], v[208:211], v[122:125]
	v_mfma_f32_16x16x32_bf16 v[110:113], v[176:179], v[216:219], v[110:113]
	v_mfma_f32_16x16x32_bf16 v[106:109], v[184:187], v[216:219], v[106:109]
	v_mfma_f32_16x16x32_bf16 v[94:97], v[176:179], v[224:227], v[94:97]
	v_mfma_f32_16x16x32_bf16 v[90:93], v[184:187], v[224:227], v[90:93]
	v_mfma_f32_16x16x32_bf16 v[78:81], v[176:179], v[232:235], v[78:81]
	v_mfma_f32_16x16x32_bf16 v[74:77], v[184:187], v[232:235], v[74:77]
	v_mfma_f32_16x16x32_bf16 v[118:121], v[188:191], v[204:207], v[118:121]
	v_mfma_f32_16x16x32_bf16 v[114:117], v[196:199], v[204:207], v[114:117]
	v_mfma_f32_16x16x32_bf16 v[102:105], v[188:191], v[212:215], v[102:105]
	v_mfma_f32_16x16x32_bf16 v[98:101], v[196:199], v[212:215], v[98:101]
	v_mfma_f32_16x16x32_bf16 v[86:89], v[188:191], v[220:223], v[86:89]
	v_mfma_f32_16x16x32_bf16 v[82:85], v[196:199], v[220:223], v[82:85]
	v_mfma_f32_16x16x32_bf16 v[70:73], v[188:191], v[228:231], v[70:73]
	v_mfma_f32_16x16x32_bf16 v[66:69], v[196:199], v[228:231], v[66:69]
	v_mfma_f32_16x16x32_bf16 v[118:121], v[192:195], v[208:211], v[118:121]
	v_mfma_f32_16x16x32_bf16 v[114:117], v[200:203], v[208:211], v[114:117]
	v_mfma_f32_16x16x32_bf16 v[102:105], v[192:195], v[216:219], v[102:105]
	v_mfma_f32_16x16x32_bf16 v[98:101], v[200:203], v[216:219], v[98:101]
	v_mfma_f32_16x16x32_bf16 v[86:89], v[192:195], v[224:227], v[86:89]
	v_mfma_f32_16x16x32_bf16 v[82:85], v[200:203], v[224:227], v[82:85]
	v_mfma_f32_16x16x32_bf16 v[70:73], v[192:195], v[232:235], v[70:73]
	v_mfma_f32_16x16x32_bf16 v[66:69], v[200:203], v[232:235], v[66:69]
	s_barrier
; #define PG8_STAGE(bufoff, gbase, voff) do { _Pragma("unroll") for (int _i = 0; _i < 2; ++_i) \
;         __builtin_amdgcn_global_load_lds((const unsigned*)((const char*)(gbase) + (voff)[_i]), (LAS unsigned*)(lds + (bufoff) + ldsw + _i * 8192), 16, 0, 0); } while (0)
; #define PG8_LDA(dst, b, h) do { _Pragma("unroll") for (int m = 0; m < 4; ++m) _Pragma("unroll") for (int k = 0; k < 2; ++k) dst[m][k] = *(const LAS bf16x8*)(lds + PG8_SA(b, h) + aoff + m * 2048 + k * 1024); } while (0)
; #define PG8_WAIT_V(n) asm volatile("s_waitcnt vmcnt(" #n ")" ::: "memory")
; #define PG8_WAIT_L(n) asm volatile("s_waitcnt lgkmcnt(" #n ")" ::: "memory")
; template <class Epi, class Sched, bool ABLK = false, bool ALIGN_EPI = true, bool SP2 = true, bool BBLK = true>
; __device__ __forceinline__ void gemm_phase(LAS unsigned char* lds, const Gemm g, const Sched& S, const Epi& E) {
;     ...
;         for (int t = 0; t < nt; t += 2) {
;             const bool last = (t == nt - 2);
;             const char* a1 = a_tile(uA, tbA + t + 1);
;             const char* a2 = last ? a_tile(nuA, ntbA) : a_tile(uA, tbA + t + 2); const char* b2 = last ? nB : cB + (size_t)(t + 2) * kstepB;
;             const char* a3 = last ? a_tile(nuA, ntbA + 1) : a_tile(uA, tbA + t + 3); const char* b3 = b2 + kstepB;
;             if (last && has_next) S.a_ready(nxt);
;             if constexpr (SP2) {
;             PG8_LDB(B0, 0, 0); PG8_LDB(B1, 0, 1); PG8_SCHED; PG8_LDA(At, 0, 0); PG8_STAGE(PG8_SA(1, 1), a1 + hstepA, voffA);
;             PG8_WAIT_V(8); PG8_WAIT_L(0); PG8_BAR; PG8_MMA(0, 0, At, B0); PG8_MMA(0, 1, At, B1); PG8_BAR; PG8_SCHED;
;             PG8_LDA(At, 0, 1); PG8_STAGE(PG8_SB(0, 0), b2, voffB); PG8_STAGE(PG8_SB(0, 1), b2 + hstepB, voffB); PG8_STAGE(PG8_SA(0, 0), a2, voffA);
;             PG8_WAIT_V(8); PG8_WAIT_L(0); PG8_BAR; PG8_MMA(1, 0, At, B0); PG8_MMA(1, 1, At, B1); PG8_BAR; PG8_SCHED;
;             PG8_LDB(B0, 1, 0); PG8_LDB(B1, 1, 1); PG8_SCHED; PG8_LDA(At, 1, 0); PG8_STAGE(PG8_SA(0, 1), a2 + hstepA, voffA);
;             PG8_WAIT_V(8); PG8_WAIT_L(0); PG8_BAR; PG8_MMA(0, 0, At, B0); PG8_MMA(0, 1, At, B1); PG8_BAR; PG8_SCHED;
;             PG8_LDA(At, 1, 1); PG8_STAGE(PG8_SB(1, 0), b3, voffB); PG8_STAGE(PG8_SB(1, 1), b3 + hstepB, voffB); PG8_STAGE(PG8_SA(1, 0), a3, voffA);
;             PG8_WAIT_V(8); PG8_WAIT_L(0); PG8_BAR; PG8_MMA(1, 0, At, B0); PG8_MMA(1, 1, At, B1); PG8_BAR; PG8_SCHED;
	s_add_u32 s36, s34, 0x8000
	s_addc_u32 s37, s35, 0
	s_add_i32 s58, s60, s40
	s_mov_b32 m0, s58
	ds_read_b128 v[204:207], v170 offset:49152
	ds_read_b128 v[208:211], v170 offset:50176
	ds_read_b128 v[212:215], v170 offset:51200
	ds_read_b128 v[216:219], v170 offset:52224
	global_load_lds_dwordx4 v134, s[36:37]
	s_add_i32 m0, s58, 0x2000
	s_add_u32 s34, s34, 0xc000
	v_lshl_add_u64 v[236:237], s[36:37], 0, v[130:131]
	s_addc_u32 s35, s35, 0
	s_add_i32 s36, s61, s40
	global_load_lds_dwordx4 v[236:237], off
	s_mov_b32 m0, s36
	ds_read_b128 v[220:223], v170 offset:53248
	global_load_lds_dwordx4 v134, s[34:35]
	s_add_i32 m0, s36, 0x2000
	ds_read_b128 v[224:227], v170 offset:54272
	global_load_lds_dwordx4 v130, s[34:35]
	s_mov_b32 m0, s48
	ds_read_b128 v[228:231], v170 offset:55296
	global_load_lds_dwordx4 v136, s[30:31]
	s_mov_b32 m0, s49
	ds_read_b128 v[232:235], v170 offset:56320
	global_load_lds_dwordx4 v132, s[30:31]
	s_waitcnt vmcnt(8) lgkmcnt(0)
	s_barrier
	v_mfma_f32_16x16x32_bf16 v[62:65], v[172:175], v[204:207], v[62:65]
	v_mfma_f32_16x16x32_bf16 v[58:61], v[180:183], v[204:207], v[58:61]
	v_mfma_f32_16x16x32_bf16 v[46:49], v[172:175], v[212:215], v[46:49]
	v_mfma_f32_16x16x32_bf16 v[42:45], v[180:183], v[212:215], v[42:45]
	v_mfma_f32_16x16x32_bf16 v[30:33], v[172:175], v[220:223], v[30:33]
	v_mfma_f32_16x16x32_bf16 v[26:29], v[180:183], v[220:223], v[26:29]
	v_mfma_f32_16x16x32_bf16 v[14:17], v[172:175], v[228:231], v[14:17]
	v_mfma_f32_16x16x32_bf16 v[10:13], v[180:183], v[228:231], v[10:13]
	v_mfma_f32_16x16x32_bf16 v[62:65], v[176:179], v[208:211], v[62:65]
	v_mfma_f32_16x16x32_bf16 v[58:61], v[184:187], v[208:211], v[58:61]
	v_mfma_f32_16x16x32_bf16 v[46:49], v[176:179], v[216:219], v[46:49]
	v_mfma_f32_16x16x32_bf16 v[42:45], v[184:187], v[216:219], v[42:45]
	v_mfma_f32_16x16x32_bf16 v[30:33], v[176:179], v[224:227], v[30:33]
	v_mfma_f32_16x16x32_bf16 v[26:29], v[184:187], v[224:227], v[26:29]
	v_mfma_f32_16x16x32_bf16 v[14:17], v[176:179], v[232:235], v[14:17]
	v_mfma_f32_16x16x32_bf16 v[10:13], v[184:187], v[232:235], v[10:13]
	v_mfma_f32_16x16x32_bf16 v[54:57], v[188:191], v[204:207], v[54:57]
	v_mfma_f32_16x16x32_bf16 v[50:53], v[196:199], v[204:207], v[50:53]
	v_mfma_f32_16x16x32_bf16 v[38:41], v[188:191], v[212:215], v[38:41]
	v_mfma_f32_16x16x32_bf16 v[34:37], v[196:199], v[212:215], v[34:37]
	v_mfma_f32_16x16x32_bf16 v[22:25], v[188:191], v[220:223], v[22:25]
	v_mfma_f32_16x16x32_bf16 v[18:21], v[196:199], v[220:223], v[18:21]
	v_mfma_f32_16x16x32_bf16 v[6:9], v[188:191], v[228:231], v[6:9]
	v_mfma_f32_16x16x32_bf16 v[2:5], v[196:199], v[228:231], v[2:5]
	v_mfma_f32_16x16x32_bf16 v[54:57], v[192:195], v[208:211], v[54:57]
	v_mfma_f32_16x16x32_bf16 v[50:53], v[200:203], v[208:211], v[50:53]
	v_mfma_f32_16x16x32_bf16 v[38:41], v[192:195], v[216:219], v[38:41]
	v_mfma_f32_16x16x32_bf16 v[34:37], v[200:203], v[216:219], v[34:37]
	v_mfma_f32_16x16x32_bf16 v[22:25], v[192:195], v[224:227], v[22:25]
	v_mfma_f32_16x16x32_bf16 v[18:21], v[200:203], v[224:227], v[18:21]
	v_mfma_f32_16x16x32_bf16 v[6:9], v[192:195], v[232:235], v[6:9]
	v_mfma_f32_16x16x32_bf16 v[2:5], v[200:203], v[232:235], v[2:5]
	s_barrier
	s_add_i32 s57, s57, 2
	s_add_u32 s28, s28, 0x100
	s_addc_u32 s29, s29, 0
	s_add_u32 s55, s55, 0x10000
	s_addc_u32 s56, s56, 0
	s_cmp_gt_u32 s57, 29
.LBB0_2263:
	ds_read_b128 v[172:175], v168
	ds_read_b128 v[176:179], v168 offset:1024
	ds_read_b128 v[180:183], v168 offset:2048
	ds_read_b128 v[184:187], v168 offset:3072
	ds_read_b128 v[188:191], v169
	ds_read_b128 v[192:195], v169 offset:1024
	ds_read_b128 v[196:199], v169 offset:2048
	ds_read_b128 v[200:203], v169 offset:3072
	s_add_u32 s30, s26, s28
	s_addc_u32 s31, s27, s29
	s_add_u32 s36, s30, 0x100
	s_addc_u32 s37, s31, 0
	s_add_u32 s30, s30, 0x180
	s_addc_u32 s31, s31, 0
	s_cmpk_eq_i32 s28, 0xf00
	s_cselect_b32 s31, s54, s31
	s_cselect_b32 s30, s23, s30
	s_cselect_b32 s35, s13, s56
	s_cselect_b32 s34, s15, s55
	s_cselect_b32 s37, s4, s37
	s_cselect_b32 s36, s5, s36
	s_mov_b32 m0, s50
	v_lshl_add_u64 v[236:237], v[164:165], 0, s[28:29]
	ds_read_b128 v[204:207], v170
	ds_read_b128 v[208:211], v170 offset:1024
	ds_read_b128 v[212:215], v170 offset:2048
	ds_read_b128 v[216:219], v170 offset:3072
	ds_read_b128 v[220:223], v170 offset:4096
	ds_read_b128 v[224:227], v170 offset:5120
	ds_read_b128 v[228:231], v170 offset:6144
	global_load_lds_dwordx4 v[236:237], off
	v_lshl_add_u64 v[236:237], v[166:167], 0, s[28:29]
	s_mov_b32 m0, s51
	ds_read_b128 v[232:235], v170 offset:7168
	global_load_lds_dwordx4 v[236:237], off
	s_waitcnt vmcnt(8) lgkmcnt(0)
	s_barrier
; #define PG8_STAGE(bufoff, gbase, voff) do { _Pragma("unroll") for (int _i = 0; _i < 2; ++_i) \
;         __builtin_amdgcn_global_load_lds((const unsigned*)((const char*)(gbase) + (voff)[_i]), (LAS unsigned*)(lds + (bufoff) + ldsw + _i * 8192), 16, 0, 0); } while (0)
; #define PG8_LDA(dst, b, h) do { _Pragma("unroll") for (int m = 0; m < 4; ++m) _Pragma("unroll") for (int k = 0; k < 2; ++k) dst[m][k] = *(const LAS bf16x8*)(lds + PG8_SA(b, h) + aoff + m * 2048 + k * 1024); } while (0)
; #define PG8_MMA(ai, bj, At, Bt) do { __builtin_amdgcn_s_setprio(1); _Pragma("unroll") for (int m = 0; m < 4; ++m) _Pragma("unroll") for (int n = 0; n < 2; ++n) _Pragma("unroll") for (int k = 0; k < 2; ++k) \
;         acc[ai][bj][m][n] = __builtin_amdgcn_mfma_f32_16x16x32_bf16(Bt[n][k], At[m][k], acc[ai][bj][m][n], 0, 0, 0); __builtin_amdgcn_s_setprio(0); } while (0)
; #define PG8_WAIT_V(n) asm volatile("s_waitcnt vmcnt(" #n ")" ::: "memory")
; #define PG8_WAIT_L(n) asm volatile("s_waitcnt lgkmcnt(" #n ")" ::: "memory")
; #define PG8_BAR __builtin_amdgcn_s_barrier()
; #define PG8_SCHED __builtin_amdgcn_sched_barrier(0)
; template <class Epi, class Sched, bool ABLK = false, bool ALIGN_EPI = true, bool SP2 = true, bool BBLK = true>
; __device__ __forceinline__ void gemm_phase(LAS unsigned char* lds, const Gemm g, const Sched& S, const Epi& E) {
;     ...
;             PG8_WAIT_V(8); PG8_WAIT_L(0); PG8_BAR; PG8_MMA(0, 0, At, B0); PG8_MMA(0, 1, At, B1); PG8_BAR; PG8_SCHED;
;             PG8_LDA(At, 0, 1); PG8_STAGE(PG8_SB(0, 0), b2, voffB); PG8_STAGE(PG8_SB(0, 1), b2 + hstepB, voffB); PG8_STAGE(PG8_SA(0, 0), a2, voffA);
;             PG8_WAIT_V(8); PG8_WAIT_L(0); PG8_BAR; PG8_MMA(1, 0, At, B0); PG8_MMA(1, 1, At, B1); PG8_BAR; PG8_SCHED;
	v_mfma_f32_16x16x32_bf16 v[126:129], v[172:175], v[204:207], v[126:129]
	v_mfma_f32_16x16x32_bf16 v[122:125], v[180:183], v[204:207], v[122:125]
	v_mfma_f32_16x16x32_bf16 v[110:113], v[172:175], v[212:215], v[110:113]
	v_mfma_f32_16x16x32_bf16 v[106:109], v[180:183], v[212:215], v[106:109]
	v_mfma_f32_16x16x32_bf16 v[94:97], v[172:175], v[220:223], v[94:97]
	v_mfma_f32_16x16x32_bf16 v[90:93], v[180:183], v[220:223], v[90:93]
	v_mfma_f32_16x16x32_bf16 v[78:81], v[172:175], v[228:231], v[78:81]
	v_mfma_f32_16x16x32_bf16 v[74:77], v[180:183], v[228:231], v[74:77]
	v_mfma_f32_16x16x32_bf16 v[126:129], v[176:179], v[208:211], v[126:129]
	v_mfma_f32_16x16x32_bf16 v[122:125], v[184:187], v[208:211], v[122:125]
	v_mfma_f32_16x16x32_bf16 v[110:113], v[176:179], v[216:219], v[110:113]
	v_mfma_f32_16x16x32_bf16 v[106:109], v[184:187], v[216:219], v[106:109]
	v_mfma_f32_16x16x32_bf16 v[94:97], v[176:179], v[224:227], v[94:97]
	v_mfma_f32_16x16x32_bf16 v[90:93], v[184:187], v[224:227], v[90:93]
	v_mfma_f32_16x16x32_bf16 v[78:81], v[176:179], v[232:235], v[78:81]
	v_mfma_f32_16x16x32_bf16 v[74:77], v[184:187], v[232:235], v[74:77]
	v_mfma_f32_16x16x32_bf16 v[118:121], v[188:191], v[204:207], v[118:121]
	v_mfma_f32_16x16x32_bf16 v[114:117], v[196:199], v[204:207], v[114:117]
	v_mfma_f32_16x16x32_bf16 v[102:105], v[188:191], v[212:215], v[102:105]
	v_mfma_f32_16x16x32_bf16 v[98:101], v[196:199], v[212:215], v[98:101]
	v_mfma_f32_16x16x32_bf16 v[86:89], v[188:191], v[220:223], v[86:89]
	v_mfma_f32_16x16x32_bf16 v[82:85], v[196:199], v[220:223], v[82:85]
	v_mfma_f32_16x16x32_bf16 v[70:73], v[188:191], v[228:231], v[70:73]
	v_mfma_f32_16x16x32_bf16 v[66:69], v[196:199], v[228:231], v[66:69]
	v_mfma_f32_16x16x32_bf16 v[118:121], v[192:195], v[208:211], v[118:121]
	v_mfma_f32_16x16x32_bf16 v[114:117], v[200:203], v[208:211], v[114:117]
	v_mfma_f32_16x16x32_bf16 v[102:105], v[192:195], v[216:219], v[102:105]
	v_mfma_f32_16x16x32_bf16 v[98:101], v[200:203], v[216:219], v[98:101]
	v_mfma_f32_16x16x32_bf16 v[86:89], v[192:195], v[224:227], v[86:89]
	v_mfma_f32_16x16x32_bf16 v[82:85], v[200:203], v[224:227], v[82:85]
	v_mfma_f32_16x16x32_bf16 v[70:73], v[192:195], v[232:235], v[70:73]
	v_mfma_f32_16x16x32_bf16 v[66:69], v[200:203], v[232:235], v[66:69]
	s_barrier
	s_mov_b32 m0, s52
	s_add_u32 s58, s34, 0x4000
	ds_read_b128 v[204:207], v170 offset:16384
	ds_read_b128 v[208:211], v170 offset:17408
	ds_read_b128 v[212:215], v170 offset:18432
	ds_read_b128 v[216:219], v170 offset:19456
	global_load_lds_dwordx4 v134, s[34:35]
	s_mov_b32 m0, s53
	s_addc_u32 s59, s35, 0
	s_add_i32 s62, s73, s40
	global_load_lds_dwordx4 v130, s[34:35]
	s_mov_b32 m0, s62
	ds_read_b128 v[220:223], v170 offset:20480
	global_load_lds_dwordx4 v134, s[58:59]
	s_add_i32 m0, s62, 0x2000
	ds_read_b128 v[224:227], v170 offset:21504
	global_load_lds_dwordx4 v130, s[58:59]
	s_mov_b32 m0, s25
	ds_read_b128 v[228:231], v170 offset:22528
	global_load_lds_dwordx4 v136, s[36:37]
	s_mov_b32 m0, s43
	ds_read_b128 v[232:235], v170 offset:23552
	global_load_lds_dwordx4 v132, s[36:37]
	s_waitcnt vmcnt(8) lgkmcnt(0)
	s_barrier
	v_mfma_f32_16x16x32_bf16 v[62:65], v[172:175], v[204:207], v[62:65]
	v_mfma_f32_16x16x32_bf16 v[58:61], v[180:183], v[204:207], v[58:61]
	v_mfma_f32_16x16x32_bf16 v[46:49], v[172:175], v[212:215], v[46:49]
	v_mfma_f32_16x16x32_bf16 v[42:45], v[180:183], v[212:215], v[42:45]
	v_mfma_f32_16x16x32_bf16 v[30:33], v[172:175], v[220:223], v[30:33]
	v_mfma_f32_16x16x32_bf16 v[26:29], v[180:183], v[220:223], v[26:29]
	v_mfma_f32_16x16x32_bf16 v[14:17], v[172:175], v[228:231], v[14:17]
	v_mfma_f32_16x16x32_bf16 v[10:13], v[180:183], v[228:231], v[10:13]
	v_mfma_f32_16x16x32_bf16 v[62:65], v[176:179], v[208:211], v[62:65]
	v_mfma_f32_16x16x32_bf16 v[58:61], v[184:187], v[208:211], v[58:61]
	v_mfma_f32_16x16x32_bf16 v[46:49], v[176:179], v[216:219], v[46:49]
	v_mfma_f32_16x16x32_bf16 v[42:45], v[184:187], v[216:219], v[42:45]
	v_mfma_f32_16x16x32_bf16 v[30:33], v[176:179], v[224:227], v[30:33]
	v_mfma_f32_16x16x32_bf16 v[26:29], v[184:187], v[224:227], v[26:29]
	v_mfma_f32_16x16x32_bf16 v[14:17], v[176:179], v[232:235], v[14:17]
	v_mfma_f32_16x16x32_bf16 v[10:13], v[184:187], v[232:235], v[10:13]
	v_mfma_f32_16x16x32_bf16 v[54:57], v[188:191], v[204:207], v[54:57]
	v_mfma_f32_16x16x32_bf16 v[50:53], v[196:199], v[204:207], v[50:53]
	v_mfma_f32_16x16x32_bf16 v[38:41], v[188:191], v[212:215], v[38:41]
	v_mfma_f32_16x16x32_bf16 v[34:37], v[196:199], v[212:215], v[34:37]
	v_mfma_f32_16x16x32_bf16 v[22:25], v[188:191], v[220:223], v[22:25]
	v_mfma_f32_16x16x32_bf16 v[18:21], v[196:199], v[220:223], v[18:21]
	v_mfma_f32_16x16x32_bf16 v[6:9], v[188:191], v[228:231], v[6:9]
	v_mfma_f32_16x16x32_bf16 v[2:5], v[196:199], v[228:231], v[2:5]
	v_mfma_f32_16x16x32_bf16 v[54:57], v[192:195], v[208:211], v[54:57]
	v_mfma_f32_16x16x32_bf16 v[50:53], v[200:203], v[208:211], v[50:53]
	v_mfma_f32_16x16x32_bf16 v[38:41], v[192:195], v[216:219], v[38:41]
	v_mfma_f32_16x16x32_bf16 v[34:37], v[200:203], v[216:219], v[34:37]
	v_mfma_f32_16x16x32_bf16 v[22:25], v[192:195], v[224:227], v[22:25]
	v_mfma_f32_16x16x32_bf16 v[18:21], v[200:203], v[224:227], v[18:21]
	v_mfma_f32_16x16x32_bf16 v[6:9], v[192:195], v[232:235], v[6:9]
	v_mfma_f32_16x16x32_bf16 v[2:5], v[200:203], v[232:235], v[2:5]
	s_barrier
; #define PG8_STAGE(bufoff, gbase, voff) do { _Pragma("unroll") for (int _i = 0; _i < 2; ++_i) \
;         __builtin_amdgcn_global_load_lds((const unsigned*)((const char*)(gbase) + (voff)[_i]), (LAS unsigned*)(lds + (bufoff) + ldsw + _i * 8192), 16, 0, 0); } while (0)
; #define PG8_LDA(dst, b, h) do { _Pragma("unroll") for (int m = 0; m < 4; ++m) _Pragma("unroll") for (int k = 0; k < 2; ++k) dst[m][k] = *(const LAS bf16x8*)(lds + PG8_SA(b, h) + aoff + m * 2048 + k * 1024); } while (0)
; #define PG8_LDB(dst, b, h) do { _Pragma("unroll") for (int n = 0; n < 2; ++n) _Pragma("unroll") for (int k = 0; k < 2; ++k) dst[n][k] = *(const LAS bf16x8*)(lds + PG8_SB(b, h) + boff + n * 2048 + k * 1024); } while (0)
; #define PG8_MMA(ai, bj, At, Bt) do { __builtin_amdgcn_s_setprio(1); _Pragma("unroll") for (int m = 0; m < 4; ++m) _Pragma("unroll") for (int n = 0; n < 2; ++n) _Pragma("unroll") for (int k = 0; k < 2; ++k) \
;         acc[ai][bj][m][n] = __builtin_amdgcn_mfma_f32_16x16x32_bf16(Bt[n][k], At[m][k], acc[ai][bj][m][n], 0, 0, 0); __builtin_amdgcn_s_setprio(0); } while (0)
; #define PG8_WAIT_V(n) asm volatile("s_waitcnt vmcnt(" #n ")" ::: "memory")
; #define PG8_WAIT_L(n) asm volatile("s_waitcnt lgkmcnt(" #n ")" ::: "memory")
; #define PG8_BAR __builtin_amdgcn_s_barrier()
; #define PG8_SCHED __builtin_amdgcn_sched_barrier(0)
; template <class Epi, class Sched, bool ABLK = false, bool ALIGN_EPI = true, bool SP2 = true, bool BBLK = true>
; __device__ __forceinline__ void gemm_phase(LAS unsigned char* lds, const Gemm g, const Sched& S, const Epi& E) {
;     ...
;             PG8_LDB(B0, 1, 0); PG8_LDB(B1, 1, 1); PG8_SCHED; PG8_LDA(At, 1, 0); PG8_STAGE(PG8_SA(0, 1), a2 + hstepA, voffA);
;             PG8_WAIT_V(8); PG8_WAIT_L(0); PG8_BAR; PG8_MMA(0, 0, At, B0); PG8_MMA(0, 1, At, B1); PG8_BAR; PG8_SCHED;
;             PG8_LDA(At, 1, 1); PG8_STAGE(PG8_SB(1, 0), b3, voffB); PG8_STAGE(PG8_SB(1, 1), b3 + hstepB, voffB); PG8_STAGE(PG8_SA(1, 0), a3, voffA);
;             PG8_WAIT_V(8); PG8_WAIT_L(0); PG8_BAR; PG8_MMA(1, 0, At, B0); PG8_MMA(1, 1, At, B1); PG8_BAR; PG8_SCHED;
;     ...
;         }
;         if constexpr (ALIGN_EPI) { if (wr == 0) PG8_BAR; }
	v_add_u32_e32 v171, s60, v1
	ds_read_b128 v[172:175], v171
	ds_read_b128 v[176:179], v171 offset:1024
	ds_read_b128 v[180:183], v171 offset:2048
	ds_read_b128 v[184:187], v171 offset:3072
	v_add_u32_e32 v171, s61, v1
	ds_read_b128 v[188:191], v171
	ds_read_b128 v[192:195], v171 offset:1024
	ds_read_b128 v[196:199], v171 offset:2048
	ds_read_b128 v[200:203], v171 offset:3072
	s_add_u32 s36, s36, 0x80000
	s_addc_u32 s37, s37, 0
	s_mov_b32 m0, s44
	ds_read_b128 v[204:207], v170 offset:32768
	ds_read_b128 v[208:211], v170 offset:33792
	ds_read_b128 v[212:215], v170 offset:34816
	ds_read_b128 v[216:219], v170 offset:35840
	ds_read_b128 v[220:223], v170 offset:36864
	ds_read_b128 v[224:227], v170 offset:37888
	ds_read_b128 v[228:231], v170 offset:38912
	global_load_lds_dwordx4 v136, s[36:37]
	s_mov_b32 m0, s45
	ds_read_b128 v[232:235], v170 offset:39936
	global_load_lds_dwordx4 v132, s[36:37]
	s_waitcnt vmcnt(8) lgkmcnt(0)
	s_barrier
	v_mfma_f32_16x16x32_bf16 v[126:129], v[172:175], v[204:207], v[126:129]
	v_mfma_f32_16x16x32_bf16 v[122:125], v[180:183], v[204:207], v[122:125]
	v_mfma_f32_16x16x32_bf16 v[110:113], v[172:175], v[212:215], v[110:113]
	v_mfma_f32_16x16x32_bf16 v[106:109], v[180:183], v[212:215], v[106:109]
	v_mfma_f32_16x16x32_bf16 v[94:97], v[172:175], v[220:223], v[94:97]
	v_mfma_f32_16x16x32_bf16 v[90:93], v[180:183], v[220:223], v[90:93]
	v_mfma_f32_16x16x32_bf16 v[78:81], v[172:175], v[228:231], v[78:81]
	v_mfma_f32_16x16x32_bf16 v[74:77], v[180:183], v[228:231], v[74:77]
	v_mfma_f32_16x16x32_bf16 v[126:129], v[176:179], v[208:211], v[126:129]
	v_mfma_f32_16x16x32_bf16 v[122:125], v[184:187], v[208:211], v[122:125]
	v_mfma_f32_16x16x32_bf16 v[110:113], v[176:179], v[216:219], v[110:113]
	v_mfma_f32_16x16x32_bf16 v[106:109], v[184:187], v[216:219], v[106:109]
	v_mfma_f32_16x16x32_bf16 v[94:97], v[176:179], v[224:227], v[94:97]
	v_mfma_f32_16x16x32_bf16 v[90:93], v[184:187], v[224:227], v[90:93]
	v_mfma_f32_16x16x32_bf16 v[78:81], v[176:179], v[232:235], v[78:81]
	v_mfma_f32_16x16x32_bf16 v[74:77], v[184:187], v[232:235], v[74:77]
	v_mfma_f32_16x16x32_bf16 v[118:121], v[188:191], v[204:207], v[118:121]
	v_mfma_f32_16x16x32_bf16 v[114:117], v[196:199], v[204:207], v[114:117]
	v_mfma_f32_16x16x32_bf16 v[102:105], v[188:191], v[212:215], v[102:105]
	v_mfma_f32_16x16x32_bf16 v[98:101], v[196:199], v[212:215], v[98:101]
	v_mfma_f32_16x16x32_bf16 v[86:89], v[188:191], v[220:223], v[86:89]
	v_mfma_f32_16x16x32_bf16 v[82:85], v[196:199], v[220:223], v[82:85]
	v_mfma_f32_16x16x32_bf16 v[70:73], v[188:191], v[228:231], v[70:73]
	v_mfma_f32_16x16x32_bf16 v[66:69], v[196:199], v[228:231], v[66:69]
	v_mfma_f32_16x16x32_bf16 v[118:121], v[192:195], v[208:211], v[118:121]
	v_mfma_f32_16x16x32_bf16 v[114:117], v[200:203], v[208:211], v[114:117]
	v_mfma_f32_16x16x32_bf16 v[102:105], v[192:195], v[216:219], v[102:105]
	v_mfma_f32_16x16x32_bf16 v[98:101], v[200:203], v[216:219], v[98:101]
	v_mfma_f32_16x16x32_bf16 v[86:89], v[192:195], v[224:227], v[86:89]
	v_mfma_f32_16x16x32_bf16 v[82:85], v[200:203], v[224:227], v[82:85]
	v_mfma_f32_16x16x32_bf16 v[70:73], v[192:195], v[232:235], v[70:73]
	v_mfma_f32_16x16x32_bf16 v[66:69], v[200:203], v[232:235], v[66:69]
	s_barrier
	s_add_u32 s36, s34, 0x8000
	s_addc_u32 s37, s35, 0
	s_add_i32 s58, s60, s40
	s_mov_b32 m0, s58
	ds_read_b128 v[204:207], v170 offset:49152
	ds_read_b128 v[208:211], v170 offset:50176
	ds_read_b128 v[212:215], v170 offset:51200
	ds_read_b128 v[216:219], v170 offset:52224
	global_load_lds_dwordx4 v134, s[36:37]
	s_add_i32 m0, s58, 0x2000
	s_add_u32 s34, s34, 0xc000
	v_lshl_add_u64 v[236:237], s[36:37], 0, v[130:131]
	s_addc_u32 s35, s35, 0
	s_add_i32 s36, s61, s40
	global_load_lds_dwordx4 v[236:237], off
	s_mov_b32 m0, s36
	ds_read_b128 v[220:223], v170 offset:53248
	global_load_lds_dwordx4 v134, s[34:35]
	s_add_i32 m0, s36, 0x2000
	ds_read_b128 v[224:227], v170 offset:54272
	global_load_lds_dwordx4 v130, s[34:35]
	s_mov_b32 m0, s48
	ds_read_b128 v[228:231], v170 offset:55296
	global_load_lds_dwordx4 v136, s[30:31]
	s_mov_b32 m0, s49
	ds_read_b128 v[232:235], v170 offset:56320
	global_load_lds_dwordx4 v132, s[30:31]
	s_waitcnt vmcnt(8) lgkmcnt(0)
	s_barrier
	v_mfma_f32_16x16x32_bf16 v[62:65], v[172:175], v[204:207], v[62:65]
	v_mfma_f32_16x16x32_bf16 v[58:61], v[180:183], v[204:207], v[58:61]
	v_mfma_f32_16x16x32_bf16 v[46:49], v[172:175], v[212:215], v[46:49]
	v_mfma_f32_16x16x32_bf16 v[42:45], v[180:183], v[212:215], v[42:45]
	v_mfma_f32_16x16x32_bf16 v[30:33], v[172:175], v[220:223], v[30:33]
	v_mfma_f32_16x16x32_bf16 v[26:29], v[180:183], v[220:223], v[26:29]
	v_mfma_f32_16x16x32_bf16 v[14:17], v[172:175], v[228:231], v[14:17]
	v_mfma_f32_16x16x32_bf16 v[10:13], v[180:183], v[228:231], v[10:13]
	v_mfma_f32_16x16x32_bf16 v[62:65], v[176:179], v[208:211], v[62:65]
	v_mfma_f32_16x16x32_bf16 v[58:61], v[184:187], v[208:211], v[58:61]
	v_mfma_f32_16x16x32_bf16 v[46:49], v[176:179], v[216:219], v[46:49]
	v_mfma_f32_16x16x32_bf16 v[42:45], v[184:187], v[216:219], v[42:45]
	v_mfma_f32_16x16x32_bf16 v[30:33], v[176:179], v[224:227], v[30:33]
	v_mfma_f32_16x16x32_bf16 v[26:29], v[184:187], v[224:227], v[26:29]
	v_mfma_f32_16x16x32_bf16 v[14:17], v[176:179], v[232:235], v[14:17]
	v_mfma_f32_16x16x32_bf16 v[10:13], v[184:187], v[232:235], v[10:13]
	v_mfma_f32_16x16x32_bf16 v[54:57], v[188:191], v[204:207], v[54:57]
	v_mfma_f32_16x16x32_bf16 v[50:53], v[196:199], v[204:207], v[50:53]
	v_mfma_f32_16x16x32_bf16 v[38:41], v[188:191], v[212:215], v[38:41]
	v_mfma_f32_16x16x32_bf16 v[34:37], v[196:199], v[212:215], v[34:37]
	v_mfma_f32_16x16x32_bf16 v[22:25], v[188:191], v[220:223], v[22:25]
	v_mfma_f32_16x16x32_bf16 v[18:21], v[196:199], v[220:223], v[18:21]
	v_mfma_f32_16x16x32_bf16 v[6:9], v[188:191], v[228:231], v[6:9]
	v_mfma_f32_16x16x32_bf16 v[2:5], v[196:199], v[228:231], v[2:5]
	v_mfma_f32_16x16x32_bf16 v[54:57], v[192:195], v[208:211], v[54:57]
	v_mfma_f32_16x16x32_bf16 v[50:53], v[200:203], v[208:211], v[50:53]
	v_mfma_f32_16x16x32_bf16 v[38:41], v[192:195], v[216:219], v[38:41]
	v_mfma_f32_16x16x32_bf16 v[34:37], v[200:203], v[216:219], v[34:37]
	v_mfma_f32_16x16x32_bf16 v[22:25], v[192:195], v[224:227], v[22:25]
	v_mfma_f32_16x16x32_bf16 v[18:21], v[200:203], v[224:227], v[18:21]
	v_mfma_f32_16x16x32_bf16 v[6:9], v[192:195], v[232:235], v[6:9]
	v_mfma_f32_16x16x32_bf16 v[2:5], v[200:203], v[232:235], v[2:5]
	s_barrier
	s_add_i32 s57, s57, 2
	s_add_u32 s28, s28, 0x100
	s_addc_u32 s29, s29, 0
	s_add_u32 s55, s55, 0x10000
	s_addc_u32 s56, s56, 0
	s_cmp_gt_u32 s57, 29
	s_cbranch_scc0 .LBB0_2263
	s_and_b64 vcc, exec, s[10:11]
	s_cbranch_vccz .LBB0_2266
	s_barrier

; #define PG8_STAGE(bufoff, gbase, voff) do { _Pragma("unroll") for (int _i = 0; _i < 2; ++_i) \
;         __builtin_amdgcn_global_load_lds((const unsigned*)((const char*)(gbase) + (voff)[_i]), (LAS unsigned*)(lds + (bufoff) + ldsw + _i * 8192), 16, 0, 0); } while (0)
; #define PG8_LDA(dst, b, h) do { _Pragma("unroll") for (int m = 0; m < 4; ++m) _Pragma("unroll") for (int k = 0; k < 2; ++k) dst[m][k] = *(const LAS bf16x8*)(lds + PG8_SA(b, h) + aoff + m * 2048 + k * 1024); } while (0)
; template <class Epi, class Sched, bool ABLK = false, bool ALIGN_EPI = true, bool SP2 = true, bool BBLK = true>
; __device__ __forceinline__ void gemm_phase(LAS unsigned char* lds, const Gemm g, const Sched& S, const Epi& E) {
;     ...
;     auto a_unit = [&](const Unit& u) -> const char* { return ABLK ? (const char*)g.A + (size_t)u.pm * ((size_t)g.lda / 64) * 32768 : (const char*)g.A + (size_t)u.pm * 2 * hstepA; };
;     auto a_tile = [&](const char* ub, int tau) -> const char* { return ub + (size_t)tau * (ABLK ? (size_t)32768 : kstep); };
;     const char* uA = a_unit(cur); int tbA = cur.k0 / BK;
;     const char* cA = a_tile(uA, tbA); const char* cB = (const char*)g.Bt + (size_t)cur.pn * tstepB + b_k0(cur.k0);
;     ...
;         const bool has_next = S.next(ui + 1, nxt);
;         const int nt = cur.nt;
;         const char* nuA = has_next ? a_unit(nxt) : uA; const int ntbA = has_next ? nxt.k0 / BK : tbA; const char* nB = has_next ? (const char*)g.Bt + (size_t)nxt.pn * tstepB + b_k0(nxt.k0) : cB;
;         for (int t = 0; t < nt; t += 2) {
;             const bool last = (t == nt - 2);
;             const char* a1 = a_tile(uA, tbA + t + 1);
;             const char* a2 = last ? a_tile(nuA, ntbA) : a_tile(uA, tbA + t + 2); const char* b2 = last ? nB : cB + (size_t)(t + 2) * kstepB;
;             const char* a3 = last ? a_tile(nuA, ntbA + 1) : a_tile(uA, tbA + t + 3); const char* b3 = b2 + kstepB;
;             if (last && has_next) S.a_ready(nxt);
;             if constexpr (SP2) {
;             PG8_LDB(B0, 0, 0); PG8_LDB(B1, 0, 1); PG8_SCHED; PG8_LDA(At, 0, 0); PG8_STAGE(PG8_SA(1, 1), a1 + hstepA, voffA);
;             PG8_WAIT_V(8); PG8_WAIT_L(0); PG8_BAR; PG8_MMA(0, 0, At, B0); PG8_MMA(0, 1, At, B1); PG8_BAR; PG8_SCHED;
;             PG8_LDA(At, 0, 1); PG8_STAGE(PG8_SB(0, 0), b2, voffB); PG8_STAGE(PG8_SB(0, 1), b2 + hstepB, voffB); PG8_STAGE(PG8_SA(0, 0), a2, voffA);
.LBB0_2327:
	s_ashr_i32 s81, s80, 31
	s_andn2_b64 vcc, exec, s[4:5]
	s_lshl_b64 s[30:31], s[80:81], 22
	s_add_u32 s30, s1, s30
	s_addc_u32 s31, s33, s31
	s_and_b64 s[34:35], s[4:5], exec
	s_cselect_b32 s43, s31, s41
	s_cselect_b32 s57, s30, s40
	s_ashr_i32 s34, s0, 31
	s_lshr_b32 s34, s34, 26
	s_add_i32 s34, s0, s34
	s_ashr_i32 s34, s34, 6
	s_and_b64 s[36:37], s[4:5], exec
	s_cselect_b32 s44, s34, s42
	s_ashr_i32 s79, s78, 31
	s_lshl_b64 s[36:37], s[78:79], 22
	s_add_u32 s45, s46, s36
	s_addc_u32 s58, s47, s37
	s_ashr_i32 s35, s34, 31
	s_lshl_b64 s[36:37], s[34:35], 15
	s_add_u32 s36, s45, s36
	s_addc_u32 s37, s58, s37
	v_cndmask_b32_e64 v2, 0, 1, s[4:5]
	s_and_b64 s[4:5], s[4:5], exec
	s_cselect_b32 s4, s37, s39
	s_cselect_b32 s5, s36, s38
	s_ashr_i32 s45, s44, 31
	s_lshl_b64 s[44:45], s[44:45], 15
	s_add_u32 s35, s57, s44
	s_addc_u32 s57, s43, s45
	s_add_u32 s58, s35, 0x8000
	s_addc_u32 s59, s57, 0
	s_add_u32 s62, s38, 0x10000
	s_addc_u32 s63, s39, 0
	s_ashr_i32 s43, s42, 31
	v_cmp_ne_u32_e64 s[6:7], 1, v2
	s_lshl_b64 s[38:39], s[42:43], 15
	v_lshl_add_u64 v[2:3], s[40:41], 0, v[138:139]
	s_add_u32 s64, s40, s38
	v_lshl_add_u64 v[142:143], v[2:3], 0, s[38:39]
	v_lshl_add_u64 v[2:3], s[40:41], 0, v[140:141]
	s_addc_u32 s65, s41, s39
	v_lshl_add_u64 v[144:145], v[2:3], 0, s[38:39]
	s_lshl_b32 s38, s56, 15
	s_add_i32 s38, s38, 0xfff00000
	v_mov_b32_e32 v2, 0
	s_add_u32 s66, s38, 0xf0000
	s_mov_b32 s67, 0
	s_mov_b64 s[38:39], 0
	ds_read_b128 v[152:155], v148
	ds_read_b128 v[156:159], v148 offset:1024
	ds_read_b128 v[160:163], v148 offset:2048
	ds_read_b128 v[164:167], v148 offset:3072
	ds_read_b128 v[168:171], v149
	ds_read_b128 v[172:175], v149 offset:1024
	ds_read_b128 v[176:179], v149 offset:2048
	ds_read_b128 v[180:183], v149 offset:3072
	s_add_u32 s40, s64, s38
	s_addc_u32 s41, s65, s39
	s_add_u32 s44, s40, 0x10000
	s_addc_u32 s45, s41, 0
	s_add_i32 s67, s67, 2
	s_add_u32 s42, s62, s38
	s_addc_u32 s43, s63, s39
	s_add_u32 s40, s40, 0x18000
	s_addc_u32 s41, s41, 0
	s_cmp_eq_u32 s66, s38
	s_cselect_b32 s41, s59, s41
	s_cselect_b32 s40, s58, s40
	s_cselect_b32 s43, s4, s43
	s_cselect_b32 s42, s5, s42
	s_cselect_b32 s45, s57, s45
	s_cselect_b32 s44, s35, s44
	v_lshl_add_u64 v[216:217], v[142:143], 0, s[38:39]
	s_add_i32 m0, s49, 0xc000
	ds_read_b128 v[184:187], v150
	ds_read_b128 v[188:191], v150 offset:1024
	ds_read_b128 v[192:195], v150 offset:2048
	ds_read_b128 v[196:199], v150 offset:3072
	ds_read_b128 v[200:203], v150 offset:4096
	ds_read_b128 v[204:207], v150 offset:5120
	ds_read_b128 v[208:211], v150 offset:6144
	global_load_lds_dwordx4 v[216:217], off
	v_lshl_add_u64 v[216:217], v[144:145], 0, s[38:39]
	s_add_i32 m0, s49, 0xe000
	ds_read_b128 v[212:215], v150 offset:7168
	global_load_lds_dwordx4 v[216:217], off
	s_waitcnt vmcnt(8) lgkmcnt(0)
	s_barrier
	v_mfma_f32_16x16x32_bf16 v[126:129], v[152:155], v[184:187], 0
	v_mfma_f32_16x16x32_bf16 v[122:125], v[160:163], v[184:187], 0
	v_mfma_f32_16x16x32_bf16 v[110:113], v[152:155], v[192:195], 0
	v_mfma_f32_16x16x32_bf16 v[106:109], v[160:163], v[192:195], 0
	v_mfma_f32_16x16x32_bf16 v[94:97], v[152:155], v[200:203], 0
	v_mfma_f32_16x16x32_bf16 v[90:93], v[160:163], v[200:203], 0
	v_mfma_f32_16x16x32_bf16 v[78:81], v[152:155], v[208:211], 0
	v_mfma_f32_16x16x32_bf16 v[74:77], v[160:163], v[208:211], 0
	v_mfma_f32_16x16x32_bf16 v[126:129], v[156:159], v[188:191], v[126:129]
	v_mfma_f32_16x16x32_bf16 v[122:125], v[164:167], v[188:191], v[122:125]
	v_mfma_f32_16x16x32_bf16 v[110:113], v[156:159], v[196:199], v[110:113]
	v_mfma_f32_16x16x32_bf16 v[106:109], v[164:167], v[196:199], v[106:109]
	v_mfma_f32_16x16x32_bf16 v[94:97], v[156:159], v[204:207], v[94:97]
	v_mfma_f32_16x16x32_bf16 v[90:93], v[164:167], v[204:207], v[90:93]
	v_mfma_f32_16x16x32_bf16 v[78:81], v[156:159], v[212:215], v[78:81]
	v_mfma_f32_16x16x32_bf16 v[74:77], v[164:167], v[212:215], v[74:77]
	v_mfma_f32_16x16x32_bf16 v[118:121], v[168:171], v[184:187], 0
	v_mfma_f32_16x16x32_bf16 v[114:117], v[176:179], v[184:187], 0
	v_mfma_f32_16x16x32_bf16 v[102:105], v[168:171], v[192:195], 0
	v_mfma_f32_16x16x32_bf16 v[98:101], v[176:179], v[192:195], 0
	v_mfma_f32_16x16x32_bf16 v[86:89], v[168:171], v[200:203], 0
	v_mfma_f32_16x16x32_bf16 v[82:85], v[176:179], v[200:203], 0
	v_mfma_f32_16x16x32_bf16 v[70:73], v[168:171], v[208:211], 0
	v_mfma_f32_16x16x32_bf16 v[66:69], v[176:179], v[208:211], 0
	v_mfma_f32_16x16x32_bf16 v[118:121], v[172:175], v[188:191], v[118:121]
	v_mfma_f32_16x16x32_bf16 v[114:117], v[180:183], v[188:191], v[114:117]
	v_mfma_f32_16x16x32_bf16 v[102:105], v[172:175], v[196:199], v[102:105]
	v_mfma_f32_16x16x32_bf16 v[98:101], v[180:183], v[196:199], v[98:101]
	v_mfma_f32_16x16x32_bf16 v[86:89], v[172:175], v[204:207], v[86:89]
	v_mfma_f32_16x16x32_bf16 v[82:85], v[180:183], v[204:207], v[82:85]
	v_mfma_f32_16x16x32_bf16 v[70:73], v[172:175], v[212:215], v[70:73]
	v_mfma_f32_16x16x32_bf16 v[66:69], v[180:183], v[212:215], v[66:69]
	s_barrier
	s_add_i32 s70, s72, s48
	s_mov_b32 m0, s70
	ds_read_b128 v[184:187], v150 offset:16384
	ds_read_b128 v[188:191], v150 offset:17408
	ds_read_b128 v[192:195], v150 offset:18432
	ds_read_b128 v[196:199], v150 offset:19456
	global_load_lds_dwordx4 v130, s[42:43]
	s_add_i32 m0, s70, 0x2000
	s_add_u32 s76, s42, 0x4000
	s_addc_u32 s77, s43, 0
	s_add_i32 s70, s73, s48
	global_load_lds_dwordx4 v132, s[42:43]
	s_mov_b32 m0, s70
	ds_read_b128 v[200:203], v150 offset:20480
	global_load_lds_dwordx4 v130, s[76:77]
	s_add_i32 m0, s70, 0x2000
	ds_read_b128 v[204:207], v150 offset:21504
	global_load_lds_dwordx4 v132, s[76:77]
	s_mov_b32 m0, s49
	ds_read_b128 v[208:211], v150 offset:22528
	global_load_lds_dwordx4 v130, s[44:45]
	s_mov_b32 m0, s50
	ds_read_b128 v[212:215], v150 offset:23552
	global_load_lds_dwordx4 v132, s[44:45]
	s_waitcnt vmcnt(8) lgkmcnt(0)
	s_barrier
; #define PG8_STAGE(bufoff, gbase, voff) do { _Pragma("unroll") for (int _i = 0; _i < 2; ++_i) \
;         __builtin_amdgcn_global_load_lds((const unsigned*)((const char*)(gbase) + (voff)[_i]), (LAS unsigned*)(lds + (bufoff) + ldsw + _i * 8192), 16, 0, 0); } while (0)
; #define PG8_LDA(dst, b, h) do { _Pragma("unroll") for (int m = 0; m < 4; ++m) _Pragma("unroll") for (int k = 0; k < 2; ++k) dst[m][k] = *(const LAS bf16x8*)(lds + PG8_SA(b, h) + aoff + m * 2048 + k * 1024); } while (0)
; #define PG8_LDB(dst, b, h) do { _Pragma("unroll") for (int n = 0; n < 2; ++n) _Pragma("unroll") for (int k = 0; k < 2; ++k) dst[n][k] = *(const LAS bf16x8*)(lds + PG8_SB(b, h) + boff + n * 2048 + k * 1024); } while (0)
; #define PG8_MMA(ai, bj, At, Bt) do { __builtin_amdgcn_s_setprio(1); _Pragma("unroll") for (int m = 0; m < 4; ++m) _Pragma("unroll") for (int n = 0; n < 2; ++n) _Pragma("unroll") for (int k = 0; k < 2; ++k) \
;         acc[ai][bj][m][n] = __builtin_amdgcn_mfma_f32_16x16x32_bf16(Bt[n][k], At[m][k], acc[ai][bj][m][n], 0, 0, 0); __builtin_amdgcn_s_setprio(0); } while (0)
; #define PG8_WAIT_V(n) asm volatile("s_waitcnt vmcnt(" #n ")" ::: "memory")
; #define PG8_WAIT_L(n) asm volatile("s_waitcnt lgkmcnt(" #n ")" ::: "memory")
; #define PG8_BAR __builtin_amdgcn_s_barrier()
; #define PG8_SCHED __builtin_amdgcn_sched_barrier(0)
; template <class Epi, class Sched, bool ABLK = false, bool ALIGN_EPI = true, bool SP2 = true, bool BBLK = true>
; __device__ __forceinline__ void gemm_phase(LAS unsigned char* lds, const Gemm g, const Sched& S, const Epi& E) {
;     ...
;             PG8_WAIT_V(8); PG8_WAIT_L(0); PG8_BAR; PG8_MMA(1, 0, At, B0); PG8_MMA(1, 1, At, B1); PG8_BAR; PG8_SCHED;
;             PG8_LDB(B0, 1, 0); PG8_LDB(B1, 1, 1); PG8_SCHED; PG8_LDA(At, 1, 0); PG8_STAGE(PG8_SA(0, 1), a2 + hstepA, voffA);
;             PG8_WAIT_V(8); PG8_WAIT_L(0); PG8_BAR; PG8_MMA(0, 0, At, B0); PG8_MMA(0, 1, At, B1); PG8_BAR; PG8_SCHED;
	v_mfma_f32_16x16x32_bf16 v[62:65], v[152:155], v[184:187], 0
	v_mfma_f32_16x16x32_bf16 v[58:61], v[160:163], v[184:187], 0
	v_mfma_f32_16x16x32_bf16 v[46:49], v[152:155], v[192:195], 0
	v_mfma_f32_16x16x32_bf16 v[42:45], v[160:163], v[192:195], 0
	v_mfma_f32_16x16x32_bf16 v[30:33], v[152:155], v[200:203], 0
	v_mfma_f32_16x16x32_bf16 v[26:29], v[160:163], v[200:203], 0
	v_mfma_f32_16x16x32_bf16 v[14:17], v[152:155], v[208:211], 0
	v_mfma_f32_16x16x32_bf16 v[10:13], v[160:163], v[208:211], 0
	v_mfma_f32_16x16x32_bf16 v[62:65], v[156:159], v[188:191], v[62:65]
	v_mfma_f32_16x16x32_bf16 v[58:61], v[164:167], v[188:191], v[58:61]
	v_mfma_f32_16x16x32_bf16 v[46:49], v[156:159], v[196:199], v[46:49]
	v_mfma_f32_16x16x32_bf16 v[42:45], v[164:167], v[196:199], v[42:45]
	v_mfma_f32_16x16x32_bf16 v[30:33], v[156:159], v[204:207], v[30:33]
	v_mfma_f32_16x16x32_bf16 v[26:29], v[164:167], v[204:207], v[26:29]
	v_mfma_f32_16x16x32_bf16 v[14:17], v[156:159], v[212:215], v[14:17]
	v_mfma_f32_16x16x32_bf16 v[10:13], v[164:167], v[212:215], v[10:13]
	v_mfma_f32_16x16x32_bf16 v[54:57], v[168:171], v[184:187], 0
	v_mfma_f32_16x16x32_bf16 v[50:53], v[176:179], v[184:187], 0
	v_mfma_f32_16x16x32_bf16 v[38:41], v[168:171], v[192:195], 0
	v_mfma_f32_16x16x32_bf16 v[34:37], v[176:179], v[192:195], 0
	v_mfma_f32_16x16x32_bf16 v[22:25], v[168:171], v[200:203], 0
	v_mfma_f32_16x16x32_bf16 v[18:21], v[176:179], v[200:203], 0
	v_mfma_f32_16x16x32_bf16 v[6:9], v[168:171], v[208:211], 0
	v_mfma_f32_16x16x32_bf16 v[2:5], v[176:179], v[208:211], 0
	v_mfma_f32_16x16x32_bf16 v[54:57], v[172:175], v[188:191], v[54:57]
	v_mfma_f32_16x16x32_bf16 v[50:53], v[180:183], v[188:191], v[50:53]
	v_mfma_f32_16x16x32_bf16 v[38:41], v[172:175], v[196:199], v[38:41]
	v_mfma_f32_16x16x32_bf16 v[34:37], v[180:183], v[196:199], v[34:37]
	v_mfma_f32_16x16x32_bf16 v[22:25], v[172:175], v[204:207], v[22:25]
	v_mfma_f32_16x16x32_bf16 v[18:21], v[180:183], v[204:207], v[18:21]
	v_mfma_f32_16x16x32_bf16 v[6:9], v[172:175], v[212:215], v[6:9]
	v_mfma_f32_16x16x32_bf16 v[2:5], v[180:183], v[212:215], v[2:5]
	s_barrier
	v_add_u32_e32 v151, s60, v146
	ds_read_b128 v[152:155], v151
	ds_read_b128 v[156:159], v151 offset:1024
	ds_read_b128 v[160:163], v151 offset:2048
	ds_read_b128 v[164:167], v151 offset:3072
	v_add_u32_e32 v151, s61, v146
	ds_read_b128 v[168:171], v151
	ds_read_b128 v[172:175], v151 offset:1024
	ds_read_b128 v[176:179], v151 offset:2048
	ds_read_b128 v[180:183], v151 offset:3072
	s_add_u32 s44, s44, 0x4000
	s_addc_u32 s45, s45, 0
	s_mov_b32 m0, s51
	ds_read_b128 v[184:187], v150 offset:32768
	ds_read_b128 v[188:191], v150 offset:33792
	ds_read_b128 v[192:195], v150 offset:34816
	ds_read_b128 v[196:199], v150 offset:35840
	ds_read_b128 v[200:203], v150 offset:36864
	ds_read_b128 v[204:207], v150 offset:37888
	ds_read_b128 v[208:211], v150 offset:38912
	global_load_lds_dwordx4 v130, s[44:45]
	s_mov_b32 m0, s52
	ds_read_b128 v[212:215], v150 offset:39936
	global_load_lds_dwordx4 v132, s[44:45]
	s_waitcnt vmcnt(8) lgkmcnt(0)
	s_barrier
	v_mfma_f32_16x16x32_bf16 v[126:129], v[152:155], v[184:187], v[126:129]
	v_mfma_f32_16x16x32_bf16 v[122:125], v[160:163], v[184:187], v[122:125]
	v_mfma_f32_16x16x32_bf16 v[110:113], v[152:155], v[192:195], v[110:113]
	v_mfma_f32_16x16x32_bf16 v[106:109], v[160:163], v[192:195], v[106:109]
	v_mfma_f32_16x16x32_bf16 v[94:97], v[152:155], v[200:203], v[94:97]
	v_mfma_f32_16x16x32_bf16 v[90:93], v[160:163], v[200:203], v[90:93]
	v_mfma_f32_16x16x32_bf16 v[78:81], v[152:155], v[208:211], v[78:81]
	v_mfma_f32_16x16x32_bf16 v[74:77], v[160:163], v[208:211], v[74:77]
	v_mfma_f32_16x16x32_bf16 v[126:129], v[156:159], v[188:191], v[126:129]
	v_mfma_f32_16x16x32_bf16 v[122:125], v[164:167], v[188:191], v[122:125]
	v_mfma_f32_16x16x32_bf16 v[110:113], v[156:159], v[196:199], v[110:113]
	v_mfma_f32_16x16x32_bf16 v[106:109], v[164:167], v[196:199], v[106:109]
	v_mfma_f32_16x16x32_bf16 v[94:97], v[156:159], v[204:207], v[94:97]
	v_mfma_f32_16x16x32_bf16 v[90:93], v[164:167], v[204:207], v[90:93]
	v_mfma_f32_16x16x32_bf16 v[78:81], v[156:159], v[212:215], v[78:81]
	v_mfma_f32_16x16x32_bf16 v[74:77], v[164:167], v[212:215], v[74:77]
	v_mfma_f32_16x16x32_bf16 v[118:121], v[168:171], v[184:187], v[118:121]
	v_mfma_f32_16x16x32_bf16 v[114:117], v[176:179], v[184:187], v[114:117]
	v_mfma_f32_16x16x32_bf16 v[102:105], v[168:171], v[192:195], v[102:105]
	v_mfma_f32_16x16x32_bf16 v[98:101], v[176:179], v[192:195], v[98:101]
	v_mfma_f32_16x16x32_bf16 v[86:89], v[168:171], v[200:203], v[86:89]
	v_mfma_f32_16x16x32_bf16 v[82:85], v[176:179], v[200:203], v[82:85]
	v_mfma_f32_16x16x32_bf16 v[70:73], v[168:171], v[208:211], v[70:73]
	v_mfma_f32_16x16x32_bf16 v[66:69], v[176:179], v[208:211], v[66:69]
	v_mfma_f32_16x16x32_bf16 v[118:121], v[172:175], v[188:191], v[118:121]
	v_mfma_f32_16x16x32_bf16 v[114:117], v[180:183], v[188:191], v[114:117]
	v_mfma_f32_16x16x32_bf16 v[102:105], v[172:175], v[196:199], v[102:105]
	v_mfma_f32_16x16x32_bf16 v[98:101], v[180:183], v[196:199], v[98:101]
	v_mfma_f32_16x16x32_bf16 v[86:89], v[172:175], v[204:207], v[86:89]
	v_mfma_f32_16x16x32_bf16 v[82:85], v[180:183], v[204:207], v[82:85]
	v_mfma_f32_16x16x32_bf16 v[70:73], v[172:175], v[212:215], v[70:73]
	v_mfma_f32_16x16x32_bf16 v[66:69], v[180:183], v[212:215], v[66:69]
	s_barrier
; #define PG8_STAGE(bufoff, gbase, voff) do { _Pragma("unroll") for (int _i = 0; _i < 2; ++_i) \
;         __builtin_amdgcn_global_load_lds((const unsigned*)((const char*)(gbase) + (voff)[_i]), (LAS unsigned*)(lds + (bufoff) + ldsw + _i * 8192), 16, 0, 0); } while (0)
; #define PG8_LDA(dst, b, h) do { _Pragma("unroll") for (int m = 0; m < 4; ++m) _Pragma("unroll") for (int k = 0; k < 2; ++k) dst[m][k] = *(const LAS bf16x8*)(lds + PG8_SA(b, h) + aoff + m * 2048 + k * 1024); } while (0)
; #define PG8_WAIT_V(n) asm volatile("s_waitcnt vmcnt(" #n ")" ::: "memory")
; #define PG8_WAIT_L(n) asm volatile("s_waitcnt lgkmcnt(" #n ")" ::: "memory")
; template <class Epi, class Sched, bool ABLK = false, bool ALIGN_EPI = true, bool SP2 = true, bool BBLK = true>
; __device__ __forceinline__ void gemm_phase(LAS unsigned char* lds, const Gemm g, const Sched& S, const Epi& E) {
;     ...
;         for (int t = 0; t < nt; t += 2) {
;             const bool last = (t == nt - 2);
;             const char* a1 = a_tile(uA, tbA + t + 1);
;             const char* a2 = last ? a_tile(nuA, ntbA) : a_tile(uA, tbA + t + 2); const char* b2 = last ? nB : cB + (size_t)(t + 2) * kstepB;
;             const char* a3 = last ? a_tile(nuA, ntbA + 1) : a_tile(uA, tbA + t + 3); const char* b3 = b2 + kstepB;
;             if (last && has_next) S.a_ready(nxt);
;             if constexpr (SP2) {
;             PG8_LDB(B0, 0, 0); PG8_LDB(B1, 0, 1); PG8_SCHED; PG8_LDA(At, 0, 0); PG8_STAGE(PG8_SA(1, 1), a1 + hstepA, voffA);
;             PG8_WAIT_V(8); PG8_WAIT_L(0); PG8_BAR; PG8_MMA(0, 0, At, B0); PG8_MMA(0, 1, At, B1); PG8_BAR; PG8_SCHED;
;             PG8_LDA(At, 0, 1); PG8_STAGE(PG8_SB(0, 0), b2, voffB); PG8_STAGE(PG8_SB(0, 1), b2 + hstepB, voffB); PG8_STAGE(PG8_SA(0, 0), a2, voffA);
;             PG8_WAIT_V(8); PG8_WAIT_L(0); PG8_BAR; PG8_MMA(1, 0, At, B0); PG8_MMA(1, 1, At, B1); PG8_BAR; PG8_SCHED;
;             PG8_LDB(B0, 1, 0); PG8_LDB(B1, 1, 1); PG8_SCHED; PG8_LDA(At, 1, 0); PG8_STAGE(PG8_SA(0, 1), a2 + hstepA, voffA);
;             PG8_WAIT_V(8); PG8_WAIT_L(0); PG8_BAR; PG8_MMA(0, 0, At, B0); PG8_MMA(0, 1, At, B1); PG8_BAR; PG8_SCHED;
;             PG8_LDA(At, 1, 1); PG8_STAGE(PG8_SB(1, 0), b3, voffB); PG8_STAGE(PG8_SB(1, 1), b3 + hstepB, voffB); PG8_STAGE(PG8_SA(1, 0), a3, voffA);
;             PG8_WAIT_V(8); PG8_WAIT_L(0); PG8_BAR; PG8_MMA(1, 0, At, B0); PG8_MMA(1, 1, At, B1); PG8_BAR; PG8_SCHED;
	s_add_u32 s44, s42, 0x8000
	s_addc_u32 s45, s43, 0
	s_add_i32 s70, s60, s48
	s_mov_b32 m0, s70
	ds_read_b128 v[184:187], v150 offset:49152
	ds_read_b128 v[188:191], v150 offset:50176
	ds_read_b128 v[192:195], v150 offset:51200
	ds_read_b128 v[196:199], v150 offset:52224
	global_load_lds_dwordx4 v130, s[44:45]
	s_add_i32 m0, s70, 0x2000
	s_add_u32 s42, s42, 0xc000
	v_lshl_add_u64 v[216:217], s[44:45], 0, v[132:133]
	s_addc_u32 s43, s43, 0
	s_add_i32 s44, s61, s48
	global_load_lds_dwordx4 v[216:217], off
	s_mov_b32 m0, s44
	ds_read_b128 v[200:203], v150 offset:53248
	global_load_lds_dwordx4 v130, s[42:43]
	s_add_i32 m0, s44, 0x2000
	ds_read_b128 v[204:207], v150 offset:54272
	global_load_lds_dwordx4 v132, s[42:43]
	s_mov_b32 m0, s53
	ds_read_b128 v[208:211], v150 offset:55296
	global_load_lds_dwordx4 v130, s[40:41]
	s_mov_b32 m0, s54
	ds_read_b128 v[212:215], v150 offset:56320
	global_load_lds_dwordx4 v132, s[40:41]
	s_waitcnt vmcnt(8) lgkmcnt(0)
	s_barrier
	v_mfma_f32_16x16x32_bf16 v[62:65], v[152:155], v[184:187], v[62:65]
	v_mfma_f32_16x16x32_bf16 v[58:61], v[160:163], v[184:187], v[58:61]
	v_mfma_f32_16x16x32_bf16 v[46:49], v[152:155], v[192:195], v[46:49]
	v_mfma_f32_16x16x32_bf16 v[42:45], v[160:163], v[192:195], v[42:45]
	v_mfma_f32_16x16x32_bf16 v[30:33], v[152:155], v[200:203], v[30:33]
	v_mfma_f32_16x16x32_bf16 v[26:29], v[160:163], v[200:203], v[26:29]
	v_mfma_f32_16x16x32_bf16 v[14:17], v[152:155], v[208:211], v[14:17]
	v_mfma_f32_16x16x32_bf16 v[10:13], v[160:163], v[208:211], v[10:13]
	v_mfma_f32_16x16x32_bf16 v[62:65], v[156:159], v[188:191], v[62:65]
	v_mfma_f32_16x16x32_bf16 v[58:61], v[164:167], v[188:191], v[58:61]
	v_mfma_f32_16x16x32_bf16 v[46:49], v[156:159], v[196:199], v[46:49]
	v_mfma_f32_16x16x32_bf16 v[42:45], v[164:167], v[196:199], v[42:45]
	v_mfma_f32_16x16x32_bf16 v[30:33], v[156:159], v[204:207], v[30:33]
	v_mfma_f32_16x16x32_bf16 v[26:29], v[164:167], v[204:207], v[26:29]
	v_mfma_f32_16x16x32_bf16 v[14:17], v[156:159], v[212:215], v[14:17]
	v_mfma_f32_16x16x32_bf16 v[10:13], v[164:167], v[212:215], v[10:13]
	v_mfma_f32_16x16x32_bf16 v[54:57], v[168:171], v[184:187], v[54:57]
	v_mfma_f32_16x16x32_bf16 v[50:53], v[176:179], v[184:187], v[50:53]
	v_mfma_f32_16x16x32_bf16 v[38:41], v[168:171], v[192:195], v[38:41]
	v_mfma_f32_16x16x32_bf16 v[34:37], v[176:179], v[192:195], v[34:37]
	v_mfma_f32_16x16x32_bf16 v[22:25], v[168:171], v[200:203], v[22:25]
	v_mfma_f32_16x16x32_bf16 v[18:21], v[176:179], v[200:203], v[18:21]
	v_mfma_f32_16x16x32_bf16 v[6:9], v[168:171], v[208:211], v[6:9]
	v_mfma_f32_16x16x32_bf16 v[2:5], v[176:179], v[208:211], v[2:5]
	v_mfma_f32_16x16x32_bf16 v[54:57], v[172:175], v[188:191], v[54:57]
	v_mfma_f32_16x16x32_bf16 v[50:53], v[180:183], v[188:191], v[50:53]
	v_mfma_f32_16x16x32_bf16 v[38:41], v[172:175], v[196:199], v[38:41]
	v_mfma_f32_16x16x32_bf16 v[34:37], v[180:183], v[196:199], v[34:37]
	v_mfma_f32_16x16x32_bf16 v[22:25], v[172:175], v[204:207], v[22:25]
	v_mfma_f32_16x16x32_bf16 v[18:21], v[180:183], v[204:207], v[18:21]
	v_mfma_f32_16x16x32_bf16 v[6:9], v[172:175], v[212:215], v[6:9]
	v_mfma_f32_16x16x32_bf16 v[2:5], v[180:183], v[212:215], v[2:5]
	s_barrier
	s_add_u32 s38, s38, 0x10000
	s_addc_u32 s39, s39, 0
	s_cmp_ge_u32 s67, s56
.LBB0_2328:
	ds_read_b128 v[152:155], v148
	ds_read_b128 v[156:159], v148 offset:1024
	ds_read_b128 v[160:163], v148 offset:2048
	ds_read_b128 v[164:167], v148 offset:3072
	ds_read_b128 v[168:171], v149
	ds_read_b128 v[172:175], v149 offset:1024
	ds_read_b128 v[176:179], v149 offset:2048
	ds_read_b128 v[180:183], v149 offset:3072
	s_add_u32 s40, s64, s38
	s_addc_u32 s41, s65, s39
	s_add_u32 s44, s40, 0x10000
	s_addc_u32 s45, s41, 0
	s_add_i32 s67, s67, 2
	s_add_u32 s42, s62, s38
	s_addc_u32 s43, s63, s39
	s_add_u32 s40, s40, 0x18000
	s_addc_u32 s41, s41, 0
	s_cmp_eq_u32 s66, s38
	s_cselect_b32 s41, s59, s41
	s_cselect_b32 s40, s58, s40
	s_cselect_b32 s43, s4, s43
	s_cselect_b32 s42, s5, s42
	s_cselect_b32 s45, s57, s45
	s_cselect_b32 s44, s35, s44
	v_lshl_add_u64 v[216:217], v[142:143], 0, s[38:39]
	s_add_i32 m0, s49, 0xc000
	ds_read_b128 v[184:187], v150
	ds_read_b128 v[188:191], v150 offset:1024
	ds_read_b128 v[192:195], v150 offset:2048
	ds_read_b128 v[196:199], v150 offset:3072
	ds_read_b128 v[200:203], v150 offset:4096
	ds_read_b128 v[204:207], v150 offset:5120
	ds_read_b128 v[208:211], v150 offset:6144
	global_load_lds_dwordx4 v[216:217], off
	v_lshl_add_u64 v[216:217], v[144:145], 0, s[38:39]
	s_add_i32 m0, s49, 0xe000
	ds_read_b128 v[212:215], v150 offset:7168
	global_load_lds_dwordx4 v[216:217], off
	s_waitcnt vmcnt(8) lgkmcnt(0)
	s_barrier
; #define PG8_STAGE(bufoff, gbase, voff) do { _Pragma("unroll") for (int _i = 0; _i < 2; ++_i) \
;         __builtin_amdgcn_global_load_lds((const unsigned*)((const char*)(gbase) + (voff)[_i]), (LAS unsigned*)(lds + (bufoff) + ldsw + _i * 8192), 16, 0, 0); } while (0)
; #define PG8_LDA(dst, b, h) do { _Pragma("unroll") for (int m = 0; m < 4; ++m) _Pragma("unroll") for (int k = 0; k < 2; ++k) dst[m][k] = *(const LAS bf16x8*)(lds + PG8_SA(b, h) + aoff + m * 2048 + k * 1024); } while (0)
; #define PG8_MMA(ai, bj, At, Bt) do { __builtin_amdgcn_s_setprio(1); _Pragma("unroll") for (int m = 0; m < 4; ++m) _Pragma("unroll") for (int n = 0; n < 2; ++n) _Pragma("unroll") for (int k = 0; k < 2; ++k) \
;         acc[ai][bj][m][n] = __builtin_amdgcn_mfma_f32_16x16x32_bf16(Bt[n][k], At[m][k], acc[ai][bj][m][n], 0, 0, 0); __builtin_amdgcn_s_setprio(0); } while (0)
; #define PG8_WAIT_V(n) asm volatile("s_waitcnt vmcnt(" #n ")" ::: "memory")
; #define PG8_WAIT_L(n) asm volatile("s_waitcnt lgkmcnt(" #n ")" ::: "memory")
; #define PG8_BAR __builtin_amdgcn_s_barrier()
; #define PG8_SCHED __builtin_amdgcn_sched_barrier(0)
; template <class Epi, class Sched, bool ABLK = false, bool ALIGN_EPI = true, bool SP2 = true, bool BBLK = true>
; __device__ __forceinline__ void gemm_phase(LAS unsigned char* lds, const Gemm g, const Sched& S, const Epi& E) {
;     ...
;             PG8_WAIT_V(8); PG8_WAIT_L(0); PG8_BAR; PG8_MMA(0, 0, At, B0); PG8_MMA(0, 1, At, B1); PG8_BAR; PG8_SCHED;
;             PG8_LDA(At, 0, 1); PG8_STAGE(PG8_SB(0, 0), b2, voffB); PG8_STAGE(PG8_SB(0, 1), b2 + hstepB, voffB); PG8_STAGE(PG8_SA(0, 0), a2, voffA);
;             PG8_WAIT_V(8); PG8_WAIT_L(0); PG8_BAR; PG8_MMA(1, 0, At, B0); PG8_MMA(1, 1, At, B1); PG8_BAR; PG8_SCHED;
	v_mfma_f32_16x16x32_bf16 v[126:129], v[152:155], v[184:187], v[126:129]
	v_mfma_f32_16x16x32_bf16 v[122:125], v[160:163], v[184:187], v[122:125]
	v_mfma_f32_16x16x32_bf16 v[110:113], v[152:155], v[192:195], v[110:113]
	v_mfma_f32_16x16x32_bf16 v[106:109], v[160:163], v[192:195], v[106:109]
	v_mfma_f32_16x16x32_bf16 v[94:97], v[152:155], v[200:203], v[94:97]
	v_mfma_f32_16x16x32_bf16 v[90:93], v[160:163], v[200:203], v[90:93]
	v_mfma_f32_16x16x32_bf16 v[78:81], v[152:155], v[208:211], v[78:81]
	v_mfma_f32_16x16x32_bf16 v[74:77], v[160:163], v[208:211], v[74:77]
	v_mfma_f32_16x16x32_bf16 v[126:129], v[156:159], v[188:191], v[126:129]
	v_mfma_f32_16x16x32_bf16 v[122:125], v[164:167], v[188:191], v[122:125]
	v_mfma_f32_16x16x32_bf16 v[110:113], v[156:159], v[196:199], v[110:113]
	v_mfma_f32_16x16x32_bf16 v[106:109], v[164:167], v[196:199], v[106:109]
	v_mfma_f32_16x16x32_bf16 v[94:97], v[156:159], v[204:207], v[94:97]
	v_mfma_f32_16x16x32_bf16 v[90:93], v[164:167], v[204:207], v[90:93]
	v_mfma_f32_16x16x32_bf16 v[78:81], v[156:159], v[212:215], v[78:81]
	v_mfma_f32_16x16x32_bf16 v[74:77], v[164:167], v[212:215], v[74:77]
	v_mfma_f32_16x16x32_bf16 v[118:121], v[168:171], v[184:187], v[118:121]
	v_mfma_f32_16x16x32_bf16 v[114:117], v[176:179], v[184:187], v[114:117]
	v_mfma_f32_16x16x32_bf16 v[102:105], v[168:171], v[192:195], v[102:105]
	v_mfma_f32_16x16x32_bf16 v[98:101], v[176:179], v[192:195], v[98:101]
	v_mfma_f32_16x16x32_bf16 v[86:89], v[168:171], v[200:203], v[86:89]
	v_mfma_f32_16x16x32_bf16 v[82:85], v[176:179], v[200:203], v[82:85]
	v_mfma_f32_16x16x32_bf16 v[70:73], v[168:171], v[208:211], v[70:73]
	v_mfma_f32_16x16x32_bf16 v[66:69], v[176:179], v[208:211], v[66:69]
	v_mfma_f32_16x16x32_bf16 v[118:121], v[172:175], v[188:191], v[118:121]
	v_mfma_f32_16x16x32_bf16 v[114:117], v[180:183], v[188:191], v[114:117]
	v_mfma_f32_16x16x32_bf16 v[102:105], v[172:175], v[196:199], v[102:105]
	v_mfma_f32_16x16x32_bf16 v[98:101], v[180:183], v[196:199], v[98:101]
	v_mfma_f32_16x16x32_bf16 v[86:89], v[172:175], v[204:207], v[86:89]
	v_mfma_f32_16x16x32_bf16 v[82:85], v[180:183], v[204:207], v[82:85]
	v_mfma_f32_16x16x32_bf16 v[70:73], v[172:175], v[212:215], v[70:73]
	v_mfma_f32_16x16x32_bf16 v[66:69], v[180:183], v[212:215], v[66:69]
	s_barrier
	s_add_i32 s70, s72, s48
	s_mov_b32 m0, s70
	ds_read_b128 v[184:187], v150 offset:16384
	ds_read_b128 v[188:191], v150 offset:17408
	ds_read_b128 v[192:195], v150 offset:18432
	ds_read_b128 v[196:199], v150 offset:19456
	global_load_lds_dwordx4 v130, s[42:43]
	s_add_i32 m0, s70, 0x2000
	s_add_u32 s76, s42, 0x4000
	s_addc_u32 s77, s43, 0
	s_add_i32 s70, s73, s48
	global_load_lds_dwordx4 v132, s[42:43]
	s_mov_b32 m0, s70
	ds_read_b128 v[200:203], v150 offset:20480
	global_load_lds_dwordx4 v130, s[76:77]
	s_add_i32 m0, s70, 0x2000
	ds_read_b128 v[204:207], v150 offset:21504
	global_load_lds_dwordx4 v132, s[76:77]
	s_mov_b32 m0, s49
	ds_read_b128 v[208:211], v150 offset:22528
	global_load_lds_dwordx4 v130, s[44:45]
	s_mov_b32 m0, s50
	ds_read_b128 v[212:215], v150 offset:23552
	global_load_lds_dwordx4 v132, s[44:45]
	s_waitcnt vmcnt(8) lgkmcnt(0)
	s_barrier
	v_mfma_f32_16x16x32_bf16 v[62:65], v[152:155], v[184:187], v[62:65]
	v_mfma_f32_16x16x32_bf16 v[58:61], v[160:163], v[184:187], v[58:61]
	v_mfma_f32_16x16x32_bf16 v[46:49], v[152:155], v[192:195], v[46:49]
	v_mfma_f32_16x16x32_bf16 v[42:45], v[160:163], v[192:195], v[42:45]
	v_mfma_f32_16x16x32_bf16 v[30:33], v[152:155], v[200:203], v[30:33]
	v_mfma_f32_16x16x32_bf16 v[26:29], v[160:163], v[200:203], v[26:29]
	v_mfma_f32_16x16x32_bf16 v[14:17], v[152:155], v[208:211], v[14:17]
	v_mfma_f32_16x16x32_bf16 v[10:13], v[160:163], v[208:211], v[10:13]
	v_mfma_f32_16x16x32_bf16 v[62:65], v[156:159], v[188:191], v[62:65]
	v_mfma_f32_16x16x32_bf16 v[58:61], v[164:167], v[188:191], v[58:61]
	v_mfma_f32_16x16x32_bf16 v[46:49], v[156:159], v[196:199], v[46:49]
	v_mfma_f32_16x16x32_bf16 v[42:45], v[164:167], v[196:199], v[42:45]
	v_mfma_f32_16x16x32_bf16 v[30:33], v[156:159], v[204:207], v[30:33]
	v_mfma_f32_16x16x32_bf16 v[26:29], v[164:167], v[204:207], v[26:29]
	v_mfma_f32_16x16x32_bf16 v[14:17], v[156:159], v[212:215], v[14:17]
	v_mfma_f32_16x16x32_bf16 v[10:13], v[164:167], v[212:215], v[10:13]
	v_mfma_f32_16x16x32_bf16 v[54:57], v[168:171], v[184:187], v[54:57]
	v_mfma_f32_16x16x32_bf16 v[50:53], v[176:179], v[184:187], v[50:53]
	v_mfma_f32_16x16x32_bf16 v[38:41], v[168:171], v[192:195], v[38:41]
	v_mfma_f32_16x16x32_bf16 v[34:37], v[176:179], v[192:195], v[34:37]
	v_mfma_f32_16x16x32_bf16 v[22:25], v[168:171], v[200:203], v[22:25]
	v_mfma_f32_16x16x32_bf16 v[18:21], v[176:179], v[200:203], v[18:21]
	v_mfma_f32_16x16x32_bf16 v[6:9], v[168:171], v[208:211], v[6:9]
	v_mfma_f32_16x16x32_bf16 v[2:5], v[176:179], v[208:211], v[2:5]
	v_mfma_f32_16x16x32_bf16 v[54:57], v[172:175], v[188:191], v[54:57]
	v_mfma_f32_16x16x32_bf16 v[50:53], v[180:183], v[188:191], v[50:53]
	v_mfma_f32_16x16x32_bf16 v[38:41], v[172:175], v[196:199], v[38:41]
	v_mfma_f32_16x16x32_bf16 v[34:37], v[180:183], v[196:199], v[34:37]
	v_mfma_f32_16x16x32_bf16 v[22:25], v[172:175], v[204:207], v[22:25]
	v_mfma_f32_16x16x32_bf16 v[18:21], v[180:183], v[204:207], v[18:21]
	v_mfma_f32_16x16x32_bf16 v[6:9], v[172:175], v[212:215], v[6:9]
	v_mfma_f32_16x16x32_bf16 v[2:5], v[180:183], v[212:215], v[2:5]
	s_barrier
; #define PG8_STAGE(bufoff, gbase, voff) do { _Pragma("unroll") for (int _i = 0; _i < 2; ++_i) \
;         __builtin_amdgcn_global_load_lds((const unsigned*)((const char*)(gbase) + (voff)[_i]), (LAS unsigned*)(lds + (bufoff) + ldsw + _i * 8192), 16, 0, 0); } while (0)
; #define PG8_LDA(dst, b, h) do { _Pragma("unroll") for (int m = 0; m < 4; ++m) _Pragma("unroll") for (int k = 0; k < 2; ++k) dst[m][k] = *(const LAS bf16x8*)(lds + PG8_SA(b, h) + aoff + m * 2048 + k * 1024); } while (0)
; #define PG8_LDB(dst, b, h) do { _Pragma("unroll") for (int n = 0; n < 2; ++n) _Pragma("unroll") for (int k = 0; k < 2; ++k) dst[n][k] = *(const LAS bf16x8*)(lds + PG8_SB(b, h) + boff + n * 2048 + k * 1024); } while (0)
; #define PG8_MMA(ai, bj, At, Bt) do { __builtin_amdgcn_s_setprio(1); _Pragma("unroll") for (int m = 0; m < 4; ++m) _Pragma("unroll") for (int n = 0; n < 2; ++n) _Pragma("unroll") for (int k = 0; k < 2; ++k) \
;         acc[ai][bj][m][n] = __builtin_amdgcn_mfma_f32_16x16x32_bf16(Bt[n][k], At[m][k], acc[ai][bj][m][n], 0, 0, 0); __builtin_amdgcn_s_setprio(0); } while (0)
; #define PG8_WAIT_V(n) asm volatile("s_waitcnt vmcnt(" #n ")" ::: "memory")
; #define PG8_WAIT_L(n) asm volatile("s_waitcnt lgkmcnt(" #n ")" ::: "memory")
; #define PG8_BAR __builtin_amdgcn_s_barrier()
; #define PG8_SCHED __builtin_amdgcn_sched_barrier(0)
; template <class Epi, class Sched, bool ABLK = false, bool ALIGN_EPI = true, bool SP2 = true, bool BBLK = true>
; __device__ __forceinline__ void gemm_phase(LAS unsigned char* lds, const Gemm g, const Sched& S, const Epi& E) {
;     ...
;             PG8_LDB(B0, 1, 0); PG8_LDB(B1, 1, 1); PG8_SCHED; PG8_LDA(At, 1, 0); PG8_STAGE(PG8_SA(0, 1), a2 + hstepA, voffA);
;             PG8_WAIT_V(8); PG8_WAIT_L(0); PG8_BAR; PG8_MMA(0, 0, At, B0); PG8_MMA(0, 1, At, B1); PG8_BAR; PG8_SCHED;
;             PG8_LDA(At, 1, 1); PG8_STAGE(PG8_SB(1, 0), b3, voffB); PG8_STAGE(PG8_SB(1, 1), b3 + hstepB, voffB); PG8_STAGE(PG8_SA(1, 0), a3, voffA);
;             PG8_WAIT_V(8); PG8_WAIT_L(0); PG8_BAR; PG8_MMA(1, 0, At, B0); PG8_MMA(1, 1, At, B1); PG8_BAR; PG8_SCHED;
;     ...
;         }
;         if constexpr (ALIGN_EPI) { if (wr == 0) PG8_BAR; }
	v_add_u32_e32 v151, s60, v146
	ds_read_b128 v[152:155], v151
	ds_read_b128 v[156:159], v151 offset:1024
	ds_read_b128 v[160:163], v151 offset:2048
	ds_read_b128 v[164:167], v151 offset:3072
	v_add_u32_e32 v151, s61, v146
	ds_read_b128 v[168:171], v151
	ds_read_b128 v[172:175], v151 offset:1024
	ds_read_b128 v[176:179], v151 offset:2048
	ds_read_b128 v[180:183], v151 offset:3072
	s_add_u32 s44, s44, 0x4000
	s_addc_u32 s45, s45, 0
	s_mov_b32 m0, s51
	ds_read_b128 v[184:187], v150 offset:32768
	ds_read_b128 v[188:191], v150 offset:33792
	ds_read_b128 v[192:195], v150 offset:34816
	ds_read_b128 v[196:199], v150 offset:35840
	ds_read_b128 v[200:203], v150 offset:36864
	ds_read_b128 v[204:207], v150 offset:37888
	ds_read_b128 v[208:211], v150 offset:38912
	global_load_lds_dwordx4 v130, s[44:45]
	s_mov_b32 m0, s52
	ds_read_b128 v[212:215], v150 offset:39936
	global_load_lds_dwordx4 v132, s[44:45]
	s_waitcnt vmcnt(8) lgkmcnt(0)
	s_barrier
	v_mfma_f32_16x16x32_bf16 v[126:129], v[152:155], v[184:187], v[126:129]
	v_mfma_f32_16x16x32_bf16 v[122:125], v[160:163], v[184:187], v[122:125]
	v_mfma_f32_16x16x32_bf16 v[110:113], v[152:155], v[192:195], v[110:113]
	v_mfma_f32_16x16x32_bf16 v[106:109], v[160:163], v[192:195], v[106:109]
	v_mfma_f32_16x16x32_bf16 v[94:97], v[152:155], v[200:203], v[94:97]
	v_mfma_f32_16x16x32_bf16 v[90:93], v[160:163], v[200:203], v[90:93]
	v_mfma_f32_16x16x32_bf16 v[78:81], v[152:155], v[208:211], v[78:81]
	v_mfma_f32_16x16x32_bf16 v[74:77], v[160:163], v[208:211], v[74:77]
	v_mfma_f32_16x16x32_bf16 v[126:129], v[156:159], v[188:191], v[126:129]
	v_mfma_f32_16x16x32_bf16 v[122:125], v[164:167], v[188:191], v[122:125]
	v_mfma_f32_16x16x32_bf16 v[110:113], v[156:159], v[196:199], v[110:113]
	v_mfma_f32_16x16x32_bf16 v[106:109], v[164:167], v[196:199], v[106:109]
	v_mfma_f32_16x16x32_bf16 v[94:97], v[156:159], v[204:207], v[94:97]
	v_mfma_f32_16x16x32_bf16 v[90:93], v[164:167], v[204:207], v[90:93]
	v_mfma_f32_16x16x32_bf16 v[78:81], v[156:159], v[212:215], v[78:81]
	v_mfma_f32_16x16x32_bf16 v[74:77], v[164:167], v[212:215], v[74:77]
	v_mfma_f32_16x16x32_bf16 v[118:121], v[168:171], v[184:187], v[118:121]
	v_mfma_f32_16x16x32_bf16 v[114:117], v[176:179], v[184:187], v[114:117]
	v_mfma_f32_16x16x32_bf16 v[102:105], v[168:171], v[192:195], v[102:105]
	v_mfma_f32_16x16x32_bf16 v[98:101], v[176:179], v[192:195], v[98:101]
	v_mfma_f32_16x16x32_bf16 v[86:89], v[168:171], v[200:203], v[86:89]
	v_mfma_f32_16x16x32_bf16 v[82:85], v[176:179], v[200:203], v[82:85]
	v_mfma_f32_16x16x32_bf16 v[70:73], v[168:171], v[208:211], v[70:73]
	v_mfma_f32_16x16x32_bf16 v[66:69], v[176:179], v[208:211], v[66:69]
	v_mfma_f32_16x16x32_bf16 v[118:121], v[172:175], v[188:191], v[118:121]
	v_mfma_f32_16x16x32_bf16 v[114:117], v[180:183], v[188:191], v[114:117]
	v_mfma_f32_16x16x32_bf16 v[102:105], v[172:175], v[196:199], v[102:105]
	v_mfma_f32_16x16x32_bf16 v[98:101], v[180:183], v[196:199], v[98:101]
	v_mfma_f32_16x16x32_bf16 v[86:89], v[172:175], v[204:207], v[86:89]
	v_mfma_f32_16x16x32_bf16 v[82:85], v[180:183], v[204:207], v[82:85]
	v_mfma_f32_16x16x32_bf16 v[70:73], v[172:175], v[212:215], v[70:73]
	v_mfma_f32_16x16x32_bf16 v[66:69], v[180:183], v[212:215], v[66:69]
	s_barrier
	s_add_u32 s44, s42, 0x8000
	s_addc_u32 s45, s43, 0
	s_add_i32 s70, s60, s48
	s_mov_b32 m0, s70
	ds_read_b128 v[184:187], v150 offset:49152
	ds_read_b128 v[188:191], v150 offset:50176
	ds_read_b128 v[192:195], v150 offset:51200
	ds_read_b128 v[196:199], v150 offset:52224
	global_load_lds_dwordx4 v130, s[44:45]
	s_add_i32 m0, s70, 0x2000
	s_add_u32 s42, s42, 0xc000
	v_lshl_add_u64 v[216:217], s[44:45], 0, v[132:133]
	s_addc_u32 s43, s43, 0
	s_add_i32 s44, s61, s48
	global_load_lds_dwordx4 v[216:217], off
	s_mov_b32 m0, s44
	ds_read_b128 v[200:203], v150 offset:53248
	global_load_lds_dwordx4 v130, s[42:43]
	s_add_i32 m0, s44, 0x2000
	ds_read_b128 v[204:207], v150 offset:54272
	global_load_lds_dwordx4 v132, s[42:43]
	s_mov_b32 m0, s53
	ds_read_b128 v[208:211], v150 offset:55296
	global_load_lds_dwordx4 v130, s[40:41]
	s_mov_b32 m0, s54
	ds_read_b128 v[212:215], v150 offset:56320
	global_load_lds_dwordx4 v132, s[40:41]
	s_waitcnt vmcnt(8) lgkmcnt(0)
	s_barrier
	v_mfma_f32_16x16x32_bf16 v[62:65], v[152:155], v[184:187], v[62:65]
	v_mfma_f32_16x16x32_bf16 v[58:61], v[160:163], v[184:187], v[58:61]
	v_mfma_f32_16x16x32_bf16 v[46:49], v[152:155], v[192:195], v[46:49]
	v_mfma_f32_16x16x32_bf16 v[42:45], v[160:163], v[192:195], v[42:45]
	v_mfma_f32_16x16x32_bf16 v[30:33], v[152:155], v[200:203], v[30:33]
	v_mfma_f32_16x16x32_bf16 v[26:29], v[160:163], v[200:203], v[26:29]
	v_mfma_f32_16x16x32_bf16 v[14:17], v[152:155], v[208:211], v[14:17]
	v_mfma_f32_16x16x32_bf16 v[10:13], v[160:163], v[208:211], v[10:13]
	v_mfma_f32_16x16x32_bf16 v[62:65], v[156:159], v[188:191], v[62:65]
	v_mfma_f32_16x16x32_bf16 v[58:61], v[164:167], v[188:191], v[58:61]
	v_mfma_f32_16x16x32_bf16 v[46:49], v[156:159], v[196:199], v[46:49]
	v_mfma_f32_16x16x32_bf16 v[42:45], v[164:167], v[196:199], v[42:45]
	v_mfma_f32_16x16x32_bf16 v[30:33], v[156:159], v[204:207], v[30:33]
	v_mfma_f32_16x16x32_bf16 v[26:29], v[164:167], v[204:207], v[26:29]
	v_mfma_f32_16x16x32_bf16 v[14:17], v[156:159], v[212:215], v[14:17]
	v_mfma_f32_16x16x32_bf16 v[10:13], v[164:167], v[212:215], v[10:13]
	v_mfma_f32_16x16x32_bf16 v[54:57], v[168:171], v[184:187], v[54:57]
	v_mfma_f32_16x16x32_bf16 v[50:53], v[176:179], v[184:187], v[50:53]
	v_mfma_f32_16x16x32_bf16 v[38:41], v[168:171], v[192:195], v[38:41]
	v_mfma_f32_16x16x32_bf16 v[34:37], v[176:179], v[192:195], v[34:37]
	v_mfma_f32_16x16x32_bf16 v[22:25], v[168:171], v[200:203], v[22:25]
	v_mfma_f32_16x16x32_bf16 v[18:21], v[176:179], v[200:203], v[18:21]
	v_mfma_f32_16x16x32_bf16 v[6:9], v[168:171], v[208:211], v[6:9]
	v_mfma_f32_16x16x32_bf16 v[2:5], v[176:179], v[208:211], v[2:5]
	v_mfma_f32_16x16x32_bf16 v[54:57], v[172:175], v[188:191], v[54:57]
	v_mfma_f32_16x16x32_bf16 v[50:53], v[180:183], v[188:191], v[50:53]
	v_mfma_f32_16x16x32_bf16 v[38:41], v[172:175], v[196:199], v[38:41]
	v_mfma_f32_16x16x32_bf16 v[34:37], v[180:183], v[196:199], v[34:37]
	v_mfma_f32_16x16x32_bf16 v[22:25], v[172:175], v[204:207], v[22:25]
	v_mfma_f32_16x16x32_bf16 v[18:21], v[180:183], v[204:207], v[18:21]
	v_mfma_f32_16x16x32_bf16 v[6:9], v[172:175], v[212:215], v[6:9]
	v_mfma_f32_16x16x32_bf16 v[2:5], v[180:183], v[212:215], v[2:5]
	s_barrier
	s_add_u32 s38, s38, 0x10000
	s_addc_u32 s39, s39, 0
	s_cmp_ge_u32 s67, s56
	s_cbranch_scc0 .LBB0_2328
	s_and_b64 vcc, exec, s[14:15]
	s_cbranch_vccz .LBB0_2331
	s_barrier
